# baseline (speedup 1.0000x reference)
; __device__ __forceinline__ unsigned pack2(float a, float b) { return (unsigned)f2bf(a) | ((unsigned)f2bf(b) << 16); }
; __device__ void convert_weights(const Params& p, int layer, char* smem) {
;     ...
;     __syncthreads();
; #pragma unroll
;     for (int i = 0; i < 4; ++i) {
;       int kk = (tid >> 4) + 16 * i, nn = (tid & 15) * 4;
;       float4 v = *reinterpret_cast<const float4*>(src + (size_t)(kt * 64 + kk) * N + nt * 64 + nn);
;       tile[kk * 65 + nn + 0] = v.x; tile[kk * 65 + nn + 1] = v.y;
;       tile[kk * 65 + nn + 2] = v.z; tile[kk * 65 + nn + 3] = v.w;
;     }
;     __syncthreads();
; #pragma unroll
;     for (int i = 0; i < 2; ++i) {
;       int nn = (tid >> 3) + 32 * i, kk0 = (tid & 7) * 8;
;       uint4 o;
;       o.x = pack2(tile[(kk0 + 0) * 65 + nn], tile[(kk0 + 1) * 65 + nn]);
;       o.y = pack2(tile[(kk0 + 2) * 65 + nn], tile[(kk0 + 3) * 65 + nn]);
;       o.z = pack2(tile[(kk0 + 4) * 65 + nn], tile[(kk0 + 5) * 65 + nn]);
;       o.w = pack2(tile[(kk0 + 6) * 65 + nn], tile[(kk0 + 7) * 65 + nn]);
;       *reinterpret_cast<uint4*>(dst + (size_t)(nt * 64 + nn) * K + kt * 64 + kk0) = o;
;     }
.LBB0_45:
	s_andn2_b64 vcc, exec, s[40:41]
	s_cbranch_vccnz .LBB0_27
	s_load_dwordx2 s[42:43], s[42:43], 0x0
	s_lshl_b32 s46, s56, 6
	s_ashr_i32 s47, s46, 31
	s_lshl_b32 s40, s55, 6
	s_lshl_b64 s[60:61], s[46:47], 2
	s_waitcnt lgkmcnt(0)
	s_add_u32 s42, s42, s60
	v_add_u32_e32 v5, s40, v12
	s_addc_u32 s43, s43, s61
	v_add_u32_e32 v7, 16, v5
	v_lshl_add_u64 v[34:35], s[42:43], 0, v[2:3]
	v_mad_i64_i32 v[8:9], s[42:43], s44, v5, 0
	v_mad_i64_i32 v[10:11], s[42:43], s44, v7, 0
	v_lshl_add_u64 v[8:9], v[8:9], 2, v[34:35]
	v_lshl_add_u64 v[26:27], v[10:11], 2, v[34:35]
	s_barrier
	global_load_dwordx4 v[8:11], v[8:9], off
	s_nop 0
	global_load_dwordx4 v[26:29], v[26:27], off
	v_add_u32_e32 v7, 32, v5
	v_mad_i64_i32 v[30:31], s[42:43], s44, v7, 0
	v_lshl_add_u64 v[30:31], v[30:31], 2, v[34:35]
	v_add_u32_e32 v5, 48, v5
	global_load_dwordx4 v[30:33], v[30:31], off
	v_mad_i64_i32 v[36:37], s[42:43], s44, v5, 0
	v_lshl_add_u64 v[34:35], v[36:37], 2, v[34:35]
	global_load_dwordx4 v[34:37], v[34:35], off
	v_add_u32_e32 v5, s46, v13
	v_ashrrev_i32_e32 v25, 31, v5
	v_mul_lo_u32 v42, s39, v5
	v_mad_u64_u32 v[38:39], s[42:43], s38, v5, 0
	v_add_u32_e32 v5, 32, v5
	v_ashrrev_i32_e32 v43, 31, v5
	s_ashr_i32 s41, s40, 31
	v_mul_lo_u32 v25, s38, v25
	v_mul_lo_u32 v44, s39, v5
	v_mad_u64_u32 v[40:41], s[42:43], s38, v5, 0
	v_mul_lo_u32 v5, s38, v43
	s_lshl_b64 s[38:39], s[40:41], 1
	s_add_u32 s36, s36, s38
	v_mov_b32_e32 v7, v3
	s_addc_u32 s37, s37, s39
	v_add3_u32 v39, v39, v25, v42
	v_add3_u32 v41, v41, v5, v44
	v_lshl_add_u64 v[42:43], s[36:37], 0, v[6:7]
	v_lshl_add_u64 v[38:39], v[38:39], 1, v[42:43]
	v_lshl_add_u64 v[40:41], v[40:41], 1, v[42:43]
	s_waitcnt vmcnt(3)
	ds_write2_b32 v16, v8, v9 offset1:1
	ds_write2_b32 v16, v10, v11 offset0:2 offset1:3
	s_waitcnt vmcnt(2)
	ds_write2_b32 v17, v26, v27 offset1:1
	ds_write2_b32 v18, v28, v29 offset1:1
	s_waitcnt vmcnt(1)
	ds_write2_b32 v19, v30, v31 offset1:1
	ds_write2_b32 v20, v32, v33 offset1:1
	s_waitcnt vmcnt(0)
	ds_write2_b32 v21, v34, v35 offset1:1
	ds_write2_b32 v22, v36, v37 offset1:1
	s_waitcnt lgkmcnt(0)
	s_barrier
	ds_read2_b32 v[26:27], v15 offset1:32
	ds_read2_b32 v[28:29], v15 offset0:65 offset1:97
	ds_read2_b32 v[30:31], v15 offset0:130 offset1:162
	ds_read2_b32 v[32:33], v15 offset0:195 offset1:227
	ds_read2_b32 v[34:35], v23 offset0:4 offset1:36
	ds_read2_b32 v[36:37], v23 offset0:69 offset1:101
	ds_read2_b32 v[42:43], v23 offset0:134 offset1:166
	ds_read2_b32 v[44:45], v23 offset0:199 offset1:231
	s_waitcnt lgkmcnt(7)
	s_waitcnt lgkmcnt(4)
	s_waitcnt lgkmcnt(3)
	s_waitcnt lgkmcnt(0)
	v_cvt_pk_bf16_f32 v7, 0, v26
	v_cvt_pk_bf16_f32 v9, 0, v28
	v_and_b32_e32 v28, 0xffff0000, v9
	v_cvt_pk_bf16_f32 v9, v30, v32
	v_or_b32_sdwa v8, v28, v7 dst_sel:DWORD dst_unused:UNUSED_PAD src0_sel:DWORD src1_sel:WORD_1
	v_cvt_pk_bf16_f32 v11, v42, v44
	v_cvt_pk_bf16_f32 v10, v34, v36
	global_store_dwordx4 v[38:39], v[8:11], off
	s_nop 1
	s_nop 0
	v_cvt_pk_bf16_f32 v9, 0, v29
	v_cvt_pk_bf16_f32 v5, 0, v27
	v_and_b32_e32 v10, 0xffff0000, v9
	v_cvt_pk_bf16_f32 v9, v31, v33
	v_or_b32_sdwa v8, v10, v5 dst_sel:DWORD dst_unused:UNUSED_PAD src0_sel:DWORD src1_sel:WORD_1
	v_cvt_pk_bf16_f32 v11, 0, v37
	v_cvt_pk_bf16_f32 v7, 0, v35
	v_and_b32_e32 v25, 0xffff0000, v11
	v_cvt_pk_bf16_f32 v11, v43, v45
	v_or_b32_sdwa v10, v25, v7 dst_sel:DWORD dst_unused:UNUSED_PAD src0_sel:DWORD src1_sel:WORD_1
	global_store_dwordx4 v[40:41], v[8:11], off
	s_branch .LBB0_27

; __device__ __forceinline__ unsigned pack2(float a, float b) { return (unsigned)f2bf(a) | ((unsigned)f2bf(b) << 16); }
; __device__ __forceinline__ float bflo(unsigned w) { return __uint_as_float(w << 16); }
; __device__ void norm_phase(const Params& p, int layer) {
;     ...
;   for (int r2 = gw; r2 < NTOK / 2; r2 += nw) {
;     const int row = r2 * 2 + sub;
;     const size_t rbase = (size_t)row * DM + l32 * 4;
;     float4 xv[8];
;     if (layer < 0) {
; #pragma unroll
;       for (int i = 0; i < 8; ++i) xv[i] = *reinterpret_cast<const float4*>(p.x + rbase + i * 128);
;     } else {
;       const float* xr = (layer == 0) ? p.x : p.out;
;       float4 ov[8];
;       float ss = 0.f;
; #pragma unroll
;       for (int i = 0; i < 8; ++i) {
;         {
;           uint2 ob = *reinterpret_cast<const uint2*>(OUTB + rbase + i * 128);
;           ov[i] = make_float4(bflo(ob.x), bfhi(ob.x), bflo(ob.y), bfhi(ob.y));
;         }
;         xv[i] = *reinterpret_cast<const float4*>(xr + rbase + i * 128);
;       }
; #pragma unroll
;       for (int i = 0; i < 8; ++i) ss += ov[i].x * ov[i].x + ov[i].y * ov[i].y + ov[i].z * ov[i].z + ov[i].w * ov[i].w;
;       ss = half_wave_sum(ss);
;       float rstd = rsqrtf(ss * (1.f / 1024.f) + 1e-6f);
; #pragma unroll
;       for (int i = 0; i < 8; ++i) {
;         float4 g = *reinterpret_cast<const float4*>(p.g_post + (size_t)layer * DM + l32 * 4 + i * 128);
;         xv[i].x += ov[i].x * rstd * g.x;
;         xv[i].y += ov[i].y * rstd * g.y;
;         xv[i].z += ov[i].z * rstd * g.z;
;         xv[i].w += ov[i].w * rstd * g.w;
;         *reinterpret_cast<float4*>(p.out + rbase + i * 128) = xv[i];
;       }
;     }
;     const int nl = layer + 1;
;     if (nl < 4) {
;       float ss = 0.f;
; #pragma unroll
;       for (int i = 0; i < 8; ++i) ss += xv[i].x * xv[i].x + xv[i].y * xv[i].y + xv[i].z * xv[i].z + xv[i].w * xv[i].w;
;       ss = half_wave_sum(ss);
;       float rstd = rsqrtf(ss * (1.f / 1024.f) + 1e-6f);
; #pragma unroll
;       for (int i = 0; i < 8; ++i) {
;         float4 g = *reinterpret_cast<const float4*>(p.g_pre + (size_t)nl * DM + l32 * 4 + i * 128);
;         uint2 o;
;         o.x = pack2(xv[i].x * rstd * g.x, xv[i].y * rstd * g.y);
;         o.y = pack2(xv[i].z * rstd * g.z, xv[i].w * rstd * g.w);
;         *reinterpret_cast<uint2*>(H + rbase + i * 128) = o;
;       }
.LBB0_49:
	v_ashrrev_i32_e32 v23, 31, v22
	v_lshlrev_b64 v[24:25], 10, v[22:23]
	v_or_b32_e32 v24, v24, v18
	v_lshl_add_u64 v[54:55], v[24:25], 2, s[10:11]
	global_load_dwordx4 v[34:37], v[54:55], off
	global_load_dwordx4 v[38:41], v[54:55], off offset:512
	global_load_dwordx4 v[42:45], v[54:55], off offset:1024
	global_load_dwordx4 v[46:49], v[54:55], off offset:1536
	global_load_dwordx4 v[14:17], v[54:55], off offset:2048
	global_load_dwordx4 v[10:13], v[54:55], off offset:2560
	global_load_dwordx4 v[6:9], v[54:55], off offset:3072
	global_load_dwordx4 v[2:5], v[54:55], off offset:3584
	global_load_dwordx4 v[50:53], v[20:21], off
	v_lshl_add_u64 v[24:25], v[24:25], 1, s[8:9]
	v_add_u32_e32 v1, s56, v1
	v_add_u32_e32 v22, s14, v22
	s_waitcnt vmcnt(8)
	v_mul_f32_e32 v23, v35, v35
	s_waitcnt vmcnt(7)
	v_mul_f32_e32 v26, v39, v39
	s_waitcnt vmcnt(6)
	v_mov_b32_e32 v56, v43
	s_waitcnt vmcnt(5)
	v_mov_b32_e32 v57, v47
	v_mov_b32_e32 v54, v42
	v_mov_b32_e32 v55, v46
	v_fmac_f32_e32 v23, v34, v34
	v_fmac_f32_e32 v26, v38, v38
	v_pk_mul_f32 v[56:57], v[56:57], v[56:57]
	v_mov_b32_e32 v58, v44
	v_mov_b32_e32 v59, v48
	s_waitcnt vmcnt(4)
	v_mov_b32_e32 v64, v15
	s_waitcnt vmcnt(3)
	v_mov_b32_e32 v65, v11
	v_fmac_f32_e32 v23, v36, v36
	v_fmac_f32_e32 v26, v40, v40
	v_pk_fma_f32 v[54:55], v[54:55], v[54:55], v[56:57]
	v_mov_b32_e32 v60, v45
	v_mov_b32_e32 v61, v49
	v_mov_b32_e32 v62, v14
	v_mov_b32_e32 v63, v10
	v_pk_mul_f32 v[64:65], v[64:65], v[64:65]
	v_fmac_f32_e32 v23, v37, v37
	v_fmac_f32_e32 v26, v41, v41
	v_pk_fma_f32 v[54:55], v[58:59], v[58:59], v[54:55]
	v_mov_b32_e32 v66, v16
	v_mov_b32_e32 v67, v12
	s_waitcnt vmcnt(2)
	v_mov_b32_e32 v72, v7
	s_waitcnt vmcnt(1)
	v_mov_b32_e32 v73, v3
	v_pk_fma_f32 v[56:57], v[62:63], v[62:63], v[64:65]
	v_add_f32_e32 v23, v23, v26
	v_pk_fma_f32 v[54:55], v[60:61], v[60:61], v[54:55]
	v_mov_b32_e32 v68, v17
	v_mov_b32_e32 v69, v13
	v_mov_b32_e32 v70, v6
	v_mov_b32_e32 v71, v2
	v_pk_mul_f32 v[72:73], v[72:73], v[72:73]
	v_pk_fma_f32 v[56:57], v[66:67], v[66:67], v[56:57]
	v_add_f32_e32 v23, v23, v54
	v_mov_b32_e32 v74, v8
	v_mov_b32_e32 v75, v4
	v_pk_fma_f32 v[62:63], v[70:71], v[70:71], v[72:73]
	v_pk_fma_f32 v[56:57], v[68:69], v[68:69], v[56:57]
	v_add_f32_e32 v23, v23, v55
	v_mov_b32_e32 v76, v9
	v_mov_b32_e32 v77, v5
	v_pk_fma_f32 v[58:59], v[74:75], v[74:75], v[62:63]
	v_add_f32_e32 v23, v23, v56
	v_pk_fma_f32 v[58:59], v[76:77], v[76:77], v[58:59]
	v_add_f32_e32 v23, v23, v57
	v_add_f32_e32 v23, v23, v58
	v_add_f32_e32 v23, v23, v59
	ds_bpermute_b32 v26, v19, v23
	s_waitcnt vmcnt(0)
	v_mov_b32_e32 v54, v50
	v_mov_b32_e32 v55, v52
	v_mov_b32_e32 v52, v51
	v_mov_b32_e32 v50, v34
	s_waitcnt lgkmcnt(0)
	v_add_f32_e32 v23, v23, v26
	ds_bpermute_b32 v26, v27, v23
	v_mov_b32_e32 v51, v36
	v_mov_b32_e32 v36, v35
	s_waitcnt lgkmcnt(0)
	v_add_f32_e32 v23, v23, v26
	ds_bpermute_b32 v26, v28, v23
	s_waitcnt lgkmcnt(0)
	v_add_f32_e32 v23, v23, v26
	ds_bpermute_b32 v26, v29, v23
	s_waitcnt lgkmcnt(0)
	v_add_f32_e32 v23, v23, v26
	ds_bpermute_b32 v26, v30, v23
	s_waitcnt lgkmcnt(0)
	v_add_f32_e32 v23, v23, v26
	v_fmamk_f32 v23, v23, 0x3a800000, v31
	v_mul_f32_e32 v26, 0x4b800000, v23
	v_cmp_gt_f32_e32 vcc, s15, v23
	s_nop 1
	v_cndmask_b32_e32 v23, v23, v26, vcc
	v_rsq_f32_e32 v23, v23
	s_nop 0
	v_mul_f32_e32 v26, 0x45800000, v23
	v_cndmask_b32_e32 v26, v23, v26, vcc
	v_pk_mul_f32 v[34:35], v[50:51], v[26:27] op_sel_hi:[1,0]
	v_pk_mul_f32 v[36:37], v[36:37], v[26:27] op_sel_hi:[1,0]
	v_pk_mul_f32 v[34:35], v[54:55], v[34:35]
	v_pk_mul_f32 v[36:37], v[52:53], v[36:37]
	v_cvt_pk_bf16_f32 v33, 0, v34
	v_cvt_pk_bf16_f32 v23, 0, v35
	v_cvt_pk_bf16_f32 v34, 0, v37
	v_cvt_pk_bf16_f32 v35, 0, v36
	v_and_b32_e32 v34, 0xffff0000, v34
	v_and_b32_e32 v36, 0xffff0000, v35
	v_or_b32_sdwa v35, v34, v23 dst_sel:DWORD dst_unused:UNUSED_PAD src0_sel:DWORD src1_sel:WORD_1
	v_or_b32_sdwa v34, v36, v33 dst_sel:DWORD dst_unused:UNUSED_PAD src0_sel:DWORD src1_sel:WORD_1
	global_store_dwordx2 v[24:25], v[34:35], off
	global_load_dwordx4 v[34:37], v[20:21], off offset:512
	v_mov_b32_e32 v50, v38
	v_mov_b32_e32 v51, v40
	v_mov_b32_e32 v40, v39
	v_pk_mul_f32 v[38:39], v[50:51], v[26:27] op_sel_hi:[1,0]
	v_pk_mul_f32 v[40:41], v[40:41], v[26:27] op_sel_hi:[1,0]
	v_cmp_lt_i32_e32 vcc, s21, v1
	s_or_b64 s[12:13], vcc, s[12:13]
	s_waitcnt vmcnt(0)
; __device__ __forceinline__ unsigned pack2(float a, float b) { return (unsigned)f2bf(a) | ((unsigned)f2bf(b) << 16); }
; __device__ void norm_phase(const Params& p, int layer) {
;     ...
; #pragma unroll
;       for (int i = 0; i < 8; ++i) {
;         float4 g = *reinterpret_cast<const float4*>(p.g_pre + (size_t)nl * DM + l32 * 4 + i * 128);
;         uint2 o;
;         o.x = pack2(xv[i].x * rstd * g.x, xv[i].y * rstd * g.y);
;         o.y = pack2(xv[i].z * rstd * g.z, xv[i].w * rstd * g.w);
;         *reinterpret_cast<uint2*>(H + rbase + i * 128) = o;
;       }
	v_mov_b32_e32 v50, v34
	v_mov_b32_e32 v51, v36
	v_mov_b32_e32 v36, v35
	v_pk_mul_f32 v[34:35], v[50:51], v[38:39]
	v_pk_mul_f32 v[36:37], v[36:37], v[40:41]
	v_cvt_pk_bf16_f32 v33, 0, v34
	v_cvt_pk_bf16_f32 v23, 0, v35
	v_cvt_pk_bf16_f32 v34, 0, v37
	v_cvt_pk_bf16_f32 v35, 0, v36
	v_and_b32_e32 v34, 0xffff0000, v34
	v_and_b32_e32 v36, 0xffff0000, v35
	v_or_b32_sdwa v35, v34, v23 dst_sel:DWORD dst_unused:UNUSED_PAD src0_sel:DWORD src1_sel:WORD_1
	v_or_b32_sdwa v34, v36, v33 dst_sel:DWORD dst_unused:UNUSED_PAD src0_sel:DWORD src1_sel:WORD_1
	global_store_dwordx2 v[24:25], v[34:35], off offset:256
	global_load_dwordx4 v[34:37], v[20:21], off offset:1024
	v_mov_b32_e32 v38, v42
	v_mov_b32_e32 v39, v44
	v_mov_b32_e32 v40, v43
	v_mov_b32_e32 v41, v45
	v_pk_mul_f32 v[38:39], v[38:39], v[26:27] op_sel_hi:[1,0]
	v_pk_mul_f32 v[40:41], v[40:41], v[26:27] op_sel_hi:[1,0]
	s_waitcnt vmcnt(0)
	v_mov_b32_e32 v42, v34
	v_mov_b32_e32 v43, v36
	v_mov_b32_e32 v36, v35
	v_pk_mul_f32 v[34:35], v[38:39], v[42:43]
	v_pk_mul_f32 v[36:37], v[40:41], v[36:37]
	v_cvt_pk_bf16_f32 v33, 0, v34
	v_cvt_pk_bf16_f32 v23, 0, v35
	v_cvt_pk_bf16_f32 v34, 0, v37
	v_cvt_pk_bf16_f32 v35, 0, v36
	v_and_b32_e32 v34, 0xffff0000, v34
	v_and_b32_e32 v36, 0xffff0000, v35
	v_or_b32_sdwa v35, v34, v23 dst_sel:DWORD dst_unused:UNUSED_PAD src0_sel:DWORD src1_sel:WORD_1
	v_or_b32_sdwa v34, v36, v33 dst_sel:DWORD dst_unused:UNUSED_PAD src0_sel:DWORD src1_sel:WORD_1
	global_store_dwordx2 v[24:25], v[34:35], off offset:512
	global_load_dwordx4 v[34:37], v[20:21], off offset:1536
	v_mov_b32_e32 v38, v46
	v_mov_b32_e32 v39, v48
	v_mov_b32_e32 v48, v47
	v_pk_mul_f32 v[38:39], v[38:39], v[26:27] op_sel_hi:[1,0]
	v_pk_mul_f32 v[40:41], v[48:49], v[26:27] op_sel_hi:[1,0]
	s_waitcnt vmcnt(0)
	v_mov_b32_e32 v42, v34
	v_mov_b32_e32 v43, v36
	v_mov_b32_e32 v36, v35
	v_pk_mul_f32 v[34:35], v[38:39], v[42:43]
	v_pk_mul_f32 v[36:37], v[40:41], v[36:37]
	v_cvt_pk_bf16_f32 v33, 0, v34
	v_cvt_pk_bf16_f32 v23, 0, v35
	v_cvt_pk_bf16_f32 v34, 0, v37
	v_cvt_pk_bf16_f32 v35, 0, v36
	v_and_b32_e32 v34, 0xffff0000, v34
	v_and_b32_e32 v36, 0xffff0000, v35
	v_or_b32_sdwa v35, v34, v23 dst_sel:DWORD dst_unused:UNUSED_PAD src0_sel:DWORD src1_sel:WORD_1
	v_or_b32_sdwa v34, v36, v33 dst_sel:DWORD dst_unused:UNUSED_PAD src0_sel:DWORD src1_sel:WORD_1
	global_store_dwordx2 v[24:25], v[34:35], off offset:768
	global_load_dwordx4 v[34:37], v[20:21], off offset:2048
	v_mov_b32_e32 v38, v14
	v_mov_b32_e32 v39, v16
	v_mov_b32_e32 v14, v15
	v_mov_b32_e32 v15, v17
	v_pk_mul_f32 v[16:17], v[38:39], v[26:27] op_sel_hi:[1,0]
	v_pk_mul_f32 v[14:15], v[14:15], v[26:27] op_sel_hi:[1,0]
	s_waitcnt vmcnt(0)
	v_mov_b32_e32 v39, v36
	v_mov_b32_e32 v36, v35
	v_mov_b32_e32 v38, v34
	v_pk_mul_f32 v[14:15], v[14:15], v[36:37]
	v_pk_mul_f32 v[16:17], v[16:17], v[38:39]
	v_cvt_pk_bf16_f32 v15, v17, v15
	v_cvt_pk_bf16_f32 v14, v16, v14
	global_store_dwordx2 v[24:25], v[14:15], off offset:1024
	global_load_dwordx4 v[14:17], v[20:21], off offset:2560
	v_mov_b32_e32 v34, v10
	v_mov_b32_e32 v35, v12
	v_mov_b32_e32 v12, v11
	v_pk_mul_f32 v[10:11], v[34:35], v[26:27] op_sel_hi:[1,0]
	v_pk_mul_f32 v[12:13], v[12:13], v[26:27] op_sel_hi:[1,0]
	s_waitcnt vmcnt(0)
	v_mov_b32_e32 v35, v16
	v_mov_b32_e32 v16, v15
	v_mov_b32_e32 v34, v14
	v_pk_mul_f32 v[12:13], v[12:13], v[16:17]
	v_pk_mul_f32 v[10:11], v[10:11], v[34:35]
	v_cvt_pk_bf16_f32 v11, v11, v13
	v_cvt_pk_bf16_f32 v10, v10, v12
	global_store_dwordx2 v[24:25], v[10:11], off offset:1280
	global_load_dwordx4 v[10:13], v[20:21], off offset:3072
	v_mov_b32_e32 v14, v6
	v_mov_b32_e32 v15, v8
	v_mov_b32_e32 v6, v7
	v_mov_b32_e32 v7, v9
	v_pk_mul_f32 v[8:9], v[14:15], v[26:27] op_sel_hi:[1,0]
	v_pk_mul_f32 v[6:7], v[6:7], v[26:27] op_sel_hi:[1,0]
	s_waitcnt vmcnt(0)
	v_mov_b32_e32 v15, v12
	v_mov_b32_e32 v12, v11
	v_mov_b32_e32 v14, v10
	v_pk_mul_f32 v[6:7], v[6:7], v[12:13]
	v_pk_mul_f32 v[8:9], v[8:9], v[14:15]
	v_cvt_pk_bf16_f32 v7, v9, v7
	v_cvt_pk_bf16_f32 v6, v8, v6
	global_store_dwordx2 v[24:25], v[6:7], off offset:1536
	global_load_dwordx4 v[6:9], v[20:21], off offset:3584
	v_mov_b32_e32 v10, v2
	v_mov_b32_e32 v11, v4
	v_mov_b32_e32 v4, v3
	v_pk_mul_f32 v[2:3], v[10:11], v[26:27] op_sel_hi:[1,0]
	v_pk_mul_f32 v[4:5], v[4:5], v[26:27] op_sel_hi:[1,0]
	s_waitcnt vmcnt(0)
	v_mov_b32_e32 v11, v8
	v_mov_b32_e32 v8, v7
	v_mov_b32_e32 v10, v6
	v_pk_mul_f32 v[4:5], v[4:5], v[8:9]
	v_pk_mul_f32 v[2:3], v[2:3], v[10:11]
	v_cvt_pk_bf16_f32 v3, v3, v5
	v_cvt_pk_bf16_f32 v2, v2, v4
	global_store_dwordx2 v[24:25], v[2:3], off offset:1792
	s_andn2_b64 exec, exec, s[12:13]
	s_cbranch_execnz .LBB0_49

; __device__ void gmlp_item(const Params& p, int layer, int b, int n, int g, char* smem) {
;     ...
;   {
;     float* Tf = reinterpret_cast<float*>(smem);
; #pragma unroll
;     for (int m = 0; m < 4; ++m)
; #pragma unroll
;       for (int j = 0; j < 4; ++j) {
;         int t = wr * 64 + m * 16 + fq * 4 + j;
;         float bias = p.gm_b_s[(size_t)layer * 512 + g * 128 + t];
; #pragma unroll
;         for (int nn = 0; nn < 4; ++nn) Tf[t * 132 + wc * 64 + nn * 16 + fr] = acc[m][nn][j] + bias;
;       }
;     __syncthreads();
;     uint4 uu[8], gt[8];
; #pragma unroll
;     for (int i = 0; i < 8; ++i) {
;       int q = tid + 256 * i, t = q >> 4, c = (q & 15) * 8;
;       uu[i] = *reinterpret_cast<const uint4*>(P + (t0 + t) * NP + g * 128 + c);
;       gt[i] = *reinterpret_cast<const uint4*>(P + (t0 + t) * NP + 1024 + g * 128 + c);
;     }
.LBB0_149:
	s_ashr_i32 s5, s83, 31
	s_add_u32 s4, s28, s83
	s_addc_u32 s5, s29, s5
	s_lshl_b32 s6, s80, 1
	s_add_u32 s8, s48, s6
	s_addc_u32 s9, s49, 0
	v_lshl_add_u64 v[2:3], s[10:11], 0, v[134:135]
	v_mov_b64_e32 v[4:5], s[8:9]
	v_mad_u64_u32 v[0:1], s[8:9], v2, s55, v[4:5]
	v_mad_i32_i24 v1, v3, s55, v1
	s_waitcnt vmcnt(12)
	v_lshl_add_u64 v[76:77], v[0:1], 0, v[138:139]
	v_add_u32_e32 v0, 0x100, v161
	v_ashrrev_i32_e32 v1, 31, v0
	v_lshrrev_b32_e32 v1, 28, v1
	v_add_u32_e32 v1, v0, v1
	v_ashrrev_i32_e32 v8, 4, v1
	v_and_b32_e32 v1, -16, v1
	s_waitcnt vmcnt(5)
	v_sub_u32_e32 v99, v0, v1
	v_lshlrev_b32_e32 v0, 3, v99
	v_ashrrev_i32_e32 v1, 31, v0
	s_waitcnt vmcnt(3)
	v_lshlrev_b64 v[92:93], 1, v[0:1]
	v_add_u32_e32 v0, 0x200, v161
	v_ashrrev_i32_e32 v1, 31, v0
	v_lshrrev_b32_e32 v1, 28, v1
	v_add_u32_e32 v1, v0, v1
	v_ashrrev_i32_e32 v9, 31, v8
	v_ashrrev_i32_e32 v94, 4, v1
	v_and_b32_e32 v1, -16, v1
	v_lshl_add_u64 v[10:11], s[10:11], 0, v[8:9]
	v_sub_u32_e32 v9, v0, v1
	v_lshlrev_b32_e32 v0, 3, v9
	v_ashrrev_i32_e32 v1, 31, v0
	v_lshlrev_b64 v[100:101], 1, v[0:1]
	v_add_u32_e32 v0, 0x300, v161
	v_ashrrev_i32_e32 v1, 31, v0
	v_lshrrev_b32_e32 v1, 28, v1
	v_add_u32_e32 v1, v0, v1
	v_ashrrev_i32_e32 v102, 4, v1
	v_and_b32_e32 v1, -16, v1
	v_sub_u32_e32 v128, v0, v1
	v_lshlrev_b32_e32 v0, 3, v128
	v_ashrrev_i32_e32 v1, 31, v0
	s_waitcnt vmcnt(0)
	v_lshlrev_b64 v[106:107], 1, v[0:1]
	v_add_u32_e32 v0, 0x400, v161
	v_ashrrev_i32_e32 v1, 31, v0
	v_lshrrev_b32_e32 v1, 28, v1
	v_add_u32_e32 v1, v0, v1
	v_ashrrev_i32_e32 v103, 31, v102
	v_ashrrev_i32_e32 v108, 4, v1
	v_and_b32_e32 v1, -16, v1
	v_lshl_add_u64 v[104:105], s[10:11], 0, v[102:103]
	v_sub_u32_e32 v103, v0, v1
	v_lshlrev_b32_e32 v0, 3, v103
	v_ashrrev_i32_e32 v1, 31, v0
	v_lshlrev_b64 v[112:113], 1, v[0:1]
	v_add_u32_e32 v0, 0x500, v161
	v_ashrrev_i32_e32 v1, 31, v0
	v_lshrrev_b32_e32 v1, 28, v1
	v_add_u32_e32 v1, v0, v1
	v_ashrrev_i32_e32 v109, 31, v108
	v_ashrrev_i32_e32 v114, 4, v1
	v_and_b32_e32 v1, -16, v1
	v_mad_u64_u32 v[6:7], s[8:9], v10, s55, v[4:5]
	v_ashrrev_i32_e32 v95, 31, v94
	v_lshl_add_u64 v[110:111], s[10:11], 0, v[108:109]
	v_sub_u32_e32 v109, v0, v1
	v_mad_i32_i24 v7, v11, s55, v7
	v_lshl_add_u64 v[96:97], s[10:11], 0, v[94:95]
	v_lshlrev_b32_e32 v0, 3, v109
	v_lshl_add_u64 v[78:79], v[6:7], 0, v[92:93]
	v_mad_u64_u32 v[6:7], s[8:9], v96, s55, v[4:5]
	v_ashrrev_i32_e32 v1, 31, v0
	v_mad_i32_i24 v7, v97, s55, v7
	v_lshlrev_b64 v[118:119], 1, v[0:1]
	v_add_u32_e32 v0, 0x600, v161
	v_lshl_add_u64 v[80:81], v[6:7], 0, v[100:101]
	v_mad_u64_u32 v[6:7], s[8:9], v104, s55, v[4:5]
	v_ashrrev_i32_e32 v1, 31, v0
	v_mad_i32_i24 v7, v105, s55, v7
	v_lshrrev_b32_e32 v1, 28, v1
	v_lshl_add_u64 v[82:83], v[6:7], 0, v[106:107]
	v_mad_u64_u32 v[6:7], s[8:9], v110, s55, v[4:5]
	v_ashrrev_i32_e32 v115, 31, v114
	v_add_u32_e32 v1, v0, v1
	v_mad_i32_i24 v7, v111, s55, v7
	v_lshl_add_u64 v[116:117], s[10:11], 0, v[114:115]
	v_ashrrev_i32_e32 v120, 4, v1
	v_and_b32_e32 v1, -16, v1
	v_lshl_add_u64 v[84:85], v[6:7], 0, v[112:113]
	v_mad_u64_u32 v[6:7], s[8:9], v116, s55, v[4:5]
	v_sub_u32_e32 v115, v0, v1
	v_ashrrev_i32_e32 v121, 31, v120
	v_mad_i32_i24 v7, v117, s55, v7
	v_lshlrev_b32_e32 v0, 3, v115
	v_lshl_add_u64 v[122:123], s[10:11], 0, v[120:121]
	v_lshl_add_u64 v[86:87], v[6:7], 0, v[118:119]
	v_mad_u64_u32 v[6:7], s[8:9], v122, s55, v[4:5]
	v_ashrrev_i32_e32 v1, 31, v0
	v_mad_i32_i24 v7, v123, s55, v7
	v_lshlrev_b64 v[124:125], 1, v[0:1]
	v_lshl_add_u64 v[0:1], v[6:7], 0, v[124:125]
	v_add_u32_e32 v6, 0x700, v161
	v_ashrrev_i32_e32 v7, 31, v6
	v_lshrrev_b32_e32 v7, 28, v7
	v_add_u32_e32 v7, v6, v7
	v_ashrrev_i32_e32 v126, 4, v7
	v_and_b32_e32 v7, -16, v7
	v_sub_u32_e32 v121, v6, v7
	v_lshlrev_b32_e32 v6, 3, v121
	v_ashrrev_i32_e32 v127, 31, v126
	v_lshl_add_u64 v[88:89], s[10:11], 0, v[126:127]
	v_ashrrev_i32_e32 v7, 31, v6
	v_mad_u64_u32 v[4:5], s[8:9], v88, s55, v[4:5]
	v_lshlrev_b64 v[90:91], 1, v[6:7]
	v_lshl_or_b32 v6, v137, 2, v130
	v_mad_i32_i24 v5, v89, s55, v5
	v_mul_lo_u32 v6, v6, s67
	v_lshl_add_u64 v[4:5], v[4:5], 0, v[90:91]
	v_lshl_add_u32 v95, v162, 2, v6
	s_barrier
	ds_write2_b32 v95, v12, v48 offset1:16
	ds_write2_b32 v95, v52, v56 offset0:32 offset1:48
	ds_write2_b32 v95, v60, v64 offset0:64 offset1:80
	ds_write2_b32 v95, v68, v72 offset0:96 offset1:112
	ds_write2_b32 v95, v13, v49 offset0:132 offset1:148
	ds_write2_b32 v95, v53, v57 offset0:164 offset1:180
	ds_write2_b32 v95, v61, v65 offset0:196 offset1:212
	ds_write2_b32 v95, v69, v73 offset0:228 offset1:244
	v_add_u32_e32 v12, 0x400, v95
	v_add_co_u32_e32 v4, vcc, s77, v4
	ds_write2_b32 v12, v14, v50 offset0:8 offset1:24
	ds_write2_b32 v12, v54, v58 offset0:40 offset1:56
	v_addc_co_u32_e32 v5, vcc, 0, v5, vcc
	global_load_dwordx4 v[4:7], v[4:5], off offset:512
	ds_write2_b32 v12, v62, v66 offset0:72 offset1:88
	ds_write2_b32 v12, v70, v74 offset0:104 offset1:120
	ds_write2_b32 v12, v15, v51 offset0:140 offset1:156
	ds_write2_b32 v12, v55, v59 offset0:172 offset1:188
	ds_write2_b32 v12, v63, v67 offset0:204 offset1:220
	ds_write2_b32 v12, v71, v75 offset0:236 offset1:252
	v_add_u32_e32 v12, 0x2000, v95
	ds_write2_b32 v12, v16, v20 offset0:64 offset1:80
	ds_write2_b32 v12, v24, v36 offset0:96 offset1:112
	ds_write2_b32 v12, v28, v40 offset0:128 offset1:144
	ds_write2_b32 v12, v44, v32 offset0:160 offset1:176
	ds_write2_b32 v12, v17, v21 offset0:196 offset1:212
	ds_write2_b32 v12, v25, v37 offset0:228 offset1:244
	v_add_u32_e32 v12, 0x2400, v95
	s_add_u32 s4, s4, s6
	ds_write2_b32 v12, v29, v41 offset0:4 offset1:20
	ds_write2_b32 v12, v45, v33 offset0:36 offset1:52
	ds_write2_b32 v12, v18, v22 offset0:72 offset1:88
; __device__ __forceinline__ unsigned pack2(float a, float b) { return (unsigned)f2bf(a) | ((unsigned)f2bf(b) << 16); }
; __device__ __forceinline__ float bflo(unsigned w) { return __uint_as_float(w << 16); }
; __device__ __forceinline__ float bfhi(unsigned w) { return __uint_as_float(w & 0xffff0000u); }
; __device__ __forceinline__ float silu_f(float g) { return g / (1.f + __expf(-g)); }
; __device__ void gmlp_item(const Params& p, int layer, int b, int n, int g, char* smem) {
;     ...
;     uint4 uu[8], gt[8];
; #pragma unroll
;     for (int i = 0; i < 8; ++i) {
;       int q = tid + 256 * i, t = q >> 4, c = (q & 15) * 8;
;       uu[i] = *reinterpret_cast<const uint4*>(P + (t0 + t) * NP + g * 128 + c);
;       gt[i] = *reinterpret_cast<const uint4*>(P + (t0 + t) * NP + 1024 + g * 128 + c);
;     }
; #pragma unroll
;     for (int i = 0; i < 8; ++i) {
;       int q = tid + 256 * i, t = q >> 4, c = (q & 15) * 8;
;       float4 m0 = *reinterpret_cast<const float4*>(Tf + t * 132 + c);
;       float4 m1 = *reinterpret_cast<const float4*>(Tf + t * 132 + c + 4);
;       float mm[8] = {m0.x, m0.y, m0.z, m0.w, m1.x, m1.y, m1.z, m1.w};
;       unsigned uw[4] = {uu[i].x, uu[i].y, uu[i].z, uu[i].w};
;       unsigned gw[4] = {gt[i].x, gt[i].y, gt[i].z, gt[i].w};
;       unsigned ow[4];
; #pragma unroll
;       for (int e = 0; e < 4; ++e) {
;         float y0 = bflo(uw[e]) * mm[2 * e] * silu_f(bflo(gw[e]));
;         float y1 = bfhi(uw[e]) * mm[2 * e + 1] * silu_f(bfhi(gw[e]));
;         ow[e] = pack2(y0, y1);
	ds_write2_b32 v12, v26, v38 offset0:104 offset1:120
	ds_write2_b32 v12, v30, v42 offset0:136 offset1:152
	ds_write2_b32 v12, v46, v34 offset0:168 offset1:184
	ds_write2_b32 v12, v19, v23 offset0:204 offset1:220
	ds_write2_b32 v12, v27, v39 offset0:236 offset1:252
	v_add_u32_e32 v12, 0x2800, v95
	s_addc_u32 s5, s5, 0
	ds_write2_b32 v12, v31, v43 offset0:12 offset1:28
	ds_write2_b32 v12, v47, v35 offset0:44 offset1:60
	v_mul_lo_u32 v12, v134, s67
	v_mov_b64_e32 v[14:15], s[4:5]
	v_lshl_add_u32 v98, v136, 2, v12
	v_mad_u64_u32 v[12:13], s[4:5], v2, s68, v[14:15]
	v_mul_lo_u32 v2, v8, s67
	v_mad_i32_i24 v13, v3, s68, v13
	v_lshl_add_u32 v95, v99, 5, v2
	v_mad_u64_u32 v[2:3], s[4:5], v10, s68, v[14:15]
	v_mad_i32_i24 v3, v11, s68, v3
	v_lshl_add_u64 v[26:27], v[2:3], 0, v[92:93]
	v_mul_lo_u32 v2, v94, s67
	v_lshl_add_u32 v93, v9, 5, v2
	v_mad_u64_u32 v[2:3], s[4:5], v96, s68, v[14:15]
	v_mad_i32_i24 v3, v97, s68, v3
	v_lshl_add_u64 v[20:21], v[2:3], 0, v[100:101]
	v_mul_lo_u32 v2, v102, s67
	v_lshl_add_u32 v92, v128, 5, v2
	v_mad_u64_u32 v[2:3], s[4:5], v104, s68, v[14:15]
	v_mad_i32_i24 v3, v105, s68, v3
	v_lshl_add_u64 v[16:17], v[2:3], 0, v[106:107]
	v_mul_lo_u32 v2, v108, s67
	v_lshl_add_u32 v75, v103, 5, v2
	v_mad_u64_u32 v[2:3], s[4:5], v110, s68, v[14:15]
	v_mad_i32_i24 v3, v111, s68, v3
	v_lshl_add_u64 v[30:31], v[12:13], 0, v[138:139]
	v_lshl_add_u64 v[12:13], v[2:3], 0, v[112:113]
	v_mul_lo_u32 v2, v114, s67
	v_lshl_add_u32 v74, v109, 5, v2
	v_mad_u64_u32 v[2:3], s[4:5], v116, s68, v[14:15]
	v_mad_i32_i24 v3, v117, s68, v3
	v_lshl_add_u64 v[10:11], v[2:3], 0, v[118:119]
	v_mul_lo_u32 v2, v120, s67
	v_lshl_add_u32 v73, v115, 5, v2
	v_mad_u64_u32 v[2:3], s[4:5], v122, s68, v[14:15]
	v_mad_i32_i24 v3, v123, s68, v3
	v_add_co_u32_e32 v0, vcc, s77, v0
	v_lshl_add_u64 v[8:9], v[2:3], 0, v[124:125]
	v_mul_lo_u32 v2, v126, s67
	v_addc_co_u32_e32 v1, vcc, 0, v1, vcc
	v_lshl_add_u32 v72, v121, 5, v2
	global_load_dwordx4 v[0:3], v[0:1], off offset:512
	v_mad_u64_u32 v[14:15], s[4:5], v88, s68, v[14:15]
	v_mad_i32_i24 v15, v89, s68, v15
	v_lshl_add_u64 v[14:15], v[14:15], 0, v[90:91]
	s_waitcnt vmcnt(1)
	v_lshlrev_b32_e32 v22, 16, v5
	v_lshlrev_b32_e32 v23, 16, v4
	v_mul_f32_e32 v18, 0xbfb8aa3b, v23
	v_mul_f32_e32 v19, 0xbfb8aa3b, v22
	v_exp_f32_e32 v18, v18
	v_exp_f32_e32 v19, v19
	v_and_b32_e32 v24, 0xffff0000, v5
	v_and_b32_e32 v28, 0xffff0000, v4
	v_mul_f32_e32 v4, 0xbfb8aa3b, v28
	v_pk_add_f32 v[18:19], v[18:19], 1.0 op_sel_hi:[1,0]
	v_exp_f32_e32 v4, v4
	v_and_b32_e32 v34, 0xffff0000, v6
	v_rcp_f32_e32 v19, v19
	s_nop 0
	v_mul_f32_e32 v19, v22, v19
	v_mul_f32_e32 v5, 0xbfb8aa3b, v24
	v_exp_f32_e32 v5, v5
	s_nop 0
	v_pk_add_f32 v[4:5], v[4:5], 1.0 op_sel_hi:[1,0]
	v_rcp_f32_e32 v18, v18
	s_nop 0
	v_mul_f32_e32 v18, v23, v18
	v_lshlrev_b32_e32 v33, 16, v6
	v_rcp_f32_e32 v23, v5
	s_nop 0
	v_mul_f32_e32 v23, v24, v23
	v_lshlrev_b32_e32 v32, 16, v7
	v_mul_f32_e32 v24, 0xbfb8aa3b, v33
	v_mul_f32_e32 v25, 0xbfb8aa3b, v32
	v_exp_f32_e32 v24, v24
	v_exp_f32_e32 v25, v25
	v_rcp_f32_e32 v22, v4
	s_nop 0
	v_mul_f32_e32 v22, v28, v22
	v_and_b32_e32 v28, 0xffff0000, v7
	v_pk_add_f32 v[4:5], v[24:25], 1.0 op_sel_hi:[1,0]
	v_mul_f32_e32 v6, 0xbfb8aa3b, v34
	v_exp_f32_e32 v6, v6
	s_waitcnt vmcnt(0)
	v_lshlrev_b32_e32 v40, 16, v3
	v_lshlrev_b32_e32 v41, 16, v2
	v_rcp_f32_e32 v25, v5
	s_nop 0
	v_mul_f32_e32 v25, v32, v25
	v_mul_f32_e32 v7, 0xbfb8aa3b, v28
	v_exp_f32_e32 v7, v7
	s_nop 0
	v_pk_add_f32 v[6:7], v[6:7], 1.0 op_sel_hi:[1,0]
	v_rcp_f32_e32 v24, v4
	s_nop 0
	v_mul_f32_e32 v24, v33, v24
	v_rcp_f32_e32 v29, v7
	s_nop 0
	v_mul_f32_e32 v29, v28, v29
	v_lshlrev_b32_e32 v32, 16, v1
	v_lshlrev_b32_e32 v36, 16, v0
	v_mul_f32_e32 v4, 0xbfb8aa3b, v36
	v_mul_f32_e32 v5, 0xbfb8aa3b, v32
	v_exp_f32_e32 v4, v4
	v_exp_f32_e32 v5, v5
	v_rcp_f32_e32 v28, v6
	s_nop 0
	v_mul_f32_e32 v28, v34, v28
	v_and_b32_e32 v6, 0xffff0000, v1
	v_pk_add_f32 v[4:5], v[4:5], 1.0 op_sel_hi:[1,0]
	v_and_b32_e32 v34, 0xffff0000, v0
	v_mul_f32_e32 v0, 0xbfb8aa3b, v34
	v_exp_f32_e32 v0, v0
	v_and_b32_e32 v42, 0xffff0000, v3
	v_rcp_f32_e32 v33, v5
	s_nop 0
	v_mul_f32_e32 v33, v32, v33
	v_mul_f32_e32 v1, 0xbfb8aa3b, v6
	v_exp_f32_e32 v1, v1
	s_nop 0
	v_pk_add_f32 v[0:1], v[0:1], 1.0 op_sel_hi:[1,0]
	v_rcp_f32_e32 v32, v4
	s_nop 0
	v_mul_f32_e32 v32, v36, v32
	v_rcp_f32_e32 v35, v1
	s_nop 0
	v_mul_f32_e32 v35, v6, v35
	v_add_co_u32_e64 v4, s[4:5], s77, v86
	s_nop 0
	s_nop 0
	v_addc_co_u32_e64 v5, s[4:5], 0, v87, s[4:5]
	global_load_dwordx4 v[4:7], v[4:5], off offset:512
	v_mul_f32_e32 v36, 0xbfb8aa3b, v41
	v_mul_f32_e32 v37, 0xbfb8aa3b, v40
	v_exp_f32_e32 v36, v36
	v_exp_f32_e32 v37, v37
	v_rcp_f32_e32 v1, v0
	s_nop 0
	v_mul_f32_e32 v34, v34, v1
	v_and_b32_e32 v43, 0xffff0000, v2
	v_pk_add_f32 v[0:1], v[36:37], 1.0 op_sel_hi:[1,0]
	v_mul_f32_e32 v2, 0xbfb8aa3b, v43
	v_exp_f32_e32 v2, v2
	v_rcp_f32_e32 v37, v1
	s_nop 0
	v_mul_f32_e32 v37, v40, v37
	v_mul_f32_e32 v3, 0xbfb8aa3b, v42
	v_exp_f32_e32 v3, v3
	s_nop 0
	v_pk_add_f32 v[38:39], v[2:3], 1.0 op_sel_hi:[1,0]
	v_rcp_f32_e32 v36, v0
	s_nop 0
	v_mul_f32_e32 v36, v41, v36
	v_rcp_f32_e32 v39, v39
	s_nop 0
	v_mul_f32_e32 v39, v42, v39
	v_add_co_u32_e64 v0, s[4:5], s77, v84
	s_waitcnt vmcnt(0)
; __device__ __forceinline__ unsigned pack2(float a, float b) { return (unsigned)f2bf(a) | ((unsigned)f2bf(b) << 16); }
; __device__ __forceinline__ float bflo(unsigned w) { return __uint_as_float(w << 16); }
; __device__ __forceinline__ float bfhi(unsigned w) { return __uint_as_float(w & 0xffff0000u); }
; __device__ __forceinline__ float silu_f(float g) { return g / (1.f + __expf(-g)); }
; __device__ void gmlp_item(const Params& p, int layer, int b, int n, int g, char* smem) {
;     ...
;     uint4 uu[8], gt[8];
; #pragma unroll
;     for (int i = 0; i < 8; ++i) {
;       int q = tid + 256 * i, t = q >> 4, c = (q & 15) * 8;
;       uu[i] = *reinterpret_cast<const uint4*>(P + (t0 + t) * NP + g * 128 + c);
;       gt[i] = *reinterpret_cast<const uint4*>(P + (t0 + t) * NP + 1024 + g * 128 + c);
;     }
; #pragma unroll
;     for (int i = 0; i < 8; ++i) {
;       int q = tid + 256 * i, t = q >> 4, c = (q & 15) * 8;
;       float4 m0 = *reinterpret_cast<const float4*>(Tf + t * 132 + c);
;       float4 m1 = *reinterpret_cast<const float4*>(Tf + t * 132 + c + 4);
;       float mm[8] = {m0.x, m0.y, m0.z, m0.w, m1.x, m1.y, m1.z, m1.w};
;       unsigned uw[4] = {uu[i].x, uu[i].y, uu[i].z, uu[i].w};
;       unsigned gw[4] = {gt[i].x, gt[i].y, gt[i].z, gt[i].w};
;       unsigned ow[4];
; #pragma unroll
;       for (int e = 0; e < 4; ++e) {
;         float y0 = bflo(uw[e]) * mm[2 * e] * silu_f(bflo(gw[e]));
;         float y1 = bfhi(uw[e]) * mm[2 * e + 1] * silu_f(bfhi(gw[e]));
;         ow[e] = pack2(y0, y1);
	v_lshlrev_b32_e32 v46, 16, v5
	v_lshlrev_b32_e32 v47, 16, v4
	v_mul_f32_e32 v40, 0xbfb8aa3b, v47
	v_mul_f32_e32 v41, 0xbfb8aa3b, v46
	v_exp_f32_e32 v40, v40
	v_exp_f32_e32 v41, v41
	v_addc_co_u32_e64 v1, s[4:5], 0, v85, s[4:5]
	v_rcp_f32_e32 v38, v38
	s_nop 0
	v_mul_f32_e32 v38, v43, v38
	v_pk_add_f32 v[40:41], v[40:41], 1.0 op_sel_hi:[1,0]
	v_and_b32_e32 v42, 0xffff0000, v5
	global_load_dwordx4 v[0:3], v[0:1], off offset:512
	v_and_b32_e32 v48, 0xffff0000, v4
	v_mul_f32_e32 v4, 0xbfb8aa3b, v48
	v_rcp_f32_e32 v41, v41
	s_nop 0
	v_mul_f32_e32 v41, v46, v41
	v_exp_f32_e32 v4, v4
	v_mul_f32_e32 v5, 0xbfb8aa3b, v42
	v_exp_f32_e32 v5, v5
	s_nop 0
	v_pk_add_f32 v[4:5], v[4:5], 1.0 op_sel_hi:[1,0]
	v_rcp_f32_e32 v40, v40
	s_nop 0
	v_mul_f32_e32 v40, v47, v40
	v_lshlrev_b32_e32 v49, 16, v6
	v_rcp_f32_e32 v43, v5
	s_nop 0
	v_mul_f32_e32 v43, v42, v43
	v_lshlrev_b32_e32 v46, 16, v7
	v_mul_f32_e32 v44, 0xbfb8aa3b, v49
	v_mul_f32_e32 v45, 0xbfb8aa3b, v46
	v_exp_f32_e32 v44, v44
	v_exp_f32_e32 v45, v45
	v_rcp_f32_e32 v42, v4
	s_nop 0
	v_mul_f32_e32 v42, v48, v42
	v_and_b32_e32 v47, 0xffff0000, v7
	v_pk_add_f32 v[4:5], v[44:45], 1.0 op_sel_hi:[1,0]
	v_and_b32_e32 v48, 0xffff0000, v6
	v_mul_f32_e32 v6, 0xbfb8aa3b, v48
	v_exp_f32_e32 v6, v6
	v_rcp_f32_e32 v45, v5
	s_nop 0
	v_mul_f32_e32 v45, v46, v45
	v_mul_f32_e32 v7, 0xbfb8aa3b, v47
	v_exp_f32_e32 v7, v7
	s_nop 0
	v_pk_add_f32 v[6:7], v[6:7], 1.0 op_sel_hi:[1,0]
	v_rcp_f32_e32 v44, v4
	s_nop 0
	v_mul_f32_e32 v44, v49, v44
	v_rcp_f32_e32 v4, v7
	s_nop 0
	v_mul_f32_e32 v47, v47, v4
	s_waitcnt vmcnt(0)
	v_lshlrev_b32_e32 v50, 16, v1
	v_lshlrev_b32_e32 v51, 16, v0
	v_mul_f32_e32 v4, 0xbfb8aa3b, v51
	v_mul_f32_e32 v5, 0xbfb8aa3b, v50
	v_exp_f32_e32 v4, v4
	v_exp_f32_e32 v5, v5
	v_rcp_f32_e32 v46, v6
	s_nop 0
	v_mul_f32_e32 v46, v48, v46
	v_and_b32_e32 v6, 0xffff0000, v1
	v_pk_add_f32 v[4:5], v[4:5], 1.0 op_sel_hi:[1,0]
	v_and_b32_e32 v54, 0xffff0000, v0
	v_mul_f32_e32 v0, 0xbfb8aa3b, v54
	v_exp_f32_e32 v0, v0
	v_lshlrev_b32_e32 v58, 16, v2
	v_rcp_f32_e32 v49, v5
	s_nop 0
	v_mul_f32_e32 v49, v50, v49
	v_mul_f32_e32 v1, 0xbfb8aa3b, v6
	v_exp_f32_e32 v1, v1
	s_nop 0
	v_pk_add_f32 v[0:1], v[0:1], 1.0 op_sel_hi:[1,0]
	v_rcp_f32_e32 v48, v4
	s_nop 0
	v_mul_f32_e32 v48, v51, v48
	v_lshlrev_b32_e32 v57, 16, v3
	v_rcp_f32_e32 v51, v1
	s_nop 0
	v_mul_f32_e32 v51, v6, v51
	v_add_co_u32_e64 v4, s[4:5], s77, v82
	s_nop 0
	s_nop 0
	v_addc_co_u32_e64 v5, s[4:5], 0, v83, s[4:5]
	global_load_dwordx4 v[4:7], v[4:5], off offset:512
	v_mul_f32_e32 v50, 0xbfb8aa3b, v58
	v_exp_f32_e32 v52, v50
	v_mul_f32_e32 v50, 0xbfb8aa3b, v57
	v_exp_f32_e32 v53, v50
	v_rcp_f32_e32 v50, v0
	s_nop 0
	v_mul_f32_e32 v50, v54, v50
	v_and_b32_e32 v56, 0xffff0000, v3
	v_pk_add_f32 v[0:1], v[52:53], 1.0 op_sel_hi:[1,0]
	v_and_b32_e32 v59, 0xffff0000, v2
	v_mul_f32_e32 v2, 0xbfb8aa3b, v59
	v_exp_f32_e32 v2, v2
	v_rcp_f32_e32 v53, v1
	s_nop 0
	v_mul_f32_e32 v53, v57, v53
	v_mul_f32_e32 v3, 0xbfb8aa3b, v56
	v_exp_f32_e32 v3, v3
	s_nop 0
	v_pk_add_f32 v[54:55], v[2:3], 1.0 op_sel_hi:[1,0]
	v_rcp_f32_e32 v52, v0
	s_nop 0
	v_mul_f32_e32 v52, v58, v52
	v_rcp_f32_e32 v55, v55
	s_nop 0
	v_mul_f32_e32 v55, v56, v55
	v_add_co_u32_e64 v0, s[4:5], s77, v80
	s_waitcnt vmcnt(0)
	v_lshlrev_b32_e32 v62, 16, v5
	v_lshlrev_b32_e32 v63, 16, v4
	v_mul_f32_e32 v56, 0xbfb8aa3b, v63
	v_mul_f32_e32 v57, 0xbfb8aa3b, v62
	v_exp_f32_e32 v56, v56
	v_exp_f32_e32 v57, v57
	v_addc_co_u32_e64 v1, s[4:5], 0, v81, s[4:5]
	v_rcp_f32_e32 v54, v54
	s_nop 0
	v_mul_f32_e32 v54, v59, v54
	v_pk_add_f32 v[56:57], v[56:57], 1.0 op_sel_hi:[1,0]
	v_and_b32_e32 v58, 0xffff0000, v5
	global_load_dwordx4 v[0:3], v[0:1], off offset:512
	v_and_b32_e32 v64, 0xffff0000, v4
	v_mul_f32_e32 v4, 0xbfb8aa3b, v64
	v_rcp_f32_e32 v57, v57
	s_nop 0
	v_mul_f32_e32 v57, v62, v57
	v_exp_f32_e32 v4, v4
	v_mul_f32_e32 v5, 0xbfb8aa3b, v58
	v_exp_f32_e32 v5, v5
	s_nop 0
	v_pk_add_f32 v[4:5], v[4:5], 1.0 op_sel_hi:[1,0]
	v_rcp_f32_e32 v56, v56
	s_nop 0
	v_mul_f32_e32 v56, v63, v56
	v_lshlrev_b32_e32 v65, 16, v6
	v_rcp_f32_e32 v59, v5
	s_nop 0
	v_mul_f32_e32 v59, v58, v59
	v_lshlrev_b32_e32 v62, 16, v7
	v_mul_f32_e32 v60, 0xbfb8aa3b, v65
	v_mul_f32_e32 v61, 0xbfb8aa3b, v62
	v_exp_f32_e32 v60, v60
	v_exp_f32_e32 v61, v61
	v_rcp_f32_e32 v58, v4
	s_nop 0
	v_mul_f32_e32 v58, v64, v58
	v_and_b32_e32 v63, 0xffff0000, v7
	v_pk_add_f32 v[4:5], v[60:61], 1.0 op_sel_hi:[1,0]
	v_and_b32_e32 v64, 0xffff0000, v6
	v_mul_f32_e32 v6, 0xbfb8aa3b, v64
	v_exp_f32_e32 v6, v6
	v_rcp_f32_e32 v61, v5
	s_nop 0
	v_mul_f32_e32 v61, v62, v61
	v_mul_f32_e32 v7, 0xbfb8aa3b, v63
	v_exp_f32_e32 v7, v7
	s_nop 0
	v_pk_add_f32 v[6:7], v[6:7], 1.0 op_sel_hi:[1,0]
	v_rcp_f32_e32 v60, v4
	s_nop 0
	v_mul_f32_e32 v60, v65, v60
	v_rcp_f32_e32 v4, v7
	s_nop 0
	v_mul_f32_e32 v63, v63, v4
	s_waitcnt vmcnt(0)
	v_lshlrev_b32_e32 v66, 16, v1
	v_lshlrev_b32_e32 v67, 16, v0
	v_mul_f32_e32 v4, 0xbfb8aa3b, v67
	v_mul_f32_e32 v5, 0xbfb8aa3b, v66
	v_exp_f32_e32 v4, v4
	v_exp_f32_e32 v5, v5
	v_and_b32_e32 v68, 0xffff0000, v1
	v_rcp_f32_e32 v62, v6
	s_nop 0
	v_mul_f32_e32 v62, v64, v62
	v_pk_add_f32 v[4:5], v[4:5], 1.0 op_sel_hi:[1,0]
	v_and_b32_e32 v69, 0xffff0000, v0
	v_mul_f32_e32 v0, 0xbfb8aa3b, v69
	v_exp_f32_e32 v6, v0
	v_and_b32_e32 v80, 0xffff0000, v2
	v_rcp_f32_e32 v1, v5
	s_nop 0
	v_mul_f32_e32 v1, v66, v1
	v_mul_f32_e32 v7, 0xbfb8aa3b, v68
	v_exp_f32_e32 v7, v7
	s_nop 0
	v_pk_add_f32 v[64:65], v[6:7], 1.0 op_sel_hi:[1,0]
	v_rcp_f32_e32 v0, v4
	s_nop 0
	v_mul_f32_e32 v0, v67, v0
	v_rcp_f32_e32 v65, v65
	s_nop 0
	v_mul_f32_e32 v65, v68, v65
	v_add_co_u32_e64 v4, s[4:5], s77, v78
	s_nop 0
	s_nop 0
	v_addc_co_u32_e64 v5, s[4:5], 0, v79, s[4:5]
	global_load_dwordx4 v[4:7], v[4:5], off offset:512
	v_lshlrev_b32_e32 v78, 16, v3
	v_lshlrev_b32_e32 v79, 16, v2
	v_mul_f32_e32 v66, 0xbfb8aa3b, v79
	v_mul_f32_e32 v67, 0xbfb8aa3b, v78
	v_exp_f32_e32 v66, v66
	v_exp_f32_e32 v67, v67
	v_and_b32_e32 v70, 0xffff0000, v3
	v_rcp_f32_e32 v64, v64
	s_nop 0
	v_mul_f32_e32 v64, v69, v64
	v_pk_add_f32 v[66:67], v[66:67], 1.0 op_sel_hi:[1,0]
	v_mul_f32_e32 v2, 0xbfb8aa3b, v80
	v_exp_f32_e32 v68, v2
	v_mul_f32_e32 v69, 0xbfb8aa3b, v70
	v_exp_f32_e32 v69, v69
	v_rcp_f32_e32 v3, v67
	s_nop 0
	v_mul_f32_e32 v3, v78, v3
	v_pk_add_f32 v[68:69], v[68:69], 1.0 op_sel_hi:[1,0]
	v_rcp_f32_e32 v2, v66
	s_nop 0
	v_mul_f32_e32 v2, v79, v2
	v_rcp_f32_e32 v67, v69
	s_nop 0
	v_mul_f32_e32 v67, v70, v67
	v_add_co_u32_e64 v70, s[4:5], s77, v76
	s_nop 0
	s_nop 0
	v_addc_co_u32_e64 v71, s[4:5], 0, v77, s[4:5]
	global_load_dwordx4 v[76:79], v[70:71], off offset:512
	v_rcp_f32_e32 v66, v68
	s_nop 0
	v_mul_f32_e32 v66, v80, v66
	s_waitcnt vmcnt(1)
	v_lshlrev_b32_e32 v82, 16, v5
	v_lshlrev_b32_e32 v83, 16, v4
	v_mul_f32_e32 v70, 0xbfb8aa3b, v83
	v_mul_f32_e32 v71, 0xbfb8aa3b, v82
	v_exp_f32_e32 v70, v70
	v_exp_f32_e32 v71, v71
	v_and_b32_e32 v80, 0xffff0000, v5
	v_and_b32_e32 v84, 0xffff0000, v4
	v_mul_f32_e32 v4, 0xbfb8aa3b, v84
	v_pk_add_f32 v[68:69], v[70:71], 1.0 op_sel_hi:[1,0]
	v_exp_f32_e32 v70, v4
	s_waitcnt lgkmcnt(0)
	s_barrier
; __device__ __forceinline__ unsigned pack2(float a, float b) { return (unsigned)f2bf(a) | ((unsigned)f2bf(b) << 16); }
; __device__ __forceinline__ float bflo(unsigned w) { return __uint_as_float(w << 16); }
; __device__ __forceinline__ float bfhi(unsigned w) { return __uint_as_float(w & 0xffff0000u); }
; __device__ __forceinline__ float silu_f(float g) { return g / (1.f + __expf(-g)); }
; __device__ void gmlp_item(const Params& p, int layer, int b, int n, int g, char* smem) {
;     ...
; #pragma unroll
;     for (int i = 0; i < 8; ++i) {
;       int q = tid + 256 * i, t = q >> 4, c = (q & 15) * 8;
;       float4 m0 = *reinterpret_cast<const float4*>(Tf + t * 132 + c);
;       float4 m1 = *reinterpret_cast<const float4*>(Tf + t * 132 + c + 4);
;       float mm[8] = {m0.x, m0.y, m0.z, m0.w, m1.x, m1.y, m1.z, m1.w};
;       unsigned uw[4] = {uu[i].x, uu[i].y, uu[i].z, uu[i].w};
;       unsigned gw[4] = {gt[i].x, gt[i].y, gt[i].z, gt[i].w};
;       unsigned ow[4];
; #pragma unroll
;       for (int e = 0; e < 4; ++e) {
;         float y0 = bflo(uw[e]) * mm[2 * e] * silu_f(bflo(gw[e]));
;         float y1 = bfhi(uw[e]) * mm[2 * e + 1] * silu_f(bfhi(gw[e]));
;         ow[e] = pack2(y0, y1);
;       }
;       *reinterpret_cast<uint4*>(Y + (t0 + t) * YW + g * 128 + c) = make_uint4(ow[0], ow[1], ow[2], ow[3]);
;     }
	v_mul_f32_e32 v71, 0xbfb8aa3b, v80
	v_exp_f32_e32 v71, v71
	v_rcp_f32_e32 v5, v69
	s_nop 0
	v_mul_f32_e32 v5, v82, v5
	v_pk_add_f32 v[70:71], v[70:71], 1.0 op_sel_hi:[1,0]
	v_rcp_f32_e32 v4, v68
	s_nop 0
	v_mul_f32_e32 v4, v83, v4
	v_rcp_f32_e32 v69, v71
	s_nop 0
	v_mul_f32_e32 v69, v80, v69
	v_lshlrev_b32_e32 v82, 16, v7
	v_lshlrev_b32_e32 v85, 16, v6
	v_mul_f32_e32 v80, 0xbfb8aa3b, v85
	v_mul_f32_e32 v81, 0xbfb8aa3b, v82
	v_exp_f32_e32 v80, v80
	v_exp_f32_e32 v81, v81
	v_rcp_f32_e32 v68, v70
	s_nop 0
	v_mul_f32_e32 v68, v84, v68
	v_and_b32_e32 v83, 0xffff0000, v7
	v_pk_add_f32 v[70:71], v[80:81], 1.0 op_sel_hi:[1,0]
	v_and_b32_e32 v84, 0xffff0000, v6
	v_mul_f32_e32 v6, 0xbfb8aa3b, v84
	v_exp_f32_e32 v80, v6
	s_waitcnt vmcnt(0)
	v_and_b32_e32 v94, 0xffff0000, v78
	v_mul_f32_e32 v81, 0xbfb8aa3b, v83
	v_exp_f32_e32 v81, v81
	v_rcp_f32_e32 v7, v71
	s_nop 0
	v_mul_f32_e32 v7, v82, v7
	v_pk_add_f32 v[80:81], v[80:81], 1.0 op_sel_hi:[1,0]
	v_rcp_f32_e32 v6, v70
	s_nop 0
	v_mul_f32_e32 v6, v85, v6
	v_rcp_f32_e32 v71, v81
	s_nop 0
	v_mul_f32_e32 v71, v83, v71
	v_lshlrev_b32_e32 v86, 16, v77
	v_lshlrev_b32_e32 v87, 16, v76
	v_mul_f32_e32 v82, 0xbfb8aa3b, v87
	v_mul_f32_e32 v83, 0xbfb8aa3b, v86
	v_exp_f32_e32 v82, v82
	v_exp_f32_e32 v83, v83
	v_rcp_f32_e32 v70, v80
	s_nop 0
	v_mul_f32_e32 v70, v84, v70
	v_and_b32_e32 v88, 0xffff0000, v77
	v_pk_add_f32 v[80:81], v[82:83], 1.0 op_sel_hi:[1,0]
	v_and_b32_e32 v83, 0xffff0000, v76
	v_mul_f32_e32 v76, 0xbfb8aa3b, v83
	v_exp_f32_e32 v76, v76
	v_rcp_f32_e32 v85, v81
	s_nop 0
	v_mul_f32_e32 v85, v86, v85
	v_mul_f32_e32 v77, 0xbfb8aa3b, v88
	v_exp_f32_e32 v77, v77
	s_nop 0
	v_pk_add_f32 v[76:77], v[76:77], 1.0 op_sel_hi:[1,0]
	v_rcp_f32_e32 v84, v80
	s_nop 0
	v_mul_f32_e32 v84, v87, v84
	v_rcp_f32_e32 v87, v77
	s_nop 0
	v_mul_f32_e32 v87, v88, v87
	v_lshlrev_b32_e32 v90, 16, v78
	v_lshlrev_b32_e32 v82, 16, v79
	v_mul_f32_e32 v80, 0xbfb8aa3b, v90
	v_mul_f32_e32 v81, 0xbfb8aa3b, v82
	v_exp_f32_e32 v80, v80
	v_exp_f32_e32 v81, v81
	v_rcp_f32_e32 v86, v76
	s_nop 0
	v_mul_f32_e32 v86, v83, v86
	v_and_b32_e32 v83, 0xffff0000, v79
	v_pk_add_f32 v[76:77], v[80:81], 1.0 op_sel_hi:[1,0]
	v_mul_f32_e32 v78, 0xbfb8aa3b, v94
	v_exp_f32_e32 v78, v78
	v_rcp_f32_e32 v89, v77
	s_nop 0
	v_mul_f32_e32 v89, v82, v89
	v_mul_f32_e32 v79, 0xbfb8aa3b, v83
	v_exp_f32_e32 v79, v79
	s_nop 0
	v_pk_add_f32 v[80:81], v[78:79], 1.0 op_sel_hi:[1,0]
	v_rcp_f32_e32 v88, v76
	s_nop 0
	v_mul_f32_e32 v88, v90, v88
	v_rcp_f32_e32 v91, v81
	s_nop 0
	v_mul_f32_e32 v91, v83, v91
	ds_read_b128 v[76:79], v98
	v_rcp_f32_e32 v90, v80
	s_nop 0
	v_mul_f32_e32 v90, v94, v90
	ds_read_b128 v[80:83], v98 offset:16
	v_add_co_u32_e32 v30, vcc, s74, v30
	s_waitcnt lgkmcnt(1)
	v_mov_b32_e32 v96, v76
	v_mov_b32_e32 v97, v78
	v_pk_mul_f32 v[84:85], v[84:85], v[96:97]
	v_mov_b32_e32 v78, v77
	v_pk_mul_f32 v[76:77], v[86:87], v[78:79]
	v_cvt_pk_bf16_f32 v77, v85, v77
	v_cvt_pk_bf16_f32 v76, v84, v76
	s_waitcnt lgkmcnt(0)
	v_mov_b32_e32 v78, v80
	v_mov_b32_e32 v79, v82
	v_pk_mul_f32 v[78:79], v[88:89], v[78:79]
	v_mov_b32_e32 v82, v81
	v_pk_mul_f32 v[80:81], v[90:91], v[82:83]
	v_cvt_pk_bf16_f32 v79, v79, v81
	v_cvt_pk_bf16_f32 v78, v78, v80
	ds_read_b128 v[80:83], v95
	v_addc_co_u32_e32 v31, vcc, 0, v31, vcc
	global_store_dwordx4 v[30:31], v[76:79], off offset:2048
	s_nop 0
	ds_read_b128 v[76:79], v95 offset:16
	s_waitcnt lgkmcnt(1)
	v_mov_b32_e32 v30, v80
	v_mov_b32_e32 v31, v82
	v_pk_mul_f32 v[4:5], v[4:5], v[30:31]
	v_mov_b32_e32 v82, v81
	v_pk_mul_f32 v[30:31], v[68:69], v[82:83]
	v_cvt_pk_bf16_f32 v5, v5, v31
	v_cvt_pk_bf16_f32 v4, v4, v30
	s_waitcnt lgkmcnt(0)
	v_mov_b32_e32 v30, v76
	v_mov_b32_e32 v31, v78
	v_pk_mul_f32 v[6:7], v[6:7], v[30:31]
	v_mov_b32_e32 v78, v77
	v_pk_mul_f32 v[30:31], v[70:71], v[78:79]
	ds_read_b128 v[68:71], v93
	v_add_co_u32_e32 v26, vcc, s74, v26
	v_cvt_pk_bf16_f32 v7, v7, v31
	v_cvt_pk_bf16_f32 v6, v6, v30
	v_addc_co_u32_e32 v27, vcc, 0, v27, vcc
	global_store_dwordx4 v[26:27], v[4:7], off offset:2048
	s_waitcnt lgkmcnt(0)
; __device__ __forceinline__ unsigned pack2(float a, float b) { return (unsigned)f2bf(a) | ((unsigned)f2bf(b) << 16); }
; __device__ __forceinline__ float bflo(unsigned w) { return __uint_as_float(w << 16); }
; __device__ __forceinline__ float bfhi(unsigned w) { return __uint_as_float(w & 0xffff0000u); }
; __device__ __forceinline__ float silu_f(float g) { return g / (1.f + __expf(-g)); }
; __device__ void gmlp_item(const Params& p, int layer, int b, int n, int g, char* smem) {
;     ...
; #pragma unroll
;     for (int i = 0; i < 8; ++i) {
;       int q = tid + 256 * i, t = q >> 4, c = (q & 15) * 8;
;       float4 m0 = *reinterpret_cast<const float4*>(Tf + t * 132 + c);
;       float4 m1 = *reinterpret_cast<const float4*>(Tf + t * 132 + c + 4);
;       float mm[8] = {m0.x, m0.y, m0.z, m0.w, m1.x, m1.y, m1.z, m1.w};
;       unsigned uw[4] = {uu[i].x, uu[i].y, uu[i].z, uu[i].w};
;       unsigned gw[4] = {gt[i].x, gt[i].y, gt[i].z, gt[i].w};
;       unsigned ow[4];
; #pragma unroll
;       for (int e = 0; e < 4; ++e) {
;         float y0 = bflo(uw[e]) * mm[2 * e] * silu_f(bflo(gw[e]));
;         float y1 = bfhi(uw[e]) * mm[2 * e + 1] * silu_f(bfhi(gw[e]));
;         ow[e] = pack2(y0, y1);
;       }
;       *reinterpret_cast<uint4*>(Y + (t0 + t) * YW + g * 128 + c) = make_uint4(ow[0], ow[1], ow[2], ow[3]);
;     }
;   }
;   __syncthreads();
	v_mov_b32_e32 v26, v68
	v_mov_b32_e32 v27, v70
	ds_read_b128 v[4:7], v93 offset:16
	v_pk_mul_f32 v[0:1], v[0:1], v[26:27]
	v_mov_b32_e32 v70, v69
	v_pk_mul_f32 v[26:27], v[64:65], v[70:71]
	v_cvt_pk_bf16_f32 v1, v1, v27
	v_cvt_pk_bf16_f32 v0, v0, v26
	s_waitcnt lgkmcnt(0)
	v_mov_b32_e32 v26, v4
	v_mov_b32_e32 v27, v6
	v_pk_mul_f32 v[2:3], v[2:3], v[26:27]
	v_mov_b32_e32 v6, v5
	v_pk_mul_f32 v[4:5], v[66:67], v[6:7]
	v_cvt_pk_bf16_f32 v3, v3, v5
	v_cvt_pk_bf16_f32 v2, v2, v4
	ds_read_b128 v[4:7], v92
	v_add_co_u32_e32 v20, vcc, s74, v20
	s_nop 1
	v_addc_co_u32_e32 v21, vcc, 0, v21, vcc
	global_store_dwordx4 v[20:21], v[0:3], off offset:2048
	s_waitcnt lgkmcnt(0)
	v_mov_b32_e32 v20, v4
	v_mov_b32_e32 v21, v6
	ds_read_b128 v[0:3], v92 offset:16
	v_pk_mul_f32 v[20:21], v[56:57], v[20:21]
	v_mov_b32_e32 v6, v5
	v_pk_mul_f32 v[4:5], v[58:59], v[6:7]
	v_cvt_pk_bf16_f32 v5, v21, v5
	v_cvt_pk_bf16_f32 v4, v20, v4
	s_waitcnt lgkmcnt(0)
	v_mov_b32_e32 v6, v0
	v_mov_b32_e32 v7, v2
	v_pk_mul_f32 v[6:7], v[60:61], v[6:7]
	v_mov_b32_e32 v2, v1
	v_pk_mul_f32 v[0:1], v[62:63], v[2:3]
	v_cvt_pk_bf16_f32 v7, v7, v1
	v_cvt_pk_bf16_f32 v6, v6, v0
	ds_read_b128 v[0:3], v75
	v_add_co_u32_e32 v16, vcc, s74, v16
	s_nop 1
	v_addc_co_u32_e32 v17, vcc, 0, v17, vcc
	global_store_dwordx4 v[16:17], v[4:7], off offset:2048
	s_waitcnt lgkmcnt(0)
	v_mov_b32_e32 v16, v0
	v_mov_b32_e32 v17, v2
	ds_read_b128 v[4:7], v75 offset:16
	v_pk_mul_f32 v[16:17], v[48:49], v[16:17]
	v_mov_b32_e32 v2, v1
	v_pk_mul_f32 v[0:1], v[50:51], v[2:3]
	v_cvt_pk_bf16_f32 v1, v17, v1
	v_cvt_pk_bf16_f32 v0, v16, v0
	s_waitcnt lgkmcnt(0)
	v_mov_b32_e32 v2, v4
	v_mov_b32_e32 v3, v6
	v_pk_mul_f32 v[2:3], v[52:53], v[2:3]
	v_mov_b32_e32 v6, v5
	v_pk_mul_f32 v[4:5], v[54:55], v[6:7]
	v_cvt_pk_bf16_f32 v3, v3, v5
	v_cvt_pk_bf16_f32 v2, v2, v4
	ds_read_b128 v[4:7], v74
	v_add_co_u32_e32 v12, vcc, s74, v12
	s_nop 1
	v_addc_co_u32_e32 v13, vcc, 0, v13, vcc
	global_store_dwordx4 v[12:13], v[0:3], off offset:2048
	s_waitcnt lgkmcnt(0)
	v_mov_b32_e32 v12, v4
	v_mov_b32_e32 v13, v6
	ds_read_b128 v[0:3], v74 offset:16
	v_pk_mul_f32 v[12:13], v[40:41], v[12:13]
	v_mov_b32_e32 v6, v5
	v_pk_mul_f32 v[4:5], v[42:43], v[6:7]
	v_cvt_pk_bf16_f32 v5, v13, v5
	v_cvt_pk_bf16_f32 v4, v12, v4
	s_waitcnt lgkmcnt(0)
	v_mov_b32_e32 v6, v0
	v_mov_b32_e32 v7, v2
	v_pk_mul_f32 v[6:7], v[44:45], v[6:7]
	v_mov_b32_e32 v2, v1
	v_pk_mul_f32 v[0:1], v[46:47], v[2:3]
	v_cvt_pk_bf16_f32 v7, v7, v1
	v_cvt_pk_bf16_f32 v6, v6, v0
	ds_read_b128 v[0:3], v73
	v_add_co_u32_e32 v10, vcc, s74, v10
	s_nop 1
	v_addc_co_u32_e32 v11, vcc, 0, v11, vcc
	global_store_dwordx4 v[10:11], v[4:7], off offset:2048
	s_waitcnt lgkmcnt(0)
	v_mov_b32_e32 v10, v0
	v_mov_b32_e32 v11, v2
	ds_read_b128 v[4:7], v73 offset:16
	v_pk_mul_f32 v[10:11], v[32:33], v[10:11]
	v_mov_b32_e32 v2, v1
	v_pk_mul_f32 v[0:1], v[34:35], v[2:3]
	v_cvt_pk_bf16_f32 v1, v11, v1
	v_cvt_pk_bf16_f32 v0, v10, v0
	s_waitcnt lgkmcnt(0)
	v_mov_b32_e32 v2, v4
	v_mov_b32_e32 v3, v6
	v_pk_mul_f32 v[2:3], v[36:37], v[2:3]
	v_mov_b32_e32 v6, v5
	v_pk_mul_f32 v[4:5], v[38:39], v[6:7]
	v_cvt_pk_bf16_f32 v3, v3, v5
	v_cvt_pk_bf16_f32 v2, v2, v4
	ds_read_b128 v[4:7], v72
	v_add_co_u32_e32 v8, vcc, s74, v8
	s_nop 1
	v_addc_co_u32_e32 v9, vcc, 0, v9, vcc
	global_store_dwordx4 v[8:9], v[0:3], off offset:2048
	s_waitcnt lgkmcnt(0)
	v_mov_b32_e32 v8, v4
	v_mov_b32_e32 v9, v6
	ds_read_b128 v[0:3], v72 offset:16
	v_pk_mul_f32 v[8:9], v[18:19], v[8:9]
	v_mov_b32_e32 v6, v5
	v_pk_mul_f32 v[4:5], v[22:23], v[6:7]
	v_cvt_pk_bf16_f32 v5, v9, v5
	v_cvt_pk_bf16_f32 v4, v8, v4
	s_waitcnt lgkmcnt(0)
	v_mov_b32_e32 v6, v0
	v_mov_b32_e32 v7, v2
	v_pk_mul_f32 v[6:7], v[24:25], v[6:7]
	v_mov_b32_e32 v2, v1
	v_pk_mul_f32 v[0:1], v[28:29], v[2:3]
	v_cvt_pk_bf16_f32 v6, v6, v0
	v_add_co_u32_e32 v0, vcc, 0x184a1000, v14
	v_cvt_pk_bf16_f32 v7, v7, v1
	s_nop 0
	v_addc_co_u32_e32 v1, vcc, 0, v15, vcc
	global_store_dwordx4 v[0:1], v[4:7], off offset:2048
	s_barrier

; #define MFMA16(a, b, c) __builtin_amdgcn_mfma_f32_16x16x32_bf16(a, b, c, 0, 0, 0)
; __device__ void gmlp_item(const Params& p, int layer, int b, int n, int g, char* smem) {
;     ...
; #pragma unroll 2
;   for (int i = 0; i < 8; ++i) {
;     int q = tid + 256 * i;
;     int t = q >> 4, cch = q & 15;
;     uint4 v = *reinterpret_cast<const uint4*>(Ws + (size_t)g * 16384 + t * 128 + cch * 8);
;     *reinterpret_cast<uint4*>(smem + (cch >> 2) * 8192 + t * 64 + (cch & 3) * 16) = v;
;   }
;   __syncthreads();
;   f32x4 acc[4][4];
; #pragma unroll
;   for (int m = 0; m < 4; ++m)
; #pragma unroll
;     for (int nn = 0; nn < 4; ++nn) acc[m][nn] = f32x4{0.f, 0.f, 0.f, 0.f};
; #pragma unroll
;   for (int ks = 0; ks < 4; ++ks) {
;     bf16x8 a[4], bb[4];
; #pragma unroll
;     for (int m = 0; m < 4; ++m)
;       a[m] = *reinterpret_cast<const bf16x8*>(smem + ks * 8192 + (wr * 64 + m * 16 + fr) * 64 + fq * 16);
; #pragma unroll
;     for (int nn = 0; nn < 4; ++nn)
;       bb[nn] = *reinterpret_cast<const bf16x8*>(smem + 32768 + ks * 8192 + (wc * 64 + nn * 16 + fr) * 64 + fq * 16);
; #pragma unroll
;     for (int m = 0; m < 4; ++m)
; #pragma unroll
;       for (int nn = 0; nn < 4; ++nn) acc[m][nn] = MFMA16(a[m], bb[nn], acc[m][nn]);
;   }
.LBB0_159:
	v_add_u32_e32 v3, s6, v60
	v_ashrrev_i32_e32 v12, 4, v3
	v_add_u32_e32 v3, 0x100, v3
	v_ashrrev_i32_e32 v3, 4, v3
	v_lshlrev_b32_e32 v4, 7, v12
	v_lshlrev_b32_e32 v6, 7, v3
	v_ashrrev_i32_e32 v5, 31, v4
	v_ashrrev_i32_e32 v7, 31, v6
	v_lshl_add_u64 v[4:5], v[4:5], 1, v[0:1]
	v_lshl_add_u64 v[8:9], v[6:7], 1, v[0:1]
	global_load_dwordx4 v[4:7], v[4:5], off
	s_nop 0
	global_load_dwordx4 v[8:11], v[8:9], off
	s_addk_i32 s6, 0x200
	s_cmpk_lg_i32 s6, 0x800
	v_lshl_add_u32 v12, v12, 6, v2
	v_lshl_add_u32 v3, v3, 6, v2
	s_waitcnt vmcnt(1)
	ds_write_b128 v12, v[4:7]
	s_waitcnt vmcnt(0)
	ds_write_b128 v3, v[8:11]
	s_cbranch_scc1 .LBB0_159
	v_bfe_u32 v32, v60, 4, 2
	v_ashrrev_i32_e32 v33, 7, v60
	v_lshlrev_b32_e32 v4, 4, v32
	v_lshlrev_b32_e32 v0, 12, v33
	v_lshlrev_b32_e32 v5, 6, v35
	v_or3_b32 v37, v4, v0, v5
	s_waitcnt lgkmcnt(0)
	s_barrier
	ds_read_b128 v[0:3], v37
	v_bfe_u32 v39, v60, 6, 1
	v_lshlrev_b32_e32 v6, 12, v39
	v_or3_b32 v41, v4, v6, v5
	ds_read_b128 v[4:7], v41 offset:32768
	ds_read_b128 v[8:11], v37 offset:1024
	ds_read_b128 v[12:15], v41 offset:33792
	ds_read_b128 v[24:27], v41 offset:34816
	ds_read_b128 v[28:31], v41 offset:35840
	s_waitcnt lgkmcnt(4)
	v_mfma_f32_16x16x32_bf16 v[16:19], v[0:3], v[4:7], 0
	s_ashr_i32 s7, s9, 31
	s_add_u32 s6, s28, s9
	s_addc_u32 s7, s29, s7
	s_waitcnt lgkmcnt(2)
	v_mfma_f32_16x16x32_bf16 v[20:23], v[0:3], v[12:15], 0
	v_lshlrev_b32_e32 v33, 6, v33
	s_lshl_b32 s9, s8, 2
	v_lshl_or_b32 v32, v32, 2, v33
	s_waitcnt lgkmcnt(1)
	v_mfma_f32_16x16x32_bf16 v[50:53], v[0:3], v[24:27], 0
	s_add_u32 s10, s12, s9
	s_addc_u32 s11, s13, 0
	v_ashrrev_i32_e32 v33, 31, v32
	s_waitcnt lgkmcnt(0)
	v_mfma_f32_16x16x32_bf16 v[54:57], v[0:3], v[28:31], 0
	ds_read_b128 v[0:3], v37 offset:2048
	ds_read_b128 v[74:77], v37 offset:3072
	ds_read_b128 v[98:101], v37 offset:8192
	v_lshl_add_u64 v[58:59], v[32:33], 2, s[10:11]
	v_mfma_f32_16x16x32_bf16 v[62:65], v[8:11], v[4:7], 0
	v_lshlrev_b32_e32 v33, 2, v35
	v_lshl_or_b32 v126, v39, 8, v33
	v_mad_u64_u32 v[32:33], s[10:11], v32, s67, v[126:127]
	v_mfma_f32_16x16x32_bf16 v[66:69], v[8:11], v[12:15], 0
	v_add_u32_e32 v33, 0x400, v32
	v_ashrrev_i32_e32 v49, 31, v48
	v_ashrrev_i32_e32 v47, 31, v46
	v_mfma_f32_16x16x32_bf16 v[70:73], v[8:11], v[24:27], 0
	v_ashrrev_i32_e32 v45, 31, v44
	v_ashrrev_i32_e32 v43, 31, v42
	v_ashrrev_i32_e32 v39, 31, v38
	v_mfma_f32_16x16x32_bf16 v[8:11], v[8:11], v[28:31], 0
	s_waitcnt lgkmcnt(2)
	v_mfma_f32_16x16x32_bf16 v[78:81], v[0:3], v[4:7], 0
	v_mfma_f32_16x16x32_bf16 v[82:85], v[0:3], v[12:15], 0
	v_mfma_f32_16x16x32_bf16 v[86:89], v[0:3], v[24:27], 0
	v_mfma_f32_16x16x32_bf16 v[90:93], v[0:3], v[28:31], 0
	s_waitcnt lgkmcnt(1)
	v_mfma_f32_16x16x32_bf16 v[94:97], v[74:77], v[4:7], 0
	v_mfma_f32_16x16x32_bf16 v[12:15], v[74:77], v[12:15], 0
	v_mfma_f32_16x16x32_bf16 v[24:27], v[74:77], v[24:27], 0
	v_mfma_f32_16x16x32_bf16 v[0:3], v[74:77], v[28:31], 0
	ds_read_b128 v[28:31], v41 offset:40960
	ds_read_b128 v[74:77], v37 offset:9216
	ds_read_b128 v[102:105], v41 offset:41984
	ds_read_b128 v[106:109], v41 offset:43008
	ds_read_b128 v[4:7], v41 offset:44032
	s_waitcnt lgkmcnt(4)
	v_mfma_f32_16x16x32_bf16 v[16:19], v[98:101], v[28:31], v[16:19]
	s_waitcnt lgkmcnt(2)
	v_mfma_f32_16x16x32_bf16 v[20:23], v[98:101], v[102:105], v[20:23]
	s_waitcnt lgkmcnt(1)
	v_mfma_f32_16x16x32_bf16 v[50:53], v[98:101], v[106:109], v[50:53]
	s_waitcnt lgkmcnt(0)
	v_mfma_f32_16x16x32_bf16 v[54:57], v[98:101], v[4:7], v[54:57]
	ds_read_b128 v[98:101], v37 offset:10240
	v_mfma_f32_16x16x32_bf16 v[62:65], v[74:77], v[28:31], v[62:65]
	v_mfma_f32_16x16x32_bf16 v[66:69], v[74:77], v[102:105], v[66:69]
	v_mfma_f32_16x16x32_bf16 v[70:73], v[74:77], v[106:109], v[70:73]
	v_mfma_f32_16x16x32_bf16 v[8:11], v[74:77], v[4:7], v[8:11]
	ds_read_b128 v[74:77], v37 offset:11264
	ds_read_b128 v[110:113], v37 offset:16384
	ds_read_b128 v[114:117], v37 offset:17408
	ds_read_b128 v[118:121], v37 offset:18432
	ds_read_b128 v[122:125], v37 offset:19456
	ds_read_b128 v[134:137], v41 offset:49152
	ds_read_b128 v[138:141], v41 offset:50176
	ds_read_b128 v[146:149], v41 offset:51200
	ds_read_b128 v[150:153], v41 offset:52224
	ds_read_b128 v[162:165], v37 offset:24576
	ds_read_b128 v[166:169], v37 offset:25600
	s_waitcnt lgkmcnt(11)
	v_mfma_f32_16x16x32_bf16 v[78:81], v[98:101], v[28:31], v[78:81]
	v_mfma_f32_16x16x32_bf16 v[82:85], v[98:101], v[102:105], v[82:85]
	v_mfma_f32_16x16x32_bf16 v[86:89], v[98:101], v[106:109], v[86:89]
	v_mfma_f32_16x16x32_bf16 v[90:93], v[98:101], v[4:7], v[90:93]
	ds_read_b128 v[98:101], v37 offset:26624
	ds_read_b128 v[170:173], v37 offset:27648
	ds_read_b128 v[174:177], v41 offset:57344
	ds_read_b128 v[178:181], v41 offset:58368
	s_waitcnt lgkmcnt(14)
	v_mfma_f32_16x16x32_bf16 v[28:31], v[74:77], v[28:31], v[94:97]
	s_nop 2
	ds_read_b128 v[94:97], v41 offset:59392
	ds_read_b128 v[182:185], v41 offset:60416
	s_waitcnt lgkmcnt(0)
	s_barrier
; #define MFMA16(a, b, c) __builtin_amdgcn_mfma_f32_16x16x32_bf16(a, b, c, 0, 0, 0)
; __device__ void gmlp_item(const Params& p, int layer, int b, int n, int g, char* smem) {
;     ...
;   for (int ks = 0; ks < 4; ++ks) {
;     bf16x8 a[4], bb[4];
; #pragma unroll
;     for (int m = 0; m < 4; ++m)
;       a[m] = *reinterpret_cast<const bf16x8*>(smem + ks * 8192 + (wr * 64 + m * 16 + fr) * 64 + fq * 16);
; #pragma unroll
;     for (int nn = 0; nn < 4; ++nn)
;       bb[nn] = *reinterpret_cast<const bf16x8*>(smem + 32768 + ks * 8192 + (wc * 64 + nn * 16 + fr) * 64 + fq * 16);
; #pragma unroll
;     for (int m = 0; m < 4; ++m)
; #pragma unroll
;       for (int nn = 0; nn < 4; ++nn) acc[m][nn] = MFMA16(a[m], bb[nn], acc[m][nn]);
;   }
;   __syncthreads();
;   {
;     float* Tf = reinterpret_cast<float*>(smem);
; #pragma unroll
;     for (int m = 0; m < 4; ++m)
; #pragma unroll
;       for (int j = 0; j < 4; ++j) {
;         int t = wr * 64 + m * 16 + fq * 4 + j;
;         float bias = p.gm_b_s[(size_t)layer * 512 + g * 128 + t];
; #pragma unroll
;         for (int nn = 0; nn < 4; ++nn) Tf[t * 132 + wc * 64 + nn * 16 + fr] = acc[m][nn][j] + bias;
;       }
	v_mfma_f32_16x16x32_bf16 v[16:19], v[110:113], v[134:137], v[16:19]
	global_load_dwordx4 v[186:189], v[58:59], off offset:64
	global_load_dwordx4 v[190:193], v[58:59], off offset:128
	v_mfma_f32_16x16x32_bf16 v[20:23], v[110:113], v[138:141], v[20:23]
	v_ashrrev_i32_e32 v41, 31, v40
	v_mfma_f32_16x16x32_bf16 v[50:53], v[110:113], v[146:149], v[50:53]
	v_mfma_f32_16x16x32_bf16 v[54:57], v[110:113], v[150:153], v[54:57]
	global_load_dwordx4 v[110:113], v[58:59], off
	v_mfma_f32_16x16x32_bf16 v[16:19], v[162:165], v[174:177], v[16:19]
	v_mfma_f32_16x16x32_bf16 v[20:23], v[162:165], v[178:181], v[20:23]
	v_mfma_f32_16x16x32_bf16 v[50:53], v[162:165], v[94:97], v[50:53]
	s_waitcnt vmcnt(0)
	s_nop 4
	v_add_f32_e32 v16, v16, v110
	v_mfma_f32_16x16x32_bf16 v[54:57], v[162:165], v[182:185], v[54:57]
	v_add_f32_e32 v20, v20, v110
	ds_write2_b32 v32, v16, v20 offset1:16
	v_add_f32_e32 v16, v50, v110
	v_add_f32_e32 v35, v53, v113
	v_mfma_f32_16x16x32_bf16 v[62:65], v[114:117], v[134:137], v[62:65]
	s_nop 2
	v_add_f32_e32 v20, v54, v110
	ds_write2_b32 v32, v16, v20 offset0:32 offset1:48
	v_add_f32_e32 v16, v17, v111
	v_add_f32_e32 v17, v21, v111
	ds_write2_b32 v32, v16, v17 offset0:132 offset1:148
	v_add_f32_e32 v16, v51, v111
	v_add_f32_e32 v17, v55, v111
	ds_write2_b32 v32, v16, v17 offset0:164 offset1:180
	v_add_f32_e32 v16, v18, v112
	v_add_f32_e32 v17, v22, v112
	ds_write2_b32 v33, v16, v17 offset0:8 offset1:24
	v_add_f32_e32 v16, v52, v112
	global_load_dwordx4 v[50:53], v[58:59], off offset:192
	v_mfma_f32_16x16x32_bf16 v[66:69], v[114:117], v[138:141], v[66:69]
	v_add_f32_e32 v17, v56, v112
	v_add_f32_e32 v20, v19, v113
	v_add_f32_e32 v21, v23, v113
	v_mfma_f32_16x16x32_bf16 v[70:73], v[114:117], v[146:149], v[70:73]
	ds_write2_b32 v33, v16, v17 offset0:40 offset1:56
	ds_write2_b32 v33, v20, v21 offset0:140 offset1:156
	v_add_f32_e32 v37, v57, v113
	v_mfma_f32_16x16x32_bf16 v[8:11], v[114:117], v[150:153], v[8:11]
	ds_write2_b32 v33, v35, v37 offset0:172 offset1:188
	v_add_u32_e32 v33, 0x2000, v32
	v_ashrrev_i32_e32 v35, 31, v34
	v_mfma_f32_16x16x32_bf16 v[16:19], v[166:169], v[174:177], v[62:65]
	v_ashrrev_i32_e32 v37, 31, v36
	v_lshl_add_u64 v[58:59], v[42:43], 0, s[26:27]
	v_mfma_f32_16x16x32_bf16 v[20:23], v[166:169], v[178:181], v[66:69]
	v_mfma_f32_16x16x32_bf16 v[54:57], v[166:169], v[94:97], v[70:73]
	s_nop 3
	v_add_f32_e32 v16, v16, v186
	s_nop 1
	v_add_f32_e32 v20, v20, v186
	ds_write2_b32 v33, v16, v20 offset0:64 offset1:80
	v_mfma_f32_16x16x32_bf16 v[8:11], v[166:169], v[182:185], v[8:11]
	v_add_u32_e32 v20, 0x2400, v32
	v_add_f32_e32 v16, v54, v186
	v_mfma_f32_16x16x32_bf16 v[62:65], v[118:121], v[134:137], v[78:81]
	v_mfma_f32_16x16x32_bf16 v[66:69], v[118:121], v[138:141], v[82:85]
	s_nop 3
	v_add_f32_e32 v8, v8, v186
	ds_write2_b32 v33, v16, v8 offset0:96 offset1:112
	v_add_f32_e32 v8, v17, v187
	v_add_f32_e32 v16, v21, v187
	ds_write2_b32 v33, v8, v16 offset0:196 offset1:212
	v_add_f32_e32 v8, v55, v187
	v_add_f32_e32 v9, v9, v187
	ds_write2_b32 v33, v8, v9 offset0:228 offset1:244
	v_add_f32_e32 v8, v18, v188
	v_add_f32_e32 v9, v22, v188
	v_mfma_f32_16x16x32_bf16 v[70:73], v[118:121], v[146:149], v[86:89]
	ds_write2_b32 v20, v8, v9 offset0:72 offset1:88
	v_add_f32_e32 v8, v56, v188
	v_add_f32_e32 v9, v10, v188
	v_mfma_f32_16x16x32_bf16 v[78:81], v[118:121], v[150:153], v[90:93]
	ds_write2_b32 v20, v8, v9 offset0:104 offset1:120
	v_add_f32_e32 v8, v19, v189
	v_add_f32_e32 v9, v23, v189
	v_mfma_f32_16x16x32_bf16 v[16:19], v[98:101], v[174:177], v[62:65]
	ds_write2_b32 v20, v8, v9 offset0:204 offset1:220
	v_add_f32_e32 v21, v57, v189
	v_add_f32_e32 v22, v11, v189
	v_mfma_f32_16x16x32_bf16 v[8:11], v[98:101], v[178:181], v[66:69]
	ds_write2_b32 v20, v21, v22 offset0:236 offset1:252
	s_nop 2
	v_add_f32_e32 v16, v16, v190
	v_add_u32_e32 v33, 0x4000, v32
	v_mfma_f32_16x16x32_bf16 v[20:23], v[98:101], v[94:97], v[70:73]
	v_lshl_add_u64 v[62:63], v[38:39], 0, s[26:27]
	v_add_f32_e32 v8, v8, v190
	ds_write2_b32 v33, v16, v8 offset0:128 offset1:144
	v_mfma_f32_16x16x32_bf16 v[54:57], v[98:101], v[182:185], v[78:81]
	v_add_f32_e32 v10, v10, v192
	s_nop 2
	v_add_f32_e32 v8, v20, v190
	v_mfma_f32_16x16x32_bf16 v[12:15], v[74:77], v[102:105], v[12:15]
	v_mfma_f32_16x16x32_bf16 v[24:27], v[74:77], v[106:109], v[24:27]
	s_nop 0
	v_add_f32_e32 v16, v54, v190
	ds_write2_b32 v33, v8, v16 offset0:160 offset1:176
	v_add_f32_e32 v8, v17, v191
	v_mfma_f32_16x16x32_bf16 v[0:3], v[74:77], v[4:7], v[0:3]
	v_add_f32_e32 v4, v9, v191
	v_add_u32_e32 v9, 0x4400, v32
	ds_write2_b32 v9, v8, v4 offset0:4 offset1:20
	v_mfma_f32_16x16x32_bf16 v[4:7], v[122:125], v[134:137], v[28:31]
	v_add_f32_e32 v8, v21, v191
	v_add_f32_e32 v16, v55, v191
	ds_write2_b32 v9, v8, v16 offset0:36 offset1:52
	v_mfma_f32_16x16x32_bf16 v[12:15], v[122:125], v[138:141], v[12:15]
	v_add_f32_e32 v8, v18, v192
	ds_write2_b32 v9, v8, v10 offset0:136 offset1:152
	v_add_f32_e32 v8, v22, v192
	v_mfma_f32_16x16x32_bf16 v[24:27], v[122:125], v[146:149], v[24:27]
	v_add_f32_e32 v10, v56, v192
	ds_write2_b32 v9, v8, v10 offset0:168 offset1:184
	v_add_f32_e32 v8, v19, v193
	v_mfma_f32_16x16x32_bf16 v[0:3], v[122:125], v[150:153], v[0:3]
	v_add_f32_e32 v9, v11, v193
	v_add_u32_e32 v16, 0x4800, v32
	ds_write2_b32 v16, v8, v9 offset0:12 offset1:28
	v_mfma_f32_16x16x32_bf16 v[4:7], v[170:173], v[174:177], v[4:7]
	v_add_f32_e32 v17, v23, v193
	v_add_f32_e32 v18, v57, v193
	ds_write2_b32 v16, v17, v18 offset0:44 offset1:60
	v_mfma_f32_16x16x32_bf16 v[8:11], v[170:173], v[178:181], v[12:15]
	v_add_u32_e32 v16, 0x6000, v32
	s_waitcnt vmcnt(0)
; __device__ __forceinline__ unsigned pack2(float a, float b) { return (unsigned)f2bf(a) | ((unsigned)f2bf(b) << 16); }
; __device__ __forceinline__ float bflo(unsigned w) { return __uint_as_float(w << 16); }
; __device__ __forceinline__ float bfhi(unsigned w) { return __uint_as_float(w & 0xffff0000u); }
; __device__ __forceinline__ float silu_f(float g) { return g / (1.f + __expf(-g)); }
; __device__ void gmlp_item(const Params& p, int layer, int b, int n, int g, char* smem) {
;     ...
;         for (int nn = 0; nn < 4; ++nn) Tf[t * 132 + wc * 64 + nn * 16 + fr] = acc[m][nn][j] + bias;
;       }
;     __syncthreads();
;     uint4 uu[8], gt[8];
; #pragma unroll
;     for (int i = 0; i < 8; ++i) {
;       int q = tid + 256 * i, t = q >> 4, c = (q & 15) * 8;
;       uu[i] = *reinterpret_cast<const uint4*>(P + (t0 + t) * NP + g * 128 + c);
;       gt[i] = *reinterpret_cast<const uint4*>(P + (t0 + t) * NP + 1024 + g * 128 + c);
;     }
; #pragma unroll
;     for (int i = 0; i < 8; ++i) {
;       int q = tid + 256 * i, t = q >> 4, c = (q & 15) * 8;
;       float4 m0 = *reinterpret_cast<const float4*>(Tf + t * 132 + c);
;       float4 m1 = *reinterpret_cast<const float4*>(Tf + t * 132 + c + 4);
;       float mm[8] = {m0.x, m0.y, m0.z, m0.w, m1.x, m1.y, m1.z, m1.w};
;       unsigned uw[4] = {uu[i].x, uu[i].y, uu[i].z, uu[i].w};
;       unsigned gw[4] = {gt[i].x, gt[i].y, gt[i].z, gt[i].w};
;       unsigned ow[4];
; #pragma unroll
;       for (int e = 0; e < 4; ++e) {
;         float y0 = bflo(uw[e]) * mm[2 * e] * silu_f(bflo(gw[e]));
;         float y1 = bfhi(uw[e]) * mm[2 * e + 1] * silu_f(bfhi(gw[e]));
;         ow[e] = pack2(y0, y1);
;       }
;       *reinterpret_cast<uint4*>(Y + (t0 + t) * YW + g * 128 + c) = make_uint4(ow[0], ow[1], ow[2], ow[3]);
	s_nop 1
	v_add_f32_e32 v4, v4, v50
	v_lshl_add_u64 v[56:57], v[36:37], 0, s[26:27]
	v_mfma_f32_16x16x32_bf16 v[12:15], v[170:173], v[94:97], v[24:27]
	v_lshl_add_u64 v[20:21], v[44:45], 0, s[26:27]
	v_add_f32_e32 v8, v8, v50
	ds_write2_b32 v16, v4, v8 offset0:192 offset1:208
	v_mfma_f32_16x16x32_bf16 v[0:3], v[170:173], v[182:185], v[0:3]
	s_nop 3
	v_add_f32_e32 v4, v12, v50
	s_nop 2
	v_add_f32_e32 v0, v0, v50
	ds_write2_b32 v16, v4, v0 offset0:224 offset1:240
	v_add_f32_e32 v0, v5, v51
	v_add_f32_e32 v4, v9, v51
	v_add_u32_e32 v5, 0x6400, v32
	ds_write2_b32 v5, v0, v4 offset0:68 offset1:84
	v_add_f32_e32 v0, v13, v51
	v_add_f32_e32 v1, v1, v51
	ds_write2_b32 v5, v0, v1 offset0:100 offset1:116
	v_add_f32_e32 v0, v6, v52
	v_add_f32_e32 v1, v10, v52
	ds_write2_b32 v5, v0, v1 offset0:200 offset1:216
	v_add_f32_e32 v0, v14, v52
	v_add_f32_e32 v1, v2, v52
	ds_write2_b32 v5, v0, v1 offset0:232 offset1:248
	v_add_f32_e32 v0, v7, v53
	v_add_f32_e32 v1, v11, v53
	v_add_u32_e32 v2, 0x6800, v32
	ds_write2_b32 v2, v0, v1 offset0:76 offset1:92
	v_add_f32_e32 v0, v15, v53
	v_add_f32_e32 v1, v3, v53
	ds_write2_b32 v2, v0, v1 offset0:108 offset1:124
	v_lshlrev_b32_e32 v0, 3, v60
	v_lshl_add_u64 v[8:9], v[34:35], 0, s[26:27]
	v_mov_b64_e32 v[10:11], s[4:5]
	v_and_b32_e32 v24, 0x78, v0
	v_mad_u64_u32 v[0:1], s[4:5], v8, s55, v[10:11]
	v_mad_i32_i24 v1, v9, s55, v1
	s_lshl_b32 s4, s8, 1
	s_mov_b32 s5, s27
	v_lshl_add_u64 v[0:1], v[0:1], 0, s[4:5]
	v_lshlrev_b32_e32 v128, 1, v24
	v_lshl_add_u64 v[12:13], v[48:49], 0, s[26:27]
	v_lshl_add_u64 v[52:53], v[0:1], 0, v[128:129]
	v_mad_u64_u32 v[0:1], s[8:9], v12, s55, v[10:11]
	v_mad_i32_i24 v1, v13, s55, v1
	v_lshl_add_u64 v[0:1], v[0:1], 0, s[4:5]
	v_lshl_add_u64 v[32:33], v[0:1], 0, v[128:129]
	v_mad_u64_u32 v[0:1], s[8:9], v56, s55, v[10:11]
	v_mad_i32_i24 v1, v57, s55, v1
	v_lshl_add_u64 v[0:1], v[0:1], 0, s[4:5]
	v_lshl_add_u64 v[4:5], v[0:1], 0, v[128:129]
	s_waitcnt lgkmcnt(0)
	s_barrier
	global_load_dwordx4 v[0:3], v[4:5], off
	s_nop 0
	global_load_dwordx4 v[4:7], v[4:5], off offset:2048
	v_lshl_add_u64 v[16:17], v[46:47], 0, s[26:27]
	v_mad_u64_u32 v[14:15], s[8:9], v16, s55, v[10:11]
	v_mad_i32_i24 v15, v17, s55, v15
	v_lshl_add_u64 v[14:15], v[14:15], 0, s[4:5]
	v_lshl_add_u64 v[30:31], v[14:15], 0, v[128:129]
	v_mad_u64_u32 v[14:15], s[8:9], v20, s55, v[10:11]
	v_mad_i32_i24 v15, v21, s55, v15
	v_lshl_add_u64 v[14:15], v[14:15], 0, s[4:5]
	v_lshl_add_u64 v[26:27], v[14:15], 0, v[128:129]
	v_mad_u64_u32 v[14:15], s[8:9], v58, s55, v[10:11]
	v_mad_i32_i24 v15, v59, s55, v15
	v_lshl_add_u64 v[14:15], v[14:15], 0, s[4:5]
	v_lshl_add_u64 v[60:61], v[40:41], 0, s[26:27]
	v_lshl_add_u64 v[22:23], v[14:15], 0, v[128:129]
	v_mad_u64_u32 v[14:15], s[8:9], v60, s55, v[10:11]
	v_mad_u64_u32 v[10:11], s[8:9], v62, s55, v[10:11]
	v_mad_i32_i24 v15, v61, s55, v15
	v_mad_i32_i24 v11, v63, s55, v11
	v_lshl_add_u64 v[14:15], v[14:15], 0, s[4:5]
	v_lshl_add_u64 v[10:11], v[10:11], 0, s[4:5]
	s_add_u32 s4, s6, s4
	s_addc_u32 s5, s7, 0
	v_lshl_add_u64 v[18:19], v[14:15], 0, v[128:129]
	v_lshl_add_u64 v[14:15], v[10:11], 0, v[128:129]
	v_lshlrev_b32_e32 v10, 2, v24
	v_lshl_add_u64 v[24:25], s[4:5], 0, v[128:129]
	v_lshl_add_u64 v[64:65], v[24:25], 0, s[40:41]
	v_mad_u64_u32 v[54:55], s[4:5], v34, s67, v[10:11]
	v_mad_u64_u32 v[34:35], s[4:5], v48, s67, v[10:11]
	v_mad_u64_u32 v[48:49], s[4:5], v12, s68, v[64:65]
	v_mad_u64_u32 v[28:29], s[4:5], v46, s67, v[10:11]
	v_mad_u64_u32 v[46:47], s[4:5], v16, s68, v[64:65]
	v_mad_u64_u32 v[50:51], s[4:5], v8, s68, v[64:65]
	v_mad_i32_i24 v49, v13, s68, v49
	v_mad_i32_i24 v47, v17, s68, v47
	v_mad_u64_u32 v[24:25], s[4:5], v44, s67, v[10:11]
	v_mad_u64_u32 v[44:45], s[4:5], v20, s68, v[64:65]
	v_mad_u64_u32 v[16:17], s[4:5], v40, s67, v[10:11]
	v_mad_u64_u32 v[12:13], s[4:5], v38, s67, v[10:11]
	v_mad_i32_i24 v51, v9, s68, v51
	v_mad_i32_i24 v45, v21, s68, v45
	v_mad_u64_u32 v[20:21], s[4:5], v42, s67, v[10:11]
	v_mad_u64_u32 v[8:9], s[4:5], v36, s67, v[10:11]
	v_mad_u64_u32 v[40:41], s[4:5], v60, s68, v[64:65]
	v_mad_i32_i24 v41, v61, s68, v41
	v_mad_u64_u32 v[42:43], s[4:5], v58, s68, v[64:65]
	v_mad_u64_u32 v[36:37], s[4:5], v56, s68, v[64:65]
	v_mad_i32_i24 v43, v59, s68, v43
	v_mad_i32_i24 v37, v57, s68, v37
	v_mad_u64_u32 v[38:39], s[4:5], v62, s68, v[64:65]
	v_mad_i32_i24 v39, v63, s68, v39
	s_waitcnt vmcnt(1)
	v_lshlrev_b32_e32 v63, 16, v1
	s_waitcnt vmcnt(0)
	v_lshlrev_b32_e32 v13, 16, v5
	v_lshlrev_b32_e32 v17, 16, v4
	v_mul_f32_e32 v9, 0xbfb8aa3b, v17
	v_and_b32_e32 v21, 0xffff0000, v5
	v_mul_f32_e32 v5, 0xbfb8aa3b, v13
	v_exp_f32_e32 v60, v9
	v_exp_f32_e32 v61, v5
	ds_read_b128 v[56:59], v8
	ds_read_b128 v[8:11], v8 offset:16
	v_and_b32_e32 v25, 0xffff0000, v4
	v_mul_f32_e32 v4, 0xbfb8aa3b, v25
	v_pk_add_f32 v[60:61], v[60:61], 1.0 op_sel_hi:[1,0]
	s_waitcnt lgkmcnt(1)
	v_mov_b32_e32 v64, v56
	v_exp_f32_e32 v4, v4
	v_lshlrev_b32_e32 v62, 16, v0
	v_mov_b32_e32 v65, v58
	v_rcp_f32_e32 v61, v61
	s_nop 0
	v_mul_f32_e32 v61, v13, v61
	v_and_b32_e32 v1, 0xffff0000, v1
	v_mul_f32_e32 v5, 0xbfb8aa3b, v21
	v_exp_f32_e32 v5, v5
	v_rcp_f32_e32 v60, v60
	s_nop 0
	v_mul_f32_e32 v60, v17, v60
	v_and_b32_e32 v0, 0xffff0000, v0
	v_mov_b32_e32 v58, v57
	v_pk_add_f32 v[4:5], v[4:5], 1.0 op_sel_hi:[1,0]
	v_pk_mul_f32 v[0:1], v[58:59], v[0:1]
	v_pk_mul_f32 v[62:63], v[64:65], v[62:63]
	v_rcp_f32_e32 v5, v5
	s_nop 0
	v_mul_f32_e32 v5, v21, v5
	v_pk_mul_f32 v[60:61], v[60:61], v[62:63]
	v_rcp_f32_e32 v4, v4
	s_nop 0
	v_mul_f32_e32 v4, v25, v4
	v_pk_mul_f32 v[0:1], v[4:5], v[0:1]
	v_lshlrev_b32_e32 v13, 16, v7
	v_lshlrev_b32_e32 v17, 16, v6
	v_cvt_pk_bf16_f32 v1, v61, v1
	v_cvt_pk_bf16_f32 v0, v60, v0
	v_mul_f32_e32 v4, 0xbfb8aa3b, v17
	v_mul_f32_e32 v5, 0xbfb8aa3b, v13
	v_exp_f32_e32 v4, v4
	v_exp_f32_e32 v5, v5
	v_and_b32_e32 v25, 0xffff0000, v6
	v_mul_f32_e32 v6, 0xbfb8aa3b, v25
	v_and_b32_e32 v21, 0xffff0000, v7
	v_exp_f32_e32 v60, v6
	v_pk_add_f32 v[64:65], v[4:5], 1.0 op_sel_hi:[1,0]
	global_load_dwordx4 v[4:7], v[14:15], off
	global_load_dwordx4 v[56:59], v[14:15], off offset:2048
	s_waitcnt lgkmcnt(0)
; __device__ __forceinline__ unsigned pack2(float a, float b) { return (unsigned)f2bf(a) | ((unsigned)f2bf(b) << 16); }
; __device__ __forceinline__ float bflo(unsigned w) { return __uint_as_float(w << 16); }
; __device__ __forceinline__ float bfhi(unsigned w) { return __uint_as_float(w & 0xffff0000u); }
; __device__ __forceinline__ float silu_f(float g) { return g / (1.f + __expf(-g)); }
; __device__ void gmlp_item(const Params& p, int layer, int b, int n, int g, char* smem) {
;     ...
;       int q = tid + 256 * i, t = q >> 4, c = (q & 15) * 8;
;       uu[i] = *reinterpret_cast<const uint4*>(P + (t0 + t) * NP + g * 128 + c);
;       gt[i] = *reinterpret_cast<const uint4*>(P + (t0 + t) * NP + 1024 + g * 128 + c);
;     }
; #pragma unroll
;     for (int i = 0; i < 8; ++i) {
;       int q = tid + 256 * i, t = q >> 4, c = (q & 15) * 8;
;       float4 m0 = *reinterpret_cast<const float4*>(Tf + t * 132 + c);
;       float4 m1 = *reinterpret_cast<const float4*>(Tf + t * 132 + c + 4);
;       float mm[8] = {m0.x, m0.y, m0.z, m0.w, m1.x, m1.y, m1.z, m1.w};
;       unsigned uw[4] = {uu[i].x, uu[i].y, uu[i].z, uu[i].w};
;       unsigned gw[4] = {gt[i].x, gt[i].y, gt[i].z, gt[i].w};
;       unsigned ow[4];
; #pragma unroll
;       for (int e = 0; e < 4; ++e) {
;         float y0 = bflo(uw[e]) * mm[2 * e] * silu_f(bflo(gw[e]));
;         float y1 = bfhi(uw[e]) * mm[2 * e + 1] * silu_f(bfhi(gw[e]));
;         ow[e] = pack2(y0, y1);
;       }
;       *reinterpret_cast<uint4*>(Y + (t0 + t) * YW + g * 128 + c) = make_uint4(ow[0], ow[1], ow[2], ow[3]);
	v_mov_b32_e32 v14, v8
	v_mov_b32_e32 v15, v10
	v_lshlrev_b32_e32 v63, 16, v3
	v_lshlrev_b32_e32 v62, 16, v2
	v_pk_mul_f32 v[14:15], v[14:15], v[62:63]
	v_rcp_f32_e32 v63, v65
	s_nop 0
	v_mul_f32_e32 v63, v13, v63
	v_mul_f32_e32 v10, 0xbfb8aa3b, v21
	v_exp_f32_e32 v61, v10
	v_rcp_f32_e32 v62, v64
	s_nop 0
	v_mul_f32_e32 v62, v17, v62
	v_mov_b32_e32 v10, v9
	v_and_b32_e32 v3, 0xffff0000, v3
	v_pk_add_f32 v[60:61], v[60:61], 1.0 op_sel_hi:[1,0]
	v_and_b32_e32 v2, 0xffff0000, v2
	v_pk_mul_f32 v[2:3], v[10:11], v[2:3]
	v_pk_mul_f32 v[14:15], v[62:63], v[14:15]
	v_rcp_f32_e32 v9, v61
	s_nop 0
	v_mul_f32_e32 v9, v21, v9
	v_rcp_f32_e32 v8, v60
	s_nop 0
	v_mul_f32_e32 v8, v25, v8
	v_pk_mul_f32 v[2:3], v[8:9], v[2:3]
	v_cvt_pk_bf16_f32 v3, v15, v3
	v_cvt_pk_bf16_f32 v2, v14, v2
	s_waitcnt vmcnt(0)
	v_lshlrev_b32_e32 v21, 16, v56
	v_mul_f32_e32 v8, 0xbfb8aa3b, v21
	v_and_b32_e32 v29, 0xffff0000, v56
	v_lshlrev_b32_e32 v17, 16, v57
	v_exp_f32_e32 v60, v8
	v_mul_f32_e32 v8, 0xbfb8aa3b, v29
	v_exp_f32_e32 v56, v8
	v_mul_f32_e32 v8, 0xbfb8aa3b, v17
	v_exp_f32_e32 v61, v8
	ds_read_b128 v[8:11], v12
	ds_read_b128 v[12:15], v12 offset:16
	v_and_b32_e32 v25, 0xffff0000, v57
	v_lshlrev_b32_e32 v63, 16, v5
	v_pk_add_f32 v[60:61], v[60:61], 1.0 op_sel_hi:[1,0]
	s_waitcnt lgkmcnt(1)
	v_mov_b32_e32 v64, v8
	v_mov_b32_e32 v65, v10
	v_lshlrev_b32_e32 v62, 16, v4
	v_and_b32_e32 v5, 0xffff0000, v5
	v_rcp_f32_e32 v61, v61
	s_nop 0
	v_mul_f32_e32 v61, v17, v61
	v_and_b32_e32 v4, 0xffff0000, v4
	v_mul_f32_e32 v10, 0xbfb8aa3b, v25
	v_exp_f32_e32 v57, v10
	v_rcp_f32_e32 v60, v60
	s_nop 0
	v_mul_f32_e32 v60, v21, v60
	v_mov_b32_e32 v10, v9
	v_pk_mul_f32 v[4:5], v[10:11], v[4:5]
	v_pk_add_f32 v[56:57], v[56:57], 1.0 op_sel_hi:[1,0]
	v_pk_mul_f32 v[62:63], v[64:65], v[62:63]
	v_pk_mul_f32 v[60:61], v[60:61], v[62:63]
	v_lshlrev_b32_e32 v63, 16, v7
	v_lshlrev_b32_e32 v62, 16, v6
	v_rcp_f32_e32 v9, v57
	s_nop 0
	v_mul_f32_e32 v9, v25, v9
	v_rcp_f32_e32 v8, v56
	s_nop 0
	v_mul_f32_e32 v8, v29, v8
	v_pk_mul_f32 v[4:5], v[8:9], v[4:5]
	v_lshlrev_b32_e32 v17, 16, v59
	v_lshlrev_b32_e32 v21, 16, v58
	v_cvt_pk_bf16_f32 v5, v61, v5
	v_cvt_pk_bf16_f32 v4, v60, v4
	v_mul_f32_e32 v8, 0xbfb8aa3b, v21
	v_mul_f32_e32 v9, 0xbfb8aa3b, v17
	v_exp_f32_e32 v8, v8
	v_exp_f32_e32 v9, v9
	v_and_b32_e32 v29, 0xffff0000, v58
	v_mul_f32_e32 v10, 0xbfb8aa3b, v29
	v_and_b32_e32 v25, 0xffff0000, v59
	v_exp_f32_e32 v60, v10
	v_pk_add_f32 v[64:65], v[8:9], 1.0 op_sel_hi:[1,0]
	global_load_dwordx4 v[8:11], v[18:19], off
	global_load_dwordx4 v[56:59], v[18:19], off offset:2048
	s_waitcnt lgkmcnt(0)
	v_mov_b32_e32 v18, v12
	v_mov_b32_e32 v19, v14
	v_pk_mul_f32 v[18:19], v[18:19], v[62:63]
	v_rcp_f32_e32 v63, v65
	s_nop 0
	v_mul_f32_e32 v63, v17, v63
	v_and_b32_e32 v7, 0xffff0000, v7
	v_mul_f32_e32 v14, 0xbfb8aa3b, v25
	v_exp_f32_e32 v61, v14
	v_rcp_f32_e32 v62, v64
	s_nop 0
	v_mul_f32_e32 v62, v21, v62
	v_mov_b32_e32 v14, v13
	v_and_b32_e32 v6, 0xffff0000, v6
	v_pk_add_f32 v[60:61], v[60:61], 1.0 op_sel_hi:[1,0]
	v_pk_mul_f32 v[6:7], v[14:15], v[6:7]
	v_pk_mul_f32 v[18:19], v[62:63], v[18:19]
	v_rcp_f32_e32 v13, v61
	s_nop 0
	v_mul_f32_e32 v13, v25, v13
	v_rcp_f32_e32 v12, v60
	s_nop 0
	v_mul_f32_e32 v12, v29, v12
	v_pk_mul_f32 v[6:7], v[12:13], v[6:7]
	v_cvt_pk_bf16_f32 v7, v19, v7
	v_cvt_pk_bf16_f32 v6, v18, v6
	s_waitcnt vmcnt(1)
	v_lshlrev_b32_e32 v63, 16, v9
	s_waitcnt vmcnt(0)
	v_lshlrev_b32_e32 v25, 16, v56
	v_mul_f32_e32 v12, 0xbfb8aa3b, v25
	v_and_b32_e32 v35, 0xffff0000, v56
	v_lshlrev_b32_e32 v21, 16, v57
	v_exp_f32_e32 v60, v12
	v_mul_f32_e32 v12, 0xbfb8aa3b, v35
	v_exp_f32_e32 v56, v12
	v_mul_f32_e32 v12, 0xbfb8aa3b, v21
	v_exp_f32_e32 v61, v12
	v_and_b32_e32 v29, 0xffff0000, v57
	ds_read_b128 v[12:15], v16
	ds_read_b128 v[16:19], v16 offset:16
	v_lshlrev_b32_e32 v62, 16, v8
	v_pk_add_f32 v[60:61], v[60:61], 1.0 op_sel_hi:[1,0]
	v_and_b32_e32 v9, 0xffff0000, v9
	s_waitcnt lgkmcnt(1)
	v_mov_b32_e32 v64, v12
	v_mov_b32_e32 v65, v14
	v_pk_mul_f32 v[62:63], v[64:65], v[62:63]
	v_rcp_f32_e32 v61, v61
	s_nop 0
	v_mul_f32_e32 v61, v21, v61
	v_and_b32_e32 v8, 0xffff0000, v8
	v_mul_f32_e32 v14, 0xbfb8aa3b, v29
	v_exp_f32_e32 v57, v14
	v_rcp_f32_e32 v60, v60
	s_nop 0
	v_mul_f32_e32 v60, v25, v60
	v_mov_b32_e32 v14, v13
	v_pk_mul_f32 v[8:9], v[14:15], v[8:9]
	v_pk_add_f32 v[56:57], v[56:57], 1.0 op_sel_hi:[1,0]
	v_pk_mul_f32 v[60:61], v[60:61], v[62:63]
	v_lshlrev_b32_e32 v63, 16, v11
	v_lshlrev_b32_e32 v62, 16, v10
	v_and_b32_e32 v11, 0xffff0000, v11
	v_rcp_f32_e32 v13, v57
	s_nop 0
	v_mul_f32_e32 v13, v29, v13
	v_rcp_f32_e32 v12, v56
	s_nop 0
	v_mul_f32_e32 v12, v35, v12
	v_pk_mul_f32 v[8:9], v[12:13], v[8:9]
	v_lshlrev_b32_e32 v21, 16, v59
	v_lshlrev_b32_e32 v25, 16, v58
	v_cvt_pk_bf16_f32 v9, v61, v9
	v_cvt_pk_bf16_f32 v8, v60, v8
	v_mul_f32_e32 v12, 0xbfb8aa3b, v25
	v_mul_f32_e32 v13, 0xbfb8aa3b, v21
	v_exp_f32_e32 v12, v12
	v_exp_f32_e32 v13, v13
	v_and_b32_e32 v35, 0xffff0000, v58
	v_mul_f32_e32 v14, 0xbfb8aa3b, v35
	v_and_b32_e32 v29, 0xffff0000, v59
	v_exp_f32_e32 v60, v14
	v_pk_add_f32 v[64:65], v[12:13], 1.0 op_sel_hi:[1,0]
	global_load_dwordx4 v[12:15], v[22:23], off
	global_load_dwordx4 v[56:59], v[22:23], off offset:2048
	s_waitcnt lgkmcnt(0)
	v_mov_b32_e32 v22, v16
	v_mov_b32_e32 v23, v18
	v_pk_mul_f32 v[22:23], v[22:23], v[62:63]
	v_rcp_f32_e32 v63, v65
	s_nop 0
	v_mul_f32_e32 v63, v21, v63
	v_and_b32_e32 v10, 0xffff0000, v10
	v_mul_f32_e32 v18, 0xbfb8aa3b, v29
	v_exp_f32_e32 v61, v18
	v_rcp_f32_e32 v62, v64
	s_nop 0
	v_mul_f32_e32 v62, v25, v62
	v_mov_b32_e32 v18, v17
	v_pk_mul_f32 v[10:11], v[18:19], v[10:11]
	v_pk_add_f32 v[60:61], v[60:61], 1.0 op_sel_hi:[1,0]
	v_pk_mul_f32 v[22:23], v[62:63], v[22:23]
	s_waitcnt vmcnt(1)
; __device__ __forceinline__ unsigned pack2(float a, float b) { return (unsigned)f2bf(a) | ((unsigned)f2bf(b) << 16); }
; __device__ __forceinline__ float bflo(unsigned w) { return __uint_as_float(w << 16); }
; __device__ __forceinline__ float bfhi(unsigned w) { return __uint_as_float(w & 0xffff0000u); }
; __device__ __forceinline__ float silu_f(float g) { return g / (1.f + __expf(-g)); }
; __device__ void gmlp_item(const Params& p, int layer, int b, int n, int g, char* smem) {
;     ...
;       int q = tid + 256 * i, t = q >> 4, c = (q & 15) * 8;
;       uu[i] = *reinterpret_cast<const uint4*>(P + (t0 + t) * NP + g * 128 + c);
;       gt[i] = *reinterpret_cast<const uint4*>(P + (t0 + t) * NP + 1024 + g * 128 + c);
;     }
; #pragma unroll
;     for (int i = 0; i < 8; ++i) {
;       int q = tid + 256 * i, t = q >> 4, c = (q & 15) * 8;
;       float4 m0 = *reinterpret_cast<const float4*>(Tf + t * 132 + c);
;       float4 m1 = *reinterpret_cast<const float4*>(Tf + t * 132 + c + 4);
;       float mm[8] = {m0.x, m0.y, m0.z, m0.w, m1.x, m1.y, m1.z, m1.w};
;       unsigned uw[4] = {uu[i].x, uu[i].y, uu[i].z, uu[i].w};
;       unsigned gw[4] = {gt[i].x, gt[i].y, gt[i].z, gt[i].w};
;       unsigned ow[4];
; #pragma unroll
;       for (int e = 0; e < 4; ++e) {
;         float y0 = bflo(uw[e]) * mm[2 * e] * silu_f(bflo(gw[e]));
;         float y1 = bfhi(uw[e]) * mm[2 * e + 1] * silu_f(bfhi(gw[e]));
;         ow[e] = pack2(y0, y1);
;       }
;       *reinterpret_cast<uint4*>(Y + (t0 + t) * YW + g * 128 + c) = make_uint4(ow[0], ow[1], ow[2], ow[3]);
	v_lshlrev_b32_e32 v63, 16, v13
	v_rcp_f32_e32 v17, v61
	s_nop 0
	v_mul_f32_e32 v17, v29, v17
	v_rcp_f32_e32 v16, v60
	s_nop 0
	v_mul_f32_e32 v16, v35, v16
	v_pk_mul_f32 v[10:11], v[16:17], v[10:11]
	s_waitcnt vmcnt(0)
	v_lshlrev_b32_e32 v29, 16, v56
	v_cvt_pk_bf16_f32 v11, v23, v11
	v_mul_f32_e32 v16, 0xbfb8aa3b, v29
	v_and_b32_e32 v55, 0xffff0000, v56
	v_lshlrev_b32_e32 v25, 16, v57
	v_exp_f32_e32 v60, v16
	v_mul_f32_e32 v16, 0xbfb8aa3b, v55
	v_exp_f32_e32 v56, v16
	v_mul_f32_e32 v16, 0xbfb8aa3b, v25
	v_exp_f32_e32 v61, v16
	s_nop 0
	v_pk_add_f32 v[60:61], v[60:61], 1.0 op_sel_hi:[1,0]
	v_and_b32_e32 v35, 0xffff0000, v57
	v_cvt_pk_bf16_f32 v10, v22, v10
	ds_read_b128 v[16:19], v20
	ds_read_b128 v[20:23], v20 offset:16
	v_lshlrev_b32_e32 v62, 16, v12
	v_and_b32_e32 v13, 0xffff0000, v13
	s_waitcnt lgkmcnt(1)
	v_mov_b32_e32 v64, v16
	v_mov_b32_e32 v65, v18
	v_pk_mul_f32 v[62:63], v[64:65], v[62:63]
	v_rcp_f32_e32 v61, v61
	s_nop 0
	v_mul_f32_e32 v61, v25, v61
	v_and_b32_e32 v12, 0xffff0000, v12
	v_mul_f32_e32 v18, 0xbfb8aa3b, v35
	v_exp_f32_e32 v57, v18
	v_rcp_f32_e32 v60, v60
	s_nop 0
	v_mul_f32_e32 v60, v29, v60
	v_mov_b32_e32 v18, v17
	v_pk_mul_f32 v[12:13], v[18:19], v[12:13]
	v_pk_add_f32 v[56:57], v[56:57], 1.0 op_sel_hi:[1,0]
	v_pk_mul_f32 v[60:61], v[60:61], v[62:63]
	v_lshlrev_b32_e32 v63, 16, v15
	v_lshlrev_b32_e32 v62, 16, v14
	v_and_b32_e32 v15, 0xffff0000, v15
	v_rcp_f32_e32 v17, v57
	s_nop 0
	v_mul_f32_e32 v17, v35, v17
	v_rcp_f32_e32 v16, v56
	s_nop 0
	v_mul_f32_e32 v16, v55, v16
	v_pk_mul_f32 v[12:13], v[16:17], v[12:13]
	v_lshlrev_b32_e32 v25, 16, v59
	v_lshlrev_b32_e32 v29, 16, v58
	v_cvt_pk_bf16_f32 v13, v61, v13
	v_cvt_pk_bf16_f32 v12, v60, v12
	v_mul_f32_e32 v16, 0xbfb8aa3b, v29
	v_mul_f32_e32 v17, 0xbfb8aa3b, v25
	v_exp_f32_e32 v16, v16
	v_exp_f32_e32 v17, v17
	v_and_b32_e32 v55, 0xffff0000, v58
	v_mul_f32_e32 v18, 0xbfb8aa3b, v55
	v_and_b32_e32 v35, 0xffff0000, v59
	v_exp_f32_e32 v60, v18
	v_pk_add_f32 v[64:65], v[16:17], 1.0 op_sel_hi:[1,0]
	global_load_dwordx4 v[16:19], v[26:27], off
	global_load_dwordx4 v[56:59], v[26:27], off offset:2048
	s_waitcnt lgkmcnt(0)
	v_mov_b32_e32 v26, v20
	v_mov_b32_e32 v27, v22
	v_pk_mul_f32 v[26:27], v[26:27], v[62:63]
	v_rcp_f32_e32 v63, v65
	s_nop 0
	v_mul_f32_e32 v63, v25, v63
	v_and_b32_e32 v14, 0xffff0000, v14
	v_mul_f32_e32 v22, 0xbfb8aa3b, v35
	v_exp_f32_e32 v61, v22
	v_rcp_f32_e32 v62, v64
	s_nop 0
	v_mul_f32_e32 v62, v29, v62
	v_mov_b32_e32 v22, v21
	v_pk_mul_f32 v[14:15], v[22:23], v[14:15]
	v_pk_add_f32 v[60:61], v[60:61], 1.0 op_sel_hi:[1,0]
	v_pk_mul_f32 v[26:27], v[62:63], v[26:27]
	s_waitcnt vmcnt(1)
	v_lshlrev_b32_e32 v63, 16, v17
	v_rcp_f32_e32 v21, v61
	s_nop 0
	v_mul_f32_e32 v21, v35, v21
	v_rcp_f32_e32 v20, v60
	s_nop 0
	v_mul_f32_e32 v20, v55, v20
	v_pk_mul_f32 v[14:15], v[20:21], v[14:15]
	s_waitcnt vmcnt(0)
	v_lshlrev_b32_e32 v35, 16, v56
	v_cvt_pk_bf16_f32 v15, v27, v15
	v_mul_f32_e32 v20, 0xbfb8aa3b, v35
	v_and_b32_e32 v66, 0xffff0000, v56
	v_lshlrev_b32_e32 v29, 16, v57
	v_exp_f32_e32 v60, v20
	v_mul_f32_e32 v20, 0xbfb8aa3b, v66
	v_exp_f32_e32 v56, v20
	v_mul_f32_e32 v20, 0xbfb8aa3b, v29
	v_exp_f32_e32 v61, v20
	s_nop 0
	v_pk_add_f32 v[60:61], v[60:61], 1.0 op_sel_hi:[1,0]
	v_and_b32_e32 v55, 0xffff0000, v57
	v_cvt_pk_bf16_f32 v14, v26, v14
	ds_read_b128 v[20:23], v24
	ds_read_b128 v[24:27], v24 offset:16
	v_lshlrev_b32_e32 v62, 16, v16
	v_and_b32_e32 v17, 0xffff0000, v17
	s_waitcnt lgkmcnt(1)
	v_mov_b32_e32 v64, v20
	v_mov_b32_e32 v65, v22
	v_pk_mul_f32 v[62:63], v[64:65], v[62:63]
	v_rcp_f32_e32 v61, v61
	s_nop 0
	v_mul_f32_e32 v61, v29, v61
	v_and_b32_e32 v16, 0xffff0000, v16
	v_mul_f32_e32 v22, 0xbfb8aa3b, v55
	v_exp_f32_e32 v57, v22
	v_rcp_f32_e32 v60, v60
	s_nop 0
	v_mul_f32_e32 v60, v35, v60
	v_mov_b32_e32 v22, v21
	v_pk_mul_f32 v[16:17], v[22:23], v[16:17]
	v_pk_add_f32 v[56:57], v[56:57], 1.0 op_sel_hi:[1,0]
	v_pk_mul_f32 v[60:61], v[60:61], v[62:63]
	v_lshlrev_b32_e32 v63, 16, v19
	v_lshlrev_b32_e32 v62, 16, v18
	v_and_b32_e32 v19, 0xffff0000, v19
	v_rcp_f32_e32 v21, v57
	s_nop 0
	v_mul_f32_e32 v21, v55, v21
	v_rcp_f32_e32 v20, v56
	s_nop 0
	v_mul_f32_e32 v20, v66, v20
	v_pk_mul_f32 v[16:17], v[20:21], v[16:17]
	v_lshlrev_b32_e32 v29, 16, v59
	v_lshlrev_b32_e32 v35, 16, v58
	v_cvt_pk_bf16_f32 v17, v61, v17
	v_cvt_pk_bf16_f32 v16, v60, v16
	v_mul_f32_e32 v20, 0xbfb8aa3b, v35
	v_mul_f32_e32 v21, 0xbfb8aa3b, v29
	v_exp_f32_e32 v20, v20
	v_exp_f32_e32 v21, v21
	v_and_b32_e32 v66, 0xffff0000, v58
	v_mul_f32_e32 v22, 0xbfb8aa3b, v66
	v_and_b32_e32 v55, 0xffff0000, v59
	v_exp_f32_e32 v60, v22
	v_pk_add_f32 v[64:65], v[20:21], 1.0 op_sel_hi:[1,0]
	global_load_dwordx4 v[20:23], v[30:31], off
	global_load_dwordx4 v[56:59], v[30:31], off offset:2048
	s_waitcnt lgkmcnt(0)
	v_mov_b32_e32 v30, v24
	v_mov_b32_e32 v31, v26
	v_pk_mul_f32 v[30:31], v[30:31], v[62:63]
	v_rcp_f32_e32 v63, v65
	s_nop 0
	v_mul_f32_e32 v63, v29, v63
	v_and_b32_e32 v18, 0xffff0000, v18
	v_mul_f32_e32 v26, 0xbfb8aa3b, v55
	v_exp_f32_e32 v61, v26
	v_rcp_f32_e32 v62, v64
	s_nop 0
	v_mul_f32_e32 v62, v35, v62
	v_mov_b32_e32 v26, v25
	v_pk_mul_f32 v[18:19], v[26:27], v[18:19]
	v_pk_add_f32 v[60:61], v[60:61], 1.0 op_sel_hi:[1,0]
	v_pk_mul_f32 v[30:31], v[62:63], v[30:31]
	s_waitcnt vmcnt(1)
	v_lshlrev_b32_e32 v63, 16, v21
	v_rcp_f32_e32 v25, v61
	s_nop 0
	v_mul_f32_e32 v25, v55, v25
	v_rcp_f32_e32 v24, v60
	s_nop 0
	v_mul_f32_e32 v24, v66, v24
	v_pk_mul_f32 v[18:19], v[24:25], v[18:19]
	s_waitcnt vmcnt(0)
; __device__ __forceinline__ unsigned pack2(float a, float b) { return (unsigned)f2bf(a) | ((unsigned)f2bf(b) << 16); }
; __device__ __forceinline__ float bflo(unsigned w) { return __uint_as_float(w << 16); }
; __device__ __forceinline__ float bfhi(unsigned w) { return __uint_as_float(w & 0xffff0000u); }
; __device__ __forceinline__ float silu_f(float g) { return g / (1.f + __expf(-g)); }
; __device__ void gmlp_item(const Params& p, int layer, int b, int n, int g, char* smem) {
;     ...
;       int q = tid + 256 * i, t = q >> 4, c = (q & 15) * 8;
;       uu[i] = *reinterpret_cast<const uint4*>(P + (t0 + t) * NP + g * 128 + c);
;       gt[i] = *reinterpret_cast<const uint4*>(P + (t0 + t) * NP + 1024 + g * 128 + c);
;     }
; #pragma unroll
;     for (int i = 0; i < 8; ++i) {
;       int q = tid + 256 * i, t = q >> 4, c = (q & 15) * 8;
;       float4 m0 = *reinterpret_cast<const float4*>(Tf + t * 132 + c);
;       float4 m1 = *reinterpret_cast<const float4*>(Tf + t * 132 + c + 4);
;       float mm[8] = {m0.x, m0.y, m0.z, m0.w, m1.x, m1.y, m1.z, m1.w};
;       unsigned uw[4] = {uu[i].x, uu[i].y, uu[i].z, uu[i].w};
;       unsigned gw[4] = {gt[i].x, gt[i].y, gt[i].z, gt[i].w};
;       unsigned ow[4];
; #pragma unroll
;       for (int e = 0; e < 4; ++e) {
;         float y0 = bflo(uw[e]) * mm[2 * e] * silu_f(bflo(gw[e]));
;         float y1 = bfhi(uw[e]) * mm[2 * e + 1] * silu_f(bfhi(gw[e]));
;         ow[e] = pack2(y0, y1);
;       }
;       *reinterpret_cast<uint4*>(Y + (t0 + t) * YW + g * 128 + c) = make_uint4(ow[0], ow[1], ow[2], ow[3]);
	v_lshlrev_b32_e32 v55, 16, v56
	v_cvt_pk_bf16_f32 v19, v31, v19
	v_mul_f32_e32 v24, 0xbfb8aa3b, v55
	v_and_b32_e32 v67, 0xffff0000, v56
	v_lshlrev_b32_e32 v35, 16, v57
	v_exp_f32_e32 v60, v24
	v_mul_f32_e32 v24, 0xbfb8aa3b, v67
	v_exp_f32_e32 v56, v24
	v_mul_f32_e32 v24, 0xbfb8aa3b, v35
	v_exp_f32_e32 v61, v24
	s_nop 0
	v_pk_add_f32 v[60:61], v[60:61], 1.0 op_sel_hi:[1,0]
	v_and_b32_e32 v66, 0xffff0000, v57
	v_cvt_pk_bf16_f32 v18, v30, v18
	ds_read_b128 v[24:27], v28
	ds_read_b128 v[28:31], v28 offset:16
	v_lshlrev_b32_e32 v62, 16, v20
	v_and_b32_e32 v21, 0xffff0000, v21
	s_waitcnt lgkmcnt(1)
	v_mov_b32_e32 v64, v24
	v_mov_b32_e32 v65, v26
	v_pk_mul_f32 v[62:63], v[64:65], v[62:63]
	v_rcp_f32_e32 v61, v61
	s_nop 0
	v_mul_f32_e32 v61, v35, v61
	v_and_b32_e32 v20, 0xffff0000, v20
	v_mul_f32_e32 v26, 0xbfb8aa3b, v66
	v_exp_f32_e32 v57, v26
	v_rcp_f32_e32 v60, v60
	s_nop 0
	v_mul_f32_e32 v60, v55, v60
	v_mov_b32_e32 v26, v25
	v_pk_mul_f32 v[20:21], v[26:27], v[20:21]
	v_pk_add_f32 v[56:57], v[56:57], 1.0 op_sel_hi:[1,0]
	v_pk_mul_f32 v[60:61], v[60:61], v[62:63]
	v_lshlrev_b32_e32 v63, 16, v23
	v_lshlrev_b32_e32 v62, 16, v22
	v_and_b32_e32 v23, 0xffff0000, v23
	v_rcp_f32_e32 v25, v57
	s_nop 0
	v_mul_f32_e32 v25, v66, v25
	v_rcp_f32_e32 v24, v56
	s_nop 0
	v_mul_f32_e32 v24, v67, v24
	v_pk_mul_f32 v[20:21], v[24:25], v[20:21]
	v_lshlrev_b32_e32 v35, 16, v59
	v_lshlrev_b32_e32 v55, 16, v58
	v_cvt_pk_bf16_f32 v21, v61, v21
	v_cvt_pk_bf16_f32 v20, v60, v20
	v_mul_f32_e32 v24, 0xbfb8aa3b, v55
	v_mul_f32_e32 v25, 0xbfb8aa3b, v35
	v_exp_f32_e32 v24, v24
	v_exp_f32_e32 v25, v25
	v_and_b32_e32 v67, 0xffff0000, v58
	v_mul_f32_e32 v26, 0xbfb8aa3b, v67
	v_and_b32_e32 v66, 0xffff0000, v59
	v_exp_f32_e32 v60, v26
	v_pk_add_f32 v[64:65], v[24:25], 1.0 op_sel_hi:[1,0]
	global_load_dwordx4 v[24:27], v[32:33], off
	global_load_dwordx4 v[56:59], v[32:33], off offset:2048
	s_waitcnt lgkmcnt(0)
	v_mov_b32_e32 v32, v28
	v_mov_b32_e32 v33, v30
	v_pk_mul_f32 v[32:33], v[32:33], v[62:63]
	v_rcp_f32_e32 v63, v65
	s_nop 0
	v_mul_f32_e32 v63, v35, v63
	v_and_b32_e32 v22, 0xffff0000, v22
	v_mul_f32_e32 v30, 0xbfb8aa3b, v66
	v_exp_f32_e32 v61, v30
	v_rcp_f32_e32 v62, v64
	s_nop 0
	v_mul_f32_e32 v62, v55, v62
	v_mov_b32_e32 v30, v29
	v_pk_mul_f32 v[22:23], v[30:31], v[22:23]
	v_pk_add_f32 v[60:61], v[60:61], 1.0 op_sel_hi:[1,0]
	v_pk_mul_f32 v[32:33], v[62:63], v[32:33]
	s_waitcnt vmcnt(1)
	v_lshlrev_b32_e32 v63, 16, v25
	v_rcp_f32_e32 v29, v61
	s_nop 0
	v_mul_f32_e32 v29, v66, v29
	v_rcp_f32_e32 v28, v60
	s_nop 0
	v_mul_f32_e32 v28, v67, v28
	v_pk_mul_f32 v[22:23], v[28:29], v[22:23]
	s_waitcnt vmcnt(0)
	v_lshlrev_b32_e32 v66, 16, v56
	v_cvt_pk_bf16_f32 v23, v33, v23
	v_mul_f32_e32 v28, 0xbfb8aa3b, v66
	v_and_b32_e32 v68, 0xffff0000, v56
	v_lshlrev_b32_e32 v55, 16, v57
	v_exp_f32_e32 v60, v28
	v_mul_f32_e32 v28, 0xbfb8aa3b, v68
	v_exp_f32_e32 v56, v28
	v_mul_f32_e32 v28, 0xbfb8aa3b, v55
	v_exp_f32_e32 v61, v28
	s_nop 0
	v_pk_add_f32 v[60:61], v[60:61], 1.0 op_sel_hi:[1,0]
	v_and_b32_e32 v67, 0xffff0000, v57
	v_cvt_pk_bf16_f32 v22, v32, v22
	ds_read_b128 v[28:31], v34
	ds_read_b128 v[32:35], v34 offset:16
	v_lshlrev_b32_e32 v62, 16, v24
	v_and_b32_e32 v25, 0xffff0000, v25
	s_waitcnt lgkmcnt(1)
	v_mov_b32_e32 v64, v28
	v_mov_b32_e32 v65, v30
	v_pk_mul_f32 v[62:63], v[64:65], v[62:63]
	v_rcp_f32_e32 v61, v61
	s_nop 0
	v_mul_f32_e32 v61, v55, v61
	v_and_b32_e32 v24, 0xffff0000, v24
	v_mul_f32_e32 v30, 0xbfb8aa3b, v67
	v_exp_f32_e32 v57, v30
	v_rcp_f32_e32 v60, v60
	s_nop 0
	v_mul_f32_e32 v60, v66, v60
	v_mov_b32_e32 v30, v29
	v_pk_mul_f32 v[24:25], v[30:31], v[24:25]
	v_pk_add_f32 v[56:57], v[56:57], 1.0 op_sel_hi:[1,0]
	v_pk_mul_f32 v[60:61], v[60:61], v[62:63]
	v_lshlrev_b32_e32 v66, 16, v58
	v_lshlrev_b32_e32 v63, 16, v27
	v_and_b32_e32 v27, 0xffff0000, v27
	v_rcp_f32_e32 v29, v57
	s_nop 0
	v_mul_f32_e32 v29, v67, v29
	v_rcp_f32_e32 v28, v56
	s_nop 0
	v_mul_f32_e32 v28, v68, v28
	v_pk_mul_f32 v[24:25], v[28:29], v[24:25]
	v_lshlrev_b32_e32 v55, 16, v59
	v_cvt_pk_bf16_f32 v25, v61, v25
	v_cvt_pk_bf16_f32 v24, v60, v24
	v_mul_f32_e32 v28, 0xbfb8aa3b, v66
	v_mul_f32_e32 v29, 0xbfb8aa3b, v55
	v_exp_f32_e32 v28, v28
	v_exp_f32_e32 v29, v29
	v_and_b32_e32 v68, 0xffff0000, v58
	v_mul_f32_e32 v30, 0xbfb8aa3b, v68
	v_and_b32_e32 v67, 0xffff0000, v59
	v_exp_f32_e32 v60, v30
	v_pk_add_f32 v[64:65], v[28:29], 1.0 op_sel_hi:[1,0]
	global_load_dwordx4 v[28:31], v[52:53], off
	global_load_dwordx4 v[56:59], v[52:53], off offset:2048
	s_waitcnt lgkmcnt(0)
; __device__ __forceinline__ unsigned pack2(float a, float b) { return (unsigned)f2bf(a) | ((unsigned)f2bf(b) << 16); }
; __device__ __forceinline__ float bflo(unsigned w) { return __uint_as_float(w << 16); }
; __device__ __forceinline__ float bfhi(unsigned w) { return __uint_as_float(w & 0xffff0000u); }
; __device__ __forceinline__ float silu_f(float g) { return g / (1.f + __expf(-g)); }
; __device__ void gmlp_item(const Params& p, int layer, int b, int n, int g, char* smem) {
;     ...
;       int q = tid + 256 * i, t = q >> 4, c = (q & 15) * 8;
;       uu[i] = *reinterpret_cast<const uint4*>(P + (t0 + t) * NP + g * 128 + c);
;       gt[i] = *reinterpret_cast<const uint4*>(P + (t0 + t) * NP + 1024 + g * 128 + c);
;     }
; #pragma unroll
;     for (int i = 0; i < 8; ++i) {
;       int q = tid + 256 * i, t = q >> 4, c = (q & 15) * 8;
;       float4 m0 = *reinterpret_cast<const float4*>(Tf + t * 132 + c);
;       float4 m1 = *reinterpret_cast<const float4*>(Tf + t * 132 + c + 4);
;       float mm[8] = {m0.x, m0.y, m0.z, m0.w, m1.x, m1.y, m1.z, m1.w};
;       unsigned uw[4] = {uu[i].x, uu[i].y, uu[i].z, uu[i].w};
;       unsigned gw[4] = {gt[i].x, gt[i].y, gt[i].z, gt[i].w};
;       unsigned ow[4];
; #pragma unroll
;       for (int e = 0; e < 4; ++e) {
;         float y0 = bflo(uw[e]) * mm[2 * e] * silu_f(bflo(gw[e]));
;         float y1 = bfhi(uw[e]) * mm[2 * e + 1] * silu_f(bfhi(gw[e]));
;         ow[e] = pack2(y0, y1);
;       }
;       *reinterpret_cast<uint4*>(Y + (t0 + t) * YW + g * 128 + c) = make_uint4(ow[0], ow[1], ow[2], ow[3]);
	v_mov_b32_e32 v52, v32
	v_lshlrev_b32_e32 v62, 16, v26
	v_mov_b32_e32 v53, v34
	v_pk_mul_f32 v[52:53], v[52:53], v[62:63]
	v_rcp_f32_e32 v63, v65
	s_nop 0
	v_mul_f32_e32 v63, v55, v63
	v_and_b32_e32 v26, 0xffff0000, v26
	v_mul_f32_e32 v34, 0xbfb8aa3b, v67
	v_exp_f32_e32 v61, v34
	v_rcp_f32_e32 v62, v64
	s_nop 0
	v_mul_f32_e32 v62, v66, v62
	v_mov_b32_e32 v34, v33
	v_pk_mul_f32 v[26:27], v[34:35], v[26:27]
	v_pk_add_f32 v[60:61], v[60:61], 1.0 op_sel_hi:[1,0]
	v_pk_mul_f32 v[52:53], v[62:63], v[52:53]
	s_waitcnt vmcnt(1)
	v_lshlrev_b32_e32 v63, 16, v29
	v_rcp_f32_e32 v33, v61
	s_nop 0
	v_mul_f32_e32 v33, v67, v33
	v_rcp_f32_e32 v32, v60
	s_nop 0
	v_mul_f32_e32 v32, v68, v32
	v_pk_mul_f32 v[26:27], v[32:33], v[26:27]
	s_waitcnt vmcnt(0)
	v_lshlrev_b32_e32 v67, 16, v56
	v_cvt_pk_bf16_f32 v27, v53, v27
	v_mul_f32_e32 v32, 0xbfb8aa3b, v67
	v_and_b32_e32 v69, 0xffff0000, v56
	v_lshlrev_b32_e32 v66, 16, v57
	v_exp_f32_e32 v60, v32
	v_mul_f32_e32 v32, 0xbfb8aa3b, v69
	v_exp_f32_e32 v56, v32
	v_mul_f32_e32 v32, 0xbfb8aa3b, v66
	v_exp_f32_e32 v61, v32
	s_nop 0
	v_pk_add_f32 v[60:61], v[60:61], 1.0 op_sel_hi:[1,0]
	v_and_b32_e32 v68, 0xffff0000, v57
	v_cvt_pk_bf16_f32 v26, v52, v26
	ds_read_b128 v[32:35], v54
	ds_read_b128 v[52:55], v54 offset:16
	v_lshlrev_b32_e32 v62, 16, v28
	v_and_b32_e32 v29, 0xffff0000, v29
	s_waitcnt lgkmcnt(1)
	v_mov_b32_e32 v64, v32
	v_mov_b32_e32 v65, v34
	v_pk_mul_f32 v[62:63], v[64:65], v[62:63]
	v_rcp_f32_e32 v61, v61
	s_nop 0
	v_mul_f32_e32 v61, v66, v61
	v_and_b32_e32 v28, 0xffff0000, v28
	v_mul_f32_e32 v34, 0xbfb8aa3b, v68
	v_exp_f32_e32 v57, v34
	v_rcp_f32_e32 v60, v60
	s_nop 0
	v_mul_f32_e32 v60, v67, v60
	v_pk_mul_f32 v[60:61], v[60:61], v[62:63]
	v_mov_b32_e32 v34, v33
	v_pk_add_f32 v[56:57], v[56:57], 1.0 op_sel_hi:[1,0]
	v_pk_mul_f32 v[28:29], v[34:35], v[28:29]
	s_nop 0
	v_rcp_f32_e32 v33, v57
	s_nop 0
	v_mul_f32_e32 v33, v68, v33
	v_rcp_f32_e32 v32, v56
	s_nop 0
	v_mul_f32_e32 v32, v69, v32
	v_pk_mul_f32 v[28:29], v[32:33], v[28:29]
	v_cvt_pk_bf16_f32 v28, 0, v28
	v_cvt_pk_bf16_f32 v33, 0, v60
	v_and_b32_e32 v28, 0xffff0000, v28
	v_lshlrev_b32_e32 v35, 16, v59
	v_lshlrev_b32_e32 v60, 16, v58
	v_cvt_pk_bf16_f32 v29, v61, v29
	v_or_b32_sdwa v28, v28, v33 dst_sel:DWORD dst_unused:UNUSED_PAD src0_sel:DWORD src1_sel:WORD_1
	v_mul_f32_e32 v32, 0xbfb8aa3b, v60
	v_mul_f32_e32 v33, 0xbfb8aa3b, v35
	v_exp_f32_e32 v32, v32
	v_exp_f32_e32 v33, v33
	v_and_b32_e32 v62, 0xffff0000, v58
	s_waitcnt lgkmcnt(0)
	v_mov_b32_e32 v58, v52
	v_and_b32_e32 v61, 0xffff0000, v59
	v_pk_add_f32 v[32:33], v[32:33], 1.0 op_sel_hi:[1,0]
	v_lshlrev_b32_e32 v57, 16, v31
	v_lshlrev_b32_e32 v56, 16, v30
	v_mov_b32_e32 v59, v54
	v_pk_mul_f32 v[56:57], v[58:59], v[56:57]
	v_rcp_f32_e32 v33, v33
	s_nop 0
	v_mul_f32_e32 v33, v35, v33
	v_mul_f32_e32 v34, 0xbfb8aa3b, v62
	v_mul_f32_e32 v35, 0xbfb8aa3b, v61
	v_exp_f32_e32 v34, v34
	v_exp_f32_e32 v35, v35
	v_rcp_f32_e32 v32, v32
	s_nop 0
	v_mul_f32_e32 v32, v60, v32
	v_pk_mul_f32 v[32:33], v[32:33], v[56:57]
	v_mov_b32_e32 v54, v53
	v_pk_add_f32 v[34:35], v[34:35], 1.0 op_sel_hi:[1,0]
	v_and_b32_e32 v31, 0xffff0000, v31
	v_and_b32_e32 v30, 0xffff0000, v30
	v_pk_mul_f32 v[30:31], v[54:55], v[30:31]
	v_rcp_f32_e32 v35, v35
	s_nop 0
	v_mul_f32_e32 v35, v61, v35
	s_mov_b64 s[4:5], 0
	v_rcp_f32_e32 v34, v34
	s_nop 0
	v_mul_f32_e32 v34, v62, v34
	v_pk_mul_f32 v[30:31], v[34:35], v[30:31]
	v_cvt_pk_bf16_f32 v31, v33, v31
	v_cvt_pk_bf16_f32 v30, v32, v30
	global_store_dwordx4 v[50:51], v[28:31], off
	global_store_dwordx4 v[48:49], v[24:27], off
	global_store_dwordx4 v[46:47], v[20:23], off
	global_store_dwordx4 v[44:45], v[16:19], off
	global_store_dwordx4 v[42:43], v[12:15], off
	global_store_dwordx4 v[40:41], v[8:11], off
	global_store_dwordx4 v[38:39], v[4:7], off
	global_store_dwordx4 v[36:37], v[0:3], off
	s_barrier

; __device__ __forceinline__ unsigned pack2(float a, float b) { return (unsigned)f2bf(a) | ((unsigned)f2bf(b) << 16); }
; template <int DH, int MODE>
; __device__ void attn_item(const Params& p, int layer, int b, int blk, int head, char* smem) {
;     ...
; #pragma unroll 2
;         for (int s8 = 0; s8 < 4; ++s8) {
;           float4 va = s4[2 * s8], vb = s4[2 * s8 + 1];
;           float e[8] = {va.x, va.y, va.z, va.w, vb.x, vb.y, vb.z, vb.w};
;           float pv[8];
; #pragma unroll
;           for (int k = 0; k < 8; ++k) {
;             int kj = kjb + s8 * 8 + k;
;             bool valid = (kj > row) && (kj <= row + 128);
;             float pe = valid ? __builtin_amdgcn_exp2f(e[k] - m_new) : 0.f;
;             pv[k] = pe;
;             psum += pe;
;           }
;           uint4 ov;
;           ov.x = pack2(pv[0], pv[1]); ov.y = pack2(pv[2], pv[3]);
;           ov.z = pack2(pv[4], pv[5]); ov.w = pack2(pv[6], pv[7]);
;           *reinterpret_cast<uint4*>(prow + s8 * 16) = ov;
;         }
;         psum += __shfl_xor(psum, 1);
;         l_run = l_run * alpha + psum;
;         m_run = m_new;
;         if (half == 0) alpha_s[row] = alpha;
.LBB0_184:
	ds_read_b128 v[104:107], v102
	ds_read_b128 v[108:111], v102 offset:16
	v_add_u32_e32 v112, s87, v92
	v_add_u32_e32 v113, 2, v112
	v_cmp_gt_i32_e64 s[6:7], v112, v74
	s_waitcnt lgkmcnt(1)
	v_sub_f32_e32 v104, v104, v82
	v_exp_f32_e32 v104, v104
	v_sub_f32_e32 v106, v106, v82
	v_sub_f32_e32 v105, v105, v82
	v_exp_f32_e32 v106, v106
	v_exp_f32_e32 v105, v105
	v_sub_f32_e32 v107, v107, v82
	v_cmp_le_i32_e64 s[10:11], v112, v80
	v_exp_f32_e32 v107, v107
	v_cmp_gt_i32_e32 vcc, v113, v65
	v_cmp_le_i32_e64 s[8:9], v113, v69
	s_and_b64 s[6:7], s[6:7], s[10:11]
	v_add_u32_e32 v114, 3, v112
	s_and_b64 vcc, vcc, s[8:9]
	v_cndmask_b32_e64 v104, 0, v104, s[6:7]
	v_cmp_lt_i32_e64 s[6:7], v112, v80
	v_cmp_ge_i32_e64 s[10:11], v112, v74
	v_cndmask_b32_e32 v106, 0, v106, vcc
	v_cmp_lt_i32_e32 vcc, v74, v114
	v_cmp_ge_i32_e64 s[8:9], v80, v114
	s_and_b64 s[6:7], s[6:7], s[10:11]
	v_add_f32_e32 v103, v103, v104
	s_and_b64 vcc, vcc, s[8:9]
	v_cndmask_b32_e64 v105, 0, v105, s[6:7]
	v_cndmask_b32_e32 v107, 0, v107, vcc
	v_add_f32_e32 v103, v103, v105
	v_add_f32_e32 v103, v103, v106
	s_waitcnt lgkmcnt(0)
	v_sub_f32_e32 v108, v108, v82
	v_sub_f32_e32 v110, v110, v82
	v_add_f32_e32 v103, v103, v107
	v_cvt_pk_bf16_f32 v104, 0, v104
	v_exp_f32_e32 v108, v108
	v_exp_f32_e32 v110, v110
	v_cvt_pk_bf16_f32 v105, 0, v105
	v_sub_f32_e32 v109, v109, v82
	v_sub_f32_e32 v111, v111, v82
	v_and_b32_e32 v113, 0xffff0000, v105
	v_cvt_pk_bf16_f32 v105, v106, v107
	v_or_b32_e32 v106, 6, v112
	v_or_b32_e32 v107, 4, v112
	v_exp_f32_e32 v109, v109
	v_exp_f32_e32 v111, v111
	v_cmp_gt_i32_e32 vcc, v107, v74
	v_cmp_gt_i32_e64 s[6:7], v106, v65
	v_cmp_le_i32_e64 s[8:9], v107, v80
	v_cmp_le_i32_e64 s[10:11], v106, v69
	s_and_b64 s[6:7], s[6:7], s[10:11]
	s_and_b64 vcc, vcc, s[8:9]
	v_or_b32_e32 v106, 7, v112
	v_or_b32_e32 v107, 5, v112
	v_cndmask_b32_e32 v108, 0, v108, vcc
	v_cndmask_b32_e64 v110, 0, v110, s[6:7]
	v_cmp_gt_i32_e32 vcc, v107, v74
	v_cmp_gt_i32_e64 s[6:7], v106, v65
	v_cmp_le_i32_e64 s[8:9], v107, v80
	v_cmp_le_i32_e64 s[10:11], v106, v69
	s_and_b64 s[6:7], s[6:7], s[10:11]
	s_and_b64 vcc, vcc, s[8:9]
	v_cndmask_b32_e32 v109, 0, v109, vcc
	v_cndmask_b32_e64 v111, 0, v111, s[6:7]
	v_or_b32_sdwa v104, v113, v104 dst_sel:DWORD dst_unused:UNUSED_PAD src0_sel:DWORD src1_sel:WORD_1
	v_add_f32_e32 v103, v103, v108
	v_cvt_pk_bf16_f32 v107, v110, v111
	v_cvt_pk_bf16_f32 v106, v108, v109
	v_add_f32_e32 v103, v103, v109
	v_add_f32_e32 v103, v103, v110
	ds_write_b128 v101, v[104:107]
	v_add_f32_e32 v103, v103, v111
	ds_read_b128 v[104:107], v102 offset:32
	ds_read_b128 v[108:111], v102 offset:48
	v_add_u32_e32 v113, 8, v112
	v_add_u32_e32 v114, 10, v112
	v_cmp_gt_i32_e64 s[6:7], v113, v74
	s_waitcnt lgkmcnt(1)
	v_sub_f32_e32 v104, v104, v82
	v_exp_f32_e32 v104, v104
	v_sub_f32_e32 v106, v106, v82
	v_sub_f32_e32 v105, v105, v82
	v_exp_f32_e32 v106, v106
	v_exp_f32_e32 v105, v105
	v_sub_f32_e32 v107, v107, v82
	v_cmp_le_i32_e64 s[10:11], v113, v80
	v_exp_f32_e32 v107, v107
	v_cmp_gt_i32_e32 vcc, v114, v65
	v_cmp_le_i32_e64 s[8:9], v114, v69
	s_and_b64 s[6:7], s[6:7], s[10:11]
	v_add_u32_e32 v112, 11, v112
	s_and_b64 vcc, vcc, s[8:9]
	v_cndmask_b32_e64 v104, 0, v104, s[6:7]
	v_cmp_lt_i32_e64 s[6:7], v113, v80
	v_cmp_ge_i32_e64 s[10:11], v113, v74
	v_cndmask_b32_e32 v106, 0, v106, vcc
	v_cmp_lt_i32_e32 vcc, v74, v112
	v_cmp_ge_i32_e64 s[8:9], v80, v112
	s_and_b64 s[6:7], s[6:7], s[10:11]
	v_add_f32_e32 v103, v103, v104
	s_and_b64 vcc, vcc, s[8:9]
	v_cndmask_b32_e64 v105, 0, v105, s[6:7]
	v_cndmask_b32_e32 v107, 0, v107, vcc
	v_add_f32_e32 v103, v103, v105
	v_add_f32_e32 v103, v103, v106
	s_waitcnt lgkmcnt(0)
	v_sub_f32_e32 v108, v108, v82
	v_sub_f32_e32 v110, v110, v82
	v_add_f32_e32 v103, v103, v107
	v_cvt_pk_bf16_f32 v104, 0, v104
	v_exp_f32_e32 v108, v108
	v_exp_f32_e32 v110, v110
	v_cvt_pk_bf16_f32 v105, 0, v105
	v_sub_f32_e32 v109, v109, v82
	v_sub_f32_e32 v111, v111, v82
	v_and_b32_e32 v112, 0xffff0000, v105
	v_cvt_pk_bf16_f32 v105, v106, v107
	v_or_b32_e32 v106, 6, v113
	v_or_b32_e32 v107, 4, v113
	v_exp_f32_e32 v109, v109
	v_exp_f32_e32 v111, v111
	v_cmp_gt_i32_e32 vcc, v107, v74
	v_cmp_gt_i32_e64 s[6:7], v106, v65
	v_cmp_le_i32_e64 s[8:9], v107, v80
	v_cmp_le_i32_e64 s[10:11], v106, v69
	s_and_b64 s[6:7], s[6:7], s[10:11]
	s_and_b64 vcc, vcc, s[8:9]
	v_or_b32_e32 v106, 7, v113
	v_or_b32_e32 v107, 5, v113
	v_cndmask_b32_e32 v108, 0, v108, vcc
	v_cndmask_b32_e64 v110, 0, v110, s[6:7]
	v_cmp_gt_i32_e32 vcc, v107, v74
	v_cmp_gt_i32_e64 s[6:7], v106, v65
	v_cmp_le_i32_e64 s[8:9], v107, v80
	v_cmp_le_i32_e64 s[10:11], v106, v69
	s_and_b64 s[6:7], s[6:7], s[10:11]
	s_and_b64 vcc, vcc, s[8:9]
	v_cndmask_b32_e32 v109, 0, v109, vcc
	v_cndmask_b32_e64 v111, 0, v111, s[6:7]
	v_or_b32_sdwa v104, v112, v104 dst_sel:DWORD dst_unused:UNUSED_PAD src0_sel:DWORD src1_sel:WORD_1
	v_add_f32_e32 v103, v103, v108
	v_add_f32_e32 v103, v103, v109
	v_cvt_pk_bf16_f32 v107, v110, v111
	v_cvt_pk_bf16_f32 v106, v108, v109
	v_add_f32_e32 v103, v103, v110
	s_add_i32 s87, s87, 16
	v_add_f32_e32 v103, v103, v111
	ds_write_b128 v101, v[104:107] offset:16
	v_add_u32_e32 v102, 64, v102
	v_add_u32_e32 v101, 32, v101
	s_cmp_eq_u32 s87, 32
	s_cbranch_scc0 .LBB0_184
	v_sub_f32_e32 v101, v87, v82
	ds_bpermute_b32 v87, v83, v103
	v_exp_f32_e32 v83, v101
	s_and_saveexec_b64 s[6:7], s[4:5]
	ds_write_b32 v97, v83 offset:8192
	s_or_b64 exec, exec, s[6:7]
	s_waitcnt lgkmcnt(0)
	v_add_f32_e32 v101, v103, v87
	v_fmac_f32_e32 v101, v88, v83
	v_mov_b32_e32 v87, v82
	v_mov_b32_e32 v88, v101

; template <int DH, int MODE>
; __device__ void attn_item(const Params& p, int layer, int b, int blk, int head, char* smem) {
;     ...
;   if (MODE == 0 && half == 0) linv_s[row] = 1.f / l_run;
;   __syncthreads();
;   {
;     constexpr int OST = DH + 4;
;     constexpr int CPR = DH / 8;
;     constexpr int NCH = 128 * CPR / 256;
;     float* Of = reinterpret_cast<float*>(smem);
;     uint4 gt[NCH];
; #pragma unroll
;     for (int i = 0; i < NCH; ++i) {
;       int q = tid + 256 * i, r = q / CPR, c = (q % CPR) * 8;
;       gt[i] = *reinterpret_cast<const uint4*>(P + (tq0 + r) * NP + gcol + c);
;     }
;     float lis[2][4];
; #pragma unroll
;     for (int m = 0; m < 2; ++m)
; #pragma unroll
;       for (int j = 0; j < 4; ++j) lis[m][j] = (MODE == 0) ? linv_s[wid * 32 + m * 16 + fq * 4 + j] : 1.f;
;     if (MODE == 0) __syncthreads();
; #pragma unroll
;     for (int m = 0; m < 2; ++m)
; #pragma unroll
;       for (int j = 0; j < 4; ++j) {
;         int r = wid * 32 + m * 16 + fq * 4 + j;
; #pragma unroll
;         for (int n = 0; n < NDT; ++n) Of[r * OST + n * 16 + fr] = o[m][n][j] * lis[m][j];
;       }
.LBB0_192:
	s_or_b64 exec, exec, s[6:7]
	v_lshl_add_u64 v[44:45], v[66:67], 0, s[26:27]
	v_mov_b64_e32 v[46:47], s[48:49]
	v_mad_u64_u32 v[32:33], s[6:7], v44, s55, v[46:47]
	v_mad_i32_i24 v33, v45, s55, v33
	v_lshl_add_u64 v[36:37], v[32:33], 0, v[70:71]
	v_add_u32_e32 v32, 0x100, v81
	v_ashrrev_i32_e32 v33, 31, v32
	v_lshrrev_b32_e32 v33, 29, v33
	v_add_u32_e32 v33, v32, v33
	v_ashrrev_i32_e32 v86, 3, v33
	v_and_b32_e32 v33, -8, v33
	v_sub_u32_e32 v85, v32, v33
	v_lshlrev_b32_e32 v32, 3, v85
	v_ashrrev_i32_e32 v33, 31, v32
	s_waitcnt vmcnt(2)
	v_add_u32_e32 v48, 0x200, v81
	v_lshlrev_b64 v[90:91], 1, v[32:33]
	v_ashrrev_i32_e32 v32, 31, v48
	v_lshrrev_b32_e32 v32, 29, v32
	v_add_u32_e32 v32, v48, v32
	v_ashrrev_i32_e32 v92, 3, v32
	v_and_b32_e32 v49, -8, v32
	v_add_u32_e32 v32, 0x300, v81
	v_ashrrev_i32_e32 v33, 31, v32
	v_lshrrev_b32_e32 v33, 29, v33
	v_ashrrev_i32_e32 v87, 31, v86
	v_add_u32_e32 v33, v32, v33
	v_lshl_add_u64 v[88:89], v[86:87], 0, s[26:27]
	v_ashrrev_i32_e32 v94, 3, v33
	v_and_b32_e32 v33, -8, v33
	v_mad_u64_u32 v[34:35], s[6:7], v88, s55, v[46:47]
	v_sub_u32_e32 v87, v32, v33
	v_ashrrev_i32_e32 v95, 31, v94
	v_mad_i32_i24 v35, v89, s55, v35
	v_lshlrev_b32_e32 v32, 3, v87
	v_lshl_add_u64 v[40:41], v[94:95], 0, s[26:27]
	v_lshl_add_u64 v[38:39], v[34:35], 0, v[90:91]
	v_mad_u64_u32 v[34:35], s[6:7], v40, s55, v[46:47]
	v_ashrrev_i32_e32 v33, 31, v32
	v_mad_i32_i24 v35, v41, s55, v35
	v_lshlrev_b64 v[42:43], 1, v[32:33]
	v_lshl_add_u64 v[32:33], v[34:35], 0, v[42:43]
	v_add_co_u32_e32 v32, vcc, s37, v32
	s_waitcnt lgkmcnt(0)
	s_nop 0
	v_addc_co_u32_e32 v33, vcc, 0, v33, vcc
	s_barrier
	global_load_dwordx4 v[32:35], v[32:33], off offset:512
	v_sub_u32_e32 v95, v48, v49
	v_ashrrev_i32_e32 v93, 31, v92
	v_lshlrev_b32_e32 v48, 3, v95
	v_lshl_add_u64 v[96:97], v[92:93], 0, s[26:27]
	v_mad_u64_u32 v[46:47], s[6:7], v96, s55, v[46:47]
	v_ashrrev_i32_e32 v49, 31, v48
	v_mad_i32_i24 v47, v97, s55, v47
	v_lshlrev_b64 v[98:99], 1, v[48:49]
	v_lshl_add_u64 v[100:101], v[46:47], 0, v[98:99]
	v_lshl_or_b32 v46, v75, 7, v128
	ds_read_b128 v[60:63], v46 offset:8704
	ds_read_b128 v[80:83], v46 offset:8768
	s_ashr_i32 s5, s8, 31
	s_add_u32 s4, s28, s8
	s_addc_u32 s5, s29, s5
	s_lshl_b32 s6, s80, 1
	s_add_u32 s4, s4, s6
	v_lshl_or_b32 v46, v84, 2, v64
	s_waitcnt lgkmcnt(0)
	v_mul_f32_e32 v69, v0, v80
	s_addc_u32 s5, s5, 0
	v_mul_lo_u32 v0, v66, s71
	v_mul_lo_u32 v46, v46, s71
	v_mul_f32_e32 v75, v1, v81
	v_lshl_add_u32 v66, v68, 2, v0
	v_mov_b64_e32 v[0:1], s[4:5]
	v_lshl_add_u32 v47, v73, 2, v46
	v_mul_f32_e32 v48, v16, v60
	v_mul_f32_e32 v49, v28, v60
	v_mul_f32_e32 v50, v24, v60
	v_mul_f32_e32 v51, v20, v60
	s_waitcnt vmcnt(1)
	v_mul_f32_e32 v52, v17, v61
	v_mul_f32_e32 v53, v29, v61
	v_mul_f32_e32 v54, v25, v61
	v_mul_f32_e32 v55, v21, v61
	v_mul_f32_e32 v56, v18, v62
	v_mul_f32_e32 v57, v30, v62
	v_mul_f32_e32 v58, v26, v62
	v_mul_f32_e32 v59, v22, v62
	v_mul_f32_e32 v60, v19, v63
	v_mul_f32_e32 v61, v31, v63
	v_mul_f32_e32 v62, v27, v63
	v_mul_f32_e32 v64, v23, v63
	v_mul_f32_e32 v63, v12, v80
	v_mul_f32_e32 v65, v8, v80
	v_mul_f32_e32 v67, v4, v80
	v_mul_f32_e32 v72, v13, v81
	v_mul_f32_e32 v73, v9, v81
	v_mul_f32_e32 v74, v5, v81
	v_mul_f32_e32 v76, v14, v82
	v_mul_f32_e32 v77, v10, v82
	v_mul_f32_e32 v78, v6, v82
	v_mul_f32_e32 v80, v2, v82
	v_mul_f32_e32 v79, v15, v83
	v_mul_f32_e32 v81, v11, v83
	v_mul_f32_e32 v82, v7, v83
	v_mul_f32_e32 v83, v3, v83
	v_mad_u64_u32 v[2:3], s[4:5], v44, s68, v[0:1]
	v_mad_i32_i24 v3, v45, s68, v3
	v_lshl_add_u64 v[12:13], v[2:3], 0, v[70:71]
	v_mul_lo_u32 v2, v86, s71
	v_lshl_add_u32 v46, v85, 5, v2
	v_mad_u64_u32 v[2:3], s[4:5], v88, s68, v[0:1]
	v_mad_i32_i24 v3, v89, s68, v3
	v_mad_u64_u32 v[4:5], s[4:5], v40, s68, v[0:1]
	v_lshl_add_u64 v[10:11], v[2:3], 0, v[90:91]
	v_mul_lo_u32 v2, v92, s71
	v_mad_i32_i24 v5, v41, s68, v5
	v_lshl_add_u32 v45, v95, 5, v2
	v_mad_u64_u32 v[2:3], s[4:5], v96, s68, v[0:1]
	v_lshl_add_u64 v[14:15], v[4:5], 0, v[42:43]
	v_mad_i32_i24 v3, v97, s68, v3
	v_add_co_u32_e32 v0, vcc, s37, v100
	v_lshl_add_u64 v[8:9], v[2:3], 0, v[98:99]
	v_mul_lo_u32 v2, v94, s71
	s_waitcnt vmcnt(0)
	v_lshlrev_b32_e32 v16, 16, v33
	v_lshlrev_b32_e32 v18, 16, v32
	v_mul_f32_e32 v6, 0xbfb8aa3b, v18
	v_mul_f32_e32 v7, 0xbfb8aa3b, v16
	v_exp_f32_e32 v6, v6
	v_exp_f32_e32 v7, v7
	v_addc_co_u32_e32 v1, vcc, 0, v101, vcc
	v_lshl_add_u32 v44, v87, 5, v2
	v_pk_add_f32 v[4:5], v[6:7], 1.0 op_sel_hi:[1,0]
	global_load_dwordx4 v[0:3], v[0:1], off offset:512
	v_and_b32_e32 v19, 0xffff0000, v33
	v_and_b32_e32 v20, 0xffff0000, v32
	v_mul_f32_e32 v6, 0xbfb8aa3b, v20
	v_rcp_f32_e32 v17, v5
	s_nop 0
	v_mul_f32_e32 v17, v16, v17
	v_mul_f32_e32 v7, 0xbfb8aa3b, v19
	v_exp_f32_e32 v6, v6
	v_exp_f32_e32 v7, v7
	s_nop 0
	v_pk_add_f32 v[6:7], v[6:7], 1.0 op_sel_hi:[1,0]
	v_rcp_f32_e32 v16, v4
	s_nop 0
	v_mul_f32_e32 v16, v18, v16
	v_lshlrev_b32_e32 v23, 16, v34
	v_rcp_f32_e32 v4, v7
	s_nop 0
	v_mul_f32_e32 v19, v19, v4
	v_lshlrev_b32_e32 v22, 16, v35
	v_mul_f32_e32 v4, 0xbfb8aa3b, v23
	v_mul_f32_e32 v5, 0xbfb8aa3b, v22
	v_exp_f32_e32 v4, v4
	v_exp_f32_e32 v5, v5
	v_rcp_f32_e32 v18, v6
	s_nop 0
	v_mul_f32_e32 v18, v20, v18
	v_and_b32_e32 v24, 0xffff0000, v35
	v_pk_add_f32 v[4:5], v[4:5], 1.0 op_sel_hi:[1,0]
	v_and_b32_e32 v25, 0xffff0000, v34
	v_mul_f32_e32 v6, 0xbfb8aa3b, v25
	v_exp_f32_e32 v6, v6
	v_rcp_f32_e32 v21, v5
	s_nop 0
	v_mul_f32_e32 v21, v22, v21
	v_mul_f32_e32 v7, 0xbfb8aa3b, v24
	v_exp_f32_e32 v7, v7
	s_nop 0
	v_pk_add_f32 v[6:7], v[6:7], 1.0 op_sel_hi:[1,0]
	v_rcp_f32_e32 v20, v4
	s_nop 0
	v_mul_f32_e32 v20, v23, v20
	v_rcp_f32_e32 v23, v7
	s_nop 0
	v_mul_f32_e32 v23, v24, v23
	s_waitcnt vmcnt(0)
; template <int DH, int MODE>
; __device__ void attn_item(const Params& p, int layer, int b, int blk, int head, char* smem) {
;     ...
;     for (int i = 0; i < NCH; ++i) {
;       int q = tid + 256 * i, r = q / CPR, c = (q % CPR) * 8;
;       gt[i] = *reinterpret_cast<const uint4*>(P + (tq0 + r) * NP + gcol + c);
;     }
;     float lis[2][4];
; #pragma unroll
;     for (int m = 0; m < 2; ++m)
; #pragma unroll
;       for (int j = 0; j < 4; ++j) lis[m][j] = (MODE == 0) ? linv_s[wid * 32 + m * 16 + fq * 4 + j] : 1.f;
;     if (MODE == 0) __syncthreads();
; #pragma unroll
;     for (int m = 0; m < 2; ++m)
; #pragma unroll
;       for (int j = 0; j < 4; ++j) {
;         int r = wid * 32 + m * 16 + fq * 4 + j;
; #pragma unroll
;         for (int n = 0; n < NDT; ++n) Of[r * OST + n * 16 + fr] = o[m][n][j] * lis[m][j];
;       }
;     __syncthreads();
	v_lshlrev_b32_e32 v24, 16, v1
	v_lshlrev_b32_e32 v26, 16, v0
	v_mul_f32_e32 v4, 0xbfb8aa3b, v26
	v_mul_f32_e32 v5, 0xbfb8aa3b, v24
	v_exp_f32_e32 v4, v4
	v_exp_f32_e32 v5, v5
	v_and_b32_e32 v27, 0xffff0000, v1
	v_rcp_f32_e32 v22, v6
	s_nop 0
	v_mul_f32_e32 v22, v25, v22
	v_pk_add_f32 v[4:5], v[4:5], 1.0 op_sel_hi:[1,0]
	v_and_b32_e32 v28, 0xffff0000, v0
	v_mul_f32_e32 v0, 0xbfb8aa3b, v28
	v_exp_f32_e32 v6, v0
	v_lshlrev_b32_e32 v32, 16, v3
	v_mul_f32_e32 v7, 0xbfb8aa3b, v27
	v_rcp_f32_e32 v1, v5
	s_nop 0
	v_mul_f32_e32 v1, v24, v1
	v_exp_f32_e32 v7, v7
	s_nop 0
	v_pk_add_f32 v[24:25], v[6:7], 1.0 op_sel_hi:[1,0]
	v_rcp_f32_e32 v0, v4
	s_nop 0
	v_mul_f32_e32 v0, v26, v0
	v_lshlrev_b32_e32 v33, 16, v2
	v_rcp_f32_e32 v25, v25
	s_nop 0
	v_mul_f32_e32 v25, v27, v25
	v_add_co_u32_e64 v4, s[4:5], s37, v38
	s_nop 0
	s_nop 0
	v_addc_co_u32_e64 v5, s[4:5], 0, v39, s[4:5]
	global_load_dwordx4 v[4:7], v[4:5], off offset:512
	v_mul_f32_e32 v26, 0xbfb8aa3b, v33
	v_mul_f32_e32 v27, 0xbfb8aa3b, v32
	v_exp_f32_e32 v26, v26
	v_exp_f32_e32 v27, v27
	v_and_b32_e32 v30, 0xffff0000, v3
	v_rcp_f32_e32 v24, v24
	s_nop 0
	v_mul_f32_e32 v24, v28, v24
	v_pk_add_f32 v[26:27], v[26:27], 1.0 op_sel_hi:[1,0]
	v_and_b32_e32 v38, 0xffff0000, v2
	v_mul_f32_e32 v2, 0xbfb8aa3b, v38
	v_exp_f32_e32 v28, v2
	v_mul_f32_e32 v29, 0xbfb8aa3b, v30
	v_exp_f32_e32 v29, v29
	v_rcp_f32_e32 v3, v27
	s_nop 0
	v_mul_f32_e32 v3, v32, v3
	v_pk_add_f32 v[28:29], v[28:29], 1.0 op_sel_hi:[1,0]
	v_rcp_f32_e32 v2, v26
	s_nop 0
	v_mul_f32_e32 v2, v33, v2
	v_rcp_f32_e32 v27, v29
	s_nop 0
	v_mul_f32_e32 v27, v30, v27
	v_add_co_u32_e64 v30, s[4:5], s37, v36
	s_nop 0
	s_nop 0
	v_addc_co_u32_e64 v31, s[4:5], 0, v37, s[4:5]
	global_load_dwordx4 v[32:35], v[30:31], off offset:512
	v_rcp_f32_e32 v26, v28
	s_nop 0
	v_mul_f32_e32 v26, v38, v26
	s_barrier
	s_waitcnt vmcnt(1)
	v_lshlrev_b32_e32 v36, 16, v5
	v_lshlrev_b32_e32 v37, 16, v4
	v_mul_f32_e32 v30, 0xbfb8aa3b, v37
	v_mul_f32_e32 v31, 0xbfb8aa3b, v36
	v_exp_f32_e32 v30, v30
	v_exp_f32_e32 v31, v31
	v_and_b32_e32 v38, 0xffff0000, v5
	v_and_b32_e32 v39, 0xffff0000, v4
	v_mul_f32_e32 v4, 0xbfb8aa3b, v39
	v_pk_add_f32 v[28:29], v[30:31], 1.0 op_sel_hi:[1,0]
	v_exp_f32_e32 v30, v4
	ds_write2_b32 v47, v48, v49 offset1:16
	ds_write2_b32 v47, v50, v51 offset0:32 offset1:48
	ds_write2_b32 v47, v52, v53 offset0:68 offset1:84
	ds_write2_b32 v47, v54, v55 offset0:100 offset1:116
	ds_write2_b32 v47, v56, v57 offset0:136 offset1:152
	ds_write2_b32 v47, v58, v59 offset0:168 offset1:184
	ds_write2_b32 v47, v60, v61 offset0:204 offset1:220
	ds_write2_b32 v47, v62, v64 offset0:236 offset1:252
	v_mul_f32_e32 v31, 0xbfb8aa3b, v38
	v_exp_f32_e32 v31, v31
	v_rcp_f32_e32 v5, v29
	s_nop 0
	v_mul_f32_e32 v5, v36, v5
	v_pk_add_f32 v[30:31], v[30:31], 1.0 op_sel_hi:[1,0]
	v_rcp_f32_e32 v4, v28
	s_nop 0
	v_mul_f32_e32 v4, v37, v4
	v_rcp_f32_e32 v29, v31
	s_nop 0
	v_mul_f32_e32 v29, v38, v29
	v_lshlrev_b32_e32 v38, 16, v7
	v_lshlrev_b32_e32 v40, 16, v6
	v_mul_f32_e32 v36, 0xbfb8aa3b, v40
	v_mul_f32_e32 v37, 0xbfb8aa3b, v38
	v_exp_f32_e32 v36, v36
	v_exp_f32_e32 v37, v37
	v_rcp_f32_e32 v28, v30
	s_nop 0
	v_mul_f32_e32 v28, v39, v28
	v_and_b32_e32 v39, 0xffff0000, v7
	v_pk_add_f32 v[30:31], v[36:37], 1.0 op_sel_hi:[1,0]
	v_and_b32_e32 v41, 0xffff0000, v6
	v_mul_f32_e32 v6, 0xbfb8aa3b, v41
	v_exp_f32_e32 v36, v6
	v_mul_f32_e32 v37, 0xbfb8aa3b, v39
	v_exp_f32_e32 v37, v37
	v_rcp_f32_e32 v7, v31
	s_nop 0
	v_mul_f32_e32 v7, v38, v7
	v_pk_add_f32 v[36:37], v[36:37], 1.0 op_sel_hi:[1,0]
	v_rcp_f32_e32 v6, v30
	s_nop 0
	v_mul_f32_e32 v6, v40, v6
	v_rcp_f32_e32 v31, v37
	s_nop 0
	v_mul_f32_e32 v31, v39, v31
	s_waitcnt vmcnt(0)
	v_lshlrev_b32_e32 v42, 16, v33
	v_lshlrev_b32_e32 v43, 16, v32
	v_mul_f32_e32 v38, 0xbfb8aa3b, v43
	v_mul_f32_e32 v39, 0xbfb8aa3b, v42
	v_exp_f32_e32 v38, v38
	v_exp_f32_e32 v39, v39
	v_rcp_f32_e32 v30, v36
	s_nop 0
	v_mul_f32_e32 v30, v41, v30
	v_and_b32_e32 v68, 0xffff0000, v33
	v_pk_add_f32 v[36:37], v[38:39], 1.0 op_sel_hi:[1,0]
	v_and_b32_e32 v39, 0xffff0000, v32
	v_mul_f32_e32 v32, 0xbfb8aa3b, v39
	v_exp_f32_e32 v32, v32
	v_rcp_f32_e32 v41, v37
	s_nop 0
	v_mul_f32_e32 v41, v42, v41
	v_mul_f32_e32 v33, 0xbfb8aa3b, v68
	v_exp_f32_e32 v33, v33
	s_nop 0
	v_pk_add_f32 v[32:33], v[32:33], 1.0 op_sel_hi:[1,0]
	v_rcp_f32_e32 v40, v36
	s_nop 0
	v_mul_f32_e32 v40, v43, v40
	v_lshlrev_b32_e32 v70, 16, v34
	v_rcp_f32_e32 v43, v33
	s_nop 0
	v_mul_f32_e32 v43, v68, v43
	v_lshlrev_b32_e32 v38, 16, v35
	v_mul_f32_e32 v36, 0xbfb8aa3b, v70
	v_mul_f32_e32 v37, 0xbfb8aa3b, v38
	v_exp_f32_e32 v36, v36
	v_exp_f32_e32 v37, v37
	v_rcp_f32_e32 v42, v32
	s_nop 0
	v_mul_f32_e32 v42, v39, v42
	v_and_b32_e32 v39, 0xffff0000, v35
	v_pk_add_f32 v[32:33], v[36:37], 1.0 op_sel_hi:[1,0]
	v_and_b32_e32 v68, 0xffff0000, v34
	v_mul_f32_e32 v34, 0xbfb8aa3b, v68
	v_exp_f32_e32 v34, v34
	v_rcp_f32_e32 v71, v33
	s_nop 0
	v_mul_f32_e32 v71, v38, v71
	v_mul_f32_e32 v35, 0xbfb8aa3b, v39
	v_exp_f32_e32 v35, v35
	s_nop 0
	v_pk_add_f32 v[36:37], v[34:35], 1.0 op_sel_hi:[1,0]
	v_rcp_f32_e32 v33, v32
	s_nop 0
	v_mul_f32_e32 v70, v70, v33
	v_rcp_f32_e32 v85, v37
	s_nop 0
	v_mul_f32_e32 v85, v39, v85
	v_add_u32_e32 v32, 0x1000, v47
	ds_write2_b32 v32, v63, v65 offset0:64 offset1:80
	ds_write2_b32 v32, v67, v69 offset0:96 offset1:112
	ds_write2_b32 v32, v72, v73 offset0:132 offset1:148
	ds_write2_b32 v32, v74, v75 offset0:164 offset1:180
	ds_write2_b32 v32, v76, v77 offset0:200 offset1:216
	ds_write2_b32 v32, v78, v80 offset0:232 offset1:248
	v_add_u32_e32 v32, 0x1400, v47
	ds_write2_b32 v32, v79, v81 offset0:12 offset1:28
	ds_write2_b32 v32, v82, v83 offset0:44 offset1:60
	s_waitcnt lgkmcnt(0)
	s_barrier
; __device__ __forceinline__ unsigned pack2(float a, float b) { return (unsigned)f2bf(a) | ((unsigned)f2bf(b) << 16); }
; __device__ __forceinline__ float bflo(unsigned w) { return __uint_as_float(w << 16); }
; __device__ __forceinline__ float bfhi(unsigned w) { return __uint_as_float(w & 0xffff0000u); }
; __device__ __forceinline__ float silu_f(float g) { return g / (1.f + __expf(-g)); }
; template <int DH, int MODE>
; __device__ void attn_item(const Params& p, int layer, int b, int blk, int head, char* smem) {
;     ...
; #pragma unroll
;     for (int i = 0; i < NCH; ++i) {
;       int q = tid + 256 * i, r = q / CPR, c = (q % CPR) * 8;
;       float4 m0 = *reinterpret_cast<const float4*>(Of + r * OST + c);
;       float4 m1 = *reinterpret_cast<const float4*>(Of + r * OST + c + 4);
;       float mm[8] = {m0.x, m0.y, m0.z, m0.w, m1.x, m1.y, m1.z, m1.w};
;       unsigned gw[4] = {gt[i].x, gt[i].y, gt[i].z, gt[i].w};
;       unsigned ow[4];
; #pragma unroll
;       for (int e = 0; e < 4; ++e)
;         ow[e] = pack2(mm[2 * e] * silu_f(bflo(gw[e])), mm[2 * e + 1] * silu_f(bfhi(gw[e])));
;       *reinterpret_cast<uint4*>(Y + (tq0 + r) * YW + ycol + c) = make_uint4(ow[0], ow[1], ow[2], ow[3]);
;     }
	ds_read_b128 v[32:35], v66
	v_rcp_f32_e32 v84, v36
	s_nop 0
	v_mul_f32_e32 v84, v68, v84
	ds_read_b128 v[36:39], v66 offset:16
	v_add_co_u32_e32 v12, vcc, s74, v12
	s_waitcnt lgkmcnt(1)
	v_mov_b32_e32 v48, v32
	v_mov_b32_e32 v49, v34
	v_pk_mul_f32 v[40:41], v[40:41], v[48:49]
	v_mov_b32_e32 v34, v33
	v_pk_mul_f32 v[32:33], v[42:43], v[34:35]
	v_cvt_pk_bf16_f32 v33, v41, v33
	v_cvt_pk_bf16_f32 v32, v40, v32
	s_waitcnt lgkmcnt(0)
	v_mov_b32_e32 v34, v36
	v_mov_b32_e32 v35, v38
	v_pk_mul_f32 v[34:35], v[70:71], v[34:35]
	v_mov_b32_e32 v38, v37
	v_pk_mul_f32 v[36:37], v[84:85], v[38:39]
	v_cvt_pk_bf16_f32 v35, v35, v37
	v_cvt_pk_bf16_f32 v34, v34, v36
	ds_read_b128 v[36:39], v46
	v_addc_co_u32_e32 v13, vcc, 0, v13, vcc
	global_store_dwordx4 v[12:13], v[32:35], off offset:1024
	s_nop 0
	ds_read_b128 v[32:35], v46 offset:16
	s_waitcnt lgkmcnt(1)
	v_mov_b32_e32 v12, v36
	v_mov_b32_e32 v13, v38
	v_pk_mul_f32 v[4:5], v[4:5], v[12:13]
	v_mov_b32_e32 v38, v37
	v_pk_mul_f32 v[12:13], v[28:29], v[38:39]
	v_cvt_pk_bf16_f32 v5, v5, v13
	v_cvt_pk_bf16_f32 v4, v4, v12
	s_waitcnt lgkmcnt(0)
	v_mov_b32_e32 v12, v32
	v_mov_b32_e32 v13, v34
	v_pk_mul_f32 v[6:7], v[6:7], v[12:13]
	v_mov_b32_e32 v34, v33
	v_pk_mul_f32 v[12:13], v[30:31], v[34:35]
	ds_read_b128 v[28:31], v45
	v_add_co_u32_e32 v10, vcc, s74, v10
	v_cvt_pk_bf16_f32 v7, v7, v13
	v_cvt_pk_bf16_f32 v6, v6, v12
	v_addc_co_u32_e32 v11, vcc, 0, v11, vcc
	global_store_dwordx4 v[10:11], v[4:7], off offset:1024
	s_waitcnt lgkmcnt(0)
	v_mov_b32_e32 v10, v28
	v_mov_b32_e32 v11, v30
	ds_read_b128 v[4:7], v45 offset:16
	v_pk_mul_f32 v[0:1], v[0:1], v[10:11]
	v_mov_b32_e32 v30, v29
	v_pk_mul_f32 v[10:11], v[24:25], v[30:31]
	v_cvt_pk_bf16_f32 v1, v1, v11
	v_cvt_pk_bf16_f32 v0, v0, v10
	s_waitcnt lgkmcnt(0)
	v_mov_b32_e32 v10, v4
	v_mov_b32_e32 v11, v6
	v_pk_mul_f32 v[2:3], v[2:3], v[10:11]
	v_mov_b32_e32 v6, v5
	v_pk_mul_f32 v[4:5], v[26:27], v[6:7]
	v_cvt_pk_bf16_f32 v3, v3, v5
	v_cvt_pk_bf16_f32 v2, v2, v4
	ds_read_b128 v[4:7], v44
	v_add_co_u32_e32 v8, vcc, s74, v8
	s_nop 1
	v_addc_co_u32_e32 v9, vcc, 0, v9, vcc
	global_store_dwordx4 v[8:9], v[0:3], off offset:1024
	s_waitcnt lgkmcnt(0)
	v_mov_b32_e32 v8, v4
	v_mov_b32_e32 v9, v6
	ds_read_b128 v[0:3], v44 offset:16
	v_pk_mul_f32 v[8:9], v[16:17], v[8:9]
	v_mov_b32_e32 v6, v5
	v_pk_mul_f32 v[4:5], v[18:19], v[6:7]
	v_cvt_pk_bf16_f32 v5, v9, v5
	v_cvt_pk_bf16_f32 v4, v8, v4
	s_waitcnt lgkmcnt(0)
	v_mov_b32_e32 v6, v0
	v_mov_b32_e32 v7, v2
	v_pk_mul_f32 v[6:7], v[20:21], v[6:7]
	v_mov_b32_e32 v2, v1
	v_pk_mul_f32 v[0:1], v[22:23], v[2:3]
	v_cvt_pk_bf16_f32 v6, v6, v0
	v_add_co_u32_e32 v0, vcc, 0x184a1000, v14
	v_cvt_pk_bf16_f32 v7, v7, v1
	s_nop 0
	v_addc_co_u32_e32 v1, vcc, 0, v15, vcc
	global_store_dwordx4 v[0:1], v[4:7], off offset:1024
	s_barrier

; __device__ __forceinline__ unsigned pack2(float a, float b) { return (unsigned)f2bf(a) | ((unsigned)f2bf(b) << 16); }
; template <int DH, int MODE>
; __device__ void attn_item(const Params& p, int layer, int b, int blk, int head, char* smem) {
;     ...
; #pragma unroll 2
;         for (int s8 = 0; s8 < 4; ++s8) {
;           float4 va = s4[2 * s8], vb = s4[2 * s8 + 1];
;           float e[8] = {va.x, va.y, va.z, va.w, vb.x, vb.y, vb.z, vb.w};
;           float pv[8];
; #pragma unroll
;           for (int k = 0; k < 8; ++k) {
;             bool valid = (kpb + s8 * 8 + k) < qpos;
;             pv[k] = valid ? __builtin_amdgcn_exp2f(e[k] + offs) : 0.f;
;           }
;           uint4 ov;
;           ov.x = pack2(pv[0], pv[1]); ov.y = pack2(pv[2], pv[3]);
;           ov.z = pack2(pv[4], pv[5]); ov.w = pack2(pv[6], pv[7]);
;           *reinterpret_cast<uint4*>(prow + s8 * 16) = ov;
;         }
.LBB0_207:
	s_or_b64 exec, exec, s[52:53]
	s_waitcnt lgkmcnt(3)
	v_add_f32_e32 v152, v176, v152
	v_exp_f32_e32 v152, v152
	s_waitcnt lgkmcnt(1)
	v_add_f32_e32 v149, v176, v149
	v_exp_f32_e32 v149, v149
	v_add_u32_e32 v182, 0x3fc9, v178
	v_add_f32_e32 v151, v176, v151
	v_add_f32_e32 v148, v176, v148
	v_cmp_lt_i32_e32 vcc, v182, v144
	v_exp_f32_e32 v185, v151
	v_exp_f32_e32 v186, v148
	v_add_u32_e32 v148, 0x3fce, v178
	s_waitcnt lgkmcnt(0)
	v_add_f32_e32 v151, v176, v180
	v_cndmask_b32_e32 v152, 0, v152, vcc
	v_exp_f32_e32 v151, v151
	v_cmp_lt_i32_e32 vcc, v148, v144
	v_add_u32_e32 v148, 0x3fcf, v178
	v_add_f32_e32 v153, v176, v153
	v_cndmask_b32_e32 v149, 0, v149, vcc
	v_cmp_lt_i32_e32 vcc, v148, v144
	v_cvt_pk_bf16_f32 v148, 0, v179
	v_exp_f32_e32 v153, v153
	v_lshrrev_b32_e32 v148, 16, v148
	v_cvt_pk_bf16_f32 v152, 0, v152
	v_add_f32_e32 v150, v176, v150
	v_cndmask_b32_e32 v151, 0, v151, vcc
	v_and_or_b32 v148, v152, s62, v148
	v_or_b32_e32 v182, 2, v181
	v_exp_f32_e32 v150, v150
	v_cvt_pk_bf16_f32 v149, 0, v149
	v_or_b32_e32 v183, 4, v181
	v_lshrrev_b32_e32 v149, 16, v149
	v_cvt_pk_bf16_f32 v151, 0, v151
	v_cmp_lt_i32_e32 vcc, v182, v144
	v_or_b32_e32 v184, 5, v181
	v_or_b32_e32 v181, 3, v181
	v_and_or_b32 v151, v151, s62, v149
	v_cndmask_b32_e32 v149, 0, v153, vcc
	v_cmp_lt_i32_e32 vcc, v183, v131
	v_cvt_pk_bf16_f32 v149, 0, v149
	s_nop 0
	v_cndmask_b32_e32 v152, 0, v185, vcc
	v_cmp_lt_i32_e32 vcc, v181, v144
	s_nop 0
	s_nop 0
	v_cndmask_b32_e32 v150, 0, v150, vcc
	v_cmp_lt_i32_e32 vcc, v184, v131
	v_cvt_pk_bf16_f32 v150, 0, v150
	s_nop 0
	v_cndmask_b32_e32 v153, 0, v186, vcc
	v_and_b32_e32 v178, 0xffff0000, v150
	v_cvt_pk_bf16_f32 v150, v152, v153
	v_or_b32_sdwa v149, v178, v149 dst_sel:DWORD dst_unused:UNUSED_PAD src0_sel:DWORD src1_sel:WORD_1
	s_add_i32 s85, s85, 16
	ds_write_b128 v175, v[148:151] offset:16
	v_add_u32_e32 v177, 64, v177
	s_cmp_eq_u32 s85, 32
	v_add_u32_e32 v175, 32, v175
	s_cbranch_scc1 .LBB0_213

; __device__ __forceinline__ unsigned pack2(float a, float b) { return (unsigned)f2bf(a) | ((unsigned)f2bf(b) << 16); }
; template <int DH, int MODE>
; __device__ void attn_item(const Params& p, int layer, int b, int blk, int head, char* smem) {
;     ...
; #pragma unroll 2
;         for (int s8 = 0; s8 < 4; ++s8) {
;           float4 va = s4[2 * s8], vb = s4[2 * s8 + 1];
;           float e[8] = {va.x, va.y, va.z, va.w, vb.x, vb.y, vb.z, vb.w};
;           float pv[8];
; #pragma unroll
;           for (int k = 0; k < 8; ++k) {
;             bool valid = (kpb + s8 * 8 + k) < qpos;
;             pv[k] = valid ? __builtin_amdgcn_exp2f(e[k] + offs) : 0.f;
;           }
;           uint4 ov;
;           ov.x = pack2(pv[0], pv[1]); ov.y = pack2(pv[2], pv[3]);
;           ov.z = pack2(pv[4], pv[5]); ov.w = pack2(pv[6], pv[7]);
;           *reinterpret_cast<uint4*>(prow + s8 * 16) = ov;
;         }
.LBB0_210:
	s_or_b64 exec, exec, s[52:53]
	s_waitcnt lgkmcnt(3)
	v_add_f32_e32 v152, v176, v152
	v_exp_f32_e32 v152, v152
	s_waitcnt lgkmcnt(1)
	v_add_f32_e32 v149, v176, v149
	v_exp_f32_e32 v149, v149
	v_add_u32_e32 v183, 0x3fc1, v178
	v_add_f32_e32 v151, v176, v151
	v_add_f32_e32 v148, v176, v148
	v_cmp_lt_i32_e32 vcc, v183, v144
	v_exp_f32_e32 v186, v151
	v_exp_f32_e32 v187, v148
	v_add_u32_e32 v148, 0x3fc6, v178
	s_waitcnt lgkmcnt(0)
	v_add_f32_e32 v151, v176, v180
	v_cndmask_b32_e32 v152, 0, v152, vcc
	v_exp_f32_e32 v151, v151
	v_cmp_lt_i32_e32 vcc, v148, v144
	v_add_u32_e32 v148, 0x3fc7, v178
	v_add_f32_e32 v153, v176, v153
	v_cndmask_b32_e32 v149, 0, v149, vcc
	v_cmp_lt_i32_e32 vcc, v148, v144
	v_cvt_pk_bf16_f32 v148, 0, v181
	v_exp_f32_e32 v153, v153
	v_lshrrev_b32_e32 v148, 16, v148
	v_cvt_pk_bf16_f32 v152, 0, v152
	v_add_f32_e32 v150, v176, v150
	v_cndmask_b32_e32 v151, 0, v151, vcc
	v_and_or_b32 v148, v152, s62, v148
	v_or_b32_e32 v183, 2, v182
	v_exp_f32_e32 v150, v150
	v_cvt_pk_bf16_f32 v149, 0, v149
	v_or_b32_e32 v184, 4, v182
	v_lshrrev_b32_e32 v149, 16, v149
	v_cvt_pk_bf16_f32 v151, 0, v151
	v_cmp_lt_i32_e32 vcc, v183, v144
	v_or_b32_e32 v185, 5, v182
	v_or_b32_e32 v182, 3, v182
	v_and_or_b32 v151, v151, s62, v149
	v_cndmask_b32_e32 v149, 0, v153, vcc
	v_cmp_lt_i32_e32 vcc, v184, v131
	v_cvt_pk_bf16_f32 v149, 0, v149
	s_nop 0
	v_cndmask_b32_e32 v152, 0, v186, vcc
	v_cmp_lt_i32_e32 vcc, v182, v144
	s_nop 0
	s_nop 0
	v_cndmask_b32_e32 v150, 0, v150, vcc
	v_cmp_lt_i32_e32 vcc, v185, v131
	v_cvt_pk_bf16_f32 v150, 0, v150
	s_nop 0
	v_cndmask_b32_e32 v153, 0, v187, vcc
	v_and_b32_e32 v180, 0xffff0000, v150
	v_cvt_pk_bf16_f32 v150, v152, v153
	v_or_b32_sdwa v149, v180, v149 dst_sel:DWORD dst_unused:UNUSED_PAD src0_sel:DWORD src1_sel:WORD_1
	ds_write_b128 v175, v[148:151]
	ds_read2_b32 v[152:153], v177 offset0:9 offset1:10
	ds_read2_b32 v[150:151], v177 offset0:11 offset1:12
	ds_read2_b32 v[148:149], v177 offset0:13 offset1:14
	ds_read_b32 v180, v177 offset:60
	v_add_u32_e32 v181, 0x3fc8, v178
	v_cmp_lt_i32_e32 vcc, v181, v144
	s_and_saveexec_b64 s[52:53], vcc
	s_cbranch_execz .LBB0_207
	ds_read_b32 v179, v177 offset:32
	s_waitcnt lgkmcnt(0)
	v_add_f32_e32 v179, v176, v179
	v_exp_f32_e32 v179, v179
	s_branch .LBB0_207

; __device__ __forceinline__ float bflo(unsigned w) { return __uint_as_float(w << 16); }
; __device__ __forceinline__ float bfhi(unsigned w) { return __uint_as_float(w & 0xffff0000u); }
; __device__ void norm_phase(const Params& p, int layer) {
;     ...
;   for (int r2 = gw; r2 < NTOK / 2; r2 += nw) {
;     const int row = r2 * 2 + sub;
;     const size_t rbase = (size_t)row * DM + l32 * 4;
;     float4 xv[8];
;     if (layer < 0) {
; #pragma unroll
;       for (int i = 0; i < 8; ++i) xv[i] = *reinterpret_cast<const float4*>(p.x + rbase + i * 128);
;     } else {
;       const float* xr = (layer == 0) ? p.x : p.out;
;       float4 ov[8];
;       float ss = 0.f;
; #pragma unroll
;       for (int i = 0; i < 8; ++i) {
;         {
;           uint2 ob = *reinterpret_cast<const uint2*>(OUTB + rbase + i * 128);
;           ov[i] = make_float4(bflo(ob.x), bfhi(ob.x), bflo(ob.y), bfhi(ob.y));
;         }
;         xv[i] = *reinterpret_cast<const float4*>(xr + rbase + i * 128);
;       }
; #pragma unroll
;       for (int i = 0; i < 8; ++i) ss += ov[i].x * ov[i].x + ov[i].y * ov[i].y + ov[i].z * ov[i].z + ov[i].w * ov[i].w;
;       ss = half_wave_sum(ss);
;       float rstd = rsqrtf(ss * (1.f / 1024.f) + 1e-6f);
; #pragma unroll
;       for (int i = 0; i < 8; ++i) {
;         float4 g = *reinterpret_cast<const float4*>(p.g_post + (size_t)layer * DM + l32 * 4 + i * 128);
;         xv[i].x += ov[i].x * rstd * g.x;
;         xv[i].y += ov[i].y * rstd * g.y;
;         xv[i].z += ov[i].z * rstd * g.z;
;         xv[i].w += ov[i].w * rstd * g.w;
;         *reinterpret_cast<float4*>(p.out + rbase + i * 128) = xv[i];
;       }
.LBB0_359:
	v_ashrrev_i32_e32 v39, 31, v38
	v_lshlrev_b64 v[4:5], 10, v[38:39]
	v_or_b32_e32 v4, v4, v32
	v_lshlrev_b64 v[40:41], 1, v[4:5]
	v_lshl_add_u64 v[6:7], s[10:11], 0, v[40:41]
	global_load_dwordx2 v[12:13], v[6:7], off
	global_load_dwordx2 v[14:15], v[6:7], off offset:256
	global_load_dwordx2 v[16:17], v[6:7], off offset:512
	global_load_dwordx2 v[18:19], v[6:7], off offset:768
	global_load_dwordx2 v[20:21], v[6:7], off offset:1024
	global_load_dwordx2 v[22:23], v[6:7], off offset:1280
	global_load_dwordx2 v[24:25], v[6:7], off offset:1536
	global_load_dwordx2 v[26:27], v[6:7], off offset:1792
	global_load_dwordx4 v[0:3], v[34:35], off
	v_lshlrev_b64 v[28:29], 2, v[4:5]
	v_lshl_add_u64 v[30:31], s[12:13], 0, v[28:29]
	global_load_dwordx4 v[8:11], v[30:31], off
	s_waitcnt vmcnt(18)
	v_lshl_add_u64 v[98:99], s[14:15], 0, v[28:29]
	v_lshl_add_u64 v[40:41], s[8:9], 0, v[40:41]
	v_add_u32_e32 v33, s56, v33
	v_add_u32_e32 v38, s26, v38
	s_waitcnt vmcnt(9)
	v_lshlrev_b32_e32 v70, 16, v12
	v_and_b32_e32 v71, 0xffff0000, v12
	s_waitcnt vmcnt(8)
	v_lshlrev_b32_e32 v74, 16, v14
	v_and_b32_e32 v75, 0xffff0000, v14
	s_waitcnt vmcnt(7)
	v_and_b32_e32 v79, 0xffff0000, v16
	s_waitcnt vmcnt(6)
	v_and_b32_e32 v83, 0xffff0000, v18
	v_lshlrev_b32_e32 v72, 16, v13
	v_and_b32_e32 v73, 0xffff0000, v13
	v_lshlrev_b32_e32 v76, 16, v15
	v_and_b32_e32 v77, 0xffff0000, v15
	v_lshlrev_b32_e32 v78, 16, v16
	v_lshlrev_b32_e32 v80, 16, v17
	v_and_b32_e32 v81, 0xffff0000, v17
	v_lshlrev_b32_e32 v82, 16, v18
	s_waitcnt vmcnt(4)
	v_lshlrev_b32_e32 v90, 16, v22
	v_and_b32_e32 v91, 0xffff0000, v22
	v_lshlrev_b32_e32 v92, 16, v23
	v_and_b32_e32 v93, 0xffff0000, v23
	v_pk_mul_f32 v[12:13], v[70:71], v[70:71]
	v_pk_mul_f32 v[16:17], v[74:75], v[74:75]
	v_mov_b32_e32 v22, v79
	v_mov_b32_e32 v23, v83
	v_lshlrev_b32_e32 v84, 16, v19
	v_and_b32_e32 v85, 0xffff0000, v19
	v_lshlrev_b32_e32 v86, 16, v20
	v_and_b32_e32 v87, 0xffff0000, v20
	v_lshlrev_b32_e32 v88, 16, v21
	v_and_b32_e32 v89, 0xffff0000, v21
	v_pk_mul_f32 v[14:15], v[72:73], v[72:73]
	v_pk_mul_f32 v[18:19], v[76:77], v[76:77]
	v_mov_b32_e32 v20, v78
	v_mov_b32_e32 v21, v82
	v_pk_mul_f32 v[22:23], v[22:23], v[22:23]
	v_add_f32_e32 v39, v16, v17
	v_add_f32_e32 v12, v12, v13
	s_waitcnt vmcnt(3)
	v_lshlrev_b32_e32 v94, 16, v24
	v_and_b32_e32 v95, 0xffff0000, v24
	v_lshlrev_b32_e32 v96, 16, v25
	v_and_b32_e32 v97, 0xffff0000, v25
	v_mov_b32_e32 v24, v80
	v_mov_b32_e32 v25, v84
	v_mov_b32_e32 v52, v87
	v_mov_b32_e32 v53, v91
	v_pk_fma_f32 v[16:17], v[20:21], v[20:21], v[22:23]
	v_add_f32_e32 v18, v39, v18
	v_add_f32_e32 v12, v12, v14
	s_waitcnt vmcnt(2)
	v_lshlrev_b32_e32 v6, 16, v26
	v_and_b32_e32 v7, 0xffff0000, v26
	v_lshlrev_b32_e32 v4, 16, v27
	v_and_b32_e32 v5, 0xffff0000, v27
	v_mov_b32_e32 v26, v81
	v_mov_b32_e32 v27, v85
	v_mov_b32_e32 v50, v86
	v_mov_b32_e32 v51, v90
	v_pk_mul_f32 v[52:53], v[52:53], v[52:53]
	v_pk_fma_f32 v[16:17], v[24:25], v[24:25], v[16:17]
	v_add_f32_e32 v18, v19, v18
	v_add_f32_e32 v12, v15, v12
	v_mov_b32_e32 v54, v88
	v_mov_b32_e32 v55, v92
	v_mov_b32_e32 v60, v95
	v_mov_b32_e32 v61, v7
	v_pk_fma_f32 v[20:21], v[50:51], v[50:51], v[52:53]
	v_pk_fma_f32 v[16:17], v[26:27], v[26:27], v[16:17]
	v_add_f32_e32 v12, v12, v18
	v_mov_b32_e32 v56, v89
	v_mov_b32_e32 v57, v93
	v_mov_b32_e32 v58, v94
	v_mov_b32_e32 v59, v6
	v_pk_mul_f32 v[60:61], v[60:61], v[60:61]
	v_pk_fma_f32 v[20:21], v[54:55], v[54:55], v[20:21]
	v_add_f32_e32 v12, v12, v16
	v_mov_b32_e32 v62, v96
	v_mov_b32_e32 v63, v4
	v_pk_fma_f32 v[22:23], v[58:59], v[58:59], v[60:61]
	v_pk_fma_f32 v[20:21], v[56:57], v[56:57], v[20:21]
	v_add_f32_e32 v12, v12, v17
	v_mov_b32_e32 v64, v97
	v_mov_b32_e32 v65, v5
	v_pk_fma_f32 v[22:23], v[62:63], v[62:63], v[22:23]
	v_add_f32_e32 v12, v12, v20
	v_pk_fma_f32 v[22:23], v[64:65], v[64:65], v[22:23]
	v_add_f32_e32 v12, v12, v21
	v_add_f32_e32 v12, v12, v22
	v_add_f32_e32 v12, v12, v23
	ds_bpermute_b32 v13, v42, v12
	s_waitcnt lgkmcnt(0)
	v_add_f32_e32 v12, v12, v13
	ds_bpermute_b32 v13, v43, v12
	s_waitcnt lgkmcnt(0)
	v_add_f32_e32 v12, v12, v13
	ds_bpermute_b32 v13, v44, v12
	s_waitcnt lgkmcnt(0)
	v_add_f32_e32 v12, v12, v13
	ds_bpermute_b32 v13, v45, v12
	s_waitcnt lgkmcnt(0)
	v_add_f32_e32 v20, v12, v13
	ds_bpermute_b32 v21, v46, v20
	global_load_dwordx4 v[12:15], v[30:31], off offset:512
	global_load_dwordx4 v[16:19], v[30:31], off offset:1024
	global_load_dwordx4 v[50:53], v[30:31], off offset:1536
	global_load_dwordx4 v[54:57], v[30:31], off offset:2048
	global_load_dwordx4 v[58:61], v[30:31], off offset:2560
	global_load_dwordx4 v[62:65], v[30:31], off offset:3072
	global_load_dwordx4 v[66:69], v[30:31], off offset:3584
	s_waitcnt lgkmcnt(0)
	v_add_f32_e32 v20, v20, v21
	v_fmamk_f32 v20, v20, 0x3a800000, v47
	v_mul_f32_e32 v21, 0x4b800000, v20
	v_cmp_gt_f32_e32 vcc, s27, v20
	s_nop 1
	v_cndmask_b32_e32 v20, v20, v21, vcc
	v_rsq_f32_e32 v20, v20
	s_nop 0
	v_mul_f32_e32 v21, 0x45800000, v20
	v_cndmask_b32_e32 v100, v20, v21, vcc
	v_pk_mul_f32 v[20:21], v[100:101], v[70:71] op_sel_hi:[0,1]
	v_pk_mul_f32 v[22:23], v[100:101], v[72:73] op_sel_hi:[0,1]
	s_waitcnt vmcnt(7)
	v_pk_fma_f32 v[28:29], v[0:1], v[20:21], v[8:9]
	v_pk_fma_f32 v[30:31], v[2:3], v[22:23], v[10:11]
	global_store_dwordx4 v[98:99], v[28:31], off
	global_load_dwordx4 v[0:3], v[34:35], off offset:512
	v_pk_mul_f32 v[8:9], v[100:101], v[74:75] op_sel_hi:[0,1]
	v_pk_mul_f32 v[10:11], v[100:101], v[76:77] op_sel_hi:[0,1]
	v_pk_mul_f32 v[6:7], v[100:101], v[6:7] op_sel_hi:[0,1]
	s_waitcnt vmcnt(0)
; __device__ void norm_phase(const Params& p, int layer) {
;     ...
;       for (int i = 0; i < 8; ++i) {
;         float4 g = *reinterpret_cast<const float4*>(p.g_post + (size_t)layer * DM + l32 * 4 + i * 128);
;         xv[i].x += ov[i].x * rstd * g.x;
;         xv[i].y += ov[i].y * rstd * g.y;
;         xv[i].z += ov[i].z * rstd * g.z;
;         xv[i].w += ov[i].w * rstd * g.w;
;         *reinterpret_cast<float4*>(p.out + rbase + i * 128) = xv[i];
;       }
;     }
;     const int nl = layer + 1;
;     if (nl < 4) {
;       float ss = 0.f;
; #pragma unroll
;       for (int i = 0; i < 8; ++i) ss += xv[i].x * xv[i].x + xv[i].y * xv[i].y + xv[i].z * xv[i].z + xv[i].w * xv[i].w;
;       ss = half_wave_sum(ss);
;       float rstd = rsqrtf(ss * (1.f / 1024.f) + 1e-6f);
	v_pk_fma_f32 v[24:25], v[8:9], v[0:1], v[12:13]
	v_pk_fma_f32 v[26:27], v[10:11], v[2:3], v[14:15]
	global_store_dwordx4 v[98:99], v[24:27], off offset:512
	global_load_dwordx4 v[0:3], v[34:35], off offset:1024
	v_pk_mul_f32 v[8:9], v[100:101], v[78:79] op_sel_hi:[0,1]
	v_pk_mul_f32 v[10:11], v[100:101], v[80:81] op_sel_hi:[0,1]
	s_waitcnt vmcnt(0)
	v_pk_fma_f32 v[20:21], v[8:9], v[0:1], v[16:17]
	v_pk_fma_f32 v[22:23], v[10:11], v[2:3], v[18:19]
	global_store_dwordx4 v[98:99], v[20:23], off offset:1024
	global_load_dwordx4 v[0:3], v[34:35], off offset:1536
	v_pk_mul_f32 v[8:9], v[100:101], v[82:83] op_sel_hi:[0,1]
	v_pk_mul_f32 v[10:11], v[100:101], v[84:85] op_sel_hi:[0,1]
	s_waitcnt vmcnt(0)
	v_pk_fma_f32 v[16:17], v[8:9], v[0:1], v[50:51]
	v_pk_fma_f32 v[18:19], v[10:11], v[2:3], v[52:53]
	global_store_dwordx4 v[98:99], v[16:19], off offset:1536
	global_load_dwordx4 v[0:3], v[34:35], off offset:2048
	v_pk_mul_f32 v[8:9], v[100:101], v[86:87] op_sel_hi:[0,1]
	v_pk_mul_f32 v[10:11], v[100:101], v[88:89] op_sel_hi:[0,1]
	v_pk_mul_f32 v[50:51], v[100:101], v[94:95] op_sel_hi:[0,1]
	v_pk_mul_f32 v[52:53], v[100:101], v[96:97] op_sel_hi:[0,1]
	s_waitcnt vmcnt(0)
	v_pk_fma_f32 v[12:13], v[8:9], v[0:1], v[54:55]
	v_pk_fma_f32 v[14:15], v[10:11], v[2:3], v[56:57]
	global_store_dwordx4 v[98:99], v[12:15], off offset:2048
	global_load_dwordx4 v[0:3], v[34:35], off offset:2560
	v_pk_mul_f32 v[8:9], v[100:101], v[90:91] op_sel_hi:[0,1]
	v_pk_mul_f32 v[10:11], v[100:101], v[92:93] op_sel_hi:[0,1]
	v_pk_mul_f32 v[54:55], v[100:101], v[4:5] op_sel_hi:[0,1]
	v_pk_mul_f32 v[4:5], v[28:29], v[28:29]
	v_pk_mul_f32 v[56:57], v[30:31], v[30:31]
	v_add_f32_e32 v4, v4, v5
	v_add_f32_e32 v4, v56, v4
	v_add_f32_e32 v39, v57, v4
	v_pk_mul_f32 v[4:5], v[24:25], v[24:25]
	v_pk_mul_f32 v[56:57], v[26:27], v[26:27]
	v_add_f32_e32 v4, v4, v5
	v_add_f32_e32 v4, v4, v56
	v_add_f32_e32 v4, v4, v57
	v_add_f32_e32 v39, v39, v4
	v_mov_b32_e32 v56, v20
	v_mov_b32_e32 v57, v16
	s_waitcnt vmcnt(0)
	v_pk_fma_f32 v[8:9], v[8:9], v[0:1], v[58:59]
	v_pk_fma_f32 v[10:11], v[10:11], v[2:3], v[60:61]
	global_store_dwordx4 v[98:99], v[8:11], off offset:2560
	global_load_dwordx4 v[0:3], v[34:35], off offset:3072
	v_mov_b32_e32 v58, v21
	v_mov_b32_e32 v59, v17
	v_mov_b32_e32 v60, v22
	v_mov_b32_e32 v61, v18
	s_waitcnt vmcnt(0)
	v_pk_fma_f32 v[0:1], v[50:51], v[0:1], v[62:63]
	v_pk_fma_f32 v[2:3], v[52:53], v[2:3], v[64:65]
	global_store_dwordx4 v[98:99], v[0:3], off offset:3072
	global_load_dwordx4 v[50:53], v[34:35], off offset:3584
	v_mov_b32_e32 v62, v23
	v_mov_b32_e32 v63, v19
	s_waitcnt vmcnt(0)
	v_pk_fma_f32 v[4:5], v[6:7], v[50:51], v[66:67]
	v_pk_fma_f32 v[6:7], v[54:55], v[52:53], v[68:69]
	global_store_dwordx4 v[98:99], v[4:7], off offset:3584
	global_load_dwordx4 v[50:53], v[36:37], off
	v_pk_mul_f32 v[54:55], v[58:59], v[58:59]
	v_mov_b32_e32 v58, v14
	v_pk_fma_f32 v[54:55], v[56:57], v[56:57], v[54:55]
	v_mov_b32_e32 v56, v13
	v_pk_fma_f32 v[54:55], v[60:61], v[60:61], v[54:55]
	v_mov_b32_e32 v57, v9
	v_pk_fma_f32 v[54:55], v[62:63], v[62:63], v[54:55]
	v_pk_mul_f32 v[56:57], v[56:57], v[56:57]
	v_add_f32_e32 v39, v39, v54
	v_add_f32_e32 v39, v39, v55
	v_mov_b32_e32 v54, v12
	v_mov_b32_e32 v55, v8
	v_mov_b32_e32 v59, v10
	v_pk_fma_f32 v[54:55], v[54:55], v[54:55], v[56:57]
	v_mov_b32_e32 v60, v15
	v_mov_b32_e32 v61, v11
	v_pk_fma_f32 v[54:55], v[58:59], v[58:59], v[54:55]
	v_mov_b32_e32 v56, v1
	v_pk_fma_f32 v[54:55], v[60:61], v[60:61], v[54:55]
	v_mov_b32_e32 v57, v5
	v_add_f32_e32 v39, v39, v54
	v_add_f32_e32 v39, v39, v55
	v_mov_b32_e32 v54, v0
	v_mov_b32_e32 v55, v4
	v_pk_mul_f32 v[56:57], v[56:57], v[56:57]
	v_mov_b32_e32 v58, v2
	v_mov_b32_e32 v59, v6
	v_pk_fma_f32 v[54:55], v[54:55], v[54:55], v[56:57]
	v_mov_b32_e32 v60, v3
	v_mov_b32_e32 v61, v7
	v_pk_fma_f32 v[54:55], v[58:59], v[58:59], v[54:55]
	s_waitcnt vmcnt(0)
	v_mov_b32_e32 v57, v52
	v_pk_fma_f32 v[54:55], v[60:61], v[60:61], v[54:55]
	v_mov_b32_e32 v52, v51
	v_add_f32_e32 v39, v39, v54
	v_add_f32_e32 v39, v39, v55
	ds_bpermute_b32 v49, v42, v39
	v_mov_b32_e32 v54, v28
	v_mov_b32_e32 v55, v30
	v_mov_b32_e32 v30, v29
	v_mov_b32_e32 v56, v50
	s_waitcnt lgkmcnt(0)
	v_add_f32_e32 v39, v39, v49
	ds_bpermute_b32 v49, v43, v39
	s_waitcnt lgkmcnt(0)
	v_add_f32_e32 v39, v39, v49
	ds_bpermute_b32 v49, v44, v39
	s_waitcnt lgkmcnt(0)
	v_add_f32_e32 v39, v39, v49
	ds_bpermute_b32 v49, v45, v39
	s_waitcnt lgkmcnt(0)
	v_add_f32_e32 v39, v39, v49
	ds_bpermute_b32 v49, v46, v39
	s_waitcnt lgkmcnt(0)
; __device__ __forceinline__ unsigned pack2(float a, float b) { return (unsigned)f2bf(a) | ((unsigned)f2bf(b) << 16); }
; __device__ void norm_phase(const Params& p, int layer) {
;     ...
;       float rstd = rsqrtf(ss * (1.f / 1024.f) + 1e-6f);
; #pragma unroll
;       for (int i = 0; i < 8; ++i) {
;         float4 g = *reinterpret_cast<const float4*>(p.g_pre + (size_t)nl * DM + l32 * 4 + i * 128);
;         uint2 o;
;         o.x = pack2(xv[i].x * rstd * g.x, xv[i].y * rstd * g.y);
;         o.y = pack2(xv[i].z * rstd * g.z, xv[i].w * rstd * g.w);
;         *reinterpret_cast<uint2*>(H + rbase + i * 128) = o;
;       }
	v_add_f32_e32 v39, v39, v49
	v_fmamk_f32 v39, v39, 0x3a800000, v47
	v_mul_f32_e32 v49, 0x4b800000, v39
	v_cmp_gt_f32_e32 vcc, s27, v39
	s_nop 1
	v_cndmask_b32_e32 v39, v39, v49, vcc
	v_rsq_f32_e32 v39, v39
	s_nop 0
	v_mul_f32_e32 v28, 0x45800000, v39
	v_cndmask_b32_e32 v28, v39, v28, vcc
	v_pk_mul_f32 v[30:31], v[30:31], v[28:29] op_sel_hi:[1,0]
	v_pk_mul_f32 v[54:55], v[54:55], v[28:29] op_sel_hi:[1,0]
	v_pk_mul_f32 v[30:31], v[52:53], v[30:31]
	v_pk_mul_f32 v[50:51], v[56:57], v[54:55]
	v_cvt_pk_bf16_f32 v31, 0, v31
	v_cvt_pk_bf16_f32 v29, 0, v51
	v_and_b32_e32 v31, 0xffff0000, v31
	v_or_b32_sdwa v31, v31, v29 dst_sel:DWORD dst_unused:UNUSED_PAD src0_sel:DWORD src1_sel:WORD_1
	v_cvt_pk_bf16_f32 v30, v50, v30
	global_store_dwordx2 v[40:41], v[30:31], off
	global_load_dwordx4 v[50:53], v[36:37], off offset:512
	v_mov_b32_e32 v30, v24
	v_mov_b32_e32 v31, v26
	v_mov_b32_e32 v26, v25
	v_pk_mul_f32 v[24:25], v[30:31], v[28:29] op_sel_hi:[1,0]
	v_pk_mul_f32 v[26:27], v[26:27], v[28:29] op_sel_hi:[1,0]
	v_cmp_lt_i32_e32 vcc, s37, v33
	s_or_b64 s[24:25], vcc, s[24:25]
	s_waitcnt vmcnt(0)
	v_mov_b32_e32 v31, v52
	v_mov_b32_e32 v52, v51
	v_mov_b32_e32 v30, v50
	v_pk_mul_f32 v[26:27], v[52:53], v[26:27]
	v_pk_mul_f32 v[24:25], v[30:31], v[24:25]
	v_and_b32_sdwa v29, v25, v48 dst_sel:DWORD dst_unused:UNUSED_PAD src0_sel:WORD_1 src1_sel:DWORD
	v_cvt_pk_bf16_f32 v25, v25, v27
	v_cvt_pk_bf16_f32 v24, v24, v26
	global_store_dwordx2 v[40:41], v[24:25], off offset:256
	global_load_dwordx4 v[24:27], v[36:37], off offset:1024
	v_mov_b32_e32 v30, v20
	v_mov_b32_e32 v31, v22
	v_mov_b32_e32 v22, v21
	v_pk_mul_f32 v[20:21], v[30:31], v[28:29] op_sel_hi:[1,0]
	v_pk_mul_f32 v[22:23], v[22:23], v[28:29] op_sel_hi:[1,0]
	s_waitcnt vmcnt(0)
	v_mov_b32_e32 v31, v26
	v_mov_b32_e32 v26, v25
	v_mov_b32_e32 v30, v24
	v_pk_mul_f32 v[22:23], v[22:23], v[26:27]
	v_pk_mul_f32 v[20:21], v[20:21], v[30:31]
	v_cvt_pk_bf16_f32 v21, v21, v23
	v_cvt_pk_bf16_f32 v20, v20, v22
	global_store_dwordx2 v[40:41], v[20:21], off offset:512
	global_load_dwordx4 v[20:23], v[36:37], off offset:1536
	v_mov_b32_e32 v24, v16
	v_mov_b32_e32 v25, v18
	v_mov_b32_e32 v18, v17
	v_pk_mul_f32 v[16:17], v[24:25], v[28:29] op_sel_hi:[1,0]
	v_pk_mul_f32 v[18:19], v[18:19], v[28:29] op_sel_hi:[1,0]
	s_waitcnt vmcnt(0)
	v_mov_b32_e32 v25, v22
	v_mov_b32_e32 v22, v21
	v_mov_b32_e32 v24, v20
	v_pk_mul_f32 v[18:19], v[18:19], v[22:23]
	v_pk_mul_f32 v[16:17], v[16:17], v[24:25]
	v_cvt_pk_bf16_f32 v17, v17, v19
	v_cvt_pk_bf16_f32 v16, v16, v18
	global_store_dwordx2 v[40:41], v[16:17], off offset:768
	global_load_dwordx4 v[16:19], v[36:37], off offset:2048
	v_mov_b32_e32 v20, v12
	v_mov_b32_e32 v21, v14
	v_mov_b32_e32 v14, v13
	v_pk_mul_f32 v[12:13], v[20:21], v[28:29] op_sel_hi:[1,0]
	v_pk_mul_f32 v[14:15], v[14:15], v[28:29] op_sel_hi:[1,0]
	s_waitcnt vmcnt(0)
	v_mov_b32_e32 v21, v18
	v_mov_b32_e32 v18, v17
	v_mov_b32_e32 v20, v16
	v_pk_mul_f32 v[14:15], v[14:15], v[18:19]
	v_pk_mul_f32 v[12:13], v[12:13], v[20:21]
	v_cvt_pk_bf16_f32 v13, v13, v15
	v_cvt_pk_bf16_f32 v12, v12, v14
	global_store_dwordx2 v[40:41], v[12:13], off offset:1024
	global_load_dwordx4 v[12:15], v[36:37], off offset:2560
	v_mov_b32_e32 v16, v8
	v_mov_b32_e32 v17, v10
	v_mov_b32_e32 v10, v9
	v_pk_mul_f32 v[8:9], v[16:17], v[28:29] op_sel_hi:[1,0]
	v_pk_mul_f32 v[10:11], v[10:11], v[28:29] op_sel_hi:[1,0]
	s_waitcnt vmcnt(0)
	v_mov_b32_e32 v17, v14
	v_mov_b32_e32 v14, v13
	v_mov_b32_e32 v16, v12
	v_pk_mul_f32 v[10:11], v[10:11], v[14:15]
	v_pk_mul_f32 v[8:9], v[8:9], v[16:17]
	v_and_b32_sdwa v14, v11, v48 dst_sel:DWORD dst_unused:UNUSED_PAD src0_sel:WORD_1 src1_sel:DWORD
	v_and_b32_sdwa v15, v10, v48 dst_sel:DWORD dst_unused:UNUSED_PAD src0_sel:WORD_1 src1_sel:DWORD
	v_cvt_pk_bf16_f32 v9, v9, v11
	v_cvt_pk_bf16_f32 v8, v8, v10
	global_store_dwordx2 v[40:41], v[8:9], off offset:1280
	global_load_dwordx4 v[8:11], v[36:37], off offset:3072
	v_mov_b32_e32 v12, v0
	v_mov_b32_e32 v13, v2
	v_mov_b32_e32 v2, v1
	v_pk_mul_f32 v[0:1], v[12:13], v[28:29] op_sel_hi:[1,0]
	v_pk_mul_f32 v[2:3], v[2:3], v[28:29] op_sel_hi:[1,0]
	s_waitcnt vmcnt(0)
	v_mov_b32_e32 v13, v10
	v_mov_b32_e32 v10, v9
	v_mov_b32_e32 v12, v8
	v_pk_mul_f32 v[2:3], v[2:3], v[10:11]
	v_pk_mul_f32 v[0:1], v[0:1], v[12:13]
	v_cvt_pk_bf16_f32 v1, v1, v3
	v_cvt_pk_bf16_f32 v0, v0, v2
	global_store_dwordx2 v[40:41], v[0:1], off offset:1536
	global_load_dwordx4 v[0:3], v[36:37], off offset:3584
	v_mov_b32_e32 v8, v4
	v_mov_b32_e32 v9, v6
	v_mov_b32_e32 v6, v5
	v_pk_mul_f32 v[4:5], v[8:9], v[28:29] op_sel_hi:[1,0]
	v_pk_mul_f32 v[6:7], v[6:7], v[28:29] op_sel_hi:[1,0]
	s_waitcnt vmcnt(0)
	v_mov_b32_e32 v9, v2
	v_mov_b32_e32 v2, v1
	v_mov_b32_e32 v8, v0
	v_pk_mul_f32 v[2:3], v[6:7], v[2:3]
	v_pk_mul_f32 v[0:1], v[4:5], v[8:9]
	v_cvt_pk_bf16_f32 v1, v1, v3
	v_cvt_pk_bf16_f32 v0, v0, v2
	global_store_dwordx2 v[40:41], v[0:1], off offset:1792
	s_andn2_b64 exec, exec, s[24:25]
	s_cbranch_execnz .LBB0_359
	s_or_b64 exec, exec, s[24:25]
	v_mov_b64_e32 v[10:11], s[28:29]

; __device__ __forceinline__ unsigned pack2(float a, float b) { return (unsigned)f2bf(a) | ((unsigned)f2bf(b) << 16); }
; __device__ void convert_weights(const Params& p, int layer, char* smem) {
;     ...
;     __syncthreads();
; #pragma unroll
;     for (int i = 0; i < 4; ++i) {
;       int kk = (tid >> 4) + 16 * i, nn = (tid & 15) * 4;
;       float4 v = *reinterpret_cast<const float4*>(src + (size_t)(kt * 64 + kk) * N + nt * 64 + nn);
;       tile[kk * 65 + nn + 0] = v.x; tile[kk * 65 + nn + 1] = v.y;
;       tile[kk * 65 + nn + 2] = v.z; tile[kk * 65 + nn + 3] = v.w;
;     }
;     __syncthreads();
; #pragma unroll
;     for (int i = 0; i < 2; ++i) {
;       int nn = (tid >> 3) + 32 * i, kk0 = (tid & 7) * 8;
;       uint4 o;
;       o.x = pack2(tile[(kk0 + 0) * 65 + nn], tile[(kk0 + 1) * 65 + nn]);
;       o.y = pack2(tile[(kk0 + 2) * 65 + nn], tile[(kk0 + 3) * 65 + nn]);
;       o.z = pack2(tile[(kk0 + 4) * 65 + nn], tile[(kk0 + 5) * 65 + nn]);
;       o.w = pack2(tile[(kk0 + 6) * 65 + nn], tile[(kk0 + 7) * 65 + nn]);
;       *reinterpret_cast<uint4*>(dst + (size_t)(nt * 64 + nn) * K + kt * 64 + kk0) = o;
;     }
.LBB0_381:
	s_andn2_b64 vcc, exec, s[38:39]
	s_cbranch_vccnz .LBB0_363
	s_lshl_b32 s44, s53, 6
	s_ashr_i32 s45, s44, 31
	s_lshl_b32 s38, s52, 6
	s_lshl_b64 s[52:53], s[44:45], 2
	s_add_u32 s40, s40, s52
	v_add_u32_e32 v9, s38, v19
	s_addc_u32 s41, s41, s53
	v_add_u32_e32 v13, 16, v9
	v_lshl_add_u64 v[16:17], s[40:41], 0, v[0:1]
	v_mad_i64_i32 v[32:33], s[40:41], s42, v9, 0
	v_mad_i64_i32 v[34:35], s[40:41], s42, v13, 0
	v_lshl_add_u64 v[32:33], v[32:33], 2, v[16:17]
	v_lshl_add_u64 v[36:37], v[34:35], 2, v[16:17]
	s_barrier
	global_load_dwordx4 v[32:35], v[32:33], off
	s_nop 0
	global_load_dwordx4 v[36:39], v[36:37], off
	v_add_u32_e32 v13, 32, v9
	v_mad_i64_i32 v[40:41], s[40:41], s42, v13, 0
	v_lshl_add_u64 v[40:41], v[40:41], 2, v[16:17]
	v_add_u32_e32 v9, 48, v9
	global_load_dwordx4 v[40:43], v[40:41], off
	v_mad_i64_i32 v[44:45], s[40:41], s42, v9, 0
	v_lshl_add_u64 v[16:17], v[44:45], 2, v[16:17]
	global_load_dwordx4 v[44:47], v[16:17], off
	v_add_u32_e32 v9, s44, v20
	v_ashrrev_i32_e32 v48, 31, v9
	v_mul_lo_u32 v50, s37, v9
	v_mad_u64_u32 v[16:17], s[40:41], s36, v9, 0
	v_add_u32_e32 v9, 32, v9
	v_ashrrev_i32_e32 v52, 31, v9
	s_ashr_i32 s39, s38, 31
	v_mov_b32_e32 v13, v1
	v_mul_lo_u32 v51, s36, v48
	v_mul_lo_u32 v53, s37, v9
	v_mad_u64_u32 v[48:49], s[40:41], s36, v9, 0
	v_mul_lo_u32 v9, s36, v52
	v_lshl_add_u64 v[14:15], s[38:39], 1, v[14:15]
	v_add3_u32 v17, v17, v51, v50
	v_add3_u32 v49, v49, v9, v53
	v_lshl_add_u64 v[14:15], v[14:15], 0, v[12:13]
	v_lshl_add_u64 v[50:51], v[16:17], 1, v[14:15]
	v_lshl_add_u64 v[48:49], v[48:49], 1, v[14:15]
	s_waitcnt vmcnt(3)
	ds_write2_b32 v23, v32, v33 offset1:1
	ds_write2_b32 v23, v34, v35 offset0:2 offset1:3
	s_waitcnt vmcnt(2)
	ds_write2_b32 v24, v36, v37 offset1:1
	ds_write2_b32 v25, v38, v39 offset1:1
	s_waitcnt vmcnt(1)
	ds_write2_b32 v26, v40, v41 offset1:1
	ds_write2_b32 v27, v42, v43 offset1:1
	s_waitcnt vmcnt(0)
	ds_write2_b32 v28, v44, v45 offset1:1
	ds_write2_b32 v29, v46, v47 offset1:1
	s_waitcnt lgkmcnt(0)
	s_barrier
	ds_read2_b32 v[14:15], v22 offset1:32
	ds_read2_b32 v[32:33], v22 offset0:65 offset1:97
	ds_read2_b32 v[34:35], v22 offset0:130 offset1:162
	ds_read2_b32 v[36:37], v22 offset0:195 offset1:227
	ds_read2_b32 v[38:39], v30 offset0:4 offset1:36
	ds_read2_b32 v[40:41], v30 offset0:69 offset1:101
	ds_read2_b32 v[42:43], v30 offset0:134 offset1:166
	ds_read2_b32 v[44:45], v30 offset0:199 offset1:231
	s_waitcnt lgkmcnt(7)
	s_waitcnt lgkmcnt(4)
	s_waitcnt lgkmcnt(0)
	v_cvt_pk_bf16_f32 v13, 0, v14
	v_cvt_pk_bf16_f32 v14, 0, v36
	v_cvt_pk_bf16_f32 v16, 0, v32
	v_cvt_pk_bf16_f32 v9, 0, v34
	v_cvt_pk_bf16_f32 v36, 0, v40
	v_and_b32_e32 v14, 0xffff0000, v14
	v_and_b32_e32 v16, 0xffff0000, v16
	v_cvt_pk_bf16_f32 v32, 0, v38
	v_cvt_pk_bf16_f32 v38, 0, v15
	v_and_b32_e32 v36, 0xffff0000, v36
	v_or_b32_sdwa v15, v14, v9 dst_sel:DWORD dst_unused:UNUSED_PAD src0_sel:DWORD src1_sel:WORD_1
	v_or_b32_sdwa v14, v16, v13 dst_sel:DWORD dst_unused:UNUSED_PAD src0_sel:DWORD src1_sel:WORD_1
	v_cvt_pk_bf16_f32 v17, v42, v44
	v_or_b32_sdwa v16, v36, v32 dst_sel:DWORD dst_unused:UNUSED_PAD src0_sel:DWORD src1_sel:WORD_1
	global_store_dwordx4 v[50:51], v[14:17], off
	s_nop 1
	v_cvt_pk_bf16_f32 v14, 0, v33
	s_nop 0
	v_cvt_pk_bf16_f32 v15, v35, v37
	v_cvt_pk_bf16_f32 v17, 0, v41
	v_and_b32_e32 v14, 0xffff0000, v14
	v_cvt_pk_bf16_f32 v13, 0, v39
	v_and_b32_e32 v32, 0xffff0000, v17
	v_or_b32_sdwa v14, v14, v38 dst_sel:DWORD dst_unused:UNUSED_PAD src0_sel:DWORD src1_sel:WORD_1
	v_cvt_pk_bf16_f32 v17, v43, v45
	v_or_b32_sdwa v16, v32, v13 dst_sel:DWORD dst_unused:UNUSED_PAD src0_sel:DWORD src1_sel:WORD_1
	global_store_dwordx4 v[48:49], v[14:17], off
	s_branch .LBB0_363

; template <int DH, int MODE>
; __device__ void attn_item(const Params& p, int layer, int b, int blk, int head, char* smem) {
;     ...
;   {
;     constexpr int OST = DH + 4;
;     constexpr int CPR = DH / 8;
;     constexpr int NCH = 128 * CPR / 256;
;     float* Of = reinterpret_cast<float*>(smem);
;     uint4 gt[NCH];
; #pragma unroll
;     for (int i = 0; i < NCH; ++i) {
;       int q = tid + 256 * i, r = q / CPR, c = (q % CPR) * 8;
;       gt[i] = *reinterpret_cast<const uint4*>(P + (tq0 + r) * NP + gcol + c);
;     }
;     float lis[2][4];
; #pragma unroll
;     for (int m = 0; m < 2; ++m)
; #pragma unroll
;       for (int j = 0; j < 4; ++j) lis[m][j] = (MODE == 0) ? linv_s[wid * 32 + m * 16 + fq * 4 + j] : 1.f;
;     if (MODE == 0) __syncthreads();
; #pragma unroll
;     for (int m = 0; m < 2; ++m)
; #pragma unroll
;       for (int j = 0; j < 4; ++j) {
;         int r = wid * 32 + m * 16 + fq * 4 + j;
; #pragma unroll
;         for (int n = 0; n < NDT; ++n) Of[r * OST + n * 16 + fr] = o[m][n][j] * lis[m][j];
;       }
.LBB0_470:
	s_ashr_i32 s13, s86, 31
	s_add_u32 s12, s28, s86
	s_addc_u32 s13, s29, s13
	s_lshl_b32 s14, s83, 1
	s_add_u32 s16, s50, s14
	s_addc_u32 s17, s51, 0
	v_lshl_add_u64 v[2:3], s[20:21], 0, v[134:135]
	v_mov_b64_e32 v[4:5], s[16:17]
	v_mad_u64_u32 v[0:1], s[16:17], v2, s63, v[4:5]
	v_mad_i32_i24 v1, v3, s63, v1
	s_waitcnt vmcnt(12)
	v_lshl_add_u64 v[76:77], v[0:1], 0, v[138:139]
	v_add_u32_e32 v0, 0x100, v161
	v_ashrrev_i32_e32 v1, 31, v0
	v_lshrrev_b32_e32 v1, 28, v1
	v_add_u32_e32 v1, v0, v1
	v_ashrrev_i32_e32 v8, 4, v1
	v_and_b32_e32 v1, -16, v1
	s_waitcnt vmcnt(5)
	v_sub_u32_e32 v99, v0, v1
	v_lshlrev_b32_e32 v0, 3, v99
	v_ashrrev_i32_e32 v1, 31, v0
	s_waitcnt vmcnt(3)
	v_lshlrev_b64 v[92:93], 1, v[0:1]
	v_add_u32_e32 v0, 0x200, v161
	v_ashrrev_i32_e32 v1, 31, v0
	v_lshrrev_b32_e32 v1, 28, v1
	v_add_u32_e32 v1, v0, v1
	v_ashrrev_i32_e32 v9, 31, v8
	v_ashrrev_i32_e32 v94, 4, v1
	v_and_b32_e32 v1, -16, v1
	v_lshl_add_u64 v[10:11], s[20:21], 0, v[8:9]
	v_sub_u32_e32 v9, v0, v1
	v_lshlrev_b32_e32 v0, 3, v9
	v_ashrrev_i32_e32 v1, 31, v0
	v_lshlrev_b64 v[100:101], 1, v[0:1]
	v_add_u32_e32 v0, 0x300, v161
	v_ashrrev_i32_e32 v1, 31, v0
	v_lshrrev_b32_e32 v1, 28, v1
	v_add_u32_e32 v1, v0, v1
	v_ashrrev_i32_e32 v102, 4, v1
	v_and_b32_e32 v1, -16, v1
	v_sub_u32_e32 v128, v0, v1
	v_lshlrev_b32_e32 v0, 3, v128
	v_ashrrev_i32_e32 v1, 31, v0
	s_waitcnt vmcnt(0)
	v_lshlrev_b64 v[106:107], 1, v[0:1]
	v_add_u32_e32 v0, 0x400, v161
	v_ashrrev_i32_e32 v1, 31, v0
	v_lshrrev_b32_e32 v1, 28, v1
	v_add_u32_e32 v1, v0, v1
	v_ashrrev_i32_e32 v103, 31, v102
	v_ashrrev_i32_e32 v108, 4, v1
	v_and_b32_e32 v1, -16, v1
	v_lshl_add_u64 v[104:105], s[20:21], 0, v[102:103]
	v_sub_u32_e32 v103, v0, v1
	v_lshlrev_b32_e32 v0, 3, v103
	v_ashrrev_i32_e32 v1, 31, v0
	v_lshlrev_b64 v[112:113], 1, v[0:1]
	v_add_u32_e32 v0, 0x500, v161
	v_ashrrev_i32_e32 v1, 31, v0
	v_lshrrev_b32_e32 v1, 28, v1
	v_add_u32_e32 v1, v0, v1
	v_ashrrev_i32_e32 v109, 31, v108
	v_ashrrev_i32_e32 v114, 4, v1
	v_and_b32_e32 v1, -16, v1
	v_mad_u64_u32 v[6:7], s[16:17], v10, s63, v[4:5]
	v_ashrrev_i32_e32 v95, 31, v94
	v_lshl_add_u64 v[110:111], s[20:21], 0, v[108:109]
	v_sub_u32_e32 v109, v0, v1
	v_mad_i32_i24 v7, v11, s63, v7
	v_lshl_add_u64 v[96:97], s[20:21], 0, v[94:95]
	v_lshlrev_b32_e32 v0, 3, v109
	v_lshl_add_u64 v[78:79], v[6:7], 0, v[92:93]
	v_mad_u64_u32 v[6:7], s[16:17], v96, s63, v[4:5]
	v_ashrrev_i32_e32 v1, 31, v0
	v_mad_i32_i24 v7, v97, s63, v7
	v_lshlrev_b64 v[118:119], 1, v[0:1]
	v_add_u32_e32 v0, 0x600, v161
	v_lshl_add_u64 v[80:81], v[6:7], 0, v[100:101]
	v_mad_u64_u32 v[6:7], s[16:17], v104, s63, v[4:5]
	v_ashrrev_i32_e32 v1, 31, v0
	v_mad_i32_i24 v7, v105, s63, v7
	v_lshrrev_b32_e32 v1, 28, v1
	v_lshl_add_u64 v[82:83], v[6:7], 0, v[106:107]
	v_mad_u64_u32 v[6:7], s[16:17], v110, s63, v[4:5]
	v_ashrrev_i32_e32 v115, 31, v114
	v_add_u32_e32 v1, v0, v1
	v_mad_i32_i24 v7, v111, s63, v7
	v_lshl_add_u64 v[116:117], s[20:21], 0, v[114:115]
	v_ashrrev_i32_e32 v120, 4, v1
	v_and_b32_e32 v1, -16, v1
	v_lshl_add_u64 v[84:85], v[6:7], 0, v[112:113]
	v_mad_u64_u32 v[6:7], s[16:17], v116, s63, v[4:5]
	v_sub_u32_e32 v115, v0, v1
	v_ashrrev_i32_e32 v121, 31, v120
	v_mad_i32_i24 v7, v117, s63, v7
	v_lshlrev_b32_e32 v0, 3, v115
	v_lshl_add_u64 v[122:123], s[20:21], 0, v[120:121]
	v_lshl_add_u64 v[86:87], v[6:7], 0, v[118:119]
	v_mad_u64_u32 v[6:7], s[16:17], v122, s63, v[4:5]
	v_ashrrev_i32_e32 v1, 31, v0
	v_mad_i32_i24 v7, v123, s63, v7
	v_lshlrev_b64 v[124:125], 1, v[0:1]
	v_lshl_add_u64 v[0:1], v[6:7], 0, v[124:125]
	v_add_u32_e32 v6, 0x700, v161
	v_ashrrev_i32_e32 v7, 31, v6
	v_lshrrev_b32_e32 v7, 28, v7
	v_add_u32_e32 v7, v6, v7
	v_ashrrev_i32_e32 v126, 4, v7
	v_and_b32_e32 v7, -16, v7
	v_sub_u32_e32 v121, v6, v7
	v_lshlrev_b32_e32 v6, 3, v121
	v_ashrrev_i32_e32 v127, 31, v126
	v_lshl_add_u64 v[88:89], s[20:21], 0, v[126:127]
	v_ashrrev_i32_e32 v7, 31, v6
	v_mad_u64_u32 v[4:5], s[16:17], v88, s63, v[4:5]
	v_lshlrev_b64 v[90:91], 1, v[6:7]
	v_lshl_or_b32 v6, v137, 2, v130
	v_mad_i32_i24 v5, v89, s63, v5
	v_mul_lo_u32 v6, v6, s69
	v_lshl_add_u64 v[4:5], v[4:5], 0, v[90:91]
	v_lshl_add_u32 v95, v162, 2, v6
	s_barrier
	ds_write2_b32 v95, v12, v48 offset1:16
	ds_write2_b32 v95, v52, v56 offset0:32 offset1:48
	ds_write2_b32 v95, v60, v64 offset0:64 offset1:80
	ds_write2_b32 v95, v68, v72 offset0:96 offset1:112
	ds_write2_b32 v95, v13, v49 offset0:132 offset1:148
	ds_write2_b32 v95, v53, v57 offset0:164 offset1:180
	ds_write2_b32 v95, v61, v65 offset0:196 offset1:212
	ds_write2_b32 v95, v69, v73 offset0:228 offset1:244
	v_add_u32_e32 v12, 0x400, v95
	v_add_co_u32_e32 v4, vcc, s80, v4
	ds_write2_b32 v12, v14, v50 offset0:8 offset1:24
	ds_write2_b32 v12, v54, v58 offset0:40 offset1:56
	v_addc_co_u32_e32 v5, vcc, 0, v5, vcc
	global_load_dwordx4 v[4:7], v[4:5], off offset:512
	ds_write2_b32 v12, v62, v66 offset0:72 offset1:88
	ds_write2_b32 v12, v70, v74 offset0:104 offset1:120
	ds_write2_b32 v12, v15, v51 offset0:140 offset1:156
	ds_write2_b32 v12, v55, v59 offset0:172 offset1:188
	ds_write2_b32 v12, v63, v67 offset0:204 offset1:220
	ds_write2_b32 v12, v71, v75 offset0:236 offset1:252
	v_add_u32_e32 v12, 0x2000, v95
	ds_write2_b32 v12, v16, v20 offset0:64 offset1:80
	ds_write2_b32 v12, v24, v36 offset0:96 offset1:112
	ds_write2_b32 v12, v28, v40 offset0:128 offset1:144
	ds_write2_b32 v12, v44, v32 offset0:160 offset1:176
	ds_write2_b32 v12, v17, v21 offset0:196 offset1:212
	ds_write2_b32 v12, v25, v37 offset0:228 offset1:244
	v_add_u32_e32 v12, 0x2400, v95
	s_add_u32 s12, s12, s14
	ds_write2_b32 v12, v29, v41 offset0:4 offset1:20
	ds_write2_b32 v12, v45, v33 offset0:36 offset1:52
; __device__ __forceinline__ unsigned pack2(float a, float b) { return (unsigned)f2bf(a) | ((unsigned)f2bf(b) << 16); }
; __device__ __forceinline__ float bflo(unsigned w) { return __uint_as_float(w << 16); }
; __device__ __forceinline__ float bfhi(unsigned w) { return __uint_as_float(w & 0xffff0000u); }
; __device__ __forceinline__ float silu_f(float g) { return g / (1.f + __expf(-g)); }
; template <int DH, int MODE>
; __device__ void attn_item(const Params& p, int layer, int b, int blk, int head, char* smem) {
;     ...
;     for (int i = 0; i < NCH; ++i) {
;       int q = tid + 256 * i, r = q / CPR, c = (q % CPR) * 8;
;       gt[i] = *reinterpret_cast<const uint4*>(P + (tq0 + r) * NP + gcol + c);
;     }
;     float lis[2][4];
; #pragma unroll
;     for (int m = 0; m < 2; ++m)
; #pragma unroll
;       for (int j = 0; j < 4; ++j) lis[m][j] = (MODE == 0) ? linv_s[wid * 32 + m * 16 + fq * 4 + j] : 1.f;
;     if (MODE == 0) __syncthreads();
; #pragma unroll
;     for (int m = 0; m < 2; ++m)
; #pragma unroll
;       for (int j = 0; j < 4; ++j) {
;         int r = wid * 32 + m * 16 + fq * 4 + j;
; #pragma unroll
;         for (int n = 0; n < NDT; ++n) Of[r * OST + n * 16 + fr] = o[m][n][j] * lis[m][j];
;       }
;     __syncthreads();
; #pragma unroll
;     for (int i = 0; i < NCH; ++i) {
;       int q = tid + 256 * i, r = q / CPR, c = (q % CPR) * 8;
;       float4 m0 = *reinterpret_cast<const float4*>(Of + r * OST + c);
;       float4 m1 = *reinterpret_cast<const float4*>(Of + r * OST + c + 4);
;       float mm[8] = {m0.x, m0.y, m0.z, m0.w, m1.x, m1.y, m1.z, m1.w};
;       unsigned gw[4] = {gt[i].x, gt[i].y, gt[i].z, gt[i].w};
;       unsigned ow[4];
; #pragma unroll
;       for (int e = 0; e < 4; ++e)
;         ow[e] = pack2(mm[2 * e] * silu_f(bflo(gw[e])), mm[2 * e + 1] * silu_f(bfhi(gw[e])));
	ds_write2_b32 v12, v18, v22 offset0:72 offset1:88
	ds_write2_b32 v12, v26, v38 offset0:104 offset1:120
	ds_write2_b32 v12, v30, v42 offset0:136 offset1:152
	ds_write2_b32 v12, v46, v34 offset0:168 offset1:184
	ds_write2_b32 v12, v19, v23 offset0:204 offset1:220
	ds_write2_b32 v12, v27, v39 offset0:236 offset1:252
	v_add_u32_e32 v12, 0x2800, v95
	s_addc_u32 s13, s13, 0
	ds_write2_b32 v12, v31, v43 offset0:12 offset1:28
	ds_write2_b32 v12, v47, v35 offset0:44 offset1:60
	v_mul_lo_u32 v12, v134, s69
	v_mov_b64_e32 v[14:15], s[12:13]
	v_lshl_add_u32 v98, v136, 2, v12
	v_mad_u64_u32 v[12:13], s[12:13], v2, s70, v[14:15]
	v_mul_lo_u32 v2, v8, s69
	v_mad_i32_i24 v13, v3, s70, v13
	v_lshl_add_u32 v95, v99, 5, v2
	v_mad_u64_u32 v[2:3], s[12:13], v10, s70, v[14:15]
	v_mad_i32_i24 v3, v11, s70, v3
	v_lshl_add_u64 v[26:27], v[2:3], 0, v[92:93]
	v_mul_lo_u32 v2, v94, s69
	v_lshl_add_u32 v93, v9, 5, v2
	v_mad_u64_u32 v[2:3], s[12:13], v96, s70, v[14:15]
	v_mad_i32_i24 v3, v97, s70, v3
	v_lshl_add_u64 v[20:21], v[2:3], 0, v[100:101]
	v_mul_lo_u32 v2, v102, s69
	v_lshl_add_u32 v92, v128, 5, v2
	v_mad_u64_u32 v[2:3], s[12:13], v104, s70, v[14:15]
	v_mad_i32_i24 v3, v105, s70, v3
	v_lshl_add_u64 v[16:17], v[2:3], 0, v[106:107]
	v_mul_lo_u32 v2, v108, s69
	v_lshl_add_u32 v75, v103, 5, v2
	v_mad_u64_u32 v[2:3], s[12:13], v110, s70, v[14:15]
	v_mad_i32_i24 v3, v111, s70, v3
	v_lshl_add_u64 v[30:31], v[12:13], 0, v[138:139]
	v_lshl_add_u64 v[12:13], v[2:3], 0, v[112:113]
	v_mul_lo_u32 v2, v114, s69
	v_lshl_add_u32 v74, v109, 5, v2
	v_mad_u64_u32 v[2:3], s[12:13], v116, s70, v[14:15]
	v_mad_i32_i24 v3, v117, s70, v3
	v_lshl_add_u64 v[10:11], v[2:3], 0, v[118:119]
	v_mul_lo_u32 v2, v120, s69
	v_lshl_add_u32 v73, v115, 5, v2
	v_mad_u64_u32 v[2:3], s[12:13], v122, s70, v[14:15]
	v_mad_i32_i24 v3, v123, s70, v3
	v_add_co_u32_e32 v0, vcc, s80, v0
	v_lshl_add_u64 v[8:9], v[2:3], 0, v[124:125]
	v_mul_lo_u32 v2, v126, s69
	v_addc_co_u32_e32 v1, vcc, 0, v1, vcc
	v_lshl_add_u32 v72, v121, 5, v2
	global_load_dwordx4 v[0:3], v[0:1], off offset:512
	v_mad_u64_u32 v[14:15], s[12:13], v88, s70, v[14:15]
	v_mad_i32_i24 v15, v89, s70, v15
	v_lshl_add_u64 v[14:15], v[14:15], 0, v[90:91]
	s_waitcnt vmcnt(1)
	v_lshlrev_b32_e32 v22, 16, v5
	v_lshlrev_b32_e32 v23, 16, v4
	v_mul_f32_e32 v18, 0xbfb8aa3b, v23
	v_mul_f32_e32 v19, 0xbfb8aa3b, v22
	v_exp_f32_e32 v18, v18
	v_exp_f32_e32 v19, v19
	v_and_b32_e32 v24, 0xffff0000, v5
	v_and_b32_e32 v28, 0xffff0000, v4
	v_mul_f32_e32 v4, 0xbfb8aa3b, v28
	v_pk_add_f32 v[18:19], v[18:19], 1.0 op_sel_hi:[1,0]
	v_exp_f32_e32 v4, v4
	v_and_b32_e32 v34, 0xffff0000, v6
	v_rcp_f32_e32 v19, v19
	s_nop 0
	v_mul_f32_e32 v19, v22, v19
	v_mul_f32_e32 v5, 0xbfb8aa3b, v24
	v_exp_f32_e32 v5, v5
	s_nop 0
	v_pk_add_f32 v[4:5], v[4:5], 1.0 op_sel_hi:[1,0]
	v_rcp_f32_e32 v18, v18
	s_nop 0
	v_mul_f32_e32 v18, v23, v18
	v_lshlrev_b32_e32 v33, 16, v6
	v_rcp_f32_e32 v23, v5
	s_nop 0
	v_mul_f32_e32 v23, v24, v23
	v_lshlrev_b32_e32 v32, 16, v7
	v_mul_f32_e32 v24, 0xbfb8aa3b, v33
	v_mul_f32_e32 v25, 0xbfb8aa3b, v32
	v_exp_f32_e32 v24, v24
	v_exp_f32_e32 v25, v25
	v_rcp_f32_e32 v22, v4
	s_nop 0
	v_mul_f32_e32 v22, v28, v22
	v_and_b32_e32 v28, 0xffff0000, v7
	v_pk_add_f32 v[4:5], v[24:25], 1.0 op_sel_hi:[1,0]
	v_mul_f32_e32 v6, 0xbfb8aa3b, v34
	v_exp_f32_e32 v6, v6
	s_waitcnt vmcnt(0)
	v_lshlrev_b32_e32 v40, 16, v3
	v_lshlrev_b32_e32 v41, 16, v2
	v_rcp_f32_e32 v25, v5
	s_nop 0
	v_mul_f32_e32 v25, v32, v25
	v_mul_f32_e32 v7, 0xbfb8aa3b, v28
	v_exp_f32_e32 v7, v7
	s_nop 0
	v_pk_add_f32 v[6:7], v[6:7], 1.0 op_sel_hi:[1,0]
	v_rcp_f32_e32 v24, v4
	s_nop 0
	v_mul_f32_e32 v24, v33, v24
	v_rcp_f32_e32 v29, v7
	s_nop 0
	v_mul_f32_e32 v29, v28, v29
	v_lshlrev_b32_e32 v32, 16, v1
	v_lshlrev_b32_e32 v36, 16, v0
	v_mul_f32_e32 v4, 0xbfb8aa3b, v36
	v_mul_f32_e32 v5, 0xbfb8aa3b, v32
	v_exp_f32_e32 v4, v4
	v_exp_f32_e32 v5, v5
	v_rcp_f32_e32 v28, v6
	s_nop 0
	v_mul_f32_e32 v28, v34, v28
	v_and_b32_e32 v6, 0xffff0000, v1
	v_pk_add_f32 v[4:5], v[4:5], 1.0 op_sel_hi:[1,0]
	v_and_b32_e32 v34, 0xffff0000, v0
	v_mul_f32_e32 v0, 0xbfb8aa3b, v34
	v_exp_f32_e32 v0, v0
	v_and_b32_e32 v42, 0xffff0000, v3
	v_rcp_f32_e32 v33, v5
	s_nop 0
	v_mul_f32_e32 v33, v32, v33
	v_mul_f32_e32 v1, 0xbfb8aa3b, v6
	v_exp_f32_e32 v1, v1
	s_nop 0
	v_pk_add_f32 v[0:1], v[0:1], 1.0 op_sel_hi:[1,0]
	v_rcp_f32_e32 v32, v4
	s_nop 0
	v_mul_f32_e32 v32, v36, v32
	v_rcp_f32_e32 v35, v1
	s_nop 0
	v_mul_f32_e32 v35, v6, v35
	v_add_co_u32_e64 v4, s[12:13], s80, v86
	s_nop 0
	s_nop 0
	v_addc_co_u32_e64 v5, s[12:13], 0, v87, s[12:13]
	global_load_dwordx4 v[4:7], v[4:5], off offset:512
	v_mul_f32_e32 v36, 0xbfb8aa3b, v41
	v_mul_f32_e32 v37, 0xbfb8aa3b, v40
	v_exp_f32_e32 v36, v36
	v_exp_f32_e32 v37, v37
	v_rcp_f32_e32 v1, v0
	s_nop 0
	v_mul_f32_e32 v34, v34, v1
	v_and_b32_e32 v43, 0xffff0000, v2
	v_pk_add_f32 v[0:1], v[36:37], 1.0 op_sel_hi:[1,0]
	v_mul_f32_e32 v2, 0xbfb8aa3b, v43
	v_exp_f32_e32 v2, v2
	v_rcp_f32_e32 v37, v1
	s_nop 0
	v_mul_f32_e32 v37, v40, v37
	v_mul_f32_e32 v3, 0xbfb8aa3b, v42
	v_exp_f32_e32 v3, v3
	s_nop 0
	v_pk_add_f32 v[38:39], v[2:3], 1.0 op_sel_hi:[1,0]
	v_rcp_f32_e32 v36, v0
	s_nop 0
	v_mul_f32_e32 v36, v41, v36
	v_rcp_f32_e32 v39, v39
	s_nop 0
	v_mul_f32_e32 v39, v42, v39
	v_add_co_u32_e64 v0, s[12:13], s80, v84
	s_waitcnt vmcnt(0)
; __device__ __forceinline__ unsigned pack2(float a, float b) { return (unsigned)f2bf(a) | ((unsigned)f2bf(b) << 16); }
; __device__ __forceinline__ float bflo(unsigned w) { return __uint_as_float(w << 16); }
; __device__ __forceinline__ float bfhi(unsigned w) { return __uint_as_float(w & 0xffff0000u); }
; __device__ __forceinline__ float silu_f(float g) { return g / (1.f + __expf(-g)); }
; template <int DH, int MODE>
; __device__ void attn_item(const Params& p, int layer, int b, int blk, int head, char* smem) {
;     ...
; #pragma unroll
;     for (int i = 0; i < NCH; ++i) {
;       int q = tid + 256 * i, r = q / CPR, c = (q % CPR) * 8;
;       float4 m0 = *reinterpret_cast<const float4*>(Of + r * OST + c);
;       float4 m1 = *reinterpret_cast<const float4*>(Of + r * OST + c + 4);
;       float mm[8] = {m0.x, m0.y, m0.z, m0.w, m1.x, m1.y, m1.z, m1.w};
;       unsigned gw[4] = {gt[i].x, gt[i].y, gt[i].z, gt[i].w};
;       unsigned ow[4];
; #pragma unroll
;       for (int e = 0; e < 4; ++e)
;         ow[e] = pack2(mm[2 * e] * silu_f(bflo(gw[e])), mm[2 * e + 1] * silu_f(bfhi(gw[e])));
	v_lshlrev_b32_e32 v46, 16, v5
	v_lshlrev_b32_e32 v47, 16, v4
	v_mul_f32_e32 v40, 0xbfb8aa3b, v47
	v_mul_f32_e32 v41, 0xbfb8aa3b, v46
	v_exp_f32_e32 v40, v40
	v_exp_f32_e32 v41, v41
	v_addc_co_u32_e64 v1, s[12:13], 0, v85, s[12:13]
	v_rcp_f32_e32 v38, v38
	s_nop 0
	v_mul_f32_e32 v38, v43, v38
	v_pk_add_f32 v[40:41], v[40:41], 1.0 op_sel_hi:[1,0]
	v_and_b32_e32 v42, 0xffff0000, v5
	global_load_dwordx4 v[0:3], v[0:1], off offset:512
	v_and_b32_e32 v48, 0xffff0000, v4
	v_mul_f32_e32 v4, 0xbfb8aa3b, v48
	v_rcp_f32_e32 v41, v41
	s_nop 0
	v_mul_f32_e32 v41, v46, v41
	v_exp_f32_e32 v4, v4
	v_mul_f32_e32 v5, 0xbfb8aa3b, v42
	v_exp_f32_e32 v5, v5
	s_nop 0
	v_pk_add_f32 v[4:5], v[4:5], 1.0 op_sel_hi:[1,0]
	v_rcp_f32_e32 v40, v40
	s_nop 0
	v_mul_f32_e32 v40, v47, v40
	v_lshlrev_b32_e32 v49, 16, v6
	v_rcp_f32_e32 v43, v5
	s_nop 0
	v_mul_f32_e32 v43, v42, v43
	v_lshlrev_b32_e32 v46, 16, v7
	v_mul_f32_e32 v44, 0xbfb8aa3b, v49
	v_mul_f32_e32 v45, 0xbfb8aa3b, v46
	v_exp_f32_e32 v44, v44
	v_exp_f32_e32 v45, v45
	v_rcp_f32_e32 v42, v4
	s_nop 0
	v_mul_f32_e32 v42, v48, v42
	v_and_b32_e32 v47, 0xffff0000, v7
	v_pk_add_f32 v[4:5], v[44:45], 1.0 op_sel_hi:[1,0]
	v_and_b32_e32 v48, 0xffff0000, v6
	v_mul_f32_e32 v6, 0xbfb8aa3b, v48
	v_exp_f32_e32 v6, v6
	v_rcp_f32_e32 v45, v5
	s_nop 0
	v_mul_f32_e32 v45, v46, v45
	v_mul_f32_e32 v7, 0xbfb8aa3b, v47
	v_exp_f32_e32 v7, v7
	s_nop 0
	v_pk_add_f32 v[6:7], v[6:7], 1.0 op_sel_hi:[1,0]
	v_rcp_f32_e32 v44, v4
	s_nop 0
	v_mul_f32_e32 v44, v49, v44
	v_rcp_f32_e32 v4, v7
	s_nop 0
	v_mul_f32_e32 v47, v47, v4
	s_waitcnt vmcnt(0)
	v_lshlrev_b32_e32 v50, 16, v1
	v_lshlrev_b32_e32 v51, 16, v0
	v_mul_f32_e32 v4, 0xbfb8aa3b, v51
	v_mul_f32_e32 v5, 0xbfb8aa3b, v50
	v_exp_f32_e32 v4, v4
	v_exp_f32_e32 v5, v5
	v_rcp_f32_e32 v46, v6
	s_nop 0
	v_mul_f32_e32 v46, v48, v46
	v_and_b32_e32 v6, 0xffff0000, v1
	v_pk_add_f32 v[4:5], v[4:5], 1.0 op_sel_hi:[1,0]
	v_and_b32_e32 v54, 0xffff0000, v0
	v_mul_f32_e32 v0, 0xbfb8aa3b, v54
	v_exp_f32_e32 v0, v0
	v_lshlrev_b32_e32 v58, 16, v2
	v_rcp_f32_e32 v49, v5
	s_nop 0
	v_mul_f32_e32 v49, v50, v49
	v_mul_f32_e32 v1, 0xbfb8aa3b, v6
	v_exp_f32_e32 v1, v1
	s_nop 0
	v_pk_add_f32 v[0:1], v[0:1], 1.0 op_sel_hi:[1,0]
	v_rcp_f32_e32 v48, v4
	s_nop 0
	v_mul_f32_e32 v48, v51, v48
	v_lshlrev_b32_e32 v57, 16, v3
	v_rcp_f32_e32 v51, v1
	s_nop 0
	v_mul_f32_e32 v51, v6, v51
	v_add_co_u32_e64 v4, s[12:13], s80, v82
	s_nop 0
	s_nop 0
	v_addc_co_u32_e64 v5, s[12:13], 0, v83, s[12:13]
	global_load_dwordx4 v[4:7], v[4:5], off offset:512
	v_mul_f32_e32 v50, 0xbfb8aa3b, v58
	v_exp_f32_e32 v52, v50
	v_mul_f32_e32 v50, 0xbfb8aa3b, v57
	v_exp_f32_e32 v53, v50
	v_rcp_f32_e32 v50, v0
	s_nop 0
	v_mul_f32_e32 v50, v54, v50
	v_and_b32_e32 v56, 0xffff0000, v3
	v_pk_add_f32 v[0:1], v[52:53], 1.0 op_sel_hi:[1,0]
	v_and_b32_e32 v59, 0xffff0000, v2
	v_mul_f32_e32 v2, 0xbfb8aa3b, v59
	v_exp_f32_e32 v2, v2
	v_rcp_f32_e32 v53, v1
	s_nop 0
	v_mul_f32_e32 v53, v57, v53
	v_mul_f32_e32 v3, 0xbfb8aa3b, v56
	v_exp_f32_e32 v3, v3
	s_nop 0
	v_pk_add_f32 v[54:55], v[2:3], 1.0 op_sel_hi:[1,0]
	v_rcp_f32_e32 v52, v0
	s_nop 0
	v_mul_f32_e32 v52, v58, v52
	v_rcp_f32_e32 v55, v55
	s_nop 0
	v_mul_f32_e32 v55, v56, v55
	v_add_co_u32_e64 v0, s[12:13], s80, v80
	s_waitcnt vmcnt(0)
	v_lshlrev_b32_e32 v62, 16, v5
	v_lshlrev_b32_e32 v63, 16, v4
	v_mul_f32_e32 v56, 0xbfb8aa3b, v63
	v_mul_f32_e32 v57, 0xbfb8aa3b, v62
	v_exp_f32_e32 v56, v56
	v_exp_f32_e32 v57, v57
	v_addc_co_u32_e64 v1, s[12:13], 0, v81, s[12:13]
	v_rcp_f32_e32 v54, v54
	s_nop 0
	v_mul_f32_e32 v54, v59, v54
	v_pk_add_f32 v[56:57], v[56:57], 1.0 op_sel_hi:[1,0]
	v_and_b32_e32 v58, 0xffff0000, v5
	global_load_dwordx4 v[0:3], v[0:1], off offset:512
	v_and_b32_e32 v64, 0xffff0000, v4
	v_mul_f32_e32 v4, 0xbfb8aa3b, v64
	v_rcp_f32_e32 v57, v57
	s_nop 0
	v_mul_f32_e32 v57, v62, v57
	v_exp_f32_e32 v4, v4
	v_mul_f32_e32 v5, 0xbfb8aa3b, v58
	v_exp_f32_e32 v5, v5
	s_nop 0
	v_pk_add_f32 v[4:5], v[4:5], 1.0 op_sel_hi:[1,0]
	v_rcp_f32_e32 v56, v56
	s_nop 0
	v_mul_f32_e32 v56, v63, v56
	v_lshlrev_b32_e32 v65, 16, v6
	v_rcp_f32_e32 v59, v5
	s_nop 0
	v_mul_f32_e32 v59, v58, v59
	v_lshlrev_b32_e32 v62, 16, v7
	v_mul_f32_e32 v60, 0xbfb8aa3b, v65
	v_mul_f32_e32 v61, 0xbfb8aa3b, v62
	v_exp_f32_e32 v60, v60
	v_exp_f32_e32 v61, v61
	v_rcp_f32_e32 v58, v4
	s_nop 0
	v_mul_f32_e32 v58, v64, v58
	v_and_b32_e32 v63, 0xffff0000, v7
	v_pk_add_f32 v[4:5], v[60:61], 1.0 op_sel_hi:[1,0]
	v_and_b32_e32 v64, 0xffff0000, v6
	v_mul_f32_e32 v6, 0xbfb8aa3b, v64
	v_exp_f32_e32 v6, v6
	v_rcp_f32_e32 v61, v5
	s_nop 0
	v_mul_f32_e32 v61, v62, v61
	v_mul_f32_e32 v7, 0xbfb8aa3b, v63
	v_exp_f32_e32 v7, v7
	s_nop 0
	v_pk_add_f32 v[6:7], v[6:7], 1.0 op_sel_hi:[1,0]
	v_rcp_f32_e32 v60, v4
	s_nop 0
	v_mul_f32_e32 v60, v65, v60
	v_rcp_f32_e32 v4, v7
	s_nop 0
	v_mul_f32_e32 v63, v63, v4
	s_waitcnt vmcnt(0)
	v_lshlrev_b32_e32 v66, 16, v1
	v_lshlrev_b32_e32 v67, 16, v0
	v_mul_f32_e32 v4, 0xbfb8aa3b, v67
	v_mul_f32_e32 v5, 0xbfb8aa3b, v66
	v_exp_f32_e32 v4, v4
	v_exp_f32_e32 v5, v5
	v_and_b32_e32 v68, 0xffff0000, v1
	v_rcp_f32_e32 v62, v6
	s_nop 0
	v_mul_f32_e32 v62, v64, v62
	v_pk_add_f32 v[4:5], v[4:5], 1.0 op_sel_hi:[1,0]
	v_and_b32_e32 v69, 0xffff0000, v0
	v_mul_f32_e32 v0, 0xbfb8aa3b, v69
	v_exp_f32_e32 v6, v0
	v_and_b32_e32 v80, 0xffff0000, v2
	v_rcp_f32_e32 v1, v5
	s_nop 0
	v_mul_f32_e32 v1, v66, v1
	v_mul_f32_e32 v7, 0xbfb8aa3b, v68
	v_exp_f32_e32 v7, v7
	s_nop 0
	v_pk_add_f32 v[64:65], v[6:7], 1.0 op_sel_hi:[1,0]
	v_rcp_f32_e32 v0, v4
	s_nop 0
	v_mul_f32_e32 v0, v67, v0
	v_rcp_f32_e32 v65, v65
	s_nop 0
	v_mul_f32_e32 v65, v68, v65
	v_add_co_u32_e64 v4, s[12:13], s80, v78
	s_nop 0
	s_nop 0
	v_addc_co_u32_e64 v5, s[12:13], 0, v79, s[12:13]
	global_load_dwordx4 v[4:7], v[4:5], off offset:512
	v_lshlrev_b32_e32 v78, 16, v3
	v_lshlrev_b32_e32 v79, 16, v2
	v_mul_f32_e32 v66, 0xbfb8aa3b, v79
	v_mul_f32_e32 v67, 0xbfb8aa3b, v78
	v_exp_f32_e32 v66, v66
	v_exp_f32_e32 v67, v67
	v_and_b32_e32 v70, 0xffff0000, v3
	v_rcp_f32_e32 v64, v64
	s_nop 0
	v_mul_f32_e32 v64, v69, v64
	v_pk_add_f32 v[66:67], v[66:67], 1.0 op_sel_hi:[1,0]
	v_mul_f32_e32 v2, 0xbfb8aa3b, v80
	v_exp_f32_e32 v68, v2
	v_mul_f32_e32 v69, 0xbfb8aa3b, v70
	v_exp_f32_e32 v69, v69
	v_rcp_f32_e32 v3, v67
	s_nop 0
	v_mul_f32_e32 v3, v78, v3
	v_pk_add_f32 v[68:69], v[68:69], 1.0 op_sel_hi:[1,0]
	v_rcp_f32_e32 v2, v66
	s_nop 0
	v_mul_f32_e32 v2, v79, v2
	v_rcp_f32_e32 v67, v69
	s_nop 0
	v_mul_f32_e32 v67, v70, v67
	v_add_co_u32_e64 v70, s[12:13], s80, v76
	s_nop 0
	s_nop 0
	v_addc_co_u32_e64 v71, s[12:13], 0, v77, s[12:13]
	global_load_dwordx4 v[76:79], v[70:71], off offset:512
	v_rcp_f32_e32 v66, v68
	s_nop 0
	v_mul_f32_e32 v66, v80, v66
	s_waitcnt vmcnt(1)
	v_lshlrev_b32_e32 v82, 16, v5
	v_lshlrev_b32_e32 v83, 16, v4
	v_mul_f32_e32 v70, 0xbfb8aa3b, v83
	v_mul_f32_e32 v71, 0xbfb8aa3b, v82
	v_exp_f32_e32 v70, v70
	v_exp_f32_e32 v71, v71
	v_and_b32_e32 v80, 0xffff0000, v5
	v_and_b32_e32 v84, 0xffff0000, v4
	v_mul_f32_e32 v4, 0xbfb8aa3b, v84
	v_pk_add_f32 v[68:69], v[70:71], 1.0 op_sel_hi:[1,0]
	v_exp_f32_e32 v70, v4
	s_waitcnt lgkmcnt(0)
	s_barrier
; __device__ __forceinline__ unsigned pack2(float a, float b) { return (unsigned)f2bf(a) | ((unsigned)f2bf(b) << 16); }
; __device__ __forceinline__ float bflo(unsigned w) { return __uint_as_float(w << 16); }
; __device__ __forceinline__ float bfhi(unsigned w) { return __uint_as_float(w & 0xffff0000u); }
; __device__ __forceinline__ float silu_f(float g) { return g / (1.f + __expf(-g)); }
; template <int DH, int MODE>
; __device__ void attn_item(const Params& p, int layer, int b, int blk, int head, char* smem) {
;     ...
; #pragma unroll
;     for (int i = 0; i < NCH; ++i) {
;       int q = tid + 256 * i, r = q / CPR, c = (q % CPR) * 8;
;       float4 m0 = *reinterpret_cast<const float4*>(Of + r * OST + c);
;       float4 m1 = *reinterpret_cast<const float4*>(Of + r * OST + c + 4);
;       float mm[8] = {m0.x, m0.y, m0.z, m0.w, m1.x, m1.y, m1.z, m1.w};
;       unsigned gw[4] = {gt[i].x, gt[i].y, gt[i].z, gt[i].w};
;       unsigned ow[4];
; #pragma unroll
;       for (int e = 0; e < 4; ++e)
;         ow[e] = pack2(mm[2 * e] * silu_f(bflo(gw[e])), mm[2 * e + 1] * silu_f(bfhi(gw[e])));
;       *reinterpret_cast<uint4*>(Y + (tq0 + r) * YW + ycol + c) = make_uint4(ow[0], ow[1], ow[2], ow[3]);
;     }
	v_mul_f32_e32 v71, 0xbfb8aa3b, v80
	v_exp_f32_e32 v71, v71
	v_rcp_f32_e32 v5, v69
	s_nop 0
	v_mul_f32_e32 v5, v82, v5
	v_pk_add_f32 v[70:71], v[70:71], 1.0 op_sel_hi:[1,0]
	v_rcp_f32_e32 v4, v68
	s_nop 0
	v_mul_f32_e32 v4, v83, v4
	v_rcp_f32_e32 v69, v71
	s_nop 0
	v_mul_f32_e32 v69, v80, v69
	v_lshlrev_b32_e32 v82, 16, v7
	v_lshlrev_b32_e32 v85, 16, v6
	v_mul_f32_e32 v80, 0xbfb8aa3b, v85
	v_mul_f32_e32 v81, 0xbfb8aa3b, v82
	v_exp_f32_e32 v80, v80
	v_exp_f32_e32 v81, v81
	v_rcp_f32_e32 v68, v70
	s_nop 0
	v_mul_f32_e32 v68, v84, v68
	v_and_b32_e32 v83, 0xffff0000, v7
	v_pk_add_f32 v[70:71], v[80:81], 1.0 op_sel_hi:[1,0]
	v_and_b32_e32 v84, 0xffff0000, v6
	v_mul_f32_e32 v6, 0xbfb8aa3b, v84
	v_exp_f32_e32 v80, v6
	s_waitcnt vmcnt(0)
	v_and_b32_e32 v94, 0xffff0000, v78
	v_mul_f32_e32 v81, 0xbfb8aa3b, v83
	v_exp_f32_e32 v81, v81
	v_rcp_f32_e32 v7, v71
	s_nop 0
	v_mul_f32_e32 v7, v82, v7
	v_pk_add_f32 v[80:81], v[80:81], 1.0 op_sel_hi:[1,0]
	v_rcp_f32_e32 v6, v70
	s_nop 0
	v_mul_f32_e32 v6, v85, v6
	v_rcp_f32_e32 v71, v81
	s_nop 0
	v_mul_f32_e32 v71, v83, v71
	v_lshlrev_b32_e32 v86, 16, v77
	v_lshlrev_b32_e32 v87, 16, v76
	v_mul_f32_e32 v82, 0xbfb8aa3b, v87
	v_mul_f32_e32 v83, 0xbfb8aa3b, v86
	v_exp_f32_e32 v82, v82
	v_exp_f32_e32 v83, v83
	v_rcp_f32_e32 v70, v80
	s_nop 0
	v_mul_f32_e32 v70, v84, v70
	v_and_b32_e32 v88, 0xffff0000, v77
	v_pk_add_f32 v[80:81], v[82:83], 1.0 op_sel_hi:[1,0]
	v_and_b32_e32 v83, 0xffff0000, v76
	v_mul_f32_e32 v76, 0xbfb8aa3b, v83
	v_exp_f32_e32 v76, v76
	v_rcp_f32_e32 v85, v81
	s_nop 0
	v_mul_f32_e32 v85, v86, v85
	v_mul_f32_e32 v77, 0xbfb8aa3b, v88
	v_exp_f32_e32 v77, v77
	s_nop 0
	v_pk_add_f32 v[76:77], v[76:77], 1.0 op_sel_hi:[1,0]
	v_rcp_f32_e32 v84, v80
	s_nop 0
	v_mul_f32_e32 v84, v87, v84
	v_rcp_f32_e32 v87, v77
	s_nop 0
	v_mul_f32_e32 v87, v88, v87
	v_lshlrev_b32_e32 v90, 16, v78
	v_lshlrev_b32_e32 v82, 16, v79
	v_mul_f32_e32 v80, 0xbfb8aa3b, v90
	v_mul_f32_e32 v81, 0xbfb8aa3b, v82
	v_exp_f32_e32 v80, v80
	v_exp_f32_e32 v81, v81
	v_rcp_f32_e32 v86, v76
	s_nop 0
	v_mul_f32_e32 v86, v83, v86
	v_and_b32_e32 v83, 0xffff0000, v79
	v_pk_add_f32 v[76:77], v[80:81], 1.0 op_sel_hi:[1,0]
	v_mul_f32_e32 v78, 0xbfb8aa3b, v94
	v_exp_f32_e32 v78, v78
	v_rcp_f32_e32 v89, v77
	s_nop 0
	v_mul_f32_e32 v89, v82, v89
	v_mul_f32_e32 v79, 0xbfb8aa3b, v83
	v_exp_f32_e32 v79, v79
	s_nop 0
	v_pk_add_f32 v[80:81], v[78:79], 1.0 op_sel_hi:[1,0]
	v_rcp_f32_e32 v88, v76
	s_nop 0
	v_mul_f32_e32 v88, v90, v88
	v_rcp_f32_e32 v91, v81
	s_nop 0
	v_mul_f32_e32 v91, v83, v91
	ds_read_b128 v[76:79], v98
	v_rcp_f32_e32 v90, v80
	s_nop 0
	v_mul_f32_e32 v90, v94, v90
	ds_read_b128 v[80:83], v98 offset:16
	v_add_co_u32_e32 v30, vcc, s77, v30
	s_waitcnt lgkmcnt(1)
	v_mov_b32_e32 v96, v76
	v_mov_b32_e32 v97, v78
	v_pk_mul_f32 v[84:85], v[84:85], v[96:97]
	v_mov_b32_e32 v78, v77
	v_pk_mul_f32 v[76:77], v[86:87], v[78:79]
	v_cvt_pk_bf16_f32 v77, v85, v77
	v_cvt_pk_bf16_f32 v76, v84, v76
	s_waitcnt lgkmcnt(0)
	v_mov_b32_e32 v78, v80
	v_mov_b32_e32 v79, v82
	v_pk_mul_f32 v[78:79], v[88:89], v[78:79]
	v_mov_b32_e32 v82, v81
	v_pk_mul_f32 v[80:81], v[90:91], v[82:83]
	v_cvt_pk_bf16_f32 v79, v79, v81
	v_cvt_pk_bf16_f32 v78, v78, v80
	ds_read_b128 v[80:83], v95
	v_addc_co_u32_e32 v31, vcc, 0, v31, vcc
	global_store_dwordx4 v[30:31], v[76:79], off offset:2048
	s_nop 0
	ds_read_b128 v[76:79], v95 offset:16
	s_waitcnt lgkmcnt(1)
	v_mov_b32_e32 v30, v80
	v_mov_b32_e32 v31, v82
	v_pk_mul_f32 v[4:5], v[4:5], v[30:31]
	v_mov_b32_e32 v82, v81
	v_pk_mul_f32 v[30:31], v[68:69], v[82:83]
	v_cvt_pk_bf16_f32 v5, v5, v31
	v_cvt_pk_bf16_f32 v4, v4, v30
	s_waitcnt lgkmcnt(0)
	v_mov_b32_e32 v30, v76
	v_mov_b32_e32 v31, v78
	v_pk_mul_f32 v[6:7], v[6:7], v[30:31]
	v_mov_b32_e32 v78, v77
	v_pk_mul_f32 v[30:31], v[70:71], v[78:79]
	ds_read_b128 v[68:71], v93
	v_add_co_u32_e32 v26, vcc, s77, v26
	v_cvt_pk_bf16_f32 v7, v7, v31
	v_cvt_pk_bf16_f32 v6, v6, v30
	v_addc_co_u32_e32 v27, vcc, 0, v27, vcc
	global_store_dwordx4 v[26:27], v[4:7], off offset:2048
	s_waitcnt lgkmcnt(0)
; __device__ __forceinline__ unsigned pack2(float a, float b) { return (unsigned)f2bf(a) | ((unsigned)f2bf(b) << 16); }
; __device__ __forceinline__ float bflo(unsigned w) { return __uint_as_float(w << 16); }
; __device__ __forceinline__ float bfhi(unsigned w) { return __uint_as_float(w & 0xffff0000u); }
; __device__ __forceinline__ float silu_f(float g) { return g / (1.f + __expf(-g)); }
; template <int DH, int MODE>
; __device__ void attn_item(const Params& p, int layer, int b, int blk, int head, char* smem) {
;     ...
; #pragma unroll
;     for (int i = 0; i < NCH; ++i) {
;       int q = tid + 256 * i, r = q / CPR, c = (q % CPR) * 8;
;       float4 m0 = *reinterpret_cast<const float4*>(Of + r * OST + c);
;       float4 m1 = *reinterpret_cast<const float4*>(Of + r * OST + c + 4);
;       float mm[8] = {m0.x, m0.y, m0.z, m0.w, m1.x, m1.y, m1.z, m1.w};
;       unsigned gw[4] = {gt[i].x, gt[i].y, gt[i].z, gt[i].w};
;       unsigned ow[4];
; #pragma unroll
;       for (int e = 0; e < 4; ++e)
;         ow[e] = pack2(mm[2 * e] * silu_f(bflo(gw[e])), mm[2 * e + 1] * silu_f(bfhi(gw[e])));
;       *reinterpret_cast<uint4*>(Y + (tq0 + r) * YW + ycol + c) = make_uint4(ow[0], ow[1], ow[2], ow[3]);
;     }
	v_mov_b32_e32 v26, v68
	v_mov_b32_e32 v27, v70
	ds_read_b128 v[4:7], v93 offset:16
	v_pk_mul_f32 v[0:1], v[0:1], v[26:27]
	v_mov_b32_e32 v70, v69
	v_pk_mul_f32 v[26:27], v[64:65], v[70:71]
	v_cvt_pk_bf16_f32 v1, v1, v27
	v_cvt_pk_bf16_f32 v0, v0, v26
	s_waitcnt lgkmcnt(0)
	v_mov_b32_e32 v26, v4
	v_mov_b32_e32 v27, v6
	v_pk_mul_f32 v[2:3], v[2:3], v[26:27]
	v_mov_b32_e32 v6, v5
	v_pk_mul_f32 v[4:5], v[66:67], v[6:7]
	v_cvt_pk_bf16_f32 v3, v3, v5
	v_cvt_pk_bf16_f32 v2, v2, v4
	ds_read_b128 v[4:7], v92
	v_add_co_u32_e32 v20, vcc, s77, v20
	s_nop 1
	v_addc_co_u32_e32 v21, vcc, 0, v21, vcc
	global_store_dwordx4 v[20:21], v[0:3], off offset:2048
	s_waitcnt lgkmcnt(0)
	v_mov_b32_e32 v20, v4
	v_mov_b32_e32 v21, v6
	ds_read_b128 v[0:3], v92 offset:16
	v_pk_mul_f32 v[20:21], v[56:57], v[20:21]
	v_mov_b32_e32 v6, v5
	v_pk_mul_f32 v[4:5], v[58:59], v[6:7]
	v_cvt_pk_bf16_f32 v5, v21, v5
	v_cvt_pk_bf16_f32 v4, v20, v4
	s_waitcnt lgkmcnt(0)
	v_mov_b32_e32 v6, v0
	v_mov_b32_e32 v7, v2
	v_pk_mul_f32 v[6:7], v[60:61], v[6:7]
	v_mov_b32_e32 v2, v1
	v_pk_mul_f32 v[0:1], v[62:63], v[2:3]
	v_cvt_pk_bf16_f32 v7, v7, v1
	v_cvt_pk_bf16_f32 v6, v6, v0
	ds_read_b128 v[0:3], v75
	v_add_co_u32_e32 v16, vcc, s77, v16
	s_nop 1
	v_addc_co_u32_e32 v17, vcc, 0, v17, vcc
	global_store_dwordx4 v[16:17], v[4:7], off offset:2048
	s_waitcnt lgkmcnt(0)
	v_mov_b32_e32 v16, v0
	v_mov_b32_e32 v17, v2
	ds_read_b128 v[4:7], v75 offset:16
	v_pk_mul_f32 v[16:17], v[48:49], v[16:17]
	v_mov_b32_e32 v2, v1
	v_pk_mul_f32 v[0:1], v[50:51], v[2:3]
	v_cvt_pk_bf16_f32 v1, v17, v1
	v_cvt_pk_bf16_f32 v0, v16, v0
	s_waitcnt lgkmcnt(0)
	v_mov_b32_e32 v2, v4
	v_mov_b32_e32 v3, v6
	v_pk_mul_f32 v[2:3], v[52:53], v[2:3]
	v_mov_b32_e32 v6, v5
	v_pk_mul_f32 v[4:5], v[54:55], v[6:7]
	v_cvt_pk_bf16_f32 v3, v3, v5
	v_cvt_pk_bf16_f32 v2, v2, v4
	ds_read_b128 v[4:7], v74
	v_add_co_u32_e32 v12, vcc, s77, v12
	s_nop 1
	v_addc_co_u32_e32 v13, vcc, 0, v13, vcc
	global_store_dwordx4 v[12:13], v[0:3], off offset:2048
	s_waitcnt lgkmcnt(0)
	v_mov_b32_e32 v12, v4
	v_mov_b32_e32 v13, v6
	ds_read_b128 v[0:3], v74 offset:16
	v_pk_mul_f32 v[12:13], v[40:41], v[12:13]
	v_mov_b32_e32 v6, v5
	v_pk_mul_f32 v[4:5], v[42:43], v[6:7]
	v_cvt_pk_bf16_f32 v5, v13, v5
	v_cvt_pk_bf16_f32 v4, v12, v4
	s_waitcnt lgkmcnt(0)
	v_mov_b32_e32 v6, v0
	v_mov_b32_e32 v7, v2
	v_pk_mul_f32 v[6:7], v[44:45], v[6:7]
	v_mov_b32_e32 v2, v1
	v_pk_mul_f32 v[0:1], v[46:47], v[2:3]
	v_cvt_pk_bf16_f32 v7, v7, v1
	v_cvt_pk_bf16_f32 v6, v6, v0
	ds_read_b128 v[0:3], v73
	v_add_co_u32_e32 v10, vcc, s77, v10
	s_nop 1
	v_addc_co_u32_e32 v11, vcc, 0, v11, vcc
	global_store_dwordx4 v[10:11], v[4:7], off offset:2048
	s_waitcnt lgkmcnt(0)
	v_mov_b32_e32 v10, v0
	v_mov_b32_e32 v11, v2
	ds_read_b128 v[4:7], v73 offset:16
	v_pk_mul_f32 v[10:11], v[32:33], v[10:11]
	v_mov_b32_e32 v2, v1
	v_pk_mul_f32 v[0:1], v[34:35], v[2:3]
	v_cvt_pk_bf16_f32 v1, v11, v1
	v_cvt_pk_bf16_f32 v0, v10, v0
	s_waitcnt lgkmcnt(0)
	v_mov_b32_e32 v2, v4
	v_mov_b32_e32 v3, v6
	v_pk_mul_f32 v[2:3], v[36:37], v[2:3]
	v_mov_b32_e32 v6, v5
	v_pk_mul_f32 v[4:5], v[38:39], v[6:7]
	v_cvt_pk_bf16_f32 v3, v3, v5
	v_cvt_pk_bf16_f32 v2, v2, v4
	ds_read_b128 v[4:7], v72
	v_add_co_u32_e32 v8, vcc, s77, v8
	s_nop 1
	v_addc_co_u32_e32 v9, vcc, 0, v9, vcc
	global_store_dwordx4 v[8:9], v[0:3], off offset:2048
	s_waitcnt lgkmcnt(0)
	v_mov_b32_e32 v8, v4
	v_mov_b32_e32 v9, v6
	ds_read_b128 v[0:3], v72 offset:16
	v_pk_mul_f32 v[8:9], v[18:19], v[8:9]
	v_mov_b32_e32 v6, v5
	v_pk_mul_f32 v[4:5], v[22:23], v[6:7]
	v_cvt_pk_bf16_f32 v5, v9, v5
	v_cvt_pk_bf16_f32 v4, v8, v4
	s_waitcnt lgkmcnt(0)
	v_mov_b32_e32 v6, v0
	v_mov_b32_e32 v7, v2
	v_pk_mul_f32 v[6:7], v[24:25], v[6:7]
	v_mov_b32_e32 v2, v1
	v_pk_mul_f32 v[0:1], v[28:29], v[2:3]
	v_cvt_pk_bf16_f32 v6, v6, v0
	v_add_co_u32_e32 v0, vcc, 0x184a1000, v14
	v_cvt_pk_bf16_f32 v7, v7, v1
	s_nop 0
	v_addc_co_u32_e32 v1, vcc, 0, v15, vcc
	global_store_dwordx4 v[0:1], v[4:7], off offset:2048
	s_barrier

; #define MFMA16(a, b, c) __builtin_amdgcn_mfma_f32_16x16x32_bf16(a, b, c, 0, 0, 0)
; __device__ void gmlp_item(const Params& p, int layer, int b, int n, int g, char* smem) {
;     ...
; #pragma unroll 2
;   for (int i = 0; i < 8; ++i) {
;     int q = tid + 256 * i;
;     int t = q >> 4, cch = q & 15;
;     uint4 v = *reinterpret_cast<const uint4*>(Ws + (size_t)g * 16384 + t * 128 + cch * 8);
;     *reinterpret_cast<uint4*>(smem + (cch >> 2) * 8192 + t * 64 + (cch & 3) * 16) = v;
;   }
;   __syncthreads();
;   f32x4 acc[4][4];
; #pragma unroll
;   for (int m = 0; m < 4; ++m)
; #pragma unroll
;     for (int nn = 0; nn < 4; ++nn) acc[m][nn] = f32x4{0.f, 0.f, 0.f, 0.f};
; #pragma unroll
;   for (int ks = 0; ks < 4; ++ks) {
;     bf16x8 a[4], bb[4];
; #pragma unroll
;     for (int m = 0; m < 4; ++m)
;       a[m] = *reinterpret_cast<const bf16x8*>(smem + ks * 8192 + (wr * 64 + m * 16 + fr) * 64 + fq * 16);
; #pragma unroll
;     for (int nn = 0; nn < 4; ++nn)
;       bb[nn] = *reinterpret_cast<const bf16x8*>(smem + 32768 + ks * 8192 + (wc * 64 + nn * 16 + fr) * 64 + fq * 16);
; #pragma unroll
;     for (int m = 0; m < 4; ++m)
; #pragma unroll
;       for (int nn = 0; nn < 4; ++nn) acc[m][nn] = MFMA16(a[m], bb[nn], acc[m][nn]);
;   }
;   __syncthreads();
.LBB0_480:
	v_add_u32_e32 v3, s14, v60
	v_ashrrev_i32_e32 v12, 4, v3
	v_add_u32_e32 v3, 0x100, v3
	v_ashrrev_i32_e32 v3, 4, v3
	v_lshlrev_b32_e32 v4, 7, v12
	v_lshlrev_b32_e32 v6, 7, v3
	v_ashrrev_i32_e32 v5, 31, v4
	v_ashrrev_i32_e32 v7, 31, v6
	v_lshl_add_u64 v[4:5], v[4:5], 1, v[0:1]
	v_lshl_add_u64 v[8:9], v[6:7], 1, v[0:1]
	global_load_dwordx4 v[4:7], v[4:5], off
	s_nop 0
	global_load_dwordx4 v[8:11], v[8:9], off
	s_addk_i32 s14, 0x200
	s_cmpk_lg_i32 s14, 0x800
	v_lshl_add_u32 v12, v12, 6, v2
	v_lshl_add_u32 v3, v3, 6, v2
	s_waitcnt vmcnt(1)
	ds_write_b128 v12, v[4:7]
	s_waitcnt vmcnt(0)
	ds_write_b128 v3, v[8:11]
	s_cbranch_scc1 .LBB0_480
	v_bfe_u32 v32, v60, 4, 2
	v_ashrrev_i32_e32 v33, 7, v60
	v_lshlrev_b32_e32 v4, 4, v32
	v_lshlrev_b32_e32 v0, 12, v33
	v_lshlrev_b32_e32 v5, 6, v35
	v_or3_b32 v37, v4, v0, v5
	s_waitcnt lgkmcnt(0)
	s_barrier
	ds_read_b128 v[0:3], v37
	v_bfe_u32 v39, v60, 6, 1
	v_lshlrev_b32_e32 v6, 12, v39
	v_or3_b32 v41, v4, v6, v5
	ds_read_b128 v[4:7], v41 offset:32768
	ds_read_b128 v[8:11], v37 offset:1024
	ds_read_b128 v[12:15], v41 offset:33792
	ds_read_b128 v[24:27], v41 offset:34816
	ds_read_b128 v[28:31], v41 offset:35840
	s_waitcnt lgkmcnt(4)
	v_mfma_f32_16x16x32_bf16 v[16:19], v[0:3], v[4:7], 0
	s_ashr_i32 s15, s17, 31
	s_add_u32 s14, s28, s17
	s_addc_u32 s15, s29, s15
	s_waitcnt lgkmcnt(2)
	v_mfma_f32_16x16x32_bf16 v[20:23], v[0:3], v[12:15], 0
	v_lshlrev_b32_e32 v33, 6, v33
	s_lshl_b32 s17, s16, 2
	v_lshl_or_b32 v32, v32, 2, v33
	s_waitcnt lgkmcnt(1)
	v_mfma_f32_16x16x32_bf16 v[50:53], v[0:3], v[24:27], 0
	s_add_u32 s20, s24, s17
	s_addc_u32 s21, s25, 0
	v_ashrrev_i32_e32 v33, 31, v32
	s_waitcnt lgkmcnt(0)
	v_mfma_f32_16x16x32_bf16 v[54:57], v[0:3], v[28:31], 0
	ds_read_b128 v[0:3], v37 offset:2048
	ds_read_b128 v[74:77], v37 offset:3072
	ds_read_b128 v[98:101], v37 offset:8192
	v_lshl_add_u64 v[58:59], v[32:33], 2, s[20:21]
	v_mfma_f32_16x16x32_bf16 v[62:65], v[8:11], v[4:7], 0
	v_lshlrev_b32_e32 v33, 2, v35
	v_lshl_or_b32 v126, v39, 8, v33
	v_mad_u64_u32 v[32:33], s[20:21], v32, s69, v[126:127]
	v_mfma_f32_16x16x32_bf16 v[66:69], v[8:11], v[12:15], 0
	v_add_u32_e32 v33, 0x400, v32
	v_ashrrev_i32_e32 v49, 31, v48
	v_ashrrev_i32_e32 v47, 31, v46
	v_mfma_f32_16x16x32_bf16 v[70:73], v[8:11], v[24:27], 0
	v_ashrrev_i32_e32 v45, 31, v44
	v_ashrrev_i32_e32 v43, 31, v42
	v_ashrrev_i32_e32 v39, 31, v38
	v_mfma_f32_16x16x32_bf16 v[8:11], v[8:11], v[28:31], 0
	s_waitcnt lgkmcnt(2)
	v_mfma_f32_16x16x32_bf16 v[78:81], v[0:3], v[4:7], 0
	v_mfma_f32_16x16x32_bf16 v[82:85], v[0:3], v[12:15], 0
	v_mfma_f32_16x16x32_bf16 v[86:89], v[0:3], v[24:27], 0
	v_mfma_f32_16x16x32_bf16 v[90:93], v[0:3], v[28:31], 0
	s_waitcnt lgkmcnt(1)
	v_mfma_f32_16x16x32_bf16 v[94:97], v[74:77], v[4:7], 0
	v_mfma_f32_16x16x32_bf16 v[12:15], v[74:77], v[12:15], 0
	v_mfma_f32_16x16x32_bf16 v[24:27], v[74:77], v[24:27], 0
	v_mfma_f32_16x16x32_bf16 v[0:3], v[74:77], v[28:31], 0
	ds_read_b128 v[28:31], v41 offset:40960
	ds_read_b128 v[74:77], v37 offset:9216
	ds_read_b128 v[102:105], v41 offset:41984
	ds_read_b128 v[106:109], v41 offset:43008
	ds_read_b128 v[4:7], v41 offset:44032
	s_waitcnt lgkmcnt(4)
	v_mfma_f32_16x16x32_bf16 v[16:19], v[98:101], v[28:31], v[16:19]
	s_waitcnt lgkmcnt(2)
	v_mfma_f32_16x16x32_bf16 v[20:23], v[98:101], v[102:105], v[20:23]
	s_waitcnt lgkmcnt(1)
	v_mfma_f32_16x16x32_bf16 v[50:53], v[98:101], v[106:109], v[50:53]
	s_waitcnt lgkmcnt(0)
	v_mfma_f32_16x16x32_bf16 v[54:57], v[98:101], v[4:7], v[54:57]
	ds_read_b128 v[98:101], v37 offset:10240
	v_mfma_f32_16x16x32_bf16 v[62:65], v[74:77], v[28:31], v[62:65]
	v_mfma_f32_16x16x32_bf16 v[66:69], v[74:77], v[102:105], v[66:69]
	v_mfma_f32_16x16x32_bf16 v[70:73], v[74:77], v[106:109], v[70:73]
	v_mfma_f32_16x16x32_bf16 v[8:11], v[74:77], v[4:7], v[8:11]
	ds_read_b128 v[74:77], v37 offset:11264
	ds_read_b128 v[110:113], v37 offset:16384
	ds_read_b128 v[114:117], v37 offset:17408
	ds_read_b128 v[118:121], v37 offset:18432
	ds_read_b128 v[122:125], v37 offset:19456
	ds_read_b128 v[134:137], v41 offset:49152
	ds_read_b128 v[138:141], v41 offset:50176
	ds_read_b128 v[146:149], v41 offset:51200
	ds_read_b128 v[150:153], v41 offset:52224
	ds_read_b128 v[162:165], v37 offset:24576
	ds_read_b128 v[166:169], v37 offset:25600
	s_waitcnt lgkmcnt(11)
	v_mfma_f32_16x16x32_bf16 v[78:81], v[98:101], v[28:31], v[78:81]
	v_mfma_f32_16x16x32_bf16 v[82:85], v[98:101], v[102:105], v[82:85]
	v_mfma_f32_16x16x32_bf16 v[86:89], v[98:101], v[106:109], v[86:89]
	v_mfma_f32_16x16x32_bf16 v[90:93], v[98:101], v[4:7], v[90:93]
	ds_read_b128 v[98:101], v37 offset:26624
	ds_read_b128 v[170:173], v37 offset:27648
	ds_read_b128 v[174:177], v41 offset:57344
	ds_read_b128 v[178:181], v41 offset:58368
	s_waitcnt lgkmcnt(14)
	v_mfma_f32_16x16x32_bf16 v[28:31], v[74:77], v[28:31], v[94:97]
	s_nop 2
	ds_read_b128 v[94:97], v41 offset:59392
	ds_read_b128 v[182:185], v41 offset:60416
	s_waitcnt lgkmcnt(0)
	s_barrier
; #define MFMA16(a, b, c) __builtin_amdgcn_mfma_f32_16x16x32_bf16(a, b, c, 0, 0, 0)
; __device__ void gmlp_item(const Params& p, int layer, int b, int n, int g, char* smem) {
;     ...
;   for (int ks = 0; ks < 4; ++ks) {
;     bf16x8 a[4], bb[4];
; #pragma unroll
;     for (int m = 0; m < 4; ++m)
;       a[m] = *reinterpret_cast<const bf16x8*>(smem + ks * 8192 + (wr * 64 + m * 16 + fr) * 64 + fq * 16);
; #pragma unroll
;     for (int nn = 0; nn < 4; ++nn)
;       bb[nn] = *reinterpret_cast<const bf16x8*>(smem + 32768 + ks * 8192 + (wc * 64 + nn * 16 + fr) * 64 + fq * 16);
; #pragma unroll
;     for (int m = 0; m < 4; ++m)
; #pragma unroll
;       for (int nn = 0; nn < 4; ++nn) acc[m][nn] = MFMA16(a[m], bb[nn], acc[m][nn]);
;   }
;   __syncthreads();
;   {
;     float* Tf = reinterpret_cast<float*>(smem);
; #pragma unroll
;     for (int m = 0; m < 4; ++m)
; #pragma unroll
;       for (int j = 0; j < 4; ++j) {
;         int t = wr * 64 + m * 16 + fq * 4 + j;
;         float bias = p.gm_b_s[(size_t)layer * 512 + g * 128 + t];
; #pragma unroll
;         for (int nn = 0; nn < 4; ++nn) Tf[t * 132 + wc * 64 + nn * 16 + fr] = acc[m][nn][j] + bias;
;       }
	v_mfma_f32_16x16x32_bf16 v[16:19], v[110:113], v[134:137], v[16:19]
	global_load_dwordx4 v[186:189], v[58:59], off offset:2112
	global_load_dwordx4 v[190:193], v[58:59], off offset:2176
	v_mfma_f32_16x16x32_bf16 v[20:23], v[110:113], v[138:141], v[20:23]
	v_ashrrev_i32_e32 v41, 31, v40
	v_mfma_f32_16x16x32_bf16 v[50:53], v[110:113], v[146:149], v[50:53]
	v_mfma_f32_16x16x32_bf16 v[54:57], v[110:113], v[150:153], v[54:57]
	global_load_dwordx4 v[110:113], v[58:59], off offset:2048
	v_mfma_f32_16x16x32_bf16 v[16:19], v[162:165], v[174:177], v[16:19]
	v_mfma_f32_16x16x32_bf16 v[20:23], v[162:165], v[178:181], v[20:23]
	v_mfma_f32_16x16x32_bf16 v[50:53], v[162:165], v[94:97], v[50:53]
	s_waitcnt vmcnt(0)
	s_nop 4
	v_add_f32_e32 v16, v16, v110
	v_mfma_f32_16x16x32_bf16 v[54:57], v[162:165], v[182:185], v[54:57]
	v_add_f32_e32 v20, v20, v110
	ds_write2_b32 v32, v16, v20 offset1:16
	v_add_f32_e32 v16, v50, v110
	v_add_f32_e32 v35, v53, v113
	v_mfma_f32_16x16x32_bf16 v[62:65], v[114:117], v[134:137], v[62:65]
	s_nop 2
	v_add_f32_e32 v20, v54, v110
	ds_write2_b32 v32, v16, v20 offset0:32 offset1:48
	v_add_f32_e32 v16, v17, v111
	v_add_f32_e32 v17, v21, v111
	ds_write2_b32 v32, v16, v17 offset0:132 offset1:148
	v_add_f32_e32 v16, v51, v111
	v_add_f32_e32 v17, v55, v111
	ds_write2_b32 v32, v16, v17 offset0:164 offset1:180
	v_add_f32_e32 v16, v18, v112
	v_add_f32_e32 v17, v22, v112
	ds_write2_b32 v33, v16, v17 offset0:8 offset1:24
	v_add_f32_e32 v16, v52, v112
	global_load_dwordx4 v[50:53], v[58:59], off offset:2240
	v_mfma_f32_16x16x32_bf16 v[66:69], v[114:117], v[138:141], v[66:69]
	v_add_f32_e32 v17, v56, v112
	v_add_f32_e32 v20, v19, v113
	v_add_f32_e32 v21, v23, v113
	v_mfma_f32_16x16x32_bf16 v[70:73], v[114:117], v[146:149], v[70:73]
	ds_write2_b32 v33, v16, v17 offset0:40 offset1:56
	ds_write2_b32 v33, v20, v21 offset0:140 offset1:156
	v_add_f32_e32 v37, v57, v113
	v_mfma_f32_16x16x32_bf16 v[8:11], v[114:117], v[150:153], v[8:11]
	ds_write2_b32 v33, v35, v37 offset0:172 offset1:188
	v_add_u32_e32 v33, 0x2000, v32
	v_ashrrev_i32_e32 v35, 31, v34
	v_mfma_f32_16x16x32_bf16 v[16:19], v[166:169], v[174:177], v[62:65]
	v_ashrrev_i32_e32 v37, 31, v36
	v_lshl_add_u64 v[58:59], v[42:43], 0, s[36:37]
	v_mfma_f32_16x16x32_bf16 v[20:23], v[166:169], v[178:181], v[66:69]
	v_mfma_f32_16x16x32_bf16 v[54:57], v[166:169], v[94:97], v[70:73]
	s_nop 3
	v_add_f32_e32 v16, v16, v186
	s_nop 1
	v_add_f32_e32 v20, v20, v186
	ds_write2_b32 v33, v16, v20 offset0:64 offset1:80
	v_mfma_f32_16x16x32_bf16 v[8:11], v[166:169], v[182:185], v[8:11]
	v_add_u32_e32 v20, 0x2400, v32
	v_add_f32_e32 v16, v54, v186
	v_mfma_f32_16x16x32_bf16 v[62:65], v[118:121], v[134:137], v[78:81]
	v_mfma_f32_16x16x32_bf16 v[66:69], v[118:121], v[138:141], v[82:85]
	s_nop 3
	v_add_f32_e32 v8, v8, v186
	ds_write2_b32 v33, v16, v8 offset0:96 offset1:112
	v_add_f32_e32 v8, v17, v187
	v_add_f32_e32 v16, v21, v187
	ds_write2_b32 v33, v8, v16 offset0:196 offset1:212
	v_add_f32_e32 v8, v55, v187
	v_add_f32_e32 v9, v9, v187
	ds_write2_b32 v33, v8, v9 offset0:228 offset1:244
	v_add_f32_e32 v8, v18, v188
	v_add_f32_e32 v9, v22, v188
	v_mfma_f32_16x16x32_bf16 v[70:73], v[118:121], v[146:149], v[86:89]
	ds_write2_b32 v20, v8, v9 offset0:72 offset1:88
	v_add_f32_e32 v8, v56, v188
	v_add_f32_e32 v9, v10, v188
	v_mfma_f32_16x16x32_bf16 v[78:81], v[118:121], v[150:153], v[90:93]
	ds_write2_b32 v20, v8, v9 offset0:104 offset1:120
	v_add_f32_e32 v8, v19, v189
	v_add_f32_e32 v9, v23, v189
	v_mfma_f32_16x16x32_bf16 v[16:19], v[98:101], v[174:177], v[62:65]
	ds_write2_b32 v20, v8, v9 offset0:204 offset1:220
	v_add_f32_e32 v21, v57, v189
	v_add_f32_e32 v22, v11, v189
	v_mfma_f32_16x16x32_bf16 v[8:11], v[98:101], v[178:181], v[66:69]
	ds_write2_b32 v20, v21, v22 offset0:236 offset1:252
	s_nop 2
	v_add_f32_e32 v16, v16, v190
	v_add_u32_e32 v33, 0x4000, v32
	v_mfma_f32_16x16x32_bf16 v[20:23], v[98:101], v[94:97], v[70:73]
	v_lshl_add_u64 v[62:63], v[38:39], 0, s[36:37]
	v_add_f32_e32 v8, v8, v190
	ds_write2_b32 v33, v16, v8 offset0:128 offset1:144
	v_mfma_f32_16x16x32_bf16 v[54:57], v[98:101], v[182:185], v[78:81]
	v_add_f32_e32 v10, v10, v192
	s_nop 2
	v_add_f32_e32 v8, v20, v190
	v_mfma_f32_16x16x32_bf16 v[12:15], v[74:77], v[102:105], v[12:15]
	v_mfma_f32_16x16x32_bf16 v[24:27], v[74:77], v[106:109], v[24:27]
	s_nop 0
	v_add_f32_e32 v16, v54, v190
	ds_write2_b32 v33, v8, v16 offset0:160 offset1:176
	v_add_f32_e32 v8, v17, v191
	v_mfma_f32_16x16x32_bf16 v[0:3], v[74:77], v[4:7], v[0:3]
	v_add_f32_e32 v4, v9, v191
	v_add_u32_e32 v9, 0x4400, v32
	ds_write2_b32 v9, v8, v4 offset0:4 offset1:20
	v_mfma_f32_16x16x32_bf16 v[4:7], v[122:125], v[134:137], v[28:31]
	v_add_f32_e32 v8, v21, v191
	v_add_f32_e32 v16, v55, v191
	ds_write2_b32 v9, v8, v16 offset0:36 offset1:52
	v_mfma_f32_16x16x32_bf16 v[12:15], v[122:125], v[138:141], v[12:15]
	v_add_f32_e32 v8, v18, v192
	ds_write2_b32 v9, v8, v10 offset0:136 offset1:152
	v_add_f32_e32 v8, v22, v192
	v_mfma_f32_16x16x32_bf16 v[24:27], v[122:125], v[146:149], v[24:27]
	v_add_f32_e32 v10, v56, v192
	ds_write2_b32 v9, v8, v10 offset0:168 offset1:184
	v_add_f32_e32 v8, v19, v193
	v_mfma_f32_16x16x32_bf16 v[0:3], v[122:125], v[150:153], v[0:3]
	v_add_f32_e32 v9, v11, v193
	v_add_u32_e32 v16, 0x4800, v32
	ds_write2_b32 v16, v8, v9 offset0:12 offset1:28
	v_mfma_f32_16x16x32_bf16 v[4:7], v[170:173], v[174:177], v[4:7]
	v_add_f32_e32 v17, v23, v193
	v_add_f32_e32 v18, v57, v193
	ds_write2_b32 v16, v17, v18 offset0:44 offset1:60
	v_mfma_f32_16x16x32_bf16 v[8:11], v[170:173], v[178:181], v[12:15]
	v_add_u32_e32 v16, 0x6000, v32
	s_waitcnt vmcnt(0)
; __device__ __forceinline__ unsigned pack2(float a, float b) { return (unsigned)f2bf(a) | ((unsigned)f2bf(b) << 16); }
; __device__ __forceinline__ float bflo(unsigned w) { return __uint_as_float(w << 16); }
; __device__ __forceinline__ float bfhi(unsigned w) { return __uint_as_float(w & 0xffff0000u); }
; __device__ __forceinline__ float silu_f(float g) { return g / (1.f + __expf(-g)); }
; __device__ void gmlp_item(const Params& p, int layer, int b, int n, int g, char* smem) {
;     ...
;     for (int m = 0; m < 4; ++m)
; #pragma unroll
;       for (int j = 0; j < 4; ++j) {
;         int t = wr * 64 + m * 16 + fq * 4 + j;
;         float bias = p.gm_b_s[(size_t)layer * 512 + g * 128 + t];
; #pragma unroll
;         for (int nn = 0; nn < 4; ++nn) Tf[t * 132 + wc * 64 + nn * 16 + fr] = acc[m][nn][j] + bias;
;       }
;     __syncthreads();
;     uint4 uu[8], gt[8];
; #pragma unroll
;     for (int i = 0; i < 8; ++i) {
;       int q = tid + 256 * i, t = q >> 4, c = (q & 15) * 8;
;       uu[i] = *reinterpret_cast<const uint4*>(P + (t0 + t) * NP + g * 128 + c);
;       gt[i] = *reinterpret_cast<const uint4*>(P + (t0 + t) * NP + 1024 + g * 128 + c);
;     }
; #pragma unroll
;     for (int i = 0; i < 8; ++i) {
;       int q = tid + 256 * i, t = q >> 4, c = (q & 15) * 8;
;       float4 m0 = *reinterpret_cast<const float4*>(Tf + t * 132 + c);
;       float4 m1 = *reinterpret_cast<const float4*>(Tf + t * 132 + c + 4);
;       float mm[8] = {m0.x, m0.y, m0.z, m0.w, m1.x, m1.y, m1.z, m1.w};
;       unsigned uw[4] = {uu[i].x, uu[i].y, uu[i].z, uu[i].w};
;       unsigned gw[4] = {gt[i].x, gt[i].y, gt[i].z, gt[i].w};
;       unsigned ow[4];
; #pragma unroll
;       for (int e = 0; e < 4; ++e) {
;         float y0 = bflo(uw[e]) * mm[2 * e] * silu_f(bflo(gw[e]));
;         float y1 = bfhi(uw[e]) * mm[2 * e + 1] * silu_f(bfhi(gw[e]));
;         ow[e] = pack2(y0, y1);
;       }
;       *reinterpret_cast<uint4*>(Y + (t0 + t) * YW + g * 128 + c) = make_uint4(ow[0], ow[1], ow[2], ow[3]);
	s_nop 1
	v_add_f32_e32 v4, v4, v50
	v_lshl_add_u64 v[56:57], v[36:37], 0, s[36:37]
	v_mfma_f32_16x16x32_bf16 v[12:15], v[170:173], v[94:97], v[24:27]
	v_lshl_add_u64 v[20:21], v[44:45], 0, s[36:37]
	v_add_f32_e32 v8, v8, v50
	ds_write2_b32 v16, v4, v8 offset0:192 offset1:208
	v_mfma_f32_16x16x32_bf16 v[0:3], v[170:173], v[182:185], v[0:3]
	s_nop 3
	v_add_f32_e32 v4, v12, v50
	s_nop 2
	v_add_f32_e32 v0, v0, v50
	ds_write2_b32 v16, v4, v0 offset0:224 offset1:240
	v_add_f32_e32 v0, v5, v51
	v_add_f32_e32 v4, v9, v51
	v_add_u32_e32 v5, 0x6400, v32
	ds_write2_b32 v5, v0, v4 offset0:68 offset1:84
	v_add_f32_e32 v0, v13, v51
	v_add_f32_e32 v1, v1, v51
	ds_write2_b32 v5, v0, v1 offset0:100 offset1:116
	v_add_f32_e32 v0, v6, v52
	v_add_f32_e32 v1, v10, v52
	ds_write2_b32 v5, v0, v1 offset0:200 offset1:216
	v_add_f32_e32 v0, v14, v52
	v_add_f32_e32 v1, v2, v52
	ds_write2_b32 v5, v0, v1 offset0:232 offset1:248
	v_add_f32_e32 v0, v7, v53
	v_add_f32_e32 v1, v11, v53
	v_add_u32_e32 v2, 0x6800, v32
	ds_write2_b32 v2, v0, v1 offset0:76 offset1:92
	v_add_f32_e32 v0, v15, v53
	v_add_f32_e32 v1, v3, v53
	ds_write2_b32 v2, v0, v1 offset0:108 offset1:124
	v_lshlrev_b32_e32 v0, 3, v60
	v_lshl_add_u64 v[8:9], v[34:35], 0, s[36:37]
	v_mov_b64_e32 v[10:11], s[12:13]
	v_and_b32_e32 v24, 0x78, v0
	v_mad_u64_u32 v[0:1], s[12:13], v8, s63, v[10:11]
	v_mad_i32_i24 v1, v9, s63, v1
	s_lshl_b32 s12, s16, 1
	s_mov_b32 s13, s37
	v_lshl_add_u64 v[0:1], v[0:1], 0, s[12:13]
	v_lshlrev_b32_e32 v128, 1, v24
	v_lshl_add_u64 v[12:13], v[48:49], 0, s[36:37]
	v_lshl_add_u64 v[52:53], v[0:1], 0, v[128:129]
	v_mad_u64_u32 v[0:1], s[16:17], v12, s63, v[10:11]
	v_mad_i32_i24 v1, v13, s63, v1
	v_lshl_add_u64 v[0:1], v[0:1], 0, s[12:13]
	v_lshl_add_u64 v[32:33], v[0:1], 0, v[128:129]
	v_mad_u64_u32 v[0:1], s[16:17], v56, s63, v[10:11]
	v_mad_i32_i24 v1, v57, s63, v1
	v_lshl_add_u64 v[0:1], v[0:1], 0, s[12:13]
	v_lshl_add_u64 v[4:5], v[0:1], 0, v[128:129]
	s_waitcnt lgkmcnt(0)
	s_barrier
	global_load_dwordx4 v[0:3], v[4:5], off
	s_nop 0
	global_load_dwordx4 v[4:7], v[4:5], off offset:2048
	v_lshl_add_u64 v[16:17], v[46:47], 0, s[36:37]
	v_mad_u64_u32 v[14:15], s[16:17], v16, s63, v[10:11]
	v_mad_i32_i24 v15, v17, s63, v15
	v_lshl_add_u64 v[14:15], v[14:15], 0, s[12:13]
	v_lshl_add_u64 v[30:31], v[14:15], 0, v[128:129]
	v_mad_u64_u32 v[14:15], s[16:17], v20, s63, v[10:11]
	v_mad_i32_i24 v15, v21, s63, v15
	v_lshl_add_u64 v[14:15], v[14:15], 0, s[12:13]
	v_lshl_add_u64 v[26:27], v[14:15], 0, v[128:129]
	v_mad_u64_u32 v[14:15], s[16:17], v58, s63, v[10:11]
	v_mad_i32_i24 v15, v59, s63, v15
	v_lshl_add_u64 v[14:15], v[14:15], 0, s[12:13]
	v_lshl_add_u64 v[60:61], v[40:41], 0, s[36:37]
	v_lshl_add_u64 v[22:23], v[14:15], 0, v[128:129]
	v_mad_u64_u32 v[14:15], s[16:17], v60, s63, v[10:11]
	v_mad_u64_u32 v[10:11], s[16:17], v62, s63, v[10:11]
	v_mad_i32_i24 v15, v61, s63, v15
	v_mad_i32_i24 v11, v63, s63, v11
	v_lshl_add_u64 v[14:15], v[14:15], 0, s[12:13]
	v_lshl_add_u64 v[10:11], v[10:11], 0, s[12:13]
	s_add_u32 s12, s14, s12
	s_addc_u32 s13, s15, 0
	v_lshl_add_u64 v[18:19], v[14:15], 0, v[128:129]
	v_lshl_add_u64 v[14:15], v[10:11], 0, v[128:129]
	v_lshlrev_b32_e32 v10, 2, v24
	v_lshl_add_u64 v[24:25], s[12:13], 0, v[128:129]
	v_lshl_add_u64 v[64:65], v[24:25], 0, s[42:43]
	v_mad_u64_u32 v[54:55], s[12:13], v34, s69, v[10:11]
	v_mad_u64_u32 v[34:35], s[12:13], v48, s69, v[10:11]
	v_mad_u64_u32 v[48:49], s[12:13], v12, s70, v[64:65]
	v_mad_u64_u32 v[28:29], s[12:13], v46, s69, v[10:11]
	v_mad_u64_u32 v[46:47], s[12:13], v16, s70, v[64:65]
	v_mad_u64_u32 v[50:51], s[12:13], v8, s70, v[64:65]
	v_mad_i32_i24 v49, v13, s70, v49
	v_mad_i32_i24 v47, v17, s70, v47
	v_mad_u64_u32 v[24:25], s[12:13], v44, s69, v[10:11]
	v_mad_u64_u32 v[44:45], s[12:13], v20, s70, v[64:65]
	v_mad_u64_u32 v[16:17], s[12:13], v40, s69, v[10:11]
	v_mad_u64_u32 v[12:13], s[12:13], v38, s69, v[10:11]
	v_mad_i32_i24 v51, v9, s70, v51
	v_mad_i32_i24 v45, v21, s70, v45
	v_mad_u64_u32 v[20:21], s[12:13], v42, s69, v[10:11]
	v_mad_u64_u32 v[8:9], s[12:13], v36, s69, v[10:11]
	v_mad_u64_u32 v[40:41], s[12:13], v60, s70, v[64:65]
	v_mad_i32_i24 v41, v61, s70, v41
	v_mad_u64_u32 v[42:43], s[12:13], v58, s70, v[64:65]
	v_mad_u64_u32 v[36:37], s[12:13], v56, s70, v[64:65]
	v_mad_i32_i24 v43, v59, s70, v43
	v_mad_i32_i24 v37, v57, s70, v37
	v_mad_u64_u32 v[38:39], s[12:13], v62, s70, v[64:65]
	v_mad_i32_i24 v39, v63, s70, v39
	s_waitcnt vmcnt(1)
	v_lshlrev_b32_e32 v63, 16, v1
	s_waitcnt vmcnt(0)
	v_lshlrev_b32_e32 v13, 16, v5
	v_lshlrev_b32_e32 v17, 16, v4
	v_mul_f32_e32 v9, 0xbfb8aa3b, v17
	v_and_b32_e32 v21, 0xffff0000, v5
	v_mul_f32_e32 v5, 0xbfb8aa3b, v13
	v_exp_f32_e32 v60, v9
	v_exp_f32_e32 v61, v5
	ds_read_b128 v[56:59], v8
	ds_read_b128 v[8:11], v8 offset:16
	v_and_b32_e32 v25, 0xffff0000, v4
	v_mul_f32_e32 v4, 0xbfb8aa3b, v25
	v_pk_add_f32 v[60:61], v[60:61], 1.0 op_sel_hi:[1,0]
	s_waitcnt lgkmcnt(1)
	v_mov_b32_e32 v64, v56
	v_exp_f32_e32 v4, v4
	v_lshlrev_b32_e32 v62, 16, v0
	v_mov_b32_e32 v65, v58
	v_rcp_f32_e32 v61, v61
	s_nop 0
	v_mul_f32_e32 v61, v13, v61
	v_and_b32_e32 v1, 0xffff0000, v1
	v_mul_f32_e32 v5, 0xbfb8aa3b, v21
	v_exp_f32_e32 v5, v5
	v_rcp_f32_e32 v60, v60
	s_nop 0
	v_mul_f32_e32 v60, v17, v60
	v_and_b32_e32 v0, 0xffff0000, v0
	v_mov_b32_e32 v58, v57
	v_pk_add_f32 v[4:5], v[4:5], 1.0 op_sel_hi:[1,0]
	v_pk_mul_f32 v[0:1], v[58:59], v[0:1]
	v_pk_mul_f32 v[62:63], v[64:65], v[62:63]
	v_rcp_f32_e32 v5, v5
	s_nop 0
	v_mul_f32_e32 v5, v21, v5
	v_pk_mul_f32 v[60:61], v[60:61], v[62:63]
	v_rcp_f32_e32 v4, v4
	s_nop 0
	v_mul_f32_e32 v4, v25, v4
	v_pk_mul_f32 v[0:1], v[4:5], v[0:1]
	v_lshlrev_b32_e32 v13, 16, v7
	v_lshlrev_b32_e32 v17, 16, v6
	v_cvt_pk_bf16_f32 v1, v61, v1
	v_cvt_pk_bf16_f32 v0, v60, v0
	v_mul_f32_e32 v4, 0xbfb8aa3b, v17
	v_mul_f32_e32 v5, 0xbfb8aa3b, v13
	v_exp_f32_e32 v4, v4
	v_exp_f32_e32 v5, v5
	v_and_b32_e32 v25, 0xffff0000, v6
	v_mul_f32_e32 v6, 0xbfb8aa3b, v25
	v_and_b32_e32 v21, 0xffff0000, v7
	v_exp_f32_e32 v60, v6
	v_pk_add_f32 v[64:65], v[4:5], 1.0 op_sel_hi:[1,0]
	global_load_dwordx4 v[4:7], v[14:15], off
	global_load_dwordx4 v[56:59], v[14:15], off offset:2048
	s_waitcnt lgkmcnt(0)
; __device__ __forceinline__ unsigned pack2(float a, float b) { return (unsigned)f2bf(a) | ((unsigned)f2bf(b) << 16); }
; __device__ __forceinline__ float bflo(unsigned w) { return __uint_as_float(w << 16); }
; __device__ __forceinline__ float bfhi(unsigned w) { return __uint_as_float(w & 0xffff0000u); }
; __device__ __forceinline__ float silu_f(float g) { return g / (1.f + __expf(-g)); }
; __device__ void gmlp_item(const Params& p, int layer, int b, int n, int g, char* smem) {
;     ...
;     for (int i = 0; i < 8; ++i) {
;       int q = tid + 256 * i, t = q >> 4, c = (q & 15) * 8;
;       float4 m0 = *reinterpret_cast<const float4*>(Tf + t * 132 + c);
;       float4 m1 = *reinterpret_cast<const float4*>(Tf + t * 132 + c + 4);
;       float mm[8] = {m0.x, m0.y, m0.z, m0.w, m1.x, m1.y, m1.z, m1.w};
;       unsigned uw[4] = {uu[i].x, uu[i].y, uu[i].z, uu[i].w};
;       unsigned gw[4] = {gt[i].x, gt[i].y, gt[i].z, gt[i].w};
;       unsigned ow[4];
; #pragma unroll
;       for (int e = 0; e < 4; ++e) {
;         float y0 = bflo(uw[e]) * mm[2 * e] * silu_f(bflo(gw[e]));
;         float y1 = bfhi(uw[e]) * mm[2 * e + 1] * silu_f(bfhi(gw[e]));
;         ow[e] = pack2(y0, y1);
;       }
;       *reinterpret_cast<uint4*>(Y + (t0 + t) * YW + g * 128 + c) = make_uint4(ow[0], ow[1], ow[2], ow[3]);
	v_mov_b32_e32 v14, v8
	v_mov_b32_e32 v15, v10
	v_lshlrev_b32_e32 v63, 16, v3
	v_lshlrev_b32_e32 v62, 16, v2
	v_pk_mul_f32 v[14:15], v[14:15], v[62:63]
	v_rcp_f32_e32 v63, v65
	s_nop 0
	v_mul_f32_e32 v63, v13, v63
	v_mul_f32_e32 v10, 0xbfb8aa3b, v21
	v_exp_f32_e32 v61, v10
	v_rcp_f32_e32 v62, v64
	s_nop 0
	v_mul_f32_e32 v62, v17, v62
	v_mov_b32_e32 v10, v9
	v_and_b32_e32 v3, 0xffff0000, v3
	v_pk_add_f32 v[60:61], v[60:61], 1.0 op_sel_hi:[1,0]
	v_and_b32_e32 v2, 0xffff0000, v2
	v_pk_mul_f32 v[2:3], v[10:11], v[2:3]
	v_pk_mul_f32 v[14:15], v[62:63], v[14:15]
	v_rcp_f32_e32 v9, v61
	s_nop 0
	v_mul_f32_e32 v9, v21, v9
	v_rcp_f32_e32 v8, v60
	s_nop 0
	v_mul_f32_e32 v8, v25, v8
	v_pk_mul_f32 v[2:3], v[8:9], v[2:3]
	v_cvt_pk_bf16_f32 v3, v15, v3
	v_cvt_pk_bf16_f32 v2, v14, v2
	s_waitcnt vmcnt(0)
	v_lshlrev_b32_e32 v21, 16, v56
	v_mul_f32_e32 v8, 0xbfb8aa3b, v21
	v_and_b32_e32 v29, 0xffff0000, v56
	v_lshlrev_b32_e32 v17, 16, v57
	v_exp_f32_e32 v60, v8
	v_mul_f32_e32 v8, 0xbfb8aa3b, v29
	v_exp_f32_e32 v56, v8
	v_mul_f32_e32 v8, 0xbfb8aa3b, v17
	v_exp_f32_e32 v61, v8
	ds_read_b128 v[8:11], v12
	ds_read_b128 v[12:15], v12 offset:16
	v_and_b32_e32 v25, 0xffff0000, v57
	v_lshlrev_b32_e32 v63, 16, v5
	v_pk_add_f32 v[60:61], v[60:61], 1.0 op_sel_hi:[1,0]
	s_waitcnt lgkmcnt(1)
	v_mov_b32_e32 v64, v8
	v_mov_b32_e32 v65, v10
	v_lshlrev_b32_e32 v62, 16, v4
	v_and_b32_e32 v5, 0xffff0000, v5
	v_rcp_f32_e32 v61, v61
	s_nop 0
	v_mul_f32_e32 v61, v17, v61
	v_and_b32_e32 v4, 0xffff0000, v4
	v_mul_f32_e32 v10, 0xbfb8aa3b, v25
	v_exp_f32_e32 v57, v10
	v_rcp_f32_e32 v60, v60
	s_nop 0
	v_mul_f32_e32 v60, v21, v60
	v_mov_b32_e32 v10, v9
	v_pk_mul_f32 v[4:5], v[10:11], v[4:5]
	v_pk_add_f32 v[56:57], v[56:57], 1.0 op_sel_hi:[1,0]
	v_pk_mul_f32 v[62:63], v[64:65], v[62:63]
	v_pk_mul_f32 v[60:61], v[60:61], v[62:63]
	v_lshlrev_b32_e32 v63, 16, v7
	v_lshlrev_b32_e32 v62, 16, v6
	v_rcp_f32_e32 v9, v57
	s_nop 0
	v_mul_f32_e32 v9, v25, v9
	v_rcp_f32_e32 v8, v56
	s_nop 0
	v_mul_f32_e32 v8, v29, v8
	v_pk_mul_f32 v[4:5], v[8:9], v[4:5]
	v_lshlrev_b32_e32 v17, 16, v59
	v_lshlrev_b32_e32 v21, 16, v58
	v_cvt_pk_bf16_f32 v5, v61, v5
	v_cvt_pk_bf16_f32 v4, v60, v4
	v_mul_f32_e32 v8, 0xbfb8aa3b, v21
	v_mul_f32_e32 v9, 0xbfb8aa3b, v17
	v_exp_f32_e32 v8, v8
	v_exp_f32_e32 v9, v9
	v_and_b32_e32 v29, 0xffff0000, v58
	v_mul_f32_e32 v10, 0xbfb8aa3b, v29
	v_and_b32_e32 v25, 0xffff0000, v59
	v_exp_f32_e32 v60, v10
	v_pk_add_f32 v[64:65], v[8:9], 1.0 op_sel_hi:[1,0]
	global_load_dwordx4 v[8:11], v[18:19], off
	global_load_dwordx4 v[56:59], v[18:19], off offset:2048
	s_waitcnt lgkmcnt(0)
	v_mov_b32_e32 v18, v12
	v_mov_b32_e32 v19, v14
	v_pk_mul_f32 v[18:19], v[18:19], v[62:63]
	v_rcp_f32_e32 v63, v65
	s_nop 0
	v_mul_f32_e32 v63, v17, v63
	v_and_b32_e32 v7, 0xffff0000, v7
	v_mul_f32_e32 v14, 0xbfb8aa3b, v25
	v_exp_f32_e32 v61, v14
	v_rcp_f32_e32 v62, v64
	s_nop 0
	v_mul_f32_e32 v62, v21, v62
	v_mov_b32_e32 v14, v13
	v_and_b32_e32 v6, 0xffff0000, v6
	v_pk_add_f32 v[60:61], v[60:61], 1.0 op_sel_hi:[1,0]
	v_pk_mul_f32 v[6:7], v[14:15], v[6:7]
	v_pk_mul_f32 v[18:19], v[62:63], v[18:19]
	v_rcp_f32_e32 v13, v61
	s_nop 0
	v_mul_f32_e32 v13, v25, v13
	v_rcp_f32_e32 v12, v60
	s_nop 0
	v_mul_f32_e32 v12, v29, v12
	v_pk_mul_f32 v[6:7], v[12:13], v[6:7]
	v_cvt_pk_bf16_f32 v7, v19, v7
	v_cvt_pk_bf16_f32 v6, v18, v6
	s_waitcnt vmcnt(1)
	v_lshlrev_b32_e32 v63, 16, v9
	s_waitcnt vmcnt(0)
	v_lshlrev_b32_e32 v25, 16, v56
	v_mul_f32_e32 v12, 0xbfb8aa3b, v25
	v_and_b32_e32 v35, 0xffff0000, v56
	v_lshlrev_b32_e32 v21, 16, v57
	v_exp_f32_e32 v60, v12
	v_mul_f32_e32 v12, 0xbfb8aa3b, v35
	v_exp_f32_e32 v56, v12
	v_mul_f32_e32 v12, 0xbfb8aa3b, v21
	v_exp_f32_e32 v61, v12
	v_and_b32_e32 v29, 0xffff0000, v57
	ds_read_b128 v[12:15], v16
	ds_read_b128 v[16:19], v16 offset:16
	v_lshlrev_b32_e32 v62, 16, v8
	v_pk_add_f32 v[60:61], v[60:61], 1.0 op_sel_hi:[1,0]
	v_and_b32_e32 v9, 0xffff0000, v9
	s_waitcnt lgkmcnt(1)
	v_mov_b32_e32 v64, v12
	v_mov_b32_e32 v65, v14
	v_pk_mul_f32 v[62:63], v[64:65], v[62:63]
	v_rcp_f32_e32 v61, v61
	s_nop 0
	v_mul_f32_e32 v61, v21, v61
	v_and_b32_e32 v8, 0xffff0000, v8
	v_mul_f32_e32 v14, 0xbfb8aa3b, v29
	v_exp_f32_e32 v57, v14
	v_rcp_f32_e32 v60, v60
	s_nop 0
	v_mul_f32_e32 v60, v25, v60
	v_mov_b32_e32 v14, v13
	v_pk_mul_f32 v[8:9], v[14:15], v[8:9]
	v_pk_add_f32 v[56:57], v[56:57], 1.0 op_sel_hi:[1,0]
	v_pk_mul_f32 v[60:61], v[60:61], v[62:63]
	v_lshlrev_b32_e32 v63, 16, v11
	v_lshlrev_b32_e32 v62, 16, v10
	v_and_b32_e32 v11, 0xffff0000, v11
	v_rcp_f32_e32 v13, v57
	s_nop 0
	v_mul_f32_e32 v13, v29, v13
	v_rcp_f32_e32 v12, v56
	s_nop 0
	v_mul_f32_e32 v12, v35, v12
	v_pk_mul_f32 v[8:9], v[12:13], v[8:9]
	v_lshlrev_b32_e32 v21, 16, v59
	v_lshlrev_b32_e32 v25, 16, v58
	v_cvt_pk_bf16_f32 v9, v61, v9
	v_cvt_pk_bf16_f32 v8, v60, v8
	v_mul_f32_e32 v12, 0xbfb8aa3b, v25
	v_mul_f32_e32 v13, 0xbfb8aa3b, v21
	v_exp_f32_e32 v12, v12
	v_exp_f32_e32 v13, v13
	v_and_b32_e32 v35, 0xffff0000, v58
	v_mul_f32_e32 v14, 0xbfb8aa3b, v35
	v_and_b32_e32 v29, 0xffff0000, v59
	v_exp_f32_e32 v60, v14
	v_pk_add_f32 v[64:65], v[12:13], 1.0 op_sel_hi:[1,0]
	global_load_dwordx4 v[12:15], v[22:23], off
	global_load_dwordx4 v[56:59], v[22:23], off offset:2048
	s_waitcnt lgkmcnt(0)
	v_mov_b32_e32 v22, v16
	v_mov_b32_e32 v23, v18
	v_pk_mul_f32 v[22:23], v[22:23], v[62:63]
	v_rcp_f32_e32 v63, v65
	s_nop 0
	v_mul_f32_e32 v63, v21, v63
	v_and_b32_e32 v10, 0xffff0000, v10
	v_mul_f32_e32 v18, 0xbfb8aa3b, v29
	v_exp_f32_e32 v61, v18
	v_rcp_f32_e32 v62, v64
	s_nop 0
	v_mul_f32_e32 v62, v25, v62
	v_mov_b32_e32 v18, v17
	v_pk_mul_f32 v[10:11], v[18:19], v[10:11]
	v_pk_add_f32 v[60:61], v[60:61], 1.0 op_sel_hi:[1,0]
	v_pk_mul_f32 v[22:23], v[62:63], v[22:23]
	s_waitcnt vmcnt(1)
; __device__ __forceinline__ unsigned pack2(float a, float b) { return (unsigned)f2bf(a) | ((unsigned)f2bf(b) << 16); }
; __device__ __forceinline__ float bflo(unsigned w) { return __uint_as_float(w << 16); }
; __device__ __forceinline__ float bfhi(unsigned w) { return __uint_as_float(w & 0xffff0000u); }
; __device__ __forceinline__ float silu_f(float g) { return g / (1.f + __expf(-g)); }
; __device__ void gmlp_item(const Params& p, int layer, int b, int n, int g, char* smem) {
;     ...
;     for (int i = 0; i < 8; ++i) {
;       int q = tid + 256 * i, t = q >> 4, c = (q & 15) * 8;
;       float4 m0 = *reinterpret_cast<const float4*>(Tf + t * 132 + c);
;       float4 m1 = *reinterpret_cast<const float4*>(Tf + t * 132 + c + 4);
;       float mm[8] = {m0.x, m0.y, m0.z, m0.w, m1.x, m1.y, m1.z, m1.w};
;       unsigned uw[4] = {uu[i].x, uu[i].y, uu[i].z, uu[i].w};
;       unsigned gw[4] = {gt[i].x, gt[i].y, gt[i].z, gt[i].w};
;       unsigned ow[4];
; #pragma unroll
;       for (int e = 0; e < 4; ++e) {
;         float y0 = bflo(uw[e]) * mm[2 * e] * silu_f(bflo(gw[e]));
;         float y1 = bfhi(uw[e]) * mm[2 * e + 1] * silu_f(bfhi(gw[e]));
;         ow[e] = pack2(y0, y1);
;       }
;       *reinterpret_cast<uint4*>(Y + (t0 + t) * YW + g * 128 + c) = make_uint4(ow[0], ow[1], ow[2], ow[3]);
	v_lshlrev_b32_e32 v63, 16, v13
	v_rcp_f32_e32 v17, v61
	s_nop 0
	v_mul_f32_e32 v17, v29, v17
	v_rcp_f32_e32 v16, v60
	s_nop 0
	v_mul_f32_e32 v16, v35, v16
	v_pk_mul_f32 v[10:11], v[16:17], v[10:11]
	s_waitcnt vmcnt(0)
	v_lshlrev_b32_e32 v29, 16, v56
	v_cvt_pk_bf16_f32 v11, v23, v11
	v_mul_f32_e32 v16, 0xbfb8aa3b, v29
	v_and_b32_e32 v55, 0xffff0000, v56
	v_lshlrev_b32_e32 v25, 16, v57
	v_exp_f32_e32 v60, v16
	v_mul_f32_e32 v16, 0xbfb8aa3b, v55
	v_exp_f32_e32 v56, v16
	v_mul_f32_e32 v16, 0xbfb8aa3b, v25
	v_exp_f32_e32 v61, v16
	s_nop 0
	v_pk_add_f32 v[60:61], v[60:61], 1.0 op_sel_hi:[1,0]
	v_and_b32_e32 v35, 0xffff0000, v57
	v_cvt_pk_bf16_f32 v10, v22, v10
	ds_read_b128 v[16:19], v20
	ds_read_b128 v[20:23], v20 offset:16
	v_lshlrev_b32_e32 v62, 16, v12
	v_and_b32_e32 v13, 0xffff0000, v13
	s_waitcnt lgkmcnt(1)
	v_mov_b32_e32 v64, v16
	v_mov_b32_e32 v65, v18
	v_pk_mul_f32 v[62:63], v[64:65], v[62:63]
	v_rcp_f32_e32 v61, v61
	s_nop 0
	v_mul_f32_e32 v61, v25, v61
	v_and_b32_e32 v12, 0xffff0000, v12
	v_mul_f32_e32 v18, 0xbfb8aa3b, v35
	v_exp_f32_e32 v57, v18
	v_rcp_f32_e32 v60, v60
	s_nop 0
	v_mul_f32_e32 v60, v29, v60
	v_mov_b32_e32 v18, v17
	v_pk_mul_f32 v[12:13], v[18:19], v[12:13]
	v_pk_add_f32 v[56:57], v[56:57], 1.0 op_sel_hi:[1,0]
	v_pk_mul_f32 v[60:61], v[60:61], v[62:63]
	v_lshlrev_b32_e32 v63, 16, v15
	v_lshlrev_b32_e32 v62, 16, v14
	v_and_b32_e32 v15, 0xffff0000, v15
	v_rcp_f32_e32 v17, v57
	s_nop 0
	v_mul_f32_e32 v17, v35, v17
	v_rcp_f32_e32 v16, v56
	s_nop 0
	v_mul_f32_e32 v16, v55, v16
	v_pk_mul_f32 v[12:13], v[16:17], v[12:13]
	v_lshlrev_b32_e32 v25, 16, v59
	v_lshlrev_b32_e32 v29, 16, v58
	v_cvt_pk_bf16_f32 v13, v61, v13
	v_cvt_pk_bf16_f32 v12, v60, v12
	v_mul_f32_e32 v16, 0xbfb8aa3b, v29
	v_mul_f32_e32 v17, 0xbfb8aa3b, v25
	v_exp_f32_e32 v16, v16
	v_exp_f32_e32 v17, v17
	v_and_b32_e32 v55, 0xffff0000, v58
	v_mul_f32_e32 v18, 0xbfb8aa3b, v55
	v_and_b32_e32 v35, 0xffff0000, v59
	v_exp_f32_e32 v60, v18
	v_pk_add_f32 v[64:65], v[16:17], 1.0 op_sel_hi:[1,0]
	global_load_dwordx4 v[16:19], v[26:27], off
	global_load_dwordx4 v[56:59], v[26:27], off offset:2048
	s_waitcnt lgkmcnt(0)
	v_mov_b32_e32 v26, v20
	v_mov_b32_e32 v27, v22
	v_pk_mul_f32 v[26:27], v[26:27], v[62:63]
	v_rcp_f32_e32 v63, v65
	s_nop 0
	v_mul_f32_e32 v63, v25, v63
	v_and_b32_e32 v14, 0xffff0000, v14
	v_mul_f32_e32 v22, 0xbfb8aa3b, v35
	v_exp_f32_e32 v61, v22
	v_rcp_f32_e32 v62, v64
	s_nop 0
	v_mul_f32_e32 v62, v29, v62
	v_mov_b32_e32 v22, v21
	v_pk_mul_f32 v[14:15], v[22:23], v[14:15]
	v_pk_add_f32 v[60:61], v[60:61], 1.0 op_sel_hi:[1,0]
	v_pk_mul_f32 v[26:27], v[62:63], v[26:27]
	s_waitcnt vmcnt(1)
	v_lshlrev_b32_e32 v63, 16, v17
	v_rcp_f32_e32 v21, v61
	s_nop 0
	v_mul_f32_e32 v21, v35, v21
	v_rcp_f32_e32 v20, v60
	s_nop 0
	v_mul_f32_e32 v20, v55, v20
	v_pk_mul_f32 v[14:15], v[20:21], v[14:15]
	s_waitcnt vmcnt(0)
	v_lshlrev_b32_e32 v35, 16, v56
	v_cvt_pk_bf16_f32 v15, v27, v15
	v_mul_f32_e32 v20, 0xbfb8aa3b, v35
	v_and_b32_e32 v66, 0xffff0000, v56
	v_lshlrev_b32_e32 v29, 16, v57
	v_exp_f32_e32 v60, v20
	v_mul_f32_e32 v20, 0xbfb8aa3b, v66
	v_exp_f32_e32 v56, v20
	v_mul_f32_e32 v20, 0xbfb8aa3b, v29
	v_exp_f32_e32 v61, v20
	s_nop 0
	v_pk_add_f32 v[60:61], v[60:61], 1.0 op_sel_hi:[1,0]
	v_and_b32_e32 v55, 0xffff0000, v57
	v_cvt_pk_bf16_f32 v14, v26, v14
	ds_read_b128 v[20:23], v24
	ds_read_b128 v[24:27], v24 offset:16
	v_lshlrev_b32_e32 v62, 16, v16
	v_and_b32_e32 v17, 0xffff0000, v17
	s_waitcnt lgkmcnt(1)
	v_mov_b32_e32 v64, v20
	v_mov_b32_e32 v65, v22
	v_pk_mul_f32 v[62:63], v[64:65], v[62:63]
	v_rcp_f32_e32 v61, v61
	s_nop 0
	v_mul_f32_e32 v61, v29, v61
	v_and_b32_e32 v16, 0xffff0000, v16
	v_mul_f32_e32 v22, 0xbfb8aa3b, v55
	v_exp_f32_e32 v57, v22
	v_rcp_f32_e32 v60, v60
	s_nop 0
	v_mul_f32_e32 v60, v35, v60
	v_mov_b32_e32 v22, v21
	v_pk_mul_f32 v[16:17], v[22:23], v[16:17]
	v_pk_add_f32 v[56:57], v[56:57], 1.0 op_sel_hi:[1,0]
	v_pk_mul_f32 v[60:61], v[60:61], v[62:63]
	v_lshlrev_b32_e32 v63, 16, v19
	v_lshlrev_b32_e32 v62, 16, v18
	v_and_b32_e32 v19, 0xffff0000, v19
	v_rcp_f32_e32 v21, v57
	s_nop 0
	v_mul_f32_e32 v21, v55, v21
	v_rcp_f32_e32 v20, v56
	s_nop 0
	v_mul_f32_e32 v20, v66, v20
	v_pk_mul_f32 v[16:17], v[20:21], v[16:17]
	v_lshlrev_b32_e32 v29, 16, v59
	v_lshlrev_b32_e32 v35, 16, v58
	v_cvt_pk_bf16_f32 v17, v61, v17
	v_cvt_pk_bf16_f32 v16, v60, v16
	v_mul_f32_e32 v20, 0xbfb8aa3b, v35
	v_mul_f32_e32 v21, 0xbfb8aa3b, v29
	v_exp_f32_e32 v20, v20
	v_exp_f32_e32 v21, v21
	v_and_b32_e32 v66, 0xffff0000, v58
	v_mul_f32_e32 v22, 0xbfb8aa3b, v66
	v_and_b32_e32 v55, 0xffff0000, v59
	v_exp_f32_e32 v60, v22
	v_pk_add_f32 v[64:65], v[20:21], 1.0 op_sel_hi:[1,0]
	global_load_dwordx4 v[20:23], v[30:31], off
	global_load_dwordx4 v[56:59], v[30:31], off offset:2048
	s_waitcnt lgkmcnt(0)
	v_mov_b32_e32 v30, v24
	v_mov_b32_e32 v31, v26
	v_pk_mul_f32 v[30:31], v[30:31], v[62:63]
	v_rcp_f32_e32 v63, v65
	s_nop 0
	v_mul_f32_e32 v63, v29, v63
	v_and_b32_e32 v18, 0xffff0000, v18
	v_mul_f32_e32 v26, 0xbfb8aa3b, v55
	v_exp_f32_e32 v61, v26
	v_rcp_f32_e32 v62, v64
	s_nop 0
	v_mul_f32_e32 v62, v35, v62
	v_mov_b32_e32 v26, v25
	v_pk_mul_f32 v[18:19], v[26:27], v[18:19]
	v_pk_add_f32 v[60:61], v[60:61], 1.0 op_sel_hi:[1,0]
	v_pk_mul_f32 v[30:31], v[62:63], v[30:31]
	s_waitcnt vmcnt(1)
	v_lshlrev_b32_e32 v63, 16, v21
	v_rcp_f32_e32 v25, v61
	s_nop 0
	v_mul_f32_e32 v25, v55, v25
	v_rcp_f32_e32 v24, v60
	s_nop 0
	v_mul_f32_e32 v24, v66, v24
	v_pk_mul_f32 v[18:19], v[24:25], v[18:19]
	s_waitcnt vmcnt(0)
; __device__ __forceinline__ unsigned pack2(float a, float b) { return (unsigned)f2bf(a) | ((unsigned)f2bf(b) << 16); }
; __device__ __forceinline__ float bflo(unsigned w) { return __uint_as_float(w << 16); }
; __device__ __forceinline__ float bfhi(unsigned w) { return __uint_as_float(w & 0xffff0000u); }
; __device__ __forceinline__ float silu_f(float g) { return g / (1.f + __expf(-g)); }
; __device__ void gmlp_item(const Params& p, int layer, int b, int n, int g, char* smem) {
;     ...
;     for (int i = 0; i < 8; ++i) {
;       int q = tid + 256 * i, t = q >> 4, c = (q & 15) * 8;
;       float4 m0 = *reinterpret_cast<const float4*>(Tf + t * 132 + c);
;       float4 m1 = *reinterpret_cast<const float4*>(Tf + t * 132 + c + 4);
;       float mm[8] = {m0.x, m0.y, m0.z, m0.w, m1.x, m1.y, m1.z, m1.w};
;       unsigned uw[4] = {uu[i].x, uu[i].y, uu[i].z, uu[i].w};
;       unsigned gw[4] = {gt[i].x, gt[i].y, gt[i].z, gt[i].w};
;       unsigned ow[4];
; #pragma unroll
;       for (int e = 0; e < 4; ++e) {
;         float y0 = bflo(uw[e]) * mm[2 * e] * silu_f(bflo(gw[e]));
;         float y1 = bfhi(uw[e]) * mm[2 * e + 1] * silu_f(bfhi(gw[e]));
;         ow[e] = pack2(y0, y1);
;       }
;       *reinterpret_cast<uint4*>(Y + (t0 + t) * YW + g * 128 + c) = make_uint4(ow[0], ow[1], ow[2], ow[3]);
	v_lshlrev_b32_e32 v55, 16, v56
	v_cvt_pk_bf16_f32 v19, v31, v19
	v_mul_f32_e32 v24, 0xbfb8aa3b, v55
	v_and_b32_e32 v67, 0xffff0000, v56
	v_lshlrev_b32_e32 v35, 16, v57
	v_exp_f32_e32 v60, v24
	v_mul_f32_e32 v24, 0xbfb8aa3b, v67
	v_exp_f32_e32 v56, v24
	v_mul_f32_e32 v24, 0xbfb8aa3b, v35
	v_exp_f32_e32 v61, v24
	s_nop 0
	v_pk_add_f32 v[60:61], v[60:61], 1.0 op_sel_hi:[1,0]
	v_and_b32_e32 v66, 0xffff0000, v57
	v_cvt_pk_bf16_f32 v18, v30, v18
	ds_read_b128 v[24:27], v28
	ds_read_b128 v[28:31], v28 offset:16
	v_lshlrev_b32_e32 v62, 16, v20
	v_and_b32_e32 v21, 0xffff0000, v21
	s_waitcnt lgkmcnt(1)
	v_mov_b32_e32 v64, v24
	v_mov_b32_e32 v65, v26
	v_pk_mul_f32 v[62:63], v[64:65], v[62:63]
	v_rcp_f32_e32 v61, v61
	s_nop 0
	v_mul_f32_e32 v61, v35, v61
	v_and_b32_e32 v20, 0xffff0000, v20
	v_mul_f32_e32 v26, 0xbfb8aa3b, v66
	v_exp_f32_e32 v57, v26
	v_rcp_f32_e32 v60, v60
	s_nop 0
	v_mul_f32_e32 v60, v55, v60
	v_mov_b32_e32 v26, v25
	v_pk_mul_f32 v[20:21], v[26:27], v[20:21]
	v_pk_add_f32 v[56:57], v[56:57], 1.0 op_sel_hi:[1,0]
	v_pk_mul_f32 v[60:61], v[60:61], v[62:63]
	v_lshlrev_b32_e32 v63, 16, v23
	v_lshlrev_b32_e32 v62, 16, v22
	v_and_b32_e32 v23, 0xffff0000, v23
	v_rcp_f32_e32 v25, v57
	s_nop 0
	v_mul_f32_e32 v25, v66, v25
	v_rcp_f32_e32 v24, v56
	s_nop 0
	v_mul_f32_e32 v24, v67, v24
	v_pk_mul_f32 v[20:21], v[24:25], v[20:21]
	v_lshlrev_b32_e32 v35, 16, v59
	v_lshlrev_b32_e32 v55, 16, v58
	v_cvt_pk_bf16_f32 v21, v61, v21
	v_cvt_pk_bf16_f32 v20, v60, v20
	v_mul_f32_e32 v24, 0xbfb8aa3b, v55
	v_mul_f32_e32 v25, 0xbfb8aa3b, v35
	v_exp_f32_e32 v24, v24
	v_exp_f32_e32 v25, v25
	v_and_b32_e32 v67, 0xffff0000, v58
	v_mul_f32_e32 v26, 0xbfb8aa3b, v67
	v_and_b32_e32 v66, 0xffff0000, v59
	v_exp_f32_e32 v60, v26
	v_pk_add_f32 v[64:65], v[24:25], 1.0 op_sel_hi:[1,0]
	global_load_dwordx4 v[24:27], v[32:33], off
	global_load_dwordx4 v[56:59], v[32:33], off offset:2048
	s_waitcnt lgkmcnt(0)
	v_mov_b32_e32 v32, v28
	v_mov_b32_e32 v33, v30
	v_pk_mul_f32 v[32:33], v[32:33], v[62:63]
	v_rcp_f32_e32 v63, v65
	s_nop 0
	v_mul_f32_e32 v63, v35, v63
	v_and_b32_e32 v22, 0xffff0000, v22
	v_mul_f32_e32 v30, 0xbfb8aa3b, v66
	v_exp_f32_e32 v61, v30
	v_rcp_f32_e32 v62, v64
	s_nop 0
	v_mul_f32_e32 v62, v55, v62
	v_mov_b32_e32 v30, v29
	v_pk_mul_f32 v[22:23], v[30:31], v[22:23]
	v_pk_add_f32 v[60:61], v[60:61], 1.0 op_sel_hi:[1,0]
	v_pk_mul_f32 v[32:33], v[62:63], v[32:33]
	s_waitcnt vmcnt(1)
	v_lshlrev_b32_e32 v63, 16, v25
	v_rcp_f32_e32 v29, v61
	s_nop 0
	v_mul_f32_e32 v29, v66, v29
	v_rcp_f32_e32 v28, v60
	s_nop 0
	v_mul_f32_e32 v28, v67, v28
	v_pk_mul_f32 v[22:23], v[28:29], v[22:23]
	s_waitcnt vmcnt(0)
	v_lshlrev_b32_e32 v66, 16, v56
	v_cvt_pk_bf16_f32 v23, v33, v23
	v_mul_f32_e32 v28, 0xbfb8aa3b, v66
	v_and_b32_e32 v68, 0xffff0000, v56
	v_lshlrev_b32_e32 v55, 16, v57
	v_exp_f32_e32 v60, v28
	v_mul_f32_e32 v28, 0xbfb8aa3b, v68
	v_exp_f32_e32 v56, v28
	v_mul_f32_e32 v28, 0xbfb8aa3b, v55
	v_exp_f32_e32 v61, v28
	s_nop 0
	v_pk_add_f32 v[60:61], v[60:61], 1.0 op_sel_hi:[1,0]
	v_and_b32_e32 v67, 0xffff0000, v57
	v_cvt_pk_bf16_f32 v22, v32, v22
	ds_read_b128 v[28:31], v34
	ds_read_b128 v[32:35], v34 offset:16
	v_lshlrev_b32_e32 v62, 16, v24
	v_and_b32_e32 v25, 0xffff0000, v25
	s_waitcnt lgkmcnt(1)
	v_mov_b32_e32 v64, v28
	v_mov_b32_e32 v65, v30
	v_pk_mul_f32 v[62:63], v[64:65], v[62:63]
	v_rcp_f32_e32 v61, v61
	s_nop 0
	v_mul_f32_e32 v61, v55, v61
	v_and_b32_e32 v24, 0xffff0000, v24
	v_mul_f32_e32 v30, 0xbfb8aa3b, v67
	v_exp_f32_e32 v57, v30
	v_rcp_f32_e32 v60, v60
	s_nop 0
	v_mul_f32_e32 v60, v66, v60
	v_mov_b32_e32 v30, v29
	v_pk_mul_f32 v[24:25], v[30:31], v[24:25]
	v_pk_add_f32 v[56:57], v[56:57], 1.0 op_sel_hi:[1,0]
	v_pk_mul_f32 v[60:61], v[60:61], v[62:63]
	v_lshlrev_b32_e32 v66, 16, v58
	v_lshlrev_b32_e32 v63, 16, v27
	v_and_b32_e32 v27, 0xffff0000, v27
	v_rcp_f32_e32 v29, v57
	s_nop 0
	v_mul_f32_e32 v29, v67, v29
	v_rcp_f32_e32 v28, v56
	s_nop 0
	v_mul_f32_e32 v28, v68, v28
	v_pk_mul_f32 v[24:25], v[28:29], v[24:25]
	v_lshlrev_b32_e32 v55, 16, v59
	v_cvt_pk_bf16_f32 v25, v61, v25
	v_cvt_pk_bf16_f32 v24, v60, v24
	v_mul_f32_e32 v28, 0xbfb8aa3b, v66
	v_mul_f32_e32 v29, 0xbfb8aa3b, v55
	v_exp_f32_e32 v28, v28
	v_exp_f32_e32 v29, v29
	v_and_b32_e32 v68, 0xffff0000, v58
	v_mul_f32_e32 v30, 0xbfb8aa3b, v68
	v_and_b32_e32 v67, 0xffff0000, v59
	v_exp_f32_e32 v60, v30
	v_pk_add_f32 v[64:65], v[28:29], 1.0 op_sel_hi:[1,0]
	global_load_dwordx4 v[28:31], v[52:53], off
	global_load_dwordx4 v[56:59], v[52:53], off offset:2048
	s_waitcnt lgkmcnt(0)
; __device__ __forceinline__ unsigned pack2(float a, float b) { return (unsigned)f2bf(a) | ((unsigned)f2bf(b) << 16); }
; __device__ __forceinline__ float bflo(unsigned w) { return __uint_as_float(w << 16); }
; __device__ __forceinline__ float bfhi(unsigned w) { return __uint_as_float(w & 0xffff0000u); }
; __device__ __forceinline__ float silu_f(float g) { return g / (1.f + __expf(-g)); }
; __device__ void gmlp_item(const Params& p, int layer, int b, int n, int g, char* smem) {
;     ...
;     for (int i = 0; i < 8; ++i) {
;       int q = tid + 256 * i, t = q >> 4, c = (q & 15) * 8;
;       float4 m0 = *reinterpret_cast<const float4*>(Tf + t * 132 + c);
;       float4 m1 = *reinterpret_cast<const float4*>(Tf + t * 132 + c + 4);
;       float mm[8] = {m0.x, m0.y, m0.z, m0.w, m1.x, m1.y, m1.z, m1.w};
;       unsigned uw[4] = {uu[i].x, uu[i].y, uu[i].z, uu[i].w};
;       unsigned gw[4] = {gt[i].x, gt[i].y, gt[i].z, gt[i].w};
;       unsigned ow[4];
; #pragma unroll
;       for (int e = 0; e < 4; ++e) {
;         float y0 = bflo(uw[e]) * mm[2 * e] * silu_f(bflo(gw[e]));
;         float y1 = bfhi(uw[e]) * mm[2 * e + 1] * silu_f(bfhi(gw[e]));
;         ow[e] = pack2(y0, y1);
;       }
;       *reinterpret_cast<uint4*>(Y + (t0 + t) * YW + g * 128 + c) = make_uint4(ow[0], ow[1], ow[2], ow[3]);
;     }
;   }
;   __syncthreads();
	v_mov_b32_e32 v52, v32
	v_lshlrev_b32_e32 v62, 16, v26
	v_mov_b32_e32 v53, v34
	v_pk_mul_f32 v[52:53], v[52:53], v[62:63]
	v_rcp_f32_e32 v63, v65
	s_nop 0
	v_mul_f32_e32 v63, v55, v63
	v_and_b32_e32 v26, 0xffff0000, v26
	v_mul_f32_e32 v34, 0xbfb8aa3b, v67
	v_exp_f32_e32 v61, v34
	v_rcp_f32_e32 v62, v64
	s_nop 0
	v_mul_f32_e32 v62, v66, v62
	v_mov_b32_e32 v34, v33
	v_pk_mul_f32 v[26:27], v[34:35], v[26:27]
	v_pk_add_f32 v[60:61], v[60:61], 1.0 op_sel_hi:[1,0]
	v_pk_mul_f32 v[52:53], v[62:63], v[52:53]
	s_waitcnt vmcnt(1)
	v_lshlrev_b32_e32 v63, 16, v29
	v_rcp_f32_e32 v33, v61
	s_nop 0
	v_mul_f32_e32 v33, v67, v33
	v_rcp_f32_e32 v32, v60
	s_nop 0
	v_mul_f32_e32 v32, v68, v32
	v_pk_mul_f32 v[26:27], v[32:33], v[26:27]
	s_waitcnt vmcnt(0)
	v_lshlrev_b32_e32 v67, 16, v56
	v_cvt_pk_bf16_f32 v27, v53, v27
	v_mul_f32_e32 v32, 0xbfb8aa3b, v67
	v_and_b32_e32 v69, 0xffff0000, v56
	v_lshlrev_b32_e32 v66, 16, v57
	v_exp_f32_e32 v60, v32
	v_mul_f32_e32 v32, 0xbfb8aa3b, v69
	v_exp_f32_e32 v56, v32
	v_mul_f32_e32 v32, 0xbfb8aa3b, v66
	v_exp_f32_e32 v61, v32
	s_nop 0
	v_pk_add_f32 v[60:61], v[60:61], 1.0 op_sel_hi:[1,0]
	v_and_b32_e32 v68, 0xffff0000, v57
	v_cvt_pk_bf16_f32 v26, v52, v26
	ds_read_b128 v[32:35], v54
	ds_read_b128 v[52:55], v54 offset:16
	v_lshlrev_b32_e32 v62, 16, v28
	v_and_b32_e32 v29, 0xffff0000, v29
	s_waitcnt lgkmcnt(1)
	v_mov_b32_e32 v64, v32
	v_mov_b32_e32 v65, v34
	v_pk_mul_f32 v[62:63], v[64:65], v[62:63]
	v_rcp_f32_e32 v61, v61
	s_nop 0
	v_mul_f32_e32 v61, v66, v61
	v_and_b32_e32 v28, 0xffff0000, v28
	v_mul_f32_e32 v34, 0xbfb8aa3b, v68
	v_exp_f32_e32 v57, v34
	v_rcp_f32_e32 v60, v60
	s_nop 0
	v_mul_f32_e32 v60, v67, v60
	v_pk_mul_f32 v[60:61], v[60:61], v[62:63]
	v_mov_b32_e32 v34, v33
	v_pk_add_f32 v[56:57], v[56:57], 1.0 op_sel_hi:[1,0]
	v_pk_mul_f32 v[28:29], v[34:35], v[28:29]
	s_nop 0
	v_rcp_f32_e32 v33, v57
	s_nop 0
	v_mul_f32_e32 v33, v68, v33
	v_rcp_f32_e32 v32, v56
	s_nop 0
	v_mul_f32_e32 v32, v69, v32
	v_pk_mul_f32 v[28:29], v[32:33], v[28:29]
	v_cvt_pk_bf16_f32 v28, 0, v28
	v_cvt_pk_bf16_f32 v33, 0, v60
	v_and_b32_e32 v28, 0xffff0000, v28
	v_lshlrev_b32_e32 v35, 16, v59
	v_lshlrev_b32_e32 v60, 16, v58
	v_cvt_pk_bf16_f32 v29, v61, v29
	v_or_b32_sdwa v28, v28, v33 dst_sel:DWORD dst_unused:UNUSED_PAD src0_sel:DWORD src1_sel:WORD_1
	v_mul_f32_e32 v32, 0xbfb8aa3b, v60
	v_mul_f32_e32 v33, 0xbfb8aa3b, v35
	v_exp_f32_e32 v32, v32
	v_exp_f32_e32 v33, v33
	v_and_b32_e32 v62, 0xffff0000, v58
	s_waitcnt lgkmcnt(0)
	v_mov_b32_e32 v58, v52
	v_and_b32_e32 v61, 0xffff0000, v59
	v_pk_add_f32 v[32:33], v[32:33], 1.0 op_sel_hi:[1,0]
	v_lshlrev_b32_e32 v57, 16, v31
	v_lshlrev_b32_e32 v56, 16, v30
	v_mov_b32_e32 v59, v54
	v_pk_mul_f32 v[56:57], v[58:59], v[56:57]
	v_rcp_f32_e32 v33, v33
	s_nop 0
	v_mul_f32_e32 v33, v35, v33
	v_mul_f32_e32 v34, 0xbfb8aa3b, v62
	v_mul_f32_e32 v35, 0xbfb8aa3b, v61
	v_exp_f32_e32 v34, v34
	v_exp_f32_e32 v35, v35
	v_rcp_f32_e32 v32, v32
	s_nop 0
	v_mul_f32_e32 v32, v60, v32
	v_pk_mul_f32 v[32:33], v[32:33], v[56:57]
	v_mov_b32_e32 v54, v53
	v_pk_add_f32 v[34:35], v[34:35], 1.0 op_sel_hi:[1,0]
	v_and_b32_e32 v31, 0xffff0000, v31
	v_and_b32_e32 v30, 0xffff0000, v30
	v_pk_mul_f32 v[30:31], v[54:55], v[30:31]
	v_rcp_f32_e32 v35, v35
	s_nop 0
	v_mul_f32_e32 v35, v61, v35
	s_mov_b64 s[12:13], 0
	v_rcp_f32_e32 v34, v34
	s_nop 0
	v_mul_f32_e32 v34, v62, v34
	v_pk_mul_f32 v[30:31], v[34:35], v[30:31]
	v_cvt_pk_bf16_f32 v31, v33, v31
	v_cvt_pk_bf16_f32 v30, v32, v30
	global_store_dwordx4 v[50:51], v[28:31], off
	global_store_dwordx4 v[48:49], v[24:27], off
	global_store_dwordx4 v[46:47], v[20:23], off
	global_store_dwordx4 v[44:45], v[16:19], off
	global_store_dwordx4 v[42:43], v[12:15], off
	global_store_dwordx4 v[40:41], v[8:11], off
	global_store_dwordx4 v[38:39], v[4:7], off
	global_store_dwordx4 v[36:37], v[0:3], off
	s_barrier

; __device__ __forceinline__ unsigned pack2(float a, float b) { return (unsigned)f2bf(a) | ((unsigned)f2bf(b) << 16); }
; template <int DH, int MODE>
; __device__ void attn_item(const Params& p, int layer, int b, int blk, int head, char* smem) {
;     ...
; #pragma unroll 2
;         for (int s8 = 0; s8 < 4; ++s8) {
;           float4 va = s4[2 * s8], vb = s4[2 * s8 + 1];
;           float e[8] = {va.x, va.y, va.z, va.w, vb.x, vb.y, vb.z, vb.w};
;           float pv[8];
; #pragma unroll
;           for (int k = 0; k < 8; ++k) {
;             int kj = kjb + s8 * 8 + k;
;             bool valid = (kj > row) && (kj <= row + 128);
;             float pe = valid ? __builtin_amdgcn_exp2f(e[k] - m_new) : 0.f;
;             pv[k] = pe;
;             psum += pe;
;           }
;           uint4 ov;
;           ov.x = pack2(pv[0], pv[1]); ov.y = pack2(pv[2], pv[3]);
;           ov.z = pack2(pv[4], pv[5]); ov.w = pack2(pv[6], pv[7]);
;           *reinterpret_cast<uint4*>(prow + s8 * 16) = ov;
;         }
;         psum += __shfl_xor(psum, 1);
;         l_run = l_run * alpha + psum;
;         m_run = m_new;
;         if (half == 0) alpha_s[row] = alpha;
.LBB0_505:
	ds_read_b128 v[104:107], v102
	ds_read_b128 v[108:111], v102 offset:16
	v_add_u32_e32 v112, s90, v92
	v_add_u32_e32 v113, 2, v112
	v_cmp_gt_i32_e64 s[14:15], v112, v74
	s_waitcnt lgkmcnt(1)
	v_sub_f32_e32 v104, v104, v82
	v_exp_f32_e32 v104, v104
	v_sub_f32_e32 v106, v106, v82
	v_sub_f32_e32 v105, v105, v82
	v_exp_f32_e32 v106, v106
	v_exp_f32_e32 v105, v105
	v_sub_f32_e32 v107, v107, v82
	v_cmp_le_i32_e64 s[20:21], v112, v80
	v_exp_f32_e32 v107, v107
	v_cmp_gt_i32_e32 vcc, v113, v65
	v_cmp_le_i32_e64 s[16:17], v113, v69
	s_and_b64 s[14:15], s[14:15], s[20:21]
	v_add_u32_e32 v114, 3, v112
	s_and_b64 vcc, vcc, s[16:17]
	v_cndmask_b32_e64 v104, 0, v104, s[14:15]
	v_cmp_lt_i32_e64 s[14:15], v112, v80
	v_cmp_ge_i32_e64 s[20:21], v112, v74
	v_cndmask_b32_e32 v106, 0, v106, vcc
	v_cmp_lt_i32_e32 vcc, v74, v114
	v_cmp_ge_i32_e64 s[16:17], v80, v114
	s_and_b64 s[14:15], s[14:15], s[20:21]
	v_add_f32_e32 v103, v103, v104
	s_and_b64 vcc, vcc, s[16:17]
	v_cndmask_b32_e64 v105, 0, v105, s[14:15]
	v_cndmask_b32_e32 v107, 0, v107, vcc
	v_add_f32_e32 v103, v103, v105
	v_add_f32_e32 v103, v103, v106
	s_waitcnt lgkmcnt(0)
	v_sub_f32_e32 v108, v108, v82
	v_sub_f32_e32 v110, v110, v82
	v_add_f32_e32 v103, v103, v107
	v_cvt_pk_bf16_f32 v104, 0, v104
	v_exp_f32_e32 v108, v108
	v_exp_f32_e32 v110, v110
	v_cvt_pk_bf16_f32 v105, 0, v105
	v_sub_f32_e32 v109, v109, v82
	v_sub_f32_e32 v111, v111, v82
	v_and_b32_e32 v113, 0xffff0000, v105
	v_cvt_pk_bf16_f32 v105, v106, v107
	v_or_b32_e32 v106, 6, v112
	v_or_b32_e32 v107, 4, v112
	v_exp_f32_e32 v109, v109
	v_exp_f32_e32 v111, v111
	v_cmp_gt_i32_e32 vcc, v107, v74
	v_cmp_gt_i32_e64 s[14:15], v106, v65
	v_cmp_le_i32_e64 s[16:17], v107, v80
	v_cmp_le_i32_e64 s[20:21], v106, v69
	s_and_b64 s[14:15], s[14:15], s[20:21]
	s_and_b64 vcc, vcc, s[16:17]
	v_or_b32_e32 v106, 7, v112
	v_or_b32_e32 v107, 5, v112
	v_cndmask_b32_e32 v108, 0, v108, vcc
	v_cndmask_b32_e64 v110, 0, v110, s[14:15]
	v_cmp_gt_i32_e32 vcc, v107, v74
	v_cmp_gt_i32_e64 s[14:15], v106, v65
	v_cmp_le_i32_e64 s[16:17], v107, v80
	v_cmp_le_i32_e64 s[20:21], v106, v69
	s_and_b64 s[14:15], s[14:15], s[20:21]
	s_and_b64 vcc, vcc, s[16:17]
	v_cndmask_b32_e32 v109, 0, v109, vcc
	v_cndmask_b32_e64 v111, 0, v111, s[14:15]
	v_or_b32_sdwa v104, v113, v104 dst_sel:DWORD dst_unused:UNUSED_PAD src0_sel:DWORD src1_sel:WORD_1
	v_add_f32_e32 v103, v103, v108
	v_cvt_pk_bf16_f32 v107, v110, v111
	v_cvt_pk_bf16_f32 v106, v108, v109
	v_add_f32_e32 v103, v103, v109
	v_add_f32_e32 v103, v103, v110
	ds_write_b128 v101, v[104:107]
	v_add_f32_e32 v103, v103, v111
	ds_read_b128 v[104:107], v102 offset:32
	ds_read_b128 v[108:111], v102 offset:48
	v_add_u32_e32 v113, 8, v112
	v_add_u32_e32 v114, 10, v112
	v_cmp_gt_i32_e64 s[14:15], v113, v74
	s_waitcnt lgkmcnt(1)
	v_sub_f32_e32 v104, v104, v82
	v_exp_f32_e32 v104, v104
	v_sub_f32_e32 v106, v106, v82
	v_sub_f32_e32 v105, v105, v82
	v_exp_f32_e32 v106, v106
	v_exp_f32_e32 v105, v105
	v_sub_f32_e32 v107, v107, v82
	v_cmp_le_i32_e64 s[20:21], v113, v80
	v_exp_f32_e32 v107, v107
	v_cmp_gt_i32_e32 vcc, v114, v65
	v_cmp_le_i32_e64 s[16:17], v114, v69
	s_and_b64 s[14:15], s[14:15], s[20:21]
	v_add_u32_e32 v112, 11, v112
	s_and_b64 vcc, vcc, s[16:17]
	v_cndmask_b32_e64 v104, 0, v104, s[14:15]
	v_cmp_lt_i32_e64 s[14:15], v113, v80
	v_cmp_ge_i32_e64 s[20:21], v113, v74
	v_cndmask_b32_e32 v106, 0, v106, vcc
	v_cmp_lt_i32_e32 vcc, v74, v112
	v_cmp_ge_i32_e64 s[16:17], v80, v112
	s_and_b64 s[14:15], s[14:15], s[20:21]
	v_add_f32_e32 v103, v103, v104
	s_and_b64 vcc, vcc, s[16:17]
	v_cndmask_b32_e64 v105, 0, v105, s[14:15]
	v_cndmask_b32_e32 v107, 0, v107, vcc
	v_add_f32_e32 v103, v103, v105
	v_add_f32_e32 v103, v103, v106
	s_waitcnt lgkmcnt(0)
	v_sub_f32_e32 v108, v108, v82
	v_sub_f32_e32 v110, v110, v82
	v_add_f32_e32 v103, v103, v107
	v_cvt_pk_bf16_f32 v104, 0, v104
	v_exp_f32_e32 v108, v108
	v_exp_f32_e32 v110, v110
	v_cvt_pk_bf16_f32 v105, 0, v105
	v_sub_f32_e32 v109, v109, v82
	v_sub_f32_e32 v111, v111, v82
	v_and_b32_e32 v112, 0xffff0000, v105
	v_cvt_pk_bf16_f32 v105, v106, v107
	v_or_b32_e32 v106, 6, v113
	v_or_b32_e32 v107, 4, v113
	v_exp_f32_e32 v109, v109
	v_exp_f32_e32 v111, v111
	v_cmp_gt_i32_e32 vcc, v107, v74
	v_cmp_gt_i32_e64 s[14:15], v106, v65
	v_cmp_le_i32_e64 s[16:17], v107, v80
	v_cmp_le_i32_e64 s[20:21], v106, v69
	s_and_b64 s[14:15], s[14:15], s[20:21]
	s_and_b64 vcc, vcc, s[16:17]
	v_or_b32_e32 v106, 7, v113
	v_or_b32_e32 v107, 5, v113
	v_cndmask_b32_e32 v108, 0, v108, vcc
	v_cndmask_b32_e64 v110, 0, v110, s[14:15]
	v_cmp_gt_i32_e32 vcc, v107, v74
	v_cmp_gt_i32_e64 s[14:15], v106, v65
	v_cmp_le_i32_e64 s[16:17], v107, v80
	v_cmp_le_i32_e64 s[20:21], v106, v69
	s_and_b64 s[14:15], s[14:15], s[20:21]
	s_and_b64 vcc, vcc, s[16:17]
	v_cndmask_b32_e32 v109, 0, v109, vcc
	v_cndmask_b32_e64 v111, 0, v111, s[14:15]
	v_or_b32_sdwa v104, v112, v104 dst_sel:DWORD dst_unused:UNUSED_PAD src0_sel:DWORD src1_sel:WORD_1
	v_add_f32_e32 v103, v103, v108
	v_add_f32_e32 v103, v103, v109
	v_cvt_pk_bf16_f32 v107, v110, v111
	v_cvt_pk_bf16_f32 v106, v108, v109
	v_add_f32_e32 v103, v103, v110
	s_add_i32 s90, s90, 16
	v_add_f32_e32 v103, v103, v111
	ds_write_b128 v101, v[104:107] offset:16
	v_add_u32_e32 v102, 64, v102
	v_add_u32_e32 v101, 32, v101
	s_cmp_eq_u32 s90, 32
	s_cbranch_scc0 .LBB0_505
	v_sub_f32_e32 v101, v87, v82
	ds_bpermute_b32 v87, v83, v103
	v_exp_f32_e32 v83, v101
	s_and_saveexec_b64 s[14:15], s[12:13]
	ds_write_b32 v97, v83 offset:8192
	s_or_b64 exec, exec, s[14:15]
	s_waitcnt lgkmcnt(0)
	v_add_f32_e32 v101, v103, v87
	v_fmac_f32_e32 v101, v88, v83
	v_mov_b32_e32 v87, v82
	v_mov_b32_e32 v88, v101

; __device__ __forceinline__ unsigned pack2(float a, float b) { return (unsigned)f2bf(a) | ((unsigned)f2bf(b) << 16); }
; __device__ __forceinline__ float bflo(unsigned w) { return __uint_as_float(w << 16); }
; __device__ __forceinline__ float bfhi(unsigned w) { return __uint_as_float(w & 0xffff0000u); }
; __device__ __forceinline__ float silu_f(float g) { return g / (1.f + __expf(-g)); }
; template <int DH, int MODE>
; __device__ void attn_item(const Params& p, int layer, int b, int blk, int head, char* smem) {
;     ...
;   if (MODE == 0 && half == 0) linv_s[row] = 1.f / l_run;
;   __syncthreads();
;   {
;     constexpr int OST = DH + 4;
;     constexpr int CPR = DH / 8;
;     constexpr int NCH = 128 * CPR / 256;
;     float* Of = reinterpret_cast<float*>(smem);
;     uint4 gt[NCH];
; #pragma unroll
;     for (int i = 0; i < NCH; ++i) {
;       int q = tid + 256 * i, r = q / CPR, c = (q % CPR) * 8;
;       gt[i] = *reinterpret_cast<const uint4*>(P + (tq0 + r) * NP + gcol + c);
;     }
;     float lis[2][4];
; #pragma unroll
;     for (int m = 0; m < 2; ++m)
; #pragma unroll
;       for (int j = 0; j < 4; ++j) lis[m][j] = (MODE == 0) ? linv_s[wid * 32 + m * 16 + fq * 4 + j] : 1.f;
;     if (MODE == 0) __syncthreads();
; #pragma unroll
;     for (int m = 0; m < 2; ++m)
; #pragma unroll
;       for (int j = 0; j < 4; ++j) {
;         int r = wid * 32 + m * 16 + fq * 4 + j;
; #pragma unroll
;         for (int n = 0; n < NDT; ++n) Of[r * OST + n * 16 + fr] = o[m][n][j] * lis[m][j];
;       }
;     __syncthreads();
; #pragma unroll
;     for (int i = 0; i < NCH; ++i) {
;       int q = tid + 256 * i, r = q / CPR, c = (q % CPR) * 8;
;       float4 m0 = *reinterpret_cast<const float4*>(Of + r * OST + c);
;       float4 m1 = *reinterpret_cast<const float4*>(Of + r * OST + c + 4);
;       float mm[8] = {m0.x, m0.y, m0.z, m0.w, m1.x, m1.y, m1.z, m1.w};
;       unsigned gw[4] = {gt[i].x, gt[i].y, gt[i].z, gt[i].w};
;       unsigned ow[4];
; #pragma unroll
;       for (int e = 0; e < 4; ++e)
;         ow[e] = pack2(mm[2 * e] * silu_f(bflo(gw[e])), mm[2 * e + 1] * silu_f(bfhi(gw[e])));
.LBB0_513:
	s_or_b64 exec, exec, s[14:15]
	v_lshl_add_u64 v[44:45], v[66:67], 0, s[36:37]
	v_mov_b64_e32 v[46:47], s[50:51]
	v_mad_u64_u32 v[32:33], s[14:15], v44, s63, v[46:47]
	v_mad_i32_i24 v33, v45, s63, v33
	v_lshl_add_u64 v[36:37], v[32:33], 0, v[70:71]
	v_add_u32_e32 v32, 0x100, v81
	v_ashrrev_i32_e32 v33, 31, v32
	v_lshrrev_b32_e32 v33, 29, v33
	v_add_u32_e32 v33, v32, v33
	v_ashrrev_i32_e32 v86, 3, v33
	v_and_b32_e32 v33, -8, v33
	v_sub_u32_e32 v85, v32, v33
	v_lshlrev_b32_e32 v32, 3, v85
	v_ashrrev_i32_e32 v33, 31, v32
	s_waitcnt vmcnt(2)
	v_add_u32_e32 v48, 0x200, v81
	v_lshlrev_b64 v[90:91], 1, v[32:33]
	v_ashrrev_i32_e32 v32, 31, v48
	v_lshrrev_b32_e32 v32, 29, v32
	v_add_u32_e32 v32, v48, v32
	v_ashrrev_i32_e32 v92, 3, v32
	v_and_b32_e32 v49, -8, v32
	v_add_u32_e32 v32, 0x300, v81
	v_ashrrev_i32_e32 v33, 31, v32
	v_lshrrev_b32_e32 v33, 29, v33
	v_ashrrev_i32_e32 v87, 31, v86
	v_add_u32_e32 v33, v32, v33
	v_lshl_add_u64 v[88:89], v[86:87], 0, s[36:37]
	v_ashrrev_i32_e32 v94, 3, v33
	v_and_b32_e32 v33, -8, v33
	v_mad_u64_u32 v[34:35], s[14:15], v88, s63, v[46:47]
	v_sub_u32_e32 v87, v32, v33
	v_ashrrev_i32_e32 v95, 31, v94
	v_mad_i32_i24 v35, v89, s63, v35
	v_lshlrev_b32_e32 v32, 3, v87
	v_lshl_add_u64 v[40:41], v[94:95], 0, s[36:37]
	v_lshl_add_u64 v[38:39], v[34:35], 0, v[90:91]
	v_mad_u64_u32 v[34:35], s[14:15], v40, s63, v[46:47]
	v_ashrrev_i32_e32 v33, 31, v32
	v_mad_i32_i24 v35, v41, s63, v35
	v_lshlrev_b64 v[42:43], 1, v[32:33]
	v_lshl_add_u64 v[32:33], v[34:35], 0, v[42:43]
	v_add_co_u32_e32 v32, vcc, s72, v32
	s_waitcnt lgkmcnt(0)
	s_nop 0
	v_addc_co_u32_e32 v33, vcc, 0, v33, vcc
	s_barrier
	global_load_dwordx4 v[32:35], v[32:33], off offset:512
	v_sub_u32_e32 v95, v48, v49
	v_ashrrev_i32_e32 v93, 31, v92
	v_lshlrev_b32_e32 v48, 3, v95
	v_lshl_add_u64 v[96:97], v[92:93], 0, s[36:37]
	v_mad_u64_u32 v[46:47], s[14:15], v96, s63, v[46:47]
	v_ashrrev_i32_e32 v49, 31, v48
	v_mad_i32_i24 v47, v97, s63, v47
	v_lshlrev_b64 v[98:99], 1, v[48:49]
	v_lshl_add_u64 v[100:101], v[46:47], 0, v[98:99]
	v_lshl_or_b32 v46, v75, 7, v128
	ds_read_b128 v[60:63], v46 offset:8704
	ds_read_b128 v[80:83], v46 offset:8768
	s_ashr_i32 s13, s16, 31
	s_add_u32 s12, s28, s16
	s_addc_u32 s13, s29, s13
	s_lshl_b32 s14, s83, 1
	s_add_u32 s12, s12, s14
	v_lshl_or_b32 v46, v84, 2, v64
	s_waitcnt lgkmcnt(0)
	v_mul_f32_e32 v69, v0, v80
	s_addc_u32 s13, s13, 0
	v_mul_lo_u32 v0, v66, s74
	v_mul_lo_u32 v46, v46, s74
	v_mul_f32_e32 v75, v1, v81
	v_lshl_add_u32 v66, v68, 2, v0
	v_mov_b64_e32 v[0:1], s[12:13]
	v_lshl_add_u32 v47, v73, 2, v46
	v_mul_f32_e32 v48, v16, v60
	v_mul_f32_e32 v49, v28, v60
	v_mul_f32_e32 v50, v24, v60
	v_mul_f32_e32 v51, v20, v60
	s_waitcnt vmcnt(1)
	v_mul_f32_e32 v52, v17, v61
	v_mul_f32_e32 v53, v29, v61
	v_mul_f32_e32 v54, v25, v61
	v_mul_f32_e32 v55, v21, v61
	v_mul_f32_e32 v56, v18, v62
	v_mul_f32_e32 v57, v30, v62
	v_mul_f32_e32 v58, v26, v62
	v_mul_f32_e32 v59, v22, v62
	v_mul_f32_e32 v60, v19, v63
	v_mul_f32_e32 v61, v31, v63
	v_mul_f32_e32 v62, v27, v63
	v_mul_f32_e32 v64, v23, v63
	v_mul_f32_e32 v63, v12, v80
	v_mul_f32_e32 v65, v8, v80
	v_mul_f32_e32 v67, v4, v80
	v_mul_f32_e32 v72, v13, v81
	v_mul_f32_e32 v73, v9, v81
	v_mul_f32_e32 v74, v5, v81
	v_mul_f32_e32 v76, v14, v82
	v_mul_f32_e32 v77, v10, v82
	v_mul_f32_e32 v78, v6, v82
	v_mul_f32_e32 v80, v2, v82
	v_mul_f32_e32 v79, v15, v83
	v_mul_f32_e32 v81, v11, v83
	v_mul_f32_e32 v82, v7, v83
	v_mul_f32_e32 v83, v3, v83
	v_mad_u64_u32 v[2:3], s[12:13], v44, s70, v[0:1]
	v_mad_i32_i24 v3, v45, s70, v3
	v_lshl_add_u64 v[12:13], v[2:3], 0, v[70:71]
	v_mul_lo_u32 v2, v86, s74
	v_lshl_add_u32 v46, v85, 5, v2
	v_mad_u64_u32 v[2:3], s[12:13], v88, s70, v[0:1]
	v_mad_i32_i24 v3, v89, s70, v3
	v_mad_u64_u32 v[4:5], s[12:13], v40, s70, v[0:1]
	v_lshl_add_u64 v[10:11], v[2:3], 0, v[90:91]
	v_mul_lo_u32 v2, v92, s74
	v_mad_i32_i24 v5, v41, s70, v5
	v_lshl_add_u32 v45, v95, 5, v2
	v_mad_u64_u32 v[2:3], s[12:13], v96, s70, v[0:1]
	v_lshl_add_u64 v[14:15], v[4:5], 0, v[42:43]
	v_mad_i32_i24 v3, v97, s70, v3
	v_add_co_u32_e32 v0, vcc, s72, v100
	v_lshl_add_u64 v[8:9], v[2:3], 0, v[98:99]
	v_mul_lo_u32 v2, v94, s74
	s_waitcnt vmcnt(0)
	v_lshlrev_b32_e32 v16, 16, v33
	v_lshlrev_b32_e32 v18, 16, v32
	v_mul_f32_e32 v6, 0xbfb8aa3b, v18
	v_mul_f32_e32 v7, 0xbfb8aa3b, v16
	v_exp_f32_e32 v6, v6
	v_exp_f32_e32 v7, v7
	v_addc_co_u32_e32 v1, vcc, 0, v101, vcc
	v_lshl_add_u32 v44, v87, 5, v2
	v_pk_add_f32 v[4:5], v[6:7], 1.0 op_sel_hi:[1,0]
	global_load_dwordx4 v[0:3], v[0:1], off offset:512
	v_and_b32_e32 v19, 0xffff0000, v33
	v_and_b32_e32 v20, 0xffff0000, v32
	v_mul_f32_e32 v6, 0xbfb8aa3b, v20
	v_rcp_f32_e32 v17, v5
	s_nop 0
	v_mul_f32_e32 v17, v16, v17
	v_mul_f32_e32 v7, 0xbfb8aa3b, v19
	v_exp_f32_e32 v6, v6
	v_exp_f32_e32 v7, v7
	s_nop 0
	v_pk_add_f32 v[6:7], v[6:7], 1.0 op_sel_hi:[1,0]
	v_rcp_f32_e32 v16, v4
	s_nop 0
	v_mul_f32_e32 v16, v18, v16
	v_lshlrev_b32_e32 v23, 16, v34
	v_rcp_f32_e32 v4, v7
	s_nop 0
	v_mul_f32_e32 v19, v19, v4
	v_lshlrev_b32_e32 v22, 16, v35
	v_mul_f32_e32 v4, 0xbfb8aa3b, v23
	v_mul_f32_e32 v5, 0xbfb8aa3b, v22
	v_exp_f32_e32 v4, v4
	v_exp_f32_e32 v5, v5
	v_rcp_f32_e32 v18, v6
	s_nop 0
	v_mul_f32_e32 v18, v20, v18
	v_and_b32_e32 v24, 0xffff0000, v35
	v_pk_add_f32 v[4:5], v[4:5], 1.0 op_sel_hi:[1,0]
	v_and_b32_e32 v25, 0xffff0000, v34
	v_mul_f32_e32 v6, 0xbfb8aa3b, v25
	v_exp_f32_e32 v6, v6
	v_rcp_f32_e32 v21, v5
	s_nop 0
	v_mul_f32_e32 v21, v22, v21
	v_mul_f32_e32 v7, 0xbfb8aa3b, v24
	v_exp_f32_e32 v7, v7
	s_nop 0
	v_pk_add_f32 v[6:7], v[6:7], 1.0 op_sel_hi:[1,0]
	v_rcp_f32_e32 v20, v4
	s_nop 0
	v_mul_f32_e32 v20, v23, v20
	v_rcp_f32_e32 v23, v7
	s_nop 0
	v_mul_f32_e32 v23, v24, v23
	s_waitcnt vmcnt(0)
; __device__ __forceinline__ unsigned pack2(float a, float b) { return (unsigned)f2bf(a) | ((unsigned)f2bf(b) << 16); }
; __device__ __forceinline__ float bflo(unsigned w) { return __uint_as_float(w << 16); }
; __device__ __forceinline__ float bfhi(unsigned w) { return __uint_as_float(w & 0xffff0000u); }
; __device__ __forceinline__ float silu_f(float g) { return g / (1.f + __expf(-g)); }
; template <int DH, int MODE>
; __device__ void attn_item(const Params& p, int layer, int b, int blk, int head, char* smem) {
;     ...
;     float lis[2][4];
; #pragma unroll
;     for (int m = 0; m < 2; ++m)
; #pragma unroll
;       for (int j = 0; j < 4; ++j) lis[m][j] = (MODE == 0) ? linv_s[wid * 32 + m * 16 + fq * 4 + j] : 1.f;
;     if (MODE == 0) __syncthreads();
; #pragma unroll
;     for (int m = 0; m < 2; ++m)
; #pragma unroll
;       for (int j = 0; j < 4; ++j) {
;         int r = wid * 32 + m * 16 + fq * 4 + j;
; #pragma unroll
;         for (int n = 0; n < NDT; ++n) Of[r * OST + n * 16 + fr] = o[m][n][j] * lis[m][j];
;       }
;     __syncthreads();
; #pragma unroll
;     for (int i = 0; i < NCH; ++i) {
;       int q = tid + 256 * i, r = q / CPR, c = (q % CPR) * 8;
;       float4 m0 = *reinterpret_cast<const float4*>(Of + r * OST + c);
;       float4 m1 = *reinterpret_cast<const float4*>(Of + r * OST + c + 4);
;       float mm[8] = {m0.x, m0.y, m0.z, m0.w, m1.x, m1.y, m1.z, m1.w};
;       unsigned gw[4] = {gt[i].x, gt[i].y, gt[i].z, gt[i].w};
;       unsigned ow[4];
; #pragma unroll
;       for (int e = 0; e < 4; ++e)
;         ow[e] = pack2(mm[2 * e] * silu_f(bflo(gw[e])), mm[2 * e + 1] * silu_f(bfhi(gw[e])));
	v_lshlrev_b32_e32 v24, 16, v1
	v_lshlrev_b32_e32 v26, 16, v0
	v_mul_f32_e32 v4, 0xbfb8aa3b, v26
	v_mul_f32_e32 v5, 0xbfb8aa3b, v24
	v_exp_f32_e32 v4, v4
	v_exp_f32_e32 v5, v5
	v_and_b32_e32 v27, 0xffff0000, v1
	v_rcp_f32_e32 v22, v6
	s_nop 0
	v_mul_f32_e32 v22, v25, v22
	v_pk_add_f32 v[4:5], v[4:5], 1.0 op_sel_hi:[1,0]
	v_and_b32_e32 v28, 0xffff0000, v0
	v_mul_f32_e32 v0, 0xbfb8aa3b, v28
	v_exp_f32_e32 v6, v0
	v_lshlrev_b32_e32 v32, 16, v3
	v_mul_f32_e32 v7, 0xbfb8aa3b, v27
	v_rcp_f32_e32 v1, v5
	s_nop 0
	v_mul_f32_e32 v1, v24, v1
	v_exp_f32_e32 v7, v7
	s_nop 0
	v_pk_add_f32 v[24:25], v[6:7], 1.0 op_sel_hi:[1,0]
	v_rcp_f32_e32 v0, v4
	s_nop 0
	v_mul_f32_e32 v0, v26, v0
	v_lshlrev_b32_e32 v33, 16, v2
	v_rcp_f32_e32 v25, v25
	s_nop 0
	v_mul_f32_e32 v25, v27, v25
	v_add_co_u32_e64 v4, s[12:13], s72, v38
	s_nop 0
	s_nop 0
	v_addc_co_u32_e64 v5, s[12:13], 0, v39, s[12:13]
	global_load_dwordx4 v[4:7], v[4:5], off offset:512
	v_mul_f32_e32 v26, 0xbfb8aa3b, v33
	v_mul_f32_e32 v27, 0xbfb8aa3b, v32
	v_exp_f32_e32 v26, v26
	v_exp_f32_e32 v27, v27
	v_and_b32_e32 v30, 0xffff0000, v3
	v_rcp_f32_e32 v24, v24
	s_nop 0
	v_mul_f32_e32 v24, v28, v24
	v_pk_add_f32 v[26:27], v[26:27], 1.0 op_sel_hi:[1,0]
	v_and_b32_e32 v38, 0xffff0000, v2
	v_mul_f32_e32 v2, 0xbfb8aa3b, v38
	v_exp_f32_e32 v28, v2
	v_mul_f32_e32 v29, 0xbfb8aa3b, v30
	v_exp_f32_e32 v29, v29
	v_rcp_f32_e32 v3, v27
	s_nop 0
	v_mul_f32_e32 v3, v32, v3
	v_pk_add_f32 v[28:29], v[28:29], 1.0 op_sel_hi:[1,0]
	v_rcp_f32_e32 v2, v26
	s_nop 0
	v_mul_f32_e32 v2, v33, v2
	v_rcp_f32_e32 v27, v29
	s_nop 0
	v_mul_f32_e32 v27, v30, v27
	v_add_co_u32_e64 v30, s[12:13], s72, v36
	s_nop 0
	s_nop 0
	v_addc_co_u32_e64 v31, s[12:13], 0, v37, s[12:13]
	global_load_dwordx4 v[32:35], v[30:31], off offset:512
	v_rcp_f32_e32 v26, v28
	s_nop 0
	v_mul_f32_e32 v26, v38, v26
	s_barrier
	s_waitcnt vmcnt(1)
	v_lshlrev_b32_e32 v36, 16, v5
	v_lshlrev_b32_e32 v37, 16, v4
	v_mul_f32_e32 v30, 0xbfb8aa3b, v37
	v_mul_f32_e32 v31, 0xbfb8aa3b, v36
	v_exp_f32_e32 v30, v30
	v_exp_f32_e32 v31, v31
	v_and_b32_e32 v38, 0xffff0000, v5
	v_and_b32_e32 v39, 0xffff0000, v4
	v_mul_f32_e32 v4, 0xbfb8aa3b, v39
	v_pk_add_f32 v[28:29], v[30:31], 1.0 op_sel_hi:[1,0]
	v_exp_f32_e32 v30, v4
	ds_write2_b32 v47, v48, v49 offset1:16
	ds_write2_b32 v47, v50, v51 offset0:32 offset1:48
	ds_write2_b32 v47, v52, v53 offset0:68 offset1:84
	ds_write2_b32 v47, v54, v55 offset0:100 offset1:116
	ds_write2_b32 v47, v56, v57 offset0:136 offset1:152
	ds_write2_b32 v47, v58, v59 offset0:168 offset1:184
	ds_write2_b32 v47, v60, v61 offset0:204 offset1:220
	ds_write2_b32 v47, v62, v64 offset0:236 offset1:252
	v_mul_f32_e32 v31, 0xbfb8aa3b, v38
	v_exp_f32_e32 v31, v31
	v_rcp_f32_e32 v5, v29
	s_nop 0
	v_mul_f32_e32 v5, v36, v5
	v_pk_add_f32 v[30:31], v[30:31], 1.0 op_sel_hi:[1,0]
	v_rcp_f32_e32 v4, v28
	s_nop 0
	v_mul_f32_e32 v4, v37, v4
	v_rcp_f32_e32 v29, v31
	s_nop 0
	v_mul_f32_e32 v29, v38, v29
	v_lshlrev_b32_e32 v38, 16, v7
	v_lshlrev_b32_e32 v40, 16, v6
	v_mul_f32_e32 v36, 0xbfb8aa3b, v40
	v_mul_f32_e32 v37, 0xbfb8aa3b, v38
	v_exp_f32_e32 v36, v36
	v_exp_f32_e32 v37, v37
	v_rcp_f32_e32 v28, v30
	s_nop 0
	v_mul_f32_e32 v28, v39, v28
	v_and_b32_e32 v39, 0xffff0000, v7
	v_pk_add_f32 v[30:31], v[36:37], 1.0 op_sel_hi:[1,0]
	v_and_b32_e32 v41, 0xffff0000, v6
	v_mul_f32_e32 v6, 0xbfb8aa3b, v41
	v_exp_f32_e32 v36, v6
	v_mul_f32_e32 v37, 0xbfb8aa3b, v39
	v_exp_f32_e32 v37, v37
	v_rcp_f32_e32 v7, v31
	s_nop 0
	v_mul_f32_e32 v7, v38, v7
	v_pk_add_f32 v[36:37], v[36:37], 1.0 op_sel_hi:[1,0]
	v_rcp_f32_e32 v6, v30
	s_nop 0
	v_mul_f32_e32 v6, v40, v6
	v_rcp_f32_e32 v31, v37
	s_nop 0
	v_mul_f32_e32 v31, v39, v31
	s_waitcnt vmcnt(0)
	v_lshlrev_b32_e32 v42, 16, v33
	v_lshlrev_b32_e32 v43, 16, v32
	v_mul_f32_e32 v38, 0xbfb8aa3b, v43
	v_mul_f32_e32 v39, 0xbfb8aa3b, v42
	v_exp_f32_e32 v38, v38
	v_exp_f32_e32 v39, v39
	v_rcp_f32_e32 v30, v36
	s_nop 0
	v_mul_f32_e32 v30, v41, v30
	v_and_b32_e32 v68, 0xffff0000, v33
	v_pk_add_f32 v[36:37], v[38:39], 1.0 op_sel_hi:[1,0]
	v_and_b32_e32 v39, 0xffff0000, v32
	v_mul_f32_e32 v32, 0xbfb8aa3b, v39
	v_exp_f32_e32 v32, v32
	v_rcp_f32_e32 v41, v37
	s_nop 0
	v_mul_f32_e32 v41, v42, v41
	v_mul_f32_e32 v33, 0xbfb8aa3b, v68
	v_exp_f32_e32 v33, v33
	s_nop 0
	v_pk_add_f32 v[32:33], v[32:33], 1.0 op_sel_hi:[1,0]
	v_rcp_f32_e32 v40, v36
	s_nop 0
	v_mul_f32_e32 v40, v43, v40
	v_lshlrev_b32_e32 v70, 16, v34
	v_rcp_f32_e32 v43, v33
	s_nop 0
	v_mul_f32_e32 v43, v68, v43
	v_lshlrev_b32_e32 v38, 16, v35
	v_mul_f32_e32 v36, 0xbfb8aa3b, v70
	v_mul_f32_e32 v37, 0xbfb8aa3b, v38
	v_exp_f32_e32 v36, v36
	v_exp_f32_e32 v37, v37
	v_rcp_f32_e32 v42, v32
	s_nop 0
	v_mul_f32_e32 v42, v39, v42
	v_and_b32_e32 v39, 0xffff0000, v35
	v_pk_add_f32 v[32:33], v[36:37], 1.0 op_sel_hi:[1,0]
	v_and_b32_e32 v68, 0xffff0000, v34
	v_mul_f32_e32 v34, 0xbfb8aa3b, v68
	v_exp_f32_e32 v34, v34
	v_rcp_f32_e32 v71, v33
	s_nop 0
	v_mul_f32_e32 v71, v38, v71
	v_mul_f32_e32 v35, 0xbfb8aa3b, v39
	v_exp_f32_e32 v35, v35
	s_nop 0
	v_pk_add_f32 v[36:37], v[34:35], 1.0 op_sel_hi:[1,0]
	v_rcp_f32_e32 v33, v32
	s_nop 0
	v_mul_f32_e32 v70, v70, v33
	v_rcp_f32_e32 v85, v37
	s_nop 0
	v_mul_f32_e32 v85, v39, v85
	v_add_u32_e32 v32, 0x1000, v47
	ds_write2_b32 v32, v63, v65 offset0:64 offset1:80
	ds_write2_b32 v32, v67, v69 offset0:96 offset1:112
	ds_write2_b32 v32, v72, v73 offset0:132 offset1:148
	ds_write2_b32 v32, v74, v75 offset0:164 offset1:180
	ds_write2_b32 v32, v76, v77 offset0:200 offset1:216
	ds_write2_b32 v32, v78, v80 offset0:232 offset1:248
	v_add_u32_e32 v32, 0x1400, v47
	ds_write2_b32 v32, v79, v81 offset0:12 offset1:28
	ds_write2_b32 v32, v82, v83 offset0:44 offset1:60
	s_waitcnt lgkmcnt(0)
	s_barrier
; __device__ __forceinline__ unsigned pack2(float a, float b) { return (unsigned)f2bf(a) | ((unsigned)f2bf(b) << 16); }
; __device__ __forceinline__ float bflo(unsigned w) { return __uint_as_float(w << 16); }
; __device__ __forceinline__ float bfhi(unsigned w) { return __uint_as_float(w & 0xffff0000u); }
; __device__ __forceinline__ float silu_f(float g) { return g / (1.f + __expf(-g)); }
; template <int DH, int MODE>
; __device__ void attn_item(const Params& p, int layer, int b, int blk, int head, char* smem) {
;     ...
; #pragma unroll
;     for (int i = 0; i < NCH; ++i) {
;       int q = tid + 256 * i, r = q / CPR, c = (q % CPR) * 8;
;       float4 m0 = *reinterpret_cast<const float4*>(Of + r * OST + c);
;       float4 m1 = *reinterpret_cast<const float4*>(Of + r * OST + c + 4);
;       float mm[8] = {m0.x, m0.y, m0.z, m0.w, m1.x, m1.y, m1.z, m1.w};
;       unsigned gw[4] = {gt[i].x, gt[i].y, gt[i].z, gt[i].w};
;       unsigned ow[4];
; #pragma unroll
;       for (int e = 0; e < 4; ++e)
;         ow[e] = pack2(mm[2 * e] * silu_f(bflo(gw[e])), mm[2 * e + 1] * silu_f(bfhi(gw[e])));
;       *reinterpret_cast<uint4*>(Y + (tq0 + r) * YW + ycol + c) = make_uint4(ow[0], ow[1], ow[2], ow[3]);
;     }
;   }
;   __syncthreads();
	ds_read_b128 v[32:35], v66
	v_rcp_f32_e32 v84, v36
	s_nop 0
	v_mul_f32_e32 v84, v68, v84
	ds_read_b128 v[36:39], v66 offset:16
	v_add_co_u32_e32 v12, vcc, s77, v12
	s_waitcnt lgkmcnt(1)
	v_mov_b32_e32 v48, v32
	v_mov_b32_e32 v49, v34
	v_pk_mul_f32 v[40:41], v[40:41], v[48:49]
	v_mov_b32_e32 v34, v33
	v_pk_mul_f32 v[32:33], v[42:43], v[34:35]
	v_cvt_pk_bf16_f32 v33, v41, v33
	v_cvt_pk_bf16_f32 v32, v40, v32
	s_waitcnt lgkmcnt(0)
	v_mov_b32_e32 v34, v36
	v_mov_b32_e32 v35, v38
	v_pk_mul_f32 v[34:35], v[70:71], v[34:35]
	v_mov_b32_e32 v38, v37
	v_pk_mul_f32 v[36:37], v[84:85], v[38:39]
	v_cvt_pk_bf16_f32 v35, v35, v37
	v_cvt_pk_bf16_f32 v34, v34, v36
	ds_read_b128 v[36:39], v46
	v_addc_co_u32_e32 v13, vcc, 0, v13, vcc
	global_store_dwordx4 v[12:13], v[32:35], off offset:1024
	s_nop 0
	ds_read_b128 v[32:35], v46 offset:16
	s_waitcnt lgkmcnt(1)
	v_mov_b32_e32 v12, v36
	v_mov_b32_e32 v13, v38
	v_pk_mul_f32 v[4:5], v[4:5], v[12:13]
	v_mov_b32_e32 v38, v37
	v_pk_mul_f32 v[12:13], v[28:29], v[38:39]
	v_cvt_pk_bf16_f32 v5, v5, v13
	v_cvt_pk_bf16_f32 v4, v4, v12
	s_waitcnt lgkmcnt(0)
	v_mov_b32_e32 v12, v32
	v_mov_b32_e32 v13, v34
	v_pk_mul_f32 v[6:7], v[6:7], v[12:13]
	v_mov_b32_e32 v34, v33
	v_pk_mul_f32 v[12:13], v[30:31], v[34:35]
	ds_read_b128 v[28:31], v45
	v_add_co_u32_e32 v10, vcc, s77, v10
	v_cvt_pk_bf16_f32 v7, v7, v13
	v_cvt_pk_bf16_f32 v6, v6, v12
	v_addc_co_u32_e32 v11, vcc, 0, v11, vcc
	global_store_dwordx4 v[10:11], v[4:7], off offset:1024
	s_waitcnt lgkmcnt(0)
	v_mov_b32_e32 v10, v28
	v_mov_b32_e32 v11, v30
	ds_read_b128 v[4:7], v45 offset:16
	v_pk_mul_f32 v[0:1], v[0:1], v[10:11]
	v_mov_b32_e32 v30, v29
	v_pk_mul_f32 v[10:11], v[24:25], v[30:31]
	v_cvt_pk_bf16_f32 v1, v1, v11
	v_cvt_pk_bf16_f32 v0, v0, v10
	s_waitcnt lgkmcnt(0)
	v_mov_b32_e32 v10, v4
	v_mov_b32_e32 v11, v6
	v_pk_mul_f32 v[2:3], v[2:3], v[10:11]
	v_mov_b32_e32 v6, v5
	v_pk_mul_f32 v[4:5], v[26:27], v[6:7]
	v_cvt_pk_bf16_f32 v3, v3, v5
	v_cvt_pk_bf16_f32 v2, v2, v4
	ds_read_b128 v[4:7], v44
	v_add_co_u32_e32 v8, vcc, s77, v8
	s_nop 1
	v_addc_co_u32_e32 v9, vcc, 0, v9, vcc
	global_store_dwordx4 v[8:9], v[0:3], off offset:1024
	s_waitcnt lgkmcnt(0)
	v_mov_b32_e32 v8, v4
	v_mov_b32_e32 v9, v6
	ds_read_b128 v[0:3], v44 offset:16
	v_pk_mul_f32 v[8:9], v[16:17], v[8:9]
	v_mov_b32_e32 v6, v5
	v_pk_mul_f32 v[4:5], v[18:19], v[6:7]
	v_cvt_pk_bf16_f32 v5, v9, v5
	v_cvt_pk_bf16_f32 v4, v8, v4
	s_waitcnt lgkmcnt(0)
	v_mov_b32_e32 v6, v0
	v_mov_b32_e32 v7, v2
	v_pk_mul_f32 v[6:7], v[20:21], v[6:7]
	v_mov_b32_e32 v2, v1
	v_pk_mul_f32 v[0:1], v[22:23], v[2:3]
	v_cvt_pk_bf16_f32 v6, v6, v0
	v_add_co_u32_e32 v0, vcc, 0x184a1000, v14
	v_cvt_pk_bf16_f32 v7, v7, v1
	s_nop 0
	v_addc_co_u32_e32 v1, vcc, 0, v15, vcc
	global_store_dwordx4 v[0:1], v[4:7], off offset:1024
	s_barrier

; __device__ __forceinline__ unsigned pack2(float a, float b) { return (unsigned)f2bf(a) | ((unsigned)f2bf(b) << 16); }
; template <int DH, int MODE>
; __device__ void attn_item(const Params& p, int layer, int b, int blk, int head, char* smem) {
;     ...
; #pragma unroll 2
;         for (int s8 = 0; s8 < 4; ++s8) {
;           float4 va = s4[2 * s8], vb = s4[2 * s8 + 1];
;           float e[8] = {va.x, va.y, va.z, va.w, vb.x, vb.y, vb.z, vb.w};
;           float pv[8];
; #pragma unroll
;           for (int k = 0; k < 8; ++k) {
;             bool valid = (kpb + s8 * 8 + k) < qpos;
;             pv[k] = valid ? __builtin_amdgcn_exp2f(e[k] + offs) : 0.f;
;           }
;           uint4 ov;
;           ov.x = pack2(pv[0], pv[1]); ov.y = pack2(pv[2], pv[3]);
;           ov.z = pack2(pv[4], pv[5]); ov.w = pack2(pv[6], pv[7]);
;           *reinterpret_cast<uint4*>(prow + s8 * 16) = ov;
;         }
.LBB0_528:
	s_or_b64 exec, exec, s[54:55]
	s_waitcnt lgkmcnt(3)
	v_add_f32_e32 v152, v176, v152
	v_exp_f32_e32 v152, v152
	s_waitcnt lgkmcnt(1)
	v_add_f32_e32 v149, v176, v149
	v_exp_f32_e32 v149, v149
	v_add_u32_e32 v182, 0x3fc9, v178
	v_add_f32_e32 v151, v176, v151
	v_add_f32_e32 v148, v176, v148
	v_cmp_lt_i32_e32 vcc, v182, v144
	v_exp_f32_e32 v185, v151
	v_exp_f32_e32 v186, v148
	v_add_u32_e32 v148, 0x3fce, v178
	s_waitcnt lgkmcnt(0)
	v_add_f32_e32 v151, v176, v180
	v_cndmask_b32_e32 v152, 0, v152, vcc
	v_exp_f32_e32 v151, v151
	v_cmp_lt_i32_e32 vcc, v148, v144
	v_add_u32_e32 v148, 0x3fcf, v178
	v_add_f32_e32 v153, v176, v153
	v_cndmask_b32_e32 v149, 0, v149, vcc
	v_cmp_lt_i32_e32 vcc, v148, v144
	v_cvt_pk_bf16_f32 v148, 0, v179
	v_exp_f32_e32 v153, v153
	v_lshrrev_b32_e32 v148, 16, v148
	v_cvt_pk_bf16_f32 v152, 0, v152
	v_add_f32_e32 v150, v176, v150
	v_cndmask_b32_e32 v151, 0, v151, vcc
	v_and_or_b32 v148, v152, s64, v148
	v_or_b32_e32 v182, 2, v181
	v_exp_f32_e32 v150, v150
	v_cvt_pk_bf16_f32 v149, 0, v149
	v_or_b32_e32 v183, 4, v181
	v_lshrrev_b32_e32 v149, 16, v149
	v_cvt_pk_bf16_f32 v151, 0, v151
	v_cmp_lt_i32_e32 vcc, v182, v144
	v_or_b32_e32 v184, 5, v181
	v_or_b32_e32 v181, 3, v181
	v_and_or_b32 v151, v151, s64, v149
	v_cndmask_b32_e32 v149, 0, v153, vcc
	v_cmp_lt_i32_e32 vcc, v183, v131
	v_cvt_pk_bf16_f32 v149, 0, v149
	s_nop 0
	v_cndmask_b32_e32 v152, 0, v185, vcc
	v_cmp_lt_i32_e32 vcc, v181, v144
	s_nop 0
	s_nop 0
	v_cndmask_b32_e32 v150, 0, v150, vcc
	v_cmp_lt_i32_e32 vcc, v184, v131
	v_cvt_pk_bf16_f32 v150, 0, v150
	s_nop 0
	v_cndmask_b32_e32 v153, 0, v186, vcc
	v_and_b32_e32 v178, 0xffff0000, v150
	v_cvt_pk_bf16_f32 v150, v152, v153
	v_or_b32_sdwa v149, v178, v149 dst_sel:DWORD dst_unused:UNUSED_PAD src0_sel:DWORD src1_sel:WORD_1
	s_add_i32 s88, s88, 16
	ds_write_b128 v175, v[148:151] offset:16
	v_add_u32_e32 v177, 64, v177
	s_cmp_eq_u32 s88, 32
	v_add_u32_e32 v175, 32, v175
	s_cbranch_scc1 .LBB0_534

; __device__ __forceinline__ unsigned pack2(float a, float b) { return (unsigned)f2bf(a) | ((unsigned)f2bf(b) << 16); }
; template <int DH, int MODE>
; __device__ void attn_item(const Params& p, int layer, int b, int blk, int head, char* smem) {
;     ...
; #pragma unroll 2
;         for (int s8 = 0; s8 < 4; ++s8) {
;           float4 va = s4[2 * s8], vb = s4[2 * s8 + 1];
;           float e[8] = {va.x, va.y, va.z, va.w, vb.x, vb.y, vb.z, vb.w};
;           float pv[8];
; #pragma unroll
;           for (int k = 0; k < 8; ++k) {
;             bool valid = (kpb + s8 * 8 + k) < qpos;
;             pv[k] = valid ? __builtin_amdgcn_exp2f(e[k] + offs) : 0.f;
;           }
;           uint4 ov;
;           ov.x = pack2(pv[0], pv[1]); ov.y = pack2(pv[2], pv[3]);
;           ov.z = pack2(pv[4], pv[5]); ov.w = pack2(pv[6], pv[7]);
;           *reinterpret_cast<uint4*>(prow + s8 * 16) = ov;
;         }
.LBB0_531:
	s_or_b64 exec, exec, s[54:55]
	s_waitcnt lgkmcnt(3)
	v_add_f32_e32 v152, v176, v152
	v_exp_f32_e32 v152, v152
	s_waitcnt lgkmcnt(1)
	v_add_f32_e32 v149, v176, v149
	v_exp_f32_e32 v149, v149
	v_add_u32_e32 v183, 0x3fc1, v178
	v_add_f32_e32 v151, v176, v151
	v_add_f32_e32 v148, v176, v148
	v_cmp_lt_i32_e32 vcc, v183, v144
	v_exp_f32_e32 v186, v151
	v_exp_f32_e32 v187, v148
	v_add_u32_e32 v148, 0x3fc6, v178
	s_waitcnt lgkmcnt(0)
	v_add_f32_e32 v151, v176, v180
	v_cndmask_b32_e32 v152, 0, v152, vcc
	v_exp_f32_e32 v151, v151
	v_cmp_lt_i32_e32 vcc, v148, v144
	v_add_u32_e32 v148, 0x3fc7, v178
	v_add_f32_e32 v153, v176, v153
	v_cndmask_b32_e32 v149, 0, v149, vcc
	v_cmp_lt_i32_e32 vcc, v148, v144
	v_cvt_pk_bf16_f32 v148, 0, v181
	v_exp_f32_e32 v153, v153
	v_lshrrev_b32_e32 v148, 16, v148
	v_cvt_pk_bf16_f32 v152, 0, v152
	v_add_f32_e32 v150, v176, v150
	v_cndmask_b32_e32 v151, 0, v151, vcc
	v_and_or_b32 v148, v152, s64, v148
	v_or_b32_e32 v183, 2, v182
	v_exp_f32_e32 v150, v150
	v_cvt_pk_bf16_f32 v149, 0, v149
	v_or_b32_e32 v184, 4, v182
	v_lshrrev_b32_e32 v149, 16, v149
	v_cvt_pk_bf16_f32 v151, 0, v151
	v_cmp_lt_i32_e32 vcc, v183, v144
	v_or_b32_e32 v185, 5, v182
	v_or_b32_e32 v182, 3, v182
	v_and_or_b32 v151, v151, s64, v149
	v_cndmask_b32_e32 v149, 0, v153, vcc
	v_cmp_lt_i32_e32 vcc, v184, v131
	v_cvt_pk_bf16_f32 v149, 0, v149
	s_nop 0
	v_cndmask_b32_e32 v152, 0, v186, vcc
	v_cmp_lt_i32_e32 vcc, v182, v144
	s_nop 0
	s_nop 0
	v_cndmask_b32_e32 v150, 0, v150, vcc
	v_cmp_lt_i32_e32 vcc, v185, v131
	v_cvt_pk_bf16_f32 v150, 0, v150
	s_nop 0
	v_cndmask_b32_e32 v153, 0, v187, vcc
	v_and_b32_e32 v180, 0xffff0000, v150
	v_cvt_pk_bf16_f32 v150, v152, v153
	v_or_b32_sdwa v149, v180, v149 dst_sel:DWORD dst_unused:UNUSED_PAD src0_sel:DWORD src1_sel:WORD_1
	ds_write_b128 v175, v[148:151]
	ds_read2_b32 v[152:153], v177 offset0:9 offset1:10
	ds_read2_b32 v[150:151], v177 offset0:11 offset1:12
	ds_read2_b32 v[148:149], v177 offset0:13 offset1:14
	ds_read_b32 v180, v177 offset:60
	v_add_u32_e32 v181, 0x3fc8, v178
	v_cmp_lt_i32_e32 vcc, v181, v144
	s_and_saveexec_b64 s[54:55], vcc
	s_cbranch_execz .LBB0_528
	ds_read_b32 v179, v177 offset:32
	s_waitcnt lgkmcnt(0)
	v_add_f32_e32 v179, v176, v179
	v_exp_f32_e32 v179, v179
	s_branch .LBB0_528

; __device__ __forceinline__ float bflo(unsigned w) { return __uint_as_float(w << 16); }
; __device__ __forceinline__ float bfhi(unsigned w) { return __uint_as_float(w & 0xffff0000u); }
; __device__ void norm_phase(const Params& p, int layer) {
;     ...
;       const float* xr = (layer == 0) ? p.x : p.out;
;       float4 ov[8];
;       float ss = 0.f;
; #pragma unroll
;       for (int i = 0; i < 8; ++i) {
;         {
;           uint2 ob = *reinterpret_cast<const uint2*>(OUTB + rbase + i * 128);
;           ov[i] = make_float4(bflo(ob.x), bfhi(ob.x), bflo(ob.y), bfhi(ob.y));
;         }
;         xv[i] = *reinterpret_cast<const float4*>(xr + rbase + i * 128);
;       }
; #pragma unroll
;       for (int i = 0; i < 8; ++i) ss += ov[i].x * ov[i].x + ov[i].y * ov[i].y + ov[i].z * ov[i].z + ov[i].w * ov[i].w;
;       ss = half_wave_sum(ss);
;       float rstd = rsqrtf(ss * (1.f / 1024.f) + 1e-6f);
; #pragma unroll
;       for (int i = 0; i < 8; ++i) {
;         float4 g = *reinterpret_cast<const float4*>(p.g_post + (size_t)layer * DM + l32 * 4 + i * 128);
;         xv[i].x += ov[i].x * rstd * g.x;
;         xv[i].y += ov[i].y * rstd * g.y;
;         xv[i].z += ov[i].z * rstd * g.z;
;         xv[i].w += ov[i].w * rstd * g.w;
;         *reinterpret_cast<float4*>(p.out + rbase + i * 128) = xv[i];
;       }
.LBB0_680:
	v_ashrrev_i32_e32 v39, 31, v38
	v_lshlrev_b64 v[4:5], 10, v[38:39]
	v_or_b32_e32 v4, v4, v32
	v_lshlrev_b64 v[40:41], 1, v[4:5]
	v_lshl_add_u64 v[6:7], s[16:17], 0, v[40:41]
	global_load_dwordx2 v[12:13], v[6:7], off
	global_load_dwordx2 v[14:15], v[6:7], off offset:256
	global_load_dwordx2 v[16:17], v[6:7], off offset:512
	global_load_dwordx2 v[18:19], v[6:7], off offset:768
	global_load_dwordx2 v[20:21], v[6:7], off offset:1024
	global_load_dwordx2 v[22:23], v[6:7], off offset:1280
	global_load_dwordx2 v[24:25], v[6:7], off offset:1536
	global_load_dwordx2 v[26:27], v[6:7], off offset:1792
	global_load_dwordx4 v[0:3], v[34:35], off
	v_lshl_add_u64 v[42:43], v[4:5], 2, s[20:21]
	global_load_dwordx4 v[8:11], v[42:43], off
	v_lshl_add_u64 v[40:41], s[14:15], 0, v[40:41]
	v_add_u32_e32 v33, s56, v33
	v_add_u32_e32 v38, s24, v38
	s_waitcnt vmcnt(9)
	v_lshlrev_b32_e32 v28, 16, v12
	v_and_b32_e32 v29, 0xffff0000, v12
	s_waitcnt vmcnt(8)
	v_lshlrev_b32_e32 v52, 16, v14
	v_and_b32_e32 v53, 0xffff0000, v14
	s_waitcnt vmcnt(7)
	v_and_b32_e32 v57, 0xffff0000, v16
	s_waitcnt vmcnt(6)
	v_and_b32_e32 v59, 0xffff0000, v18
	v_lshlrev_b32_e32 v30, 16, v13
	v_and_b32_e32 v31, 0xffff0000, v13
	v_lshlrev_b32_e32 v54, 16, v15
	v_and_b32_e32 v55, 0xffff0000, v15
	v_lshlrev_b32_e32 v56, 16, v16
	v_lshlrev_b32_e32 v58, 16, v18
	s_waitcnt vmcnt(5)
	v_lshlrev_b32_e32 v60, 16, v20
	v_and_b32_e32 v61, 0xffff0000, v20
	v_lshlrev_b32_e32 v62, 16, v21
	v_and_b32_e32 v63, 0xffff0000, v21
	s_waitcnt vmcnt(2)
	v_lshlrev_b32_e32 v6, 16, v26
	v_and_b32_e32 v7, 0xffff0000, v26
	v_lshlrev_b32_e32 v4, 16, v27
	v_and_b32_e32 v5, 0xffff0000, v27
	v_pk_mul_f32 v[12:13], v[28:29], v[28:29]
	v_pk_mul_f32 v[20:21], v[52:53], v[52:53]
	v_mov_b32_e32 v26, v57
	v_mov_b32_e32 v27, v59
	v_lshlrev_b32_e32 v16, 16, v17
	v_lshlrev_b32_e32 v18, 16, v19
	v_lshlrev_b32_e32 v64, 16, v22
	v_and_b32_e32 v65, 0xffff0000, v22
	v_lshlrev_b32_e32 v66, 16, v23
	v_and_b32_e32 v67, 0xffff0000, v23
	v_lshlrev_b32_e32 v68, 16, v24
	v_and_b32_e32 v69, 0xffff0000, v24
	v_lshlrev_b32_e32 v70, 16, v25
	v_and_b32_e32 v71, 0xffff0000, v25
	v_pk_mul_f32 v[14:15], v[30:31], v[30:31]
	v_pk_mul_f32 v[22:23], v[54:55], v[54:55]
	v_mov_b32_e32 v24, v56
	v_mov_b32_e32 v25, v58
	v_pk_mul_f32 v[26:27], v[26:27], v[26:27]
	v_add_f32_e32 v39, v20, v21
	v_add_f32_e32 v12, v12, v13
	v_and_b32_e32 v17, 0xffff0000, v17
	v_and_b32_e32 v19, 0xffff0000, v19
	v_mov_b32_e32 v72, v16
	v_mov_b32_e32 v73, v18
	v_mov_b32_e32 v78, v61
	v_mov_b32_e32 v79, v65
	v_pk_fma_f32 v[20:21], v[24:25], v[24:25], v[26:27]
	v_add_f32_e32 v22, v39, v22
	v_add_f32_e32 v12, v12, v14
	v_mov_b32_e32 v74, v17
	v_mov_b32_e32 v75, v19
	v_mov_b32_e32 v76, v60
	v_mov_b32_e32 v77, v64
	v_pk_mul_f32 v[78:79], v[78:79], v[78:79]
	v_pk_fma_f32 v[20:21], v[72:73], v[72:73], v[20:21]
	v_add_f32_e32 v39, v23, v22
	v_add_f32_e32 v12, v15, v12
	v_mov_b32_e32 v80, v62
	v_mov_b32_e32 v81, v66
	v_mov_b32_e32 v86, v69
	v_mov_b32_e32 v87, v7
	v_pk_fma_f32 v[24:25], v[76:77], v[76:77], v[78:79]
	v_pk_fma_f32 v[20:21], v[74:75], v[74:75], v[20:21]
	v_add_f32_e32 v12, v12, v39
	v_mov_b32_e32 v82, v63
	v_mov_b32_e32 v83, v67
	v_mov_b32_e32 v84, v68
	v_mov_b32_e32 v85, v6
	v_pk_mul_f32 v[86:87], v[86:87], v[86:87]
	v_pk_fma_f32 v[24:25], v[80:81], v[80:81], v[24:25]
	v_add_f32_e32 v12, v12, v20
	v_mov_b32_e32 v88, v70
	v_mov_b32_e32 v89, v4
	v_pk_fma_f32 v[26:27], v[84:85], v[84:85], v[86:87]
	v_pk_fma_f32 v[22:23], v[82:83], v[82:83], v[24:25]
	v_add_f32_e32 v12, v12, v21
	v_mov_b32_e32 v90, v71
	v_mov_b32_e32 v91, v5
	v_pk_fma_f32 v[26:27], v[88:89], v[88:89], v[26:27]
	v_add_f32_e32 v12, v12, v22
	v_pk_fma_f32 v[24:25], v[90:91], v[90:91], v[26:27]
	v_add_f32_e32 v12, v12, v23
	v_add_f32_e32 v12, v12, v24
	v_add_f32_e32 v12, v12, v25
	ds_bpermute_b32 v13, v44, v12
	s_waitcnt lgkmcnt(0)
	v_add_f32_e32 v12, v12, v13
	ds_bpermute_b32 v13, v45, v12
	s_waitcnt lgkmcnt(0)
	v_add_f32_e32 v12, v12, v13
	ds_bpermute_b32 v13, v46, v12
	s_waitcnt lgkmcnt(0)
	v_add_f32_e32 v12, v12, v13
	ds_bpermute_b32 v13, v47, v12
	s_waitcnt lgkmcnt(0)
	v_add_f32_e32 v12, v12, v13
	ds_bpermute_b32 v13, v48, v12
	s_waitcnt lgkmcnt(0)
	v_add_f32_e32 v12, v12, v13
	v_fmamk_f32 v12, v12, 0x3a800000, v49
	v_mul_f32_e32 v13, 0x4b800000, v12
	v_cmp_gt_f32_e32 vcc, s25, v12
	s_nop 1
	v_cndmask_b32_e32 v12, v12, v13, vcc
	v_rsq_f32_e32 v20, v12
	global_load_dwordx4 v[12:15], v[42:43], off offset:512
	v_mul_f32_e32 v21, 0x45800000, v20
	v_cndmask_b32_e32 v72, v20, v21, vcc
	v_pk_mul_f32 v[20:21], v[72:73], v[28:29] op_sel_hi:[0,1]
	v_pk_mul_f32 v[22:23], v[72:73], v[30:31] op_sel_hi:[0,1]
	s_waitcnt vmcnt(1)
	v_pk_fma_f32 v[28:29], v[0:1], v[20:21], v[8:9]
	v_pk_fma_f32 v[30:31], v[2:3], v[22:23], v[10:11]
	global_store_dwordx4 v[42:43], v[28:31], off
	global_load_dwordx4 v[0:3], v[34:35], off offset:512
	v_pk_mul_f32 v[8:9], v[72:73], v[52:53] op_sel_hi:[0,1]
	v_pk_mul_f32 v[10:11], v[72:73], v[54:55] op_sel_hi:[0,1]
	v_pk_mul_f32 v[20:21], v[72:73], v[56:57] op_sel_hi:[0,1]
	v_pk_mul_f32 v[16:17], v[72:73], v[16:17] op_sel_hi:[0,1]
	v_pk_mul_f32 v[6:7], v[72:73], v[6:7] op_sel_hi:[0,1]
	s_waitcnt vmcnt(0)
	v_pk_fma_f32 v[24:25], v[8:9], v[0:1], v[12:13]
	v_pk_fma_f32 v[26:27], v[10:11], v[2:3], v[14:15]
	global_store_dwordx4 v[42:43], v[24:27], off offset:512
	global_load_dwordx4 v[0:3], v[34:35], off offset:1024
	global_load_dwordx4 v[8:11], v[42:43], off offset:1024
	global_load_dwordx4 v[12:15], v[42:43], off offset:1536
	s_waitcnt vmcnt(1)
; __device__ void norm_phase(const Params& p, int layer) {
;     ...
;       for (int i = 0; i < 8; ++i) {
;         float4 g = *reinterpret_cast<const float4*>(p.g_post + (size_t)layer * DM + l32 * 4 + i * 128);
;         xv[i].x += ov[i].x * rstd * g.x;
;         xv[i].y += ov[i].y * rstd * g.y;
;         xv[i].z += ov[i].z * rstd * g.z;
;         xv[i].w += ov[i].w * rstd * g.w;
;         *reinterpret_cast<float4*>(p.out + rbase + i * 128) = xv[i];
;       }
;     }
;     const int nl = layer + 1;
;     if (nl < 4) {
;       float ss = 0.f;
; #pragma unroll
;       for (int i = 0; i < 8; ++i) ss += xv[i].x * xv[i].x + xv[i].y * xv[i].y + xv[i].z * xv[i].z + xv[i].w * xv[i].w;
;       ss = half_wave_sum(ss);
	v_pk_fma_f32 v[20:21], v[20:21], v[0:1], v[8:9]
	v_pk_fma_f32 v[22:23], v[16:17], v[2:3], v[10:11]
	global_store_dwordx4 v[42:43], v[20:23], off offset:1024
	global_load_dwordx4 v[0:3], v[34:35], off offset:1536
	v_pk_mul_f32 v[8:9], v[72:73], v[58:59] op_sel_hi:[0,1]
	v_pk_mul_f32 v[10:11], v[72:73], v[18:19] op_sel_hi:[0,1]
	s_waitcnt vmcnt(0)
	v_pk_fma_f32 v[16:17], v[8:9], v[0:1], v[12:13]
	v_pk_fma_f32 v[18:19], v[10:11], v[2:3], v[14:15]
	global_store_dwordx4 v[42:43], v[16:19], off offset:1536
	global_load_dwordx4 v[0:3], v[34:35], off offset:2048
	global_load_dwordx4 v[8:11], v[42:43], off offset:2048
	global_load_dwordx4 v[52:55], v[42:43], off offset:2560
	v_pk_mul_f32 v[12:13], v[72:73], v[60:61] op_sel_hi:[0,1]
	v_pk_mul_f32 v[14:15], v[72:73], v[62:63] op_sel_hi:[0,1]
	v_pk_mul_f32 v[60:61], v[72:73], v[68:69] op_sel_hi:[0,1]
	v_pk_mul_f32 v[62:63], v[72:73], v[70:71] op_sel_hi:[0,1]
	v_mov_b32_e32 v68, v23
	v_mov_b32_e32 v69, v19
	s_waitcnt vmcnt(1)
	v_pk_fma_f32 v[12:13], v[12:13], v[0:1], v[8:9]
	v_pk_fma_f32 v[14:15], v[14:15], v[2:3], v[10:11]
	global_store_dwordx4 v[42:43], v[12:15], off offset:2048
	global_load_dwordx4 v[0:3], v[34:35], off offset:2560
	v_pk_mul_f32 v[8:9], v[72:73], v[64:65] op_sel_hi:[0,1]
	v_pk_mul_f32 v[10:11], v[72:73], v[66:67] op_sel_hi:[0,1]
	v_mov_b32_e32 v64, v21
	v_mov_b32_e32 v65, v17
	v_mov_b32_e32 v66, v22
	v_mov_b32_e32 v67, v18
	s_waitcnt vmcnt(0)
	v_pk_fma_f32 v[8:9], v[8:9], v[0:1], v[52:53]
	v_pk_fma_f32 v[10:11], v[10:11], v[2:3], v[54:55]
	global_store_dwordx4 v[42:43], v[8:11], off offset:2560
	global_load_dwordx4 v[0:3], v[34:35], off offset:3072
	global_load_dwordx4 v[52:55], v[42:43], off offset:3072
	global_load_dwordx4 v[56:59], v[42:43], off offset:3584
	s_waitcnt vmcnt(1)
	v_pk_fma_f32 v[0:1], v[60:61], v[0:1], v[52:53]
	v_pk_fma_f32 v[2:3], v[62:63], v[2:3], v[54:55]
	global_store_dwordx4 v[42:43], v[0:3], off offset:3072
	global_load_dwordx4 v[52:55], v[34:35], off offset:3584
	v_pk_mul_f32 v[60:61], v[72:73], v[4:5] op_sel_hi:[0,1]
	v_pk_mul_f32 v[4:5], v[28:29], v[28:29]
	v_pk_mul_f32 v[62:63], v[30:31], v[30:31]
	v_add_f32_e32 v4, v4, v5
	v_add_f32_e32 v4, v62, v4
	v_add_f32_e32 v39, v63, v4
	v_pk_mul_f32 v[4:5], v[24:25], v[24:25]
	v_pk_mul_f32 v[62:63], v[26:27], v[26:27]
	v_add_f32_e32 v4, v4, v5
	v_add_f32_e32 v4, v4, v62
	v_add_f32_e32 v4, v4, v63
	v_add_f32_e32 v39, v39, v4
	v_mov_b32_e32 v62, v20
	v_mov_b32_e32 v63, v16
	s_waitcnt vmcnt(0)
	v_pk_fma_f32 v[4:5], v[6:7], v[52:53], v[56:57]
	v_pk_fma_f32 v[6:7], v[60:61], v[54:55], v[58:59]
	global_store_dwordx4 v[42:43], v[4:7], off offset:3584
	global_load_dwordx4 v[52:55], v[36:37], off
	v_pk_mul_f32 v[42:43], v[64:65], v[64:65]
	v_mov_b32_e32 v56, v13
	v_pk_fma_f32 v[42:43], v[62:63], v[62:63], v[42:43]
	v_mov_b32_e32 v57, v9
	v_pk_fma_f32 v[42:43], v[66:67], v[66:67], v[42:43]
	v_pk_mul_f32 v[56:57], v[56:57], v[56:57]
	v_pk_fma_f32 v[42:43], v[68:69], v[68:69], v[42:43]
	v_mov_b32_e32 v58, v14
	v_add_f32_e32 v39, v39, v42
	v_add_f32_e32 v39, v39, v43
	v_mov_b32_e32 v42, v12
	v_mov_b32_e32 v43, v8
	v_mov_b32_e32 v59, v10
	v_pk_fma_f32 v[42:43], v[42:43], v[42:43], v[56:57]
	v_mov_b32_e32 v60, v15
	v_mov_b32_e32 v61, v11
	v_pk_fma_f32 v[42:43], v[58:59], v[58:59], v[42:43]
	v_mov_b32_e32 v56, v1
	v_pk_fma_f32 v[42:43], v[60:61], v[60:61], v[42:43]
	v_mov_b32_e32 v57, v5
	v_add_f32_e32 v39, v39, v42
	v_add_f32_e32 v39, v39, v43
	v_mov_b32_e32 v42, v0
	v_mov_b32_e32 v43, v4
	v_pk_mul_f32 v[56:57], v[56:57], v[56:57]
	v_mov_b32_e32 v58, v2
	v_mov_b32_e32 v59, v6
	v_pk_fma_f32 v[42:43], v[42:43], v[42:43], v[56:57]
	v_mov_b32_e32 v60, v3
	v_mov_b32_e32 v61, v7
	v_pk_fma_f32 v[42:43], v[58:59], v[58:59], v[42:43]
	s_waitcnt vmcnt(0)
	v_mov_b32_e32 v57, v54
	v_pk_fma_f32 v[42:43], v[60:61], v[60:61], v[42:43]
	v_mov_b32_e32 v54, v53
	v_add_f32_e32 v39, v39, v42
	v_add_f32_e32 v39, v39, v43
	ds_bpermute_b32 v42, v44, v39
	v_mov_b32_e32 v43, v30
	v_mov_b32_e32 v30, v29
	v_mov_b32_e32 v56, v52
	s_waitcnt lgkmcnt(0)
	v_add_f32_e32 v39, v39, v42
	ds_bpermute_b32 v42, v45, v39
	s_waitcnt lgkmcnt(0)
	v_add_f32_e32 v39, v39, v42
	ds_bpermute_b32 v42, v46, v39
	s_waitcnt lgkmcnt(0)
	v_add_f32_e32 v39, v39, v42
	ds_bpermute_b32 v42, v47, v39
	s_waitcnt lgkmcnt(0)
	v_add_f32_e32 v39, v39, v42
	ds_bpermute_b32 v42, v48, v39
	s_waitcnt lgkmcnt(0)
; __device__ __forceinline__ unsigned pack2(float a, float b) { return (unsigned)f2bf(a) | ((unsigned)f2bf(b) << 16); }
; __device__ void norm_phase(const Params& p, int layer) {
;     ...
;       ss = half_wave_sum(ss);
;       float rstd = rsqrtf(ss * (1.f / 1024.f) + 1e-6f);
; #pragma unroll
;       for (int i = 0; i < 8; ++i) {
;         float4 g = *reinterpret_cast<const float4*>(p.g_pre + (size_t)nl * DM + l32 * 4 + i * 128);
;         uint2 o;
;         o.x = pack2(xv[i].x * rstd * g.x, xv[i].y * rstd * g.y);
;         o.y = pack2(xv[i].z * rstd * g.z, xv[i].w * rstd * g.w);
;         *reinterpret_cast<uint2*>(H + rbase + i * 128) = o;
;       }
	v_add_f32_e32 v39, v39, v42
	v_fmamk_f32 v39, v39, 0x3a800000, v49
	v_mul_f32_e32 v42, 0x4b800000, v39
	v_cmp_gt_f32_e32 vcc, s25, v39
	s_nop 1
	v_cndmask_b32_e32 v39, v39, v42, vcc
	v_rsq_f32_e32 v39, v39
	v_mov_b32_e32 v42, v28
	v_mul_f32_e32 v28, 0x45800000, v39
	v_cndmask_b32_e32 v28, v39, v28, vcc
	v_pk_mul_f32 v[30:31], v[30:31], v[28:29] op_sel_hi:[1,0]
	v_pk_mul_f32 v[42:43], v[42:43], v[28:29] op_sel_hi:[1,0]
	v_pk_mul_f32 v[30:31], v[54:55], v[30:31]
	v_pk_mul_f32 v[42:43], v[56:57], v[42:43]
	v_cvt_pk_bf16_f32 v31, 0, v31
	v_cvt_pk_bf16_f32 v29, 0, v43
	v_and_b32_e32 v31, 0xffff0000, v31
	v_or_b32_sdwa v31, v31, v29 dst_sel:DWORD dst_unused:UNUSED_PAD src0_sel:DWORD src1_sel:WORD_1
	v_cvt_pk_bf16_f32 v30, v42, v30
	global_store_dwordx2 v[40:41], v[30:31], off
	global_load_dwordx4 v[52:55], v[36:37], off offset:512
	v_mov_b32_e32 v30, v24
	v_mov_b32_e32 v31, v26
	v_mov_b32_e32 v26, v25
	v_pk_mul_f32 v[24:25], v[30:31], v[28:29] op_sel_hi:[1,0]
	v_pk_mul_f32 v[26:27], v[26:27], v[28:29] op_sel_hi:[1,0]
	v_cmp_lt_i32_e32 vcc, s27, v33
	s_or_b64 s[22:23], vcc, s[22:23]
	s_waitcnt vmcnt(0)
	v_mov_b32_e32 v31, v54
	v_mov_b32_e32 v54, v53
	v_mov_b32_e32 v30, v52
	v_pk_mul_f32 v[26:27], v[54:55], v[26:27]
	v_pk_mul_f32 v[24:25], v[30:31], v[24:25]
	v_and_b32_sdwa v29, v25, v50 dst_sel:DWORD dst_unused:UNUSED_PAD src0_sel:WORD_1 src1_sel:DWORD
	v_cvt_pk_bf16_f32 v25, v25, v27
	v_cvt_pk_bf16_f32 v24, v24, v26
	global_store_dwordx2 v[40:41], v[24:25], off offset:256
	global_load_dwordx4 v[24:27], v[36:37], off offset:1024
	v_mov_b32_e32 v30, v20
	v_mov_b32_e32 v31, v22
	v_mov_b32_e32 v22, v21
	v_pk_mul_f32 v[20:21], v[30:31], v[28:29] op_sel_hi:[1,0]
	v_pk_mul_f32 v[22:23], v[22:23], v[28:29] op_sel_hi:[1,0]
	s_waitcnt vmcnt(0)
	v_mov_b32_e32 v31, v26
	v_mov_b32_e32 v26, v25
	v_mov_b32_e32 v30, v24
	v_pk_mul_f32 v[22:23], v[22:23], v[26:27]
	v_pk_mul_f32 v[20:21], v[20:21], v[30:31]
	v_cvt_pk_bf16_f32 v21, v21, v23
	v_cvt_pk_bf16_f32 v20, v20, v22
	global_store_dwordx2 v[40:41], v[20:21], off offset:512
	global_load_dwordx4 v[20:23], v[36:37], off offset:1536
	v_mov_b32_e32 v24, v16
	v_mov_b32_e32 v25, v18
	v_mov_b32_e32 v18, v17
	v_pk_mul_f32 v[16:17], v[24:25], v[28:29] op_sel_hi:[1,0]
	v_pk_mul_f32 v[18:19], v[18:19], v[28:29] op_sel_hi:[1,0]
	s_waitcnt vmcnt(0)
	v_mov_b32_e32 v25, v22
	v_mov_b32_e32 v22, v21
	v_mov_b32_e32 v24, v20
	v_pk_mul_f32 v[18:19], v[18:19], v[22:23]
	v_pk_mul_f32 v[16:17], v[16:17], v[24:25]
	v_cvt_pk_bf16_f32 v17, v17, v19
	v_cvt_pk_bf16_f32 v16, v16, v18
	global_store_dwordx2 v[40:41], v[16:17], off offset:768
	global_load_dwordx4 v[16:19], v[36:37], off offset:2048
	v_mov_b32_e32 v20, v12
	v_mov_b32_e32 v21, v14
	v_mov_b32_e32 v14, v13
	v_pk_mul_f32 v[12:13], v[20:21], v[28:29] op_sel_hi:[1,0]
	v_pk_mul_f32 v[14:15], v[14:15], v[28:29] op_sel_hi:[1,0]
	s_waitcnt vmcnt(0)
	v_mov_b32_e32 v21, v18
	v_mov_b32_e32 v18, v17
	v_mov_b32_e32 v20, v16
	v_pk_mul_f32 v[14:15], v[14:15], v[18:19]
	v_pk_mul_f32 v[12:13], v[12:13], v[20:21]
	v_cvt_pk_bf16_f32 v13, v13, v15
	v_cvt_pk_bf16_f32 v12, v12, v14
	global_store_dwordx2 v[40:41], v[12:13], off offset:1024
	global_load_dwordx4 v[12:15], v[36:37], off offset:2560
	v_mov_b32_e32 v16, v8
	v_mov_b32_e32 v17, v10
	v_mov_b32_e32 v10, v9
	v_pk_mul_f32 v[8:9], v[16:17], v[28:29] op_sel_hi:[1,0]
	v_pk_mul_f32 v[10:11], v[10:11], v[28:29] op_sel_hi:[1,0]
	s_waitcnt vmcnt(0)
	v_mov_b32_e32 v17, v14
	v_mov_b32_e32 v14, v13
	v_mov_b32_e32 v16, v12
	v_pk_mul_f32 v[10:11], v[10:11], v[14:15]
	v_pk_mul_f32 v[8:9], v[8:9], v[16:17]
	v_and_b32_sdwa v14, v11, v50 dst_sel:DWORD dst_unused:UNUSED_PAD src0_sel:WORD_1 src1_sel:DWORD
	v_and_b32_sdwa v15, v10, v50 dst_sel:DWORD dst_unused:UNUSED_PAD src0_sel:WORD_1 src1_sel:DWORD
	v_cvt_pk_bf16_f32 v9, v9, v11
	v_cvt_pk_bf16_f32 v8, v8, v10
	global_store_dwordx2 v[40:41], v[8:9], off offset:1280
	global_load_dwordx4 v[8:11], v[36:37], off offset:3072
	v_mov_b32_e32 v12, v0
	v_mov_b32_e32 v13, v2
	v_mov_b32_e32 v2, v1
	v_pk_mul_f32 v[0:1], v[12:13], v[28:29] op_sel_hi:[1,0]
	v_pk_mul_f32 v[2:3], v[2:3], v[28:29] op_sel_hi:[1,0]
	s_waitcnt vmcnt(0)
	v_mov_b32_e32 v13, v10
	v_mov_b32_e32 v10, v9
	v_mov_b32_e32 v12, v8
	v_pk_mul_f32 v[2:3], v[2:3], v[10:11]
	v_pk_mul_f32 v[0:1], v[0:1], v[12:13]
	v_cvt_pk_bf16_f32 v1, v1, v3
	v_cvt_pk_bf16_f32 v0, v0, v2
	global_store_dwordx2 v[40:41], v[0:1], off offset:1536
	global_load_dwordx4 v[0:3], v[36:37], off offset:3584
	v_mov_b32_e32 v8, v4
	v_mov_b32_e32 v9, v6
	v_mov_b32_e32 v6, v5
	v_pk_mul_f32 v[4:5], v[8:9], v[28:29] op_sel_hi:[1,0]
	v_pk_mul_f32 v[6:7], v[6:7], v[28:29] op_sel_hi:[1,0]
	s_waitcnt vmcnt(0)
	v_mov_b32_e32 v9, v2
	v_mov_b32_e32 v2, v1
	v_mov_b32_e32 v8, v0
	v_pk_mul_f32 v[2:3], v[6:7], v[2:3]
	v_pk_mul_f32 v[0:1], v[4:5], v[8:9]
	v_cvt_pk_bf16_f32 v1, v1, v3
	v_cvt_pk_bf16_f32 v0, v0, v2
	global_store_dwordx2 v[40:41], v[0:1], off offset:1792
	s_andn2_b64 exec, exec, s[22:23]
	s_cbranch_execnz .LBB0_680
	s_or_b64 exec, exec, s[22:23]
	v_mov_b64_e32 v[10:11], s[28:29]

; template <int DH, int MODE>
; __device__ void attn_item(const Params& p, int layer, int b, int blk, int head, char* smem) {
;     ...
;   if (MODE == 0 && half == 0) linv_s[row] = 1.f / l_run;
;   __syncthreads();
;   {
;     constexpr int OST = DH + 4;
;     constexpr int CPR = DH / 8;
;     constexpr int NCH = 128 * CPR / 256;
;     float* Of = reinterpret_cast<float*>(smem);
;     uint4 gt[NCH];
; #pragma unroll
;     for (int i = 0; i < NCH; ++i) {
;       int q = tid + 256 * i, r = q / CPR, c = (q % CPR) * 8;
;       gt[i] = *reinterpret_cast<const uint4*>(P + (tq0 + r) * NP + gcol + c);
;     }
;     float lis[2][4];
; #pragma unroll
;     for (int m = 0; m < 2; ++m)
; #pragma unroll
;       for (int j = 0; j < 4; ++j) lis[m][j] = (MODE == 0) ? linv_s[wid * 32 + m * 16 + fq * 4 + j] : 1.f;
;     if (MODE == 0) __syncthreads();
; #pragma unroll
;     for (int m = 0; m < 2; ++m)
; #pragma unroll
;       for (int j = 0; j < 4; ++j) {
;         int r = wid * 32 + m * 16 + fq * 4 + j;
; #pragma unroll
;         for (int n = 0; n < NDT; ++n) Of[r * OST + n * 16 + fr] = o[m][n][j] * lis[m][j];
;       }
.LBB0_791:
	s_ashr_i32 s13, s86, 31
	s_add_u32 s12, s28, s86
	s_addc_u32 s13, s29, s13
	s_lshl_b32 s14, s83, 1
	s_add_u32 s16, s48, s14
	s_addc_u32 s17, s49, 0
	v_lshl_add_u64 v[2:3], s[20:21], 0, v[134:135]
	v_mov_b64_e32 v[4:5], s[16:17]
	v_mad_u64_u32 v[0:1], s[16:17], v2, s45, v[4:5]
	v_mad_i32_i24 v1, v3, s45, v1
	s_waitcnt vmcnt(12)
	v_lshl_add_u64 v[76:77], v[0:1], 0, v[138:139]
	v_add_u32_e32 v0, 0x100, v161
	v_ashrrev_i32_e32 v1, 31, v0
	v_lshrrev_b32_e32 v1, 28, v1
	v_add_u32_e32 v1, v0, v1
	v_ashrrev_i32_e32 v8, 4, v1
	v_and_b32_e32 v1, -16, v1
	s_waitcnt vmcnt(5)
	v_sub_u32_e32 v99, v0, v1
	v_lshlrev_b32_e32 v0, 3, v99
	v_ashrrev_i32_e32 v1, 31, v0
	s_waitcnt vmcnt(3)
	v_lshlrev_b64 v[92:93], 1, v[0:1]
	v_add_u32_e32 v0, 0x200, v161
	v_ashrrev_i32_e32 v1, 31, v0
	v_lshrrev_b32_e32 v1, 28, v1
	v_add_u32_e32 v1, v0, v1
	v_ashrrev_i32_e32 v9, 31, v8
	v_ashrrev_i32_e32 v94, 4, v1
	v_and_b32_e32 v1, -16, v1
	v_lshl_add_u64 v[10:11], s[20:21], 0, v[8:9]
	v_sub_u32_e32 v9, v0, v1
	v_lshlrev_b32_e32 v0, 3, v9
	v_ashrrev_i32_e32 v1, 31, v0
	v_lshlrev_b64 v[100:101], 1, v[0:1]
	v_add_u32_e32 v0, 0x300, v161
	v_ashrrev_i32_e32 v1, 31, v0
	v_lshrrev_b32_e32 v1, 28, v1
	v_add_u32_e32 v1, v0, v1
	v_ashrrev_i32_e32 v102, 4, v1
	v_and_b32_e32 v1, -16, v1
	v_sub_u32_e32 v128, v0, v1
	v_lshlrev_b32_e32 v0, 3, v128
	v_ashrrev_i32_e32 v1, 31, v0
	s_waitcnt vmcnt(0)
	v_lshlrev_b64 v[106:107], 1, v[0:1]
	v_add_u32_e32 v0, 0x400, v161
	v_ashrrev_i32_e32 v1, 31, v0
	v_lshrrev_b32_e32 v1, 28, v1
	v_add_u32_e32 v1, v0, v1
	v_ashrrev_i32_e32 v103, 31, v102
	v_ashrrev_i32_e32 v108, 4, v1
	v_and_b32_e32 v1, -16, v1
	v_lshl_add_u64 v[104:105], s[20:21], 0, v[102:103]
	v_sub_u32_e32 v103, v0, v1
	v_lshlrev_b32_e32 v0, 3, v103
	v_ashrrev_i32_e32 v1, 31, v0
	v_lshlrev_b64 v[112:113], 1, v[0:1]
	v_add_u32_e32 v0, 0x500, v161
	v_ashrrev_i32_e32 v1, 31, v0
	v_lshrrev_b32_e32 v1, 28, v1
	v_add_u32_e32 v1, v0, v1
	v_ashrrev_i32_e32 v109, 31, v108
	v_ashrrev_i32_e32 v114, 4, v1
	v_and_b32_e32 v1, -16, v1
	v_mad_u64_u32 v[6:7], s[16:17], v10, s45, v[4:5]
	v_ashrrev_i32_e32 v95, 31, v94
	v_lshl_add_u64 v[110:111], s[20:21], 0, v[108:109]
	v_sub_u32_e32 v109, v0, v1
	v_mad_i32_i24 v7, v11, s45, v7
	v_lshl_add_u64 v[96:97], s[20:21], 0, v[94:95]
	v_lshlrev_b32_e32 v0, 3, v109
	v_lshl_add_u64 v[78:79], v[6:7], 0, v[92:93]
	v_mad_u64_u32 v[6:7], s[16:17], v96, s45, v[4:5]
	v_ashrrev_i32_e32 v1, 31, v0
	v_mad_i32_i24 v7, v97, s45, v7
	v_lshlrev_b64 v[118:119], 1, v[0:1]
	v_add_u32_e32 v0, 0x600, v161
	v_lshl_add_u64 v[80:81], v[6:7], 0, v[100:101]
	v_mad_u64_u32 v[6:7], s[16:17], v104, s45, v[4:5]
	v_ashrrev_i32_e32 v1, 31, v0
	v_mad_i32_i24 v7, v105, s45, v7
	v_lshrrev_b32_e32 v1, 28, v1
	v_lshl_add_u64 v[82:83], v[6:7], 0, v[106:107]
	v_mad_u64_u32 v[6:7], s[16:17], v110, s45, v[4:5]
	v_ashrrev_i32_e32 v115, 31, v114
	v_add_u32_e32 v1, v0, v1
	v_mad_i32_i24 v7, v111, s45, v7
	v_lshl_add_u64 v[116:117], s[20:21], 0, v[114:115]
	v_ashrrev_i32_e32 v120, 4, v1
	v_and_b32_e32 v1, -16, v1
	v_lshl_add_u64 v[84:85], v[6:7], 0, v[112:113]
	v_mad_u64_u32 v[6:7], s[16:17], v116, s45, v[4:5]
	v_sub_u32_e32 v115, v0, v1
	v_ashrrev_i32_e32 v121, 31, v120
	v_mad_i32_i24 v7, v117, s45, v7
	v_lshlrev_b32_e32 v0, 3, v115
	v_lshl_add_u64 v[122:123], s[20:21], 0, v[120:121]
	v_lshl_add_u64 v[86:87], v[6:7], 0, v[118:119]
	v_mad_u64_u32 v[6:7], s[16:17], v122, s45, v[4:5]
	v_ashrrev_i32_e32 v1, 31, v0
	v_mad_i32_i24 v7, v123, s45, v7
	v_lshlrev_b64 v[124:125], 1, v[0:1]
	v_lshl_add_u64 v[0:1], v[6:7], 0, v[124:125]
	v_add_u32_e32 v6, 0x700, v161
	v_ashrrev_i32_e32 v7, 31, v6
	v_lshrrev_b32_e32 v7, 28, v7
	v_add_u32_e32 v7, v6, v7
	v_ashrrev_i32_e32 v126, 4, v7
	v_and_b32_e32 v7, -16, v7
	v_sub_u32_e32 v121, v6, v7
	v_lshlrev_b32_e32 v6, 3, v121
	v_ashrrev_i32_e32 v127, 31, v126
	v_lshl_add_u64 v[88:89], s[20:21], 0, v[126:127]
	v_ashrrev_i32_e32 v7, 31, v6
	v_mad_u64_u32 v[4:5], s[16:17], v88, s45, v[4:5]
	v_lshlrev_b64 v[90:91], 1, v[6:7]
	v_lshl_or_b32 v6, v137, 2, v130
	v_mad_i32_i24 v5, v89, s45, v5
	v_mul_lo_u32 v6, v6, s69
	v_lshl_add_u64 v[4:5], v[4:5], 0, v[90:91]
	v_lshl_add_u32 v95, v162, 2, v6
	s_barrier
	ds_write2_b32 v95, v12, v48 offset1:16
	ds_write2_b32 v95, v52, v56 offset0:32 offset1:48
	ds_write2_b32 v95, v60, v64 offset0:64 offset1:80
	ds_write2_b32 v95, v68, v72 offset0:96 offset1:112
	ds_write2_b32 v95, v13, v49 offset0:132 offset1:148
	ds_write2_b32 v95, v53, v57 offset0:164 offset1:180
	ds_write2_b32 v95, v61, v65 offset0:196 offset1:212
	ds_write2_b32 v95, v69, v73 offset0:228 offset1:244
	v_add_u32_e32 v12, 0x400, v95
	v_add_co_u32_e32 v4, vcc, s80, v4
	ds_write2_b32 v12, v14, v50 offset0:8 offset1:24
	ds_write2_b32 v12, v54, v58 offset0:40 offset1:56
	v_addc_co_u32_e32 v5, vcc, 0, v5, vcc
	global_load_dwordx4 v[4:7], v[4:5], off offset:512
	ds_write2_b32 v12, v62, v66 offset0:72 offset1:88
	ds_write2_b32 v12, v70, v74 offset0:104 offset1:120
	ds_write2_b32 v12, v15, v51 offset0:140 offset1:156
	ds_write2_b32 v12, v55, v59 offset0:172 offset1:188
	ds_write2_b32 v12, v63, v67 offset0:204 offset1:220
	ds_write2_b32 v12, v71, v75 offset0:236 offset1:252
	v_add_u32_e32 v12, 0x2000, v95
	ds_write2_b32 v12, v16, v20 offset0:64 offset1:80
	ds_write2_b32 v12, v24, v36 offset0:96 offset1:112
	ds_write2_b32 v12, v28, v40 offset0:128 offset1:144
	ds_write2_b32 v12, v44, v32 offset0:160 offset1:176
	ds_write2_b32 v12, v17, v21 offset0:196 offset1:212
	ds_write2_b32 v12, v25, v37 offset0:228 offset1:244
	v_add_u32_e32 v12, 0x2400, v95
	s_add_u32 s12, s12, s14
	ds_write2_b32 v12, v29, v41 offset0:4 offset1:20
	ds_write2_b32 v12, v45, v33 offset0:36 offset1:52
; __device__ __forceinline__ unsigned pack2(float a, float b) { return (unsigned)f2bf(a) | ((unsigned)f2bf(b) << 16); }
; __device__ __forceinline__ float bflo(unsigned w) { return __uint_as_float(w << 16); }
; __device__ __forceinline__ float bfhi(unsigned w) { return __uint_as_float(w & 0xffff0000u); }
; __device__ __forceinline__ float silu_f(float g) { return g / (1.f + __expf(-g)); }
; template <int DH, int MODE>
; __device__ void attn_item(const Params& p, int layer, int b, int blk, int head, char* smem) {
;     ...
;     uint4 gt[NCH];
; #pragma unroll
;     for (int i = 0; i < NCH; ++i) {
;       int q = tid + 256 * i, r = q / CPR, c = (q % CPR) * 8;
;       gt[i] = *reinterpret_cast<const uint4*>(P + (tq0 + r) * NP + gcol + c);
;     }
;     float lis[2][4];
; #pragma unroll
;     for (int m = 0; m < 2; ++m)
; #pragma unroll
;       for (int j = 0; j < 4; ++j) lis[m][j] = (MODE == 0) ? linv_s[wid * 32 + m * 16 + fq * 4 + j] : 1.f;
;     if (MODE == 0) __syncthreads();
; #pragma unroll
;     for (int m = 0; m < 2; ++m)
; #pragma unroll
;       for (int j = 0; j < 4; ++j) {
;         int r = wid * 32 + m * 16 + fq * 4 + j;
; #pragma unroll
;         for (int n = 0; n < NDT; ++n) Of[r * OST + n * 16 + fr] = o[m][n][j] * lis[m][j];
;       }
;     __syncthreads();
; #pragma unroll
;     for (int i = 0; i < NCH; ++i) {
;       int q = tid + 256 * i, r = q / CPR, c = (q % CPR) * 8;
;       float4 m0 = *reinterpret_cast<const float4*>(Of + r * OST + c);
;       float4 m1 = *reinterpret_cast<const float4*>(Of + r * OST + c + 4);
;       float mm[8] = {m0.x, m0.y, m0.z, m0.w, m1.x, m1.y, m1.z, m1.w};
;       unsigned gw[4] = {gt[i].x, gt[i].y, gt[i].z, gt[i].w};
;       unsigned ow[4];
; #pragma unroll
;       for (int e = 0; e < 4; ++e)
;         ow[e] = pack2(mm[2 * e] * silu_f(bflo(gw[e])), mm[2 * e + 1] * silu_f(bfhi(gw[e])));
	ds_write2_b32 v12, v18, v22 offset0:72 offset1:88
	ds_write2_b32 v12, v26, v38 offset0:104 offset1:120
	ds_write2_b32 v12, v30, v42 offset0:136 offset1:152
	ds_write2_b32 v12, v46, v34 offset0:168 offset1:184
	ds_write2_b32 v12, v19, v23 offset0:204 offset1:220
	ds_write2_b32 v12, v27, v39 offset0:236 offset1:252
	v_add_u32_e32 v12, 0x2800, v95
	s_addc_u32 s13, s13, 0
	ds_write2_b32 v12, v31, v43 offset0:12 offset1:28
	ds_write2_b32 v12, v47, v35 offset0:44 offset1:60
	v_mul_lo_u32 v12, v134, s69
	v_mov_b64_e32 v[14:15], s[12:13]
	v_lshl_add_u32 v98, v136, 2, v12
	v_mad_u64_u32 v[12:13], s[12:13], v2, s70, v[14:15]
	v_mul_lo_u32 v2, v8, s69
	v_mad_i32_i24 v13, v3, s70, v13
	v_lshl_add_u32 v95, v99, 5, v2
	v_mad_u64_u32 v[2:3], s[12:13], v10, s70, v[14:15]
	v_mad_i32_i24 v3, v11, s70, v3
	v_lshl_add_u64 v[26:27], v[2:3], 0, v[92:93]
	v_mul_lo_u32 v2, v94, s69
	v_lshl_add_u32 v93, v9, 5, v2
	v_mad_u64_u32 v[2:3], s[12:13], v96, s70, v[14:15]
	v_mad_i32_i24 v3, v97, s70, v3
	v_lshl_add_u64 v[20:21], v[2:3], 0, v[100:101]
	v_mul_lo_u32 v2, v102, s69
	v_lshl_add_u32 v92, v128, 5, v2
	v_mad_u64_u32 v[2:3], s[12:13], v104, s70, v[14:15]
	v_mad_i32_i24 v3, v105, s70, v3
	v_lshl_add_u64 v[16:17], v[2:3], 0, v[106:107]
	v_mul_lo_u32 v2, v108, s69
	v_lshl_add_u32 v75, v103, 5, v2
	v_mad_u64_u32 v[2:3], s[12:13], v110, s70, v[14:15]
	v_mad_i32_i24 v3, v111, s70, v3
	v_lshl_add_u64 v[30:31], v[12:13], 0, v[138:139]
	v_lshl_add_u64 v[12:13], v[2:3], 0, v[112:113]
	v_mul_lo_u32 v2, v114, s69
	v_lshl_add_u32 v74, v109, 5, v2
	v_mad_u64_u32 v[2:3], s[12:13], v116, s70, v[14:15]
	v_mad_i32_i24 v3, v117, s70, v3
	v_lshl_add_u64 v[10:11], v[2:3], 0, v[118:119]
	v_mul_lo_u32 v2, v120, s69
	v_lshl_add_u32 v73, v115, 5, v2
	v_mad_u64_u32 v[2:3], s[12:13], v122, s70, v[14:15]
	v_mad_i32_i24 v3, v123, s70, v3
	v_add_co_u32_e32 v0, vcc, s80, v0
	v_lshl_add_u64 v[8:9], v[2:3], 0, v[124:125]
	v_mul_lo_u32 v2, v126, s69
	v_addc_co_u32_e32 v1, vcc, 0, v1, vcc
	v_lshl_add_u32 v72, v121, 5, v2
	global_load_dwordx4 v[0:3], v[0:1], off offset:512
	v_mad_u64_u32 v[14:15], s[12:13], v88, s70, v[14:15]
	v_mad_i32_i24 v15, v89, s70, v15
	v_lshl_add_u64 v[14:15], v[14:15], 0, v[90:91]
	s_waitcnt vmcnt(1)
	v_lshlrev_b32_e32 v22, 16, v5
	v_lshlrev_b32_e32 v23, 16, v4
	v_mul_f32_e32 v18, 0xbfb8aa3b, v23
	v_mul_f32_e32 v19, 0xbfb8aa3b, v22
	v_exp_f32_e32 v18, v18
	v_exp_f32_e32 v19, v19
	v_and_b32_e32 v24, 0xffff0000, v5
	v_and_b32_e32 v28, 0xffff0000, v4
	v_mul_f32_e32 v4, 0xbfb8aa3b, v28
	v_pk_add_f32 v[18:19], v[18:19], 1.0 op_sel_hi:[1,0]
	v_exp_f32_e32 v4, v4
	v_and_b32_e32 v34, 0xffff0000, v6
	v_rcp_f32_e32 v19, v19
	s_nop 0
	v_mul_f32_e32 v19, v22, v19
	v_mul_f32_e32 v5, 0xbfb8aa3b, v24
	v_exp_f32_e32 v5, v5
	s_nop 0
	v_pk_add_f32 v[4:5], v[4:5], 1.0 op_sel_hi:[1,0]
	v_rcp_f32_e32 v18, v18
	s_nop 0
	v_mul_f32_e32 v18, v23, v18
	v_lshlrev_b32_e32 v33, 16, v6
	v_rcp_f32_e32 v23, v5
	s_nop 0
	v_mul_f32_e32 v23, v24, v23
	v_lshlrev_b32_e32 v32, 16, v7
	v_mul_f32_e32 v24, 0xbfb8aa3b, v33
	v_mul_f32_e32 v25, 0xbfb8aa3b, v32
	v_exp_f32_e32 v24, v24
	v_exp_f32_e32 v25, v25
	v_rcp_f32_e32 v22, v4
	s_nop 0
	v_mul_f32_e32 v22, v28, v22
	v_and_b32_e32 v28, 0xffff0000, v7
	v_pk_add_f32 v[4:5], v[24:25], 1.0 op_sel_hi:[1,0]
	v_mul_f32_e32 v6, 0xbfb8aa3b, v34
	v_exp_f32_e32 v6, v6
	s_waitcnt vmcnt(0)
	v_lshlrev_b32_e32 v40, 16, v3
	v_lshlrev_b32_e32 v41, 16, v2
	v_rcp_f32_e32 v25, v5
	s_nop 0
	v_mul_f32_e32 v25, v32, v25
	v_mul_f32_e32 v7, 0xbfb8aa3b, v28
	v_exp_f32_e32 v7, v7
	s_nop 0
	v_pk_add_f32 v[6:7], v[6:7], 1.0 op_sel_hi:[1,0]
	v_rcp_f32_e32 v24, v4
	s_nop 0
	v_mul_f32_e32 v24, v33, v24
	v_rcp_f32_e32 v29, v7
	s_nop 0
	v_mul_f32_e32 v29, v28, v29
	v_lshlrev_b32_e32 v32, 16, v1
	v_lshlrev_b32_e32 v36, 16, v0
	v_mul_f32_e32 v4, 0xbfb8aa3b, v36
	v_mul_f32_e32 v5, 0xbfb8aa3b, v32
	v_exp_f32_e32 v4, v4
	v_exp_f32_e32 v5, v5
	v_rcp_f32_e32 v28, v6
	s_nop 0
	v_mul_f32_e32 v28, v34, v28
	v_and_b32_e32 v6, 0xffff0000, v1
	v_pk_add_f32 v[4:5], v[4:5], 1.0 op_sel_hi:[1,0]
	v_and_b32_e32 v34, 0xffff0000, v0
	v_mul_f32_e32 v0, 0xbfb8aa3b, v34
	v_exp_f32_e32 v0, v0
	v_and_b32_e32 v42, 0xffff0000, v3
	v_rcp_f32_e32 v33, v5
	s_nop 0
	v_mul_f32_e32 v33, v32, v33
	v_mul_f32_e32 v1, 0xbfb8aa3b, v6
	v_exp_f32_e32 v1, v1
	s_nop 0
	v_pk_add_f32 v[0:1], v[0:1], 1.0 op_sel_hi:[1,0]
	v_rcp_f32_e32 v32, v4
	s_nop 0
	v_mul_f32_e32 v32, v36, v32
	v_rcp_f32_e32 v35, v1
	s_nop 0
	v_mul_f32_e32 v35, v6, v35
	v_add_co_u32_e64 v4, s[12:13], s80, v86
	s_nop 0
	s_nop 0
	v_addc_co_u32_e64 v5, s[12:13], 0, v87, s[12:13]
	global_load_dwordx4 v[4:7], v[4:5], off offset:512
	v_mul_f32_e32 v36, 0xbfb8aa3b, v41
	v_mul_f32_e32 v37, 0xbfb8aa3b, v40
	v_exp_f32_e32 v36, v36
	v_exp_f32_e32 v37, v37
	v_rcp_f32_e32 v1, v0
	s_nop 0
	v_mul_f32_e32 v34, v34, v1
	v_and_b32_e32 v43, 0xffff0000, v2
	v_pk_add_f32 v[0:1], v[36:37], 1.0 op_sel_hi:[1,0]
	v_mul_f32_e32 v2, 0xbfb8aa3b, v43
	v_exp_f32_e32 v2, v2
	v_rcp_f32_e32 v37, v1
	s_nop 0
	v_mul_f32_e32 v37, v40, v37
	v_mul_f32_e32 v3, 0xbfb8aa3b, v42
	v_exp_f32_e32 v3, v3
	s_nop 0
	v_pk_add_f32 v[38:39], v[2:3], 1.0 op_sel_hi:[1,0]
	v_rcp_f32_e32 v36, v0
	s_nop 0
	v_mul_f32_e32 v36, v41, v36
	v_rcp_f32_e32 v39, v39
	s_nop 0
	v_mul_f32_e32 v39, v42, v39
	v_add_co_u32_e64 v0, s[12:13], s80, v84
	s_waitcnt vmcnt(0)
; __device__ __forceinline__ unsigned pack2(float a, float b) { return (unsigned)f2bf(a) | ((unsigned)f2bf(b) << 16); }
; __device__ __forceinline__ float bflo(unsigned w) { return __uint_as_float(w << 16); }
; __device__ __forceinline__ float bfhi(unsigned w) { return __uint_as_float(w & 0xffff0000u); }
; __device__ __forceinline__ float silu_f(float g) { return g / (1.f + __expf(-g)); }
; template <int DH, int MODE>
; __device__ void attn_item(const Params& p, int layer, int b, int blk, int head, char* smem) {
;     ...
;     for (int i = 0; i < NCH; ++i) {
;       int q = tid + 256 * i, r = q / CPR, c = (q % CPR) * 8;
;       gt[i] = *reinterpret_cast<const uint4*>(P + (tq0 + r) * NP + gcol + c);
;     }
;     float lis[2][4];
; #pragma unroll
;     for (int m = 0; m < 2; ++m)
; #pragma unroll
;       for (int j = 0; j < 4; ++j) lis[m][j] = (MODE == 0) ? linv_s[wid * 32 + m * 16 + fq * 4 + j] : 1.f;
;     if (MODE == 0) __syncthreads();
; #pragma unroll
;     for (int m = 0; m < 2; ++m)
; #pragma unroll
;       for (int j = 0; j < 4; ++j) {
;         int r = wid * 32 + m * 16 + fq * 4 + j;
; #pragma unroll
;         for (int n = 0; n < NDT; ++n) Of[r * OST + n * 16 + fr] = o[m][n][j] * lis[m][j];
;       }
;     __syncthreads();
; #pragma unroll
;     for (int i = 0; i < NCH; ++i) {
;       int q = tid + 256 * i, r = q / CPR, c = (q % CPR) * 8;
;       float4 m0 = *reinterpret_cast<const float4*>(Of + r * OST + c);
;       float4 m1 = *reinterpret_cast<const float4*>(Of + r * OST + c + 4);
;       float mm[8] = {m0.x, m0.y, m0.z, m0.w, m1.x, m1.y, m1.z, m1.w};
;       unsigned gw[4] = {gt[i].x, gt[i].y, gt[i].z, gt[i].w};
;       unsigned ow[4];
; #pragma unroll
;       for (int e = 0; e < 4; ++e)
;         ow[e] = pack2(mm[2 * e] * silu_f(bflo(gw[e])), mm[2 * e + 1] * silu_f(bfhi(gw[e])));
	v_lshlrev_b32_e32 v46, 16, v5
	v_lshlrev_b32_e32 v47, 16, v4
	v_mul_f32_e32 v40, 0xbfb8aa3b, v47
	v_mul_f32_e32 v41, 0xbfb8aa3b, v46
	v_exp_f32_e32 v40, v40
	v_exp_f32_e32 v41, v41
	v_addc_co_u32_e64 v1, s[12:13], 0, v85, s[12:13]
	v_rcp_f32_e32 v38, v38
	s_nop 0
	v_mul_f32_e32 v38, v43, v38
	v_pk_add_f32 v[40:41], v[40:41], 1.0 op_sel_hi:[1,0]
	v_and_b32_e32 v42, 0xffff0000, v5
	global_load_dwordx4 v[0:3], v[0:1], off offset:512
	v_and_b32_e32 v48, 0xffff0000, v4
	v_mul_f32_e32 v4, 0xbfb8aa3b, v48
	v_rcp_f32_e32 v41, v41
	s_nop 0
	v_mul_f32_e32 v41, v46, v41
	v_exp_f32_e32 v4, v4
	v_mul_f32_e32 v5, 0xbfb8aa3b, v42
	v_exp_f32_e32 v5, v5
	s_nop 0
	v_pk_add_f32 v[4:5], v[4:5], 1.0 op_sel_hi:[1,0]
	v_rcp_f32_e32 v40, v40
	s_nop 0
	v_mul_f32_e32 v40, v47, v40
	v_lshlrev_b32_e32 v49, 16, v6
	v_rcp_f32_e32 v43, v5
	s_nop 0
	v_mul_f32_e32 v43, v42, v43
	v_lshlrev_b32_e32 v46, 16, v7
	v_mul_f32_e32 v44, 0xbfb8aa3b, v49
	v_mul_f32_e32 v45, 0xbfb8aa3b, v46
	v_exp_f32_e32 v44, v44
	v_exp_f32_e32 v45, v45
	v_rcp_f32_e32 v42, v4
	s_nop 0
	v_mul_f32_e32 v42, v48, v42
	v_and_b32_e32 v47, 0xffff0000, v7
	v_pk_add_f32 v[4:5], v[44:45], 1.0 op_sel_hi:[1,0]
	v_and_b32_e32 v48, 0xffff0000, v6
	v_mul_f32_e32 v6, 0xbfb8aa3b, v48
	v_exp_f32_e32 v6, v6
	v_rcp_f32_e32 v45, v5
	s_nop 0
	v_mul_f32_e32 v45, v46, v45
	v_mul_f32_e32 v7, 0xbfb8aa3b, v47
	v_exp_f32_e32 v7, v7
	s_nop 0
	v_pk_add_f32 v[6:7], v[6:7], 1.0 op_sel_hi:[1,0]
	v_rcp_f32_e32 v44, v4
	s_nop 0
	v_mul_f32_e32 v44, v49, v44
	v_rcp_f32_e32 v4, v7
	s_nop 0
	v_mul_f32_e32 v47, v47, v4
	s_waitcnt vmcnt(0)
	v_lshlrev_b32_e32 v50, 16, v1
	v_lshlrev_b32_e32 v51, 16, v0
	v_mul_f32_e32 v4, 0xbfb8aa3b, v51
	v_mul_f32_e32 v5, 0xbfb8aa3b, v50
	v_exp_f32_e32 v4, v4
	v_exp_f32_e32 v5, v5
	v_rcp_f32_e32 v46, v6
	s_nop 0
	v_mul_f32_e32 v46, v48, v46
	v_and_b32_e32 v6, 0xffff0000, v1
	v_pk_add_f32 v[4:5], v[4:5], 1.0 op_sel_hi:[1,0]
	v_and_b32_e32 v54, 0xffff0000, v0
	v_mul_f32_e32 v0, 0xbfb8aa3b, v54
	v_exp_f32_e32 v0, v0
	v_lshlrev_b32_e32 v58, 16, v2
	v_rcp_f32_e32 v49, v5
	s_nop 0
	v_mul_f32_e32 v49, v50, v49
	v_mul_f32_e32 v1, 0xbfb8aa3b, v6
	v_exp_f32_e32 v1, v1
	s_nop 0
	v_pk_add_f32 v[0:1], v[0:1], 1.0 op_sel_hi:[1,0]
	v_rcp_f32_e32 v48, v4
	s_nop 0
	v_mul_f32_e32 v48, v51, v48
	v_lshlrev_b32_e32 v57, 16, v3
	v_rcp_f32_e32 v51, v1
	s_nop 0
	v_mul_f32_e32 v51, v6, v51
	v_add_co_u32_e64 v4, s[12:13], s80, v82
	s_nop 0
	s_nop 0
	v_addc_co_u32_e64 v5, s[12:13], 0, v83, s[12:13]
	global_load_dwordx4 v[4:7], v[4:5], off offset:512
	v_mul_f32_e32 v50, 0xbfb8aa3b, v58
	v_exp_f32_e32 v52, v50
	v_mul_f32_e32 v50, 0xbfb8aa3b, v57
	v_exp_f32_e32 v53, v50
	v_rcp_f32_e32 v50, v0
	s_nop 0
	v_mul_f32_e32 v50, v54, v50
	v_and_b32_e32 v56, 0xffff0000, v3
	v_pk_add_f32 v[0:1], v[52:53], 1.0 op_sel_hi:[1,0]
	v_and_b32_e32 v59, 0xffff0000, v2
	v_mul_f32_e32 v2, 0xbfb8aa3b, v59
	v_exp_f32_e32 v2, v2
	v_rcp_f32_e32 v53, v1
	s_nop 0
	v_mul_f32_e32 v53, v57, v53
	v_mul_f32_e32 v3, 0xbfb8aa3b, v56
	v_exp_f32_e32 v3, v3
	s_nop 0
	v_pk_add_f32 v[54:55], v[2:3], 1.0 op_sel_hi:[1,0]
	v_rcp_f32_e32 v52, v0
	s_nop 0
	v_mul_f32_e32 v52, v58, v52
	v_rcp_f32_e32 v55, v55
	s_nop 0
	v_mul_f32_e32 v55, v56, v55
	v_add_co_u32_e64 v0, s[12:13], s80, v80
	s_waitcnt vmcnt(0)
	v_lshlrev_b32_e32 v62, 16, v5
	v_lshlrev_b32_e32 v63, 16, v4
	v_mul_f32_e32 v56, 0xbfb8aa3b, v63
	v_mul_f32_e32 v57, 0xbfb8aa3b, v62
	v_exp_f32_e32 v56, v56
	v_exp_f32_e32 v57, v57
	v_addc_co_u32_e64 v1, s[12:13], 0, v81, s[12:13]
	v_rcp_f32_e32 v54, v54
	s_nop 0
	v_mul_f32_e32 v54, v59, v54
	v_pk_add_f32 v[56:57], v[56:57], 1.0 op_sel_hi:[1,0]
	v_and_b32_e32 v58, 0xffff0000, v5
	global_load_dwordx4 v[0:3], v[0:1], off offset:512
	v_and_b32_e32 v64, 0xffff0000, v4
	v_mul_f32_e32 v4, 0xbfb8aa3b, v64
	v_rcp_f32_e32 v57, v57
	s_nop 0
	v_mul_f32_e32 v57, v62, v57
	v_exp_f32_e32 v4, v4
	v_mul_f32_e32 v5, 0xbfb8aa3b, v58
	v_exp_f32_e32 v5, v5
	s_nop 0
	v_pk_add_f32 v[4:5], v[4:5], 1.0 op_sel_hi:[1,0]
	v_rcp_f32_e32 v56, v56
	s_nop 0
	v_mul_f32_e32 v56, v63, v56
	v_lshlrev_b32_e32 v65, 16, v6
	v_rcp_f32_e32 v59, v5
	s_nop 0
	v_mul_f32_e32 v59, v58, v59
	v_lshlrev_b32_e32 v62, 16, v7
	v_mul_f32_e32 v60, 0xbfb8aa3b, v65
	v_mul_f32_e32 v61, 0xbfb8aa3b, v62
	v_exp_f32_e32 v60, v60
	v_exp_f32_e32 v61, v61
	v_rcp_f32_e32 v58, v4
	s_nop 0
	v_mul_f32_e32 v58, v64, v58
	v_and_b32_e32 v63, 0xffff0000, v7
	v_pk_add_f32 v[4:5], v[60:61], 1.0 op_sel_hi:[1,0]
	v_and_b32_e32 v64, 0xffff0000, v6
	v_mul_f32_e32 v6, 0xbfb8aa3b, v64
	v_exp_f32_e32 v6, v6
	v_rcp_f32_e32 v61, v5
	s_nop 0
	v_mul_f32_e32 v61, v62, v61
	v_mul_f32_e32 v7, 0xbfb8aa3b, v63
	v_exp_f32_e32 v7, v7
	s_nop 0
	v_pk_add_f32 v[6:7], v[6:7], 1.0 op_sel_hi:[1,0]
	v_rcp_f32_e32 v60, v4
	s_nop 0
	v_mul_f32_e32 v60, v65, v60
	v_rcp_f32_e32 v4, v7
	s_nop 0
	v_mul_f32_e32 v63, v63, v4
	s_waitcnt vmcnt(0)
	v_lshlrev_b32_e32 v66, 16, v1
	v_lshlrev_b32_e32 v67, 16, v0
	v_mul_f32_e32 v4, 0xbfb8aa3b, v67
	v_mul_f32_e32 v5, 0xbfb8aa3b, v66
	v_exp_f32_e32 v4, v4
	v_exp_f32_e32 v5, v5
	v_and_b32_e32 v68, 0xffff0000, v1
	v_rcp_f32_e32 v62, v6
	s_nop 0
	v_mul_f32_e32 v62, v64, v62
	v_pk_add_f32 v[4:5], v[4:5], 1.0 op_sel_hi:[1,0]
	v_and_b32_e32 v69, 0xffff0000, v0
	v_mul_f32_e32 v0, 0xbfb8aa3b, v69
	v_exp_f32_e32 v6, v0
	v_and_b32_e32 v80, 0xffff0000, v2
	v_rcp_f32_e32 v1, v5
	s_nop 0
	v_mul_f32_e32 v1, v66, v1
	v_mul_f32_e32 v7, 0xbfb8aa3b, v68
	v_exp_f32_e32 v7, v7
	s_nop 0
	v_pk_add_f32 v[64:65], v[6:7], 1.0 op_sel_hi:[1,0]
	v_rcp_f32_e32 v0, v4
	s_nop 0
	v_mul_f32_e32 v0, v67, v0
	v_rcp_f32_e32 v65, v65
	s_nop 0
	v_mul_f32_e32 v65, v68, v65
	v_add_co_u32_e64 v4, s[12:13], s80, v78
	s_nop 0
	s_nop 0
	v_addc_co_u32_e64 v5, s[12:13], 0, v79, s[12:13]
	global_load_dwordx4 v[4:7], v[4:5], off offset:512
	v_lshlrev_b32_e32 v78, 16, v3
	v_lshlrev_b32_e32 v79, 16, v2
	v_mul_f32_e32 v66, 0xbfb8aa3b, v79
	v_mul_f32_e32 v67, 0xbfb8aa3b, v78
	v_exp_f32_e32 v66, v66
	v_exp_f32_e32 v67, v67
	v_and_b32_e32 v70, 0xffff0000, v3
	v_rcp_f32_e32 v64, v64
	s_nop 0
	v_mul_f32_e32 v64, v69, v64
	v_pk_add_f32 v[66:67], v[66:67], 1.0 op_sel_hi:[1,0]
	v_mul_f32_e32 v2, 0xbfb8aa3b, v80
	v_exp_f32_e32 v68, v2
	v_mul_f32_e32 v69, 0xbfb8aa3b, v70
	v_exp_f32_e32 v69, v69
	v_rcp_f32_e32 v3, v67
	s_nop 0
	v_mul_f32_e32 v3, v78, v3
	v_pk_add_f32 v[68:69], v[68:69], 1.0 op_sel_hi:[1,0]
	v_rcp_f32_e32 v2, v66
	s_nop 0
	v_mul_f32_e32 v2, v79, v2
	v_rcp_f32_e32 v67, v69
	s_nop 0
	v_mul_f32_e32 v67, v70, v67
	v_add_co_u32_e64 v70, s[12:13], s80, v76
	s_nop 0
	s_nop 0
	v_addc_co_u32_e64 v71, s[12:13], 0, v77, s[12:13]
	global_load_dwordx4 v[76:79], v[70:71], off offset:512
	v_rcp_f32_e32 v66, v68
	s_nop 0
	v_mul_f32_e32 v66, v80, v66
	s_waitcnt vmcnt(1)
	v_lshlrev_b32_e32 v82, 16, v5
	v_lshlrev_b32_e32 v83, 16, v4
	v_mul_f32_e32 v70, 0xbfb8aa3b, v83
	v_mul_f32_e32 v71, 0xbfb8aa3b, v82
	v_exp_f32_e32 v70, v70
	v_exp_f32_e32 v71, v71
	v_and_b32_e32 v80, 0xffff0000, v5
	v_and_b32_e32 v84, 0xffff0000, v4
	v_mul_f32_e32 v4, 0xbfb8aa3b, v84
	v_pk_add_f32 v[68:69], v[70:71], 1.0 op_sel_hi:[1,0]
	v_exp_f32_e32 v70, v4
	s_waitcnt lgkmcnt(0)
	s_barrier
; __device__ __forceinline__ unsigned pack2(float a, float b) { return (unsigned)f2bf(a) | ((unsigned)f2bf(b) << 16); }
; __device__ __forceinline__ float bflo(unsigned w) { return __uint_as_float(w << 16); }
; __device__ __forceinline__ float bfhi(unsigned w) { return __uint_as_float(w & 0xffff0000u); }
; __device__ __forceinline__ float silu_f(float g) { return g / (1.f + __expf(-g)); }
; template <int DH, int MODE>
; __device__ void attn_item(const Params& p, int layer, int b, int blk, int head, char* smem) {
;     ...
; #pragma unroll
;     for (int i = 0; i < NCH; ++i) {
;       int q = tid + 256 * i, r = q / CPR, c = (q % CPR) * 8;
;       float4 m0 = *reinterpret_cast<const float4*>(Of + r * OST + c);
;       float4 m1 = *reinterpret_cast<const float4*>(Of + r * OST + c + 4);
;       float mm[8] = {m0.x, m0.y, m0.z, m0.w, m1.x, m1.y, m1.z, m1.w};
;       unsigned gw[4] = {gt[i].x, gt[i].y, gt[i].z, gt[i].w};
;       unsigned ow[4];
; #pragma unroll
;       for (int e = 0; e < 4; ++e)
;         ow[e] = pack2(mm[2 * e] * silu_f(bflo(gw[e])), mm[2 * e + 1] * silu_f(bfhi(gw[e])));
;       *reinterpret_cast<uint4*>(Y + (tq0 + r) * YW + ycol + c) = make_uint4(ow[0], ow[1], ow[2], ow[3]);
	v_mul_f32_e32 v71, 0xbfb8aa3b, v80
	v_exp_f32_e32 v71, v71
	v_rcp_f32_e32 v5, v69
	s_nop 0
	v_mul_f32_e32 v5, v82, v5
	v_pk_add_f32 v[70:71], v[70:71], 1.0 op_sel_hi:[1,0]
	v_rcp_f32_e32 v4, v68
	s_nop 0
	v_mul_f32_e32 v4, v83, v4
	v_rcp_f32_e32 v69, v71
	s_nop 0
	v_mul_f32_e32 v69, v80, v69
	v_lshlrev_b32_e32 v82, 16, v7
	v_lshlrev_b32_e32 v85, 16, v6
	v_mul_f32_e32 v80, 0xbfb8aa3b, v85
	v_mul_f32_e32 v81, 0xbfb8aa3b, v82
	v_exp_f32_e32 v80, v80
	v_exp_f32_e32 v81, v81
	v_rcp_f32_e32 v68, v70
	s_nop 0
	v_mul_f32_e32 v68, v84, v68
	v_and_b32_e32 v83, 0xffff0000, v7
	v_pk_add_f32 v[70:71], v[80:81], 1.0 op_sel_hi:[1,0]
	v_and_b32_e32 v84, 0xffff0000, v6
	v_mul_f32_e32 v6, 0xbfb8aa3b, v84
	v_exp_f32_e32 v80, v6
	s_waitcnt vmcnt(0)
	v_and_b32_e32 v94, 0xffff0000, v78
	v_mul_f32_e32 v81, 0xbfb8aa3b, v83
	v_exp_f32_e32 v81, v81
	v_rcp_f32_e32 v7, v71
	s_nop 0
	v_mul_f32_e32 v7, v82, v7
	v_pk_add_f32 v[80:81], v[80:81], 1.0 op_sel_hi:[1,0]
	v_rcp_f32_e32 v6, v70
	s_nop 0
	v_mul_f32_e32 v6, v85, v6
	v_rcp_f32_e32 v71, v81
	s_nop 0
	v_mul_f32_e32 v71, v83, v71
	v_lshlrev_b32_e32 v86, 16, v77
	v_lshlrev_b32_e32 v87, 16, v76
	v_mul_f32_e32 v82, 0xbfb8aa3b, v87
	v_mul_f32_e32 v83, 0xbfb8aa3b, v86
	v_exp_f32_e32 v82, v82
	v_exp_f32_e32 v83, v83
	v_rcp_f32_e32 v70, v80
	s_nop 0
	v_mul_f32_e32 v70, v84, v70
	v_and_b32_e32 v88, 0xffff0000, v77
	v_pk_add_f32 v[80:81], v[82:83], 1.0 op_sel_hi:[1,0]
	v_and_b32_e32 v83, 0xffff0000, v76
	v_mul_f32_e32 v76, 0xbfb8aa3b, v83
	v_exp_f32_e32 v76, v76
	v_rcp_f32_e32 v85, v81
	s_nop 0
	v_mul_f32_e32 v85, v86, v85
	v_mul_f32_e32 v77, 0xbfb8aa3b, v88
	v_exp_f32_e32 v77, v77
	s_nop 0
	v_pk_add_f32 v[76:77], v[76:77], 1.0 op_sel_hi:[1,0]
	v_rcp_f32_e32 v84, v80
	s_nop 0
	v_mul_f32_e32 v84, v87, v84
	v_rcp_f32_e32 v87, v77
	s_nop 0
	v_mul_f32_e32 v87, v88, v87
	v_lshlrev_b32_e32 v90, 16, v78
	v_lshlrev_b32_e32 v82, 16, v79
	v_mul_f32_e32 v80, 0xbfb8aa3b, v90
	v_mul_f32_e32 v81, 0xbfb8aa3b, v82
	v_exp_f32_e32 v80, v80
	v_exp_f32_e32 v81, v81
	v_rcp_f32_e32 v86, v76
	s_nop 0
	v_mul_f32_e32 v86, v83, v86
	v_and_b32_e32 v83, 0xffff0000, v79
	v_pk_add_f32 v[76:77], v[80:81], 1.0 op_sel_hi:[1,0]
	v_mul_f32_e32 v78, 0xbfb8aa3b, v94
	v_exp_f32_e32 v78, v78
	v_rcp_f32_e32 v89, v77
	s_nop 0
	v_mul_f32_e32 v89, v82, v89
	v_mul_f32_e32 v79, 0xbfb8aa3b, v83
	v_exp_f32_e32 v79, v79
	s_nop 0
	v_pk_add_f32 v[80:81], v[78:79], 1.0 op_sel_hi:[1,0]
	v_rcp_f32_e32 v88, v76
	s_nop 0
	v_mul_f32_e32 v88, v90, v88
	v_rcp_f32_e32 v91, v81
	s_nop 0
	v_mul_f32_e32 v91, v83, v91
	ds_read_b128 v[76:79], v98
	v_rcp_f32_e32 v90, v80
	s_nop 0
	v_mul_f32_e32 v90, v94, v90
	ds_read_b128 v[80:83], v98 offset:16
	v_add_co_u32_e32 v30, vcc, s77, v30
	s_waitcnt lgkmcnt(1)
	v_mov_b32_e32 v96, v76
	v_mov_b32_e32 v97, v78
	v_pk_mul_f32 v[84:85], v[84:85], v[96:97]
	v_mov_b32_e32 v78, v77
	v_pk_mul_f32 v[76:77], v[86:87], v[78:79]
	v_cvt_pk_bf16_f32 v77, v85, v77
	v_cvt_pk_bf16_f32 v76, v84, v76
	s_waitcnt lgkmcnt(0)
	v_mov_b32_e32 v78, v80
	v_mov_b32_e32 v79, v82
	v_pk_mul_f32 v[78:79], v[88:89], v[78:79]
	v_mov_b32_e32 v82, v81
	v_pk_mul_f32 v[80:81], v[90:91], v[82:83]
	v_cvt_pk_bf16_f32 v79, v79, v81
	v_cvt_pk_bf16_f32 v78, v78, v80
	ds_read_b128 v[80:83], v95
	v_addc_co_u32_e32 v31, vcc, 0, v31, vcc
	global_store_dwordx4 v[30:31], v[76:79], off offset:2048
	s_nop 0
	ds_read_b128 v[76:79], v95 offset:16
	s_waitcnt lgkmcnt(1)
	v_mov_b32_e32 v30, v80
	v_mov_b32_e32 v31, v82
	v_pk_mul_f32 v[4:5], v[4:5], v[30:31]
	v_mov_b32_e32 v82, v81
	v_pk_mul_f32 v[30:31], v[68:69], v[82:83]
	v_cvt_pk_bf16_f32 v5, v5, v31
	v_cvt_pk_bf16_f32 v4, v4, v30
	s_waitcnt lgkmcnt(0)
	v_mov_b32_e32 v30, v76
	v_mov_b32_e32 v31, v78
	v_pk_mul_f32 v[6:7], v[6:7], v[30:31]
	v_mov_b32_e32 v78, v77
	v_pk_mul_f32 v[30:31], v[70:71], v[78:79]
	ds_read_b128 v[68:71], v93
	v_add_co_u32_e32 v26, vcc, s77, v26
	v_cvt_pk_bf16_f32 v7, v7, v31
	v_cvt_pk_bf16_f32 v6, v6, v30
	v_addc_co_u32_e32 v27, vcc, 0, v27, vcc
	global_store_dwordx4 v[26:27], v[4:7], off offset:2048
	s_waitcnt lgkmcnt(0)
; __device__ __forceinline__ unsigned pack2(float a, float b) { return (unsigned)f2bf(a) | ((unsigned)f2bf(b) << 16); }
; __device__ __forceinline__ float bflo(unsigned w) { return __uint_as_float(w << 16); }
; __device__ __forceinline__ float bfhi(unsigned w) { return __uint_as_float(w & 0xffff0000u); }
; __device__ __forceinline__ float silu_f(float g) { return g / (1.f + __expf(-g)); }
; template <int DH, int MODE>
; __device__ void attn_item(const Params& p, int layer, int b, int blk, int head, char* smem) {
;     ...
; #pragma unroll
;     for (int i = 0; i < NCH; ++i) {
;       int q = tid + 256 * i, r = q / CPR, c = (q % CPR) * 8;
;       float4 m0 = *reinterpret_cast<const float4*>(Of + r * OST + c);
;       float4 m1 = *reinterpret_cast<const float4*>(Of + r * OST + c + 4);
;       float mm[8] = {m0.x, m0.y, m0.z, m0.w, m1.x, m1.y, m1.z, m1.w};
;       unsigned gw[4] = {gt[i].x, gt[i].y, gt[i].z, gt[i].w};
;       unsigned ow[4];
; #pragma unroll
;       for (int e = 0; e < 4; ++e)
;         ow[e] = pack2(mm[2 * e] * silu_f(bflo(gw[e])), mm[2 * e + 1] * silu_f(bfhi(gw[e])));
;       *reinterpret_cast<uint4*>(Y + (tq0 + r) * YW + ycol + c) = make_uint4(ow[0], ow[1], ow[2], ow[3]);
;     }
;   }
;   __syncthreads();
	v_mov_b32_e32 v26, v68
	v_mov_b32_e32 v27, v70
	ds_read_b128 v[4:7], v93 offset:16
	v_pk_mul_f32 v[0:1], v[0:1], v[26:27]
	v_mov_b32_e32 v70, v69
	v_pk_mul_f32 v[26:27], v[64:65], v[70:71]
	v_cvt_pk_bf16_f32 v1, v1, v27
	v_cvt_pk_bf16_f32 v0, v0, v26
	s_waitcnt lgkmcnt(0)
	v_mov_b32_e32 v26, v4
	v_mov_b32_e32 v27, v6
	v_pk_mul_f32 v[2:3], v[2:3], v[26:27]
	v_mov_b32_e32 v6, v5
	v_pk_mul_f32 v[4:5], v[66:67], v[6:7]
	v_cvt_pk_bf16_f32 v3, v3, v5
	v_cvt_pk_bf16_f32 v2, v2, v4
	ds_read_b128 v[4:7], v92
	v_add_co_u32_e32 v20, vcc, s77, v20
	s_nop 1
	v_addc_co_u32_e32 v21, vcc, 0, v21, vcc
	global_store_dwordx4 v[20:21], v[0:3], off offset:2048
	s_waitcnt lgkmcnt(0)
	v_mov_b32_e32 v20, v4
	v_mov_b32_e32 v21, v6
	ds_read_b128 v[0:3], v92 offset:16
	v_pk_mul_f32 v[20:21], v[56:57], v[20:21]
	v_mov_b32_e32 v6, v5
	v_pk_mul_f32 v[4:5], v[58:59], v[6:7]
	v_cvt_pk_bf16_f32 v5, v21, v5
	v_cvt_pk_bf16_f32 v4, v20, v4
	s_waitcnt lgkmcnt(0)
	v_mov_b32_e32 v6, v0
	v_mov_b32_e32 v7, v2
	v_pk_mul_f32 v[6:7], v[60:61], v[6:7]
	v_mov_b32_e32 v2, v1
	v_pk_mul_f32 v[0:1], v[62:63], v[2:3]
	v_cvt_pk_bf16_f32 v7, v7, v1
	v_cvt_pk_bf16_f32 v6, v6, v0
	ds_read_b128 v[0:3], v75
	v_add_co_u32_e32 v16, vcc, s77, v16
	s_nop 1
	v_addc_co_u32_e32 v17, vcc, 0, v17, vcc
	global_store_dwordx4 v[16:17], v[4:7], off offset:2048
	s_waitcnt lgkmcnt(0)
	v_mov_b32_e32 v16, v0
	v_mov_b32_e32 v17, v2
	ds_read_b128 v[4:7], v75 offset:16
	v_pk_mul_f32 v[16:17], v[48:49], v[16:17]
	v_mov_b32_e32 v2, v1
	v_pk_mul_f32 v[0:1], v[50:51], v[2:3]
	v_cvt_pk_bf16_f32 v1, v17, v1
	v_cvt_pk_bf16_f32 v0, v16, v0
	s_waitcnt lgkmcnt(0)
	v_mov_b32_e32 v2, v4
	v_mov_b32_e32 v3, v6
	v_pk_mul_f32 v[2:3], v[52:53], v[2:3]
	v_mov_b32_e32 v6, v5
	v_pk_mul_f32 v[4:5], v[54:55], v[6:7]
	v_cvt_pk_bf16_f32 v3, v3, v5
	v_cvt_pk_bf16_f32 v2, v2, v4
	ds_read_b128 v[4:7], v74
	v_add_co_u32_e32 v12, vcc, s77, v12
	s_nop 1
	v_addc_co_u32_e32 v13, vcc, 0, v13, vcc
	global_store_dwordx4 v[12:13], v[0:3], off offset:2048
	s_waitcnt lgkmcnt(0)
	v_mov_b32_e32 v12, v4
	v_mov_b32_e32 v13, v6
	ds_read_b128 v[0:3], v74 offset:16
	v_pk_mul_f32 v[12:13], v[40:41], v[12:13]
	v_mov_b32_e32 v6, v5
	v_pk_mul_f32 v[4:5], v[42:43], v[6:7]
	v_cvt_pk_bf16_f32 v5, v13, v5
	v_cvt_pk_bf16_f32 v4, v12, v4
	s_waitcnt lgkmcnt(0)
	v_mov_b32_e32 v6, v0
	v_mov_b32_e32 v7, v2
	v_pk_mul_f32 v[6:7], v[44:45], v[6:7]
	v_mov_b32_e32 v2, v1
	v_pk_mul_f32 v[0:1], v[46:47], v[2:3]
	v_cvt_pk_bf16_f32 v7, v7, v1
	v_cvt_pk_bf16_f32 v6, v6, v0
	ds_read_b128 v[0:3], v73
	v_add_co_u32_e32 v10, vcc, s77, v10
	s_nop 1
	v_addc_co_u32_e32 v11, vcc, 0, v11, vcc
	global_store_dwordx4 v[10:11], v[4:7], off offset:2048
	s_waitcnt lgkmcnt(0)
	v_mov_b32_e32 v10, v0
	v_mov_b32_e32 v11, v2
	ds_read_b128 v[4:7], v73 offset:16
	v_pk_mul_f32 v[10:11], v[32:33], v[10:11]
	v_mov_b32_e32 v2, v1
	v_pk_mul_f32 v[0:1], v[34:35], v[2:3]
	v_cvt_pk_bf16_f32 v1, v11, v1
	v_cvt_pk_bf16_f32 v0, v10, v0
	s_waitcnt lgkmcnt(0)
	v_mov_b32_e32 v2, v4
	v_mov_b32_e32 v3, v6
	v_pk_mul_f32 v[2:3], v[36:37], v[2:3]
	v_mov_b32_e32 v6, v5
	v_pk_mul_f32 v[4:5], v[38:39], v[6:7]
	v_cvt_pk_bf16_f32 v3, v3, v5
	v_cvt_pk_bf16_f32 v2, v2, v4
	ds_read_b128 v[4:7], v72
	v_add_co_u32_e32 v8, vcc, s77, v8
	s_nop 1
	v_addc_co_u32_e32 v9, vcc, 0, v9, vcc
	global_store_dwordx4 v[8:9], v[0:3], off offset:2048
	s_waitcnt lgkmcnt(0)
	v_mov_b32_e32 v8, v4
	v_mov_b32_e32 v9, v6
	ds_read_b128 v[0:3], v72 offset:16
	v_pk_mul_f32 v[8:9], v[18:19], v[8:9]
	v_mov_b32_e32 v6, v5
	v_pk_mul_f32 v[4:5], v[22:23], v[6:7]
	v_cvt_pk_bf16_f32 v5, v9, v5
	v_cvt_pk_bf16_f32 v4, v8, v4
	s_waitcnt lgkmcnt(0)
	v_mov_b32_e32 v6, v0
	v_mov_b32_e32 v7, v2
	v_pk_mul_f32 v[6:7], v[24:25], v[6:7]
	v_mov_b32_e32 v2, v1
	v_pk_mul_f32 v[0:1], v[28:29], v[2:3]
	v_cvt_pk_bf16_f32 v6, v6, v0
	v_add_co_u32_e32 v0, vcc, 0x184a1000, v14
	v_cvt_pk_bf16_f32 v7, v7, v1
	s_nop 0
	v_addc_co_u32_e32 v1, vcc, 0, v15, vcc
	global_store_dwordx4 v[0:1], v[4:7], off offset:2048
	s_barrier

; #define MFMA16(a, b, c) __builtin_amdgcn_mfma_f32_16x16x32_bf16(a, b, c, 0, 0, 0)
; __device__ void gmlp_item(const Params& p, int layer, int b, int n, int g, char* smem) {
;     ...
; #pragma unroll 2
;   for (int i = 0; i < 8; ++i) {
;     int q = tid + 256 * i;
;     int t = q >> 4, cch = q & 15;
;     uint4 v = *reinterpret_cast<const uint4*>(Ws + (size_t)g * 16384 + t * 128 + cch * 8);
;     *reinterpret_cast<uint4*>(smem + (cch >> 2) * 8192 + t * 64 + (cch & 3) * 16) = v;
;   }
;   __syncthreads();
;   f32x4 acc[4][4];
; #pragma unroll
;   for (int m = 0; m < 4; ++m)
; #pragma unroll
;     for (int nn = 0; nn < 4; ++nn) acc[m][nn] = f32x4{0.f, 0.f, 0.f, 0.f};
; #pragma unroll
;   for (int ks = 0; ks < 4; ++ks) {
;     bf16x8 a[4], bb[4];
; #pragma unroll
;     for (int m = 0; m < 4; ++m)
;       a[m] = *reinterpret_cast<const bf16x8*>(smem + ks * 8192 + (wr * 64 + m * 16 + fr) * 64 + fq * 16);
; #pragma unroll
;     for (int nn = 0; nn < 4; ++nn)
;       bb[nn] = *reinterpret_cast<const bf16x8*>(smem + 32768 + ks * 8192 + (wc * 64 + nn * 16 + fr) * 64 + fq * 16);
; #pragma unroll
;     for (int m = 0; m < 4; ++m)
; #pragma unroll
;       for (int nn = 0; nn < 4; ++nn) acc[m][nn] = MFMA16(a[m], bb[nn], acc[m][nn]);
;   }
.LBB0_801:
	v_add_u32_e32 v3, s14, v59
	v_ashrrev_i32_e32 v12, 4, v3
	v_add_u32_e32 v3, 0x100, v3
	v_ashrrev_i32_e32 v3, 4, v3
	v_lshlrev_b32_e32 v4, 7, v12
	v_lshlrev_b32_e32 v6, 7, v3
	v_ashrrev_i32_e32 v5, 31, v4
	v_ashrrev_i32_e32 v7, 31, v6
	v_lshl_add_u64 v[4:5], v[4:5], 1, v[0:1]
	v_lshl_add_u64 v[8:9], v[6:7], 1, v[0:1]
	global_load_dwordx4 v[4:7], v[4:5], off
	s_nop 0
	global_load_dwordx4 v[8:11], v[8:9], off
	s_addk_i32 s14, 0x200
	s_cmpk_lg_i32 s14, 0x800
	v_lshl_add_u32 v12, v12, 6, v2
	v_lshl_add_u32 v3, v3, 6, v2
	s_waitcnt vmcnt(1)
	ds_write_b128 v12, v[4:7]
	s_waitcnt vmcnt(0)
	ds_write_b128 v3, v[8:11]
	s_cbranch_scc1 .LBB0_801
	v_bfe_u32 v54, v59, 4, 2
	v_ashrrev_i32_e32 v55, 7, v59
	v_lshlrev_b32_e32 v4, 4, v54
	v_lshlrev_b32_e32 v0, 12, v55
	v_lshlrev_b32_e32 v5, 6, v49
	v_or3_b32 v57, v4, v0, v5
	s_waitcnt lgkmcnt(0)
	s_barrier
	ds_read_b128 v[0:3], v57
	v_bfe_u32 v61, v59, 6, 1
	v_lshlrev_b32_e32 v6, 12, v61
	v_or3_b32 v63, v4, v6, v5
	ds_read_b128 v[4:7], v63 offset:32768
	ds_read_b128 v[8:11], v57 offset:1024
	ds_read_b128 v[12:15], v63 offset:33792
	ds_read_b128 v[24:27], v63 offset:34816
	ds_read_b128 v[28:31], v63 offset:35840
	s_waitcnt lgkmcnt(4)
	v_mfma_f32_16x16x32_bf16 v[16:19], v[0:3], v[4:7], 0
	s_ashr_i32 s14, s17, 31
	s_add_u32 s17, s28, s17
	s_addc_u32 s20, s29, s14
	s_waitcnt lgkmcnt(2)
	v_mfma_f32_16x16x32_bf16 v[20:23], v[0:3], v[12:15], 0
	s_lshl_b32 s14, s16, 2
	s_add_u32 s14, s24, s14
	v_lshlrev_b32_e32 v55, 6, v55
	s_waitcnt lgkmcnt(1)
	v_mfma_f32_16x16x32_bf16 v[36:39], v[0:3], v[24:27], 0
	s_addc_u32 s15, s25, 0
	v_lshl_or_b32 v54, v54, 2, v55
	s_add_u32 s14, s14, 0x1000
	s_waitcnt lgkmcnt(0)
	v_mfma_f32_16x16x32_bf16 v[40:43], v[0:3], v[28:31], 0
	s_addc_u32 s15, s15, 0
	v_ashrrev_i32_e32 v55, 31, v54
	v_lshl_add_u64 v[126:127], v[54:55], 2, s[14:15]
	v_mfma_f32_16x16x32_bf16 v[44:47], v[8:11], v[4:7], 0
	v_or_b32_e32 v130, 32, v54
	v_ashrrev_i32_e32 v131, 31, v130
	v_lshlrev_b32_e32 v49, 2, v49
	v_mfma_f32_16x16x32_bf16 v[50:53], v[8:11], v[12:15], 0
	v_lshl_add_u64 v[130:131], v[130:131], 2, s[14:15]
	v_ashrrev_i32_e32 v69, 31, v68
	v_ashrrev_i32_e32 v67, 31, v66
	v_mfma_f32_16x16x32_bf16 v[70:73], v[8:11], v[24:27], 0
	v_ashrrev_i32_e32 v65, 31, v64
	v_mfma_f32_16x16x32_bf16 v[74:77], v[8:11], v[28:31], 0
	ds_read_b128 v[0:3], v57 offset:2048
	ds_read_b128 v[8:11], v57 offset:3072
	s_waitcnt lgkmcnt(1)
	v_mfma_f32_16x16x32_bf16 v[82:85], v[0:3], v[12:15], 0
	s_waitcnt lgkmcnt(0)
	v_mfma_f32_16x16x32_bf16 v[98:101], v[8:11], v[12:15], 0
	ds_read_b128 v[12:15], v57 offset:8192
	v_mfma_f32_16x16x32_bf16 v[78:81], v[0:3], v[4:7], 0
	v_mfma_f32_16x16x32_bf16 v[86:89], v[0:3], v[24:27], 0
	v_mfma_f32_16x16x32_bf16 v[94:97], v[8:11], v[4:7], 0
	v_mfma_f32_16x16x32_bf16 v[32:35], v[8:11], v[24:27], 0
	ds_read_b128 v[102:105], v63 offset:40960
	ds_read_b128 v[24:27], v57 offset:9216
	ds_read_b128 v[106:109], v63 offset:41984
	ds_read_b128 v[118:121], v63 offset:43008
	ds_read_b128 v[4:7], v63 offset:44032
	v_mfma_f32_16x16x32_bf16 v[90:93], v[0:3], v[28:31], 0
	s_waitcnt lgkmcnt(4)
	v_mfma_f32_16x16x32_bf16 v[110:113], v[12:15], v[102:105], v[16:19]
	s_waitcnt lgkmcnt(2)
	v_mfma_f32_16x16x32_bf16 v[114:117], v[12:15], v[106:109], v[20:23]
	s_waitcnt lgkmcnt(1)
	v_mfma_f32_16x16x32_bf16 v[122:125], v[12:15], v[118:121], v[36:39]
	s_waitcnt lgkmcnt(0)
	v_mfma_f32_16x16x32_bf16 v[134:137], v[12:15], v[4:7], v[40:43]
	ds_read_b128 v[146:149], v57 offset:10240
	ds_read_b128 v[12:15], v57 offset:11264
	v_mfma_f32_16x16x32_bf16 v[0:3], v[8:11], v[28:31], 0
	ds_read_b128 v[150:153], v57 offset:16384
	ds_read_b128 v[162:165], v57 offset:17408
	ds_read_b128 v[166:169], v57 offset:18432
	ds_read_b128 v[8:11], v57 offset:19456
	ds_read_b128 v[36:39], v63 offset:49152
	ds_read_b128 v[28:31], v63 offset:50176
	ds_read_b128 v[20:23], v63 offset:51200
	ds_read_b128 v[16:19], v63 offset:52224
	v_mfma_f32_16x16x32_bf16 v[138:141], v[24:27], v[102:105], v[44:47]
	v_mfma_f32_16x16x32_bf16 v[50:53], v[24:27], v[106:109], v[50:53]
	v_mfma_f32_16x16x32_bf16 v[70:73], v[24:27], v[118:121], v[70:73]
	v_mfma_f32_16x16x32_bf16 v[74:77], v[24:27], v[4:7], v[74:77]
	ds_read_b128 v[170:173], v57 offset:24576
	ds_read_b128 v[174:177], v57 offset:25600
	ds_read_b128 v[178:181], v57 offset:26624
	ds_read_b128 v[24:27], v57 offset:27648
	ds_read_b128 v[182:185], v63 offset:57344
	ds_read_b128 v[186:189], v63 offset:58368
	ds_read_b128 v[44:47], v63 offset:59392
	ds_read_b128 v[40:43], v63 offset:60416
	s_waitcnt lgkmcnt(0)
	v_mfma_f32_16x16x32_bf16 v[78:81], v[146:149], v[102:105], v[78:81]
	s_barrier
; #define MFMA16(a, b, c) __builtin_amdgcn_mfma_f32_16x16x32_bf16(a, b, c, 0, 0, 0)
; __device__ void gmlp_item(const Params& p, int layer, int b, int n, int g, char* smem) {
;     ...
; #pragma unroll
;     for (int m = 0; m < 4; ++m)
; #pragma unroll
;       for (int nn = 0; nn < 4; ++nn) acc[m][nn] = MFMA16(a[m], bb[nn], acc[m][nn]);
;   }
;   __syncthreads();
;   {
;     float* Tf = reinterpret_cast<float*>(smem);
; #pragma unroll
;     for (int m = 0; m < 4; ++m)
; #pragma unroll
;       for (int j = 0; j < 4; ++j) {
;         int t = wr * 64 + m * 16 + fq * 4 + j;
;         float bias = p.gm_b_s[(size_t)layer * 512 + g * 128 + t];
; #pragma unroll
;         for (int nn = 0; nn < 4; ++nn) Tf[t * 132 + wc * 64 + nn * 16 + fr] = acc[m][nn][j] + bias;
;       }
	global_load_dwordx4 v[190:193], v[130:131], off
	v_mfma_f32_16x16x32_bf16 v[82:85], v[146:149], v[106:109], v[82:85]
	v_ashrrev_i32_e32 v63, 31, v62
	v_mfma_f32_16x16x32_bf16 v[86:89], v[146:149], v[118:121], v[86:89]
	v_mfma_f32_16x16x32_bf16 v[90:93], v[146:149], v[4:7], v[90:93]
	global_load_dwordx4 v[146:149], v[126:127], off
	v_or_b32_e32 v126, 16, v54
	v_ashrrev_i32_e32 v127, 31, v126
	v_lshl_add_u64 v[126:127], v[126:127], 2, s[14:15]
	v_mfma_f32_16x16x32_bf16 v[110:113], v[150:153], v[36:39], v[110:113]
	v_mfma_f32_16x16x32_bf16 v[114:117], v[150:153], v[28:31], v[114:117]
	v_mfma_f32_16x16x32_bf16 v[122:125], v[150:153], v[20:23], v[122:125]
	v_mfma_f32_16x16x32_bf16 v[134:137], v[150:153], v[16:19], v[134:137]
	global_load_dwordx4 v[150:153], v[126:127], off
	v_lshl_or_b32 v126, v61, 8, v49
	v_mad_u64_u32 v[126:127], s[48:49], v54, s69, v[126:127]
	v_mfma_f32_16x16x32_bf16 v[110:113], v[170:173], v[182:185], v[110:113]
	v_add_u32_e32 v57, 0x400, v126
	v_or_b32_e32 v54, 48, v54
	v_ashrrev_i32_e32 v61, 31, v60
	v_mfma_f32_16x16x32_bf16 v[114:117], v[170:173], v[186:189], v[114:117]
	v_mfma_f32_16x16x32_bf16 v[122:125], v[170:173], v[44:47], v[122:125]
	s_waitcnt vmcnt(1)
	s_nop 1
	v_add_f32_e32 v49, v110, v146
	v_mfma_f32_16x16x32_bf16 v[134:137], v[170:173], v[40:43], v[134:137]
	s_nop 1
	v_add_f32_e32 v55, v114, v146
	ds_write2_b32 v126, v49, v55 offset1:16
	v_add_f32_e32 v49, v122, v146
	v_mfma_f32_16x16x32_bf16 v[98:101], v[12:15], v[106:109], v[98:101]
	v_mfma_f32_16x16x32_bf16 v[94:97], v[12:15], v[102:105], v[94:97]
	s_nop 0
	v_add_f32_e32 v55, v134, v146
	ds_write2_b32 v126, v49, v55 offset0:32 offset1:48
	v_add_f32_e32 v49, v111, v147
	v_add_f32_e32 v55, v115, v147
	ds_write2_b32 v126, v49, v55 offset0:132 offset1:148
	v_add_f32_e32 v49, v123, v147
	v_add_f32_e32 v55, v135, v147
	ds_write2_b32 v126, v49, v55 offset0:164 offset1:180
	v_add_f32_e32 v49, v112, v148
	v_add_f32_e32 v55, v116, v148
	ds_write2_b32 v57, v49, v55 offset0:8 offset1:24
	v_add_f32_e32 v49, v124, v148
	v_add_f32_e32 v55, v136, v148
	ds_write2_b32 v57, v49, v55 offset0:40 offset1:56
	v_add_f32_e32 v49, v113, v149
	v_add_f32_e32 v55, v117, v149
	ds_write2_b32 v57, v49, v55 offset0:140 offset1:156
	v_add_f32_e32 v49, v125, v149
	v_add_f32_e32 v55, v137, v149
	ds_write2_b32 v57, v49, v55 offset0:172 offset1:188
	v_ashrrev_i32_e32 v55, 31, v54
	v_lshl_add_u64 v[54:55], v[54:55], 2, s[14:15]
	global_load_dwordx4 v[106:109], v[54:55], off
	v_mfma_f32_16x16x32_bf16 v[102:105], v[162:165], v[36:39], v[138:141]
	v_add_u32_e32 v54, 0x2000, v126
	v_ashrrev_i32_e32 v57, 31, v56
	v_mfma_f32_16x16x32_bf16 v[50:53], v[162:165], v[28:31], v[50:53]
	v_mfma_f32_16x16x32_bf16 v[70:73], v[162:165], v[20:23], v[70:73]
	v_mfma_f32_16x16x32_bf16 v[74:77], v[162:165], v[16:19], v[74:77]
	v_mfma_f32_16x16x32_bf16 v[102:105], v[174:177], v[182:185], v[102:105]
	v_mfma_f32_16x16x32_bf16 v[50:53], v[174:177], v[186:189], v[50:53]
	v_mfma_f32_16x16x32_bf16 v[70:73], v[174:177], v[44:47], v[70:73]
	s_waitcnt vmcnt(1)
	s_nop 4
	v_add_f32_e32 v49, v102, v150
	v_add_f32_e32 v50, v50, v150
	ds_write2_b32 v54, v49, v50 offset0:64 offset1:80
	v_mfma_f32_16x16x32_bf16 v[74:77], v[174:177], v[40:43], v[74:77]
	v_add_f32_e32 v55, v53, v153
	v_add_f32_e32 v49, v70, v150
	v_mfma_f32_16x16x32_bf16 v[78:81], v[166:169], v[36:39], v[78:81]
	v_mfma_f32_16x16x32_bf16 v[82:85], v[166:169], v[28:31], v[82:85]
	s_nop 3
	v_add_f32_e32 v50, v74, v150
	ds_write2_b32 v54, v49, v50 offset0:96 offset1:112
	v_add_f32_e32 v49, v103, v151
	v_add_f32_e32 v50, v51, v151
	ds_write2_b32 v54, v49, v50 offset0:196 offset1:212
	v_add_f32_e32 v49, v71, v151
	v_add_f32_e32 v50, v75, v151
	ds_write2_b32 v54, v49, v50 offset0:228 offset1:244
	v_add_f32_e32 v49, v104, v152
	v_add_f32_e32 v50, v52, v152
	v_add_u32_e32 v54, 0x2400, v126
	v_mfma_f32_16x16x32_bf16 v[86:89], v[166:169], v[20:23], v[86:89]
	ds_write2_b32 v54, v49, v50 offset0:72 offset1:88
	v_add_f32_e32 v49, v72, v152
	v_add_f32_e32 v50, v76, v152
	v_mfma_f32_16x16x32_bf16 v[90:93], v[166:169], v[16:19], v[90:93]
	ds_write2_b32 v54, v49, v50 offset0:104 offset1:120
	v_add_f32_e32 v49, v105, v153
	ds_write2_b32 v54, v49, v55 offset0:204 offset1:220
	v_mfma_f32_16x16x32_bf16 v[50:53], v[178:181], v[182:185], v[78:81]
	v_add_f32_e32 v49, v73, v153
	v_add_f32_e32 v55, v77, v153
	ds_write2_b32 v54, v49, v55 offset0:236 offset1:252
	v_mfma_f32_16x16x32_bf16 v[70:73], v[178:181], v[186:189], v[82:85]
	v_add_u32_e32 v54, 0x4000, v126
	s_nop 2
	v_add_f32_e32 v49, v50, v190
	v_mfma_f32_16x16x32_bf16 v[74:77], v[178:181], v[44:47], v[86:89]
	v_mfma_f32_16x16x32_bf16 v[78:81], v[178:181], v[40:43], v[90:93]
	s_nop 0
	v_add_f32_e32 v50, v70, v190
	ds_write2_b32 v54, v49, v50 offset0:128 offset1:144
	s_nop 3
	v_add_f32_e32 v49, v74, v190
	v_mfma_f32_16x16x32_bf16 v[32:35], v[12:15], v[118:121], v[32:35]
	v_mfma_f32_16x16x32_bf16 v[0:3], v[12:15], v[4:7], v[0:3]
	v_add_f32_e32 v50, v78, v190
	ds_write2_b32 v54, v49, v50 offset0:160 offset1:176
	v_add_f32_e32 v49, v51, v191
	v_add_f32_e32 v4, v71, v191
	v_add_u32_e32 v50, 0x4400, v126
	v_add_f32_e32 v12, v75, v191
	v_add_f32_e32 v13, v79, v191
	ds_write2_b32 v50, v49, v4 offset0:4 offset1:20
	v_mfma_f32_16x16x32_bf16 v[4:7], v[8:11], v[36:39], v[94:97]
	ds_write2_b32 v50, v12, v13 offset0:36 offset1:52
	v_ashrrev_i32_e32 v49, 31, v48
	v_lshl_add_u64 v[70:71], v[56:57], 0, s[36:37]
	v_mfma_f32_16x16x32_bf16 v[12:15], v[8:11], v[28:31], v[98:101]
	v_add_f32_e32 v28, v52, v192
	v_add_f32_e32 v29, v72, v192
	ds_write2_b32 v50, v28, v29 offset0:136 offset1:152
	v_mfma_f32_16x16x32_bf16 v[20:23], v[8:11], v[20:23], v[32:35]
	v_add_f32_e32 v28, v76, v192
	v_add_f32_e32 v29, v80, v192
	ds_write2_b32 v50, v28, v29 offset0:168 offset1:184
	v_mfma_f32_16x16x32_bf16 v[0:3], v[8:11], v[16:19], v[0:3]
	v_add_f32_e32 v8, v53, v193
	v_add_f32_e32 v9, v73, v193
	v_add_u32_e32 v16, 0x4800, v126
	v_mfma_f32_16x16x32_bf16 v[4:7], v[24:27], v[182:185], v[4:7]
	ds_write2_b32 v16, v8, v9 offset0:12 offset1:28
	v_add_f32_e32 v17, v77, v193
	v_add_f32_e32 v18, v81, v193
	v_mfma_f32_16x16x32_bf16 v[8:11], v[24:27], v[186:189], v[12:15]
	ds_write2_b32 v16, v17, v18 offset0:44 offset1:60
	s_waitcnt vmcnt(0)
; __device__ __forceinline__ unsigned pack2(float a, float b) { return (unsigned)f2bf(a) | ((unsigned)f2bf(b) << 16); }
; __device__ __forceinline__ float bflo(unsigned w) { return __uint_as_float(w << 16); }
; __device__ __forceinline__ float bfhi(unsigned w) { return __uint_as_float(w & 0xffff0000u); }
; __device__ __forceinline__ float silu_f(float g) { return g / (1.f + __expf(-g)); }
; __device__ void gmlp_item(const Params& p, int layer, int b, int n, int g, char* smem) {
;     ...
; #pragma unroll
;     for (int m = 0; m < 4; ++m)
; #pragma unroll
;       for (int j = 0; j < 4; ++j) {
;         int t = wr * 64 + m * 16 + fq * 4 + j;
;         float bias = p.gm_b_s[(size_t)layer * 512 + g * 128 + t];
; #pragma unroll
;         for (int nn = 0; nn < 4; ++nn) Tf[t * 132 + wc * 64 + nn * 16 + fr] = acc[m][nn][j] + bias;
;       }
;     __syncthreads();
;     uint4 uu[8], gt[8];
; #pragma unroll
;     for (int i = 0; i < 8; ++i) {
;       int q = tid + 256 * i, t = q >> 4, c = (q & 15) * 8;
;       uu[i] = *reinterpret_cast<const uint4*>(P + (t0 + t) * NP + g * 128 + c);
;       gt[i] = *reinterpret_cast<const uint4*>(P + (t0 + t) * NP + 1024 + g * 128 + c);
;     }
; #pragma unroll
;     for (int i = 0; i < 8; ++i) {
;       int q = tid + 256 * i, t = q >> 4, c = (q & 15) * 8;
;       float4 m0 = *reinterpret_cast<const float4*>(Tf + t * 132 + c);
;       float4 m1 = *reinterpret_cast<const float4*>(Tf + t * 132 + c + 4);
;       float mm[8] = {m0.x, m0.y, m0.z, m0.w, m1.x, m1.y, m1.z, m1.w};
;       unsigned uw[4] = {uu[i].x, uu[i].y, uu[i].z, uu[i].w};
;       unsigned gw[4] = {gt[i].x, gt[i].y, gt[i].z, gt[i].w};
;       unsigned ow[4];
; #pragma unroll
;       for (int e = 0; e < 4; ++e) {
;         float y0 = bflo(uw[e]) * mm[2 * e] * silu_f(bflo(gw[e]));
;         float y1 = bfhi(uw[e]) * mm[2 * e + 1] * silu_f(bfhi(gw[e]));
;         ow[e] = pack2(y0, y1);
;       }
;       *reinterpret_cast<uint4*>(Y + (t0 + t) * YW + g * 128 + c) = make_uint4(ow[0], ow[1], ow[2], ow[3]);
	s_nop 1
	v_add_f32_e32 v4, v4, v106
	v_add_u32_e32 v16, 0x6000, v126
	v_mfma_f32_16x16x32_bf16 v[12:15], v[24:27], v[44:47], v[20:23]
	v_lshl_add_u64 v[36:37], v[62:63], 0, s[36:37]
	v_add_f32_e32 v8, v8, v106
	ds_write2_b32 v16, v4, v8 offset0:192 offset1:208
	v_mfma_f32_16x16x32_bf16 v[0:3], v[24:27], v[40:43], v[0:3]
	v_lshl_add_u64 v[20:21], v[64:65], 0, s[36:37]
	s_nop 2
	v_add_f32_e32 v4, v12, v106
	v_lshl_add_u64 v[38:39], v[60:61], 0, s[36:37]
	s_nop 1
	v_add_f32_e32 v0, v0, v106
	ds_write2_b32 v16, v4, v0 offset0:224 offset1:240
	v_add_f32_e32 v0, v5, v107
	v_add_f32_e32 v4, v9, v107
	v_add_u32_e32 v5, 0x6400, v126
	ds_write2_b32 v5, v0, v4 offset0:68 offset1:84
	v_add_f32_e32 v0, v13, v107
	v_add_f32_e32 v1, v1, v107
	ds_write2_b32 v5, v0, v1 offset0:100 offset1:116
	v_add_f32_e32 v0, v6, v108
	v_add_f32_e32 v1, v10, v108
	ds_write2_b32 v5, v0, v1 offset0:200 offset1:216
	v_add_f32_e32 v0, v14, v108
	v_add_f32_e32 v1, v2, v108
	ds_write2_b32 v5, v0, v1 offset0:232 offset1:248
	v_add_f32_e32 v0, v7, v109
	v_add_f32_e32 v1, v11, v109
	v_add_u32_e32 v2, 0x6800, v126
	ds_write2_b32 v2, v0, v1 offset0:76 offset1:92
	v_add_f32_e32 v0, v15, v109
	v_add_f32_e32 v1, v3, v109
	ds_write2_b32 v2, v0, v1 offset0:108 offset1:124
	v_lshlrev_b32_e32 v0, 3, v59
	v_lshl_add_u64 v[8:9], v[48:49], 0, s[36:37]
	v_mov_b64_e32 v[10:11], s[12:13]
	v_and_b32_e32 v24, 0x78, v0
	v_mad_u64_u32 v[0:1], s[12:13], v8, s45, v[10:11]
	v_mad_i32_i24 v1, v9, s45, v1
	s_lshl_b32 s12, s16, 1
	s_mov_b32 s13, s37
	v_lshl_add_u64 v[0:1], v[0:1], 0, s[12:13]
	v_lshlrev_b32_e32 v128, 1, v24
	v_lshl_add_u64 v[12:13], v[68:69], 0, s[36:37]
	v_lshl_add_u64 v[52:53], v[0:1], 0, v[128:129]
	v_mad_u64_u32 v[0:1], s[14:15], v12, s45, v[10:11]
	v_mad_i32_i24 v1, v13, s45, v1
	v_lshl_add_u64 v[0:1], v[0:1], 0, s[12:13]
	v_lshl_add_u64 v[32:33], v[0:1], 0, v[128:129]
	v_mad_u64_u32 v[0:1], s[14:15], v70, s45, v[10:11]
	v_mad_i32_i24 v1, v71, s45, v1
	v_lshl_add_u64 v[0:1], v[0:1], 0, s[12:13]
	v_lshl_add_u64 v[4:5], v[0:1], 0, v[128:129]
	s_waitcnt lgkmcnt(0)
	s_barrier
	global_load_dwordx4 v[0:3], v[4:5], off
	s_nop 0
	global_load_dwordx4 v[4:7], v[4:5], off offset:2048
	v_lshl_add_u64 v[16:17], v[66:67], 0, s[36:37]
	v_mad_u64_u32 v[14:15], s[14:15], v16, s45, v[10:11]
	v_mad_i32_i24 v15, v17, s45, v15
	v_lshl_add_u64 v[14:15], v[14:15], 0, s[12:13]
	v_lshl_add_u64 v[30:31], v[14:15], 0, v[128:129]
	v_mad_u64_u32 v[14:15], s[14:15], v20, s45, v[10:11]
	v_mad_i32_i24 v15, v21, s45, v15
	v_lshl_add_u64 v[14:15], v[14:15], 0, s[12:13]
	v_lshl_add_u64 v[26:27], v[14:15], 0, v[128:129]
	v_mad_u64_u32 v[14:15], s[14:15], v36, s45, v[10:11]
	v_mad_i32_i24 v15, v37, s45, v15
	v_ashrrev_i32_e32 v59, 31, v58
	v_lshl_add_u64 v[14:15], v[14:15], 0, s[12:13]
	v_lshl_add_u64 v[72:73], v[58:59], 0, s[36:37]
	v_lshl_add_u64 v[22:23], v[14:15], 0, v[128:129]
	v_mad_u64_u32 v[14:15], s[14:15], v38, s45, v[10:11]
	v_mad_u64_u32 v[10:11], s[14:15], v72, s45, v[10:11]
	v_mad_i32_i24 v15, v39, s45, v15
	v_mad_i32_i24 v11, v73, s45, v11
	v_lshl_add_u64 v[14:15], v[14:15], 0, s[12:13]
	v_lshl_add_u64 v[10:11], v[10:11], 0, s[12:13]
	s_add_u32 s12, s17, s12
	s_addc_u32 s13, s20, 0
	v_lshl_add_u64 v[18:19], v[14:15], 0, v[128:129]
	v_lshl_add_u64 v[14:15], v[10:11], 0, v[128:129]
	v_lshlrev_b32_e32 v10, 2, v24
	v_lshl_add_u64 v[24:25], s[12:13], 0, v[128:129]
	v_lshl_add_u64 v[74:75], v[24:25], 0, s[40:41]
	v_mad_u64_u32 v[54:55], s[12:13], v48, s69, v[10:11]
	v_mad_u64_u32 v[48:49], s[12:13], v12, s70, v[74:75]
	v_mad_u64_u32 v[46:47], s[12:13], v16, s70, v[74:75]
	v_mad_u64_u32 v[50:51], s[12:13], v8, s70, v[74:75]
	v_mad_i32_i24 v49, v13, s70, v49
	v_mad_i32_i24 v47, v17, s70, v47
	v_mad_u64_u32 v[44:45], s[12:13], v20, s70, v[74:75]
	v_mad_u64_u32 v[16:17], s[12:13], v60, s69, v[10:11]
	v_mad_u64_u32 v[12:13], s[12:13], v58, s69, v[10:11]
	v_mad_i32_i24 v51, v9, s70, v51
	v_mad_i32_i24 v45, v21, s70, v45
	v_mad_u64_u32 v[20:21], s[12:13], v62, s69, v[10:11]
	v_mad_u64_u32 v[8:9], s[12:13], v56, s69, v[10:11]
	v_mad_u64_u32 v[28:29], s[12:13], v66, s69, v[10:11]
	v_mad_u64_u32 v[34:35], s[12:13], v68, s69, v[10:11]
	v_mad_u64_u32 v[24:25], s[12:13], v64, s69, v[10:11]
	v_mad_u64_u32 v[42:43], s[12:13], v36, s70, v[74:75]
	v_mad_i32_i24 v43, v37, s70, v43
	v_mad_u64_u32 v[36:37], s[12:13], v70, s70, v[74:75]
	v_mad_u64_u32 v[40:41], s[12:13], v38, s70, v[74:75]
	v_mad_i32_i24 v41, v39, s70, v41
	v_mad_u64_u32 v[38:39], s[12:13], v72, s70, v[74:75]
	v_mad_i32_i24 v39, v73, s70, v39
	v_mad_i32_i24 v37, v71, s70, v37
	s_waitcnt vmcnt(1)
	v_lshlrev_b32_e32 v63, 16, v1
	s_waitcnt vmcnt(0)
	v_lshlrev_b32_e32 v13, 16, v5
	v_lshlrev_b32_e32 v17, 16, v4
	v_mul_f32_e32 v9, 0xbfb8aa3b, v17
	v_and_b32_e32 v21, 0xffff0000, v5
	v_mul_f32_e32 v5, 0xbfb8aa3b, v13
	v_exp_f32_e32 v60, v9
	v_exp_f32_e32 v61, v5
	ds_read_b128 v[56:59], v8
	ds_read_b128 v[8:11], v8 offset:16
	v_and_b32_e32 v25, 0xffff0000, v4
	v_mul_f32_e32 v4, 0xbfb8aa3b, v25
	v_pk_add_f32 v[60:61], v[60:61], 1.0 op_sel_hi:[1,0]
	s_waitcnt lgkmcnt(1)
; __device__ __forceinline__ unsigned pack2(float a, float b) { return (unsigned)f2bf(a) | ((unsigned)f2bf(b) << 16); }
; __device__ __forceinline__ float bflo(unsigned w) { return __uint_as_float(w << 16); }
; __device__ __forceinline__ float bfhi(unsigned w) { return __uint_as_float(w & 0xffff0000u); }
; __device__ __forceinline__ float silu_f(float g) { return g / (1.f + __expf(-g)); }
; __device__ void gmlp_item(const Params& p, int layer, int b, int n, int g, char* smem) {
;     ...
; #pragma unroll
;     for (int i = 0; i < 8; ++i) {
;       int q = tid + 256 * i, t = q >> 4, c = (q & 15) * 8;
;       float4 m0 = *reinterpret_cast<const float4*>(Tf + t * 132 + c);
;       float4 m1 = *reinterpret_cast<const float4*>(Tf + t * 132 + c + 4);
;       float mm[8] = {m0.x, m0.y, m0.z, m0.w, m1.x, m1.y, m1.z, m1.w};
;       unsigned uw[4] = {uu[i].x, uu[i].y, uu[i].z, uu[i].w};
;       unsigned gw[4] = {gt[i].x, gt[i].y, gt[i].z, gt[i].w};
;       unsigned ow[4];
; #pragma unroll
;       for (int e = 0; e < 4; ++e) {
;         float y0 = bflo(uw[e]) * mm[2 * e] * silu_f(bflo(gw[e]));
;         float y1 = bfhi(uw[e]) * mm[2 * e + 1] * silu_f(bfhi(gw[e]));
;         ow[e] = pack2(y0, y1);
;       }
;       *reinterpret_cast<uint4*>(Y + (t0 + t) * YW + g * 128 + c) = make_uint4(ow[0], ow[1], ow[2], ow[3]);
	v_mov_b32_e32 v64, v56
	v_exp_f32_e32 v4, v4
	v_lshlrev_b32_e32 v62, 16, v0
	v_mov_b32_e32 v65, v58
	v_rcp_f32_e32 v61, v61
	s_nop 0
	v_mul_f32_e32 v61, v13, v61
	v_and_b32_e32 v1, 0xffff0000, v1
	v_mul_f32_e32 v5, 0xbfb8aa3b, v21
	v_exp_f32_e32 v5, v5
	v_rcp_f32_e32 v60, v60
	s_nop 0
	v_mul_f32_e32 v60, v17, v60
	v_and_b32_e32 v0, 0xffff0000, v0
	v_mov_b32_e32 v58, v57
	v_pk_add_f32 v[4:5], v[4:5], 1.0 op_sel_hi:[1,0]
	v_pk_mul_f32 v[0:1], v[58:59], v[0:1]
	v_pk_mul_f32 v[62:63], v[64:65], v[62:63]
	v_rcp_f32_e32 v5, v5
	s_nop 0
	v_mul_f32_e32 v5, v21, v5
	v_pk_mul_f32 v[60:61], v[60:61], v[62:63]
	v_rcp_f32_e32 v4, v4
	s_nop 0
	v_mul_f32_e32 v4, v25, v4
	v_pk_mul_f32 v[0:1], v[4:5], v[0:1]
	v_lshlrev_b32_e32 v13, 16, v7
	v_lshlrev_b32_e32 v17, 16, v6
	v_cvt_pk_bf16_f32 v1, v61, v1
	v_cvt_pk_bf16_f32 v0, v60, v0
	v_mul_f32_e32 v4, 0xbfb8aa3b, v17
	v_mul_f32_e32 v5, 0xbfb8aa3b, v13
	v_exp_f32_e32 v4, v4
	v_exp_f32_e32 v5, v5
	v_and_b32_e32 v25, 0xffff0000, v6
	v_mul_f32_e32 v6, 0xbfb8aa3b, v25
	v_and_b32_e32 v21, 0xffff0000, v7
	v_exp_f32_e32 v60, v6
	v_pk_add_f32 v[64:65], v[4:5], 1.0 op_sel_hi:[1,0]
	global_load_dwordx4 v[4:7], v[14:15], off
	global_load_dwordx4 v[56:59], v[14:15], off offset:2048
	s_waitcnt lgkmcnt(0)
	v_mov_b32_e32 v14, v8
	v_mov_b32_e32 v15, v10
	v_lshlrev_b32_e32 v63, 16, v3
	v_lshlrev_b32_e32 v62, 16, v2
	v_pk_mul_f32 v[14:15], v[14:15], v[62:63]
	v_rcp_f32_e32 v63, v65
	s_nop 0
	v_mul_f32_e32 v63, v13, v63
	v_mul_f32_e32 v10, 0xbfb8aa3b, v21
	v_exp_f32_e32 v61, v10
	v_rcp_f32_e32 v62, v64
	s_nop 0
	v_mul_f32_e32 v62, v17, v62
	v_mov_b32_e32 v10, v9
	v_and_b32_e32 v3, 0xffff0000, v3
	v_pk_add_f32 v[60:61], v[60:61], 1.0 op_sel_hi:[1,0]
	v_and_b32_e32 v2, 0xffff0000, v2
	v_pk_mul_f32 v[2:3], v[10:11], v[2:3]
	v_pk_mul_f32 v[14:15], v[62:63], v[14:15]
	v_rcp_f32_e32 v9, v61
	s_nop 0
	v_mul_f32_e32 v9, v21, v9
	v_rcp_f32_e32 v8, v60
	s_nop 0
	v_mul_f32_e32 v8, v25, v8
	v_pk_mul_f32 v[2:3], v[8:9], v[2:3]
	v_cvt_pk_bf16_f32 v3, v15, v3
	v_cvt_pk_bf16_f32 v2, v14, v2
	s_waitcnt vmcnt(0)
	v_lshlrev_b32_e32 v21, 16, v56
	v_mul_f32_e32 v8, 0xbfb8aa3b, v21
	v_and_b32_e32 v29, 0xffff0000, v56
	v_lshlrev_b32_e32 v17, 16, v57
	v_exp_f32_e32 v60, v8
	v_mul_f32_e32 v8, 0xbfb8aa3b, v29
	v_exp_f32_e32 v56, v8
	v_mul_f32_e32 v8, 0xbfb8aa3b, v17
	v_exp_f32_e32 v61, v8
	ds_read_b128 v[8:11], v12
	ds_read_b128 v[12:15], v12 offset:16
	v_and_b32_e32 v25, 0xffff0000, v57
	v_lshlrev_b32_e32 v63, 16, v5
	v_pk_add_f32 v[60:61], v[60:61], 1.0 op_sel_hi:[1,0]
	s_waitcnt lgkmcnt(1)
	v_mov_b32_e32 v64, v8
	v_mov_b32_e32 v65, v10
	v_lshlrev_b32_e32 v62, 16, v4
	v_and_b32_e32 v5, 0xffff0000, v5
	v_rcp_f32_e32 v61, v61
	s_nop 0
	v_mul_f32_e32 v61, v17, v61
	v_and_b32_e32 v4, 0xffff0000, v4
	v_mul_f32_e32 v10, 0xbfb8aa3b, v25
	v_exp_f32_e32 v57, v10
	v_rcp_f32_e32 v60, v60
	s_nop 0
	v_mul_f32_e32 v60, v21, v60
	v_mov_b32_e32 v10, v9
	v_pk_mul_f32 v[4:5], v[10:11], v[4:5]
	v_pk_add_f32 v[56:57], v[56:57], 1.0 op_sel_hi:[1,0]
	v_pk_mul_f32 v[62:63], v[64:65], v[62:63]
	v_pk_mul_f32 v[60:61], v[60:61], v[62:63]
	v_lshlrev_b32_e32 v63, 16, v7
	v_lshlrev_b32_e32 v62, 16, v6
	v_rcp_f32_e32 v9, v57
	s_nop 0
	v_mul_f32_e32 v9, v25, v9
	v_rcp_f32_e32 v8, v56
	s_nop 0
	v_mul_f32_e32 v8, v29, v8
	v_pk_mul_f32 v[4:5], v[8:9], v[4:5]
	v_lshlrev_b32_e32 v17, 16, v59
	v_lshlrev_b32_e32 v21, 16, v58
	v_cvt_pk_bf16_f32 v5, v61, v5
	v_cvt_pk_bf16_f32 v4, v60, v4
	v_mul_f32_e32 v8, 0xbfb8aa3b, v21
	v_mul_f32_e32 v9, 0xbfb8aa3b, v17
	v_exp_f32_e32 v8, v8
	v_exp_f32_e32 v9, v9
	v_and_b32_e32 v29, 0xffff0000, v58
	v_mul_f32_e32 v10, 0xbfb8aa3b, v29
	v_and_b32_e32 v25, 0xffff0000, v59
	v_exp_f32_e32 v60, v10
	v_pk_add_f32 v[64:65], v[8:9], 1.0 op_sel_hi:[1,0]
	global_load_dwordx4 v[8:11], v[18:19], off
	global_load_dwordx4 v[56:59], v[18:19], off offset:2048
	s_waitcnt lgkmcnt(0)
	v_mov_b32_e32 v18, v12
	v_mov_b32_e32 v19, v14
	v_pk_mul_f32 v[18:19], v[18:19], v[62:63]
	v_rcp_f32_e32 v63, v65
	s_nop 0
	v_mul_f32_e32 v63, v17, v63
	v_and_b32_e32 v7, 0xffff0000, v7
	v_mul_f32_e32 v14, 0xbfb8aa3b, v25
	v_exp_f32_e32 v61, v14
	v_rcp_f32_e32 v62, v64
	s_nop 0
	v_mul_f32_e32 v62, v21, v62
	v_mov_b32_e32 v14, v13
	v_and_b32_e32 v6, 0xffff0000, v6
	v_pk_add_f32 v[60:61], v[60:61], 1.0 op_sel_hi:[1,0]
	v_pk_mul_f32 v[6:7], v[14:15], v[6:7]
	v_pk_mul_f32 v[18:19], v[62:63], v[18:19]
	v_rcp_f32_e32 v13, v61
	s_nop 0
	v_mul_f32_e32 v13, v25, v13
	v_rcp_f32_e32 v12, v60
	s_nop 0
	v_mul_f32_e32 v12, v29, v12
	v_pk_mul_f32 v[6:7], v[12:13], v[6:7]
	v_cvt_pk_bf16_f32 v7, v19, v7
	v_cvt_pk_bf16_f32 v6, v18, v6
	s_waitcnt vmcnt(1)
	v_lshlrev_b32_e32 v63, 16, v9
	s_waitcnt vmcnt(0)
	v_lshlrev_b32_e32 v25, 16, v56
	v_mul_f32_e32 v12, 0xbfb8aa3b, v25
	v_and_b32_e32 v35, 0xffff0000, v56
	v_lshlrev_b32_e32 v21, 16, v57
	v_exp_f32_e32 v60, v12
	v_mul_f32_e32 v12, 0xbfb8aa3b, v35
	v_exp_f32_e32 v56, v12
	v_mul_f32_e32 v12, 0xbfb8aa3b, v21
	v_exp_f32_e32 v61, v12
	v_and_b32_e32 v29, 0xffff0000, v57
	ds_read_b128 v[12:15], v16
	ds_read_b128 v[16:19], v16 offset:16
	v_lshlrev_b32_e32 v62, 16, v8
	v_pk_add_f32 v[60:61], v[60:61], 1.0 op_sel_hi:[1,0]
	v_and_b32_e32 v9, 0xffff0000, v9
	s_waitcnt lgkmcnt(1)
; __device__ __forceinline__ unsigned pack2(float a, float b) { return (unsigned)f2bf(a) | ((unsigned)f2bf(b) << 16); }
; __device__ __forceinline__ float bflo(unsigned w) { return __uint_as_float(w << 16); }
; __device__ __forceinline__ float bfhi(unsigned w) { return __uint_as_float(w & 0xffff0000u); }
; __device__ __forceinline__ float silu_f(float g) { return g / (1.f + __expf(-g)); }
; __device__ void gmlp_item(const Params& p, int layer, int b, int n, int g, char* smem) {
;     ...
; #pragma unroll
;     for (int i = 0; i < 8; ++i) {
;       int q = tid + 256 * i, t = q >> 4, c = (q & 15) * 8;
;       float4 m0 = *reinterpret_cast<const float4*>(Tf + t * 132 + c);
;       float4 m1 = *reinterpret_cast<const float4*>(Tf + t * 132 + c + 4);
;       float mm[8] = {m0.x, m0.y, m0.z, m0.w, m1.x, m1.y, m1.z, m1.w};
;       unsigned uw[4] = {uu[i].x, uu[i].y, uu[i].z, uu[i].w};
;       unsigned gw[4] = {gt[i].x, gt[i].y, gt[i].z, gt[i].w};
;       unsigned ow[4];
; #pragma unroll
;       for (int e = 0; e < 4; ++e) {
;         float y0 = bflo(uw[e]) * mm[2 * e] * silu_f(bflo(gw[e]));
;         float y1 = bfhi(uw[e]) * mm[2 * e + 1] * silu_f(bfhi(gw[e]));
;         ow[e] = pack2(y0, y1);
;       }
;       *reinterpret_cast<uint4*>(Y + (t0 + t) * YW + g * 128 + c) = make_uint4(ow[0], ow[1], ow[2], ow[3]);
	v_mov_b32_e32 v64, v12
	v_mov_b32_e32 v65, v14
	v_pk_mul_f32 v[62:63], v[64:65], v[62:63]
	v_rcp_f32_e32 v61, v61
	s_nop 0
	v_mul_f32_e32 v61, v21, v61
	v_and_b32_e32 v8, 0xffff0000, v8
	v_mul_f32_e32 v14, 0xbfb8aa3b, v29
	v_exp_f32_e32 v57, v14
	v_rcp_f32_e32 v60, v60
	s_nop 0
	v_mul_f32_e32 v60, v25, v60
	v_mov_b32_e32 v14, v13
	v_pk_mul_f32 v[8:9], v[14:15], v[8:9]
	v_pk_add_f32 v[56:57], v[56:57], 1.0 op_sel_hi:[1,0]
	v_pk_mul_f32 v[60:61], v[60:61], v[62:63]
	v_lshlrev_b32_e32 v63, 16, v11
	v_lshlrev_b32_e32 v62, 16, v10
	v_and_b32_e32 v11, 0xffff0000, v11
	v_rcp_f32_e32 v13, v57
	s_nop 0
	v_mul_f32_e32 v13, v29, v13
	v_rcp_f32_e32 v12, v56
	s_nop 0
	v_mul_f32_e32 v12, v35, v12
	v_pk_mul_f32 v[8:9], v[12:13], v[8:9]
	v_lshlrev_b32_e32 v21, 16, v59
	v_lshlrev_b32_e32 v25, 16, v58
	v_cvt_pk_bf16_f32 v9, v61, v9
	v_cvt_pk_bf16_f32 v8, v60, v8
	v_mul_f32_e32 v12, 0xbfb8aa3b, v25
	v_mul_f32_e32 v13, 0xbfb8aa3b, v21
	v_exp_f32_e32 v12, v12
	v_exp_f32_e32 v13, v13
	v_and_b32_e32 v35, 0xffff0000, v58
	v_mul_f32_e32 v14, 0xbfb8aa3b, v35
	v_and_b32_e32 v29, 0xffff0000, v59
	v_exp_f32_e32 v60, v14
	v_pk_add_f32 v[64:65], v[12:13], 1.0 op_sel_hi:[1,0]
	global_load_dwordx4 v[12:15], v[22:23], off
	global_load_dwordx4 v[56:59], v[22:23], off offset:2048
	s_waitcnt lgkmcnt(0)
	v_mov_b32_e32 v22, v16
	v_mov_b32_e32 v23, v18
	v_pk_mul_f32 v[22:23], v[22:23], v[62:63]
	v_rcp_f32_e32 v63, v65
	s_nop 0
	v_mul_f32_e32 v63, v21, v63
	v_and_b32_e32 v10, 0xffff0000, v10
	v_mul_f32_e32 v18, 0xbfb8aa3b, v29
	v_exp_f32_e32 v61, v18
	v_rcp_f32_e32 v62, v64
	s_nop 0
	v_mul_f32_e32 v62, v25, v62
	v_mov_b32_e32 v18, v17
	v_pk_mul_f32 v[10:11], v[18:19], v[10:11]
	v_pk_add_f32 v[60:61], v[60:61], 1.0 op_sel_hi:[1,0]
	v_pk_mul_f32 v[22:23], v[62:63], v[22:23]
	s_waitcnt vmcnt(1)
	v_lshlrev_b32_e32 v63, 16, v13
	v_rcp_f32_e32 v17, v61
	s_nop 0
	v_mul_f32_e32 v17, v29, v17
	v_rcp_f32_e32 v16, v60
	s_nop 0
	v_mul_f32_e32 v16, v35, v16
	v_pk_mul_f32 v[10:11], v[16:17], v[10:11]
	s_waitcnt vmcnt(0)
	v_lshlrev_b32_e32 v29, 16, v56
	v_cvt_pk_bf16_f32 v11, v23, v11
	v_mul_f32_e32 v16, 0xbfb8aa3b, v29
	v_and_b32_e32 v55, 0xffff0000, v56
	v_lshlrev_b32_e32 v25, 16, v57
	v_exp_f32_e32 v60, v16
	v_mul_f32_e32 v16, 0xbfb8aa3b, v55
	v_exp_f32_e32 v56, v16
	v_mul_f32_e32 v16, 0xbfb8aa3b, v25
	v_exp_f32_e32 v61, v16
	s_nop 0
	v_pk_add_f32 v[60:61], v[60:61], 1.0 op_sel_hi:[1,0]
	v_and_b32_e32 v35, 0xffff0000, v57
	v_cvt_pk_bf16_f32 v10, v22, v10
	ds_read_b128 v[16:19], v20
	ds_read_b128 v[20:23], v20 offset:16
	v_lshlrev_b32_e32 v62, 16, v12
	v_and_b32_e32 v13, 0xffff0000, v13
	s_waitcnt lgkmcnt(1)
	v_mov_b32_e32 v64, v16
	v_mov_b32_e32 v65, v18
	v_pk_mul_f32 v[62:63], v[64:65], v[62:63]
	v_rcp_f32_e32 v61, v61
	s_nop 0
	v_mul_f32_e32 v61, v25, v61
	v_and_b32_e32 v12, 0xffff0000, v12
	v_mul_f32_e32 v18, 0xbfb8aa3b, v35
	v_exp_f32_e32 v57, v18
	v_rcp_f32_e32 v60, v60
	s_nop 0
	v_mul_f32_e32 v60, v29, v60
	v_mov_b32_e32 v18, v17
	v_pk_mul_f32 v[12:13], v[18:19], v[12:13]
	v_pk_add_f32 v[56:57], v[56:57], 1.0 op_sel_hi:[1,0]
	v_pk_mul_f32 v[60:61], v[60:61], v[62:63]
	v_lshlrev_b32_e32 v63, 16, v15
	v_lshlrev_b32_e32 v62, 16, v14
	v_and_b32_e32 v15, 0xffff0000, v15
	v_rcp_f32_e32 v17, v57
	s_nop 0
	v_mul_f32_e32 v17, v35, v17
	v_rcp_f32_e32 v16, v56
	s_nop 0
	v_mul_f32_e32 v16, v55, v16
	v_pk_mul_f32 v[12:13], v[16:17], v[12:13]
	v_lshlrev_b32_e32 v25, 16, v59
	v_lshlrev_b32_e32 v29, 16, v58
	v_cvt_pk_bf16_f32 v13, v61, v13
	v_cvt_pk_bf16_f32 v12, v60, v12
	v_mul_f32_e32 v16, 0xbfb8aa3b, v29
	v_mul_f32_e32 v17, 0xbfb8aa3b, v25
	v_exp_f32_e32 v16, v16
	v_exp_f32_e32 v17, v17
	v_and_b32_e32 v55, 0xffff0000, v58
	v_mul_f32_e32 v18, 0xbfb8aa3b, v55
	v_and_b32_e32 v35, 0xffff0000, v59
	v_exp_f32_e32 v60, v18
	v_pk_add_f32 v[64:65], v[16:17], 1.0 op_sel_hi:[1,0]
	global_load_dwordx4 v[16:19], v[26:27], off
	global_load_dwordx4 v[56:59], v[26:27], off offset:2048
	s_waitcnt lgkmcnt(0)
	v_mov_b32_e32 v26, v20
	v_mov_b32_e32 v27, v22
	v_pk_mul_f32 v[26:27], v[26:27], v[62:63]
	v_rcp_f32_e32 v63, v65
	s_nop 0
	v_mul_f32_e32 v63, v25, v63
	v_and_b32_e32 v14, 0xffff0000, v14
	v_mul_f32_e32 v22, 0xbfb8aa3b, v35
	v_exp_f32_e32 v61, v22
	v_rcp_f32_e32 v62, v64
	s_nop 0
	v_mul_f32_e32 v62, v29, v62
	v_mov_b32_e32 v22, v21
	v_pk_mul_f32 v[14:15], v[22:23], v[14:15]
	v_pk_add_f32 v[60:61], v[60:61], 1.0 op_sel_hi:[1,0]
	v_pk_mul_f32 v[26:27], v[62:63], v[26:27]
	s_waitcnt vmcnt(1)
	v_lshlrev_b32_e32 v63, 16, v17
	v_rcp_f32_e32 v21, v61
	s_nop 0
	v_mul_f32_e32 v21, v35, v21
	v_rcp_f32_e32 v20, v60
	s_nop 0
	v_mul_f32_e32 v20, v55, v20
	v_pk_mul_f32 v[14:15], v[20:21], v[14:15]
	s_waitcnt vmcnt(0)
	v_lshlrev_b32_e32 v35, 16, v56
	v_cvt_pk_bf16_f32 v15, v27, v15
	v_mul_f32_e32 v20, 0xbfb8aa3b, v35
	v_and_b32_e32 v66, 0xffff0000, v56
	v_lshlrev_b32_e32 v29, 16, v57
	v_exp_f32_e32 v60, v20
	v_mul_f32_e32 v20, 0xbfb8aa3b, v66
	v_exp_f32_e32 v56, v20
	v_mul_f32_e32 v20, 0xbfb8aa3b, v29
	v_exp_f32_e32 v61, v20
	s_nop 0
	v_pk_add_f32 v[60:61], v[60:61], 1.0 op_sel_hi:[1,0]
	v_and_b32_e32 v55, 0xffff0000, v57
	v_cvt_pk_bf16_f32 v14, v26, v14
	ds_read_b128 v[20:23], v24
	ds_read_b128 v[24:27], v24 offset:16
	v_lshlrev_b32_e32 v62, 16, v16
	v_and_b32_e32 v17, 0xffff0000, v17
	s_waitcnt lgkmcnt(1)
; __device__ __forceinline__ unsigned pack2(float a, float b) { return (unsigned)f2bf(a) | ((unsigned)f2bf(b) << 16); }
; __device__ __forceinline__ float bflo(unsigned w) { return __uint_as_float(w << 16); }
; __device__ __forceinline__ float bfhi(unsigned w) { return __uint_as_float(w & 0xffff0000u); }
; __device__ __forceinline__ float silu_f(float g) { return g / (1.f + __expf(-g)); }
; __device__ void gmlp_item(const Params& p, int layer, int b, int n, int g, char* smem) {
;     ...
; #pragma unroll
;     for (int i = 0; i < 8; ++i) {
;       int q = tid + 256 * i, t = q >> 4, c = (q & 15) * 8;
;       float4 m0 = *reinterpret_cast<const float4*>(Tf + t * 132 + c);
;       float4 m1 = *reinterpret_cast<const float4*>(Tf + t * 132 + c + 4);
;       float mm[8] = {m0.x, m0.y, m0.z, m0.w, m1.x, m1.y, m1.z, m1.w};
;       unsigned uw[4] = {uu[i].x, uu[i].y, uu[i].z, uu[i].w};
;       unsigned gw[4] = {gt[i].x, gt[i].y, gt[i].z, gt[i].w};
;       unsigned ow[4];
; #pragma unroll
;       for (int e = 0; e < 4; ++e) {
;         float y0 = bflo(uw[e]) * mm[2 * e] * silu_f(bflo(gw[e]));
;         float y1 = bfhi(uw[e]) * mm[2 * e + 1] * silu_f(bfhi(gw[e]));
;         ow[e] = pack2(y0, y1);
;       }
;       *reinterpret_cast<uint4*>(Y + (t0 + t) * YW + g * 128 + c) = make_uint4(ow[0], ow[1], ow[2], ow[3]);
	v_mov_b32_e32 v64, v20
	v_mov_b32_e32 v65, v22
	v_pk_mul_f32 v[62:63], v[64:65], v[62:63]
	v_rcp_f32_e32 v61, v61
	s_nop 0
	v_mul_f32_e32 v61, v29, v61
	v_and_b32_e32 v16, 0xffff0000, v16
	v_mul_f32_e32 v22, 0xbfb8aa3b, v55
	v_exp_f32_e32 v57, v22
	v_rcp_f32_e32 v60, v60
	s_nop 0
	v_mul_f32_e32 v60, v35, v60
	v_mov_b32_e32 v22, v21
	v_pk_mul_f32 v[16:17], v[22:23], v[16:17]
	v_pk_add_f32 v[56:57], v[56:57], 1.0 op_sel_hi:[1,0]
	v_pk_mul_f32 v[60:61], v[60:61], v[62:63]
	v_lshlrev_b32_e32 v63, 16, v19
	v_lshlrev_b32_e32 v62, 16, v18
	v_and_b32_e32 v19, 0xffff0000, v19
	v_rcp_f32_e32 v21, v57
	s_nop 0
	v_mul_f32_e32 v21, v55, v21
	v_rcp_f32_e32 v20, v56
	s_nop 0
	v_mul_f32_e32 v20, v66, v20
	v_pk_mul_f32 v[16:17], v[20:21], v[16:17]
	v_lshlrev_b32_e32 v29, 16, v59
	v_lshlrev_b32_e32 v35, 16, v58
	v_cvt_pk_bf16_f32 v17, v61, v17
	v_cvt_pk_bf16_f32 v16, v60, v16
	v_mul_f32_e32 v20, 0xbfb8aa3b, v35
	v_mul_f32_e32 v21, 0xbfb8aa3b, v29
	v_exp_f32_e32 v20, v20
	v_exp_f32_e32 v21, v21
	v_and_b32_e32 v66, 0xffff0000, v58
	v_mul_f32_e32 v22, 0xbfb8aa3b, v66
	v_and_b32_e32 v55, 0xffff0000, v59
	v_exp_f32_e32 v60, v22
	v_pk_add_f32 v[64:65], v[20:21], 1.0 op_sel_hi:[1,0]
	global_load_dwordx4 v[20:23], v[30:31], off
	global_load_dwordx4 v[56:59], v[30:31], off offset:2048
	s_waitcnt lgkmcnt(0)
	v_mov_b32_e32 v30, v24
	v_mov_b32_e32 v31, v26
	v_pk_mul_f32 v[30:31], v[30:31], v[62:63]
	v_rcp_f32_e32 v63, v65
	s_nop 0
	v_mul_f32_e32 v63, v29, v63
	v_and_b32_e32 v18, 0xffff0000, v18
	v_mul_f32_e32 v26, 0xbfb8aa3b, v55
	v_exp_f32_e32 v61, v26
	v_rcp_f32_e32 v62, v64
	s_nop 0
	v_mul_f32_e32 v62, v35, v62
	v_mov_b32_e32 v26, v25
	v_pk_mul_f32 v[18:19], v[26:27], v[18:19]
	v_pk_add_f32 v[60:61], v[60:61], 1.0 op_sel_hi:[1,0]
	v_pk_mul_f32 v[30:31], v[62:63], v[30:31]
	s_waitcnt vmcnt(1)
	v_lshlrev_b32_e32 v63, 16, v21
	v_rcp_f32_e32 v25, v61
	s_nop 0
	v_mul_f32_e32 v25, v55, v25
	v_rcp_f32_e32 v24, v60
	s_nop 0
	v_mul_f32_e32 v24, v66, v24
	v_pk_mul_f32 v[18:19], v[24:25], v[18:19]
	s_waitcnt vmcnt(0)
	v_lshlrev_b32_e32 v55, 16, v56
	v_cvt_pk_bf16_f32 v19, v31, v19
	v_mul_f32_e32 v24, 0xbfb8aa3b, v55
	v_and_b32_e32 v67, 0xffff0000, v56
	v_lshlrev_b32_e32 v35, 16, v57
	v_exp_f32_e32 v60, v24
	v_mul_f32_e32 v24, 0xbfb8aa3b, v67
	v_exp_f32_e32 v56, v24
	v_mul_f32_e32 v24, 0xbfb8aa3b, v35
	v_exp_f32_e32 v61, v24
	s_nop 0
	v_pk_add_f32 v[60:61], v[60:61], 1.0 op_sel_hi:[1,0]
	v_and_b32_e32 v66, 0xffff0000, v57
	v_cvt_pk_bf16_f32 v18, v30, v18
	ds_read_b128 v[24:27], v28
	ds_read_b128 v[28:31], v28 offset:16
	v_lshlrev_b32_e32 v62, 16, v20
	v_and_b32_e32 v21, 0xffff0000, v21
	s_waitcnt lgkmcnt(1)
	v_mov_b32_e32 v64, v24
	v_mov_b32_e32 v65, v26
	v_pk_mul_f32 v[62:63], v[64:65], v[62:63]
	v_rcp_f32_e32 v61, v61
	s_nop 0
	v_mul_f32_e32 v61, v35, v61
	v_and_b32_e32 v20, 0xffff0000, v20
	v_mul_f32_e32 v26, 0xbfb8aa3b, v66
	v_exp_f32_e32 v57, v26
	v_rcp_f32_e32 v60, v60
	s_nop 0
	v_mul_f32_e32 v60, v55, v60
	v_mov_b32_e32 v26, v25
	v_pk_mul_f32 v[20:21], v[26:27], v[20:21]
	v_pk_add_f32 v[56:57], v[56:57], 1.0 op_sel_hi:[1,0]
	v_pk_mul_f32 v[60:61], v[60:61], v[62:63]
	v_lshlrev_b32_e32 v63, 16, v23
	v_lshlrev_b32_e32 v62, 16, v22
	v_and_b32_e32 v23, 0xffff0000, v23
	v_rcp_f32_e32 v25, v57
	s_nop 0
	v_mul_f32_e32 v25, v66, v25
	v_rcp_f32_e32 v24, v56
	s_nop 0
	v_mul_f32_e32 v24, v67, v24
	v_pk_mul_f32 v[20:21], v[24:25], v[20:21]
	v_lshlrev_b32_e32 v35, 16, v59
	v_lshlrev_b32_e32 v55, 16, v58
	v_cvt_pk_bf16_f32 v21, v61, v21
	v_cvt_pk_bf16_f32 v20, v60, v20
	v_mul_f32_e32 v24, 0xbfb8aa3b, v55
	v_mul_f32_e32 v25, 0xbfb8aa3b, v35
	v_exp_f32_e32 v24, v24
	v_exp_f32_e32 v25, v25
	v_and_b32_e32 v67, 0xffff0000, v58
	v_mul_f32_e32 v26, 0xbfb8aa3b, v67
	v_and_b32_e32 v66, 0xffff0000, v59
	v_exp_f32_e32 v60, v26
	v_pk_add_f32 v[64:65], v[24:25], 1.0 op_sel_hi:[1,0]
	global_load_dwordx4 v[24:27], v[32:33], off
	global_load_dwordx4 v[56:59], v[32:33], off offset:2048
	s_waitcnt lgkmcnt(0)
	v_mov_b32_e32 v32, v28
	v_mov_b32_e32 v33, v30
	v_pk_mul_f32 v[32:33], v[32:33], v[62:63]
	v_rcp_f32_e32 v63, v65
	s_nop 0
	v_mul_f32_e32 v63, v35, v63
	v_and_b32_e32 v22, 0xffff0000, v22
	v_mul_f32_e32 v30, 0xbfb8aa3b, v66
	v_exp_f32_e32 v61, v30
	v_rcp_f32_e32 v62, v64
	s_nop 0
	v_mul_f32_e32 v62, v55, v62
	v_mov_b32_e32 v30, v29
	v_pk_mul_f32 v[22:23], v[30:31], v[22:23]
	v_pk_add_f32 v[60:61], v[60:61], 1.0 op_sel_hi:[1,0]
	v_pk_mul_f32 v[32:33], v[62:63], v[32:33]
	s_waitcnt vmcnt(1)
	v_lshlrev_b32_e32 v63, 16, v25
	v_rcp_f32_e32 v29, v61
	s_nop 0
	v_mul_f32_e32 v29, v66, v29
	v_rcp_f32_e32 v28, v60
	s_nop 0
	v_mul_f32_e32 v28, v67, v28
	v_pk_mul_f32 v[22:23], v[28:29], v[22:23]
	s_waitcnt vmcnt(0)
	v_lshlrev_b32_e32 v66, 16, v56
	v_cvt_pk_bf16_f32 v23, v33, v23
	v_mul_f32_e32 v28, 0xbfb8aa3b, v66
	v_and_b32_e32 v68, 0xffff0000, v56
	v_lshlrev_b32_e32 v55, 16, v57
	v_exp_f32_e32 v60, v28
	v_mul_f32_e32 v28, 0xbfb8aa3b, v68
	v_exp_f32_e32 v56, v28
	v_mul_f32_e32 v28, 0xbfb8aa3b, v55
	v_exp_f32_e32 v61, v28
	s_nop 0
	v_pk_add_f32 v[60:61], v[60:61], 1.0 op_sel_hi:[1,0]
	v_and_b32_e32 v67, 0xffff0000, v57
	v_cvt_pk_bf16_f32 v22, v32, v22
	ds_read_b128 v[28:31], v34
	ds_read_b128 v[32:35], v34 offset:16
	v_lshlrev_b32_e32 v62, 16, v24
	v_and_b32_e32 v25, 0xffff0000, v25
	s_waitcnt lgkmcnt(1)
; __device__ __forceinline__ unsigned pack2(float a, float b) { return (unsigned)f2bf(a) | ((unsigned)f2bf(b) << 16); }
; __device__ __forceinline__ float bflo(unsigned w) { return __uint_as_float(w << 16); }
; __device__ __forceinline__ float bfhi(unsigned w) { return __uint_as_float(w & 0xffff0000u); }
; __device__ __forceinline__ float silu_f(float g) { return g / (1.f + __expf(-g)); }
; __device__ void gmlp_item(const Params& p, int layer, int b, int n, int g, char* smem) {
;     ...
; #pragma unroll
;     for (int i = 0; i < 8; ++i) {
;       int q = tid + 256 * i, t = q >> 4, c = (q & 15) * 8;
;       float4 m0 = *reinterpret_cast<const float4*>(Tf + t * 132 + c);
;       float4 m1 = *reinterpret_cast<const float4*>(Tf + t * 132 + c + 4);
;       float mm[8] = {m0.x, m0.y, m0.z, m0.w, m1.x, m1.y, m1.z, m1.w};
;       unsigned uw[4] = {uu[i].x, uu[i].y, uu[i].z, uu[i].w};
;       unsigned gw[4] = {gt[i].x, gt[i].y, gt[i].z, gt[i].w};
;       unsigned ow[4];
; #pragma unroll
;       for (int e = 0; e < 4; ++e) {
;         float y0 = bflo(uw[e]) * mm[2 * e] * silu_f(bflo(gw[e]));
;         float y1 = bfhi(uw[e]) * mm[2 * e + 1] * silu_f(bfhi(gw[e]));
;         ow[e] = pack2(y0, y1);
;       }
;       *reinterpret_cast<uint4*>(Y + (t0 + t) * YW + g * 128 + c) = make_uint4(ow[0], ow[1], ow[2], ow[3]);
	v_mov_b32_e32 v64, v28
	v_mov_b32_e32 v65, v30
	v_pk_mul_f32 v[62:63], v[64:65], v[62:63]
	v_rcp_f32_e32 v61, v61
	s_nop 0
	v_mul_f32_e32 v61, v55, v61
	v_and_b32_e32 v24, 0xffff0000, v24
	v_mul_f32_e32 v30, 0xbfb8aa3b, v67
	v_exp_f32_e32 v57, v30
	v_rcp_f32_e32 v60, v60
	s_nop 0
	v_mul_f32_e32 v60, v66, v60
	v_mov_b32_e32 v30, v29
	v_pk_mul_f32 v[24:25], v[30:31], v[24:25]
	v_pk_add_f32 v[56:57], v[56:57], 1.0 op_sel_hi:[1,0]
	v_pk_mul_f32 v[60:61], v[60:61], v[62:63]
	v_lshlrev_b32_e32 v66, 16, v58
	v_lshlrev_b32_e32 v63, 16, v27
	v_and_b32_e32 v27, 0xffff0000, v27
	v_rcp_f32_e32 v29, v57
	s_nop 0
	v_mul_f32_e32 v29, v67, v29
	v_rcp_f32_e32 v28, v56
	s_nop 0
	v_mul_f32_e32 v28, v68, v28
	v_pk_mul_f32 v[24:25], v[28:29], v[24:25]
	v_lshlrev_b32_e32 v55, 16, v59
	v_cvt_pk_bf16_f32 v25, v61, v25
	v_cvt_pk_bf16_f32 v24, v60, v24
	v_mul_f32_e32 v28, 0xbfb8aa3b, v66
	v_mul_f32_e32 v29, 0xbfb8aa3b, v55
	v_exp_f32_e32 v28, v28
	v_exp_f32_e32 v29, v29
	v_and_b32_e32 v68, 0xffff0000, v58
	v_mul_f32_e32 v30, 0xbfb8aa3b, v68
	v_and_b32_e32 v67, 0xffff0000, v59
	v_exp_f32_e32 v60, v30
	v_pk_add_f32 v[64:65], v[28:29], 1.0 op_sel_hi:[1,0]
	global_load_dwordx4 v[28:31], v[52:53], off
	global_load_dwordx4 v[56:59], v[52:53], off offset:2048
	s_waitcnt lgkmcnt(0)
	v_mov_b32_e32 v52, v32
	v_lshlrev_b32_e32 v62, 16, v26
	v_mov_b32_e32 v53, v34
	v_pk_mul_f32 v[52:53], v[52:53], v[62:63]
	v_rcp_f32_e32 v63, v65
	s_nop 0
	v_mul_f32_e32 v63, v55, v63
	v_and_b32_e32 v26, 0xffff0000, v26
	v_mul_f32_e32 v34, 0xbfb8aa3b, v67
	v_exp_f32_e32 v61, v34
	v_rcp_f32_e32 v62, v64
	s_nop 0
	v_mul_f32_e32 v62, v66, v62
	v_mov_b32_e32 v34, v33
	v_pk_mul_f32 v[26:27], v[34:35], v[26:27]
	v_pk_add_f32 v[60:61], v[60:61], 1.0 op_sel_hi:[1,0]
	v_pk_mul_f32 v[52:53], v[62:63], v[52:53]
	s_waitcnt vmcnt(1)
	v_lshlrev_b32_e32 v63, 16, v29
	v_rcp_f32_e32 v33, v61
	s_nop 0
	v_mul_f32_e32 v33, v67, v33
	v_rcp_f32_e32 v32, v60
	s_nop 0
	v_mul_f32_e32 v32, v68, v32
	v_pk_mul_f32 v[26:27], v[32:33], v[26:27]
	s_waitcnt vmcnt(0)
	v_lshlrev_b32_e32 v67, 16, v56
	v_cvt_pk_bf16_f32 v27, v53, v27
	v_mul_f32_e32 v32, 0xbfb8aa3b, v67
	v_and_b32_e32 v69, 0xffff0000, v56
	v_lshlrev_b32_e32 v66, 16, v57
	v_exp_f32_e32 v60, v32
	v_mul_f32_e32 v32, 0xbfb8aa3b, v69
	v_exp_f32_e32 v56, v32
	v_mul_f32_e32 v32, 0xbfb8aa3b, v66
	v_exp_f32_e32 v61, v32
	s_nop 0
	v_pk_add_f32 v[60:61], v[60:61], 1.0 op_sel_hi:[1,0]
	v_and_b32_e32 v68, 0xffff0000, v57
	v_cvt_pk_bf16_f32 v26, v52, v26
	ds_read_b128 v[32:35], v54
	ds_read_b128 v[52:55], v54 offset:16
	v_lshlrev_b32_e32 v62, 16, v28
	v_and_b32_e32 v29, 0xffff0000, v29
	s_waitcnt lgkmcnt(1)
	v_mov_b32_e32 v64, v32
	v_mov_b32_e32 v65, v34
	v_pk_mul_f32 v[62:63], v[64:65], v[62:63]
	v_rcp_f32_e32 v61, v61
	s_nop 0
	v_mul_f32_e32 v61, v66, v61
	v_and_b32_e32 v28, 0xffff0000, v28
	v_mul_f32_e32 v34, 0xbfb8aa3b, v68
	v_exp_f32_e32 v57, v34
	v_rcp_f32_e32 v60, v60
	s_nop 0
	v_mul_f32_e32 v60, v67, v60
	v_pk_mul_f32 v[60:61], v[60:61], v[62:63]
	v_mov_b32_e32 v34, v33
	v_pk_add_f32 v[56:57], v[56:57], 1.0 op_sel_hi:[1,0]
	v_pk_mul_f32 v[28:29], v[34:35], v[28:29]
	s_nop 0
	v_rcp_f32_e32 v33, v57
	s_nop 0
	v_mul_f32_e32 v33, v68, v33
	v_rcp_f32_e32 v32, v56
	s_nop 0
	v_mul_f32_e32 v32, v69, v32
	v_pk_mul_f32 v[28:29], v[32:33], v[28:29]
	v_cvt_pk_bf16_f32 v28, 0, v28
	v_cvt_pk_bf16_f32 v33, 0, v60
	v_and_b32_e32 v28, 0xffff0000, v28
	v_lshlrev_b32_e32 v35, 16, v59
	v_lshlrev_b32_e32 v60, 16, v58
	v_cvt_pk_bf16_f32 v29, v61, v29
	v_or_b32_sdwa v28, v28, v33 dst_sel:DWORD dst_unused:UNUSED_PAD src0_sel:DWORD src1_sel:WORD_1
	v_mul_f32_e32 v32, 0xbfb8aa3b, v60
	v_mul_f32_e32 v33, 0xbfb8aa3b, v35
	v_exp_f32_e32 v32, v32
	v_exp_f32_e32 v33, v33
	v_and_b32_e32 v62, 0xffff0000, v58
	s_waitcnt lgkmcnt(0)
	v_mov_b32_e32 v58, v52
	v_and_b32_e32 v61, 0xffff0000, v59
	v_pk_add_f32 v[32:33], v[32:33], 1.0 op_sel_hi:[1,0]
	v_lshlrev_b32_e32 v57, 16, v31
	v_lshlrev_b32_e32 v56, 16, v30
	v_mov_b32_e32 v59, v54
	v_pk_mul_f32 v[56:57], v[58:59], v[56:57]
	v_rcp_f32_e32 v33, v33
	s_nop 0
	v_mul_f32_e32 v33, v35, v33
	v_mul_f32_e32 v34, 0xbfb8aa3b, v62
	v_mul_f32_e32 v35, 0xbfb8aa3b, v61
	v_exp_f32_e32 v34, v34
	v_exp_f32_e32 v35, v35
	v_rcp_f32_e32 v32, v32
	s_nop 0
	v_mul_f32_e32 v32, v60, v32
	v_pk_mul_f32 v[32:33], v[32:33], v[56:57]
	v_mov_b32_e32 v54, v53
	v_pk_add_f32 v[34:35], v[34:35], 1.0 op_sel_hi:[1,0]
	v_and_b32_e32 v31, 0xffff0000, v31
	v_and_b32_e32 v30, 0xffff0000, v30
	v_pk_mul_f32 v[30:31], v[54:55], v[30:31]
	v_rcp_f32_e32 v35, v35
	s_nop 0
	v_mul_f32_e32 v35, v61, v35
	s_mov_b64 s[12:13], 0
	v_rcp_f32_e32 v34, v34
	s_nop 0
	v_mul_f32_e32 v34, v62, v34
	v_pk_mul_f32 v[30:31], v[34:35], v[30:31]
	v_cvt_pk_bf16_f32 v31, v33, v31
	v_cvt_pk_bf16_f32 v30, v32, v30
	global_store_dwordx4 v[50:51], v[28:31], off
	global_store_dwordx4 v[48:49], v[24:27], off
	global_store_dwordx4 v[46:47], v[20:23], off
	global_store_dwordx4 v[44:45], v[16:19], off
	global_store_dwordx4 v[42:43], v[12:15], off
	global_store_dwordx4 v[40:41], v[8:11], off
	global_store_dwordx4 v[38:39], v[4:7], off
	global_store_dwordx4 v[36:37], v[0:3], off
	s_barrier

; template <int DH, int MODE>
; __device__ void attn_item(const Params& p, int layer, int b, int blk, int head, char* smem) {
;     ...
;   if (MODE == 0 && half == 0) linv_s[row] = 1.f / l_run;
;   __syncthreads();
;   {
;     constexpr int OST = DH + 4;
;     constexpr int CPR = DH / 8;
;     constexpr int NCH = 128 * CPR / 256;
;     float* Of = reinterpret_cast<float*>(smem);
;     uint4 gt[NCH];
; #pragma unroll
;     for (int i = 0; i < NCH; ++i) {
;       int q = tid + 256 * i, r = q / CPR, c = (q % CPR) * 8;
;       gt[i] = *reinterpret_cast<const uint4*>(P + (tq0 + r) * NP + gcol + c);
;     }
;     float lis[2][4];
; #pragma unroll
;     for (int m = 0; m < 2; ++m)
; #pragma unroll
;       for (int j = 0; j < 4; ++j) lis[m][j] = (MODE == 0) ? linv_s[wid * 32 + m * 16 + fq * 4 + j] : 1.f;
;     if (MODE == 0) __syncthreads();
; #pragma unroll
;     for (int m = 0; m < 2; ++m)
; #pragma unroll
;       for (int j = 0; j < 4; ++j) {
;         int r = wid * 32 + m * 16 + fq * 4 + j;
; #pragma unroll
;         for (int n = 0; n < NDT; ++n) Of[r * OST + n * 16 + fr] = o[m][n][j] * lis[m][j];
.LBB0_834:
	s_or_b64 exec, exec, s[14:15]
	v_lshl_add_u64 v[44:45], v[66:67], 0, s[36:37]
	v_mov_b64_e32 v[46:47], s[48:49]
	v_mad_u64_u32 v[32:33], s[14:15], v44, s45, v[46:47]
	v_mad_i32_i24 v33, v45, s45, v33
	v_lshl_add_u64 v[36:37], v[32:33], 0, v[70:71]
	v_add_u32_e32 v32, 0x100, v81
	v_ashrrev_i32_e32 v33, 31, v32
	v_lshrrev_b32_e32 v33, 29, v33
	v_add_u32_e32 v33, v32, v33
	v_ashrrev_i32_e32 v86, 3, v33
	v_and_b32_e32 v33, -8, v33
	v_sub_u32_e32 v85, v32, v33
	v_lshlrev_b32_e32 v32, 3, v85
	v_ashrrev_i32_e32 v33, 31, v32
	s_waitcnt vmcnt(2)
	v_add_u32_e32 v48, 0x200, v81
	v_lshlrev_b64 v[90:91], 1, v[32:33]
	v_ashrrev_i32_e32 v32, 31, v48
	v_lshrrev_b32_e32 v32, 29, v32
	v_add_u32_e32 v32, v48, v32
	v_ashrrev_i32_e32 v92, 3, v32
	v_and_b32_e32 v49, -8, v32
	v_add_u32_e32 v32, 0x300, v81
	v_ashrrev_i32_e32 v33, 31, v32
	v_lshrrev_b32_e32 v33, 29, v33
	v_ashrrev_i32_e32 v87, 31, v86
	v_add_u32_e32 v33, v32, v33
	v_lshl_add_u64 v[88:89], v[86:87], 0, s[36:37]
	v_ashrrev_i32_e32 v94, 3, v33
	v_and_b32_e32 v33, -8, v33
	v_mad_u64_u32 v[34:35], s[14:15], v88, s45, v[46:47]
	v_sub_u32_e32 v87, v32, v33
	v_ashrrev_i32_e32 v95, 31, v94
	v_mad_i32_i24 v35, v89, s45, v35
	v_lshlrev_b32_e32 v32, 3, v87
	v_lshl_add_u64 v[40:41], v[94:95], 0, s[36:37]
	v_lshl_add_u64 v[38:39], v[34:35], 0, v[90:91]
	v_mad_u64_u32 v[34:35], s[14:15], v40, s45, v[46:47]
	v_ashrrev_i32_e32 v33, 31, v32
	v_mad_i32_i24 v35, v41, s45, v35
	v_lshlrev_b64 v[42:43], 1, v[32:33]
	v_lshl_add_u64 v[32:33], v[34:35], 0, v[42:43]
	v_add_co_u32_e32 v32, vcc, s72, v32
	s_waitcnt lgkmcnt(0)
	s_nop 0
	v_addc_co_u32_e32 v33, vcc, 0, v33, vcc
	s_barrier
	global_load_dwordx4 v[32:35], v[32:33], off offset:512
	v_sub_u32_e32 v95, v48, v49
	v_ashrrev_i32_e32 v93, 31, v92
	v_lshlrev_b32_e32 v48, 3, v95
	v_lshl_add_u64 v[96:97], v[92:93], 0, s[36:37]
	v_mad_u64_u32 v[46:47], s[14:15], v96, s45, v[46:47]
	v_ashrrev_i32_e32 v49, 31, v48
	v_mad_i32_i24 v47, v97, s45, v47
	v_lshlrev_b64 v[98:99], 1, v[48:49]
	v_lshl_add_u64 v[100:101], v[46:47], 0, v[98:99]
	v_lshl_or_b32 v46, v75, 7, v128
	ds_read_b128 v[60:63], v46 offset:8704
	ds_read_b128 v[80:83], v46 offset:8768
	s_ashr_i32 s13, s16, 31
	s_add_u32 s12, s28, s16
	s_addc_u32 s13, s29, s13
	s_lshl_b32 s14, s83, 1
	s_add_u32 s12, s12, s14
	v_lshl_or_b32 v46, v84, 2, v64
	s_waitcnt lgkmcnt(0)
	v_mul_f32_e32 v69, v0, v80
	s_addc_u32 s13, s13, 0
	v_mul_lo_u32 v0, v66, s74
	v_mul_lo_u32 v46, v46, s74
	v_mul_f32_e32 v75, v1, v81
	v_lshl_add_u32 v66, v68, 2, v0
	v_mov_b64_e32 v[0:1], s[12:13]
	v_lshl_add_u32 v47, v73, 2, v46
	v_mul_f32_e32 v48, v16, v60
	v_mul_f32_e32 v49, v28, v60
	v_mul_f32_e32 v50, v24, v60
	v_mul_f32_e32 v51, v20, v60
	s_waitcnt vmcnt(1)
	v_mul_f32_e32 v52, v17, v61
	v_mul_f32_e32 v53, v29, v61
	v_mul_f32_e32 v54, v25, v61
	v_mul_f32_e32 v55, v21, v61
	v_mul_f32_e32 v56, v18, v62
	v_mul_f32_e32 v57, v30, v62
	v_mul_f32_e32 v58, v26, v62
	v_mul_f32_e32 v59, v22, v62
	v_mul_f32_e32 v60, v19, v63
	v_mul_f32_e32 v61, v31, v63
	v_mul_f32_e32 v62, v27, v63
	v_mul_f32_e32 v64, v23, v63
	v_mul_f32_e32 v63, v12, v80
	v_mul_f32_e32 v65, v8, v80
	v_mul_f32_e32 v67, v4, v80
	v_mul_f32_e32 v72, v13, v81
	v_mul_f32_e32 v73, v9, v81
	v_mul_f32_e32 v74, v5, v81
	v_mul_f32_e32 v76, v14, v82
	v_mul_f32_e32 v77, v10, v82
	v_mul_f32_e32 v78, v6, v82
	v_mul_f32_e32 v80, v2, v82
	v_mul_f32_e32 v79, v15, v83
	v_mul_f32_e32 v81, v11, v83
	v_mul_f32_e32 v82, v7, v83
	v_mul_f32_e32 v83, v3, v83
	v_mad_u64_u32 v[2:3], s[12:13], v44, s70, v[0:1]
	v_mad_i32_i24 v3, v45, s70, v3
	v_lshl_add_u64 v[12:13], v[2:3], 0, v[70:71]
	v_mul_lo_u32 v2, v86, s74
	v_lshl_add_u32 v46, v85, 5, v2
	v_mad_u64_u32 v[2:3], s[12:13], v88, s70, v[0:1]
	v_mad_i32_i24 v3, v89, s70, v3
	v_mad_u64_u32 v[4:5], s[12:13], v40, s70, v[0:1]
	v_lshl_add_u64 v[10:11], v[2:3], 0, v[90:91]
	v_mul_lo_u32 v2, v92, s74
	v_mad_i32_i24 v5, v41, s70, v5
	v_lshl_add_u32 v45, v95, 5, v2
	v_mad_u64_u32 v[2:3], s[12:13], v96, s70, v[0:1]
	v_lshl_add_u64 v[14:15], v[4:5], 0, v[42:43]
	v_mad_i32_i24 v3, v97, s70, v3
	v_add_co_u32_e32 v0, vcc, s72, v100
	v_lshl_add_u64 v[8:9], v[2:3], 0, v[98:99]
	v_mul_lo_u32 v2, v94, s74
	s_waitcnt vmcnt(0)
	v_lshlrev_b32_e32 v16, 16, v33
	v_lshlrev_b32_e32 v18, 16, v32
	v_mul_f32_e32 v6, 0xbfb8aa3b, v18
	v_mul_f32_e32 v7, 0xbfb8aa3b, v16
	v_exp_f32_e32 v6, v6
	v_exp_f32_e32 v7, v7
	v_addc_co_u32_e32 v1, vcc, 0, v101, vcc
	v_lshl_add_u32 v44, v87, 5, v2
	v_pk_add_f32 v[4:5], v[6:7], 1.0 op_sel_hi:[1,0]
	global_load_dwordx4 v[0:3], v[0:1], off offset:512
	v_and_b32_e32 v19, 0xffff0000, v33
	v_and_b32_e32 v20, 0xffff0000, v32
	v_mul_f32_e32 v6, 0xbfb8aa3b, v20
	v_rcp_f32_e32 v17, v5
	s_nop 0
	v_mul_f32_e32 v17, v16, v17
	v_mul_f32_e32 v7, 0xbfb8aa3b, v19
	v_exp_f32_e32 v6, v6
	v_exp_f32_e32 v7, v7
	s_nop 0
	v_pk_add_f32 v[6:7], v[6:7], 1.0 op_sel_hi:[1,0]
	v_rcp_f32_e32 v16, v4
	s_nop 0
	v_mul_f32_e32 v16, v18, v16
	v_lshlrev_b32_e32 v23, 16, v34
	v_rcp_f32_e32 v4, v7
	s_nop 0
	v_mul_f32_e32 v19, v19, v4
	v_lshlrev_b32_e32 v22, 16, v35
	v_mul_f32_e32 v4, 0xbfb8aa3b, v23
	v_mul_f32_e32 v5, 0xbfb8aa3b, v22
	v_exp_f32_e32 v4, v4
	v_exp_f32_e32 v5, v5
	v_rcp_f32_e32 v18, v6
	s_nop 0
	v_mul_f32_e32 v18, v20, v18
	v_and_b32_e32 v24, 0xffff0000, v35
	v_pk_add_f32 v[4:5], v[4:5], 1.0 op_sel_hi:[1,0]
	v_and_b32_e32 v25, 0xffff0000, v34
	v_mul_f32_e32 v6, 0xbfb8aa3b, v25
	v_exp_f32_e32 v6, v6
	v_rcp_f32_e32 v21, v5
	s_nop 0
	v_mul_f32_e32 v21, v22, v21
	v_mul_f32_e32 v7, 0xbfb8aa3b, v24
	v_exp_f32_e32 v7, v7
	s_nop 0
	v_pk_add_f32 v[6:7], v[6:7], 1.0 op_sel_hi:[1,0]
	v_rcp_f32_e32 v20, v4
	s_nop 0
	v_mul_f32_e32 v20, v23, v20
	v_rcp_f32_e32 v23, v7
	s_nop 0
	v_mul_f32_e32 v23, v24, v23
	s_waitcnt vmcnt(0)
; __device__ __forceinline__ unsigned pack2(float a, float b) { return (unsigned)f2bf(a) | ((unsigned)f2bf(b) << 16); }
; __device__ __forceinline__ float bflo(unsigned w) { return __uint_as_float(w << 16); }
; __device__ __forceinline__ float bfhi(unsigned w) { return __uint_as_float(w & 0xffff0000u); }
; __device__ __forceinline__ float silu_f(float g) { return g / (1.f + __expf(-g)); }
; template <int DH, int MODE>
; __device__ void attn_item(const Params& p, int layer, int b, int blk, int head, char* smem) {
;     ...
;     uint4 gt[NCH];
; #pragma unroll
;     for (int i = 0; i < NCH; ++i) {
;       int q = tid + 256 * i, r = q / CPR, c = (q % CPR) * 8;
;       gt[i] = *reinterpret_cast<const uint4*>(P + (tq0 + r) * NP + gcol + c);
;     }
;     float lis[2][4];
; #pragma unroll
;     for (int m = 0; m < 2; ++m)
; #pragma unroll
;       for (int j = 0; j < 4; ++j) lis[m][j] = (MODE == 0) ? linv_s[wid * 32 + m * 16 + fq * 4 + j] : 1.f;
;     if (MODE == 0) __syncthreads();
; #pragma unroll
;     for (int m = 0; m < 2; ++m)
; #pragma unroll
;       for (int j = 0; j < 4; ++j) {
;         int r = wid * 32 + m * 16 + fq * 4 + j;
; #pragma unroll
;         for (int n = 0; n < NDT; ++n) Of[r * OST + n * 16 + fr] = o[m][n][j] * lis[m][j];
;       }
;     __syncthreads();
; #pragma unroll
;     for (int i = 0; i < NCH; ++i) {
;       int q = tid + 256 * i, r = q / CPR, c = (q % CPR) * 8;
;       float4 m0 = *reinterpret_cast<const float4*>(Of + r * OST + c);
;       float4 m1 = *reinterpret_cast<const float4*>(Of + r * OST + c + 4);
;       float mm[8] = {m0.x, m0.y, m0.z, m0.w, m1.x, m1.y, m1.z, m1.w};
;       unsigned gw[4] = {gt[i].x, gt[i].y, gt[i].z, gt[i].w};
;       unsigned ow[4];
; #pragma unroll
;       for (int e = 0; e < 4; ++e)
;         ow[e] = pack2(mm[2 * e] * silu_f(bflo(gw[e])), mm[2 * e + 1] * silu_f(bfhi(gw[e])));
	v_lshlrev_b32_e32 v24, 16, v1
	v_lshlrev_b32_e32 v26, 16, v0
	v_mul_f32_e32 v4, 0xbfb8aa3b, v26
	v_mul_f32_e32 v5, 0xbfb8aa3b, v24
	v_exp_f32_e32 v4, v4
	v_exp_f32_e32 v5, v5
	v_and_b32_e32 v27, 0xffff0000, v1
	v_rcp_f32_e32 v22, v6
	s_nop 0
	v_mul_f32_e32 v22, v25, v22
	v_pk_add_f32 v[4:5], v[4:5], 1.0 op_sel_hi:[1,0]
	v_and_b32_e32 v28, 0xffff0000, v0
	v_mul_f32_e32 v0, 0xbfb8aa3b, v28
	v_exp_f32_e32 v6, v0
	v_lshlrev_b32_e32 v32, 16, v3
	v_mul_f32_e32 v7, 0xbfb8aa3b, v27
	v_rcp_f32_e32 v1, v5
	s_nop 0
	v_mul_f32_e32 v1, v24, v1
	v_exp_f32_e32 v7, v7
	s_nop 0
	v_pk_add_f32 v[24:25], v[6:7], 1.0 op_sel_hi:[1,0]
	v_rcp_f32_e32 v0, v4
	s_nop 0
	v_mul_f32_e32 v0, v26, v0
	v_lshlrev_b32_e32 v33, 16, v2
	v_rcp_f32_e32 v25, v25
	s_nop 0
	v_mul_f32_e32 v25, v27, v25
	v_add_co_u32_e64 v4, s[12:13], s72, v38
	s_nop 0
	s_nop 0
	v_addc_co_u32_e64 v5, s[12:13], 0, v39, s[12:13]
	global_load_dwordx4 v[4:7], v[4:5], off offset:512
	v_mul_f32_e32 v26, 0xbfb8aa3b, v33
	v_mul_f32_e32 v27, 0xbfb8aa3b, v32
	v_exp_f32_e32 v26, v26
	v_exp_f32_e32 v27, v27
	v_and_b32_e32 v30, 0xffff0000, v3
	v_rcp_f32_e32 v24, v24
	s_nop 0
	v_mul_f32_e32 v24, v28, v24
	v_pk_add_f32 v[26:27], v[26:27], 1.0 op_sel_hi:[1,0]
	v_and_b32_e32 v38, 0xffff0000, v2
	v_mul_f32_e32 v2, 0xbfb8aa3b, v38
	v_exp_f32_e32 v28, v2
	v_mul_f32_e32 v29, 0xbfb8aa3b, v30
	v_exp_f32_e32 v29, v29
	v_rcp_f32_e32 v3, v27
	s_nop 0
	v_mul_f32_e32 v3, v32, v3
	v_pk_add_f32 v[28:29], v[28:29], 1.0 op_sel_hi:[1,0]
	v_rcp_f32_e32 v2, v26
	s_nop 0
	v_mul_f32_e32 v2, v33, v2
	v_rcp_f32_e32 v27, v29
	s_nop 0
	v_mul_f32_e32 v27, v30, v27
	v_add_co_u32_e64 v30, s[12:13], s72, v36
	s_nop 0
	s_nop 0
	v_addc_co_u32_e64 v31, s[12:13], 0, v37, s[12:13]
	global_load_dwordx4 v[32:35], v[30:31], off offset:512
	v_rcp_f32_e32 v26, v28
	s_nop 0
	v_mul_f32_e32 v26, v38, v26
	s_barrier
	s_waitcnt vmcnt(1)
	v_lshlrev_b32_e32 v36, 16, v5
	v_lshlrev_b32_e32 v37, 16, v4
	v_mul_f32_e32 v30, 0xbfb8aa3b, v37
	v_mul_f32_e32 v31, 0xbfb8aa3b, v36
	v_exp_f32_e32 v30, v30
	v_exp_f32_e32 v31, v31
	v_and_b32_e32 v38, 0xffff0000, v5
	v_and_b32_e32 v39, 0xffff0000, v4
	v_mul_f32_e32 v4, 0xbfb8aa3b, v39
	v_pk_add_f32 v[28:29], v[30:31], 1.0 op_sel_hi:[1,0]
	v_exp_f32_e32 v30, v4
	ds_write2_b32 v47, v48, v49 offset1:16
	ds_write2_b32 v47, v50, v51 offset0:32 offset1:48
	ds_write2_b32 v47, v52, v53 offset0:68 offset1:84
	ds_write2_b32 v47, v54, v55 offset0:100 offset1:116
	ds_write2_b32 v47, v56, v57 offset0:136 offset1:152
	ds_write2_b32 v47, v58, v59 offset0:168 offset1:184
	ds_write2_b32 v47, v60, v61 offset0:204 offset1:220
	ds_write2_b32 v47, v62, v64 offset0:236 offset1:252
	v_mul_f32_e32 v31, 0xbfb8aa3b, v38
	v_exp_f32_e32 v31, v31
	v_rcp_f32_e32 v5, v29
	s_nop 0
	v_mul_f32_e32 v5, v36, v5
	v_pk_add_f32 v[30:31], v[30:31], 1.0 op_sel_hi:[1,0]
	v_rcp_f32_e32 v4, v28
	s_nop 0
	v_mul_f32_e32 v4, v37, v4
	v_rcp_f32_e32 v29, v31
	s_nop 0
	v_mul_f32_e32 v29, v38, v29
	v_lshlrev_b32_e32 v38, 16, v7
	v_lshlrev_b32_e32 v40, 16, v6
	v_mul_f32_e32 v36, 0xbfb8aa3b, v40
	v_mul_f32_e32 v37, 0xbfb8aa3b, v38
	v_exp_f32_e32 v36, v36
	v_exp_f32_e32 v37, v37
	v_rcp_f32_e32 v28, v30
	s_nop 0
	v_mul_f32_e32 v28, v39, v28
	v_and_b32_e32 v39, 0xffff0000, v7
	v_pk_add_f32 v[30:31], v[36:37], 1.0 op_sel_hi:[1,0]
	v_and_b32_e32 v41, 0xffff0000, v6
	v_mul_f32_e32 v6, 0xbfb8aa3b, v41
	v_exp_f32_e32 v36, v6
	v_mul_f32_e32 v37, 0xbfb8aa3b, v39
	v_exp_f32_e32 v37, v37
	v_rcp_f32_e32 v7, v31
	s_nop 0
	v_mul_f32_e32 v7, v38, v7
	v_pk_add_f32 v[36:37], v[36:37], 1.0 op_sel_hi:[1,0]
	v_rcp_f32_e32 v6, v30
	s_nop 0
	v_mul_f32_e32 v6, v40, v6
	v_rcp_f32_e32 v31, v37
	s_nop 0
	v_mul_f32_e32 v31, v39, v31
	s_waitcnt vmcnt(0)
	v_lshlrev_b32_e32 v42, 16, v33
	v_lshlrev_b32_e32 v43, 16, v32
	v_mul_f32_e32 v38, 0xbfb8aa3b, v43
	v_mul_f32_e32 v39, 0xbfb8aa3b, v42
	v_exp_f32_e32 v38, v38
	v_exp_f32_e32 v39, v39
	v_rcp_f32_e32 v30, v36
	s_nop 0
	v_mul_f32_e32 v30, v41, v30
	v_and_b32_e32 v68, 0xffff0000, v33
	v_pk_add_f32 v[36:37], v[38:39], 1.0 op_sel_hi:[1,0]
	v_and_b32_e32 v39, 0xffff0000, v32
	v_mul_f32_e32 v32, 0xbfb8aa3b, v39
	v_exp_f32_e32 v32, v32
	v_rcp_f32_e32 v41, v37
	s_nop 0
	v_mul_f32_e32 v41, v42, v41
	v_mul_f32_e32 v33, 0xbfb8aa3b, v68
	v_exp_f32_e32 v33, v33
	s_nop 0
	v_pk_add_f32 v[32:33], v[32:33], 1.0 op_sel_hi:[1,0]
	v_rcp_f32_e32 v40, v36
	s_nop 0
	v_mul_f32_e32 v40, v43, v40
	v_lshlrev_b32_e32 v70, 16, v34
	v_rcp_f32_e32 v43, v33
	s_nop 0
	v_mul_f32_e32 v43, v68, v43
	v_lshlrev_b32_e32 v38, 16, v35
	v_mul_f32_e32 v36, 0xbfb8aa3b, v70
	v_mul_f32_e32 v37, 0xbfb8aa3b, v38
	v_exp_f32_e32 v36, v36
	v_exp_f32_e32 v37, v37
	v_rcp_f32_e32 v42, v32
	s_nop 0
	v_mul_f32_e32 v42, v39, v42
	v_and_b32_e32 v39, 0xffff0000, v35
	v_pk_add_f32 v[32:33], v[36:37], 1.0 op_sel_hi:[1,0]
	v_and_b32_e32 v68, 0xffff0000, v34
	v_mul_f32_e32 v34, 0xbfb8aa3b, v68
	v_exp_f32_e32 v34, v34
	v_rcp_f32_e32 v71, v33
	s_nop 0
	v_mul_f32_e32 v71, v38, v71
	v_mul_f32_e32 v35, 0xbfb8aa3b, v39
	v_exp_f32_e32 v35, v35
	s_nop 0
	v_pk_add_f32 v[36:37], v[34:35], 1.0 op_sel_hi:[1,0]
	v_rcp_f32_e32 v33, v32
	s_nop 0
	v_mul_f32_e32 v70, v70, v33
	v_rcp_f32_e32 v85, v37
	s_nop 0
	v_mul_f32_e32 v85, v39, v85
	v_add_u32_e32 v32, 0x1000, v47
	ds_write2_b32 v32, v63, v65 offset0:64 offset1:80
	ds_write2_b32 v32, v67, v69 offset0:96 offset1:112
	ds_write2_b32 v32, v72, v73 offset0:132 offset1:148
	ds_write2_b32 v32, v74, v75 offset0:164 offset1:180
	ds_write2_b32 v32, v76, v77 offset0:200 offset1:216
	ds_write2_b32 v32, v78, v80 offset0:232 offset1:248
	v_add_u32_e32 v32, 0x1400, v47
	ds_write2_b32 v32, v79, v81 offset0:12 offset1:28
	ds_write2_b32 v32, v82, v83 offset0:44 offset1:60
	s_waitcnt lgkmcnt(0)
	s_barrier
; __device__ __forceinline__ unsigned pack2(float a, float b) { return (unsigned)f2bf(a) | ((unsigned)f2bf(b) << 16); }
; __device__ __forceinline__ float bflo(unsigned w) { return __uint_as_float(w << 16); }
; __device__ __forceinline__ float bfhi(unsigned w) { return __uint_as_float(w & 0xffff0000u); }
; __device__ __forceinline__ float silu_f(float g) { return g / (1.f + __expf(-g)); }
; template <int DH, int MODE>
; __device__ void attn_item(const Params& p, int layer, int b, int blk, int head, char* smem) {
;     ...
; #pragma unroll
;     for (int i = 0; i < NCH; ++i) {
;       int q = tid + 256 * i, r = q / CPR, c = (q % CPR) * 8;
;       float4 m0 = *reinterpret_cast<const float4*>(Of + r * OST + c);
;       float4 m1 = *reinterpret_cast<const float4*>(Of + r * OST + c + 4);
;       float mm[8] = {m0.x, m0.y, m0.z, m0.w, m1.x, m1.y, m1.z, m1.w};
;       unsigned gw[4] = {gt[i].x, gt[i].y, gt[i].z, gt[i].w};
;       unsigned ow[4];
; #pragma unroll
;       for (int e = 0; e < 4; ++e)
;         ow[e] = pack2(mm[2 * e] * silu_f(bflo(gw[e])), mm[2 * e + 1] * silu_f(bfhi(gw[e])));
;       *reinterpret_cast<uint4*>(Y + (tq0 + r) * YW + ycol + c) = make_uint4(ow[0], ow[1], ow[2], ow[3]);
;     }
	ds_read_b128 v[32:35], v66
	v_rcp_f32_e32 v84, v36
	s_nop 0
	v_mul_f32_e32 v84, v68, v84
	ds_read_b128 v[36:39], v66 offset:16
	v_add_co_u32_e32 v12, vcc, s77, v12
	s_waitcnt lgkmcnt(1)
	v_mov_b32_e32 v48, v32
	v_mov_b32_e32 v49, v34
	v_pk_mul_f32 v[40:41], v[40:41], v[48:49]
	v_mov_b32_e32 v34, v33
	v_pk_mul_f32 v[32:33], v[42:43], v[34:35]
	v_cvt_pk_bf16_f32 v33, v41, v33
	v_cvt_pk_bf16_f32 v32, v40, v32
	s_waitcnt lgkmcnt(0)
	v_mov_b32_e32 v34, v36
	v_mov_b32_e32 v35, v38
	v_pk_mul_f32 v[34:35], v[70:71], v[34:35]
	v_mov_b32_e32 v38, v37
	v_pk_mul_f32 v[36:37], v[84:85], v[38:39]
	v_cvt_pk_bf16_f32 v35, v35, v37
	v_cvt_pk_bf16_f32 v34, v34, v36
	ds_read_b128 v[36:39], v46
	v_addc_co_u32_e32 v13, vcc, 0, v13, vcc
	global_store_dwordx4 v[12:13], v[32:35], off offset:1024
	s_nop 0
	ds_read_b128 v[32:35], v46 offset:16
	s_waitcnt lgkmcnt(1)
	v_mov_b32_e32 v12, v36
	v_mov_b32_e32 v13, v38
	v_pk_mul_f32 v[4:5], v[4:5], v[12:13]
	v_mov_b32_e32 v38, v37
	v_pk_mul_f32 v[12:13], v[28:29], v[38:39]
	v_cvt_pk_bf16_f32 v5, v5, v13
	v_cvt_pk_bf16_f32 v4, v4, v12
	s_waitcnt lgkmcnt(0)
	v_mov_b32_e32 v12, v32
	v_mov_b32_e32 v13, v34
	v_pk_mul_f32 v[6:7], v[6:7], v[12:13]
	v_mov_b32_e32 v34, v33
	v_pk_mul_f32 v[12:13], v[30:31], v[34:35]
	ds_read_b128 v[28:31], v45
	v_add_co_u32_e32 v10, vcc, s77, v10
	v_cvt_pk_bf16_f32 v7, v7, v13
	v_cvt_pk_bf16_f32 v6, v6, v12
	v_addc_co_u32_e32 v11, vcc, 0, v11, vcc
	global_store_dwordx4 v[10:11], v[4:7], off offset:1024
	s_waitcnt lgkmcnt(0)
	v_mov_b32_e32 v10, v28
	v_mov_b32_e32 v11, v30
	ds_read_b128 v[4:7], v45 offset:16
	v_pk_mul_f32 v[0:1], v[0:1], v[10:11]
	v_mov_b32_e32 v30, v29
	v_pk_mul_f32 v[10:11], v[24:25], v[30:31]
	v_cvt_pk_bf16_f32 v1, v1, v11
	v_cvt_pk_bf16_f32 v0, v0, v10
	s_waitcnt lgkmcnt(0)
	v_mov_b32_e32 v10, v4
	v_mov_b32_e32 v11, v6
	v_pk_mul_f32 v[2:3], v[2:3], v[10:11]
	v_mov_b32_e32 v6, v5
	v_pk_mul_f32 v[4:5], v[26:27], v[6:7]
	v_cvt_pk_bf16_f32 v3, v3, v5
	v_cvt_pk_bf16_f32 v2, v2, v4
	ds_read_b128 v[4:7], v44
	v_add_co_u32_e32 v8, vcc, s77, v8
	s_nop 1
	v_addc_co_u32_e32 v9, vcc, 0, v9, vcc
	global_store_dwordx4 v[8:9], v[0:3], off offset:1024
	s_waitcnt lgkmcnt(0)
	v_mov_b32_e32 v8, v4
	v_mov_b32_e32 v9, v6
	ds_read_b128 v[0:3], v44 offset:16
	v_pk_mul_f32 v[8:9], v[16:17], v[8:9]
	v_mov_b32_e32 v6, v5
	v_pk_mul_f32 v[4:5], v[18:19], v[6:7]
	v_cvt_pk_bf16_f32 v5, v9, v5
	v_cvt_pk_bf16_f32 v4, v8, v4
	s_waitcnt lgkmcnt(0)
	v_mov_b32_e32 v6, v0
	v_mov_b32_e32 v7, v2
	v_pk_mul_f32 v[6:7], v[20:21], v[6:7]
	v_mov_b32_e32 v2, v1
	v_pk_mul_f32 v[0:1], v[22:23], v[2:3]
	v_cvt_pk_bf16_f32 v6, v6, v0
	v_add_co_u32_e32 v0, vcc, 0x184a1000, v14
	v_cvt_pk_bf16_f32 v7, v7, v1
	s_nop 0
	v_addc_co_u32_e32 v1, vcc, 0, v15, vcc
	global_store_dwordx4 v[0:1], v[4:7], off offset:1024
	s_barrier

; __device__ __forceinline__ unsigned pack2(float a, float b) { return (unsigned)f2bf(a) | ((unsigned)f2bf(b) << 16); }
; template <int DH, int MODE>
; __device__ void attn_item(const Params& p, int layer, int b, int blk, int head, char* smem) {
;     ...
; #pragma unroll 2
;         for (int s8 = 0; s8 < 4; ++s8) {
;           float4 va = s4[2 * s8], vb = s4[2 * s8 + 1];
;           float e[8] = {va.x, va.y, va.z, va.w, vb.x, vb.y, vb.z, vb.w};
;           float pv[8];
; #pragma unroll
;           for (int k = 0; k < 8; ++k) {
;             bool valid = (kpb + s8 * 8 + k) < qpos;
;             pv[k] = valid ? __builtin_amdgcn_exp2f(e[k] + offs) : 0.f;
;           }
;           uint4 ov;
;           ov.x = pack2(pv[0], pv[1]); ov.y = pack2(pv[2], pv[3]);
;           ov.z = pack2(pv[4], pv[5]); ov.w = pack2(pv[6], pv[7]);
;           *reinterpret_cast<uint4*>(prow + s8 * 16) = ov;
;         }
.LBB0_849:
	s_or_b64 exec, exec, s[52:53]
	s_waitcnt lgkmcnt(3)
	v_add_f32_e32 v152, v176, v152
	v_exp_f32_e32 v152, v152
	s_waitcnt lgkmcnt(1)
	v_add_f32_e32 v149, v176, v149
	v_exp_f32_e32 v149, v149
	v_add_u32_e32 v182, 0x3fc9, v178
	v_add_f32_e32 v151, v176, v151
	v_add_f32_e32 v148, v176, v148
	v_cmp_lt_i32_e32 vcc, v182, v144
	v_exp_f32_e32 v185, v151
	v_exp_f32_e32 v186, v148
	v_add_u32_e32 v148, 0x3fce, v178
	s_waitcnt lgkmcnt(0)
	v_add_f32_e32 v151, v176, v180
	v_cndmask_b32_e32 v152, 0, v152, vcc
	v_exp_f32_e32 v151, v151
	v_cmp_lt_i32_e32 vcc, v148, v144
	v_add_u32_e32 v148, 0x3fcf, v178
	v_add_f32_e32 v153, v176, v153
	v_cndmask_b32_e32 v149, 0, v149, vcc
	v_cmp_lt_i32_e32 vcc, v148, v144
	v_cvt_pk_bf16_f32 v148, 0, v179
	v_exp_f32_e32 v153, v153
	v_lshrrev_b32_e32 v148, 16, v148
	v_cvt_pk_bf16_f32 v152, 0, v152
	v_add_f32_e32 v150, v176, v150
	v_cndmask_b32_e32 v151, 0, v151, vcc
	v_and_or_b32 v148, v152, s54, v148
	v_or_b32_e32 v182, 2, v181
	v_exp_f32_e32 v150, v150
	v_cvt_pk_bf16_f32 v149, 0, v149
	v_or_b32_e32 v183, 4, v181
	v_lshrrev_b32_e32 v149, 16, v149
	v_cvt_pk_bf16_f32 v151, 0, v151
	v_cmp_lt_i32_e32 vcc, v182, v144
	v_or_b32_e32 v184, 5, v181
	v_or_b32_e32 v181, 3, v181
	v_and_or_b32 v151, v151, s54, v149
	v_cndmask_b32_e32 v149, 0, v153, vcc
	v_cmp_lt_i32_e32 vcc, v183, v131
	v_cvt_pk_bf16_f32 v149, 0, v149
	s_nop 0
	v_cndmask_b32_e32 v152, 0, v185, vcc
	v_cmp_lt_i32_e32 vcc, v181, v144
	s_nop 0
	s_nop 0
	v_cndmask_b32_e32 v150, 0, v150, vcc
	v_cmp_lt_i32_e32 vcc, v184, v131
	v_cvt_pk_bf16_f32 v150, 0, v150
	s_nop 0
	v_cndmask_b32_e32 v153, 0, v186, vcc
	v_and_b32_e32 v178, 0xffff0000, v150
	v_cvt_pk_bf16_f32 v150, v152, v153
	v_or_b32_sdwa v149, v178, v149 dst_sel:DWORD dst_unused:UNUSED_PAD src0_sel:DWORD src1_sel:WORD_1
	s_add_i32 s88, s88, 16
	ds_write_b128 v175, v[148:151] offset:16
	v_add_u32_e32 v177, 64, v177
	s_cmp_eq_u32 s88, 32
	v_add_u32_e32 v175, 32, v175
	s_cbranch_scc1 .LBB0_855

; __device__ __forceinline__ unsigned pack2(float a, float b) { return (unsigned)f2bf(a) | ((unsigned)f2bf(b) << 16); }
; template <int DH, int MODE>
; __device__ void attn_item(const Params& p, int layer, int b, int blk, int head, char* smem) {
;     ...
; #pragma unroll 2
;         for (int s8 = 0; s8 < 4; ++s8) {
;           float4 va = s4[2 * s8], vb = s4[2 * s8 + 1];
;           float e[8] = {va.x, va.y, va.z, va.w, vb.x, vb.y, vb.z, vb.w};
;           float pv[8];
; #pragma unroll
;           for (int k = 0; k < 8; ++k) {
;             bool valid = (kpb + s8 * 8 + k) < qpos;
;             pv[k] = valid ? __builtin_amdgcn_exp2f(e[k] + offs) : 0.f;
;           }
;           uint4 ov;
;           ov.x = pack2(pv[0], pv[1]); ov.y = pack2(pv[2], pv[3]);
;           ov.z = pack2(pv[4], pv[5]); ov.w = pack2(pv[6], pv[7]);
;           *reinterpret_cast<uint4*>(prow + s8 * 16) = ov;
;         }
.LBB0_852:
	s_or_b64 exec, exec, s[52:53]
	s_waitcnt lgkmcnt(3)
	v_add_f32_e32 v152, v176, v152
	v_exp_f32_e32 v152, v152
	s_waitcnt lgkmcnt(1)
	v_add_f32_e32 v149, v176, v149
	v_exp_f32_e32 v149, v149
	v_add_u32_e32 v183, 0x3fc1, v178
	v_add_f32_e32 v151, v176, v151
	v_add_f32_e32 v148, v176, v148
	v_cmp_lt_i32_e32 vcc, v183, v144
	v_exp_f32_e32 v186, v151
	v_exp_f32_e32 v187, v148
	v_add_u32_e32 v148, 0x3fc6, v178
	s_waitcnt lgkmcnt(0)
	v_add_f32_e32 v151, v176, v180
	v_cndmask_b32_e32 v152, 0, v152, vcc
	v_exp_f32_e32 v151, v151
	v_cmp_lt_i32_e32 vcc, v148, v144
	v_add_u32_e32 v148, 0x3fc7, v178
	v_add_f32_e32 v153, v176, v153
	v_cndmask_b32_e32 v149, 0, v149, vcc
	v_cmp_lt_i32_e32 vcc, v148, v144
	v_cvt_pk_bf16_f32 v148, 0, v181
	v_exp_f32_e32 v153, v153
	v_lshrrev_b32_e32 v148, 16, v148
	v_cvt_pk_bf16_f32 v152, 0, v152
	v_add_f32_e32 v150, v176, v150
	v_cndmask_b32_e32 v151, 0, v151, vcc
	v_and_or_b32 v148, v152, s54, v148
	v_or_b32_e32 v183, 2, v182
	v_exp_f32_e32 v150, v150
	v_cvt_pk_bf16_f32 v149, 0, v149
	v_or_b32_e32 v184, 4, v182
	v_lshrrev_b32_e32 v149, 16, v149
	v_cvt_pk_bf16_f32 v151, 0, v151
	v_cmp_lt_i32_e32 vcc, v183, v144
	v_or_b32_e32 v185, 5, v182
	v_or_b32_e32 v182, 3, v182
	v_and_or_b32 v151, v151, s54, v149
	v_cndmask_b32_e32 v149, 0, v153, vcc
	v_cmp_lt_i32_e32 vcc, v184, v131
	v_cvt_pk_bf16_f32 v149, 0, v149
	s_nop 0
	v_cndmask_b32_e32 v152, 0, v186, vcc
	v_cmp_lt_i32_e32 vcc, v182, v144
	s_nop 0
	s_nop 0
	v_cndmask_b32_e32 v150, 0, v150, vcc
	v_cmp_lt_i32_e32 vcc, v185, v131
	v_cvt_pk_bf16_f32 v150, 0, v150
	s_nop 0
	v_cndmask_b32_e32 v153, 0, v187, vcc
	v_and_b32_e32 v180, 0xffff0000, v150
	v_cvt_pk_bf16_f32 v150, v152, v153
	v_or_b32_sdwa v149, v180, v149 dst_sel:DWORD dst_unused:UNUSED_PAD src0_sel:DWORD src1_sel:WORD_1
	ds_write_b128 v175, v[148:151]
	ds_read2_b32 v[152:153], v177 offset0:9 offset1:10
	ds_read2_b32 v[150:151], v177 offset0:11 offset1:12
	ds_read2_b32 v[148:149], v177 offset0:13 offset1:14
	ds_read_b32 v180, v177 offset:60
	v_add_u32_e32 v181, 0x3fc8, v178
	v_cmp_lt_i32_e32 vcc, v181, v144
	s_and_saveexec_b64 s[52:53], vcc
	s_cbranch_execz .LBB0_849
	ds_read_b32 v179, v177 offset:32
	s_waitcnt lgkmcnt(0)
	v_add_f32_e32 v179, v176, v179
	v_exp_f32_e32 v179, v179
	s_branch .LBB0_849

; __device__ __forceinline__ unsigned pack2(float a, float b) { return (unsigned)f2bf(a) | ((unsigned)f2bf(b) << 16); }
; __device__ void convert_weights(const Params& p, int layer, char* smem) {
;     ...
;     __syncthreads();
; #pragma unroll
;     for (int i = 0; i < 4; ++i) {
;       int kk = (tid >> 4) + 16 * i, nn = (tid & 15) * 4;
;       float4 v = *reinterpret_cast<const float4*>(src + (size_t)(kt * 64 + kk) * N + nt * 64 + nn);
;       tile[kk * 65 + nn + 0] = v.x; tile[kk * 65 + nn + 1] = v.y;
;       tile[kk * 65 + nn + 2] = v.z; tile[kk * 65 + nn + 3] = v.w;
;     }
;     __syncthreads();
; #pragma unroll
;     for (int i = 0; i < 2; ++i) {
;       int nn = (tid >> 3) + 32 * i, kk0 = (tid & 7) * 8;
;       uint4 o;
;       o.x = pack2(tile[(kk0 + 0) * 65 + nn], tile[(kk0 + 1) * 65 + nn]);
;       o.y = pack2(tile[(kk0 + 2) * 65 + nn], tile[(kk0 + 3) * 65 + nn]);
;       o.z = pack2(tile[(kk0 + 4) * 65 + nn], tile[(kk0 + 5) * 65 + nn]);
;       o.w = pack2(tile[(kk0 + 6) * 65 + nn], tile[(kk0 + 7) * 65 + nn]);
;       *reinterpret_cast<uint4*>(dst + (size_t)(nt * 64 + nn) * K + kt * 64 + kk0) = o;
;     }
.LBB0_1023:
	s_andn2_b64 vcc, exec, s[36:37]
	s_cbranch_vccnz .LBB0_1005
	s_lshl_b32 s42, s51, 6
	s_ashr_i32 s43, s42, 31
	s_lshl_b32 s36, s50, 6
	s_lshl_b64 s[50:51], s[42:43], 2
	s_add_u32 s38, s38, s50
	v_add_u32_e32 v9, s36, v19
	s_addc_u32 s39, s39, s51
	v_add_u32_e32 v13, 16, v9
	v_lshl_add_u64 v[16:17], s[38:39], 0, v[0:1]
	v_mad_i64_i32 v[32:33], s[38:39], s40, v9, 0
	v_mad_i64_i32 v[34:35], s[38:39], s40, v13, 0
	v_lshl_add_u64 v[32:33], v[32:33], 2, v[16:17]
	v_lshl_add_u64 v[36:37], v[34:35], 2, v[16:17]
	s_barrier
	global_load_dwordx4 v[32:35], v[32:33], off
	s_nop 0
	global_load_dwordx4 v[36:39], v[36:37], off
	v_add_u32_e32 v13, 32, v9
	v_mad_i64_i32 v[40:41], s[38:39], s40, v13, 0
	v_lshl_add_u64 v[40:41], v[40:41], 2, v[16:17]
	v_add_u32_e32 v9, 48, v9
	global_load_dwordx4 v[40:43], v[40:41], off
	v_mad_i64_i32 v[44:45], s[38:39], s40, v9, 0
	v_lshl_add_u64 v[16:17], v[44:45], 2, v[16:17]
	global_load_dwordx4 v[44:47], v[16:17], off
	v_add_u32_e32 v9, s42, v20
	v_ashrrev_i32_e32 v48, 31, v9
	v_mul_lo_u32 v50, s27, v9
	v_mad_u64_u32 v[16:17], s[38:39], s26, v9, 0
	v_add_u32_e32 v9, 32, v9
	v_ashrrev_i32_e32 v52, 31, v9
	s_ashr_i32 s37, s36, 31
	v_mov_b32_e32 v13, v1
	v_mul_lo_u32 v51, s26, v48
	v_mul_lo_u32 v53, s27, v9
	v_mad_u64_u32 v[48:49], s[38:39], s26, v9, 0
	v_mul_lo_u32 v9, s26, v52
	v_lshl_add_u64 v[14:15], s[36:37], 1, v[14:15]
	v_add3_u32 v17, v17, v51, v50
	v_add3_u32 v49, v49, v9, v53
	v_lshl_add_u64 v[14:15], v[14:15], 0, v[12:13]
	v_lshl_add_u64 v[50:51], v[16:17], 1, v[14:15]
	v_lshl_add_u64 v[48:49], v[48:49], 1, v[14:15]
	s_waitcnt vmcnt(3)
	ds_write2_b32 v23, v32, v33 offset1:1
	ds_write2_b32 v23, v34, v35 offset0:2 offset1:3
	s_waitcnt vmcnt(2)
	ds_write2_b32 v24, v36, v37 offset1:1
	ds_write2_b32 v25, v38, v39 offset1:1
	s_waitcnt vmcnt(1)
	ds_write2_b32 v26, v40, v41 offset1:1
	ds_write2_b32 v27, v42, v43 offset1:1
	s_waitcnt vmcnt(0)
	ds_write2_b32 v28, v44, v45 offset1:1
	ds_write2_b32 v29, v46, v47 offset1:1
	s_waitcnt lgkmcnt(0)
	s_barrier
	ds_read2_b32 v[14:15], v22 offset1:32
	ds_read2_b32 v[32:33], v22 offset0:65 offset1:97
	ds_read2_b32 v[34:35], v22 offset0:130 offset1:162
	ds_read2_b32 v[36:37], v22 offset0:195 offset1:227
	ds_read2_b32 v[38:39], v30 offset0:4 offset1:36
	ds_read2_b32 v[40:41], v30 offset0:69 offset1:101
	ds_read2_b32 v[42:43], v30 offset0:134 offset1:166
	ds_read2_b32 v[44:45], v30 offset0:199 offset1:231
	s_waitcnt lgkmcnt(7)
	s_waitcnt lgkmcnt(4)
	s_waitcnt lgkmcnt(0)
	v_cvt_pk_bf16_f32 v13, 0, v14
	v_cvt_pk_bf16_f32 v14, 0, v36
	v_cvt_pk_bf16_f32 v16, 0, v32
	v_cvt_pk_bf16_f32 v9, 0, v34
	v_cvt_pk_bf16_f32 v36, 0, v40
	v_and_b32_e32 v14, 0xffff0000, v14
	v_and_b32_e32 v16, 0xffff0000, v16
	v_cvt_pk_bf16_f32 v32, 0, v38
	v_cvt_pk_bf16_f32 v38, 0, v15
	v_and_b32_e32 v36, 0xffff0000, v36
	v_or_b32_sdwa v15, v14, v9 dst_sel:DWORD dst_unused:UNUSED_PAD src0_sel:DWORD src1_sel:WORD_1
	v_or_b32_sdwa v14, v16, v13 dst_sel:DWORD dst_unused:UNUSED_PAD src0_sel:DWORD src1_sel:WORD_1
	v_cvt_pk_bf16_f32 v17, v42, v44
	v_or_b32_sdwa v16, v36, v32 dst_sel:DWORD dst_unused:UNUSED_PAD src0_sel:DWORD src1_sel:WORD_1
	global_store_dwordx4 v[50:51], v[14:17], off
	s_nop 1
	v_cvt_pk_bf16_f32 v14, 0, v33
	s_nop 0
	v_cvt_pk_bf16_f32 v15, v35, v37
	v_cvt_pk_bf16_f32 v17, 0, v41
	v_and_b32_e32 v14, 0xffff0000, v14
	v_cvt_pk_bf16_f32 v13, 0, v39
	v_and_b32_e32 v32, 0xffff0000, v17
	v_or_b32_sdwa v14, v14, v38 dst_sel:DWORD dst_unused:UNUSED_PAD src0_sel:DWORD src1_sel:WORD_1
	v_cvt_pk_bf16_f32 v17, v43, v45
	v_or_b32_sdwa v16, v32, v13 dst_sel:DWORD dst_unused:UNUSED_PAD src0_sel:DWORD src1_sel:WORD_1
	global_store_dwordx4 v[48:49], v[14:17], off
	s_branch .LBB0_1005

; template <int DH, int MODE>
; __device__ void attn_item(const Params& p, int layer, int b, int blk, int head, char* smem) {
;     ...
;   {
;     constexpr int OST = DH + 4;
;     constexpr int CPR = DH / 8;
;     constexpr int NCH = 128 * CPR / 256;
;     float* Of = reinterpret_cast<float*>(smem);
;     uint4 gt[NCH];
; #pragma unroll
;     for (int i = 0; i < NCH; ++i) {
;       int q = tid + 256 * i, r = q / CPR, c = (q % CPR) * 8;
;       gt[i] = *reinterpret_cast<const uint4*>(P + (tq0 + r) * NP + gcol + c);
;     }
;     float lis[2][4];
; #pragma unroll
;     for (int m = 0; m < 2; ++m)
; #pragma unroll
;       for (int j = 0; j < 4; ++j) lis[m][j] = (MODE == 0) ? linv_s[wid * 32 + m * 16 + fq * 4 + j] : 1.f;
;     if (MODE == 0) __syncthreads();
; #pragma unroll
;     for (int m = 0; m < 2; ++m)
; #pragma unroll
;       for (int j = 0; j < 4; ++j) {
;         int r = wid * 32 + m * 16 + fq * 4 + j;
; #pragma unroll
;         for (int n = 0; n < NDT; ++n) Of[r * OST + n * 16 + fr] = o[m][n][j] * lis[m][j];
;       }
.LBB0_1112:
	s_ashr_i32 s7, s79, 31
	s_add_u32 s6, s28, s79
	s_addc_u32 s7, s29, s7
	s_lshl_b32 s8, s76, 1
	s_add_u32 s10, s42, s8
	s_addc_u32 s11, s43, 0
	v_lshl_add_u64 v[2:3], s[12:13], 0, v[134:135]
	v_mov_b64_e32 v[4:5], s[10:11]
	v_mad_u64_u32 v[0:1], s[10:11], v2, s39, v[4:5]
	v_mad_i32_i24 v1, v3, s39, v1
	s_waitcnt vmcnt(12)
	v_lshl_add_u64 v[76:77], v[0:1], 0, v[138:139]
	v_add_u32_e32 v0, 0x100, v161
	v_ashrrev_i32_e32 v1, 31, v0
	v_lshrrev_b32_e32 v1, 28, v1
	v_add_u32_e32 v1, v0, v1
	v_ashrrev_i32_e32 v8, 4, v1
	v_and_b32_e32 v1, -16, v1
	s_waitcnt vmcnt(5)
	v_sub_u32_e32 v99, v0, v1
	v_lshlrev_b32_e32 v0, 3, v99
	v_ashrrev_i32_e32 v1, 31, v0
	s_waitcnt vmcnt(3)
	v_lshlrev_b64 v[92:93], 1, v[0:1]
	v_add_u32_e32 v0, 0x200, v161
	v_ashrrev_i32_e32 v1, 31, v0
	v_lshrrev_b32_e32 v1, 28, v1
	v_add_u32_e32 v1, v0, v1
	v_ashrrev_i32_e32 v9, 31, v8
	v_ashrrev_i32_e32 v94, 4, v1
	v_and_b32_e32 v1, -16, v1
	v_lshl_add_u64 v[10:11], s[12:13], 0, v[8:9]
	v_sub_u32_e32 v9, v0, v1
	v_lshlrev_b32_e32 v0, 3, v9
	v_ashrrev_i32_e32 v1, 31, v0
	v_lshlrev_b64 v[100:101], 1, v[0:1]
	v_add_u32_e32 v0, 0x300, v161
	v_ashrrev_i32_e32 v1, 31, v0
	v_lshrrev_b32_e32 v1, 28, v1
	v_add_u32_e32 v1, v0, v1
	v_ashrrev_i32_e32 v102, 4, v1
	v_and_b32_e32 v1, -16, v1
	v_sub_u32_e32 v128, v0, v1
	v_lshlrev_b32_e32 v0, 3, v128
	v_ashrrev_i32_e32 v1, 31, v0
	s_waitcnt vmcnt(0)
	v_lshlrev_b64 v[106:107], 1, v[0:1]
	v_add_u32_e32 v0, 0x400, v161
	v_ashrrev_i32_e32 v1, 31, v0
	v_lshrrev_b32_e32 v1, 28, v1
	v_add_u32_e32 v1, v0, v1
	v_ashrrev_i32_e32 v103, 31, v102
	v_ashrrev_i32_e32 v108, 4, v1
	v_and_b32_e32 v1, -16, v1
	v_lshl_add_u64 v[104:105], s[12:13], 0, v[102:103]
	v_sub_u32_e32 v103, v0, v1
	v_lshlrev_b32_e32 v0, 3, v103
	v_ashrrev_i32_e32 v1, 31, v0
	v_lshlrev_b64 v[112:113], 1, v[0:1]
	v_add_u32_e32 v0, 0x500, v161
	v_ashrrev_i32_e32 v1, 31, v0
	v_lshrrev_b32_e32 v1, 28, v1
	v_add_u32_e32 v1, v0, v1
	v_ashrrev_i32_e32 v109, 31, v108
	v_ashrrev_i32_e32 v114, 4, v1
	v_and_b32_e32 v1, -16, v1
	v_mad_u64_u32 v[6:7], s[10:11], v10, s39, v[4:5]
	v_ashrrev_i32_e32 v95, 31, v94
	v_lshl_add_u64 v[110:111], s[12:13], 0, v[108:109]
	v_sub_u32_e32 v109, v0, v1
	v_mad_i32_i24 v7, v11, s39, v7
	v_lshl_add_u64 v[96:97], s[12:13], 0, v[94:95]
	v_lshlrev_b32_e32 v0, 3, v109
	v_lshl_add_u64 v[78:79], v[6:7], 0, v[92:93]
	v_mad_u64_u32 v[6:7], s[10:11], v96, s39, v[4:5]
	v_ashrrev_i32_e32 v1, 31, v0
	v_mad_i32_i24 v7, v97, s39, v7
	v_lshlrev_b64 v[118:119], 1, v[0:1]
	v_add_u32_e32 v0, 0x600, v161
	v_lshl_add_u64 v[80:81], v[6:7], 0, v[100:101]
	v_mad_u64_u32 v[6:7], s[10:11], v104, s39, v[4:5]
	v_ashrrev_i32_e32 v1, 31, v0
	v_mad_i32_i24 v7, v105, s39, v7
	v_lshrrev_b32_e32 v1, 28, v1
	v_lshl_add_u64 v[82:83], v[6:7], 0, v[106:107]
	v_mad_u64_u32 v[6:7], s[10:11], v110, s39, v[4:5]
	v_ashrrev_i32_e32 v115, 31, v114
	v_add_u32_e32 v1, v0, v1
	v_mad_i32_i24 v7, v111, s39, v7
	v_lshl_add_u64 v[116:117], s[12:13], 0, v[114:115]
	v_ashrrev_i32_e32 v120, 4, v1
	v_and_b32_e32 v1, -16, v1
	v_lshl_add_u64 v[84:85], v[6:7], 0, v[112:113]
	v_mad_u64_u32 v[6:7], s[10:11], v116, s39, v[4:5]
	v_sub_u32_e32 v115, v0, v1
	v_ashrrev_i32_e32 v121, 31, v120
	v_mad_i32_i24 v7, v117, s39, v7
	v_lshlrev_b32_e32 v0, 3, v115
	v_lshl_add_u64 v[122:123], s[12:13], 0, v[120:121]
	v_lshl_add_u64 v[86:87], v[6:7], 0, v[118:119]
	v_mad_u64_u32 v[6:7], s[10:11], v122, s39, v[4:5]
	v_ashrrev_i32_e32 v1, 31, v0
	v_mad_i32_i24 v7, v123, s39, v7
	v_lshlrev_b64 v[124:125], 1, v[0:1]
	v_lshl_add_u64 v[0:1], v[6:7], 0, v[124:125]
	v_add_u32_e32 v6, 0x700, v161
	v_ashrrev_i32_e32 v7, 31, v6
	v_lshrrev_b32_e32 v7, 28, v7
	v_add_u32_e32 v7, v6, v7
	v_ashrrev_i32_e32 v126, 4, v7
	v_and_b32_e32 v7, -16, v7
	v_sub_u32_e32 v121, v6, v7
	v_lshlrev_b32_e32 v6, 3, v121
	v_ashrrev_i32_e32 v127, 31, v126
	v_lshl_add_u64 v[88:89], s[12:13], 0, v[126:127]
	v_ashrrev_i32_e32 v7, 31, v6
	v_mad_u64_u32 v[4:5], s[10:11], v88, s39, v[4:5]
	v_lshlrev_b64 v[90:91], 1, v[6:7]
	v_lshl_or_b32 v6, v137, 2, v130
	v_mad_i32_i24 v5, v89, s39, v5
	v_mul_lo_u32 v6, v6, s55
	v_lshl_add_u64 v[4:5], v[4:5], 0, v[90:91]
	v_lshl_add_u32 v95, v162, 2, v6
	s_barrier
	ds_write2_b32 v95, v12, v48 offset1:16
	ds_write2_b32 v95, v52, v56 offset0:32 offset1:48
	ds_write2_b32 v95, v60, v64 offset0:64 offset1:80
	ds_write2_b32 v95, v68, v72 offset0:96 offset1:112
	ds_write2_b32 v95, v13, v49 offset0:132 offset1:148
	ds_write2_b32 v95, v53, v57 offset0:164 offset1:180
	ds_write2_b32 v95, v61, v65 offset0:196 offset1:212
	ds_write2_b32 v95, v69, v73 offset0:228 offset1:244
	v_add_u32_e32 v12, 0x400, v95
	v_add_co_u32_e32 v4, vcc, s73, v4
	ds_write2_b32 v12, v14, v50 offset0:8 offset1:24
	ds_write2_b32 v12, v54, v58 offset0:40 offset1:56
	v_addc_co_u32_e32 v5, vcc, 0, v5, vcc
	global_load_dwordx4 v[4:7], v[4:5], off offset:512
	ds_write2_b32 v12, v62, v66 offset0:72 offset1:88
	ds_write2_b32 v12, v70, v74 offset0:104 offset1:120
	ds_write2_b32 v12, v15, v51 offset0:140 offset1:156
	ds_write2_b32 v12, v55, v59 offset0:172 offset1:188
	ds_write2_b32 v12, v63, v67 offset0:204 offset1:220
	ds_write2_b32 v12, v71, v75 offset0:236 offset1:252
	v_add_u32_e32 v12, 0x2000, v95
	ds_write2_b32 v12, v16, v20 offset0:64 offset1:80
	ds_write2_b32 v12, v24, v36 offset0:96 offset1:112
	ds_write2_b32 v12, v28, v40 offset0:128 offset1:144
	ds_write2_b32 v12, v44, v32 offset0:160 offset1:176
	ds_write2_b32 v12, v17, v21 offset0:196 offset1:212
	ds_write2_b32 v12, v25, v37 offset0:228 offset1:244
	v_add_u32_e32 v12, 0x2400, v95
	s_add_u32 s6, s6, s8
	ds_write2_b32 v12, v29, v41 offset0:4 offset1:20
	ds_write2_b32 v12, v45, v33 offset0:36 offset1:52
; __device__ __forceinline__ unsigned pack2(float a, float b) { return (unsigned)f2bf(a) | ((unsigned)f2bf(b) << 16); }
; __device__ __forceinline__ float bflo(unsigned w) { return __uint_as_float(w << 16); }
; __device__ __forceinline__ float bfhi(unsigned w) { return __uint_as_float(w & 0xffff0000u); }
; __device__ __forceinline__ float silu_f(float g) { return g / (1.f + __expf(-g)); }
; template <int DH, int MODE>
; __device__ void attn_item(const Params& p, int layer, int b, int blk, int head, char* smem) {
;     ...
; #pragma unroll
;     for (int i = 0; i < NCH; ++i) {
;       int q = tid + 256 * i, r = q / CPR, c = (q % CPR) * 8;
;       float4 m0 = *reinterpret_cast<const float4*>(Of + r * OST + c);
;       float4 m1 = *reinterpret_cast<const float4*>(Of + r * OST + c + 4);
;       float mm[8] = {m0.x, m0.y, m0.z, m0.w, m1.x, m1.y, m1.z, m1.w};
;       unsigned gw[4] = {gt[i].x, gt[i].y, gt[i].z, gt[i].w};
;       unsigned ow[4];
; #pragma unroll
;       for (int e = 0; e < 4; ++e)
;         ow[e] = pack2(mm[2 * e] * silu_f(bflo(gw[e])), mm[2 * e + 1] * silu_f(bfhi(gw[e])));
	ds_write2_b32 v12, v18, v22 offset0:72 offset1:88
	ds_write2_b32 v12, v26, v38 offset0:104 offset1:120
	ds_write2_b32 v12, v30, v42 offset0:136 offset1:152
	ds_write2_b32 v12, v46, v34 offset0:168 offset1:184
	ds_write2_b32 v12, v19, v23 offset0:204 offset1:220
	ds_write2_b32 v12, v27, v39 offset0:236 offset1:252
	v_add_u32_e32 v12, 0x2800, v95
	s_addc_u32 s7, s7, 0
	ds_write2_b32 v12, v31, v43 offset0:12 offset1:28
	ds_write2_b32 v12, v47, v35 offset0:44 offset1:60
	v_mul_lo_u32 v12, v134, s55
	v_mov_b64_e32 v[14:15], s[6:7]
	v_lshl_add_u32 v98, v136, 2, v12
	v_mad_u64_u32 v[12:13], s[6:7], v2, s63, v[14:15]
	v_mul_lo_u32 v2, v8, s55
	v_mad_i32_i24 v13, v3, s63, v13
	v_lshl_add_u32 v95, v99, 5, v2
	v_mad_u64_u32 v[2:3], s[6:7], v10, s63, v[14:15]
	v_mad_i32_i24 v3, v11, s63, v3
	v_lshl_add_u64 v[26:27], v[2:3], 0, v[92:93]
	v_mul_lo_u32 v2, v94, s55
	v_lshl_add_u32 v93, v9, 5, v2
	v_mad_u64_u32 v[2:3], s[6:7], v96, s63, v[14:15]
	v_mad_i32_i24 v3, v97, s63, v3
	v_lshl_add_u64 v[20:21], v[2:3], 0, v[100:101]
	v_mul_lo_u32 v2, v102, s55
	v_lshl_add_u32 v92, v128, 5, v2
	v_mad_u64_u32 v[2:3], s[6:7], v104, s63, v[14:15]
	v_mad_i32_i24 v3, v105, s63, v3
	v_lshl_add_u64 v[16:17], v[2:3], 0, v[106:107]
	v_mul_lo_u32 v2, v108, s55
	v_lshl_add_u32 v75, v103, 5, v2
	v_mad_u64_u32 v[2:3], s[6:7], v110, s63, v[14:15]
	v_mad_i32_i24 v3, v111, s63, v3
	v_lshl_add_u64 v[30:31], v[12:13], 0, v[138:139]
	v_lshl_add_u64 v[12:13], v[2:3], 0, v[112:113]
	v_mul_lo_u32 v2, v114, s55
	v_lshl_add_u32 v74, v109, 5, v2
	v_mad_u64_u32 v[2:3], s[6:7], v116, s63, v[14:15]
	v_mad_i32_i24 v3, v117, s63, v3
	v_lshl_add_u64 v[10:11], v[2:3], 0, v[118:119]
	v_mul_lo_u32 v2, v120, s55
	v_lshl_add_u32 v73, v115, 5, v2
	v_mad_u64_u32 v[2:3], s[6:7], v122, s63, v[14:15]
	v_mad_i32_i24 v3, v123, s63, v3
	v_add_co_u32_e32 v0, vcc, s73, v0
	v_lshl_add_u64 v[8:9], v[2:3], 0, v[124:125]
	v_mul_lo_u32 v2, v126, s55
	v_addc_co_u32_e32 v1, vcc, 0, v1, vcc
	v_lshl_add_u32 v72, v121, 5, v2
	global_load_dwordx4 v[0:3], v[0:1], off offset:512
	v_mad_u64_u32 v[14:15], s[6:7], v88, s63, v[14:15]
	v_mad_i32_i24 v15, v89, s63, v15
	v_lshl_add_u64 v[14:15], v[14:15], 0, v[90:91]
	s_waitcnt vmcnt(1)
	v_lshlrev_b32_e32 v22, 16, v5
	v_lshlrev_b32_e32 v23, 16, v4
	v_mul_f32_e32 v18, 0xbfb8aa3b, v23
	v_mul_f32_e32 v19, 0xbfb8aa3b, v22
	v_exp_f32_e32 v18, v18
	v_exp_f32_e32 v19, v19
	v_and_b32_e32 v24, 0xffff0000, v5
	v_and_b32_e32 v28, 0xffff0000, v4
	v_mul_f32_e32 v4, 0xbfb8aa3b, v28
	v_pk_add_f32 v[18:19], v[18:19], 1.0 op_sel_hi:[1,0]
	v_exp_f32_e32 v4, v4
	v_and_b32_e32 v34, 0xffff0000, v6
	v_rcp_f32_e32 v19, v19
	s_nop 0
	v_mul_f32_e32 v19, v22, v19
	v_mul_f32_e32 v5, 0xbfb8aa3b, v24
	v_exp_f32_e32 v5, v5
	s_nop 0
	v_pk_add_f32 v[4:5], v[4:5], 1.0 op_sel_hi:[1,0]
	v_rcp_f32_e32 v18, v18
	s_nop 0
	v_mul_f32_e32 v18, v23, v18
	v_lshlrev_b32_e32 v33, 16, v6
	v_rcp_f32_e32 v23, v5
	s_nop 0
	v_mul_f32_e32 v23, v24, v23
	v_lshlrev_b32_e32 v32, 16, v7
	v_mul_f32_e32 v24, 0xbfb8aa3b, v33
	v_mul_f32_e32 v25, 0xbfb8aa3b, v32
	v_exp_f32_e32 v24, v24
	v_exp_f32_e32 v25, v25
	v_rcp_f32_e32 v22, v4
	s_nop 0
	v_mul_f32_e32 v22, v28, v22
	v_and_b32_e32 v28, 0xffff0000, v7
	v_pk_add_f32 v[4:5], v[24:25], 1.0 op_sel_hi:[1,0]
	v_mul_f32_e32 v6, 0xbfb8aa3b, v34
	v_exp_f32_e32 v6, v6
	s_waitcnt vmcnt(0)
	v_lshlrev_b32_e32 v40, 16, v3
	v_lshlrev_b32_e32 v41, 16, v2
	v_rcp_f32_e32 v25, v5
	s_nop 0
	v_mul_f32_e32 v25, v32, v25
	v_mul_f32_e32 v7, 0xbfb8aa3b, v28
	v_exp_f32_e32 v7, v7
	s_nop 0
	v_pk_add_f32 v[6:7], v[6:7], 1.0 op_sel_hi:[1,0]
	v_rcp_f32_e32 v24, v4
	s_nop 0
	v_mul_f32_e32 v24, v33, v24
	v_rcp_f32_e32 v29, v7
	s_nop 0
	v_mul_f32_e32 v29, v28, v29
	v_lshlrev_b32_e32 v32, 16, v1
	v_lshlrev_b32_e32 v36, 16, v0
	v_mul_f32_e32 v4, 0xbfb8aa3b, v36
	v_mul_f32_e32 v5, 0xbfb8aa3b, v32
	v_exp_f32_e32 v4, v4
	v_exp_f32_e32 v5, v5
	v_rcp_f32_e32 v28, v6
	s_nop 0
	v_mul_f32_e32 v28, v34, v28
	v_and_b32_e32 v6, 0xffff0000, v1
	v_pk_add_f32 v[4:5], v[4:5], 1.0 op_sel_hi:[1,0]
	v_and_b32_e32 v34, 0xffff0000, v0
	v_mul_f32_e32 v0, 0xbfb8aa3b, v34
	v_exp_f32_e32 v0, v0
	v_and_b32_e32 v42, 0xffff0000, v3
	v_rcp_f32_e32 v33, v5
	s_nop 0
	v_mul_f32_e32 v33, v32, v33
	v_mul_f32_e32 v1, 0xbfb8aa3b, v6
	v_exp_f32_e32 v1, v1
	s_nop 0
	v_pk_add_f32 v[0:1], v[0:1], 1.0 op_sel_hi:[1,0]
	v_rcp_f32_e32 v32, v4
	s_nop 0
	v_mul_f32_e32 v32, v36, v32
	v_rcp_f32_e32 v35, v1
	s_nop 0
	v_mul_f32_e32 v35, v6, v35
	v_add_co_u32_e64 v4, s[6:7], s73, v86
	s_nop 0
	s_nop 0
	v_addc_co_u32_e64 v5, s[6:7], 0, v87, s[6:7]
	global_load_dwordx4 v[4:7], v[4:5], off offset:512
	v_mul_f32_e32 v36, 0xbfb8aa3b, v41
	v_mul_f32_e32 v37, 0xbfb8aa3b, v40
	v_exp_f32_e32 v36, v36
	v_exp_f32_e32 v37, v37
	v_rcp_f32_e32 v1, v0
	s_nop 0
	v_mul_f32_e32 v34, v34, v1
	v_and_b32_e32 v43, 0xffff0000, v2
	v_pk_add_f32 v[0:1], v[36:37], 1.0 op_sel_hi:[1,0]
	v_mul_f32_e32 v2, 0xbfb8aa3b, v43
	v_exp_f32_e32 v2, v2
	v_rcp_f32_e32 v37, v1
	s_nop 0
	v_mul_f32_e32 v37, v40, v37
	v_mul_f32_e32 v3, 0xbfb8aa3b, v42
	v_exp_f32_e32 v3, v3
	s_nop 0
	v_pk_add_f32 v[38:39], v[2:3], 1.0 op_sel_hi:[1,0]
	v_rcp_f32_e32 v36, v0
	s_nop 0
	v_mul_f32_e32 v36, v41, v36
	v_rcp_f32_e32 v39, v39
	s_nop 0
	v_mul_f32_e32 v39, v42, v39
	v_add_co_u32_e64 v0, s[6:7], s73, v84
	s_waitcnt vmcnt(0)
; __device__ __forceinline__ unsigned pack2(float a, float b) { return (unsigned)f2bf(a) | ((unsigned)f2bf(b) << 16); }
; __device__ __forceinline__ float bflo(unsigned w) { return __uint_as_float(w << 16); }
; __device__ __forceinline__ float bfhi(unsigned w) { return __uint_as_float(w & 0xffff0000u); }
; __device__ __forceinline__ float silu_f(float g) { return g / (1.f + __expf(-g)); }
; template <int DH, int MODE>
; __device__ void attn_item(const Params& p, int layer, int b, int blk, int head, char* smem) {
;     ...
; #pragma unroll
;     for (int i = 0; i < NCH; ++i) {
;       int q = tid + 256 * i, r = q / CPR, c = (q % CPR) * 8;
;       float4 m0 = *reinterpret_cast<const float4*>(Of + r * OST + c);
;       float4 m1 = *reinterpret_cast<const float4*>(Of + r * OST + c + 4);
;       float mm[8] = {m0.x, m0.y, m0.z, m0.w, m1.x, m1.y, m1.z, m1.w};
;       unsigned gw[4] = {gt[i].x, gt[i].y, gt[i].z, gt[i].w};
;       unsigned ow[4];
; #pragma unroll
;       for (int e = 0; e < 4; ++e)
;         ow[e] = pack2(mm[2 * e] * silu_f(bflo(gw[e])), mm[2 * e + 1] * silu_f(bfhi(gw[e])));
	v_lshlrev_b32_e32 v46, 16, v5
	v_lshlrev_b32_e32 v47, 16, v4
	v_mul_f32_e32 v40, 0xbfb8aa3b, v47
	v_mul_f32_e32 v41, 0xbfb8aa3b, v46
	v_exp_f32_e32 v40, v40
	v_exp_f32_e32 v41, v41
	v_addc_co_u32_e64 v1, s[6:7], 0, v85, s[6:7]
	v_rcp_f32_e32 v38, v38
	s_nop 0
	v_mul_f32_e32 v38, v43, v38
	v_pk_add_f32 v[40:41], v[40:41], 1.0 op_sel_hi:[1,0]
	v_and_b32_e32 v42, 0xffff0000, v5
	global_load_dwordx4 v[0:3], v[0:1], off offset:512
	v_and_b32_e32 v48, 0xffff0000, v4
	v_mul_f32_e32 v4, 0xbfb8aa3b, v48
	v_rcp_f32_e32 v41, v41
	s_nop 0
	v_mul_f32_e32 v41, v46, v41
	v_exp_f32_e32 v4, v4
	v_mul_f32_e32 v5, 0xbfb8aa3b, v42
	v_exp_f32_e32 v5, v5
	s_nop 0
	v_pk_add_f32 v[4:5], v[4:5], 1.0 op_sel_hi:[1,0]
	v_rcp_f32_e32 v40, v40
	s_nop 0
	v_mul_f32_e32 v40, v47, v40
	v_lshlrev_b32_e32 v49, 16, v6
	v_rcp_f32_e32 v43, v5
	s_nop 0
	v_mul_f32_e32 v43, v42, v43
	v_lshlrev_b32_e32 v46, 16, v7
	v_mul_f32_e32 v44, 0xbfb8aa3b, v49
	v_mul_f32_e32 v45, 0xbfb8aa3b, v46
	v_exp_f32_e32 v44, v44
	v_exp_f32_e32 v45, v45
	v_rcp_f32_e32 v42, v4
	s_nop 0
	v_mul_f32_e32 v42, v48, v42
	v_and_b32_e32 v47, 0xffff0000, v7
	v_pk_add_f32 v[4:5], v[44:45], 1.0 op_sel_hi:[1,0]
	v_and_b32_e32 v48, 0xffff0000, v6
	v_mul_f32_e32 v6, 0xbfb8aa3b, v48
	v_exp_f32_e32 v6, v6
	v_rcp_f32_e32 v45, v5
	s_nop 0
	v_mul_f32_e32 v45, v46, v45
	v_mul_f32_e32 v7, 0xbfb8aa3b, v47
	v_exp_f32_e32 v7, v7
	s_nop 0
	v_pk_add_f32 v[6:7], v[6:7], 1.0 op_sel_hi:[1,0]
	v_rcp_f32_e32 v44, v4
	s_nop 0
	v_mul_f32_e32 v44, v49, v44
	v_rcp_f32_e32 v4, v7
	s_nop 0
	v_mul_f32_e32 v47, v47, v4
	s_waitcnt vmcnt(0)
	v_lshlrev_b32_e32 v50, 16, v1
	v_lshlrev_b32_e32 v51, 16, v0
	v_mul_f32_e32 v4, 0xbfb8aa3b, v51
	v_mul_f32_e32 v5, 0xbfb8aa3b, v50
	v_exp_f32_e32 v4, v4
	v_exp_f32_e32 v5, v5
	v_rcp_f32_e32 v46, v6
	s_nop 0
	v_mul_f32_e32 v46, v48, v46
	v_and_b32_e32 v6, 0xffff0000, v1
	v_pk_add_f32 v[4:5], v[4:5], 1.0 op_sel_hi:[1,0]
	v_and_b32_e32 v54, 0xffff0000, v0
	v_mul_f32_e32 v0, 0xbfb8aa3b, v54
	v_exp_f32_e32 v0, v0
	v_lshlrev_b32_e32 v58, 16, v2
	v_rcp_f32_e32 v49, v5
	s_nop 0
	v_mul_f32_e32 v49, v50, v49
	v_mul_f32_e32 v1, 0xbfb8aa3b, v6
	v_exp_f32_e32 v1, v1
	s_nop 0
	v_pk_add_f32 v[0:1], v[0:1], 1.0 op_sel_hi:[1,0]
	v_rcp_f32_e32 v48, v4
	s_nop 0
	v_mul_f32_e32 v48, v51, v48
	v_lshlrev_b32_e32 v57, 16, v3
	v_rcp_f32_e32 v51, v1
	s_nop 0
	v_mul_f32_e32 v51, v6, v51
	v_add_co_u32_e64 v4, s[6:7], s73, v82
	s_nop 0
	s_nop 0
	v_addc_co_u32_e64 v5, s[6:7], 0, v83, s[6:7]
	global_load_dwordx4 v[4:7], v[4:5], off offset:512
	v_mul_f32_e32 v50, 0xbfb8aa3b, v58
	v_exp_f32_e32 v52, v50
	v_mul_f32_e32 v50, 0xbfb8aa3b, v57
	v_exp_f32_e32 v53, v50
	v_rcp_f32_e32 v50, v0
	s_nop 0
	v_mul_f32_e32 v50, v54, v50
	v_and_b32_e32 v56, 0xffff0000, v3
	v_pk_add_f32 v[0:1], v[52:53], 1.0 op_sel_hi:[1,0]
	v_and_b32_e32 v59, 0xffff0000, v2
	v_mul_f32_e32 v2, 0xbfb8aa3b, v59
	v_exp_f32_e32 v2, v2
	v_rcp_f32_e32 v53, v1
	s_nop 0
	v_mul_f32_e32 v53, v57, v53
	v_mul_f32_e32 v3, 0xbfb8aa3b, v56
	v_exp_f32_e32 v3, v3
	s_nop 0
	v_pk_add_f32 v[54:55], v[2:3], 1.0 op_sel_hi:[1,0]
	v_rcp_f32_e32 v52, v0
	s_nop 0
	v_mul_f32_e32 v52, v58, v52
	v_rcp_f32_e32 v55, v55
	s_nop 0
	v_mul_f32_e32 v55, v56, v55
	v_add_co_u32_e64 v0, s[6:7], s73, v80
	s_waitcnt vmcnt(0)
	v_lshlrev_b32_e32 v62, 16, v5
	v_lshlrev_b32_e32 v63, 16, v4
	v_mul_f32_e32 v56, 0xbfb8aa3b, v63
	v_mul_f32_e32 v57, 0xbfb8aa3b, v62
	v_exp_f32_e32 v56, v56
	v_exp_f32_e32 v57, v57
	v_addc_co_u32_e64 v1, s[6:7], 0, v81, s[6:7]
	v_rcp_f32_e32 v54, v54
	s_nop 0
	v_mul_f32_e32 v54, v59, v54
	v_pk_add_f32 v[56:57], v[56:57], 1.0 op_sel_hi:[1,0]
	v_and_b32_e32 v58, 0xffff0000, v5
	global_load_dwordx4 v[0:3], v[0:1], off offset:512
	v_and_b32_e32 v64, 0xffff0000, v4
	v_mul_f32_e32 v4, 0xbfb8aa3b, v64
	v_rcp_f32_e32 v57, v57
	s_nop 0
	v_mul_f32_e32 v57, v62, v57
	v_exp_f32_e32 v4, v4
	v_mul_f32_e32 v5, 0xbfb8aa3b, v58
	v_exp_f32_e32 v5, v5
	s_nop 0
	v_pk_add_f32 v[4:5], v[4:5], 1.0 op_sel_hi:[1,0]
	v_rcp_f32_e32 v56, v56
	s_nop 0
	v_mul_f32_e32 v56, v63, v56
	v_lshlrev_b32_e32 v65, 16, v6
	v_rcp_f32_e32 v59, v5
	s_nop 0
	v_mul_f32_e32 v59, v58, v59
	v_lshlrev_b32_e32 v62, 16, v7
	v_mul_f32_e32 v60, 0xbfb8aa3b, v65
	v_mul_f32_e32 v61, 0xbfb8aa3b, v62
	v_exp_f32_e32 v60, v60
	v_exp_f32_e32 v61, v61
	v_rcp_f32_e32 v58, v4
	s_nop 0
	v_mul_f32_e32 v58, v64, v58
	v_and_b32_e32 v63, 0xffff0000, v7
	v_pk_add_f32 v[4:5], v[60:61], 1.0 op_sel_hi:[1,0]
	v_and_b32_e32 v64, 0xffff0000, v6
	v_mul_f32_e32 v6, 0xbfb8aa3b, v64
	v_exp_f32_e32 v6, v6
	v_rcp_f32_e32 v61, v5
	s_nop 0
	v_mul_f32_e32 v61, v62, v61
	v_mul_f32_e32 v7, 0xbfb8aa3b, v63
	v_exp_f32_e32 v7, v7
	s_nop 0
	v_pk_add_f32 v[6:7], v[6:7], 1.0 op_sel_hi:[1,0]
	v_rcp_f32_e32 v60, v4
	s_nop 0
	v_mul_f32_e32 v60, v65, v60
	v_rcp_f32_e32 v4, v7
	s_nop 0
	v_mul_f32_e32 v63, v63, v4
	s_waitcnt vmcnt(0)
	v_lshlrev_b32_e32 v66, 16, v1
	v_lshlrev_b32_e32 v67, 16, v0
	v_mul_f32_e32 v4, 0xbfb8aa3b, v67
	v_mul_f32_e32 v5, 0xbfb8aa3b, v66
	v_exp_f32_e32 v4, v4
	v_exp_f32_e32 v5, v5
	v_and_b32_e32 v68, 0xffff0000, v1
	v_rcp_f32_e32 v62, v6
	s_nop 0
	v_mul_f32_e32 v62, v64, v62
	v_pk_add_f32 v[4:5], v[4:5], 1.0 op_sel_hi:[1,0]
	v_and_b32_e32 v69, 0xffff0000, v0
	v_mul_f32_e32 v0, 0xbfb8aa3b, v69
	v_exp_f32_e32 v6, v0
	v_and_b32_e32 v80, 0xffff0000, v2
	v_rcp_f32_e32 v1, v5
	s_nop 0
	v_mul_f32_e32 v1, v66, v1
	v_mul_f32_e32 v7, 0xbfb8aa3b, v68
	v_exp_f32_e32 v7, v7
	s_nop 0
	v_pk_add_f32 v[64:65], v[6:7], 1.0 op_sel_hi:[1,0]
	v_rcp_f32_e32 v0, v4
	s_nop 0
	v_mul_f32_e32 v0, v67, v0
	v_rcp_f32_e32 v65, v65
	s_nop 0
	v_mul_f32_e32 v65, v68, v65
	v_add_co_u32_e64 v4, s[6:7], s73, v78
	s_nop 0
	s_nop 0
	v_addc_co_u32_e64 v5, s[6:7], 0, v79, s[6:7]
	global_load_dwordx4 v[4:7], v[4:5], off offset:512
	v_lshlrev_b32_e32 v78, 16, v3
	v_lshlrev_b32_e32 v79, 16, v2
	v_mul_f32_e32 v66, 0xbfb8aa3b, v79
	v_mul_f32_e32 v67, 0xbfb8aa3b, v78
	v_exp_f32_e32 v66, v66
	v_exp_f32_e32 v67, v67
	v_and_b32_e32 v70, 0xffff0000, v3
	v_rcp_f32_e32 v64, v64
	s_nop 0
	v_mul_f32_e32 v64, v69, v64
	v_pk_add_f32 v[66:67], v[66:67], 1.0 op_sel_hi:[1,0]
	v_mul_f32_e32 v2, 0xbfb8aa3b, v80
	v_exp_f32_e32 v68, v2
	v_mul_f32_e32 v69, 0xbfb8aa3b, v70
	v_exp_f32_e32 v69, v69
	v_rcp_f32_e32 v3, v67
	s_nop 0
	v_mul_f32_e32 v3, v78, v3
	v_pk_add_f32 v[68:69], v[68:69], 1.0 op_sel_hi:[1,0]
	v_rcp_f32_e32 v2, v66
	s_nop 0
	v_mul_f32_e32 v2, v79, v2
	v_rcp_f32_e32 v67, v69
	s_nop 0
	v_mul_f32_e32 v67, v70, v67
	v_add_co_u32_e64 v70, s[6:7], s73, v76
	s_nop 0
	s_nop 0
	v_addc_co_u32_e64 v71, s[6:7], 0, v77, s[6:7]
	global_load_dwordx4 v[76:79], v[70:71], off offset:512
	v_rcp_f32_e32 v66, v68
	s_nop 0
	v_mul_f32_e32 v66, v80, v66
	s_waitcnt vmcnt(1)
	v_lshlrev_b32_e32 v82, 16, v5
	v_lshlrev_b32_e32 v83, 16, v4
	v_mul_f32_e32 v70, 0xbfb8aa3b, v83
	v_mul_f32_e32 v71, 0xbfb8aa3b, v82
	v_exp_f32_e32 v70, v70
	v_exp_f32_e32 v71, v71
	v_and_b32_e32 v80, 0xffff0000, v5
	v_and_b32_e32 v84, 0xffff0000, v4
	v_mul_f32_e32 v4, 0xbfb8aa3b, v84
	v_pk_add_f32 v[68:69], v[70:71], 1.0 op_sel_hi:[1,0]
	v_exp_f32_e32 v70, v4
	s_waitcnt lgkmcnt(0)
	s_barrier
; __device__ __forceinline__ unsigned pack2(float a, float b) { return (unsigned)f2bf(a) | ((unsigned)f2bf(b) << 16); }
; __device__ __forceinline__ float bflo(unsigned w) { return __uint_as_float(w << 16); }
; __device__ __forceinline__ float bfhi(unsigned w) { return __uint_as_float(w & 0xffff0000u); }
; __device__ __forceinline__ float silu_f(float g) { return g / (1.f + __expf(-g)); }
; template <int DH, int MODE>
; __device__ void attn_item(const Params& p, int layer, int b, int blk, int head, char* smem) {
;     ...
; #pragma unroll
;     for (int i = 0; i < NCH; ++i) {
;       int q = tid + 256 * i, r = q / CPR, c = (q % CPR) * 8;
;       float4 m0 = *reinterpret_cast<const float4*>(Of + r * OST + c);
;       float4 m1 = *reinterpret_cast<const float4*>(Of + r * OST + c + 4);
;       float mm[8] = {m0.x, m0.y, m0.z, m0.w, m1.x, m1.y, m1.z, m1.w};
;       unsigned gw[4] = {gt[i].x, gt[i].y, gt[i].z, gt[i].w};
;       unsigned ow[4];
; #pragma unroll
;       for (int e = 0; e < 4; ++e)
;         ow[e] = pack2(mm[2 * e] * silu_f(bflo(gw[e])), mm[2 * e + 1] * silu_f(bfhi(gw[e])));
;       *reinterpret_cast<uint4*>(Y + (tq0 + r) * YW + ycol + c) = make_uint4(ow[0], ow[1], ow[2], ow[3]);
;     }
	v_mul_f32_e32 v71, 0xbfb8aa3b, v80
	v_exp_f32_e32 v71, v71
	v_rcp_f32_e32 v5, v69
	s_nop 0
	v_mul_f32_e32 v5, v82, v5
	v_pk_add_f32 v[70:71], v[70:71], 1.0 op_sel_hi:[1,0]
	v_rcp_f32_e32 v4, v68
	s_nop 0
	v_mul_f32_e32 v4, v83, v4
	v_rcp_f32_e32 v69, v71
	s_nop 0
	v_mul_f32_e32 v69, v80, v69
	v_lshlrev_b32_e32 v82, 16, v7
	v_lshlrev_b32_e32 v85, 16, v6
	v_mul_f32_e32 v80, 0xbfb8aa3b, v85
	v_mul_f32_e32 v81, 0xbfb8aa3b, v82
	v_exp_f32_e32 v80, v80
	v_exp_f32_e32 v81, v81
	v_rcp_f32_e32 v68, v70
	s_nop 0
	v_mul_f32_e32 v68, v84, v68
	v_and_b32_e32 v83, 0xffff0000, v7
	v_pk_add_f32 v[70:71], v[80:81], 1.0 op_sel_hi:[1,0]
	v_and_b32_e32 v84, 0xffff0000, v6
	v_mul_f32_e32 v6, 0xbfb8aa3b, v84
	v_exp_f32_e32 v80, v6
	s_waitcnt vmcnt(0)
	v_and_b32_e32 v94, 0xffff0000, v78
	v_mul_f32_e32 v81, 0xbfb8aa3b, v83
	v_exp_f32_e32 v81, v81
	v_rcp_f32_e32 v7, v71
	s_nop 0
	v_mul_f32_e32 v7, v82, v7
	v_pk_add_f32 v[80:81], v[80:81], 1.0 op_sel_hi:[1,0]
	v_rcp_f32_e32 v6, v70
	s_nop 0
	v_mul_f32_e32 v6, v85, v6
	v_rcp_f32_e32 v71, v81
	s_nop 0
	v_mul_f32_e32 v71, v83, v71
	v_lshlrev_b32_e32 v86, 16, v77
	v_lshlrev_b32_e32 v87, 16, v76
	v_mul_f32_e32 v82, 0xbfb8aa3b, v87
	v_mul_f32_e32 v83, 0xbfb8aa3b, v86
	v_exp_f32_e32 v82, v82
	v_exp_f32_e32 v83, v83
	v_rcp_f32_e32 v70, v80
	s_nop 0
	v_mul_f32_e32 v70, v84, v70
	v_and_b32_e32 v88, 0xffff0000, v77
	v_pk_add_f32 v[80:81], v[82:83], 1.0 op_sel_hi:[1,0]
	v_and_b32_e32 v83, 0xffff0000, v76
	v_mul_f32_e32 v76, 0xbfb8aa3b, v83
	v_exp_f32_e32 v76, v76
	v_rcp_f32_e32 v85, v81
	s_nop 0
	v_mul_f32_e32 v85, v86, v85
	v_mul_f32_e32 v77, 0xbfb8aa3b, v88
	v_exp_f32_e32 v77, v77
	s_nop 0
	v_pk_add_f32 v[76:77], v[76:77], 1.0 op_sel_hi:[1,0]
	v_rcp_f32_e32 v84, v80
	s_nop 0
	v_mul_f32_e32 v84, v87, v84
	v_rcp_f32_e32 v87, v77
	s_nop 0
	v_mul_f32_e32 v87, v88, v87
	v_lshlrev_b32_e32 v90, 16, v78
	v_lshlrev_b32_e32 v82, 16, v79
	v_mul_f32_e32 v80, 0xbfb8aa3b, v90
	v_mul_f32_e32 v81, 0xbfb8aa3b, v82
	v_exp_f32_e32 v80, v80
	v_exp_f32_e32 v81, v81
	v_rcp_f32_e32 v86, v76
	s_nop 0
	v_mul_f32_e32 v86, v83, v86
	v_and_b32_e32 v83, 0xffff0000, v79
	v_pk_add_f32 v[76:77], v[80:81], 1.0 op_sel_hi:[1,0]
	v_mul_f32_e32 v78, 0xbfb8aa3b, v94
	v_exp_f32_e32 v78, v78
	v_rcp_f32_e32 v89, v77
	s_nop 0
	v_mul_f32_e32 v89, v82, v89
	v_mul_f32_e32 v79, 0xbfb8aa3b, v83
	v_exp_f32_e32 v79, v79
	s_nop 0
	v_pk_add_f32 v[80:81], v[78:79], 1.0 op_sel_hi:[1,0]
	v_rcp_f32_e32 v88, v76
	s_nop 0
	v_mul_f32_e32 v88, v90, v88
	v_rcp_f32_e32 v91, v81
	s_nop 0
	v_mul_f32_e32 v91, v83, v91
	ds_read_b128 v[76:79], v98
	v_rcp_f32_e32 v90, v80
	s_nop 0
	v_mul_f32_e32 v90, v94, v90
	ds_read_b128 v[80:83], v98 offset:16
	v_add_co_u32_e32 v30, vcc, s70, v30
	s_waitcnt lgkmcnt(1)
	v_mov_b32_e32 v96, v76
	v_mov_b32_e32 v97, v78
	v_pk_mul_f32 v[84:85], v[84:85], v[96:97]
	v_mov_b32_e32 v78, v77
	v_pk_mul_f32 v[76:77], v[86:87], v[78:79]
	v_cvt_pk_bf16_f32 v77, v85, v77
	v_cvt_pk_bf16_f32 v76, v84, v76
	s_waitcnt lgkmcnt(0)
	v_mov_b32_e32 v78, v80
	v_mov_b32_e32 v79, v82
	v_pk_mul_f32 v[78:79], v[88:89], v[78:79]
	v_mov_b32_e32 v82, v81
	v_pk_mul_f32 v[80:81], v[90:91], v[82:83]
	v_cvt_pk_bf16_f32 v79, v79, v81
	v_cvt_pk_bf16_f32 v78, v78, v80
	ds_read_b128 v[80:83], v95
	v_addc_co_u32_e32 v31, vcc, 0, v31, vcc
	global_store_dwordx4 v[30:31], v[76:79], off offset:2048
	s_nop 0
	ds_read_b128 v[76:79], v95 offset:16
	s_waitcnt lgkmcnt(1)
	v_mov_b32_e32 v30, v80
	v_mov_b32_e32 v31, v82
	v_pk_mul_f32 v[4:5], v[4:5], v[30:31]
	v_mov_b32_e32 v82, v81
	v_pk_mul_f32 v[30:31], v[68:69], v[82:83]
	v_cvt_pk_bf16_f32 v5, v5, v31
	v_cvt_pk_bf16_f32 v4, v4, v30
	s_waitcnt lgkmcnt(0)
	v_mov_b32_e32 v30, v76
	v_mov_b32_e32 v31, v78
	v_pk_mul_f32 v[6:7], v[6:7], v[30:31]
	v_mov_b32_e32 v78, v77
	v_pk_mul_f32 v[30:31], v[70:71], v[78:79]
	ds_read_b128 v[68:71], v93
	v_add_co_u32_e32 v26, vcc, s70, v26
	v_cvt_pk_bf16_f32 v7, v7, v31
	v_cvt_pk_bf16_f32 v6, v6, v30
	v_addc_co_u32_e32 v27, vcc, 0, v27, vcc
	global_store_dwordx4 v[26:27], v[4:7], off offset:2048
	s_waitcnt lgkmcnt(0)
; __device__ __forceinline__ unsigned pack2(float a, float b) { return (unsigned)f2bf(a) | ((unsigned)f2bf(b) << 16); }
; __device__ __forceinline__ float bflo(unsigned w) { return __uint_as_float(w << 16); }
; __device__ __forceinline__ float bfhi(unsigned w) { return __uint_as_float(w & 0xffff0000u); }
; __device__ __forceinline__ float silu_f(float g) { return g / (1.f + __expf(-g)); }
; template <int DH, int MODE>
; __device__ void attn_item(const Params& p, int layer, int b, int blk, int head, char* smem) {
;     ...
; #pragma unroll
;     for (int i = 0; i < NCH; ++i) {
;       int q = tid + 256 * i, r = q / CPR, c = (q % CPR) * 8;
;       float4 m0 = *reinterpret_cast<const float4*>(Of + r * OST + c);
;       float4 m1 = *reinterpret_cast<const float4*>(Of + r * OST + c + 4);
;       float mm[8] = {m0.x, m0.y, m0.z, m0.w, m1.x, m1.y, m1.z, m1.w};
;       unsigned gw[4] = {gt[i].x, gt[i].y, gt[i].z, gt[i].w};
;       unsigned ow[4];
; #pragma unroll
;       for (int e = 0; e < 4; ++e)
;         ow[e] = pack2(mm[2 * e] * silu_f(bflo(gw[e])), mm[2 * e + 1] * silu_f(bfhi(gw[e])));
;       *reinterpret_cast<uint4*>(Y + (tq0 + r) * YW + ycol + c) = make_uint4(ow[0], ow[1], ow[2], ow[3]);
;     }
	v_mov_b32_e32 v26, v68
	v_mov_b32_e32 v27, v70
	ds_read_b128 v[4:7], v93 offset:16
	v_pk_mul_f32 v[0:1], v[0:1], v[26:27]
	v_mov_b32_e32 v70, v69
	v_pk_mul_f32 v[26:27], v[64:65], v[70:71]
	v_cvt_pk_bf16_f32 v1, v1, v27
	v_cvt_pk_bf16_f32 v0, v0, v26
	s_waitcnt lgkmcnt(0)
	v_mov_b32_e32 v26, v4
	v_mov_b32_e32 v27, v6
	v_pk_mul_f32 v[2:3], v[2:3], v[26:27]
	v_mov_b32_e32 v6, v5
	v_pk_mul_f32 v[4:5], v[66:67], v[6:7]
	v_cvt_pk_bf16_f32 v3, v3, v5
	v_cvt_pk_bf16_f32 v2, v2, v4
	ds_read_b128 v[4:7], v92
	v_add_co_u32_e32 v20, vcc, s70, v20
	s_nop 1
	v_addc_co_u32_e32 v21, vcc, 0, v21, vcc
	global_store_dwordx4 v[20:21], v[0:3], off offset:2048
	s_waitcnt lgkmcnt(0)
	v_mov_b32_e32 v20, v4
	v_mov_b32_e32 v21, v6
	ds_read_b128 v[0:3], v92 offset:16
	v_pk_mul_f32 v[20:21], v[56:57], v[20:21]
	v_mov_b32_e32 v6, v5
	v_pk_mul_f32 v[4:5], v[58:59], v[6:7]
	v_cvt_pk_bf16_f32 v5, v21, v5
	v_cvt_pk_bf16_f32 v4, v20, v4
	s_waitcnt lgkmcnt(0)
	v_mov_b32_e32 v6, v0
	v_mov_b32_e32 v7, v2
	v_pk_mul_f32 v[6:7], v[60:61], v[6:7]
	v_mov_b32_e32 v2, v1
	v_pk_mul_f32 v[0:1], v[62:63], v[2:3]
	v_cvt_pk_bf16_f32 v7, v7, v1
	v_cvt_pk_bf16_f32 v6, v6, v0
	ds_read_b128 v[0:3], v75
	v_add_co_u32_e32 v16, vcc, s70, v16
	s_nop 1
	v_addc_co_u32_e32 v17, vcc, 0, v17, vcc
	global_store_dwordx4 v[16:17], v[4:7], off offset:2048
	s_waitcnt lgkmcnt(0)
	v_mov_b32_e32 v16, v0
	v_mov_b32_e32 v17, v2
	ds_read_b128 v[4:7], v75 offset:16
	v_pk_mul_f32 v[16:17], v[48:49], v[16:17]
	v_mov_b32_e32 v2, v1
	v_pk_mul_f32 v[0:1], v[50:51], v[2:3]
	v_cvt_pk_bf16_f32 v1, v17, v1
	v_cvt_pk_bf16_f32 v0, v16, v0
	s_waitcnt lgkmcnt(0)
	v_mov_b32_e32 v2, v4
	v_mov_b32_e32 v3, v6
	v_pk_mul_f32 v[2:3], v[52:53], v[2:3]
	v_mov_b32_e32 v6, v5
	v_pk_mul_f32 v[4:5], v[54:55], v[6:7]
	v_cvt_pk_bf16_f32 v3, v3, v5
	v_cvt_pk_bf16_f32 v2, v2, v4
	ds_read_b128 v[4:7], v74
	v_add_co_u32_e32 v12, vcc, s70, v12
	s_nop 1
	v_addc_co_u32_e32 v13, vcc, 0, v13, vcc
	global_store_dwordx4 v[12:13], v[0:3], off offset:2048
	s_waitcnt lgkmcnt(0)
	v_mov_b32_e32 v12, v4
	v_mov_b32_e32 v13, v6
	ds_read_b128 v[0:3], v74 offset:16
	v_pk_mul_f32 v[12:13], v[40:41], v[12:13]
	v_mov_b32_e32 v6, v5
	v_pk_mul_f32 v[4:5], v[42:43], v[6:7]
	v_cvt_pk_bf16_f32 v5, v13, v5
	v_cvt_pk_bf16_f32 v4, v12, v4
	s_waitcnt lgkmcnt(0)
	v_mov_b32_e32 v6, v0
	v_mov_b32_e32 v7, v2
	v_pk_mul_f32 v[6:7], v[44:45], v[6:7]
	v_mov_b32_e32 v2, v1
	v_pk_mul_f32 v[0:1], v[46:47], v[2:3]
	v_cvt_pk_bf16_f32 v7, v7, v1
	v_cvt_pk_bf16_f32 v6, v6, v0
	ds_read_b128 v[0:3], v73
	v_add_co_u32_e32 v10, vcc, s70, v10
	s_nop 1
	v_addc_co_u32_e32 v11, vcc, 0, v11, vcc
	global_store_dwordx4 v[10:11], v[4:7], off offset:2048
	s_waitcnt lgkmcnt(0)
	v_mov_b32_e32 v10, v0
	v_mov_b32_e32 v11, v2
	ds_read_b128 v[4:7], v73 offset:16
	v_pk_mul_f32 v[10:11], v[32:33], v[10:11]
	v_mov_b32_e32 v2, v1
	v_pk_mul_f32 v[0:1], v[34:35], v[2:3]
	v_cvt_pk_bf16_f32 v1, v11, v1
	v_cvt_pk_bf16_f32 v0, v10, v0
	s_waitcnt lgkmcnt(0)
	v_mov_b32_e32 v2, v4
	v_mov_b32_e32 v3, v6
	v_pk_mul_f32 v[2:3], v[36:37], v[2:3]
	v_mov_b32_e32 v6, v5
	v_pk_mul_f32 v[4:5], v[38:39], v[6:7]
	v_cvt_pk_bf16_f32 v3, v3, v5
	v_cvt_pk_bf16_f32 v2, v2, v4
	ds_read_b128 v[4:7], v72
	v_add_co_u32_e32 v8, vcc, s70, v8
	s_nop 1
	v_addc_co_u32_e32 v9, vcc, 0, v9, vcc
	global_store_dwordx4 v[8:9], v[0:3], off offset:2048
	s_waitcnt lgkmcnt(0)
	v_mov_b32_e32 v8, v4
	v_mov_b32_e32 v9, v6
	ds_read_b128 v[0:3], v72 offset:16
	v_pk_mul_f32 v[8:9], v[18:19], v[8:9]
	v_mov_b32_e32 v6, v5
	v_pk_mul_f32 v[4:5], v[22:23], v[6:7]
	v_cvt_pk_bf16_f32 v5, v9, v5
	v_cvt_pk_bf16_f32 v4, v8, v4
	s_waitcnt lgkmcnt(0)
	v_mov_b32_e32 v6, v0
	v_mov_b32_e32 v7, v2
	v_pk_mul_f32 v[6:7], v[24:25], v[6:7]
	v_mov_b32_e32 v2, v1
	v_pk_mul_f32 v[0:1], v[28:29], v[2:3]
	v_cvt_pk_bf16_f32 v6, v6, v0
	v_add_co_u32_e32 v0, vcc, 0x184a1000, v14
	v_cvt_pk_bf16_f32 v7, v7, v1
	s_nop 0
	v_addc_co_u32_e32 v1, vcc, 0, v15, vcc
	global_store_dwordx4 v[0:1], v[4:7], off offset:2048
	s_barrier

; #define MFMA16(a, b, c) __builtin_amdgcn_mfma_f32_16x16x32_bf16(a, b, c, 0, 0, 0)
; __device__ void gmlp_item(const Params& p, int layer, int b, int n, int g, char* smem) {
;     ...
; #pragma unroll 2
;   for (int i = 0; i < 8; ++i) {
;     int q = tid + 256 * i;
;     int t = q >> 4, cch = q & 15;
;     uint4 v = *reinterpret_cast<const uint4*>(Ws + (size_t)g * 16384 + t * 128 + cch * 8);
;     *reinterpret_cast<uint4*>(smem + (cch >> 2) * 8192 + t * 64 + (cch & 3) * 16) = v;
;   }
;   __syncthreads();
;   f32x4 acc[4][4];
; #pragma unroll
;   for (int m = 0; m < 4; ++m)
; #pragma unroll
;     for (int nn = 0; nn < 4; ++nn) acc[m][nn] = f32x4{0.f, 0.f, 0.f, 0.f};
; #pragma unroll
;   for (int ks = 0; ks < 4; ++ks) {
;     bf16x8 a[4], bb[4];
; #pragma unroll
;     for (int m = 0; m < 4; ++m)
;       a[m] = *reinterpret_cast<const bf16x8*>(smem + ks * 8192 + (wr * 64 + m * 16 + fr) * 64 + fq * 16);
; #pragma unroll
;     for (int nn = 0; nn < 4; ++nn)
;       bb[nn] = *reinterpret_cast<const bf16x8*>(smem + 32768 + ks * 8192 + (wc * 64 + nn * 16 + fr) * 64 + fq * 16);
; #pragma unroll
;     for (int m = 0; m < 4; ++m)
; #pragma unroll
;       for (int nn = 0; nn < 4; ++nn) acc[m][nn] = MFMA16(a[m], bb[nn], acc[m][nn]);
;   }
.LBB0_1122:
	v_add_u32_e32 v3, s8, v59
	v_ashrrev_i32_e32 v12, 4, v3
	v_add_u32_e32 v3, 0x100, v3
	v_ashrrev_i32_e32 v3, 4, v3
	v_lshlrev_b32_e32 v4, 7, v12
	v_lshlrev_b32_e32 v6, 7, v3
	v_ashrrev_i32_e32 v5, 31, v4
	v_ashrrev_i32_e32 v7, 31, v6
	v_lshl_add_u64 v[4:5], v[4:5], 1, v[0:1]
	v_lshl_add_u64 v[8:9], v[6:7], 1, v[0:1]
	global_load_dwordx4 v[4:7], v[4:5], off
	s_nop 0
	global_load_dwordx4 v[8:11], v[8:9], off
	s_addk_i32 s8, 0x200
	s_cmpk_lg_i32 s8, 0x800
	v_lshl_add_u32 v12, v12, 6, v2
	v_lshl_add_u32 v3, v3, 6, v2
	s_waitcnt vmcnt(1)
	ds_write_b128 v12, v[4:7]
	s_waitcnt vmcnt(0)
	ds_write_b128 v3, v[8:11]
	s_cbranch_scc1 .LBB0_1122
	v_bfe_u32 v54, v59, 4, 2
	v_ashrrev_i32_e32 v55, 7, v59
	v_lshlrev_b32_e32 v4, 4, v54
	v_lshlrev_b32_e32 v0, 12, v55
	v_lshlrev_b32_e32 v5, 6, v49
	v_or3_b32 v57, v4, v0, v5
	s_waitcnt lgkmcnt(0)
	s_barrier
	ds_read_b128 v[0:3], v57
	v_bfe_u32 v61, v59, 6, 1
	v_lshlrev_b32_e32 v6, 12, v61
	v_or3_b32 v63, v4, v6, v5
	ds_read_b128 v[4:7], v63 offset:32768
	ds_read_b128 v[8:11], v57 offset:1024
	ds_read_b128 v[12:15], v63 offset:33792
	ds_read_b128 v[24:27], v63 offset:34816
	ds_read_b128 v[28:31], v63 offset:35840
	s_waitcnt lgkmcnt(4)
	v_mfma_f32_16x16x32_bf16 v[16:19], v[0:3], v[4:7], 0
	s_ashr_i32 s8, s11, 31
	s_add_u32 s11, s28, s11
	s_addc_u32 s12, s29, s8
	s_waitcnt lgkmcnt(2)
	v_mfma_f32_16x16x32_bf16 v[20:23], v[0:3], v[12:15], 0
	s_lshl_b32 s8, s10, 2
	s_add_u32 s8, s20, s8
	v_lshlrev_b32_e32 v55, 6, v55
	s_waitcnt lgkmcnt(1)
	v_mfma_f32_16x16x32_bf16 v[36:39], v[0:3], v[24:27], 0
	s_addc_u32 s9, s21, 0
	v_lshl_or_b32 v54, v54, 2, v55
	s_add_u32 s8, s8, 0x1800
	s_waitcnt lgkmcnt(0)
	v_mfma_f32_16x16x32_bf16 v[40:43], v[0:3], v[28:31], 0
	s_addc_u32 s9, s9, 0
	v_ashrrev_i32_e32 v55, 31, v54
	v_lshl_add_u64 v[126:127], v[54:55], 2, s[8:9]
	v_mfma_f32_16x16x32_bf16 v[44:47], v[8:11], v[4:7], 0
	v_or_b32_e32 v130, 32, v54
	v_ashrrev_i32_e32 v131, 31, v130
	v_lshlrev_b32_e32 v49, 2, v49
	v_mfma_f32_16x16x32_bf16 v[50:53], v[8:11], v[12:15], 0
	v_lshl_add_u64 v[130:131], v[130:131], 2, s[8:9]
	v_ashrrev_i32_e32 v69, 31, v68
	v_ashrrev_i32_e32 v67, 31, v66
	v_mfma_f32_16x16x32_bf16 v[70:73], v[8:11], v[24:27], 0
	v_ashrrev_i32_e32 v65, 31, v64
	v_mfma_f32_16x16x32_bf16 v[74:77], v[8:11], v[28:31], 0
	ds_read_b128 v[0:3], v57 offset:2048
	ds_read_b128 v[8:11], v57 offset:3072
	s_waitcnt lgkmcnt(1)
	v_mfma_f32_16x16x32_bf16 v[82:85], v[0:3], v[12:15], 0
	s_waitcnt lgkmcnt(0)
	v_mfma_f32_16x16x32_bf16 v[98:101], v[8:11], v[12:15], 0
	ds_read_b128 v[12:15], v57 offset:8192
	v_mfma_f32_16x16x32_bf16 v[78:81], v[0:3], v[4:7], 0
	v_mfma_f32_16x16x32_bf16 v[86:89], v[0:3], v[24:27], 0
	v_mfma_f32_16x16x32_bf16 v[94:97], v[8:11], v[4:7], 0
	v_mfma_f32_16x16x32_bf16 v[32:35], v[8:11], v[24:27], 0
	ds_read_b128 v[102:105], v63 offset:40960
	ds_read_b128 v[24:27], v57 offset:9216
	ds_read_b128 v[106:109], v63 offset:41984
	ds_read_b128 v[118:121], v63 offset:43008
	ds_read_b128 v[4:7], v63 offset:44032
	v_mfma_f32_16x16x32_bf16 v[90:93], v[0:3], v[28:31], 0
	s_waitcnt lgkmcnt(4)
	v_mfma_f32_16x16x32_bf16 v[110:113], v[12:15], v[102:105], v[16:19]
	s_waitcnt lgkmcnt(2)
	v_mfma_f32_16x16x32_bf16 v[114:117], v[12:15], v[106:109], v[20:23]
	s_waitcnt lgkmcnt(1)
	v_mfma_f32_16x16x32_bf16 v[122:125], v[12:15], v[118:121], v[36:39]
	s_waitcnt lgkmcnt(0)
	v_mfma_f32_16x16x32_bf16 v[134:137], v[12:15], v[4:7], v[40:43]
	ds_read_b128 v[146:149], v57 offset:10240
	ds_read_b128 v[12:15], v57 offset:11264
	v_mfma_f32_16x16x32_bf16 v[0:3], v[8:11], v[28:31], 0
	ds_read_b128 v[150:153], v57 offset:16384
	ds_read_b128 v[162:165], v57 offset:17408
	ds_read_b128 v[166:169], v57 offset:18432
	ds_read_b128 v[8:11], v57 offset:19456
	ds_read_b128 v[36:39], v63 offset:49152
	ds_read_b128 v[28:31], v63 offset:50176
	ds_read_b128 v[20:23], v63 offset:51200
	ds_read_b128 v[16:19], v63 offset:52224
	v_mfma_f32_16x16x32_bf16 v[138:141], v[24:27], v[102:105], v[44:47]
	v_mfma_f32_16x16x32_bf16 v[50:53], v[24:27], v[106:109], v[50:53]
	v_mfma_f32_16x16x32_bf16 v[70:73], v[24:27], v[118:121], v[70:73]
	v_mfma_f32_16x16x32_bf16 v[74:77], v[24:27], v[4:7], v[74:77]
	ds_read_b128 v[170:173], v57 offset:24576
	ds_read_b128 v[174:177], v57 offset:25600
	ds_read_b128 v[178:181], v57 offset:26624
	ds_read_b128 v[24:27], v57 offset:27648
	ds_read_b128 v[182:185], v63 offset:57344
	ds_read_b128 v[186:189], v63 offset:58368
	ds_read_b128 v[44:47], v63 offset:59392
	ds_read_b128 v[40:43], v63 offset:60416
	s_waitcnt lgkmcnt(0)
	v_mfma_f32_16x16x32_bf16 v[78:81], v[146:149], v[102:105], v[78:81]
	s_barrier
; #define MFMA16(a, b, c) __builtin_amdgcn_mfma_f32_16x16x32_bf16(a, b, c, 0, 0, 0)
; __device__ void gmlp_item(const Params& p, int layer, int b, int n, int g, char* smem) {
;     ...
; #pragma unroll
;     for (int m = 0; m < 4; ++m)
; #pragma unroll
;       for (int nn = 0; nn < 4; ++nn) acc[m][nn] = MFMA16(a[m], bb[nn], acc[m][nn]);
;   }
;   __syncthreads();
;   {
;     float* Tf = reinterpret_cast<float*>(smem);
; #pragma unroll
;     for (int m = 0; m < 4; ++m)
; #pragma unroll
;       for (int j = 0; j < 4; ++j) {
;         int t = wr * 64 + m * 16 + fq * 4 + j;
;         float bias = p.gm_b_s[(size_t)layer * 512 + g * 128 + t];
; #pragma unroll
;         for (int nn = 0; nn < 4; ++nn) Tf[t * 132 + wc * 64 + nn * 16 + fr] = acc[m][nn][j] + bias;
;       }
	global_load_dwordx4 v[190:193], v[130:131], off
	v_mfma_f32_16x16x32_bf16 v[82:85], v[146:149], v[106:109], v[82:85]
	v_ashrrev_i32_e32 v63, 31, v62
	v_mfma_f32_16x16x32_bf16 v[86:89], v[146:149], v[118:121], v[86:89]
	v_mfma_f32_16x16x32_bf16 v[90:93], v[146:149], v[4:7], v[90:93]
	global_load_dwordx4 v[146:149], v[126:127], off
	v_or_b32_e32 v126, 16, v54
	v_ashrrev_i32_e32 v127, 31, v126
	v_lshl_add_u64 v[126:127], v[126:127], 2, s[8:9]
	v_mfma_f32_16x16x32_bf16 v[110:113], v[150:153], v[36:39], v[110:113]
	v_mfma_f32_16x16x32_bf16 v[114:117], v[150:153], v[28:31], v[114:117]
	v_mfma_f32_16x16x32_bf16 v[122:125], v[150:153], v[20:23], v[122:125]
	v_mfma_f32_16x16x32_bf16 v[134:137], v[150:153], v[16:19], v[134:137]
	global_load_dwordx4 v[150:153], v[126:127], off
	v_lshl_or_b32 v126, v61, 8, v49
	v_mad_u64_u32 v[126:127], s[42:43], v54, s55, v[126:127]
	v_mfma_f32_16x16x32_bf16 v[110:113], v[170:173], v[182:185], v[110:113]
	v_add_u32_e32 v57, 0x400, v126
	v_or_b32_e32 v54, 48, v54
	v_ashrrev_i32_e32 v61, 31, v60
	v_mfma_f32_16x16x32_bf16 v[114:117], v[170:173], v[186:189], v[114:117]
	v_mfma_f32_16x16x32_bf16 v[122:125], v[170:173], v[44:47], v[122:125]
	s_waitcnt vmcnt(1)
	s_nop 1
	v_add_f32_e32 v49, v110, v146
	v_mfma_f32_16x16x32_bf16 v[134:137], v[170:173], v[40:43], v[134:137]
	s_nop 1
	v_add_f32_e32 v55, v114, v146
	ds_write2_b32 v126, v49, v55 offset1:16
	v_add_f32_e32 v49, v122, v146
	v_mfma_f32_16x16x32_bf16 v[98:101], v[12:15], v[106:109], v[98:101]
	v_mfma_f32_16x16x32_bf16 v[94:97], v[12:15], v[102:105], v[94:97]
	s_nop 0
	v_add_f32_e32 v55, v134, v146
	ds_write2_b32 v126, v49, v55 offset0:32 offset1:48
	v_add_f32_e32 v49, v111, v147
	v_add_f32_e32 v55, v115, v147
	ds_write2_b32 v126, v49, v55 offset0:132 offset1:148
	v_add_f32_e32 v49, v123, v147
	v_add_f32_e32 v55, v135, v147
	ds_write2_b32 v126, v49, v55 offset0:164 offset1:180
	v_add_f32_e32 v49, v112, v148
	v_add_f32_e32 v55, v116, v148
	ds_write2_b32 v57, v49, v55 offset0:8 offset1:24
	v_add_f32_e32 v49, v124, v148
	v_add_f32_e32 v55, v136, v148
	ds_write2_b32 v57, v49, v55 offset0:40 offset1:56
	v_add_f32_e32 v49, v113, v149
	v_add_f32_e32 v55, v117, v149
	ds_write2_b32 v57, v49, v55 offset0:140 offset1:156
	v_add_f32_e32 v49, v125, v149
	v_add_f32_e32 v55, v137, v149
	ds_write2_b32 v57, v49, v55 offset0:172 offset1:188
	v_ashrrev_i32_e32 v55, 31, v54
	v_lshl_add_u64 v[54:55], v[54:55], 2, s[8:9]
	global_load_dwordx4 v[106:109], v[54:55], off
	v_mfma_f32_16x16x32_bf16 v[102:105], v[162:165], v[36:39], v[138:141]
	v_add_u32_e32 v54, 0x2000, v126
	v_ashrrev_i32_e32 v57, 31, v56
	v_mfma_f32_16x16x32_bf16 v[50:53], v[162:165], v[28:31], v[50:53]
	v_mfma_f32_16x16x32_bf16 v[70:73], v[162:165], v[20:23], v[70:73]
	v_mfma_f32_16x16x32_bf16 v[74:77], v[162:165], v[16:19], v[74:77]
	v_mfma_f32_16x16x32_bf16 v[102:105], v[174:177], v[182:185], v[102:105]
	v_mfma_f32_16x16x32_bf16 v[50:53], v[174:177], v[186:189], v[50:53]
	v_mfma_f32_16x16x32_bf16 v[70:73], v[174:177], v[44:47], v[70:73]
	s_waitcnt vmcnt(1)
	s_nop 4
	v_add_f32_e32 v49, v102, v150
	v_add_f32_e32 v50, v50, v150
	ds_write2_b32 v54, v49, v50 offset0:64 offset1:80
	v_mfma_f32_16x16x32_bf16 v[74:77], v[174:177], v[40:43], v[74:77]
	v_add_f32_e32 v55, v53, v153
	v_add_f32_e32 v49, v70, v150
	v_mfma_f32_16x16x32_bf16 v[78:81], v[166:169], v[36:39], v[78:81]
	v_mfma_f32_16x16x32_bf16 v[82:85], v[166:169], v[28:31], v[82:85]
	s_nop 3
	v_add_f32_e32 v50, v74, v150
	ds_write2_b32 v54, v49, v50 offset0:96 offset1:112
	v_add_f32_e32 v49, v103, v151
	v_add_f32_e32 v50, v51, v151
	ds_write2_b32 v54, v49, v50 offset0:196 offset1:212
	v_add_f32_e32 v49, v71, v151
	v_add_f32_e32 v50, v75, v151
	ds_write2_b32 v54, v49, v50 offset0:228 offset1:244
	v_add_f32_e32 v49, v104, v152
	v_add_f32_e32 v50, v52, v152
	v_add_u32_e32 v54, 0x2400, v126
	v_mfma_f32_16x16x32_bf16 v[86:89], v[166:169], v[20:23], v[86:89]
	ds_write2_b32 v54, v49, v50 offset0:72 offset1:88
	v_add_f32_e32 v49, v72, v152
	v_add_f32_e32 v50, v76, v152
	v_mfma_f32_16x16x32_bf16 v[90:93], v[166:169], v[16:19], v[90:93]
	ds_write2_b32 v54, v49, v50 offset0:104 offset1:120
	v_add_f32_e32 v49, v105, v153
	ds_write2_b32 v54, v49, v55 offset0:204 offset1:220
	v_mfma_f32_16x16x32_bf16 v[50:53], v[178:181], v[182:185], v[78:81]
	v_add_f32_e32 v49, v73, v153
	v_add_f32_e32 v55, v77, v153
	ds_write2_b32 v54, v49, v55 offset0:236 offset1:252
	v_mfma_f32_16x16x32_bf16 v[70:73], v[178:181], v[186:189], v[82:85]
	v_add_u32_e32 v54, 0x4000, v126
	s_nop 2
	v_add_f32_e32 v49, v50, v190
	v_mfma_f32_16x16x32_bf16 v[74:77], v[178:181], v[44:47], v[86:89]
	v_mfma_f32_16x16x32_bf16 v[78:81], v[178:181], v[40:43], v[90:93]
	s_nop 0
	v_add_f32_e32 v50, v70, v190
	ds_write2_b32 v54, v49, v50 offset0:128 offset1:144
	s_nop 3
	v_add_f32_e32 v49, v74, v190
	v_mfma_f32_16x16x32_bf16 v[32:35], v[12:15], v[118:121], v[32:35]
	v_mfma_f32_16x16x32_bf16 v[0:3], v[12:15], v[4:7], v[0:3]
	v_add_f32_e32 v50, v78, v190
	ds_write2_b32 v54, v49, v50 offset0:160 offset1:176
	v_add_f32_e32 v49, v51, v191
	v_add_f32_e32 v4, v71, v191
	v_add_u32_e32 v50, 0x4400, v126
	v_add_f32_e32 v12, v75, v191
	v_add_f32_e32 v13, v79, v191
	ds_write2_b32 v50, v49, v4 offset0:4 offset1:20
	v_mfma_f32_16x16x32_bf16 v[4:7], v[8:11], v[36:39], v[94:97]
	ds_write2_b32 v50, v12, v13 offset0:36 offset1:52
	v_ashrrev_i32_e32 v49, 31, v48
	v_lshl_add_u64 v[70:71], v[56:57], 0, s[16:17]
	v_mfma_f32_16x16x32_bf16 v[12:15], v[8:11], v[28:31], v[98:101]
	v_add_f32_e32 v28, v52, v192
	v_add_f32_e32 v29, v72, v192
	ds_write2_b32 v50, v28, v29 offset0:136 offset1:152
	v_mfma_f32_16x16x32_bf16 v[20:23], v[8:11], v[20:23], v[32:35]
	v_add_f32_e32 v28, v76, v192
	v_add_f32_e32 v29, v80, v192
	ds_write2_b32 v50, v28, v29 offset0:168 offset1:184
	v_mfma_f32_16x16x32_bf16 v[0:3], v[8:11], v[16:19], v[0:3]
	v_add_f32_e32 v8, v53, v193
	v_add_f32_e32 v9, v73, v193
	v_add_u32_e32 v16, 0x4800, v126
	v_mfma_f32_16x16x32_bf16 v[4:7], v[24:27], v[182:185], v[4:7]
	ds_write2_b32 v16, v8, v9 offset0:12 offset1:28
	v_add_f32_e32 v17, v77, v193
	v_add_f32_e32 v18, v81, v193
	v_mfma_f32_16x16x32_bf16 v[8:11], v[24:27], v[186:189], v[12:15]
	ds_write2_b32 v16, v17, v18 offset0:44 offset1:60
	s_waitcnt vmcnt(0)
; __device__ __forceinline__ unsigned pack2(float a, float b) { return (unsigned)f2bf(a) | ((unsigned)f2bf(b) << 16); }
; __device__ __forceinline__ float bflo(unsigned w) { return __uint_as_float(w << 16); }
; __device__ __forceinline__ float bfhi(unsigned w) { return __uint_as_float(w & 0xffff0000u); }
; __device__ __forceinline__ float silu_f(float g) { return g / (1.f + __expf(-g)); }
; __device__ void gmlp_item(const Params& p, int layer, int b, int n, int g, char* smem) {
;     ...
;   {
;     float* Tf = reinterpret_cast<float*>(smem);
; #pragma unroll
;     for (int m = 0; m < 4; ++m)
; #pragma unroll
;       for (int j = 0; j < 4; ++j) {
;         int t = wr * 64 + m * 16 + fq * 4 + j;
;         float bias = p.gm_b_s[(size_t)layer * 512 + g * 128 + t];
; #pragma unroll
;         for (int nn = 0; nn < 4; ++nn) Tf[t * 132 + wc * 64 + nn * 16 + fr] = acc[m][nn][j] + bias;
;       }
;     __syncthreads();
;     uint4 uu[8], gt[8];
; #pragma unroll
;     for (int i = 0; i < 8; ++i) {
;       int q = tid + 256 * i, t = q >> 4, c = (q & 15) * 8;
;       uu[i] = *reinterpret_cast<const uint4*>(P + (t0 + t) * NP + g * 128 + c);
;       gt[i] = *reinterpret_cast<const uint4*>(P + (t0 + t) * NP + 1024 + g * 128 + c);
;     }
; #pragma unroll
;     for (int i = 0; i < 8; ++i) {
;       int q = tid + 256 * i, t = q >> 4, c = (q & 15) * 8;
;       float4 m0 = *reinterpret_cast<const float4*>(Tf + t * 132 + c);
;       float4 m1 = *reinterpret_cast<const float4*>(Tf + t * 132 + c + 4);
;       float mm[8] = {m0.x, m0.y, m0.z, m0.w, m1.x, m1.y, m1.z, m1.w};
;       unsigned uw[4] = {uu[i].x, uu[i].y, uu[i].z, uu[i].w};
;       unsigned gw[4] = {gt[i].x, gt[i].y, gt[i].z, gt[i].w};
;       unsigned ow[4];
; #pragma unroll
;       for (int e = 0; e < 4; ++e) {
;         float y0 = bflo(uw[e]) * mm[2 * e] * silu_f(bflo(gw[e]));
;         float y1 = bfhi(uw[e]) * mm[2 * e + 1] * silu_f(bfhi(gw[e]));
;         ow[e] = pack2(y0, y1);
;       }
;       *reinterpret_cast<uint4*>(Y + (t0 + t) * YW + g * 128 + c) = make_uint4(ow[0], ow[1], ow[2], ow[3]);
	s_nop 1
	v_add_f32_e32 v4, v4, v106
	v_add_u32_e32 v16, 0x6000, v126
	v_mfma_f32_16x16x32_bf16 v[12:15], v[24:27], v[44:47], v[20:23]
	v_lshl_add_u64 v[36:37], v[62:63], 0, s[16:17]
	v_add_f32_e32 v8, v8, v106
	ds_write2_b32 v16, v4, v8 offset0:192 offset1:208
	v_mfma_f32_16x16x32_bf16 v[0:3], v[24:27], v[40:43], v[0:3]
	v_lshl_add_u64 v[20:21], v[64:65], 0, s[16:17]
	s_nop 2
	v_add_f32_e32 v4, v12, v106
	v_lshl_add_u64 v[38:39], v[60:61], 0, s[16:17]
	s_nop 1
	v_add_f32_e32 v0, v0, v106
	ds_write2_b32 v16, v4, v0 offset0:224 offset1:240
	v_add_f32_e32 v0, v5, v107
	v_add_f32_e32 v4, v9, v107
	v_add_u32_e32 v5, 0x6400, v126
	ds_write2_b32 v5, v0, v4 offset0:68 offset1:84
	v_add_f32_e32 v0, v13, v107
	v_add_f32_e32 v1, v1, v107
	ds_write2_b32 v5, v0, v1 offset0:100 offset1:116
	v_add_f32_e32 v0, v6, v108
	v_add_f32_e32 v1, v10, v108
	ds_write2_b32 v5, v0, v1 offset0:200 offset1:216
	v_add_f32_e32 v0, v14, v108
	v_add_f32_e32 v1, v2, v108
	ds_write2_b32 v5, v0, v1 offset0:232 offset1:248
	v_add_f32_e32 v0, v7, v109
	v_add_f32_e32 v1, v11, v109
	v_add_u32_e32 v2, 0x6800, v126
	ds_write2_b32 v2, v0, v1 offset0:76 offset1:92
	v_add_f32_e32 v0, v15, v109
	v_add_f32_e32 v1, v3, v109
	ds_write2_b32 v2, v0, v1 offset0:108 offset1:124
	v_lshlrev_b32_e32 v0, 3, v59
	v_lshl_add_u64 v[8:9], v[48:49], 0, s[16:17]
	v_mov_b64_e32 v[10:11], s[6:7]
	v_and_b32_e32 v24, 0x78, v0
	v_mad_u64_u32 v[0:1], s[6:7], v8, s39, v[10:11]
	v_mad_i32_i24 v1, v9, s39, v1
	s_lshl_b32 s6, s10, 1
	s_mov_b32 s7, s17
	v_lshl_add_u64 v[0:1], v[0:1], 0, s[6:7]
	v_lshlrev_b32_e32 v128, 1, v24
	v_lshl_add_u64 v[12:13], v[68:69], 0, s[16:17]
	v_lshl_add_u64 v[52:53], v[0:1], 0, v[128:129]
	v_mad_u64_u32 v[0:1], s[8:9], v12, s39, v[10:11]
	v_mad_i32_i24 v1, v13, s39, v1
	v_lshl_add_u64 v[0:1], v[0:1], 0, s[6:7]
	v_lshl_add_u64 v[32:33], v[0:1], 0, v[128:129]
	v_mad_u64_u32 v[0:1], s[8:9], v70, s39, v[10:11]
	v_mad_i32_i24 v1, v71, s39, v1
	v_lshl_add_u64 v[0:1], v[0:1], 0, s[6:7]
	v_lshl_add_u64 v[4:5], v[0:1], 0, v[128:129]
	s_waitcnt lgkmcnt(0)
	s_barrier
	global_load_dwordx4 v[0:3], v[4:5], off
	s_nop 0
	global_load_dwordx4 v[4:7], v[4:5], off offset:2048
	v_lshl_add_u64 v[16:17], v[66:67], 0, s[16:17]
	v_mad_u64_u32 v[14:15], s[8:9], v16, s39, v[10:11]
	v_mad_i32_i24 v15, v17, s39, v15
	v_lshl_add_u64 v[14:15], v[14:15], 0, s[6:7]
	v_lshl_add_u64 v[30:31], v[14:15], 0, v[128:129]
	v_mad_u64_u32 v[14:15], s[8:9], v20, s39, v[10:11]
	v_mad_i32_i24 v15, v21, s39, v15
	v_lshl_add_u64 v[14:15], v[14:15], 0, s[6:7]
	v_lshl_add_u64 v[26:27], v[14:15], 0, v[128:129]
	v_mad_u64_u32 v[14:15], s[8:9], v36, s39, v[10:11]
	v_mad_i32_i24 v15, v37, s39, v15
	v_ashrrev_i32_e32 v59, 31, v58
	v_lshl_add_u64 v[14:15], v[14:15], 0, s[6:7]
	v_lshl_add_u64 v[72:73], v[58:59], 0, s[16:17]
	v_lshl_add_u64 v[22:23], v[14:15], 0, v[128:129]
	v_mad_u64_u32 v[14:15], s[8:9], v38, s39, v[10:11]
	v_mad_u64_u32 v[10:11], s[8:9], v72, s39, v[10:11]
	v_mad_i32_i24 v15, v39, s39, v15
	v_mad_i32_i24 v11, v73, s39, v11
	v_lshl_add_u64 v[14:15], v[14:15], 0, s[6:7]
	v_lshl_add_u64 v[10:11], v[10:11], 0, s[6:7]
	s_add_u32 s6, s11, s6
	s_addc_u32 s7, s12, 0
	v_lshl_add_u64 v[18:19], v[14:15], 0, v[128:129]
	v_lshl_add_u64 v[14:15], v[10:11], 0, v[128:129]
	v_lshlrev_b32_e32 v10, 2, v24
	v_lshl_add_u64 v[24:25], s[6:7], 0, v[128:129]
	v_lshl_add_u64 v[74:75], v[24:25], 0, s[26:27]
	v_mad_u64_u32 v[54:55], s[6:7], v48, s55, v[10:11]
	v_mad_u64_u32 v[48:49], s[6:7], v12, s63, v[74:75]
	v_mad_u64_u32 v[46:47], s[6:7], v16, s63, v[74:75]
	v_mad_u64_u32 v[50:51], s[6:7], v8, s63, v[74:75]
	v_mad_i32_i24 v49, v13, s63, v49
	v_mad_i32_i24 v47, v17, s63, v47
	v_mad_u64_u32 v[44:45], s[6:7], v20, s63, v[74:75]
	v_mad_u64_u32 v[16:17], s[6:7], v60, s55, v[10:11]
	v_mad_u64_u32 v[12:13], s[6:7], v58, s55, v[10:11]
	v_mad_i32_i24 v51, v9, s63, v51
	v_mad_i32_i24 v45, v21, s63, v45
	v_mad_u64_u32 v[20:21], s[6:7], v62, s55, v[10:11]
	v_mad_u64_u32 v[8:9], s[6:7], v56, s55, v[10:11]
	v_mad_u64_u32 v[28:29], s[6:7], v66, s55, v[10:11]
	v_mad_u64_u32 v[34:35], s[6:7], v68, s55, v[10:11]
	v_mad_u64_u32 v[24:25], s[6:7], v64, s55, v[10:11]
	v_mad_u64_u32 v[42:43], s[6:7], v36, s63, v[74:75]
	v_mad_i32_i24 v43, v37, s63, v43
	v_mad_u64_u32 v[36:37], s[6:7], v70, s63, v[74:75]
	v_mad_u64_u32 v[40:41], s[6:7], v38, s63, v[74:75]
	v_mad_i32_i24 v41, v39, s63, v41
	v_mad_u64_u32 v[38:39], s[6:7], v72, s63, v[74:75]
	v_mad_i32_i24 v39, v73, s63, v39
	v_mad_i32_i24 v37, v71, s63, v37
	s_waitcnt vmcnt(1)
	v_lshlrev_b32_e32 v63, 16, v1
	s_waitcnt vmcnt(0)
	v_lshlrev_b32_e32 v13, 16, v5
	v_lshlrev_b32_e32 v17, 16, v4
	v_mul_f32_e32 v9, 0xbfb8aa3b, v17
	v_and_b32_e32 v21, 0xffff0000, v5
	v_mul_f32_e32 v5, 0xbfb8aa3b, v13
	v_exp_f32_e32 v60, v9
	v_exp_f32_e32 v61, v5
	ds_read_b128 v[56:59], v8
	ds_read_b128 v[8:11], v8 offset:16
	v_and_b32_e32 v25, 0xffff0000, v4
	v_mul_f32_e32 v4, 0xbfb8aa3b, v25
	v_pk_add_f32 v[60:61], v[60:61], 1.0 op_sel_hi:[1,0]
	s_waitcnt lgkmcnt(1)
	v_mov_b32_e32 v64, v56
	v_exp_f32_e32 v4, v4
	v_lshlrev_b32_e32 v62, 16, v0
	v_mov_b32_e32 v65, v58
	v_rcp_f32_e32 v61, v61
	s_nop 0
	v_mul_f32_e32 v61, v13, v61
	v_and_b32_e32 v1, 0xffff0000, v1
	v_mul_f32_e32 v5, 0xbfb8aa3b, v21
	v_exp_f32_e32 v5, v5
	v_rcp_f32_e32 v60, v60
	s_nop 0
	v_mul_f32_e32 v60, v17, v60
	v_and_b32_e32 v0, 0xffff0000, v0
	v_mov_b32_e32 v58, v57
	v_pk_add_f32 v[4:5], v[4:5], 1.0 op_sel_hi:[1,0]
	v_pk_mul_f32 v[0:1], v[58:59], v[0:1]
	v_pk_mul_f32 v[62:63], v[64:65], v[62:63]
	v_rcp_f32_e32 v5, v5
	s_nop 0
	v_mul_f32_e32 v5, v21, v5
	v_pk_mul_f32 v[60:61], v[60:61], v[62:63]
	v_rcp_f32_e32 v4, v4
	s_nop 0
	v_mul_f32_e32 v4, v25, v4
	v_pk_mul_f32 v[0:1], v[4:5], v[0:1]
	v_lshlrev_b32_e32 v13, 16, v7
	v_lshlrev_b32_e32 v17, 16, v6
	v_cvt_pk_bf16_f32 v1, v61, v1
	v_cvt_pk_bf16_f32 v0, v60, v0
	v_mul_f32_e32 v4, 0xbfb8aa3b, v17
	v_mul_f32_e32 v5, 0xbfb8aa3b, v13
	v_exp_f32_e32 v4, v4
	v_exp_f32_e32 v5, v5
	v_and_b32_e32 v25, 0xffff0000, v6
	v_mul_f32_e32 v6, 0xbfb8aa3b, v25
	v_and_b32_e32 v21, 0xffff0000, v7
	v_exp_f32_e32 v60, v6
	v_pk_add_f32 v[64:65], v[4:5], 1.0 op_sel_hi:[1,0]
	global_load_dwordx4 v[4:7], v[14:15], off
	global_load_dwordx4 v[56:59], v[14:15], off offset:2048
	s_waitcnt lgkmcnt(0)
; __device__ __forceinline__ unsigned pack2(float a, float b) { return (unsigned)f2bf(a) | ((unsigned)f2bf(b) << 16); }
; __device__ __forceinline__ float bflo(unsigned w) { return __uint_as_float(w << 16); }
; __device__ __forceinline__ float bfhi(unsigned w) { return __uint_as_float(w & 0xffff0000u); }
; __device__ __forceinline__ float silu_f(float g) { return g / (1.f + __expf(-g)); }
; __device__ void gmlp_item(const Params& p, int layer, int b, int n, int g, char* smem) {
;     ...
;     uint4 uu[8], gt[8];
; #pragma unroll
;     for (int i = 0; i < 8; ++i) {
;       int q = tid + 256 * i, t = q >> 4, c = (q & 15) * 8;
;       uu[i] = *reinterpret_cast<const uint4*>(P + (t0 + t) * NP + g * 128 + c);
;       gt[i] = *reinterpret_cast<const uint4*>(P + (t0 + t) * NP + 1024 + g * 128 + c);
;     }
; #pragma unroll
;     for (int i = 0; i < 8; ++i) {
;       int q = tid + 256 * i, t = q >> 4, c = (q & 15) * 8;
;       float4 m0 = *reinterpret_cast<const float4*>(Tf + t * 132 + c);
;       float4 m1 = *reinterpret_cast<const float4*>(Tf + t * 132 + c + 4);
;       float mm[8] = {m0.x, m0.y, m0.z, m0.w, m1.x, m1.y, m1.z, m1.w};
;       unsigned uw[4] = {uu[i].x, uu[i].y, uu[i].z, uu[i].w};
;       unsigned gw[4] = {gt[i].x, gt[i].y, gt[i].z, gt[i].w};
;       unsigned ow[4];
; #pragma unroll
;       for (int e = 0; e < 4; ++e) {
;         float y0 = bflo(uw[e]) * mm[2 * e] * silu_f(bflo(gw[e]));
;         float y1 = bfhi(uw[e]) * mm[2 * e + 1] * silu_f(bfhi(gw[e]));
;         ow[e] = pack2(y0, y1);
;       }
;       *reinterpret_cast<uint4*>(Y + (t0 + t) * YW + g * 128 + c) = make_uint4(ow[0], ow[1], ow[2], ow[3]);
;     }
	v_mov_b32_e32 v14, v8
	v_mov_b32_e32 v15, v10
	v_lshlrev_b32_e32 v63, 16, v3
	v_lshlrev_b32_e32 v62, 16, v2
	v_pk_mul_f32 v[14:15], v[14:15], v[62:63]
	v_rcp_f32_e32 v63, v65
	s_nop 0
	v_mul_f32_e32 v63, v13, v63
	v_mul_f32_e32 v10, 0xbfb8aa3b, v21
	v_exp_f32_e32 v61, v10
	v_rcp_f32_e32 v62, v64
	s_nop 0
	v_mul_f32_e32 v62, v17, v62
	v_mov_b32_e32 v10, v9
	v_and_b32_e32 v3, 0xffff0000, v3
	v_pk_add_f32 v[60:61], v[60:61], 1.0 op_sel_hi:[1,0]
	v_and_b32_e32 v2, 0xffff0000, v2
	v_pk_mul_f32 v[2:3], v[10:11], v[2:3]
	v_pk_mul_f32 v[14:15], v[62:63], v[14:15]
	v_rcp_f32_e32 v9, v61
	s_nop 0
	v_mul_f32_e32 v9, v21, v9
	v_rcp_f32_e32 v8, v60
	s_nop 0
	v_mul_f32_e32 v8, v25, v8
	v_pk_mul_f32 v[2:3], v[8:9], v[2:3]
	v_cvt_pk_bf16_f32 v3, v15, v3
	v_cvt_pk_bf16_f32 v2, v14, v2
	s_waitcnt vmcnt(0)
	v_lshlrev_b32_e32 v21, 16, v56
	v_mul_f32_e32 v8, 0xbfb8aa3b, v21
	v_and_b32_e32 v29, 0xffff0000, v56
	v_lshlrev_b32_e32 v17, 16, v57
	v_exp_f32_e32 v60, v8
	v_mul_f32_e32 v8, 0xbfb8aa3b, v29
	v_exp_f32_e32 v56, v8
	v_mul_f32_e32 v8, 0xbfb8aa3b, v17
	v_exp_f32_e32 v61, v8
	ds_read_b128 v[8:11], v12
	ds_read_b128 v[12:15], v12 offset:16
	v_and_b32_e32 v25, 0xffff0000, v57
	v_lshlrev_b32_e32 v63, 16, v5
	v_pk_add_f32 v[60:61], v[60:61], 1.0 op_sel_hi:[1,0]
	s_waitcnt lgkmcnt(1)
	v_mov_b32_e32 v64, v8
	v_mov_b32_e32 v65, v10
	v_lshlrev_b32_e32 v62, 16, v4
	v_and_b32_e32 v5, 0xffff0000, v5
	v_rcp_f32_e32 v61, v61
	s_nop 0
	v_mul_f32_e32 v61, v17, v61
	v_and_b32_e32 v4, 0xffff0000, v4
	v_mul_f32_e32 v10, 0xbfb8aa3b, v25
	v_exp_f32_e32 v57, v10
	v_rcp_f32_e32 v60, v60
	s_nop 0
	v_mul_f32_e32 v60, v21, v60
	v_mov_b32_e32 v10, v9
	v_pk_mul_f32 v[4:5], v[10:11], v[4:5]
	v_pk_add_f32 v[56:57], v[56:57], 1.0 op_sel_hi:[1,0]
	v_pk_mul_f32 v[62:63], v[64:65], v[62:63]
	v_pk_mul_f32 v[60:61], v[60:61], v[62:63]
	v_lshlrev_b32_e32 v63, 16, v7
	v_lshlrev_b32_e32 v62, 16, v6
	v_rcp_f32_e32 v9, v57
	s_nop 0
	v_mul_f32_e32 v9, v25, v9
	v_rcp_f32_e32 v8, v56
	s_nop 0
	v_mul_f32_e32 v8, v29, v8
	v_pk_mul_f32 v[4:5], v[8:9], v[4:5]
	v_lshlrev_b32_e32 v17, 16, v59
	v_lshlrev_b32_e32 v21, 16, v58
	v_cvt_pk_bf16_f32 v5, v61, v5
	v_cvt_pk_bf16_f32 v4, v60, v4
	v_mul_f32_e32 v8, 0xbfb8aa3b, v21
	v_mul_f32_e32 v9, 0xbfb8aa3b, v17
	v_exp_f32_e32 v8, v8
	v_exp_f32_e32 v9, v9
	v_and_b32_e32 v29, 0xffff0000, v58
	v_mul_f32_e32 v10, 0xbfb8aa3b, v29
	v_and_b32_e32 v25, 0xffff0000, v59
	v_exp_f32_e32 v60, v10
	v_pk_add_f32 v[64:65], v[8:9], 1.0 op_sel_hi:[1,0]
	global_load_dwordx4 v[8:11], v[18:19], off
	global_load_dwordx4 v[56:59], v[18:19], off offset:2048
	s_waitcnt lgkmcnt(0)
	v_mov_b32_e32 v18, v12
	v_mov_b32_e32 v19, v14
	v_pk_mul_f32 v[18:19], v[18:19], v[62:63]
	v_rcp_f32_e32 v63, v65
	s_nop 0
	v_mul_f32_e32 v63, v17, v63
	v_and_b32_e32 v7, 0xffff0000, v7
	v_mul_f32_e32 v14, 0xbfb8aa3b, v25
	v_exp_f32_e32 v61, v14
	v_rcp_f32_e32 v62, v64
	s_nop 0
	v_mul_f32_e32 v62, v21, v62
	v_mov_b32_e32 v14, v13
	v_and_b32_e32 v6, 0xffff0000, v6
	v_pk_add_f32 v[60:61], v[60:61], 1.0 op_sel_hi:[1,0]
	v_pk_mul_f32 v[6:7], v[14:15], v[6:7]
	v_pk_mul_f32 v[18:19], v[62:63], v[18:19]
	v_rcp_f32_e32 v13, v61
	s_nop 0
	v_mul_f32_e32 v13, v25, v13
	v_rcp_f32_e32 v12, v60
	s_nop 0
	v_mul_f32_e32 v12, v29, v12
	v_pk_mul_f32 v[6:7], v[12:13], v[6:7]
	v_cvt_pk_bf16_f32 v7, v19, v7
	v_cvt_pk_bf16_f32 v6, v18, v6
	s_waitcnt vmcnt(1)
	v_lshlrev_b32_e32 v63, 16, v9
	s_waitcnt vmcnt(0)
	v_lshlrev_b32_e32 v25, 16, v56
	v_mul_f32_e32 v12, 0xbfb8aa3b, v25
	v_and_b32_e32 v35, 0xffff0000, v56
	v_lshlrev_b32_e32 v21, 16, v57
	v_exp_f32_e32 v60, v12
	v_mul_f32_e32 v12, 0xbfb8aa3b, v35
	v_exp_f32_e32 v56, v12
	v_mul_f32_e32 v12, 0xbfb8aa3b, v21
	v_exp_f32_e32 v61, v12
	v_and_b32_e32 v29, 0xffff0000, v57
	ds_read_b128 v[12:15], v16
	ds_read_b128 v[16:19], v16 offset:16
	v_lshlrev_b32_e32 v62, 16, v8
	v_pk_add_f32 v[60:61], v[60:61], 1.0 op_sel_hi:[1,0]
	v_and_b32_e32 v9, 0xffff0000, v9
	s_waitcnt lgkmcnt(1)
	v_mov_b32_e32 v64, v12
	v_mov_b32_e32 v65, v14
	v_pk_mul_f32 v[62:63], v[64:65], v[62:63]
	v_rcp_f32_e32 v61, v61
	s_nop 0
	v_mul_f32_e32 v61, v21, v61
	v_and_b32_e32 v8, 0xffff0000, v8
	v_mul_f32_e32 v14, 0xbfb8aa3b, v29
	v_exp_f32_e32 v57, v14
	v_rcp_f32_e32 v60, v60
	s_nop 0
	v_mul_f32_e32 v60, v25, v60
	v_mov_b32_e32 v14, v13
	v_pk_mul_f32 v[8:9], v[14:15], v[8:9]
	v_pk_add_f32 v[56:57], v[56:57], 1.0 op_sel_hi:[1,0]
	v_pk_mul_f32 v[60:61], v[60:61], v[62:63]
	v_lshlrev_b32_e32 v63, 16, v11
	v_lshlrev_b32_e32 v62, 16, v10
	v_and_b32_e32 v11, 0xffff0000, v11
	v_rcp_f32_e32 v13, v57
	s_nop 0
	v_mul_f32_e32 v13, v29, v13
	v_rcp_f32_e32 v12, v56
	s_nop 0
	v_mul_f32_e32 v12, v35, v12
	v_pk_mul_f32 v[8:9], v[12:13], v[8:9]
	v_lshlrev_b32_e32 v21, 16, v59
	v_lshlrev_b32_e32 v25, 16, v58
	v_cvt_pk_bf16_f32 v9, v61, v9
	v_cvt_pk_bf16_f32 v8, v60, v8
	v_mul_f32_e32 v12, 0xbfb8aa3b, v25
	v_mul_f32_e32 v13, 0xbfb8aa3b, v21
	v_exp_f32_e32 v12, v12
	v_exp_f32_e32 v13, v13
	v_and_b32_e32 v35, 0xffff0000, v58
	v_mul_f32_e32 v14, 0xbfb8aa3b, v35
	v_and_b32_e32 v29, 0xffff0000, v59
	v_exp_f32_e32 v60, v14
	v_pk_add_f32 v[64:65], v[12:13], 1.0 op_sel_hi:[1,0]
	global_load_dwordx4 v[12:15], v[22:23], off
	global_load_dwordx4 v[56:59], v[22:23], off offset:2048
	s_waitcnt lgkmcnt(0)
	v_mov_b32_e32 v22, v16
	v_mov_b32_e32 v23, v18
	v_pk_mul_f32 v[22:23], v[22:23], v[62:63]
	v_rcp_f32_e32 v63, v65
	s_nop 0
	v_mul_f32_e32 v63, v21, v63
	v_and_b32_e32 v10, 0xffff0000, v10
	v_mul_f32_e32 v18, 0xbfb8aa3b, v29
	v_exp_f32_e32 v61, v18
	v_rcp_f32_e32 v62, v64
	s_nop 0
	v_mul_f32_e32 v62, v25, v62
	v_mov_b32_e32 v18, v17
	v_pk_mul_f32 v[10:11], v[18:19], v[10:11]
	v_pk_add_f32 v[60:61], v[60:61], 1.0 op_sel_hi:[1,0]
	v_pk_mul_f32 v[22:23], v[62:63], v[22:23]
	s_waitcnt vmcnt(1)
; __device__ __forceinline__ unsigned pack2(float a, float b) { return (unsigned)f2bf(a) | ((unsigned)f2bf(b) << 16); }
; __device__ __forceinline__ float bflo(unsigned w) { return __uint_as_float(w << 16); }
; __device__ __forceinline__ float bfhi(unsigned w) { return __uint_as_float(w & 0xffff0000u); }
; __device__ __forceinline__ float silu_f(float g) { return g / (1.f + __expf(-g)); }
; __device__ void gmlp_item(const Params& p, int layer, int b, int n, int g, char* smem) {
;     ...
;     uint4 uu[8], gt[8];
; #pragma unroll
;     for (int i = 0; i < 8; ++i) {
;       int q = tid + 256 * i, t = q >> 4, c = (q & 15) * 8;
;       uu[i] = *reinterpret_cast<const uint4*>(P + (t0 + t) * NP + g * 128 + c);
;       gt[i] = *reinterpret_cast<const uint4*>(P + (t0 + t) * NP + 1024 + g * 128 + c);
;     }
; #pragma unroll
;     for (int i = 0; i < 8; ++i) {
;       int q = tid + 256 * i, t = q >> 4, c = (q & 15) * 8;
;       float4 m0 = *reinterpret_cast<const float4*>(Tf + t * 132 + c);
;       float4 m1 = *reinterpret_cast<const float4*>(Tf + t * 132 + c + 4);
;       float mm[8] = {m0.x, m0.y, m0.z, m0.w, m1.x, m1.y, m1.z, m1.w};
;       unsigned uw[4] = {uu[i].x, uu[i].y, uu[i].z, uu[i].w};
;       unsigned gw[4] = {gt[i].x, gt[i].y, gt[i].z, gt[i].w};
;       unsigned ow[4];
; #pragma unroll
;       for (int e = 0; e < 4; ++e) {
;         float y0 = bflo(uw[e]) * mm[2 * e] * silu_f(bflo(gw[e]));
;         float y1 = bfhi(uw[e]) * mm[2 * e + 1] * silu_f(bfhi(gw[e]));
;         ow[e] = pack2(y0, y1);
;       }
;       *reinterpret_cast<uint4*>(Y + (t0 + t) * YW + g * 128 + c) = make_uint4(ow[0], ow[1], ow[2], ow[3]);
;     }
	v_lshlrev_b32_e32 v63, 16, v13
	v_rcp_f32_e32 v17, v61
	s_nop 0
	v_mul_f32_e32 v17, v29, v17
	v_rcp_f32_e32 v16, v60
	s_nop 0
	v_mul_f32_e32 v16, v35, v16
	v_pk_mul_f32 v[10:11], v[16:17], v[10:11]
	s_waitcnt vmcnt(0)
	v_lshlrev_b32_e32 v29, 16, v56
	v_cvt_pk_bf16_f32 v11, v23, v11
	v_mul_f32_e32 v16, 0xbfb8aa3b, v29
	v_and_b32_e32 v55, 0xffff0000, v56
	v_lshlrev_b32_e32 v25, 16, v57
	v_exp_f32_e32 v60, v16
	v_mul_f32_e32 v16, 0xbfb8aa3b, v55
	v_exp_f32_e32 v56, v16
	v_mul_f32_e32 v16, 0xbfb8aa3b, v25
	v_exp_f32_e32 v61, v16
	s_nop 0
	v_pk_add_f32 v[60:61], v[60:61], 1.0 op_sel_hi:[1,0]
	v_and_b32_e32 v35, 0xffff0000, v57
	v_cvt_pk_bf16_f32 v10, v22, v10
	ds_read_b128 v[16:19], v20
	ds_read_b128 v[20:23], v20 offset:16
	v_lshlrev_b32_e32 v62, 16, v12
	v_and_b32_e32 v13, 0xffff0000, v13
	s_waitcnt lgkmcnt(1)
	v_mov_b32_e32 v64, v16
	v_mov_b32_e32 v65, v18
	v_pk_mul_f32 v[62:63], v[64:65], v[62:63]
	v_rcp_f32_e32 v61, v61
	s_nop 0
	v_mul_f32_e32 v61, v25, v61
	v_and_b32_e32 v12, 0xffff0000, v12
	v_mul_f32_e32 v18, 0xbfb8aa3b, v35
	v_exp_f32_e32 v57, v18
	v_rcp_f32_e32 v60, v60
	s_nop 0
	v_mul_f32_e32 v60, v29, v60
	v_mov_b32_e32 v18, v17
	v_pk_mul_f32 v[12:13], v[18:19], v[12:13]
	v_pk_add_f32 v[56:57], v[56:57], 1.0 op_sel_hi:[1,0]
	v_pk_mul_f32 v[60:61], v[60:61], v[62:63]
	v_lshlrev_b32_e32 v63, 16, v15
	v_lshlrev_b32_e32 v62, 16, v14
	v_and_b32_e32 v15, 0xffff0000, v15
	v_rcp_f32_e32 v17, v57
	s_nop 0
	v_mul_f32_e32 v17, v35, v17
	v_rcp_f32_e32 v16, v56
	s_nop 0
	v_mul_f32_e32 v16, v55, v16
	v_pk_mul_f32 v[12:13], v[16:17], v[12:13]
	v_lshlrev_b32_e32 v25, 16, v59
	v_lshlrev_b32_e32 v29, 16, v58
	v_cvt_pk_bf16_f32 v13, v61, v13
	v_cvt_pk_bf16_f32 v12, v60, v12
	v_mul_f32_e32 v16, 0xbfb8aa3b, v29
	v_mul_f32_e32 v17, 0xbfb8aa3b, v25
	v_exp_f32_e32 v16, v16
	v_exp_f32_e32 v17, v17
	v_and_b32_e32 v55, 0xffff0000, v58
	v_mul_f32_e32 v18, 0xbfb8aa3b, v55
	v_and_b32_e32 v35, 0xffff0000, v59
	v_exp_f32_e32 v60, v18
	v_pk_add_f32 v[64:65], v[16:17], 1.0 op_sel_hi:[1,0]
	global_load_dwordx4 v[16:19], v[26:27], off
	global_load_dwordx4 v[56:59], v[26:27], off offset:2048
	s_waitcnt lgkmcnt(0)
	v_mov_b32_e32 v26, v20
	v_mov_b32_e32 v27, v22
	v_pk_mul_f32 v[26:27], v[26:27], v[62:63]
	v_rcp_f32_e32 v63, v65
	s_nop 0
	v_mul_f32_e32 v63, v25, v63
	v_and_b32_e32 v14, 0xffff0000, v14
	v_mul_f32_e32 v22, 0xbfb8aa3b, v35
	v_exp_f32_e32 v61, v22
	v_rcp_f32_e32 v62, v64
	s_nop 0
	v_mul_f32_e32 v62, v29, v62
	v_mov_b32_e32 v22, v21
	v_pk_mul_f32 v[14:15], v[22:23], v[14:15]
	v_pk_add_f32 v[60:61], v[60:61], 1.0 op_sel_hi:[1,0]
	v_pk_mul_f32 v[26:27], v[62:63], v[26:27]
	s_waitcnt vmcnt(1)
	v_lshlrev_b32_e32 v63, 16, v17
	v_rcp_f32_e32 v21, v61
	s_nop 0
	v_mul_f32_e32 v21, v35, v21
	v_rcp_f32_e32 v20, v60
	s_nop 0
	v_mul_f32_e32 v20, v55, v20
	v_pk_mul_f32 v[14:15], v[20:21], v[14:15]
	s_waitcnt vmcnt(0)
	v_lshlrev_b32_e32 v35, 16, v56
	v_cvt_pk_bf16_f32 v15, v27, v15
	v_mul_f32_e32 v20, 0xbfb8aa3b, v35
	v_and_b32_e32 v66, 0xffff0000, v56
	v_lshlrev_b32_e32 v29, 16, v57
	v_exp_f32_e32 v60, v20
	v_mul_f32_e32 v20, 0xbfb8aa3b, v66
	v_exp_f32_e32 v56, v20
	v_mul_f32_e32 v20, 0xbfb8aa3b, v29
	v_exp_f32_e32 v61, v20
	s_nop 0
	v_pk_add_f32 v[60:61], v[60:61], 1.0 op_sel_hi:[1,0]
	v_and_b32_e32 v55, 0xffff0000, v57
	v_cvt_pk_bf16_f32 v14, v26, v14
	ds_read_b128 v[20:23], v24
	ds_read_b128 v[24:27], v24 offset:16
	v_lshlrev_b32_e32 v62, 16, v16
	v_and_b32_e32 v17, 0xffff0000, v17
	s_waitcnt lgkmcnt(1)
	v_mov_b32_e32 v64, v20
	v_mov_b32_e32 v65, v22
	v_pk_mul_f32 v[62:63], v[64:65], v[62:63]
	v_rcp_f32_e32 v61, v61
	s_nop 0
	v_mul_f32_e32 v61, v29, v61
	v_and_b32_e32 v16, 0xffff0000, v16
	v_mul_f32_e32 v22, 0xbfb8aa3b, v55
	v_exp_f32_e32 v57, v22
	v_rcp_f32_e32 v60, v60
	s_nop 0
	v_mul_f32_e32 v60, v35, v60
	v_mov_b32_e32 v22, v21
	v_pk_mul_f32 v[16:17], v[22:23], v[16:17]
	v_pk_add_f32 v[56:57], v[56:57], 1.0 op_sel_hi:[1,0]
	v_pk_mul_f32 v[60:61], v[60:61], v[62:63]
	v_lshlrev_b32_e32 v63, 16, v19
	v_lshlrev_b32_e32 v62, 16, v18
	v_and_b32_e32 v19, 0xffff0000, v19
	v_rcp_f32_e32 v21, v57
	s_nop 0
	v_mul_f32_e32 v21, v55, v21
	v_rcp_f32_e32 v20, v56
	s_nop 0
	v_mul_f32_e32 v20, v66, v20
	v_pk_mul_f32 v[16:17], v[20:21], v[16:17]
	v_lshlrev_b32_e32 v29, 16, v59
	v_lshlrev_b32_e32 v35, 16, v58
	v_cvt_pk_bf16_f32 v17, v61, v17
	v_cvt_pk_bf16_f32 v16, v60, v16
	v_mul_f32_e32 v20, 0xbfb8aa3b, v35
	v_mul_f32_e32 v21, 0xbfb8aa3b, v29
	v_exp_f32_e32 v20, v20
	v_exp_f32_e32 v21, v21
	v_and_b32_e32 v66, 0xffff0000, v58
	v_mul_f32_e32 v22, 0xbfb8aa3b, v66
	v_and_b32_e32 v55, 0xffff0000, v59
	v_exp_f32_e32 v60, v22
	v_pk_add_f32 v[64:65], v[20:21], 1.0 op_sel_hi:[1,0]
	global_load_dwordx4 v[20:23], v[30:31], off
	global_load_dwordx4 v[56:59], v[30:31], off offset:2048
	s_waitcnt lgkmcnt(0)
	v_mov_b32_e32 v30, v24
	v_mov_b32_e32 v31, v26
	v_pk_mul_f32 v[30:31], v[30:31], v[62:63]
	v_rcp_f32_e32 v63, v65
	s_nop 0
	v_mul_f32_e32 v63, v29, v63
	v_and_b32_e32 v18, 0xffff0000, v18
	v_mul_f32_e32 v26, 0xbfb8aa3b, v55
	v_exp_f32_e32 v61, v26
	v_rcp_f32_e32 v62, v64
	s_nop 0
	v_mul_f32_e32 v62, v35, v62
	v_mov_b32_e32 v26, v25
	v_pk_mul_f32 v[18:19], v[26:27], v[18:19]
	v_pk_add_f32 v[60:61], v[60:61], 1.0 op_sel_hi:[1,0]
	v_pk_mul_f32 v[30:31], v[62:63], v[30:31]
	s_waitcnt vmcnt(1)
	v_lshlrev_b32_e32 v63, 16, v21
	v_rcp_f32_e32 v25, v61
	s_nop 0
	v_mul_f32_e32 v25, v55, v25
	v_rcp_f32_e32 v24, v60
	s_nop 0
	v_mul_f32_e32 v24, v66, v24
	v_pk_mul_f32 v[18:19], v[24:25], v[18:19]
	s_waitcnt vmcnt(0)
; __device__ __forceinline__ unsigned pack2(float a, float b) { return (unsigned)f2bf(a) | ((unsigned)f2bf(b) << 16); }
; __device__ __forceinline__ float bflo(unsigned w) { return __uint_as_float(w << 16); }
; __device__ __forceinline__ float bfhi(unsigned w) { return __uint_as_float(w & 0xffff0000u); }
; __device__ __forceinline__ float silu_f(float g) { return g / (1.f + __expf(-g)); }
; __device__ void gmlp_item(const Params& p, int layer, int b, int n, int g, char* smem) {
;     ...
;     uint4 uu[8], gt[8];
; #pragma unroll
;     for (int i = 0; i < 8; ++i) {
;       int q = tid + 256 * i, t = q >> 4, c = (q & 15) * 8;
;       uu[i] = *reinterpret_cast<const uint4*>(P + (t0 + t) * NP + g * 128 + c);
;       gt[i] = *reinterpret_cast<const uint4*>(P + (t0 + t) * NP + 1024 + g * 128 + c);
;     }
; #pragma unroll
;     for (int i = 0; i < 8; ++i) {
;       int q = tid + 256 * i, t = q >> 4, c = (q & 15) * 8;
;       float4 m0 = *reinterpret_cast<const float4*>(Tf + t * 132 + c);
;       float4 m1 = *reinterpret_cast<const float4*>(Tf + t * 132 + c + 4);
;       float mm[8] = {m0.x, m0.y, m0.z, m0.w, m1.x, m1.y, m1.z, m1.w};
;       unsigned uw[4] = {uu[i].x, uu[i].y, uu[i].z, uu[i].w};
;       unsigned gw[4] = {gt[i].x, gt[i].y, gt[i].z, gt[i].w};
;       unsigned ow[4];
; #pragma unroll
;       for (int e = 0; e < 4; ++e) {
;         float y0 = bflo(uw[e]) * mm[2 * e] * silu_f(bflo(gw[e]));
;         float y1 = bfhi(uw[e]) * mm[2 * e + 1] * silu_f(bfhi(gw[e]));
;         ow[e] = pack2(y0, y1);
;       }
;       *reinterpret_cast<uint4*>(Y + (t0 + t) * YW + g * 128 + c) = make_uint4(ow[0], ow[1], ow[2], ow[3]);
;     }
	v_lshlrev_b32_e32 v55, 16, v56
	v_cvt_pk_bf16_f32 v19, v31, v19
	v_mul_f32_e32 v24, 0xbfb8aa3b, v55
	v_and_b32_e32 v67, 0xffff0000, v56
	v_lshlrev_b32_e32 v35, 16, v57
	v_exp_f32_e32 v60, v24
	v_mul_f32_e32 v24, 0xbfb8aa3b, v67
	v_exp_f32_e32 v56, v24
	v_mul_f32_e32 v24, 0xbfb8aa3b, v35
	v_exp_f32_e32 v61, v24
	s_nop 0
	v_pk_add_f32 v[60:61], v[60:61], 1.0 op_sel_hi:[1,0]
	v_and_b32_e32 v66, 0xffff0000, v57
	v_cvt_pk_bf16_f32 v18, v30, v18
	ds_read_b128 v[24:27], v28
	ds_read_b128 v[28:31], v28 offset:16
	v_lshlrev_b32_e32 v62, 16, v20
	v_and_b32_e32 v21, 0xffff0000, v21
	s_waitcnt lgkmcnt(1)
	v_mov_b32_e32 v64, v24
	v_mov_b32_e32 v65, v26
	v_pk_mul_f32 v[62:63], v[64:65], v[62:63]
	v_rcp_f32_e32 v61, v61
	s_nop 0
	v_mul_f32_e32 v61, v35, v61
	v_and_b32_e32 v20, 0xffff0000, v20
	v_mul_f32_e32 v26, 0xbfb8aa3b, v66
	v_exp_f32_e32 v57, v26
	v_rcp_f32_e32 v60, v60
	s_nop 0
	v_mul_f32_e32 v60, v55, v60
	v_mov_b32_e32 v26, v25
	v_pk_mul_f32 v[20:21], v[26:27], v[20:21]
	v_pk_add_f32 v[56:57], v[56:57], 1.0 op_sel_hi:[1,0]
	v_pk_mul_f32 v[60:61], v[60:61], v[62:63]
	v_lshlrev_b32_e32 v63, 16, v23
	v_lshlrev_b32_e32 v62, 16, v22
	v_and_b32_e32 v23, 0xffff0000, v23
	v_rcp_f32_e32 v25, v57
	s_nop 0
	v_mul_f32_e32 v25, v66, v25
	v_rcp_f32_e32 v24, v56
	s_nop 0
	v_mul_f32_e32 v24, v67, v24
	v_pk_mul_f32 v[20:21], v[24:25], v[20:21]
	v_lshlrev_b32_e32 v35, 16, v59
	v_lshlrev_b32_e32 v55, 16, v58
	v_cvt_pk_bf16_f32 v21, v61, v21
	v_cvt_pk_bf16_f32 v20, v60, v20
	v_mul_f32_e32 v24, 0xbfb8aa3b, v55
	v_mul_f32_e32 v25, 0xbfb8aa3b, v35
	v_exp_f32_e32 v24, v24
	v_exp_f32_e32 v25, v25
	v_and_b32_e32 v67, 0xffff0000, v58
	v_mul_f32_e32 v26, 0xbfb8aa3b, v67
	v_and_b32_e32 v66, 0xffff0000, v59
	v_exp_f32_e32 v60, v26
	v_pk_add_f32 v[64:65], v[24:25], 1.0 op_sel_hi:[1,0]
	global_load_dwordx4 v[24:27], v[32:33], off
	global_load_dwordx4 v[56:59], v[32:33], off offset:2048
	s_waitcnt lgkmcnt(0)
	v_mov_b32_e32 v32, v28
	v_mov_b32_e32 v33, v30
	v_pk_mul_f32 v[32:33], v[32:33], v[62:63]
	v_rcp_f32_e32 v63, v65
	s_nop 0
	v_mul_f32_e32 v63, v35, v63
	v_and_b32_e32 v22, 0xffff0000, v22
	v_mul_f32_e32 v30, 0xbfb8aa3b, v66
	v_exp_f32_e32 v61, v30
	v_rcp_f32_e32 v62, v64
	s_nop 0
	v_mul_f32_e32 v62, v55, v62
	v_mov_b32_e32 v30, v29
	v_pk_mul_f32 v[22:23], v[30:31], v[22:23]
	v_pk_add_f32 v[60:61], v[60:61], 1.0 op_sel_hi:[1,0]
	v_pk_mul_f32 v[32:33], v[62:63], v[32:33]
	s_waitcnt vmcnt(1)
	v_lshlrev_b32_e32 v63, 16, v25
	v_rcp_f32_e32 v29, v61
	s_nop 0
	v_mul_f32_e32 v29, v66, v29
	v_rcp_f32_e32 v28, v60
	s_nop 0
	v_mul_f32_e32 v28, v67, v28
	v_pk_mul_f32 v[22:23], v[28:29], v[22:23]
	s_waitcnt vmcnt(0)
	v_lshlrev_b32_e32 v66, 16, v56
	v_cvt_pk_bf16_f32 v23, v33, v23
	v_mul_f32_e32 v28, 0xbfb8aa3b, v66
	v_and_b32_e32 v68, 0xffff0000, v56
	v_lshlrev_b32_e32 v55, 16, v57
	v_exp_f32_e32 v60, v28
	v_mul_f32_e32 v28, 0xbfb8aa3b, v68
	v_exp_f32_e32 v56, v28
	v_mul_f32_e32 v28, 0xbfb8aa3b, v55
	v_exp_f32_e32 v61, v28
	s_nop 0
	v_pk_add_f32 v[60:61], v[60:61], 1.0 op_sel_hi:[1,0]
	v_and_b32_e32 v67, 0xffff0000, v57
	v_cvt_pk_bf16_f32 v22, v32, v22
	ds_read_b128 v[28:31], v34
	ds_read_b128 v[32:35], v34 offset:16
	v_lshlrev_b32_e32 v62, 16, v24
	v_and_b32_e32 v25, 0xffff0000, v25
	s_waitcnt lgkmcnt(1)
	v_mov_b32_e32 v64, v28
	v_mov_b32_e32 v65, v30
	v_pk_mul_f32 v[62:63], v[64:65], v[62:63]
	v_rcp_f32_e32 v61, v61
	s_nop 0
	v_mul_f32_e32 v61, v55, v61
	v_and_b32_e32 v24, 0xffff0000, v24
	v_mul_f32_e32 v30, 0xbfb8aa3b, v67
	v_exp_f32_e32 v57, v30
	v_rcp_f32_e32 v60, v60
	s_nop 0
	v_mul_f32_e32 v60, v66, v60
	v_mov_b32_e32 v30, v29
	v_pk_mul_f32 v[24:25], v[30:31], v[24:25]
	v_pk_add_f32 v[56:57], v[56:57], 1.0 op_sel_hi:[1,0]
	v_pk_mul_f32 v[60:61], v[60:61], v[62:63]
	v_lshlrev_b32_e32 v66, 16, v58
	v_lshlrev_b32_e32 v63, 16, v27
	v_and_b32_e32 v27, 0xffff0000, v27
	v_rcp_f32_e32 v29, v57
	s_nop 0
	v_mul_f32_e32 v29, v67, v29
	v_rcp_f32_e32 v28, v56
	s_nop 0
	v_mul_f32_e32 v28, v68, v28
	v_pk_mul_f32 v[24:25], v[28:29], v[24:25]
	v_lshlrev_b32_e32 v55, 16, v59
	v_cvt_pk_bf16_f32 v25, v61, v25
	v_cvt_pk_bf16_f32 v24, v60, v24
	v_mul_f32_e32 v28, 0xbfb8aa3b, v66
	v_mul_f32_e32 v29, 0xbfb8aa3b, v55
	v_exp_f32_e32 v28, v28
	v_exp_f32_e32 v29, v29
	v_and_b32_e32 v68, 0xffff0000, v58
	v_mul_f32_e32 v30, 0xbfb8aa3b, v68
	v_and_b32_e32 v67, 0xffff0000, v59
	v_exp_f32_e32 v60, v30
	v_pk_add_f32 v[64:65], v[28:29], 1.0 op_sel_hi:[1,0]
	global_load_dwordx4 v[28:31], v[52:53], off
	global_load_dwordx4 v[56:59], v[52:53], off offset:2048
	s_waitcnt lgkmcnt(0)
; __device__ __forceinline__ unsigned pack2(float a, float b) { return (unsigned)f2bf(a) | ((unsigned)f2bf(b) << 16); }
; __device__ __forceinline__ float bflo(unsigned w) { return __uint_as_float(w << 16); }
; __device__ __forceinline__ float bfhi(unsigned w) { return __uint_as_float(w & 0xffff0000u); }
; __device__ __forceinline__ float silu_f(float g) { return g / (1.f + __expf(-g)); }
; __device__ void gmlp_item(const Params& p, int layer, int b, int n, int g, char* smem) {
;     ...
;     uint4 uu[8], gt[8];
; #pragma unroll
;     for (int i = 0; i < 8; ++i) {
;       int q = tid + 256 * i, t = q >> 4, c = (q & 15) * 8;
;       uu[i] = *reinterpret_cast<const uint4*>(P + (t0 + t) * NP + g * 128 + c);
;       gt[i] = *reinterpret_cast<const uint4*>(P + (t0 + t) * NP + 1024 + g * 128 + c);
;     }
; #pragma unroll
;     for (int i = 0; i < 8; ++i) {
;       int q = tid + 256 * i, t = q >> 4, c = (q & 15) * 8;
;       float4 m0 = *reinterpret_cast<const float4*>(Tf + t * 132 + c);
;       float4 m1 = *reinterpret_cast<const float4*>(Tf + t * 132 + c + 4);
;       float mm[8] = {m0.x, m0.y, m0.z, m0.w, m1.x, m1.y, m1.z, m1.w};
;       unsigned uw[4] = {uu[i].x, uu[i].y, uu[i].z, uu[i].w};
;       unsigned gw[4] = {gt[i].x, gt[i].y, gt[i].z, gt[i].w};
;       unsigned ow[4];
; #pragma unroll
;       for (int e = 0; e < 4; ++e) {
;         float y0 = bflo(uw[e]) * mm[2 * e] * silu_f(bflo(gw[e]));
;         float y1 = bfhi(uw[e]) * mm[2 * e + 1] * silu_f(bfhi(gw[e]));
;         ow[e] = pack2(y0, y1);
;       }
;       *reinterpret_cast<uint4*>(Y + (t0 + t) * YW + g * 128 + c) = make_uint4(ow[0], ow[1], ow[2], ow[3]);
;     }
	v_mov_b32_e32 v52, v32
	v_lshlrev_b32_e32 v62, 16, v26
	v_mov_b32_e32 v53, v34
	v_pk_mul_f32 v[52:53], v[52:53], v[62:63]
	v_rcp_f32_e32 v63, v65
	s_nop 0
	v_mul_f32_e32 v63, v55, v63
	v_and_b32_e32 v26, 0xffff0000, v26
	v_mul_f32_e32 v34, 0xbfb8aa3b, v67
	v_exp_f32_e32 v61, v34
	v_rcp_f32_e32 v62, v64
	s_nop 0
	v_mul_f32_e32 v62, v66, v62
	v_mov_b32_e32 v34, v33
	v_pk_mul_f32 v[26:27], v[34:35], v[26:27]
	v_pk_add_f32 v[60:61], v[60:61], 1.0 op_sel_hi:[1,0]
	v_pk_mul_f32 v[52:53], v[62:63], v[52:53]
	s_waitcnt vmcnt(1)
	v_lshlrev_b32_e32 v63, 16, v29
	v_rcp_f32_e32 v33, v61
	s_nop 0
	v_mul_f32_e32 v33, v67, v33
	v_rcp_f32_e32 v32, v60
	s_nop 0
	v_mul_f32_e32 v32, v68, v32
	v_pk_mul_f32 v[26:27], v[32:33], v[26:27]
	s_waitcnt vmcnt(0)
	v_lshlrev_b32_e32 v67, 16, v56
	v_cvt_pk_bf16_f32 v27, v53, v27
	v_mul_f32_e32 v32, 0xbfb8aa3b, v67
	v_and_b32_e32 v69, 0xffff0000, v56
	v_lshlrev_b32_e32 v66, 16, v57
	v_exp_f32_e32 v60, v32
	v_mul_f32_e32 v32, 0xbfb8aa3b, v69
	v_exp_f32_e32 v56, v32
	v_mul_f32_e32 v32, 0xbfb8aa3b, v66
	v_exp_f32_e32 v61, v32
	s_nop 0
	v_pk_add_f32 v[60:61], v[60:61], 1.0 op_sel_hi:[1,0]
	v_and_b32_e32 v68, 0xffff0000, v57
	v_cvt_pk_bf16_f32 v26, v52, v26
	ds_read_b128 v[32:35], v54
	ds_read_b128 v[52:55], v54 offset:16
	v_lshlrev_b32_e32 v62, 16, v28
	v_and_b32_e32 v29, 0xffff0000, v29
	s_waitcnt lgkmcnt(1)
	v_mov_b32_e32 v64, v32
	v_mov_b32_e32 v65, v34
	v_pk_mul_f32 v[62:63], v[64:65], v[62:63]
	v_rcp_f32_e32 v61, v61
	s_nop 0
	v_mul_f32_e32 v61, v66, v61
	v_and_b32_e32 v28, 0xffff0000, v28
	v_mul_f32_e32 v34, 0xbfb8aa3b, v68
	v_exp_f32_e32 v57, v34
	v_rcp_f32_e32 v60, v60
	s_nop 0
	v_mul_f32_e32 v60, v67, v60
	v_pk_mul_f32 v[60:61], v[60:61], v[62:63]
	v_mov_b32_e32 v34, v33
	v_pk_add_f32 v[56:57], v[56:57], 1.0 op_sel_hi:[1,0]
	v_pk_mul_f32 v[28:29], v[34:35], v[28:29]
	s_nop 0
	v_rcp_f32_e32 v33, v57
	s_nop 0
	v_mul_f32_e32 v33, v68, v33
	v_rcp_f32_e32 v32, v56
	s_nop 0
	v_mul_f32_e32 v32, v69, v32
	v_pk_mul_f32 v[28:29], v[32:33], v[28:29]
	v_cvt_pk_bf16_f32 v28, 0, v28
	v_cvt_pk_bf16_f32 v33, 0, v60
	v_and_b32_e32 v28, 0xffff0000, v28
	v_lshlrev_b32_e32 v35, 16, v59
	v_lshlrev_b32_e32 v60, 16, v58
	v_cvt_pk_bf16_f32 v29, v61, v29
	v_or_b32_sdwa v28, v28, v33 dst_sel:DWORD dst_unused:UNUSED_PAD src0_sel:DWORD src1_sel:WORD_1
	v_mul_f32_e32 v32, 0xbfb8aa3b, v60
	v_mul_f32_e32 v33, 0xbfb8aa3b, v35
	v_exp_f32_e32 v32, v32
	v_exp_f32_e32 v33, v33
	v_and_b32_e32 v62, 0xffff0000, v58
	s_waitcnt lgkmcnt(0)
	v_mov_b32_e32 v58, v52
	v_and_b32_e32 v61, 0xffff0000, v59
	v_pk_add_f32 v[32:33], v[32:33], 1.0 op_sel_hi:[1,0]
	v_lshlrev_b32_e32 v57, 16, v31
	v_lshlrev_b32_e32 v56, 16, v30
	v_mov_b32_e32 v59, v54
	v_pk_mul_f32 v[56:57], v[58:59], v[56:57]
	v_rcp_f32_e32 v33, v33
	s_nop 0
	v_mul_f32_e32 v33, v35, v33
	v_mul_f32_e32 v34, 0xbfb8aa3b, v62
	v_mul_f32_e32 v35, 0xbfb8aa3b, v61
	v_exp_f32_e32 v34, v34
	v_exp_f32_e32 v35, v35
	v_rcp_f32_e32 v32, v32
	s_nop 0
	v_mul_f32_e32 v32, v60, v32
	v_pk_mul_f32 v[32:33], v[32:33], v[56:57]
	v_mov_b32_e32 v54, v53
	v_pk_add_f32 v[34:35], v[34:35], 1.0 op_sel_hi:[1,0]
	v_and_b32_e32 v31, 0xffff0000, v31
	v_and_b32_e32 v30, 0xffff0000, v30
	v_pk_mul_f32 v[30:31], v[54:55], v[30:31]
	v_rcp_f32_e32 v35, v35
	s_nop 0
	v_mul_f32_e32 v35, v61, v35
	s_mov_b64 s[6:7], 0
	v_rcp_f32_e32 v34, v34
	s_nop 0
	v_mul_f32_e32 v34, v62, v34
	v_pk_mul_f32 v[30:31], v[34:35], v[30:31]
	v_cvt_pk_bf16_f32 v31, v33, v31
	v_cvt_pk_bf16_f32 v30, v32, v30
	global_store_dwordx4 v[50:51], v[28:31], off
	global_store_dwordx4 v[48:49], v[24:27], off
	global_store_dwordx4 v[46:47], v[20:23], off
	global_store_dwordx4 v[44:45], v[16:19], off
	global_store_dwordx4 v[42:43], v[12:15], off
	global_store_dwordx4 v[40:41], v[8:11], off
	global_store_dwordx4 v[38:39], v[4:7], off
	global_store_dwordx4 v[36:37], v[0:3], off
	s_barrier

; __device__ __forceinline__ unsigned pack2(float a, float b) { return (unsigned)f2bf(a) | ((unsigned)f2bf(b) << 16); }
; template <int DH, int MODE>
; __device__ void attn_item(const Params& p, int layer, int b, int blk, int head, char* smem) {
;     ...
; #pragma unroll 2
;         for (int s8 = 0; s8 < 4; ++s8) {
;           float4 va = s4[2 * s8], vb = s4[2 * s8 + 1];
;           float e[8] = {va.x, va.y, va.z, va.w, vb.x, vb.y, vb.z, vb.w};
;           float pv[8];
; #pragma unroll
;           for (int k = 0; k < 8; ++k) {
;             int kj = kjb + s8 * 8 + k;
;             bool valid = (kj > row) && (kj <= row + 128);
;             float pe = valid ? __builtin_amdgcn_exp2f(e[k] - m_new) : 0.f;
;             pv[k] = pe;
;             psum += pe;
;           }
;           uint4 ov;
;           ov.x = pack2(pv[0], pv[1]); ov.y = pack2(pv[2], pv[3]);
;           ov.z = pack2(pv[4], pv[5]); ov.w = pack2(pv[6], pv[7]);
;           *reinterpret_cast<uint4*>(prow + s8 * 16) = ov;
;         }
;         psum += __shfl_xor(psum, 1);
;         l_run = l_run * alpha + psum;
;         m_run = m_new;
;         if (half == 0) alpha_s[row] = alpha;
.LBB0_1147:
	ds_read_b128 v[104:107], v102
	ds_read_b128 v[108:111], v102 offset:16
	v_add_u32_e32 v112, s83, v92
	v_add_u32_e32 v113, 2, v112
	v_cmp_gt_i32_e64 s[8:9], v112, v74
	s_waitcnt lgkmcnt(1)
	v_sub_f32_e32 v104, v104, v82
	v_exp_f32_e32 v104, v104
	v_sub_f32_e32 v106, v106, v82
	v_sub_f32_e32 v105, v105, v82
	v_exp_f32_e32 v106, v106
	v_exp_f32_e32 v105, v105
	v_sub_f32_e32 v107, v107, v82
	v_cmp_le_i32_e64 s[12:13], v112, v80
	v_exp_f32_e32 v107, v107
	v_cmp_gt_i32_e32 vcc, v113, v65
	v_cmp_le_i32_e64 s[10:11], v113, v69
	s_and_b64 s[8:9], s[8:9], s[12:13]
	v_add_u32_e32 v114, 3, v112
	s_and_b64 vcc, vcc, s[10:11]
	v_cndmask_b32_e64 v104, 0, v104, s[8:9]
	v_cmp_lt_i32_e64 s[8:9], v112, v80
	v_cmp_ge_i32_e64 s[12:13], v112, v74
	v_cndmask_b32_e32 v106, 0, v106, vcc
	v_cmp_lt_i32_e32 vcc, v74, v114
	v_cmp_ge_i32_e64 s[10:11], v80, v114
	s_and_b64 s[8:9], s[8:9], s[12:13]
	v_add_f32_e32 v103, v103, v104
	s_and_b64 vcc, vcc, s[10:11]
	v_cndmask_b32_e64 v105, 0, v105, s[8:9]
	v_cndmask_b32_e32 v107, 0, v107, vcc
	v_add_f32_e32 v103, v103, v105
	v_add_f32_e32 v103, v103, v106
	s_waitcnt lgkmcnt(0)
	v_sub_f32_e32 v108, v108, v82
	v_sub_f32_e32 v110, v110, v82
	v_add_f32_e32 v103, v103, v107
	v_cvt_pk_bf16_f32 v104, 0, v104
	v_exp_f32_e32 v108, v108
	v_exp_f32_e32 v110, v110
	v_cvt_pk_bf16_f32 v105, 0, v105
	v_sub_f32_e32 v109, v109, v82
	v_sub_f32_e32 v111, v111, v82
	v_and_b32_e32 v113, 0xffff0000, v105
	v_cvt_pk_bf16_f32 v105, v106, v107
	v_or_b32_e32 v106, 6, v112
	v_or_b32_e32 v107, 4, v112
	v_exp_f32_e32 v109, v109
	v_exp_f32_e32 v111, v111
	v_cmp_gt_i32_e32 vcc, v107, v74
	v_cmp_gt_i32_e64 s[8:9], v106, v65
	v_cmp_le_i32_e64 s[10:11], v107, v80
	v_cmp_le_i32_e64 s[12:13], v106, v69
	s_and_b64 s[8:9], s[8:9], s[12:13]
	s_and_b64 vcc, vcc, s[10:11]
	v_or_b32_e32 v106, 7, v112
	v_or_b32_e32 v107, 5, v112
	v_cndmask_b32_e32 v108, 0, v108, vcc
	v_cndmask_b32_e64 v110, 0, v110, s[8:9]
	v_cmp_gt_i32_e32 vcc, v107, v74
	v_cmp_gt_i32_e64 s[8:9], v106, v65
	v_cmp_le_i32_e64 s[10:11], v107, v80
	v_cmp_le_i32_e64 s[12:13], v106, v69
	s_and_b64 s[8:9], s[8:9], s[12:13]
	s_and_b64 vcc, vcc, s[10:11]
	v_cndmask_b32_e32 v109, 0, v109, vcc
	v_cndmask_b32_e64 v111, 0, v111, s[8:9]
	v_or_b32_sdwa v104, v113, v104 dst_sel:DWORD dst_unused:UNUSED_PAD src0_sel:DWORD src1_sel:WORD_1
	v_add_f32_e32 v103, v103, v108
	v_cvt_pk_bf16_f32 v107, v110, v111
	v_cvt_pk_bf16_f32 v106, v108, v109
	v_add_f32_e32 v103, v103, v109
	v_add_f32_e32 v103, v103, v110
	ds_write_b128 v101, v[104:107]
	v_add_f32_e32 v103, v103, v111
	ds_read_b128 v[104:107], v102 offset:32
	ds_read_b128 v[108:111], v102 offset:48
	v_add_u32_e32 v113, 8, v112
	v_add_u32_e32 v114, 10, v112
	v_cmp_gt_i32_e64 s[8:9], v113, v74
	s_waitcnt lgkmcnt(1)
	v_sub_f32_e32 v104, v104, v82
	v_exp_f32_e32 v104, v104
	v_sub_f32_e32 v106, v106, v82
	v_sub_f32_e32 v105, v105, v82
	v_exp_f32_e32 v106, v106
	v_exp_f32_e32 v105, v105
	v_sub_f32_e32 v107, v107, v82
	v_cmp_le_i32_e64 s[12:13], v113, v80
	v_exp_f32_e32 v107, v107
	v_cmp_gt_i32_e32 vcc, v114, v65
	v_cmp_le_i32_e64 s[10:11], v114, v69
	s_and_b64 s[8:9], s[8:9], s[12:13]
	v_add_u32_e32 v112, 11, v112
	s_and_b64 vcc, vcc, s[10:11]
	v_cndmask_b32_e64 v104, 0, v104, s[8:9]
	v_cmp_lt_i32_e64 s[8:9], v113, v80
	v_cmp_ge_i32_e64 s[12:13], v113, v74
	v_cndmask_b32_e32 v106, 0, v106, vcc
	v_cmp_lt_i32_e32 vcc, v74, v112
	v_cmp_ge_i32_e64 s[10:11], v80, v112
	s_and_b64 s[8:9], s[8:9], s[12:13]
	v_add_f32_e32 v103, v103, v104
	s_and_b64 vcc, vcc, s[10:11]
	v_cndmask_b32_e64 v105, 0, v105, s[8:9]
	v_cndmask_b32_e32 v107, 0, v107, vcc
	v_add_f32_e32 v103, v103, v105
	v_add_f32_e32 v103, v103, v106
	s_waitcnt lgkmcnt(0)
	v_sub_f32_e32 v108, v108, v82
	v_sub_f32_e32 v110, v110, v82
	v_add_f32_e32 v103, v103, v107
	v_cvt_pk_bf16_f32 v104, 0, v104
	v_exp_f32_e32 v108, v108
	v_exp_f32_e32 v110, v110
	v_cvt_pk_bf16_f32 v105, 0, v105
	v_sub_f32_e32 v109, v109, v82
	v_sub_f32_e32 v111, v111, v82
	v_and_b32_e32 v112, 0xffff0000, v105
	v_cvt_pk_bf16_f32 v105, v106, v107
	v_or_b32_e32 v106, 6, v113
	v_or_b32_e32 v107, 4, v113
	v_exp_f32_e32 v109, v109
	v_exp_f32_e32 v111, v111
	v_cmp_gt_i32_e32 vcc, v107, v74
	v_cmp_gt_i32_e64 s[8:9], v106, v65
	v_cmp_le_i32_e64 s[10:11], v107, v80
	v_cmp_le_i32_e64 s[12:13], v106, v69
	s_and_b64 s[8:9], s[8:9], s[12:13]
	s_and_b64 vcc, vcc, s[10:11]
	v_or_b32_e32 v106, 7, v113
	v_or_b32_e32 v107, 5, v113
	v_cndmask_b32_e32 v108, 0, v108, vcc
	v_cndmask_b32_e64 v110, 0, v110, s[8:9]
	v_cmp_gt_i32_e32 vcc, v107, v74
	v_cmp_gt_i32_e64 s[8:9], v106, v65
	v_cmp_le_i32_e64 s[10:11], v107, v80
	v_cmp_le_i32_e64 s[12:13], v106, v69
	s_and_b64 s[8:9], s[8:9], s[12:13]
	s_and_b64 vcc, vcc, s[10:11]
	v_cndmask_b32_e32 v109, 0, v109, vcc
	v_cndmask_b32_e64 v111, 0, v111, s[8:9]
	v_or_b32_sdwa v104, v112, v104 dst_sel:DWORD dst_unused:UNUSED_PAD src0_sel:DWORD src1_sel:WORD_1
	v_add_f32_e32 v103, v103, v108
	v_add_f32_e32 v103, v103, v109
	v_cvt_pk_bf16_f32 v107, v110, v111
	v_cvt_pk_bf16_f32 v106, v108, v109
	v_add_f32_e32 v103, v103, v110
	s_add_i32 s83, s83, 16
	v_add_f32_e32 v103, v103, v111
	ds_write_b128 v101, v[104:107] offset:16
	v_add_u32_e32 v102, 64, v102
	v_add_u32_e32 v101, 32, v101
	s_cmp_eq_u32 s83, 32
	s_cbranch_scc0 .LBB0_1147
	v_sub_f32_e32 v101, v87, v82
	ds_bpermute_b32 v87, v83, v103
	v_exp_f32_e32 v83, v101
	s_and_saveexec_b64 s[8:9], s[6:7]
	ds_write_b32 v97, v83 offset:8192
	s_or_b64 exec, exec, s[8:9]
	s_waitcnt lgkmcnt(0)
	v_add_f32_e32 v101, v103, v87
	v_fmac_f32_e32 v101, v88, v83
	v_mov_b32_e32 v87, v82
	v_mov_b32_e32 v88, v101

; __device__ __forceinline__ unsigned pack2(float a, float b) { return (unsigned)f2bf(a) | ((unsigned)f2bf(b) << 16); }
; __device__ __forceinline__ float bflo(unsigned w) { return __uint_as_float(w << 16); }
; __device__ __forceinline__ float bfhi(unsigned w) { return __uint_as_float(w & 0xffff0000u); }
; __device__ __forceinline__ float silu_f(float g) { return g / (1.f + __expf(-g)); }
; template <int DH, int MODE>
; __device__ void attn_item(const Params& p, int layer, int b, int blk, int head, char* smem) {
;     ...
;   if (MODE == 0 && half == 0) linv_s[row] = 1.f / l_run;
;   __syncthreads();
;   {
;     constexpr int OST = DH + 4;
;     constexpr int CPR = DH / 8;
;     constexpr int NCH = 128 * CPR / 256;
;     float* Of = reinterpret_cast<float*>(smem);
;     uint4 gt[NCH];
; #pragma unroll
;     for (int i = 0; i < NCH; ++i) {
;       int q = tid + 256 * i, r = q / CPR, c = (q % CPR) * 8;
;       gt[i] = *reinterpret_cast<const uint4*>(P + (tq0 + r) * NP + gcol + c);
;     }
;     float lis[2][4];
; #pragma unroll
;     for (int m = 0; m < 2; ++m)
; #pragma unroll
;       for (int j = 0; j < 4; ++j) lis[m][j] = (MODE == 0) ? linv_s[wid * 32 + m * 16 + fq * 4 + j] : 1.f;
;     if (MODE == 0) __syncthreads();
; #pragma unroll
;     for (int m = 0; m < 2; ++m)
; #pragma unroll
;       for (int j = 0; j < 4; ++j) {
;         int r = wid * 32 + m * 16 + fq * 4 + j;
; #pragma unroll
;         for (int n = 0; n < NDT; ++n) Of[r * OST + n * 16 + fr] = o[m][n][j] * lis[m][j];
;       }
;     __syncthreads();
; #pragma unroll
;     for (int i = 0; i < NCH; ++i) {
;       int q = tid + 256 * i, r = q / CPR, c = (q % CPR) * 8;
;       float4 m0 = *reinterpret_cast<const float4*>(Of + r * OST + c);
;       float4 m1 = *reinterpret_cast<const float4*>(Of + r * OST + c + 4);
;       float mm[8] = {m0.x, m0.y, m0.z, m0.w, m1.x, m1.y, m1.z, m1.w};
;       unsigned gw[4] = {gt[i].x, gt[i].y, gt[i].z, gt[i].w};
;       unsigned ow[4];
; #pragma unroll
;       for (int e = 0; e < 4; ++e)
;         ow[e] = pack2(mm[2 * e] * silu_f(bflo(gw[e])), mm[2 * e + 1] * silu_f(bfhi(gw[e])));
.LBB0_1155:
	s_or_b64 exec, exec, s[8:9]
	v_lshl_add_u64 v[44:45], v[66:67], 0, s[16:17]
	v_mov_b64_e32 v[46:47], s[42:43]
	v_mad_u64_u32 v[32:33], s[8:9], v44, s39, v[46:47]
	v_mad_i32_i24 v33, v45, s39, v33
	v_lshl_add_u64 v[36:37], v[32:33], 0, v[70:71]
	v_add_u32_e32 v32, 0x100, v81
	v_ashrrev_i32_e32 v33, 31, v32
	v_lshrrev_b32_e32 v33, 29, v33
	v_add_u32_e32 v33, v32, v33
	v_ashrrev_i32_e32 v86, 3, v33
	v_and_b32_e32 v33, -8, v33
	v_sub_u32_e32 v85, v32, v33
	v_lshlrev_b32_e32 v32, 3, v85
	v_ashrrev_i32_e32 v33, 31, v32
	s_waitcnt vmcnt(2)
	v_add_u32_e32 v48, 0x200, v81
	v_lshlrev_b64 v[90:91], 1, v[32:33]
	v_ashrrev_i32_e32 v32, 31, v48
	v_lshrrev_b32_e32 v32, 29, v32
	v_add_u32_e32 v32, v48, v32
	v_ashrrev_i32_e32 v92, 3, v32
	v_and_b32_e32 v49, -8, v32
	v_add_u32_e32 v32, 0x300, v81
	v_ashrrev_i32_e32 v33, 31, v32
	v_lshrrev_b32_e32 v33, 29, v33
	v_ashrrev_i32_e32 v87, 31, v86
	v_add_u32_e32 v33, v32, v33
	v_lshl_add_u64 v[88:89], v[86:87], 0, s[16:17]
	v_ashrrev_i32_e32 v94, 3, v33
	v_and_b32_e32 v33, -8, v33
	v_mad_u64_u32 v[34:35], s[8:9], v88, s39, v[46:47]
	v_sub_u32_e32 v87, v32, v33
	v_ashrrev_i32_e32 v95, 31, v94
	v_mad_i32_i24 v35, v89, s39, v35
	v_lshlrev_b32_e32 v32, 3, v87
	v_lshl_add_u64 v[40:41], v[94:95], 0, s[16:17]
	v_lshl_add_u64 v[38:39], v[34:35], 0, v[90:91]
	v_mad_u64_u32 v[34:35], s[8:9], v40, s39, v[46:47]
	v_ashrrev_i32_e32 v33, 31, v32
	v_mad_i32_i24 v35, v41, s39, v35
	v_lshlrev_b64 v[42:43], 1, v[32:33]
	v_lshl_add_u64 v[32:33], v[34:35], 0, v[42:43]
	v_add_co_u32_e32 v32, vcc, s65, v32
	s_waitcnt lgkmcnt(0)
	s_nop 0
	v_addc_co_u32_e32 v33, vcc, 0, v33, vcc
	s_barrier
	global_load_dwordx4 v[32:35], v[32:33], off offset:512
	v_sub_u32_e32 v95, v48, v49
	v_ashrrev_i32_e32 v93, 31, v92
	v_lshlrev_b32_e32 v48, 3, v95
	v_lshl_add_u64 v[96:97], v[92:93], 0, s[16:17]
	v_mad_u64_u32 v[46:47], s[8:9], v96, s39, v[46:47]
	v_ashrrev_i32_e32 v49, 31, v48
	v_mad_i32_i24 v47, v97, s39, v47
	v_lshlrev_b64 v[98:99], 1, v[48:49]
	v_lshl_add_u64 v[100:101], v[46:47], 0, v[98:99]
	v_lshl_or_b32 v46, v75, 7, v128
	ds_read_b128 v[60:63], v46 offset:8704
	ds_read_b128 v[80:83], v46 offset:8768
	s_ashr_i32 s7, s10, 31
	s_add_u32 s6, s28, s10
	s_addc_u32 s7, s29, s7
	s_lshl_b32 s8, s76, 1
	s_add_u32 s6, s6, s8
	v_lshl_or_b32 v46, v84, 2, v64
	s_waitcnt lgkmcnt(0)
	v_mul_f32_e32 v69, v0, v80
	s_addc_u32 s7, s7, 0
	v_mul_lo_u32 v0, v66, s67
	v_mul_lo_u32 v46, v46, s67
	v_mul_f32_e32 v75, v1, v81
	v_lshl_add_u32 v66, v68, 2, v0
	v_mov_b64_e32 v[0:1], s[6:7]
	v_lshl_add_u32 v47, v73, 2, v46
	v_mul_f32_e32 v48, v16, v60
	v_mul_f32_e32 v49, v28, v60
	v_mul_f32_e32 v50, v24, v60
	v_mul_f32_e32 v51, v20, v60
	s_waitcnt vmcnt(1)
	v_mul_f32_e32 v52, v17, v61
	v_mul_f32_e32 v53, v29, v61
	v_mul_f32_e32 v54, v25, v61
	v_mul_f32_e32 v55, v21, v61
	v_mul_f32_e32 v56, v18, v62
	v_mul_f32_e32 v57, v30, v62
	v_mul_f32_e32 v58, v26, v62
	v_mul_f32_e32 v59, v22, v62
	v_mul_f32_e32 v60, v19, v63
	v_mul_f32_e32 v61, v31, v63
	v_mul_f32_e32 v62, v27, v63
	v_mul_f32_e32 v64, v23, v63
	v_mul_f32_e32 v63, v12, v80
	v_mul_f32_e32 v65, v8, v80
	v_mul_f32_e32 v67, v4, v80
	v_mul_f32_e32 v72, v13, v81
	v_mul_f32_e32 v73, v9, v81
	v_mul_f32_e32 v74, v5, v81
	v_mul_f32_e32 v76, v14, v82
	v_mul_f32_e32 v77, v10, v82
	v_mul_f32_e32 v78, v6, v82
	v_mul_f32_e32 v80, v2, v82
	v_mul_f32_e32 v79, v15, v83
	v_mul_f32_e32 v81, v11, v83
	v_mul_f32_e32 v82, v7, v83
	v_mul_f32_e32 v83, v3, v83
	v_mad_u64_u32 v[2:3], s[6:7], v44, s63, v[0:1]
	v_mad_i32_i24 v3, v45, s63, v3
	v_lshl_add_u64 v[12:13], v[2:3], 0, v[70:71]
	v_mul_lo_u32 v2, v86, s67
	v_lshl_add_u32 v46, v85, 5, v2
	v_mad_u64_u32 v[2:3], s[6:7], v88, s63, v[0:1]
	v_mad_i32_i24 v3, v89, s63, v3
	v_mad_u64_u32 v[4:5], s[6:7], v40, s63, v[0:1]
	v_lshl_add_u64 v[10:11], v[2:3], 0, v[90:91]
	v_mul_lo_u32 v2, v92, s67
	v_mad_i32_i24 v5, v41, s63, v5
	v_lshl_add_u32 v45, v95, 5, v2
	v_mad_u64_u32 v[2:3], s[6:7], v96, s63, v[0:1]
	v_lshl_add_u64 v[14:15], v[4:5], 0, v[42:43]
	v_mad_i32_i24 v3, v97, s63, v3
	v_add_co_u32_e32 v0, vcc, s65, v100
	v_lshl_add_u64 v[8:9], v[2:3], 0, v[98:99]
	v_mul_lo_u32 v2, v94, s67
	s_waitcnt vmcnt(0)
	v_lshlrev_b32_e32 v16, 16, v33
	v_lshlrev_b32_e32 v18, 16, v32
	v_mul_f32_e32 v6, 0xbfb8aa3b, v18
	v_mul_f32_e32 v7, 0xbfb8aa3b, v16
	v_exp_f32_e32 v6, v6
	v_exp_f32_e32 v7, v7
	v_addc_co_u32_e32 v1, vcc, 0, v101, vcc
	v_lshl_add_u32 v44, v87, 5, v2
	v_pk_add_f32 v[4:5], v[6:7], 1.0 op_sel_hi:[1,0]
	global_load_dwordx4 v[0:3], v[0:1], off offset:512
	v_and_b32_e32 v19, 0xffff0000, v33
	v_and_b32_e32 v20, 0xffff0000, v32
	v_mul_f32_e32 v6, 0xbfb8aa3b, v20
	v_rcp_f32_e32 v17, v5
	s_nop 0
	v_mul_f32_e32 v17, v16, v17
	v_mul_f32_e32 v7, 0xbfb8aa3b, v19
	v_exp_f32_e32 v6, v6
	v_exp_f32_e32 v7, v7
	s_nop 0
	v_pk_add_f32 v[6:7], v[6:7], 1.0 op_sel_hi:[1,0]
	v_rcp_f32_e32 v16, v4
	s_nop 0
	v_mul_f32_e32 v16, v18, v16
	v_lshlrev_b32_e32 v23, 16, v34
	v_rcp_f32_e32 v4, v7
	s_nop 0
	v_mul_f32_e32 v19, v19, v4
	v_lshlrev_b32_e32 v22, 16, v35
	v_mul_f32_e32 v4, 0xbfb8aa3b, v23
	v_mul_f32_e32 v5, 0xbfb8aa3b, v22
	v_exp_f32_e32 v4, v4
	v_exp_f32_e32 v5, v5
	v_rcp_f32_e32 v18, v6
	s_nop 0
	v_mul_f32_e32 v18, v20, v18
	v_and_b32_e32 v24, 0xffff0000, v35
	v_pk_add_f32 v[4:5], v[4:5], 1.0 op_sel_hi:[1,0]
	v_and_b32_e32 v25, 0xffff0000, v34
	v_mul_f32_e32 v6, 0xbfb8aa3b, v25
	v_exp_f32_e32 v6, v6
	v_rcp_f32_e32 v21, v5
	s_nop 0
	v_mul_f32_e32 v21, v22, v21
	v_mul_f32_e32 v7, 0xbfb8aa3b, v24
	v_exp_f32_e32 v7, v7
	s_nop 0
	v_pk_add_f32 v[6:7], v[6:7], 1.0 op_sel_hi:[1,0]
	v_rcp_f32_e32 v20, v4
	s_nop 0
	v_mul_f32_e32 v20, v23, v20
	v_rcp_f32_e32 v23, v7
	s_nop 0
	v_mul_f32_e32 v23, v24, v23
	s_waitcnt vmcnt(0)
; __device__ __forceinline__ unsigned pack2(float a, float b) { return (unsigned)f2bf(a) | ((unsigned)f2bf(b) << 16); }
; __device__ __forceinline__ float bflo(unsigned w) { return __uint_as_float(w << 16); }
; __device__ __forceinline__ float bfhi(unsigned w) { return __uint_as_float(w & 0xffff0000u); }
; __device__ __forceinline__ float silu_f(float g) { return g / (1.f + __expf(-g)); }
; template <int DH, int MODE>
; __device__ void attn_item(const Params& p, int layer, int b, int blk, int head, char* smem) {
;     ...
;     uint4 gt[NCH];
; #pragma unroll
;     for (int i = 0; i < NCH; ++i) {
;       int q = tid + 256 * i, r = q / CPR, c = (q % CPR) * 8;
;       gt[i] = *reinterpret_cast<const uint4*>(P + (tq0 + r) * NP + gcol + c);
;     }
;     float lis[2][4];
; #pragma unroll
;     for (int m = 0; m < 2; ++m)
; #pragma unroll
;       for (int j = 0; j < 4; ++j) lis[m][j] = (MODE == 0) ? linv_s[wid * 32 + m * 16 + fq * 4 + j] : 1.f;
;     if (MODE == 0) __syncthreads();
; #pragma unroll
;     for (int m = 0; m < 2; ++m)
; #pragma unroll
;       for (int j = 0; j < 4; ++j) {
;         int r = wid * 32 + m * 16 + fq * 4 + j;
; #pragma unroll
;         for (int n = 0; n < NDT; ++n) Of[r * OST + n * 16 + fr] = o[m][n][j] * lis[m][j];
;       }
;     __syncthreads();
; #pragma unroll
;     for (int i = 0; i < NCH; ++i) {
;       int q = tid + 256 * i, r = q / CPR, c = (q % CPR) * 8;
;       float4 m0 = *reinterpret_cast<const float4*>(Of + r * OST + c);
;       float4 m1 = *reinterpret_cast<const float4*>(Of + r * OST + c + 4);
;       float mm[8] = {m0.x, m0.y, m0.z, m0.w, m1.x, m1.y, m1.z, m1.w};
;       unsigned gw[4] = {gt[i].x, gt[i].y, gt[i].z, gt[i].w};
;       unsigned ow[4];
; #pragma unroll
;       for (int e = 0; e < 4; ++e)
;         ow[e] = pack2(mm[2 * e] * silu_f(bflo(gw[e])), mm[2 * e + 1] * silu_f(bfhi(gw[e])));
	v_lshlrev_b32_e32 v24, 16, v1
	v_lshlrev_b32_e32 v26, 16, v0
	v_mul_f32_e32 v4, 0xbfb8aa3b, v26
	v_mul_f32_e32 v5, 0xbfb8aa3b, v24
	v_exp_f32_e32 v4, v4
	v_exp_f32_e32 v5, v5
	v_and_b32_e32 v27, 0xffff0000, v1
	v_rcp_f32_e32 v22, v6
	s_nop 0
	v_mul_f32_e32 v22, v25, v22
	v_pk_add_f32 v[4:5], v[4:5], 1.0 op_sel_hi:[1,0]
	v_and_b32_e32 v28, 0xffff0000, v0
	v_mul_f32_e32 v0, 0xbfb8aa3b, v28
	v_exp_f32_e32 v6, v0
	v_lshlrev_b32_e32 v32, 16, v3
	v_mul_f32_e32 v7, 0xbfb8aa3b, v27
	v_rcp_f32_e32 v1, v5
	s_nop 0
	v_mul_f32_e32 v1, v24, v1
	v_exp_f32_e32 v7, v7
	s_nop 0
	v_pk_add_f32 v[24:25], v[6:7], 1.0 op_sel_hi:[1,0]
	v_rcp_f32_e32 v0, v4
	s_nop 0
	v_mul_f32_e32 v0, v26, v0
	v_lshlrev_b32_e32 v33, 16, v2
	v_rcp_f32_e32 v25, v25
	s_nop 0
	v_mul_f32_e32 v25, v27, v25
	v_add_co_u32_e64 v4, s[6:7], s65, v38
	s_nop 0
	s_nop 0
	v_addc_co_u32_e64 v5, s[6:7], 0, v39, s[6:7]
	global_load_dwordx4 v[4:7], v[4:5], off offset:512
	v_mul_f32_e32 v26, 0xbfb8aa3b, v33
	v_mul_f32_e32 v27, 0xbfb8aa3b, v32
	v_exp_f32_e32 v26, v26
	v_exp_f32_e32 v27, v27
	v_and_b32_e32 v30, 0xffff0000, v3
	v_rcp_f32_e32 v24, v24
	s_nop 0
	v_mul_f32_e32 v24, v28, v24
	v_pk_add_f32 v[26:27], v[26:27], 1.0 op_sel_hi:[1,0]
	v_and_b32_e32 v38, 0xffff0000, v2
	v_mul_f32_e32 v2, 0xbfb8aa3b, v38
	v_exp_f32_e32 v28, v2
	v_mul_f32_e32 v29, 0xbfb8aa3b, v30
	v_exp_f32_e32 v29, v29
	v_rcp_f32_e32 v3, v27
	s_nop 0
	v_mul_f32_e32 v3, v32, v3
	v_pk_add_f32 v[28:29], v[28:29], 1.0 op_sel_hi:[1,0]
	v_rcp_f32_e32 v2, v26
	s_nop 0
	v_mul_f32_e32 v2, v33, v2
	v_rcp_f32_e32 v27, v29
	s_nop 0
	v_mul_f32_e32 v27, v30, v27
	v_add_co_u32_e64 v30, s[6:7], s65, v36
	s_nop 0
	s_nop 0
	v_addc_co_u32_e64 v31, s[6:7], 0, v37, s[6:7]
	global_load_dwordx4 v[32:35], v[30:31], off offset:512
	v_rcp_f32_e32 v26, v28
	s_nop 0
	v_mul_f32_e32 v26, v38, v26
	s_barrier
	s_waitcnt vmcnt(1)
	v_lshlrev_b32_e32 v36, 16, v5
	v_lshlrev_b32_e32 v37, 16, v4
	v_mul_f32_e32 v30, 0xbfb8aa3b, v37
	v_mul_f32_e32 v31, 0xbfb8aa3b, v36
	v_exp_f32_e32 v30, v30
	v_exp_f32_e32 v31, v31
	v_and_b32_e32 v38, 0xffff0000, v5
	v_and_b32_e32 v39, 0xffff0000, v4
	v_mul_f32_e32 v4, 0xbfb8aa3b, v39
	v_pk_add_f32 v[28:29], v[30:31], 1.0 op_sel_hi:[1,0]
	v_exp_f32_e32 v30, v4
	ds_write2_b32 v47, v48, v49 offset1:16
	ds_write2_b32 v47, v50, v51 offset0:32 offset1:48
	ds_write2_b32 v47, v52, v53 offset0:68 offset1:84
	ds_write2_b32 v47, v54, v55 offset0:100 offset1:116
	ds_write2_b32 v47, v56, v57 offset0:136 offset1:152
	ds_write2_b32 v47, v58, v59 offset0:168 offset1:184
	ds_write2_b32 v47, v60, v61 offset0:204 offset1:220
	ds_write2_b32 v47, v62, v64 offset0:236 offset1:252
	v_mul_f32_e32 v31, 0xbfb8aa3b, v38
	v_exp_f32_e32 v31, v31
	v_rcp_f32_e32 v5, v29
	s_nop 0
	v_mul_f32_e32 v5, v36, v5
	v_pk_add_f32 v[30:31], v[30:31], 1.0 op_sel_hi:[1,0]
	v_rcp_f32_e32 v4, v28
	s_nop 0
	v_mul_f32_e32 v4, v37, v4
	v_rcp_f32_e32 v29, v31
	s_nop 0
	v_mul_f32_e32 v29, v38, v29
	v_lshlrev_b32_e32 v38, 16, v7
	v_lshlrev_b32_e32 v40, 16, v6
	v_mul_f32_e32 v36, 0xbfb8aa3b, v40
	v_mul_f32_e32 v37, 0xbfb8aa3b, v38
	v_exp_f32_e32 v36, v36
	v_exp_f32_e32 v37, v37
	v_rcp_f32_e32 v28, v30
	s_nop 0
	v_mul_f32_e32 v28, v39, v28
	v_and_b32_e32 v39, 0xffff0000, v7
	v_pk_add_f32 v[30:31], v[36:37], 1.0 op_sel_hi:[1,0]
	v_and_b32_e32 v41, 0xffff0000, v6
	v_mul_f32_e32 v6, 0xbfb8aa3b, v41
	v_exp_f32_e32 v36, v6
	v_mul_f32_e32 v37, 0xbfb8aa3b, v39
	v_exp_f32_e32 v37, v37
	v_rcp_f32_e32 v7, v31
	s_nop 0
	v_mul_f32_e32 v7, v38, v7
	v_pk_add_f32 v[36:37], v[36:37], 1.0 op_sel_hi:[1,0]
	v_rcp_f32_e32 v6, v30
	s_nop 0
	v_mul_f32_e32 v6, v40, v6
	v_rcp_f32_e32 v31, v37
	s_nop 0
	v_mul_f32_e32 v31, v39, v31
	s_waitcnt vmcnt(0)
	v_lshlrev_b32_e32 v42, 16, v33
	v_lshlrev_b32_e32 v43, 16, v32
	v_mul_f32_e32 v38, 0xbfb8aa3b, v43
	v_mul_f32_e32 v39, 0xbfb8aa3b, v42
	v_exp_f32_e32 v38, v38
	v_exp_f32_e32 v39, v39
	v_rcp_f32_e32 v30, v36
	s_nop 0
	v_mul_f32_e32 v30, v41, v30
	v_and_b32_e32 v68, 0xffff0000, v33
	v_pk_add_f32 v[36:37], v[38:39], 1.0 op_sel_hi:[1,0]
	v_and_b32_e32 v39, 0xffff0000, v32
	v_mul_f32_e32 v32, 0xbfb8aa3b, v39
	v_exp_f32_e32 v32, v32
	v_rcp_f32_e32 v41, v37
	s_nop 0
	v_mul_f32_e32 v41, v42, v41
	v_mul_f32_e32 v33, 0xbfb8aa3b, v68
	v_exp_f32_e32 v33, v33
	s_nop 0
	v_pk_add_f32 v[32:33], v[32:33], 1.0 op_sel_hi:[1,0]
	v_rcp_f32_e32 v40, v36
	s_nop 0
	v_mul_f32_e32 v40, v43, v40
	v_lshlrev_b32_e32 v70, 16, v34
	v_rcp_f32_e32 v43, v33
	s_nop 0
	v_mul_f32_e32 v43, v68, v43
	v_lshlrev_b32_e32 v38, 16, v35
	v_mul_f32_e32 v36, 0xbfb8aa3b, v70
	v_mul_f32_e32 v37, 0xbfb8aa3b, v38
	v_exp_f32_e32 v36, v36
	v_exp_f32_e32 v37, v37
	v_rcp_f32_e32 v42, v32
	s_nop 0
	v_mul_f32_e32 v42, v39, v42
	v_and_b32_e32 v39, 0xffff0000, v35
	v_pk_add_f32 v[32:33], v[36:37], 1.0 op_sel_hi:[1,0]
	v_and_b32_e32 v68, 0xffff0000, v34
	v_mul_f32_e32 v34, 0xbfb8aa3b, v68
	v_exp_f32_e32 v34, v34
	v_rcp_f32_e32 v71, v33
	s_nop 0
	v_mul_f32_e32 v71, v38, v71
	v_mul_f32_e32 v35, 0xbfb8aa3b, v39
	v_exp_f32_e32 v35, v35
	s_nop 0
	v_pk_add_f32 v[36:37], v[34:35], 1.0 op_sel_hi:[1,0]
	v_rcp_f32_e32 v33, v32
	s_nop 0
	v_mul_f32_e32 v70, v70, v33
	v_rcp_f32_e32 v85, v37
	s_nop 0
	v_mul_f32_e32 v85, v39, v85
	v_add_u32_e32 v32, 0x1000, v47
	ds_write2_b32 v32, v63, v65 offset0:64 offset1:80
	ds_write2_b32 v32, v67, v69 offset0:96 offset1:112
	ds_write2_b32 v32, v72, v73 offset0:132 offset1:148
	ds_write2_b32 v32, v74, v75 offset0:164 offset1:180
	ds_write2_b32 v32, v76, v77 offset0:200 offset1:216
	ds_write2_b32 v32, v78, v80 offset0:232 offset1:248
	v_add_u32_e32 v32, 0x1400, v47
	ds_write2_b32 v32, v79, v81 offset0:12 offset1:28
	ds_write2_b32 v32, v82, v83 offset0:44 offset1:60
	s_waitcnt lgkmcnt(0)
	s_barrier
; __device__ __forceinline__ unsigned pack2(float a, float b) { return (unsigned)f2bf(a) | ((unsigned)f2bf(b) << 16); }
; __device__ __forceinline__ float bflo(unsigned w) { return __uint_as_float(w << 16); }
; __device__ __forceinline__ float bfhi(unsigned w) { return __uint_as_float(w & 0xffff0000u); }
; __device__ __forceinline__ float silu_f(float g) { return g / (1.f + __expf(-g)); }
; template <int DH, int MODE>
; __device__ void attn_item(const Params& p, int layer, int b, int blk, int head, char* smem) {
;     ...
; #pragma unroll
;     for (int i = 0; i < NCH; ++i) {
;       int q = tid + 256 * i, r = q / CPR, c = (q % CPR) * 8;
;       float4 m0 = *reinterpret_cast<const float4*>(Of + r * OST + c);
;       float4 m1 = *reinterpret_cast<const float4*>(Of + r * OST + c + 4);
;       float mm[8] = {m0.x, m0.y, m0.z, m0.w, m1.x, m1.y, m1.z, m1.w};
;       unsigned gw[4] = {gt[i].x, gt[i].y, gt[i].z, gt[i].w};
;       unsigned ow[4];
; #pragma unroll
;       for (int e = 0; e < 4; ++e)
;         ow[e] = pack2(mm[2 * e] * silu_f(bflo(gw[e])), mm[2 * e + 1] * silu_f(bfhi(gw[e])));
;       *reinterpret_cast<uint4*>(Y + (tq0 + r) * YW + ycol + c) = make_uint4(ow[0], ow[1], ow[2], ow[3]);
;     }
	ds_read_b128 v[32:35], v66
	v_rcp_f32_e32 v84, v36
	s_nop 0
	v_mul_f32_e32 v84, v68, v84
	ds_read_b128 v[36:39], v66 offset:16
	v_add_co_u32_e32 v12, vcc, s70, v12
	s_waitcnt lgkmcnt(1)
	v_mov_b32_e32 v48, v32
	v_mov_b32_e32 v49, v34
	v_pk_mul_f32 v[40:41], v[40:41], v[48:49]
	v_mov_b32_e32 v34, v33
	v_pk_mul_f32 v[32:33], v[42:43], v[34:35]
	v_cvt_pk_bf16_f32 v33, v41, v33
	v_cvt_pk_bf16_f32 v32, v40, v32
	s_waitcnt lgkmcnt(0)
	v_mov_b32_e32 v34, v36
	v_mov_b32_e32 v35, v38
	v_pk_mul_f32 v[34:35], v[70:71], v[34:35]
	v_mov_b32_e32 v38, v37
	v_pk_mul_f32 v[36:37], v[84:85], v[38:39]
	v_cvt_pk_bf16_f32 v35, v35, v37
	v_cvt_pk_bf16_f32 v34, v34, v36
	ds_read_b128 v[36:39], v46
	v_addc_co_u32_e32 v13, vcc, 0, v13, vcc
	global_store_dwordx4 v[12:13], v[32:35], off offset:1024
	s_nop 0
	ds_read_b128 v[32:35], v46 offset:16
	s_waitcnt lgkmcnt(1)
	v_mov_b32_e32 v12, v36
	v_mov_b32_e32 v13, v38
	v_pk_mul_f32 v[4:5], v[4:5], v[12:13]
	v_mov_b32_e32 v38, v37
	v_pk_mul_f32 v[12:13], v[28:29], v[38:39]
	v_cvt_pk_bf16_f32 v5, v5, v13
	v_cvt_pk_bf16_f32 v4, v4, v12
	s_waitcnt lgkmcnt(0)
	v_mov_b32_e32 v12, v32
	v_mov_b32_e32 v13, v34
	v_pk_mul_f32 v[6:7], v[6:7], v[12:13]
	v_mov_b32_e32 v34, v33
	v_pk_mul_f32 v[12:13], v[30:31], v[34:35]
	ds_read_b128 v[28:31], v45
	v_add_co_u32_e32 v10, vcc, s70, v10
	v_cvt_pk_bf16_f32 v7, v7, v13
	v_cvt_pk_bf16_f32 v6, v6, v12
	v_addc_co_u32_e32 v11, vcc, 0, v11, vcc
	global_store_dwordx4 v[10:11], v[4:7], off offset:1024
	s_waitcnt lgkmcnt(0)
	v_mov_b32_e32 v10, v28
	v_mov_b32_e32 v11, v30
	ds_read_b128 v[4:7], v45 offset:16
	v_pk_mul_f32 v[0:1], v[0:1], v[10:11]
	v_mov_b32_e32 v30, v29
	v_pk_mul_f32 v[10:11], v[24:25], v[30:31]
	v_cvt_pk_bf16_f32 v1, v1, v11
	v_cvt_pk_bf16_f32 v0, v0, v10
	s_waitcnt lgkmcnt(0)
	v_mov_b32_e32 v10, v4
	v_mov_b32_e32 v11, v6
	v_pk_mul_f32 v[2:3], v[2:3], v[10:11]
	v_mov_b32_e32 v6, v5
	v_pk_mul_f32 v[4:5], v[26:27], v[6:7]
	v_cvt_pk_bf16_f32 v3, v3, v5
	v_cvt_pk_bf16_f32 v2, v2, v4
	ds_read_b128 v[4:7], v44
	v_add_co_u32_e32 v8, vcc, s70, v8
	s_nop 1
	v_addc_co_u32_e32 v9, vcc, 0, v9, vcc
	global_store_dwordx4 v[8:9], v[0:3], off offset:1024
	s_waitcnt lgkmcnt(0)
	v_mov_b32_e32 v8, v4
	v_mov_b32_e32 v9, v6
	ds_read_b128 v[0:3], v44 offset:16
	v_pk_mul_f32 v[8:9], v[16:17], v[8:9]
	v_mov_b32_e32 v6, v5
	v_pk_mul_f32 v[4:5], v[18:19], v[6:7]
	v_cvt_pk_bf16_f32 v5, v9, v5
	v_cvt_pk_bf16_f32 v4, v8, v4
	s_waitcnt lgkmcnt(0)
	v_mov_b32_e32 v6, v0
	v_mov_b32_e32 v7, v2
	v_pk_mul_f32 v[6:7], v[20:21], v[6:7]
	v_mov_b32_e32 v2, v1
	v_pk_mul_f32 v[0:1], v[22:23], v[2:3]
	v_cvt_pk_bf16_f32 v6, v6, v0
	v_add_co_u32_e32 v0, vcc, 0x184a1000, v14
	v_cvt_pk_bf16_f32 v7, v7, v1
	s_nop 0
	v_addc_co_u32_e32 v1, vcc, 0, v15, vcc
	global_store_dwordx4 v[0:1], v[4:7], off offset:1024
	s_barrier

; __device__ __forceinline__ unsigned pack2(float a, float b) { return (unsigned)f2bf(a) | ((unsigned)f2bf(b) << 16); }
; template <int DH, int MODE>
; __device__ void attn_item(const Params& p, int layer, int b, int blk, int head, char* smem) {
;     ...
; #pragma unroll 2
;         for (int s8 = 0; s8 < 4; ++s8) {
;           float4 va = s4[2 * s8], vb = s4[2 * s8 + 1];
;           float e[8] = {va.x, va.y, va.z, va.w, vb.x, vb.y, vb.z, vb.w};
;           float pv[8];
; #pragma unroll
;           for (int k = 0; k < 8; ++k) {
;             bool valid = (kpb + s8 * 8 + k) < qpos;
;             pv[k] = valid ? __builtin_amdgcn_exp2f(e[k] + offs) : 0.f;
;           }
;           uint4 ov;
;           ov.x = pack2(pv[0], pv[1]); ov.y = pack2(pv[2], pv[3]);
;           ov.z = pack2(pv[4], pv[5]); ov.w = pack2(pv[6], pv[7]);
;           *reinterpret_cast<uint4*>(prow + s8 * 16) = ov;
;         }
.LBB0_1170:
	s_or_b64 exec, exec, s[46:47]
	s_waitcnt lgkmcnt(3)
	v_add_f32_e32 v152, v176, v152
	v_exp_f32_e32 v152, v152
	s_waitcnt lgkmcnt(1)
	v_add_f32_e32 v149, v176, v149
	v_exp_f32_e32 v149, v149
	v_add_u32_e32 v182, 0x3fc9, v178
	v_add_f32_e32 v151, v176, v151
	v_add_f32_e32 v148, v176, v148
	v_cmp_lt_i32_e32 vcc, v182, v144
	v_exp_f32_e32 v185, v151
	v_exp_f32_e32 v186, v148
	v_add_u32_e32 v148, 0x3fce, v178
	s_waitcnt lgkmcnt(0)
	v_add_f32_e32 v151, v176, v180
	v_cndmask_b32_e32 v152, 0, v152, vcc
	v_exp_f32_e32 v151, v151
	v_cmp_lt_i32_e32 vcc, v148, v144
	v_add_u32_e32 v148, 0x3fcf, v178
	v_add_f32_e32 v153, v176, v153
	v_cndmask_b32_e32 v149, 0, v149, vcc
	v_cmp_lt_i32_e32 vcc, v148, v144
	v_cvt_pk_bf16_f32 v148, 0, v179
	v_exp_f32_e32 v153, v153
	v_lshrrev_b32_e32 v148, 16, v148
	v_cvt_pk_bf16_f32 v152, 0, v152
	v_add_f32_e32 v150, v176, v150
	v_cndmask_b32_e32 v151, 0, v151, vcc
	v_and_or_b32 v148, v152, s41, v148
	v_or_b32_e32 v182, 2, v181
	v_exp_f32_e32 v150, v150
	v_cvt_pk_bf16_f32 v149, 0, v149
	v_or_b32_e32 v183, 4, v181
	v_lshrrev_b32_e32 v149, 16, v149
	v_cvt_pk_bf16_f32 v151, 0, v151
	v_cmp_lt_i32_e32 vcc, v182, v144
	v_or_b32_e32 v184, 5, v181
	v_or_b32_e32 v181, 3, v181
	v_and_or_b32 v151, v151, s41, v149
	v_cndmask_b32_e32 v149, 0, v153, vcc
	v_cmp_lt_i32_e32 vcc, v183, v131
	v_cvt_pk_bf16_f32 v149, 0, v149
	s_nop 0
	v_cndmask_b32_e32 v152, 0, v185, vcc
	v_cmp_lt_i32_e32 vcc, v181, v144
	s_nop 0
	s_nop 0
	v_cndmask_b32_e32 v150, 0, v150, vcc
	v_cmp_lt_i32_e32 vcc, v184, v131
	v_cvt_pk_bf16_f32 v150, 0, v150
	s_nop 0
	v_cndmask_b32_e32 v153, 0, v186, vcc
	v_and_b32_e32 v178, 0xffff0000, v150
	v_cvt_pk_bf16_f32 v150, v152, v153
	v_or_b32_sdwa v149, v178, v149 dst_sel:DWORD dst_unused:UNUSED_PAD src0_sel:DWORD src1_sel:WORD_1
	s_add_i32 s81, s81, 16
	ds_write_b128 v175, v[148:151] offset:16
	v_add_u32_e32 v177, 64, v177
	s_cmp_eq_u32 s81, 32
	v_add_u32_e32 v175, 32, v175
	s_cbranch_scc1 .LBB0_1176

; __device__ __forceinline__ unsigned pack2(float a, float b) { return (unsigned)f2bf(a) | ((unsigned)f2bf(b) << 16); }
; template <int DH, int MODE>
; __device__ void attn_item(const Params& p, int layer, int b, int blk, int head, char* smem) {
;     ...
; #pragma unroll 2
;         for (int s8 = 0; s8 < 4; ++s8) {
;           float4 va = s4[2 * s8], vb = s4[2 * s8 + 1];
;           float e[8] = {va.x, va.y, va.z, va.w, vb.x, vb.y, vb.z, vb.w};
;           float pv[8];
; #pragma unroll
;           for (int k = 0; k < 8; ++k) {
;             bool valid = (kpb + s8 * 8 + k) < qpos;
;             pv[k] = valid ? __builtin_amdgcn_exp2f(e[k] + offs) : 0.f;
;           }
;           uint4 ov;
;           ov.x = pack2(pv[0], pv[1]); ov.y = pack2(pv[2], pv[3]);
;           ov.z = pack2(pv[4], pv[5]); ov.w = pack2(pv[6], pv[7]);
;           *reinterpret_cast<uint4*>(prow + s8 * 16) = ov;
;         }
.LBB0_1173:
	s_or_b64 exec, exec, s[46:47]
	s_waitcnt lgkmcnt(3)
	v_add_f32_e32 v152, v176, v152
	v_exp_f32_e32 v152, v152
	s_waitcnt lgkmcnt(1)
	v_add_f32_e32 v149, v176, v149
	v_exp_f32_e32 v149, v149
	v_add_u32_e32 v183, 0x3fc1, v178
	v_add_f32_e32 v151, v176, v151
	v_add_f32_e32 v148, v176, v148
	v_cmp_lt_i32_e32 vcc, v183, v144
	v_exp_f32_e32 v186, v151
	v_exp_f32_e32 v187, v148
	v_add_u32_e32 v148, 0x3fc6, v178
	s_waitcnt lgkmcnt(0)
	v_add_f32_e32 v151, v176, v180
	v_cndmask_b32_e32 v152, 0, v152, vcc
	v_exp_f32_e32 v151, v151
	v_cmp_lt_i32_e32 vcc, v148, v144
	v_add_u32_e32 v148, 0x3fc7, v178
	v_add_f32_e32 v153, v176, v153
	v_cndmask_b32_e32 v149, 0, v149, vcc
	v_cmp_lt_i32_e32 vcc, v148, v144
	v_cvt_pk_bf16_f32 v148, 0, v181
	v_exp_f32_e32 v153, v153
	v_lshrrev_b32_e32 v148, 16, v148
	v_cvt_pk_bf16_f32 v152, 0, v152
	v_add_f32_e32 v150, v176, v150
	v_cndmask_b32_e32 v151, 0, v151, vcc
	v_and_or_b32 v148, v152, s41, v148
	v_or_b32_e32 v183, 2, v182
	v_exp_f32_e32 v150, v150
	v_cvt_pk_bf16_f32 v149, 0, v149
	v_or_b32_e32 v184, 4, v182
	v_lshrrev_b32_e32 v149, 16, v149
	v_cvt_pk_bf16_f32 v151, 0, v151
	v_cmp_lt_i32_e32 vcc, v183, v144
	v_or_b32_e32 v185, 5, v182
	v_or_b32_e32 v182, 3, v182
	v_and_or_b32 v151, v151, s41, v149
	v_cndmask_b32_e32 v149, 0, v153, vcc
	v_cmp_lt_i32_e32 vcc, v184, v131
	v_cvt_pk_bf16_f32 v149, 0, v149
	s_nop 0
	v_cndmask_b32_e32 v152, 0, v186, vcc
	v_cmp_lt_i32_e32 vcc, v182, v144
	s_nop 0
	s_nop 0
	v_cndmask_b32_e32 v150, 0, v150, vcc
	v_cmp_lt_i32_e32 vcc, v185, v131
	v_cvt_pk_bf16_f32 v150, 0, v150
	s_nop 0
	v_cndmask_b32_e32 v153, 0, v187, vcc
	v_and_b32_e32 v180, 0xffff0000, v150
	v_cvt_pk_bf16_f32 v150, v152, v153
	v_or_b32_sdwa v149, v180, v149 dst_sel:DWORD dst_unused:UNUSED_PAD src0_sel:DWORD src1_sel:WORD_1
	ds_write_b128 v175, v[148:151]
	ds_read2_b32 v[152:153], v177 offset0:9 offset1:10
	ds_read2_b32 v[150:151], v177 offset0:11 offset1:12
	ds_read2_b32 v[148:149], v177 offset0:13 offset1:14
	ds_read_b32 v180, v177 offset:60
	v_add_u32_e32 v181, 0x3fc8, v178
	v_cmp_lt_i32_e32 vcc, v181, v144
	s_and_saveexec_b64 s[46:47], vcc
	s_cbranch_execz .LBB0_1170
	ds_read_b32 v179, v177 offset:32
	s_waitcnt lgkmcnt(0)
	v_add_f32_e32 v179, v176, v179
	v_exp_f32_e32 v179, v179
	s_branch .LBB0_1170
